# concurrent wave-group epilogues extended to all GEMMs with straight-line epilogues (SwapK/V/F, DFT, out-proj, FFN2-down, SwiGLU x2); on top of v9
# baseline (speedup 1.0000x reference)
; #define PG8_STAGE(bufoff, gbase, voff) do { _Pragma("unroll") for (int _i = 0; _i < 2; ++_i) \
;         __builtin_amdgcn_global_load_lds((const unsigned*)((const char*)(gbase) + (voff)[_i]), (LAS unsigned*)(lds + (bufoff) + ldsw + _i * 8192), 16, 0, 0); } while (0)
; #define PG8_LDA(dst, b, h) do { _Pragma("unroll") for (int m = 0; m < 4; ++m) _Pragma("unroll") for (int k = 0; k < 2; ++k) dst[m][k] = *(const LAS bf16x8*)(lds + PG8_SA(b, h) + aoff + m * 2048 + k * 1024); } while (0)
; #define PG8_LDB(dst, b, h) do { _Pragma("unroll") for (int n = 0; n < 2; ++n) _Pragma("unroll") for (int k = 0; k < 2; ++k) dst[n][k] = *(const LAS bf16x8*)(lds + PG8_SB(b, h) + boff + n * 2048 + k * 1024); } while (0)
; #define PG8_MMA(ai, bj, At, Bt) do { __builtin_amdgcn_s_setprio(1); _Pragma("unroll") for (int m = 0; m < 4; ++m) _Pragma("unroll") for (int n = 0; n < 2; ++n) _Pragma("unroll") for (int k = 0; k < 2; ++k) \
;         acc[ai][bj][m][n] = __builtin_amdgcn_mfma_f32_16x16x32_bf16(Bt[n][k], At[m][k], acc[ai][bj][m][n], 0, 0, 0); __builtin_amdgcn_s_setprio(0); } while (0)
; #define PG8_WAIT_V(n) asm volatile("s_waitcnt vmcnt(" #n ")" ::: "memory")
; #define PG8_WAIT_L(n) asm volatile("s_waitcnt lgkmcnt(" #n ")" ::: "memory")
; #define PG8_BAR __builtin_amdgcn_s_barrier()
; #define PG8_SCHED __builtin_amdgcn_sched_barrier(0)
; template <class Epi, class Sched>
; __device__ __forceinline__ void gemm_phase(LAS unsigned char* lds, const Gemm g, const Sched& S, const Epi& E) {
;     ...
;             PG8_LDB(B0, 0, 0); PG8_SCHED; PG8_LDA(At, 0, 0); PG8_STAGE(PG8_SA(1, 1), a1 + hstep, voffA);
;             PG8_WAIT_L(8); PG8_BAR; PG8_WAIT_L(0); PG8_MMA(0, 0, At, B0); PG8_BAR; PG8_SCHED;
;             PG8_LDB(B1, 0, 1); PG8_STAGE(PG8_SB(0, 0), b2, voffB);
;             PG8_BAR; PG8_WAIT_L(0); PG8_MMA(0, 1, At, B1); PG8_BAR;
;             PG8_LDA(At, 0, 1); PG8_STAGE(PG8_SA(0, 0), a2, voffA);
;             PG8_BAR; PG8_WAIT_L(0); PG8_MMA(1, 0, At, B0); PG8_BAR; PG8_SCHED;
;             PG8_STAGE(PG8_SB(0, 1), b2 + hstep, voffB);
;             PG8_WAIT_V(6); PG8_BAR; PG8_MMA(1, 1, At, B1); PG8_BAR;
.LBB0_613:
	ds_read_b128 v[146:149], v171
	ds_read_b128 v[150:153], v171 offset:1024
	ds_read_b128 v[154:157], v171 offset:2048
	ds_read_b128 v[158:161], v171 offset:3072
	s_add_u32 s4, s0, 0xfffc0080
	s_addc_u32 s5, s1, -1
	s_cmp_eq_u32 s67, 12
	s_cselect_b32 s7, s8, s5
	s_cselect_b32 s6, s9, s4
	s_cselect_b32 s5, s31, s66
	s_cselect_b32 s4, s35, s65
	s_add_i32 m0, s45, 0xc000
	ds_read_b128 v[162:165], v172
	ds_read_b128 v[178:181], v172 offset:1024
	ds_read_b128 v[182:185], v172 offset:2048
	ds_read_b128 v[186:189], v172 offset:3072
	ds_read_b128 v[190:193], v172 offset:4096
	ds_read_b128 v[194:197], v172 offset:5120
	ds_read_b128 v[202:205], v172 offset:6144
	ds_read_b128 v[206:209], v172 offset:7168
	global_load_lds_dwordx4 v138, s[0:1]
	s_add_i32 m0, s45, 0xe000
	s_nop 0
	global_load_lds_dwordx4 v140, s[0:1]
	s_waitcnt lgkmcnt(8)
	s_waitcnt vmcnt(10)
	s_barrier
	s_waitcnt lgkmcnt(0)
	s_setprio 1
	s_waitcnt lgkmcnt(0)
	v_mfma_f32_16x16x32_bf16 v[124:127], v[146:149], v[162:165], v[124:127]
	v_mfma_f32_16x16x32_bf16 v[120:123], v[154:157], v[162:165], v[120:123]
	v_mfma_f32_16x16x32_bf16 v[108:111], v[146:149], v[182:185], v[108:111]
	v_mfma_f32_16x16x32_bf16 v[104:107], v[154:157], v[182:185], v[104:107]
	v_mfma_f32_16x16x32_bf16 v[92:95], v[146:149], v[190:193], v[92:95]
	v_mfma_f32_16x16x32_bf16 v[88:91], v[154:157], v[190:193], v[88:91]
	v_mfma_f32_16x16x32_bf16 v[76:79], v[146:149], v[202:205], v[76:79]
	v_mfma_f32_16x16x32_bf16 v[72:75], v[154:157], v[202:205], v[72:75]
	v_mfma_f32_16x16x32_bf16 v[124:127], v[150:153], v[178:181], v[124:127]
	v_mfma_f32_16x16x32_bf16 v[120:123], v[158:161], v[178:181], v[120:123]
	v_mfma_f32_16x16x32_bf16 v[108:111], v[150:153], v[186:189], v[108:111]
	v_mfma_f32_16x16x32_bf16 v[104:107], v[158:161], v[186:189], v[104:107]
	v_mfma_f32_16x16x32_bf16 v[92:95], v[150:153], v[194:197], v[92:95]
	v_mfma_f32_16x16x32_bf16 v[88:91], v[158:161], v[194:197], v[88:91]
	v_mfma_f32_16x16x32_bf16 v[76:79], v[150:153], v[206:209], v[76:79]
	v_mfma_f32_16x16x32_bf16 v[72:75], v[158:161], v[206:209], v[72:75]
	s_setprio 0
	s_barrier
	s_add_i32 s68, s57, s44
	s_mov_b32 m0, s68
	ds_read_b128 v[210:213], v173
	ds_read_b128 v[214:217], v173 offset:1024
	ds_read_b128 v[218:221], v173 offset:2048
	ds_read_b128 v[222:225], v173 offset:3072
	global_load_lds_dwordx4 v130, s[4:5]
	s_add_i32 m0, s68, 0x2000
	s_nop 0
	global_load_lds_dwordx4 v134, s[4:5]
	s_waitcnt vmcnt(10)
	s_barrier
	s_waitcnt lgkmcnt(0)
	s_setprio 1
	s_waitcnt lgkmcnt(0)
	v_mfma_f32_16x16x32_bf16 v[116:119], v[210:213], v[162:165], v[116:119]
	v_mfma_f32_16x16x32_bf16 v[112:115], v[218:221], v[162:165], v[112:115]
	v_mfma_f32_16x16x32_bf16 v[100:103], v[210:213], v[182:185], v[100:103]
	v_mfma_f32_16x16x32_bf16 v[96:99], v[218:221], v[182:185], v[96:99]
	v_mfma_f32_16x16x32_bf16 v[84:87], v[210:213], v[190:193], v[84:87]
	v_mfma_f32_16x16x32_bf16 v[80:83], v[218:221], v[190:193], v[80:83]
	v_mfma_f32_16x16x32_bf16 v[68:71], v[210:213], v[202:205], v[68:71]
	v_mfma_f32_16x16x32_bf16 v[64:67], v[218:221], v[202:205], v[64:67]
	v_mfma_f32_16x16x32_bf16 v[116:119], v[214:217], v[178:181], v[116:119]
	v_mfma_f32_16x16x32_bf16 v[112:115], v[222:225], v[178:181], v[112:115]
	v_mfma_f32_16x16x32_bf16 v[100:103], v[214:217], v[186:189], v[100:103]
	v_mfma_f32_16x16x32_bf16 v[96:99], v[222:225], v[186:189], v[96:99]
	v_mfma_f32_16x16x32_bf16 v[84:87], v[214:217], v[194:197], v[84:87]
	v_mfma_f32_16x16x32_bf16 v[80:83], v[222:225], v[194:197], v[80:83]
	v_mfma_f32_16x16x32_bf16 v[68:71], v[214:217], v[206:209], v[68:71]
	v_mfma_f32_16x16x32_bf16 v[64:67], v[222:225], v[206:209], v[64:67]
	s_setprio 0
	s_mov_b32 m0, s45
	v_lshl_add_u64 v[226:227], s[6:7], 0, v[128:129]
	s_barrier
	ds_read_b128 v[162:165], v172 offset:16384
	ds_read_b128 v[178:181], v172 offset:17408
	ds_read_b128 v[182:185], v172 offset:18432
	ds_read_b128 v[186:189], v172 offset:19456
	ds_read_b128 v[190:193], v172 offset:20480
	ds_read_b128 v[194:197], v172 offset:21504
	ds_read_b128 v[202:205], v172 offset:22528
	ds_read_b128 v[206:209], v172 offset:23552
	global_load_lds_dwordx4 v128, s[6:7]
	v_lshl_add_u64 v[228:229], s[6:7], 0, v[132:133]
	s_mov_b32 m0, s46
	s_nop 0
	global_load_lds_dwordx4 v132, s[6:7]
	s_barrier
	s_waitcnt lgkmcnt(0)
	s_setprio 1
	s_waitcnt lgkmcnt(0)
	v_mfma_f32_16x16x32_bf16 v[60:63], v[146:149], v[162:165], v[60:63]
	v_mfma_f32_16x16x32_bf16 v[56:59], v[154:157], v[162:165], v[56:59]
	v_mfma_f32_16x16x32_bf16 v[44:47], v[146:149], v[182:185], v[44:47]
	v_mfma_f32_16x16x32_bf16 v[40:43], v[154:157], v[182:185], v[40:43]
	v_mfma_f32_16x16x32_bf16 v[28:31], v[146:149], v[190:193], v[28:31]
	v_mfma_f32_16x16x32_bf16 v[24:27], v[154:157], v[190:193], v[24:27]
	v_mfma_f32_16x16x32_bf16 v[12:15], v[146:149], v[202:205], v[12:15]
	v_mfma_f32_16x16x32_bf16 v[8:11], v[154:157], v[202:205], v[8:11]
	v_mfma_f32_16x16x32_bf16 v[60:63], v[150:153], v[178:181], v[60:63]
	v_mfma_f32_16x16x32_bf16 v[56:59], v[158:161], v[178:181], v[56:59]
	v_mfma_f32_16x16x32_bf16 v[44:47], v[150:153], v[186:189], v[44:47]
	v_mfma_f32_16x16x32_bf16 v[40:43], v[158:161], v[186:189], v[40:43]
	v_mfma_f32_16x16x32_bf16 v[28:31], v[150:153], v[194:197], v[28:31]
	v_mfma_f32_16x16x32_bf16 v[24:27], v[158:161], v[194:197], v[24:27]
	v_mfma_f32_16x16x32_bf16 v[12:15], v[150:153], v[206:209], v[12:15]
	v_mfma_f32_16x16x32_bf16 v[8:11], v[158:161], v[206:209], v[8:11]
	s_setprio 0
	s_barrier
	s_add_u32 s68, s4, 0x40000
	s_addc_u32 s69, s5, 0
	s_add_i32 s70, s58, s44
	s_mov_b32 m0, s70
	s_nop 0
	global_load_lds_dwordx4 v130, s[68:69]
	s_add_i32 m0, s70, 0x2000
	s_nop 0
	global_load_lds_dwordx4 v134, s[68:69]
	s_add_u32 s6, s6, 0x40000
	s_addc_u32 s7, s7, 0
	s_mov_b32 m0, s47
	s_nop 0
	global_load_lds_dwordx4 v128, s[6:7]
	s_mov_b32 m0, s48
	s_nop 0
	global_load_lds_dwordx4 v132, s[6:7]
	s_waitcnt vmcnt(12)
	s_barrier
; #define PG8_STAGE(bufoff, gbase, voff) do { _Pragma("unroll") for (int _i = 0; _i < 2; ++_i) \
;         __builtin_amdgcn_global_load_lds((const unsigned*)((const char*)(gbase) + (voff)[_i]), (LAS unsigned*)(lds + (bufoff) + ldsw + _i * 8192), 16, 0, 0); } while (0)
; #define PG8_LDA(dst, b, h) do { _Pragma("unroll") for (int m = 0; m < 4; ++m) _Pragma("unroll") for (int k = 0; k < 2; ++k) dst[m][k] = *(const LAS bf16x8*)(lds + PG8_SA(b, h) + aoff + m * 2048 + k * 1024); } while (0)
; #define PG8_LDB(dst, b, h) do { _Pragma("unroll") for (int n = 0; n < 2; ++n) _Pragma("unroll") for (int k = 0; k < 2; ++k) dst[n][k] = *(const LAS bf16x8*)(lds + PG8_SB(b, h) + boff + n * 2048 + k * 1024); } while (0)
; #define PG8_MMA(ai, bj, At, Bt) do { __builtin_amdgcn_s_setprio(1); _Pragma("unroll") for (int m = 0; m < 4; ++m) _Pragma("unroll") for (int n = 0; n < 2; ++n) _Pragma("unroll") for (int k = 0; k < 2; ++k) \
;         acc[ai][bj][m][n] = __builtin_amdgcn_mfma_f32_16x16x32_bf16(Bt[n][k], At[m][k], acc[ai][bj][m][n], 0, 0, 0); __builtin_amdgcn_s_setprio(0); } while (0)
; #define PG8_WAIT_V(n) asm volatile("s_waitcnt vmcnt(" #n ")" ::: "memory")
; #define PG8_WAIT_L(n) asm volatile("s_waitcnt lgkmcnt(" #n ")" ::: "memory")
; #define PG8_BAR __builtin_amdgcn_s_barrier()
; #define PG8_SCHED __builtin_amdgcn_sched_barrier(0)
; template <class Epi, class Sched>
; __device__ __forceinline__ void gemm_phase(LAS unsigned char* lds, const Gemm g, const Sched& S, const Epi& E) {
;     ...
;             PG8_WAIT_V(6); PG8_BAR; PG8_MMA(1, 1, At, B1); PG8_BAR;
;             PG8_LDB(B0, 1, 0); PG8_SCHED; PG8_LDA(At, 1, 0); PG8_STAGE(PG8_SA(0, 1), a2 + hstep, voffA);
;             PG8_WAIT_L(8); PG8_BAR; PG8_WAIT_L(0); PG8_MMA(0, 0, At, B0); PG8_BAR; PG8_SCHED;
;             PG8_LDB(B1, 1, 1); PG8_STAGE(PG8_SB(1, 0), b3, voffB);
;             PG8_BAR; PG8_WAIT_L(0); PG8_MMA(0, 1, At, B1); PG8_BAR;
;             PG8_LDA(At, 1, 1); PG8_STAGE(PG8_SA(1, 0), a3, voffA);
;             PG8_BAR; PG8_WAIT_L(0); PG8_MMA(1, 0, At, B0); PG8_BAR; PG8_SCHED;
	s_setprio 1
	v_mfma_f32_16x16x32_bf16 v[52:55], v[210:213], v[162:165], v[52:55]
	v_mfma_f32_16x16x32_bf16 v[48:51], v[218:221], v[162:165], v[48:51]
	v_mfma_f32_16x16x32_bf16 v[36:39], v[210:213], v[182:185], v[36:39]
	v_mfma_f32_16x16x32_bf16 v[32:35], v[218:221], v[182:185], v[32:35]
	v_mfma_f32_16x16x32_bf16 v[20:23], v[210:213], v[190:193], v[20:23]
	v_mfma_f32_16x16x32_bf16 v[16:19], v[218:221], v[190:193], v[16:19]
	v_mfma_f32_16x16x32_bf16 v[4:7], v[210:213], v[202:205], v[4:7]
	v_mfma_f32_16x16x32_bf16 v[0:3], v[218:221], v[202:205], v[0:3]
	v_mfma_f32_16x16x32_bf16 v[52:55], v[214:217], v[178:181], v[52:55]
	v_mfma_f32_16x16x32_bf16 v[48:51], v[222:225], v[178:181], v[48:51]
	v_mfma_f32_16x16x32_bf16 v[36:39], v[214:217], v[186:189], v[36:39]
	v_mfma_f32_16x16x32_bf16 v[32:35], v[222:225], v[186:189], v[32:35]
	v_mfma_f32_16x16x32_bf16 v[20:23], v[214:217], v[194:197], v[20:23]
	v_mfma_f32_16x16x32_bf16 v[16:19], v[222:225], v[194:197], v[16:19]
	v_mfma_f32_16x16x32_bf16 v[4:7], v[214:217], v[206:209], v[4:7]
	v_mfma_f32_16x16x32_bf16 v[0:3], v[222:225], v[206:209], v[0:3]
	s_setprio 0
	s_add_i32 s68, 0, 0x18000
	v_add_u32_e32 v136, s68, v170
	s_barrier
	ds_read_b128 v[146:149], v136
	ds_read_b128 v[150:153], v136 offset:1024
	ds_read_b128 v[154:157], v136 offset:2048
	ds_read_b128 v[158:161], v136 offset:3072
	ds_read_b128 v[162:165], v172 offset:32768
	ds_read_b128 v[178:181], v172 offset:33792
	ds_read_b128 v[182:185], v172 offset:34816
	ds_read_b128 v[186:189], v172 offset:35840
	ds_read_b128 v[190:193], v172 offset:36864
	ds_read_b128 v[194:197], v172 offset:37888
	ds_read_b128 v[202:205], v172 offset:38912
	ds_read_b128 v[206:209], v172 offset:39936
	s_waitcnt lgkmcnt(8)
	s_waitcnt vmcnt(10)
	s_barrier
	s_waitcnt lgkmcnt(0)
	s_setprio 1
	s_waitcnt lgkmcnt(0)
	v_mfma_f32_16x16x32_bf16 v[124:127], v[146:149], v[162:165], v[124:127]
	v_mfma_f32_16x16x32_bf16 v[120:123], v[154:157], v[162:165], v[120:123]
	v_mfma_f32_16x16x32_bf16 v[108:111], v[146:149], v[182:185], v[108:111]
	v_mfma_f32_16x16x32_bf16 v[104:107], v[154:157], v[182:185], v[104:107]
	v_mfma_f32_16x16x32_bf16 v[92:95], v[146:149], v[190:193], v[92:95]
	v_mfma_f32_16x16x32_bf16 v[88:91], v[154:157], v[190:193], v[88:91]
	v_mfma_f32_16x16x32_bf16 v[76:79], v[146:149], v[202:205], v[76:79]
	v_mfma_f32_16x16x32_bf16 v[72:75], v[154:157], v[202:205], v[72:75]
	v_mfma_f32_16x16x32_bf16 v[124:127], v[150:153], v[178:181], v[124:127]
	v_mfma_f32_16x16x32_bf16 v[120:123], v[158:161], v[178:181], v[120:123]
	v_mfma_f32_16x16x32_bf16 v[108:111], v[150:153], v[186:189], v[108:111]
	v_mfma_f32_16x16x32_bf16 v[104:107], v[158:161], v[186:189], v[104:107]
	v_mfma_f32_16x16x32_bf16 v[92:95], v[150:153], v[194:197], v[92:95]
	v_mfma_f32_16x16x32_bf16 v[88:91], v[158:161], v[194:197], v[88:91]
	v_mfma_f32_16x16x32_bf16 v[76:79], v[150:153], v[206:209], v[76:79]
	v_mfma_f32_16x16x32_bf16 v[72:75], v[158:161], v[206:209], v[72:75]
	s_setprio 0
	s_barrier
	s_add_i32 s6, 0, 0x1c000
	s_add_i32 s7, s68, s44
	v_add_u32_e32 v136, s6, v170
	s_add_u32 s20, s4, 0x80
	s_addc_u32 s21, s5, 0
	s_mov_b32 m0, s7
	ds_read_b128 v[210:213], v136
	ds_read_b128 v[214:217], v136 offset:1024
	ds_read_b128 v[218:221], v136 offset:2048
	ds_read_b128 v[222:225], v136 offset:3072
	global_load_lds_dwordx4 v130, s[20:21]
	s_add_i32 m0, s7, 0x2000
	s_nop 0
	global_load_lds_dwordx4 v134, s[20:21]
	s_waitcnt vmcnt(10)
	s_barrier
	s_waitcnt lgkmcnt(0)
	s_setprio 1
	s_waitcnt lgkmcnt(0)
	v_mfma_f32_16x16x32_bf16 v[116:119], v[210:213], v[162:165], v[116:119]
	v_mfma_f32_16x16x32_bf16 v[112:115], v[218:221], v[162:165], v[112:115]
	v_mfma_f32_16x16x32_bf16 v[100:103], v[210:213], v[182:185], v[100:103]
	v_mfma_f32_16x16x32_bf16 v[96:99], v[218:221], v[182:185], v[96:99]
	v_mfma_f32_16x16x32_bf16 v[84:87], v[210:213], v[190:193], v[84:87]
	v_mfma_f32_16x16x32_bf16 v[80:83], v[218:221], v[190:193], v[80:83]
	v_mfma_f32_16x16x32_bf16 v[68:71], v[210:213], v[202:205], v[68:71]
	v_mfma_f32_16x16x32_bf16 v[64:67], v[218:221], v[202:205], v[64:67]
	v_mfma_f32_16x16x32_bf16 v[116:119], v[214:217], v[178:181], v[116:119]
	v_mfma_f32_16x16x32_bf16 v[112:115], v[222:225], v[178:181], v[112:115]
	v_mfma_f32_16x16x32_bf16 v[100:103], v[214:217], v[186:189], v[100:103]
	v_mfma_f32_16x16x32_bf16 v[96:99], v[222:225], v[186:189], v[96:99]
	v_mfma_f32_16x16x32_bf16 v[84:87], v[214:217], v[194:197], v[84:87]
	v_mfma_f32_16x16x32_bf16 v[80:83], v[222:225], v[194:197], v[80:83]
	v_mfma_f32_16x16x32_bf16 v[68:71], v[214:217], v[206:209], v[68:71]
	v_mfma_f32_16x16x32_bf16 v[64:67], v[222:225], v[206:209], v[64:67]
	s_setprio 0
	s_mov_b32 m0, s54
	s_mov_b64 s[20:21], 0x80
	v_lshl_add_u64 v[166:167], v[226:227], 0, s[20:21]
	s_barrier
	ds_read_b128 v[162:165], v172 offset:49152
	ds_read_b128 v[178:181], v172 offset:50176
	ds_read_b128 v[182:185], v172 offset:51200
	ds_read_b128 v[186:189], v172 offset:52224
	ds_read_b128 v[190:193], v172 offset:53248
	ds_read_b128 v[194:197], v172 offset:54272
	ds_read_b128 v[202:205], v172 offset:55296
	ds_read_b128 v[206:209], v172 offset:56320
	global_load_lds_dwordx4 v[166:167], off
	v_lshl_add_u64 v[166:167], v[228:229], 0, s[20:21]
	s_mov_b32 m0, s55
	s_nop 0
	global_load_lds_dwordx4 v[166:167], off
	s_barrier
; #define PG8_WAIT_V(n) asm volatile("s_waitcnt vmcnt(" #n ")" ::: "memory")
; #define PG8_BAR __builtin_amdgcn_s_barrier()
; template <class Epi, class Sched>
; __device__ __forceinline__ void gemm_phase(LAS unsigned char* lds, const Gemm g, const Sched& S, const Epi& E) {
;     ...
;             PG8_WAIT_V(6); PG8_BAR; PG8_MMA(1, 1, At, B1); PG8_BAR;
;         }
;         E(acc, cur, wr, wc, fr, fq);
;         if (!has_next) break;
;     __device__ __forceinline__ void operator()(const AccT& acc, const Unit& u, int wr, int wc, int fr, int fq) const {
;     ...
;         const int rbase = wr * 64 + fr;
;         const int tb = u.pn * 256 + wc * 32 + 8 * fq;
;         const int o0 = wc * 32 + 8 * fq;
;         const int j = fr & 3; const float sgn = ((fr >> 2) & 1) ? 1.0f : -1.0f;
; #pragma unroll
;         for (int ai = 0; ai < 2; ++ai) {
;             const int hh = 2 * ai + wr;
;             const float l2f = lgd[hh] * 1.4426950408889634f, l2b = lgd[4 + hh] * 1.4426950408889634f;
;             const float zf0 = exp2f((float)(127 - o0) * l2f), zfs = exp2f(-l2f), zb0 = exp2f((float)o0 * l2b), zbs = exp2f(l2b);
; #pragma unroll
;             for (int m = 0; m < 4; ++m) {
;                 const int r = rbase + ai * 128 + m * 16;
;                 const int d = 4 * (2 * m + (fr >> 3)) + j;
; #pragma unroll
;                 for (int bj = 0; bj < 2; ++bj) {
;                     const int t0 = tb + bj * 128;
;                     float v[8];
; #pragma unroll
;                     for (int jj = 0; jj < 4; ++jj) { v[jj] = acc[ai][bj][m][0][jj]; v[4 + jj] = acc[ai][bj][m][1][jj]; }
;                     if constexpr (ROPE) {
;                         const int t = t0 & 2047;
; #pragma unroll
;                         for (int hf = 0; hf < 2; ++hf) {
;                             f32x4 cs, sn;
;                             if (m < 2) { const float c1 = ropeA[(t >> 6) * 16 + d], s1 = ropeA[1024 + (t >> 6) * 16 + d]; cs = (f32x4){c1, c1, c1, c1}; sn = (f32x4){s1, s1, s1, s1}; }
;                             else { const float* cb = ropeA + 2048 + (d - 16) * 64 + (t & 63) + 4 * hf; cs = *(const f32x4*)(cb); sn = *(const f32x4*)(cb + 1024); }
; #pragma unroll
;                             for (int jj = 0; jj < 4; ++jj) { const float pr = __shfl_xor(v[4 * hf + jj], 4); v[4 * hf + jj] = v[4 * hf + jj] * cs[jj] + sgn * pr * sn[jj]; }
	s_waitcnt lgkmcnt(0)
	s_setprio 1
	s_waitcnt lgkmcnt(0)
	v_mfma_f32_16x16x32_bf16 v[60:63], v[146:149], v[162:165], v[60:63]
	v_mfma_f32_16x16x32_bf16 v[56:59], v[154:157], v[162:165], v[56:59]
	v_mfma_f32_16x16x32_bf16 v[44:47], v[146:149], v[182:185], v[44:47]
	v_mfma_f32_16x16x32_bf16 v[40:43], v[154:157], v[182:185], v[40:43]
	v_mfma_f32_16x16x32_bf16 v[28:31], v[146:149], v[190:193], v[28:31]
	v_mfma_f32_16x16x32_bf16 v[24:27], v[154:157], v[190:193], v[24:27]
	v_mfma_f32_16x16x32_bf16 v[12:15], v[146:149], v[202:205], v[12:15]
	v_mfma_f32_16x16x32_bf16 v[8:11], v[154:157], v[202:205], v[8:11]
	v_mfma_f32_16x16x32_bf16 v[60:63], v[150:153], v[178:181], v[60:63]
	v_mfma_f32_16x16x32_bf16 v[56:59], v[158:161], v[178:181], v[56:59]
	v_mfma_f32_16x16x32_bf16 v[44:47], v[150:153], v[186:189], v[44:47]
	v_mfma_f32_16x16x32_bf16 v[40:43], v[158:161], v[186:189], v[40:43]
	v_mfma_f32_16x16x32_bf16 v[28:31], v[150:153], v[194:197], v[28:31]
	v_mfma_f32_16x16x32_bf16 v[24:27], v[158:161], v[194:197], v[24:27]
	v_mfma_f32_16x16x32_bf16 v[12:15], v[150:153], v[206:209], v[12:15]
	v_mfma_f32_16x16x32_bf16 v[8:11], v[158:161], v[206:209], v[8:11]
	s_setprio 0
	s_barrier
	s_add_u32 s4, s4, 0x40080
	s_addc_u32 s5, s5, 0
	s_add_i32 s6, s6, s44
	s_mov_b32 m0, s6
	s_nop 0
	global_load_lds_dwordx4 v130, s[4:5]
	s_add_i32 m0, s6, 0x2000
	s_nop 0
	global_load_lds_dwordx4 v134, s[4:5]
	s_waitcnt vmcnt(10)
	s_barrier
	s_setprio 1
	v_mfma_f32_16x16x32_bf16 v[52:55], v[210:213], v[162:165], v[52:55]
	v_mfma_f32_16x16x32_bf16 v[48:51], v[218:221], v[162:165], v[48:51]
	v_mfma_f32_16x16x32_bf16 v[36:39], v[210:213], v[182:185], v[36:39]
	v_mfma_f32_16x16x32_bf16 v[32:35], v[218:221], v[182:185], v[32:35]
	v_mfma_f32_16x16x32_bf16 v[20:23], v[210:213], v[190:193], v[20:23]
	v_mfma_f32_16x16x32_bf16 v[16:19], v[218:221], v[190:193], v[16:19]
	v_mfma_f32_16x16x32_bf16 v[4:7], v[210:213], v[202:205], v[4:7]
	v_mfma_f32_16x16x32_bf16 v[0:3], v[218:221], v[202:205], v[0:3]
	v_mfma_f32_16x16x32_bf16 v[52:55], v[214:217], v[178:181], v[52:55]
	v_mfma_f32_16x16x32_bf16 v[48:51], v[222:225], v[178:181], v[48:51]
	v_mfma_f32_16x16x32_bf16 v[36:39], v[214:217], v[186:189], v[36:39]
	v_mfma_f32_16x16x32_bf16 v[32:35], v[222:225], v[186:189], v[32:35]
	v_mfma_f32_16x16x32_bf16 v[20:23], v[214:217], v[194:197], v[20:23]
	v_mfma_f32_16x16x32_bf16 v[16:19], v[222:225], v[194:197], v[16:19]
	v_mfma_f32_16x16x32_bf16 v[4:7], v[214:217], v[206:209], v[4:7]
	v_mfma_f32_16x16x32_bf16 v[0:3], v[222:225], v[206:209], v[0:3]
	s_setprio 0
	s_add_i32 s67, s67, 2
	s_add_u32 s0, s0, 0x100
	s_addc_u32 s1, s1, 0
	s_add_u32 s65, s65, 0x100
	s_addc_u32 s66, s66, 0
	s_cmp_gt_u32 s67, 13
	s_cbranch_scc1 .Lconc_last_g3
	s_barrier
	s_branch .LBB0_613
.Lconc_last_g3:
	v_readfirstlane_b32 s0, v200
	s_nop 3
	s_cmp_gt_u32 s0, 0xff
	s_cbranch_scc1 .Lconc_epi1_g3
	s_barrier
	v_mov_b32_e32 v136, v169
	v_mov_b32_e32 v150, v168
	s_lshl_b32 s0, s33, 8
	global_load_dword v154, v137, s[22:23]
	global_load_dword v155, v137, s[22:23] offset:16
	s_or_b32 s0, s0, s53
	v_lshlrev_b32_e32 v151, 3, v136
	v_ashrrev_i32_e32 v136, 1, v150
	v_add_u32_e32 v162, s0, v151
	v_bfi_b32 v136, -4, v136, v150
	v_lshrrev_b32_e32 v146, 2, v162
	v_add_u32_e32 v192, 0x400, v136
	v_and_b32_e32 v187, 0x1f0, v146
	v_add_u32_e32 v146, v192, v187
	v_add_u32_e32 v148, v187, v136
	v_ashrrev_i32_e32 v147, 31, v146
	v_ashrrev_i32_e32 v149, 31, v148
	v_lshl_add_u64 v[146:147], v[146:147], 2, s[16:17]
	v_lshl_add_u64 v[148:149], v[148:149], 2, s[16:17]
	global_load_dword v153, v[146:147], off
	global_load_dword v166, v[148:149], off
	v_and_b32_e32 v157, 64, v174
	v_xor_b32_e32 v156, 4, v174
	v_add_u32_e32 v157, 64, v157
	v_cmp_lt_i32_e32 vcc, v156, v157
	v_mov_b32_e32 v152, v124
	v_add_u32_e32 v151, s53, v151
	v_cndmask_b32_e32 v156, v174, v156, vcc
	v_lshlrev_b32_e32 v177, 2, v156
	ds_bpermute_b32 v124, v177, v124
	v_sub_u32_e32 v156, 0x7f, v151
	v_add_u32_e32 v164, s52, v150
	v_and_b32_e32 v150, 4, v150
	v_cvt_f32_i32_e32 v179, v156
	v_cvt_f32_i32_e32 v178, v151
	v_cmp_eq_u32_e32 vcc, 0, v150
	ds_bpermute_b32 v157, v177, v125
	ds_bpermute_b32 v158, v177, v127
	s_waitcnt lgkmcnt(0)
	v_cndmask_b32_e64 v167, v124, -v124, vcc
	ds_bpermute_b32 v151, v177, v126
	v_ashrrev_i32_e32 v165, 31, v164
	v_and_b32_e32 v186, 56, v162
	s_waitcnt lgkmcnt(0)
	v_cndmask_b32_e64 v151, v151, -v151, vcc
	s_waitcnt vmcnt(0)
	v_mul_f32_e32 v124, 0x3fb8aa3b, v154
	v_mul_f32_e32 v150, 0x3fb8aa3b, v155
	v_cmp_lt_f32_e64 s[4:5], s60, v124
	v_mul_f32_e32 v156, v124, v179
	v_cmp_gt_f32_e64 s[6:7], s59, v150
	v_cndmask_b32_e64 v159, 0, v176, s[4:5]
	v_mul_f32_e32 v160, v150, v178
	v_cndmask_b32_e64 v161, 0, v176, s[6:7]
	v_cmp_gt_f32_e64 s[8:9], s59, v156
	v_fmac_f32_e32 v159, 0xbfb8aa3b, v154
	s_and_b64 s[0:1], s[4:5], exec
	v_cmp_gt_f32_e64 s[4:5], s59, v160
	v_fmac_f32_e32 v161, 0x3fb8aa3b, v155
	v_cndmask_b32_e64 v154, 0, v176, s[8:9]
	v_exp_f32_e32 v155, v159
	v_cndmask_b32_e64 v159, 0, v176, s[4:5]
	v_fmac_f32_e32 v154, v124, v179
	v_fmac_f32_e32 v159, v150, v178
	v_exp_f32_e32 v150, v154
	v_cndmask_b32_e64 v156, 0, v175, s[8:9]
	s_cselect_b32 s8, 0xffffffc0, 0
	v_exp_f32_e32 v161, v161
	v_exp_f32_e32 v159, v159
	v_ldexp_f32 v163, v155, s8
	v_pk_mul_f32 v[154:155], v[152:153], v[166:167]
	v_cndmask_b32_e64 v167, v157, -v157, vcc
	v_mov_b32_e32 v152, v125
	s_and_b64 s[0:1], s[6:7], exec
	v_add_f32_e32 v190, v154, v155
	v_pk_mul_f32 v[154:155], v[152:153], v[166:167]
	v_cndmask_b32_e64 v167, v158, -v158, vcc
	v_mov_b32_e32 v152, v127
	v_cndmask_b32_e64 v160, 0, v175, s[4:5]
	s_cselect_b32 s0, 0xffffffc0, 0
	v_ldexp_f32 v180, v150, v156
	v_add_f32_e32 v191, v154, v155
	v_pk_mul_f32 v[154:155], v[152:153], v[166:167]
	v_ldexp_f32 v124, v161, s0
	v_mul_f32_e32 v161, v126, v166
	v_ldexp_f32 v150, v159, v160
	v_mul_f32_e32 v181, v163, v180
	v_add_f32_e32 v193, v154, v155
	global_load_dword v188, v[148:149], off
	global_load_dword v157, v[146:147], off
	ds_bpermute_b32 v127, v177, v121
	v_mov_b32_e32 v156, v121
	ds_bpermute_b32 v121, v177, v123
	ds_bpermute_b32 v125, v177, v120
	ds_bpermute_b32 v152, v177, v122
	s_waitcnt lgkmcnt(3)
;     __device__ __forceinline__ void operator()(const AccT& acc, const Unit& u, int wr, int wc, int fr, int fq) const {
;     ...
;                 const int r = rbase + ai * 128 + m * 16;
;                 const int d = 4 * (2 * m + (fr >> 3)) + j;
; #pragma unroll
;                 for (int bj = 0; bj < 2; ++bj) {
;                     const int t0 = tb + bj * 128;
;                     float v[8];
; #pragma unroll
;                     for (int jj = 0; jj < 4; ++jj) { v[jj] = acc[ai][bj][m][0][jj]; v[4 + jj] = acc[ai][bj][m][1][jj]; }
;                     if constexpr (ROPE) {
;                         const int t = t0 & 2047;
; #pragma unroll
;                         for (int hf = 0; hf < 2; ++hf) {
;                             f32x4 cs, sn;
;                             if (m < 2) { const float c1 = ropeA[(t >> 6) * 16 + d], s1 = ropeA[1024 + (t >> 6) * 16 + d]; cs = (f32x4){c1, c1, c1, c1}; sn = (f32x4){s1, s1, s1, s1}; }
;                             else { const float* cb = ropeA + 2048 + (d - 16) * 64 + (t & 63) + 4 * hf; cs = *(const f32x4*)(cb); sn = *(const f32x4*)(cb + 1024); }
; #pragma unroll
;                             for (int jj = 0; jj < 4; ++jj) { const float pr = __shfl_xor(v[4 * hf + jj], 4); v[4 * hf + jj] = v[4 * hf + jj] * cs[jj] + sgn * pr * sn[jj]; }
;                             __builtin_amdgcn_sched_barrier(0);
;                         }
;                     }
;                     float zf[8], zb[8]; zf[0] = zf0; zb[0] = zb0;
; #pragma unroll
;                     for (int jj = 1; jj < 8; ++jj) { zf[jj] = zf[jj - 1] * zfs; zb[jj] = zb[jj - 1] * zbs; }
;                     u32x4 wf, wb;
;                     wf.x = cvt_pk_bf16(v[0] * zf[0], v[1] * zf[1]); wf.y = cvt_pk_bf16(v[2] * zf[2], v[3] * zf[3]); wf.z = cvt_pk_bf16(v[4] * zf[4], v[5] * zf[5]); wf.w = cvt_pk_bf16(v[6] * zf[6], v[7] * zf[7]);
;                     wb.x = cvt_pk_bf16(v[0] * zb[0], v[1] * zb[1]); wb.y = cvt_pk_bf16(v[2] * zb[2], v[3] * zb[3]); wb.z = cvt_pk_bf16(v[4] * zb[4], v[5] * zb[5]); wb.w = cvt_pk_bf16(v[6] * zb[6], v[7] * zb[7]);
;                     *(u32x4*)(KTZ + (size_t)r * NT + t0) = wf;
;                     *(u32x4*)(KTZ + (size_t)(256 + r) * NT + t0) = wb;
;                     __builtin_amdgcn_sched_barrier(0);
	v_cndmask_b32_e64 v189, v127, -v127, vcc
	s_waitcnt lgkmcnt(1)
	v_cndmask_b32_e64 v158, v125, -v125, vcc
	s_waitcnt lgkmcnt(0)
	v_cndmask_b32_e64 v127, v152, -v152, vcc
	s_waitcnt vmcnt(1)
	v_mul_f32_e32 v159, v120, v188
	s_waitcnt vmcnt(0)
	v_pk_mul_f32 v[154:155], v[156:157], v[188:189]
	v_cndmask_b32_e64 v189, v121, -v121, vcc
	v_mov_b32_e32 v156, v123
	v_add_f32_e32 v121, v154, v155
	v_pk_mul_f32 v[154:155], v[156:157], v[188:189]
	s_nop 0
	v_add_f32_e32 v123, v154, v155
	v_mov_b32_e32 v125, v153
	v_pk_mul_f32 v[152:153], v[124:125], v[150:151]
	v_mov_b32_e32 v125, v161
	v_pk_mul_f32 v[154:155], v[124:125], v[152:153]
	v_mov_b32_e32 v125, v157
	v_mov_b32_e32 v155, v158
	v_pk_mul_f32 v[156:157], v[124:125], v[154:155]
	v_mov_b32_e32 v158, v124
	v_pk_mul_f32 v[158:159], v[158:159], v[156:157]
	v_mul_f32_e32 v167, v163, v181
	v_mov_b32_e32 v159, v127
	v_mul_f32_e32 v183, v163, v167
	v_pk_mul_f32 v[160:161], v[124:125], v[158:159]
	v_mul_f32_e32 v182, v163, v183
	v_mul_f32_e32 v151, v124, v160
	v_mul_f32_e32 v185, v163, v182
	v_mul_f32_e32 v155, v124, v151
	v_mul_f32_e32 v124, v180, v190
	v_mul_f32_e32 v125, v181, v191
	v_fma_f32 v153, v126, v166, v153
	v_mul_f32_e32 v184, v163, v185
	v_cvt_pk_bf16_f32 v124, v124, v125
	v_mul_f32_e32 v125, v167, v153
	v_mul_f32_e32 v126, v183, v193
	v_fma_f32 v120, v120, v188, v157
	v_mul_f32_e32 v159, v163, v184
	v_cvt_pk_bf16_f32 v125, v125, v126
	v_mul_f32_e32 v126, v182, v120
	v_mul_f32_e32 v127, v185, v121
	v_fma_f32 v122, v122, v188, v161
	v_cvt_pk_bf16_f32 v126, v126, v127
	v_mul_f32_e32 v127, v184, v122
	v_mul_f32_e32 v157, v159, v123
	v_cvt_pk_bf16_f32 v127, v127, v157
	v_mul_f32_e32 v157, v150, v190
	v_mul_f32_e32 v120, v158, v120
	v_mul_f32_e32 v121, v160, v121
	v_mul_f32_e32 v161, v152, v191
	v_cvt_pk_bf16_f32 v188, v157, v161
	v_mul_f32_e32 v153, v154, v153
	v_mul_f32_e32 v157, v156, v193
	v_cvt_pk_bf16_f32 v189, v153, v157
	v_cvt_pk_bf16_f32 v190, v120, v121
	v_mul_f32_e32 v120, v151, v122
	v_mul_f32_e32 v121, v155, v123
	v_cvt_pk_bf16_f32 v191, v120, v121
	v_lshlrev_b64 v[120:121], 17, v[164:165]
	v_lshl_add_u64 v[120:121], s[80:81], 0, v[120:121]
	v_ashrrev_i32_e32 v163, 31, v162
	v_lshl_add_u64 v[120:121], v[162:163], 1, v[120:121]
	s_mov_b64 s[0:1], 0x2000000
	global_store_dwordx4 v[120:121], v[124:127], off
	s_nop 1
	v_lshl_add_u64 v[126:127], v[120:121], 0, s[0:1]
	s_brev_b32 s0, 64
	v_add_co_u32_e64 v122, s[4:5], s0, v120
	s_nop 1
	v_addc_co_u32_e64 v123, s[4:5], 0, v121, s[4:5]
	global_store_dwordx4 v[122:123], v[188:191], off
	v_add_u32_e32 v122, 0x80, v162
	v_lshrrev_b32_e32 v122, 2, v122
	v_and_b32_e32 v153, 0x1f0, v122
	v_add_u32_e32 v122, v153, v192
	v_add_u32_e32 v124, v153, v136
	v_ashrrev_i32_e32 v123, 31, v122
	v_ashrrev_i32_e32 v125, 31, v124
	v_lshl_add_u64 v[122:123], v[122:123], 2, s[16:17]
	v_lshl_add_u64 v[124:125], v[124:125], 2, s[16:17]
	global_load_dword v163, v[122:123], off
	global_load_dword v164, v[124:125], off
	ds_bpermute_b32 v157, v177, v116
	v_mov_b32_e32 v162, v116
	ds_bpermute_b32 v116, v177, v117
	ds_bpermute_b32 v161, v177, v118
	ds_bpermute_b32 v166, v177, v119
	s_waitcnt lgkmcnt(3)
	v_cndmask_b32_e64 v165, v157, -v157, vcc
	s_waitcnt vmcnt(0)
	v_pk_mul_f32 v[188:189], v[162:163], v[164:165]
	s_waitcnt lgkmcnt(2)
	v_cndmask_b32_e64 v165, v116, -v116, vcc
	v_mov_b32_e32 v162, v117
	v_pk_mul_f32 v[116:117], v[162:163], v[164:165]
	s_waitcnt lgkmcnt(1)
	v_cndmask_b32_e64 v165, v161, -v161, vcc
	v_mov_b32_e32 v162, v118
	v_add_f32_e32 v161, v116, v117
	v_pk_mul_f32 v[116:117], v[162:163], v[164:165]
	s_waitcnt lgkmcnt(0)
	v_cndmask_b32_e64 v165, v166, -v166, vcc
	v_mov_b32_e32 v162, v119
	v_add_f32_e32 v166, v116, v117
	v_pk_mul_f32 v[116:117], v[162:163], v[164:165]
	v_add_f32_e32 v157, v188, v189
	v_add_f32_e32 v164, v116, v117
	global_load_dword v117, v[122:123], off
	global_load_dword v118, v[124:125], off
	ds_bpermute_b32 v119, v177, v112
	v_mov_b32_e32 v116, v112
	ds_bpermute_b32 v112, v177, v113
	ds_bpermute_b32 v165, v177, v114
	ds_bpermute_b32 v188, v177, v115
	s_waitcnt lgkmcnt(3)
	v_cndmask_b32_e64 v119, v119, -v119, vcc
	s_waitcnt vmcnt(0)
	v_pk_mul_f32 v[162:163], v[116:117], v[118:119]
	s_waitcnt lgkmcnt(2)
	v_cndmask_b32_e64 v119, v112, -v112, vcc
	v_mov_b32_e32 v116, v113
	v_pk_mul_f32 v[112:113], v[116:117], v[118:119]
	s_waitcnt lgkmcnt(1)
	v_cndmask_b32_e64 v119, v165, -v165, vcc
	v_mov_b32_e32 v116, v114
	v_add_f32_e32 v162, v162, v163
	v_add_f32_e32 v163, v112, v113
	v_pk_mul_f32 v[112:113], v[116:117], v[118:119]
	s_waitcnt lgkmcnt(0)
	v_cndmask_b32_e64 v119, v188, -v188, vcc
	v_mov_b32_e32 v116, v115
	v_add_f32_e32 v165, v112, v113
	v_pk_mul_f32 v[112:113], v[116:117], v[118:119]
	s_nop 0
	v_add_f32_e32 v119, v112, v113
	v_mul_f32_e32 v112, v180, v157
	v_mul_f32_e32 v113, v181, v161
	v_cvt_pk_bf16_f32 v112, v112, v113
	v_mul_f32_e32 v113, v167, v166
	v_mul_f32_e32 v114, v183, v164
	v_cvt_pk_bf16_f32 v113, v113, v114
	v_mul_f32_e32 v114, v182, v162
	v_mul_f32_e32 v115, v185, v163
	v_cvt_pk_bf16_f32 v114, v114, v115
	v_mul_f32_e32 v115, v184, v165
	v_mul_f32_e32 v116, v159, v119
	v_cvt_pk_bf16_f32 v115, v115, v116
	v_mul_f32_e32 v116, v150, v157
	v_mul_f32_e32 v117, v152, v161
	v_cvt_pk_bf16_f32 v116, v116, v117
	v_mul_f32_e32 v117, v154, v166
	v_mul_f32_e32 v118, v156, v164
	v_cvt_pk_bf16_f32 v117, v117, v118
	v_mul_f32_e32 v118, v158, v162
	v_mul_f32_e32 v157, v160, v163
	v_mul_f32_e32 v119, v155, v119
	v_cvt_pk_bf16_f32 v118, v118, v157
	v_mul_f32_e32 v157, v151, v165
	v_cvt_pk_bf16_f32 v119, v157, v119
	global_store_dwordx4 v[120:121], v[112:115], off offset:256
	global_store_dwordx4 v[126:127], v[116:119], off offset:256
	v_add_u32_e32 v161, 0x408, v136
	v_add_u32_e32 v157, 8, v136
	v_add_u32_e32 v112, v161, v187
	v_add_u32_e32 v114, v187, v157
	v_ashrrev_i32_e32 v113, 31, v112
	v_ashrrev_i32_e32 v115, 31, v114
	v_lshl_add_u64 v[112:113], v[112:113], 2, s[16:17]
	v_lshl_add_u64 v[114:115], v[114:115], 2, s[16:17]
	global_load_dword v117, v[112:113], off
	global_load_dword v118, v[114:115], off
	ds_bpermute_b32 v119, v177, v108
	v_mov_b32_e32 v116, v108
	ds_bpermute_b32 v108, v177, v109
	ds_bpermute_b32 v162, v177, v110
	ds_bpermute_b32 v163, v177, v111
	s_waitcnt lgkmcnt(3)
;     __device__ __forceinline__ void operator()(const AccT& acc, const Unit& u, int wr, int wc, int fr, int fq) const {
;     ...
;                 const int r = rbase + ai * 128 + m * 16;
;                 const int d = 4 * (2 * m + (fr >> 3)) + j;
; #pragma unroll
;                 for (int bj = 0; bj < 2; ++bj) {
;                     const int t0 = tb + bj * 128;
;                     float v[8];
; #pragma unroll
;                     for (int jj = 0; jj < 4; ++jj) { v[jj] = acc[ai][bj][m][0][jj]; v[4 + jj] = acc[ai][bj][m][1][jj]; }
;                     if constexpr (ROPE) {
;                         const int t = t0 & 2047;
; #pragma unroll
;                         for (int hf = 0; hf < 2; ++hf) {
;                             f32x4 cs, sn;
;                             if (m < 2) { const float c1 = ropeA[(t >> 6) * 16 + d], s1 = ropeA[1024 + (t >> 6) * 16 + d]; cs = (f32x4){c1, c1, c1, c1}; sn = (f32x4){s1, s1, s1, s1}; }
;                             else { const float* cb = ropeA + 2048 + (d - 16) * 64 + (t & 63) + 4 * hf; cs = *(const f32x4*)(cb); sn = *(const f32x4*)(cb + 1024); }
; #pragma unroll
;                             for (int jj = 0; jj < 4; ++jj) { const float pr = __shfl_xor(v[4 * hf + jj], 4); v[4 * hf + jj] = v[4 * hf + jj] * cs[jj] + sgn * pr * sn[jj]; }
;                             __builtin_amdgcn_sched_barrier(0);
;                         }
;                     }
;                     float zf[8], zb[8]; zf[0] = zf0; zb[0] = zb0;
; #pragma unroll
;                     for (int jj = 1; jj < 8; ++jj) { zf[jj] = zf[jj - 1] * zfs; zb[jj] = zb[jj - 1] * zbs; }
;                     u32x4 wf, wb;
;                     wf.x = cvt_pk_bf16(v[0] * zf[0], v[1] * zf[1]); wf.y = cvt_pk_bf16(v[2] * zf[2], v[3] * zf[3]); wf.z = cvt_pk_bf16(v[4] * zf[4], v[5] * zf[5]); wf.w = cvt_pk_bf16(v[6] * zf[6], v[7] * zf[7]);
;                     wb.x = cvt_pk_bf16(v[0] * zb[0], v[1] * zb[1]); wb.y = cvt_pk_bf16(v[2] * zb[2], v[3] * zb[3]); wb.z = cvt_pk_bf16(v[4] * zb[4], v[5] * zb[5]); wb.w = cvt_pk_bf16(v[6] * zb[6], v[7] * zb[7]);
;                     *(u32x4*)(KTZ + (size_t)r * NT + t0) = wf;
;                     *(u32x4*)(KTZ + (size_t)(256 + r) * NT + t0) = wb;
;                     __builtin_amdgcn_sched_barrier(0);
	v_cndmask_b32_e64 v119, v119, -v119, vcc
	s_waitcnt vmcnt(0)
	v_pk_mul_f32 v[126:127], v[116:117], v[118:119]
	s_waitcnt lgkmcnt(2)
	v_cndmask_b32_e64 v119, v108, -v108, vcc
	v_mov_b32_e32 v116, v109
	v_pk_mul_f32 v[108:109], v[116:117], v[118:119]
	s_waitcnt lgkmcnt(1)
	v_cndmask_b32_e64 v119, v162, -v162, vcc
	v_mov_b32_e32 v116, v110
	v_add_f32_e32 v126, v126, v127
	v_add_f32_e32 v127, v108, v109
	v_pk_mul_f32 v[108:109], v[116:117], v[118:119]
	s_waitcnt lgkmcnt(0)
	v_cndmask_b32_e64 v119, v163, -v163, vcc
	v_mov_b32_e32 v116, v111
	v_add_f32_e32 v162, v108, v109
	v_pk_mul_f32 v[108:109], v[116:117], v[118:119]
	s_nop 0
	v_add_f32_e32 v118, v108, v109
	global_load_dword v109, v[112:113], off
	global_load_dword v110, v[114:115], off
	ds_bpermute_b32 v111, v177, v104
	v_mov_b32_e32 v108, v104
	ds_bpermute_b32 v104, v177, v105
	ds_bpermute_b32 v119, v177, v106
	ds_bpermute_b32 v163, v177, v107
	s_waitcnt lgkmcnt(3)
	v_cndmask_b32_e64 v111, v111, -v111, vcc
	s_waitcnt vmcnt(0)
	v_pk_mul_f32 v[116:117], v[108:109], v[110:111]
	s_waitcnt lgkmcnt(2)
	v_cndmask_b32_e64 v111, v104, -v104, vcc
	v_mov_b32_e32 v108, v105
	v_pk_mul_f32 v[104:105], v[108:109], v[110:111]
	s_waitcnt lgkmcnt(1)
	v_cndmask_b32_e64 v111, v119, -v119, vcc
	v_mov_b32_e32 v108, v106
	v_add_f32_e32 v119, v104, v105
	v_pk_mul_f32 v[104:105], v[108:109], v[110:111]
	s_waitcnt lgkmcnt(0)
	v_cndmask_b32_e64 v111, v163, -v163, vcc
	v_mov_b32_e32 v108, v107
	v_add_f32_e32 v163, v104, v105
	v_pk_mul_f32 v[104:105], v[108:109], v[110:111]
	v_add_f32_e32 v164, v116, v117
	v_add_f32_e32 v108, v104, v105
	v_mul_f32_e32 v104, v180, v126
	v_mul_f32_e32 v105, v181, v127
	v_cvt_pk_bf16_f32 v104, v104, v105
	v_mul_f32_e32 v105, v167, v162
	v_mul_f32_e32 v106, v183, v118
	v_cvt_pk_bf16_f32 v105, v105, v106
	v_mul_f32_e32 v106, v182, v164
	v_mul_f32_e32 v107, v185, v119
	v_cvt_pk_bf16_f32 v106, v106, v107
	v_mul_f32_e32 v107, v184, v163
	v_mul_f32_e32 v109, v159, v108
	v_cvt_pk_bf16_f32 v107, v107, v109
	v_mul_f32_e32 v109, v150, v126
	v_mul_f32_e32 v110, v152, v127
	v_cvt_pk_bf16_f32 v116, v109, v110
	v_mul_f32_e32 v109, v154, v162
	v_mul_f32_e32 v110, v156, v118
	v_cvt_pk_bf16_f32 v117, v109, v110
	v_mul_f32_e32 v109, v158, v164
	v_mul_f32_e32 v110, v160, v119
	v_cvt_pk_bf16_f32 v118, v109, v110
	v_mul_f32_e32 v109, v151, v163
	v_mul_f32_e32 v108, v155, v108
	s_mov_b64 s[0:1], 0x200000
	v_cvt_pk_bf16_f32 v119, v109, v108
	v_lshl_add_u64 v[108:109], v[120:121], 0, s[0:1]
	s_mov_b32 s0, 0x200000
	v_add_co_u32_e64 v110, s[4:5], s0, v120
	s_mov_b64 s[0:1], 0x2200000
	s_nop 0
	v_addc_co_u32_e64 v111, s[4:5], 0, v121, s[4:5]
	global_store_dwordx4 v[110:111], v[104:107], off
	v_lshl_add_u64 v[110:111], v[120:121], 0, s[0:1]
	s_mov_b32 s0, 0x2200000
	v_add_co_u32_e64 v104, s[4:5], s0, v120
	s_nop 1
	v_addc_co_u32_e64 v105, s[4:5], 0, v121, s[4:5]
	global_store_dwordx4 v[104:105], v[116:119], off
	v_add_u32_e32 v104, v153, v161
	v_add_u32_e32 v106, v153, v157
	v_ashrrev_i32_e32 v105, 31, v104
	v_ashrrev_i32_e32 v107, 31, v106
	v_lshl_add_u64 v[104:105], v[104:105], 2, s[16:17]
	v_lshl_add_u64 v[106:107], v[106:107], 2, s[16:17]
	global_load_dword v117, v[104:105], off
	global_load_dword v118, v[106:107], off
	ds_bpermute_b32 v119, v177, v100
	v_mov_b32_e32 v116, v100
	ds_bpermute_b32 v100, v177, v101
	ds_bpermute_b32 v153, v177, v102
	ds_bpermute_b32 v157, v177, v103
	s_waitcnt lgkmcnt(3)
	v_cndmask_b32_e64 v119, v119, -v119, vcc
	s_waitcnt vmcnt(0)
	v_pk_mul_f32 v[126:127], v[116:117], v[118:119]
	s_waitcnt lgkmcnt(2)
	v_cndmask_b32_e64 v119, v100, -v100, vcc
	v_mov_b32_e32 v116, v101
	v_pk_mul_f32 v[100:101], v[116:117], v[118:119]
	s_waitcnt lgkmcnt(1)
	v_cndmask_b32_e64 v119, v153, -v153, vcc
	v_mov_b32_e32 v116, v102
	v_add_f32_e32 v126, v126, v127
	v_add_f32_e32 v127, v100, v101
	v_pk_mul_f32 v[100:101], v[116:117], v[118:119]
	s_waitcnt lgkmcnt(0)
	v_cndmask_b32_e64 v119, v157, -v157, vcc
	v_mov_b32_e32 v116, v103
	v_add_f32_e32 v153, v100, v101
	v_pk_mul_f32 v[100:101], v[116:117], v[118:119]
	s_nop 0
	v_add_f32_e32 v118, v100, v101
	global_load_dword v101, v[104:105], off
	global_load_dword v102, v[106:107], off
	ds_bpermute_b32 v103, v177, v96
	v_mov_b32_e32 v100, v96
	ds_bpermute_b32 v96, v177, v97
	ds_bpermute_b32 v119, v177, v98
	ds_bpermute_b32 v157, v177, v99
	s_waitcnt lgkmcnt(3)
	v_cndmask_b32_e64 v103, v103, -v103, vcc
	s_waitcnt vmcnt(0)
	v_pk_mul_f32 v[116:117], v[100:101], v[102:103]
	s_waitcnt lgkmcnt(2)
	v_cndmask_b32_e64 v103, v96, -v96, vcc
	v_mov_b32_e32 v100, v97
	v_pk_mul_f32 v[96:97], v[100:101], v[102:103]
	s_waitcnt lgkmcnt(1)
	v_cndmask_b32_e64 v103, v119, -v119, vcc
	v_mov_b32_e32 v100, v98
	v_add_f32_e32 v116, v116, v117
	v_add_f32_e32 v117, v96, v97
	v_pk_mul_f32 v[96:97], v[100:101], v[102:103]
	s_waitcnt lgkmcnt(0)
; __device__ __forceinline__ unsigned cvt_pk_bf16(float lo, float hi) { unsigned r; asm volatile("v_cvt_pk_bf16_f32 %0, %1, %2" : "=v"(r) : "v"(lo), "v"(hi)); return r; }
;     __device__ __forceinline__ void operator()(const AccT& acc, const Unit& u, int wr, int wc, int fr, int fq) const {
;     ...
;                         const int t = t0 & 2047;
; #pragma unroll
;                         for (int hf = 0; hf < 2; ++hf) {
;                             f32x4 cs, sn;
;                             if (m < 2) { const float c1 = ropeA[(t >> 6) * 16 + d], s1 = ropeA[1024 + (t >> 6) * 16 + d]; cs = (f32x4){c1, c1, c1, c1}; sn = (f32x4){s1, s1, s1, s1}; }
;                             else { const float* cb = ropeA + 2048 + (d - 16) * 64 + (t & 63) + 4 * hf; cs = *(const f32x4*)(cb); sn = *(const f32x4*)(cb + 1024); }
; #pragma unroll
;                             for (int jj = 0; jj < 4; ++jj) { const float pr = __shfl_xor(v[4 * hf + jj], 4); v[4 * hf + jj] = v[4 * hf + jj] * cs[jj] + sgn * pr * sn[jj]; }
;                             __builtin_amdgcn_sched_barrier(0);
;                         }
;                     }
;                     float zf[8], zb[8]; zf[0] = zf0; zb[0] = zb0;
; #pragma unroll
;                     for (int jj = 1; jj < 8; ++jj) { zf[jj] = zf[jj - 1] * zfs; zb[jj] = zb[jj - 1] * zbs; }
;                     u32x4 wf, wb;
;                     wf.x = cvt_pk_bf16(v[0] * zf[0], v[1] * zf[1]); wf.y = cvt_pk_bf16(v[2] * zf[2], v[3] * zf[3]); wf.z = cvt_pk_bf16(v[4] * zf[4], v[5] * zf[5]); wf.w = cvt_pk_bf16(v[6] * zf[6], v[7] * zf[7]);
;                     wb.x = cvt_pk_bf16(v[0] * zb[0], v[1] * zb[1]); wb.y = cvt_pk_bf16(v[2] * zb[2], v[3] * zb[3]); wb.z = cvt_pk_bf16(v[4] * zb[4], v[5] * zb[5]); wb.w = cvt_pk_bf16(v[6] * zb[6], v[7] * zb[7]);
;                     *(u32x4*)(KTZ + (size_t)r * NT + t0) = wf;
;                     *(u32x4*)(KTZ + (size_t)(256 + r) * NT + t0) = wb;
;                     __builtin_amdgcn_sched_barrier(0);
	v_cndmask_b32_e64 v103, v157, -v157, vcc
	v_mov_b32_e32 v100, v99
	v_add_f32_e32 v119, v96, v97
	v_pk_mul_f32 v[96:97], v[100:101], v[102:103]
	s_nop 0
	v_add_f32_e32 v103, v96, v97
	v_mul_f32_e32 v96, v180, v126
	v_mul_f32_e32 v97, v181, v127
	v_cvt_pk_bf16_f32 v96, v96, v97
	v_mul_f32_e32 v97, v167, v153
	v_mul_f32_e32 v98, v183, v118
	v_cvt_pk_bf16_f32 v97, v97, v98
	v_mul_f32_e32 v98, v182, v116
	v_mul_f32_e32 v99, v185, v117
	v_cvt_pk_bf16_f32 v98, v98, v99
	v_mul_f32_e32 v99, v184, v119
	v_mul_f32_e32 v100, v159, v103
	v_cvt_pk_bf16_f32 v99, v99, v100
	v_mul_f32_e32 v100, v150, v126
	v_mul_f32_e32 v101, v152, v127
	v_cvt_pk_bf16_f32 v100, v100, v101
	v_mul_f32_e32 v101, v154, v153
	v_mul_f32_e32 v102, v156, v118
	v_cvt_pk_bf16_f32 v101, v101, v102
	v_mul_f32_e32 v102, v158, v116
	v_mul_f32_e32 v116, v160, v117
	v_mul_f32_e32 v103, v155, v103
	v_cvt_pk_bf16_f32 v102, v102, v116
	v_mul_f32_e32 v116, v151, v119
	v_cvt_pk_bf16_f32 v103, v116, v103
	global_store_dwordx4 v[108:109], v[96:99], off offset:256
	global_store_dwordx4 v[110:111], v[100:103], off offset:256
	s_nop 1
	v_lshlrev_b32_e32 v100, 6, v136
	v_ashrrev_i32_e32 v101, 31, v100
	v_lshlrev_b64 v[102:103], 2, v[100:101]
	v_lshl_add_u64 v[96:97], s[24:25], 0, v[102:103]
	v_lshlrev_b32_e32 v136, 2, v186
	v_lshl_add_u64 v[96:97], v[96:97], 0, v[136:137]
	v_add_co_u32_e64 v98, s[4:5], s61, v96
	ds_bpermute_b32 v101, v177, v92
	s_nop 0
	v_addc_co_u32_e64 v99, s[4:5], 0, v97, s[4:5]
	global_load_dwordx4 v[108:111], v[98:99], off
	global_load_dwordx4 v[116:119], v[96:97], off
	ds_bpermute_b32 v127, v177, v93
	ds_bpermute_b32 v153, v177, v94
	ds_bpermute_b32 v157, v177, v95
	v_mov_b32_e32 v126, v92
	v_mov_b32_e32 v92, v94
	s_waitcnt lgkmcnt(3)
	v_cndmask_b32_e64 v163, v101, -v101, vcc
	s_waitcnt lgkmcnt(2)
	v_cndmask_b32_e64 v165, v127, -v127, vcc
	s_waitcnt lgkmcnt(1)
	v_cndmask_b32_e64 v187, v153, -v153, vcc
	s_waitcnt lgkmcnt(0)
	v_cndmask_b32_e64 v189, v157, -v157, vcc
	s_waitcnt vmcnt(1)
	v_mov_b32_e32 v127, v108
	s_waitcnt vmcnt(0)
	v_mov_b32_e32 v162, v116
	v_mov_b32_e32 v108, v93
	v_mov_b32_e32 v164, v117
	v_mov_b32_e32 v93, v110
	v_mov_b32_e32 v186, v118
	v_mov_b32_e32 v110, v95
	v_mov_b32_e32 v188, v119
	v_pk_mul_f32 v[94:95], v[126:127], v[162:163]
	v_pk_mul_f32 v[108:109], v[108:109], v[164:165]
	v_pk_mul_f32 v[92:93], v[92:93], v[186:187]
	v_pk_mul_f32 v[110:111], v[110:111], v[188:189]
	v_add_f32_e32 v101, v94, v95
	v_add_f32_e32 v153, v108, v109
	v_add_f32_e32 v157, v92, v93
	v_add_f32_e32 v161, v110, v111
	v_lshl_add_u64 v[92:93], s[16:17], 0, v[102:103]
	v_lshl_add_u64 v[94:95], v[92:93], 0, v[136:137]
	v_add_co_u32_e64 v92, s[4:5], s62, v94
	ds_bpermute_b32 v103, v177, v88
	s_nop 0
	v_addc_co_u32_e64 v93, s[4:5], 0, v95, s[4:5]
	v_add_co_u32_e64 v94, s[4:5], s49, v94
	ds_bpermute_b32 v126, v177, v89
	s_nop 0
	v_addc_co_u32_e64 v95, s[4:5], 0, v95, s[4:5]
	global_load_dwordx4 v[108:111], v[92:93], off offset:16
	global_load_dwordx4 v[116:119], v[94:95], off offset:16
	ds_bpermute_b32 v162, v177, v90
	ds_bpermute_b32 v164, v177, v91
	v_mov_b32_e32 v102, v88
	v_mov_b32_e32 v88, v90
	s_waitcnt lgkmcnt(3)
	v_cndmask_b32_e64 v127, v103, -v103, vcc
	s_waitcnt lgkmcnt(2)
	v_cndmask_b32_e64 v163, v126, -v126, vcc
	s_waitcnt lgkmcnt(1)
	v_cndmask_b32_e64 v165, v162, -v162, vcc
	s_waitcnt lgkmcnt(0)
	v_cndmask_b32_e64 v187, v164, -v164, vcc
	s_waitcnt vmcnt(1)
	v_mov_b32_e32 v103, v108
	s_waitcnt vmcnt(0)
	v_mov_b32_e32 v126, v116
	v_mov_b32_e32 v108, v89
	v_mov_b32_e32 v162, v117
	v_mov_b32_e32 v89, v110
	v_mov_b32_e32 v164, v118
	v_mov_b32_e32 v110, v91
	v_mov_b32_e32 v186, v119
	v_pk_mul_f32 v[90:91], v[102:103], v[126:127]
	v_pk_mul_f32 v[102:103], v[108:109], v[162:163]
	v_pk_mul_f32 v[88:89], v[88:89], v[164:165]
	v_pk_mul_f32 v[108:109], v[110:111], v[186:187]
	v_add_f32_e32 v90, v90, v91
	v_add_f32_e32 v91, v102, v103
	v_add_f32_e32 v88, v88, v89
	v_add_f32_e32 v89, v108, v109
	v_mul_f32_e32 v102, v180, v101
	v_mul_f32_e32 v103, v181, v153
	v_cvt_pk_bf16_f32 v108, v102, v103
	v_mul_f32_e32 v102, v167, v157
	v_mul_f32_e32 v103, v183, v161
	v_cvt_pk_bf16_f32 v109, v102, v103
	v_mul_f32_e32 v102, v182, v90
	v_mul_f32_e32 v103, v185, v91
	v_cvt_pk_bf16_f32 v110, v102, v103
	v_mul_f32_e32 v102, v184, v88
	v_mul_f32_e32 v103, v159, v89
	v_cvt_pk_bf16_f32 v111, v102, v103
	v_mul_f32_e32 v101, v150, v101
	v_mul_f32_e32 v102, v152, v153
	v_mul_f32_e32 v88, v151, v88
	v_mul_f32_e32 v89, v155, v89
	s_mov_b64 s[0:1], 0x400000
	v_cvt_pk_bf16_f32 v116, v101, v102
	v_mul_f32_e32 v101, v154, v157
	v_mul_f32_e32 v102, v156, v161
	v_cvt_pk_bf16_f32 v117, v101, v102
	v_mul_f32_e32 v90, v158, v90
	v_mul_f32_e32 v91, v160, v91
	v_cvt_pk_bf16_f32 v118, v90, v91
	v_cvt_pk_bf16_f32 v119, v88, v89
	v_lshl_add_u64 v[88:89], v[120:121], 0, s[0:1]
	s_mov_b32 s0, 0x400000
	v_add_co_u32_e64 v90, s[4:5], s0, v120
	s_mov_b64 s[0:1], 0x2400000
	s_nop 0
	v_addc_co_u32_e64 v91, s[4:5], 0, v121, s[4:5]
	global_store_dwordx4 v[90:91], v[108:111], off
	v_lshl_add_u64 v[90:91], v[120:121], 0, s[0:1]
	s_mov_b32 s0, 0x2400000
	v_add_co_u32_e64 v102, s[4:5], s0, v120
	s_nop 1
	v_addc_co_u32_e64 v103, s[4:5], 0, v121, s[4:5]
	global_store_dwordx4 v[102:103], v[116:119], off
	global_load_dwordx4 v[108:111], v[98:99], off
	s_nop 0
	global_load_dwordx4 v[116:119], v[96:97], off
	ds_bpermute_b32 v101, v177, v84
	ds_bpermute_b32 v103, v177, v85
	ds_bpermute_b32 v126, v177, v86
	ds_bpermute_b32 v153, v177, v87
	v_mov_b32_e32 v102, v84
	v_mov_b32_e32 v84, v86
	s_waitcnt lgkmcnt(3)
	v_cndmask_b32_e64 v127, v101, -v101, vcc
	s_waitcnt lgkmcnt(2)
	v_cndmask_b32_e64 v163, v103, -v103, vcc
	s_waitcnt lgkmcnt(1)
; __device__ __forceinline__ unsigned cvt_pk_bf16(float lo, float hi) { unsigned r; asm volatile("v_cvt_pk_bf16_f32 %0, %1, %2" : "=v"(r) : "v"(lo), "v"(hi)); return r; }
;     __device__ __forceinline__ void operator()(const AccT& acc, const Unit& u, int wr, int wc, int fr, int fq) const {
;     ...
;                         const int t = t0 & 2047;
; #pragma unroll
;                         for (int hf = 0; hf < 2; ++hf) {
;                             f32x4 cs, sn;
;                             if (m < 2) { const float c1 = ropeA[(t >> 6) * 16 + d], s1 = ropeA[1024 + (t >> 6) * 16 + d]; cs = (f32x4){c1, c1, c1, c1}; sn = (f32x4){s1, s1, s1, s1}; }
;                             else { const float* cb = ropeA + 2048 + (d - 16) * 64 + (t & 63) + 4 * hf; cs = *(const f32x4*)(cb); sn = *(const f32x4*)(cb + 1024); }
; #pragma unroll
;                             for (int jj = 0; jj < 4; ++jj) { const float pr = __shfl_xor(v[4 * hf + jj], 4); v[4 * hf + jj] = v[4 * hf + jj] * cs[jj] + sgn * pr * sn[jj]; }
;                             __builtin_amdgcn_sched_barrier(0);
;                         }
;                     }
;                     float zf[8], zb[8]; zf[0] = zf0; zb[0] = zb0;
; #pragma unroll
;                     for (int jj = 1; jj < 8; ++jj) { zf[jj] = zf[jj - 1] * zfs; zb[jj] = zb[jj - 1] * zbs; }
;                     u32x4 wf, wb;
;                     wf.x = cvt_pk_bf16(v[0] * zf[0], v[1] * zf[1]); wf.y = cvt_pk_bf16(v[2] * zf[2], v[3] * zf[3]); wf.z = cvt_pk_bf16(v[4] * zf[4], v[5] * zf[5]); wf.w = cvt_pk_bf16(v[6] * zf[6], v[7] * zf[7]);
;                     wb.x = cvt_pk_bf16(v[0] * zb[0], v[1] * zb[1]); wb.y = cvt_pk_bf16(v[2] * zb[2], v[3] * zb[3]); wb.z = cvt_pk_bf16(v[4] * zb[4], v[5] * zb[5]); wb.w = cvt_pk_bf16(v[6] * zb[6], v[7] * zb[7]);
;                     *(u32x4*)(KTZ + (size_t)r * NT + t0) = wf;
;                     *(u32x4*)(KTZ + (size_t)(256 + r) * NT + t0) = wb;
;                     __builtin_amdgcn_sched_barrier(0);
	v_cndmask_b32_e64 v165, v126, -v126, vcc
	s_waitcnt lgkmcnt(0)
	v_cndmask_b32_e64 v187, v153, -v153, vcc
	s_waitcnt vmcnt(1)
	v_mov_b32_e32 v103, v108
	s_waitcnt vmcnt(0)
	v_mov_b32_e32 v126, v116
	v_mov_b32_e32 v108, v85
	v_mov_b32_e32 v162, v117
	v_mov_b32_e32 v85, v110
	v_mov_b32_e32 v164, v118
	v_mov_b32_e32 v110, v87
	v_mov_b32_e32 v186, v119
	v_pk_mul_f32 v[86:87], v[102:103], v[126:127]
	v_pk_mul_f32 v[102:103], v[108:109], v[162:163]
	v_pk_mul_f32 v[84:85], v[84:85], v[164:165]
	v_pk_mul_f32 v[108:109], v[110:111], v[186:187]
	v_add_f32_e32 v101, v86, v87
	v_add_f32_e32 v153, v102, v103
	v_add_f32_e32 v157, v84, v85
	v_add_f32_e32 v161, v108, v109
	global_load_dwordx4 v[84:87], v[92:93], off offset:16
	global_load_dwordx4 v[108:111], v[94:95], off offset:16
	ds_bpermute_b32 v103, v177, v80
	ds_bpermute_b32 v116, v177, v81
	ds_bpermute_b32 v118, v177, v82
	ds_bpermute_b32 v126, v177, v83
	v_mov_b32_e32 v102, v80
	v_mov_b32_e32 v80, v82
	s_waitcnt lgkmcnt(3)
	v_cndmask_b32_e64 v117, v103, -v103, vcc
	s_waitcnt lgkmcnt(2)
	v_cndmask_b32_e64 v119, v116, -v116, vcc
	s_waitcnt lgkmcnt(1)
	v_cndmask_b32_e64 v127, v118, -v118, vcc
	s_waitcnt lgkmcnt(0)
	v_cndmask_b32_e64 v163, v126, -v126, vcc
	s_waitcnt vmcnt(1)
	v_mov_b32_e32 v103, v84
	s_waitcnt vmcnt(0)
	v_mov_b32_e32 v116, v108
	v_mov_b32_e32 v84, v81
	v_mov_b32_e32 v118, v109
	v_mov_b32_e32 v81, v86
	v_mov_b32_e32 v126, v110
	v_mov_b32_e32 v86, v83
	v_mov_b32_e32 v162, v111
	v_pk_mul_f32 v[82:83], v[102:103], v[116:117]
	v_pk_mul_f32 v[84:85], v[84:85], v[118:119]
	v_pk_mul_f32 v[80:81], v[80:81], v[126:127]
	v_pk_mul_f32 v[86:87], v[86:87], v[162:163]
	v_add_f32_e32 v102, v82, v83
	v_add_f32_e32 v103, v84, v85
	v_add_f32_e32 v108, v80, v81
	v_add_f32_e32 v87, v86, v87
	v_mul_f32_e32 v80, v180, v101
	v_mul_f32_e32 v81, v181, v153
	v_cvt_pk_bf16_f32 v80, v80, v81
	v_mul_f32_e32 v81, v167, v157
	v_mul_f32_e32 v82, v183, v161
	v_cvt_pk_bf16_f32 v81, v81, v82
	v_mul_f32_e32 v82, v182, v102
	v_mul_f32_e32 v83, v185, v103
	v_cvt_pk_bf16_f32 v82, v82, v83
	v_mul_f32_e32 v83, v184, v108
	v_mul_f32_e32 v84, v159, v87
	v_cvt_pk_bf16_f32 v83, v83, v84
	v_mul_f32_e32 v84, v150, v101
	v_mul_f32_e32 v85, v152, v153
	v_cvt_pk_bf16_f32 v84, v84, v85
	v_mul_f32_e32 v85, v154, v157
	v_mul_f32_e32 v86, v156, v161
	v_cvt_pk_bf16_f32 v85, v85, v86
	v_mul_f32_e32 v86, v158, v102
	v_mul_f32_e32 v101, v160, v103
	v_mul_f32_e32 v87, v155, v87
	v_cvt_pk_bf16_f32 v86, v86, v101
	v_mul_f32_e32 v101, v151, v108
	v_cvt_pk_bf16_f32 v87, v101, v87
	global_store_dwordx4 v[88:89], v[80:83], off offset:256
	global_store_dwordx4 v[90:91], v[84:87], off offset:256
	s_nop 0
	v_add_u32_e32 v80, 0x200, v100
	v_ashrrev_i32_e32 v81, 31, v80
	v_lshl_add_u64 v[82:83], s[24:25], 0, v[136:137]
	v_lshlrev_b64 v[100:101], 2, v[80:81]
	v_lshl_add_u64 v[80:81], v[82:83], 0, v[100:101]
	v_add_co_u32_e64 v82, s[4:5], s61, v80
	ds_bpermute_b32 v103, v177, v76
	s_nop 0
	v_addc_co_u32_e64 v83, s[4:5], 0, v81, s[4:5]
	global_load_dwordx4 v[84:87], v[82:83], off
	global_load_dwordx4 v[88:91], v[80:81], off
	ds_bpermute_b32 v108, v177, v77
	ds_bpermute_b32 v110, v177, v78
	ds_bpermute_b32 v116, v177, v79
	v_mov_b32_e32 v102, v76
	v_mov_b32_e32 v76, v78
	s_waitcnt lgkmcnt(3)
	v_cndmask_b32_e64 v109, v103, -v103, vcc
	s_waitcnt lgkmcnt(2)
	v_cndmask_b32_e64 v111, v108, -v108, vcc
	s_waitcnt lgkmcnt(1)
	v_cndmask_b32_e64 v117, v110, -v110, vcc
	s_waitcnt lgkmcnt(0)
	v_cndmask_b32_e64 v119, v116, -v116, vcc
	s_waitcnt vmcnt(1)
	v_mov_b32_e32 v103, v84
	s_waitcnt vmcnt(0)
	v_mov_b32_e32 v108, v88
	v_mov_b32_e32 v84, v77
	v_mov_b32_e32 v110, v89
	v_mov_b32_e32 v77, v86
	v_mov_b32_e32 v116, v90
	v_mov_b32_e32 v86, v79
	v_mov_b32_e32 v118, v91
	v_pk_mul_f32 v[78:79], v[102:103], v[108:109]
	v_pk_mul_f32 v[84:85], v[84:85], v[110:111]
	v_pk_mul_f32 v[76:77], v[76:77], v[116:117]
	v_pk_mul_f32 v[86:87], v[86:87], v[118:119]
	v_add_f32_e32 v118, v78, v79
	v_add_f32_e32 v119, v84, v85
	v_add_f32_e32 v126, v76, v77
	v_add_f32_e32 v127, v86, v87
	v_lshl_add_u64 v[76:77], s[16:17], 0, v[100:101]
	v_lshl_add_u64 v[78:79], v[76:77], 0, v[136:137]
	v_add_co_u32_e64 v76, s[4:5], s62, v78
	ds_bpermute_b32 v101, v177, v72
	s_nop 0
	v_addc_co_u32_e64 v77, s[4:5], 0, v79, s[4:5]
	v_add_co_u32_e64 v78, s[4:5], s49, v78
	ds_bpermute_b32 v102, v177, v73
	s_nop 0
	v_addc_co_u32_e64 v79, s[4:5], 0, v79, s[4:5]
	global_load_dwordx4 v[84:87], v[76:77], off offset:16
	global_load_dwordx4 v[88:91], v[78:79], off offset:16
	ds_bpermute_b32 v108, v177, v74
	ds_bpermute_b32 v110, v177, v75
	v_mov_b32_e32 v100, v72
	v_mov_b32_e32 v72, v74
	s_waitcnt lgkmcnt(3)
	v_cndmask_b32_e64 v103, v101, -v101, vcc
	s_waitcnt lgkmcnt(2)
	v_cndmask_b32_e64 v109, v102, -v102, vcc
	s_waitcnt lgkmcnt(1)
	v_cndmask_b32_e64 v111, v108, -v108, vcc
	s_waitcnt lgkmcnt(0)
	v_cndmask_b32_e64 v117, v110, -v110, vcc
	s_waitcnt vmcnt(1)
	v_mov_b32_e32 v101, v84
	s_waitcnt vmcnt(0)
;     __device__ __forceinline__ void operator()(const AccT& acc, const Unit& u, int wr, int wc, int fr, int fq) const {
;     ...
;         for (int ai = 0; ai < 2; ++ai) {
;             const int hh = 2 * ai + wr;
;             const float l2f = lgd[hh] * 1.4426950408889634f, l2b = lgd[4 + hh] * 1.4426950408889634f;
;             const float zf0 = exp2f((float)(127 - o0) * l2f), zfs = exp2f(-l2f), zb0 = exp2f((float)o0 * l2b), zbs = exp2f(l2b);
; #pragma unroll
;             for (int m = 0; m < 4; ++m) {
;                 const int r = rbase + ai * 128 + m * 16;
;                 const int d = 4 * (2 * m + (fr >> 3)) + j;
; #pragma unroll
;                 for (int bj = 0; bj < 2; ++bj) {
;                     const int t0 = tb + bj * 128;
;                     float v[8];
; #pragma unroll
;                     for (int jj = 0; jj < 4; ++jj) { v[jj] = acc[ai][bj][m][0][jj]; v[4 + jj] = acc[ai][bj][m][1][jj]; }
;                     if constexpr (ROPE) {
;                         const int t = t0 & 2047;
; #pragma unroll
;                         for (int hf = 0; hf < 2; ++hf) {
;                             f32x4 cs, sn;
;                             if (m < 2) { const float c1 = ropeA[(t >> 6) * 16 + d], s1 = ropeA[1024 + (t >> 6) * 16 + d]; cs = (f32x4){c1, c1, c1, c1}; sn = (f32x4){s1, s1, s1, s1}; }
;                             else { const float* cb = ropeA + 2048 + (d - 16) * 64 + (t & 63) + 4 * hf; cs = *(const f32x4*)(cb); sn = *(const f32x4*)(cb + 1024); }
; #pragma unroll
;                             for (int jj = 0; jj < 4; ++jj) { const float pr = __shfl_xor(v[4 * hf + jj], 4); v[4 * hf + jj] = v[4 * hf + jj] * cs[jj] + sgn * pr * sn[jj]; }
;                             __builtin_amdgcn_sched_barrier(0);
;                         }
;                     }
;                     float zf[8], zb[8]; zf[0] = zf0; zb[0] = zb0;
; #pragma unroll
;                     for (int jj = 1; jj < 8; ++jj) { zf[jj] = zf[jj - 1] * zfs; zb[jj] = zb[jj - 1] * zbs; }
;                     u32x4 wf, wb;
;                     wf.x = cvt_pk_bf16(v[0] * zf[0], v[1] * zf[1]); wf.y = cvt_pk_bf16(v[2] * zf[2], v[3] * zf[3]); wf.z = cvt_pk_bf16(v[4] * zf[4], v[5] * zf[5]); wf.w = cvt_pk_bf16(v[6] * zf[6], v[7] * zf[7]);
	v_mov_b32_e32 v102, v88
	v_mov_b32_e32 v84, v73
	v_mov_b32_e32 v108, v89
	v_mov_b32_e32 v73, v86
	v_mov_b32_e32 v110, v90
	v_mov_b32_e32 v86, v75
	v_mov_b32_e32 v116, v91
	v_pk_mul_f32 v[74:75], v[100:101], v[102:103]
	v_pk_mul_f32 v[84:85], v[84:85], v[108:109]
	v_pk_mul_f32 v[72:73], v[72:73], v[110:111]
	v_pk_mul_f32 v[86:87], v[86:87], v[116:117]
	v_add_f32_e32 v74, v74, v75
	v_add_f32_e32 v75, v84, v85
	v_add_f32_e32 v72, v72, v73
	v_add_f32_e32 v73, v86, v87
	v_mul_f32_e32 v84, v180, v118
	v_mul_f32_e32 v85, v181, v119
	v_cvt_pk_bf16_f32 v84, v84, v85
	v_mul_f32_e32 v85, v167, v126
	v_mul_f32_e32 v86, v183, v127
	v_cvt_pk_bf16_f32 v85, v85, v86
	v_mul_f32_e32 v86, v182, v74
	v_mul_f32_e32 v87, v185, v75
	v_cvt_pk_bf16_f32 v86, v86, v87
	v_mul_f32_e32 v87, v184, v72
	v_mul_f32_e32 v88, v159, v73
	v_cvt_pk_bf16_f32 v87, v87, v88
	v_mul_f32_e32 v88, v150, v118
	v_mul_f32_e32 v89, v152, v119
	v_cvt_pk_bf16_f32 v88, v88, v89
	v_mul_f32_e32 v89, v154, v126
	v_mul_f32_e32 v90, v156, v127
	v_mul_f32_e32 v72, v151, v72
	v_mul_f32_e32 v73, v155, v73
	s_mov_b64 s[0:1], 0x600000
	v_cvt_pk_bf16_f32 v89, v89, v90
	v_mul_f32_e32 v74, v158, v74
	v_mul_f32_e32 v75, v160, v75
	v_cvt_pk_bf16_f32 v90, v74, v75
	v_cvt_pk_bf16_f32 v91, v72, v73
	v_lshl_add_u64 v[72:73], v[120:121], 0, s[0:1]
	s_mov_b32 s0, 0x600000
	v_add_co_u32_e64 v74, s[4:5], s0, v120
	s_mov_b64 s[0:1], 0x2600000
	s_nop 0
	v_addc_co_u32_e64 v75, s[4:5], 0, v121, s[4:5]
	global_store_dwordx4 v[74:75], v[84:87], off
	v_lshl_add_u64 v[74:75], v[120:121], 0, s[0:1]
	s_mov_b32 s0, 0x2600000
	v_add_co_u32_e64 v84, s[4:5], s0, v120
	s_nop 1
	v_addc_co_u32_e64 v85, s[4:5], 0, v121, s[4:5]
	global_store_dwordx4 v[84:85], v[88:91], off
	global_load_dwordx4 v[84:87], v[82:83], off
	s_nop 0
	global_load_dwordx4 v[88:91], v[80:81], off
	ds_bpermute_b32 v101, v177, v68
	ds_bpermute_b32 v102, v177, v69
	ds_bpermute_b32 v108, v177, v70
	ds_bpermute_b32 v110, v177, v71
	v_mov_b32_e32 v100, v68
	v_mov_b32_e32 v68, v70
	s_waitcnt lgkmcnt(3)
	v_cndmask_b32_e64 v103, v101, -v101, vcc
	s_waitcnt lgkmcnt(2)
	v_cndmask_b32_e64 v109, v102, -v102, vcc
	s_waitcnt lgkmcnt(1)
	v_cndmask_b32_e64 v111, v108, -v108, vcc
	s_waitcnt lgkmcnt(0)
	v_cndmask_b32_e64 v117, v110, -v110, vcc
	s_waitcnt vmcnt(1)
	v_mov_b32_e32 v101, v84
	s_waitcnt vmcnt(0)
	v_mov_b32_e32 v102, v88
	v_mov_b32_e32 v84, v69
	v_mov_b32_e32 v108, v89
	v_mov_b32_e32 v69, v86
	v_mov_b32_e32 v110, v90
	v_mov_b32_e32 v86, v71
	v_mov_b32_e32 v116, v91
	v_pk_mul_f32 v[70:71], v[100:101], v[102:103]
	v_pk_mul_f32 v[84:85], v[84:85], v[108:109]
	v_pk_mul_f32 v[68:69], v[68:69], v[110:111]
	v_pk_mul_f32 v[86:87], v[86:87], v[116:117]
	v_add_f32_e32 v110, v70, v71
	v_add_f32_e32 v111, v84, v85
	v_add_f32_e32 v116, v68, v69
	v_add_f32_e32 v117, v86, v87
	global_load_dwordx4 v[68:71], v[76:77], off offset:16
	global_load_dwordx4 v[84:87], v[78:79], off offset:16
	ds_bpermute_b32 v89, v177, v64
	ds_bpermute_b32 v90, v177, v65
	ds_bpermute_b32 v100, v177, v66
	ds_bpermute_b32 v102, v177, v67
	v_mov_b32_e32 v88, v64
	v_mov_b32_e32 v64, v66
	s_waitcnt lgkmcnt(3)
	v_cndmask_b32_e64 v91, v89, -v89, vcc
	s_waitcnt lgkmcnt(2)
	v_cndmask_b32_e64 v101, v90, -v90, vcc
	s_waitcnt lgkmcnt(1)
	v_cndmask_b32_e64 v103, v100, -v100, vcc
	s_waitcnt lgkmcnt(0)
	v_cndmask_b32_e64 v109, v102, -v102, vcc
	s_waitcnt vmcnt(1)
	v_mov_b32_e32 v89, v68
	s_waitcnt vmcnt(0)
	v_mov_b32_e32 v90, v84
	v_mov_b32_e32 v68, v65
	v_mov_b32_e32 v100, v85
	v_mov_b32_e32 v65, v70
	v_mov_b32_e32 v102, v86
	v_mov_b32_e32 v70, v67
	v_mov_b32_e32 v108, v87
	v_pk_mul_f32 v[66:67], v[88:89], v[90:91]
	v_pk_mul_f32 v[68:69], v[68:69], v[100:101]
	v_pk_mul_f32 v[64:65], v[64:65], v[102:103]
	v_pk_mul_f32 v[70:71], v[70:71], v[108:109]
	v_add_f32_e32 v84, v66, v67
	v_add_f32_e32 v85, v68, v69
	v_add_f32_e32 v86, v64, v65
	v_add_f32_e32 v71, v70, v71
	v_mul_f32_e32 v64, v180, v110
	v_mul_f32_e32 v65, v181, v111
	v_cvt_pk_bf16_f32 v64, v64, v65
	v_mul_f32_e32 v65, v167, v116
	v_mul_f32_e32 v66, v183, v117
	v_cvt_pk_bf16_f32 v65, v65, v66
	v_mul_f32_e32 v66, v182, v84
	v_mul_f32_e32 v67, v185, v85
	v_cvt_pk_bf16_f32 v66, v66, v67
	v_mul_f32_e32 v67, v184, v86
	v_mul_f32_e32 v68, v159, v71
	v_cvt_pk_bf16_f32 v67, v67, v68
	v_mul_f32_e32 v68, v150, v110
	v_mul_f32_e32 v69, v152, v111
	v_cvt_pk_bf16_f32 v68, v68, v69
	v_mul_f32_e32 v69, v154, v116
	v_mul_f32_e32 v70, v156, v117
	v_cvt_pk_bf16_f32 v69, v69, v70
	v_mul_f32_e32 v70, v158, v84
	v_mul_f32_e32 v84, v160, v85
	v_mul_f32_e32 v71, v155, v71
	v_cvt_pk_bf16_f32 v70, v70, v84
	v_mul_f32_e32 v84, v151, v86
	v_cvt_pk_bf16_f32 v71, v84, v71
	global_store_dwordx4 v[72:73], v[64:67], off offset:256
	global_store_dwordx4 v[74:75], v[68:71], off offset:256
	global_load_dword v64, v137, s[22:23] offset:8
	s_nop 0
	global_load_dword v70, v137, s[22:23] offset:24
	global_load_dword v67, v[146:147], off
	global_load_dword v74, v[148:149], off
	ds_bpermute_b32 v65, v177, v60
	ds_bpermute_b32 v68, v177, v62
	v_mov_b32_e32 v66, v60
	ds_bpermute_b32 v60, v177, v61
	ds_bpermute_b32 v71, v177, v63
	s_waitcnt lgkmcnt(3)
	v_cndmask_b32_e64 v75, v65, -v65, vcc
	s_waitcnt lgkmcnt(2)
	v_cndmask_b32_e64 v65, v68, -v68, vcc
	s_waitcnt vmcnt(3)
	v_mul_f32_e32 v72, 0x3fb8aa3b, v64
	s_waitcnt vmcnt(2)
	v_mul_f32_e32 v73, 0x3fb8aa3b, v70
	v_mul_f32_e32 v84, v72, v179
	s_waitcnt vmcnt(0)
	v_pk_mul_f32 v[68:69], v[66:67], v[74:75]
	s_waitcnt lgkmcnt(1)
	v_cndmask_b32_e64 v75, v60, -v60, vcc
	v_mov_b32_e32 v66, v61
	v_cmp_lt_f32_e64 s[4:5], s60, v72
	v_mul_f32_e32 v87, v73, v178
	v_pk_mul_f32 v[60:61], v[66:67], v[74:75]
	s_waitcnt lgkmcnt(0)
;     __device__ __forceinline__ void operator()(const AccT& acc, const Unit& u, int wr, int wc, int fr, int fq) const {
;     ...
;         for (int ai = 0; ai < 2; ++ai) {
;             const int hh = 2 * ai + wr;
;             const float l2f = lgd[hh] * 1.4426950408889634f, l2b = lgd[4 + hh] * 1.4426950408889634f;
;             const float zf0 = exp2f((float)(127 - o0) * l2f), zfs = exp2f(-l2f), zb0 = exp2f((float)o0 * l2b), zbs = exp2f(l2b);
; #pragma unroll
;             for (int m = 0; m < 4; ++m) {
;                 const int r = rbase + ai * 128 + m * 16;
;                 const int d = 4 * (2 * m + (fr >> 3)) + j;
; #pragma unroll
;                 for (int bj = 0; bj < 2; ++bj) {
;                     const int t0 = tb + bj * 128;
;                     float v[8];
; #pragma unroll
;                     for (int jj = 0; jj < 4; ++jj) { v[jj] = acc[ai][bj][m][0][jj]; v[4 + jj] = acc[ai][bj][m][1][jj]; }
;                     if constexpr (ROPE) {
;                         const int t = t0 & 2047;
; #pragma unroll
;                         for (int hf = 0; hf < 2; ++hf) {
;                             f32x4 cs, sn;
;                             if (m < 2) { const float c1 = ropeA[(t >> 6) * 16 + d], s1 = ropeA[1024 + (t >> 6) * 16 + d]; cs = (f32x4){c1, c1, c1, c1}; sn = (f32x4){s1, s1, s1, s1}; }
;                             else { const float* cb = ropeA + 2048 + (d - 16) * 64 + (t & 63) + 4 * hf; cs = *(const f32x4*)(cb); sn = *(const f32x4*)(cb + 1024); }
; #pragma unroll
;                             for (int jj = 0; jj < 4; ++jj) { const float pr = __shfl_xor(v[4 * hf + jj], 4); v[4 * hf + jj] = v[4 * hf + jj] * cs[jj] + sgn * pr * sn[jj]; }
;                             __builtin_amdgcn_sched_barrier(0);
;                         }
;                     }
;                     float zf[8], zb[8]; zf[0] = zf0; zb[0] = zb0;
; #pragma unroll
;                     for (int jj = 1; jj < 8; ++jj) { zf[jj] = zf[jj - 1] * zfs; zb[jj] = zb[jj - 1] * zbs; }
;                     u32x4 wf, wb;
;                     wf.x = cvt_pk_bf16(v[0] * zf[0], v[1] * zf[1]); wf.y = cvt_pk_bf16(v[2] * zf[2], v[3] * zf[3]); wf.z = cvt_pk_bf16(v[4] * zf[4], v[5] * zf[5]); wf.w = cvt_pk_bf16(v[6] * zf[6], v[7] * zf[7]);
	v_cndmask_b32_e64 v75, v71, -v71, vcc
	v_mov_b32_e32 v66, v63
	v_cmp_gt_f32_e64 s[8:9], s59, v84
	v_cndmask_b32_e64 v86, 0, v176, s[4:5]
	v_cmp_gt_f32_e64 s[6:7], s59, v73
	s_and_b64 s[0:1], s[4:5], exec
	v_cmp_gt_f32_e64 s[4:5], s59, v87
	v_add_f32_e32 v110, v60, v61
	v_pk_mul_f32 v[60:61], v[66:67], v[74:75]
	v_cndmask_b32_e64 v66, 0, v176, s[8:9]
	v_cndmask_b32_e64 v88, 0, v176, s[6:7]
	v_add_f32_e32 v89, v68, v69
	v_fmac_f32_e32 v86, 0xbfb8aa3b, v64
	v_cndmask_b32_e64 v69, 0, v176, s[4:5]
	v_fmac_f32_e32 v66, v72, v179
	v_fmac_f32_e32 v88, 0x3fb8aa3b, v70
	v_exp_f32_e32 v68, v86
	v_fmac_f32_e32 v69, v73, v178
	v_exp_f32_e32 v66, v66
	v_exp_f32_e32 v70, v88
	v_exp_f32_e32 v69, v69
	v_cndmask_b32_e64 v63, 0, v175, s[8:9]
	s_cselect_b32 s8, 0xffffffc0, 0
	s_and_b64 s[0:1], s[6:7], exec
	v_cndmask_b32_e64 v64, 0, v175, s[4:5]
	s_cselect_b32 s0, 0xffffffc0, 0
	v_ldexp_f32 v100, v68, s8
	v_ldexp_f32 v63, v66, v63
	v_mul_f32_e32 v85, v62, v74
	v_ldexp_f32 v90, v70, s0
	v_ldexp_f32 v64, v69, v64
	v_mul_f32_e32 v75, v100, v63
	v_add_f32_e32 v111, v60, v61
	global_load_dword v108, v[148:149], off
	global_load_dword v69, v[146:147], off
	ds_bpermute_b32 v61, v177, v57
	ds_bpermute_b32 v60, v177, v56
	v_mov_b32_e32 v68, v57
	ds_bpermute_b32 v57, v177, v59
	ds_bpermute_b32 v66, v177, v58
	s_waitcnt lgkmcnt(3)
	v_cndmask_b32_e64 v109, v61, -v61, vcc
	s_waitcnt lgkmcnt(2)
	v_cndmask_b32_e64 v70, v60, -v60, vcc
	s_waitcnt lgkmcnt(0)
	v_cndmask_b32_e64 v72, v66, -v66, vcc
	s_waitcnt vmcnt(1)
	v_mul_f32_e32 v71, v56, v108
	s_waitcnt vmcnt(0)
	v_pk_mul_f32 v[60:61], v[68:69], v[108:109]
	v_cndmask_b32_e64 v109, v57, -v57, vcc
	v_mov_b32_e32 v68, v59
	v_add_f32_e32 v57, v60, v61
	v_pk_mul_f32 v[60:61], v[68:69], v[108:109]
	s_nop 0
	v_add_f32_e32 v59, v60, v61
	v_mov_b32_e32 v91, v67
	v_pk_mul_f32 v[60:61], v[90:91], v[64:65]
	v_mov_b32_e32 v91, v85
	v_pk_mul_f32 v[66:67], v[90:91], v[60:61]
	v_mov_b32_e32 v91, v69
	v_mov_b32_e32 v67, v70
	v_mul_f32_e32 v84, v100, v75
	v_pk_mul_f32 v[68:69], v[90:91], v[66:67]
	v_mov_b32_e32 v70, v90
	v_mul_f32_e32 v86, v100, v84
	v_pk_mul_f32 v[70:71], v[70:71], v[68:69]
	v_mul_f32_e32 v85, v100, v86
	v_mov_b32_e32 v71, v72
	v_mul_f32_e32 v88, v100, v85
	v_pk_mul_f32 v[72:73], v[90:91], v[70:71]
	v_fma_f32 v61, v62, v74, v61
	v_mul_f32_e32 v87, v100, v88
	v_mul_f32_e32 v65, v90, v72
	v_mul_f32_e32 v62, v84, v61
	v_fma_f32 v56, v56, v108, v69
	v_mul_f32_e32 v71, v100, v87
	v_mul_f32_e32 v67, v90, v65
	v_mul_f32_e32 v90, v63, v89
	v_mul_f32_e32 v91, v75, v110
	v_cvt_pk_bf16_f32 v100, v90, v91
	v_mul_f32_e32 v74, v86, v111
	v_cvt_pk_bf16_f32 v101, v62, v74
	v_mul_f32_e32 v62, v85, v56
	v_fma_f32 v58, v58, v108, v73
	v_mul_f32_e32 v69, v88, v57
	v_cvt_pk_bf16_f32 v102, v62, v69
	v_mul_f32_e32 v62, v87, v58
	v_mul_f32_e32 v69, v71, v59
	v_cvt_pk_bf16_f32 v103, v62, v69
	v_mul_f32_e32 v62, v64, v89
	v_mul_f32_e32 v56, v70, v56
	v_mul_f32_e32 v57, v72, v57
	v_mul_f32_e32 v69, v60, v110
	v_cvt_pk_bf16_f32 v108, v62, v69
	v_mul_f32_e32 v61, v66, v61
	v_mul_f32_e32 v62, v68, v111
	v_cvt_pk_bf16_f32 v109, v61, v62
	v_cvt_pk_bf16_f32 v110, v56, v57
	v_mul_f32_e32 v56, v65, v58
	v_mul_f32_e32 v57, v67, v59
	s_mov_b64 s[0:1], 0x1000000
	v_cvt_pk_bf16_f32 v111, v56, v57
	v_lshl_add_u64 v[56:57], v[120:121], 0, s[0:1]
	s_mov_b32 s0, 0x1000000
	v_add_co_u32_e64 v58, s[4:5], s0, v120
	s_mov_b64 s[0:1], 0x3000000
	s_nop 0
	v_addc_co_u32_e64 v59, s[4:5], 0, v121, s[4:5]
	global_store_dwordx4 v[58:59], v[100:103], off
	v_lshl_add_u64 v[58:59], v[120:121], 0, s[0:1]
	s_mov_b32 s0, 0x3000000
	v_add_co_u32_e64 v90, s[4:5], s0, v120
	s_nop 1
	v_addc_co_u32_e64 v91, s[4:5], 0, v121, s[4:5]
	global_store_dwordx4 v[90:91], v[108:111], off
	global_load_dword v91, v[122:123], off
	s_nop 0
	global_load_dword v100, v[124:125], off
	ds_bpermute_b32 v61, v177, v52
	v_mov_b32_e32 v90, v52
	ds_bpermute_b32 v52, v177, v53
	ds_bpermute_b32 v62, v177, v54
	ds_bpermute_b32 v69, v177, v55
	s_waitcnt lgkmcnt(3)
	v_cndmask_b32_e64 v101, v61, -v61, vcc
	s_waitcnt vmcnt(0)
	v_pk_mul_f32 v[102:103], v[90:91], v[100:101]
	s_waitcnt lgkmcnt(2)
	v_cndmask_b32_e64 v101, v52, -v52, vcc
	v_mov_b32_e32 v90, v53
	v_pk_mul_f32 v[52:53], v[90:91], v[100:101]
	s_waitcnt lgkmcnt(1)
	v_cndmask_b32_e64 v101, v62, -v62, vcc
	v_mov_b32_e32 v90, v54
	v_add_f32_e32 v62, v52, v53
	v_pk_mul_f32 v[52:53], v[90:91], v[100:101]
	s_waitcnt lgkmcnt(0)
	v_cndmask_b32_e64 v101, v69, -v69, vcc
	v_mov_b32_e32 v90, v55
	v_add_f32_e32 v69, v52, v53
	v_pk_mul_f32 v[52:53], v[90:91], v[100:101]
	v_add_f32_e32 v61, v102, v103
	v_add_f32_e32 v73, v52, v53
	global_load_dword v53, v[122:123], off
	global_load_dword v54, v[124:125], off
	ds_bpermute_b32 v55, v177, v48
	v_mov_b32_e32 v52, v48
	ds_bpermute_b32 v48, v177, v49
	ds_bpermute_b32 v74, v177, v50
	ds_bpermute_b32 v89, v177, v51
	s_waitcnt lgkmcnt(3)
	v_cndmask_b32_e64 v55, v55, -v55, vcc
	s_waitcnt vmcnt(0)
	v_pk_mul_f32 v[90:91], v[52:53], v[54:55]
	s_waitcnt lgkmcnt(2)
	v_cndmask_b32_e64 v55, v48, -v48, vcc
	v_mov_b32_e32 v52, v49
	v_pk_mul_f32 v[48:49], v[52:53], v[54:55]
	s_waitcnt lgkmcnt(1)
	v_cndmask_b32_e64 v55, v74, -v74, vcc
	v_mov_b32_e32 v52, v50
	v_add_f32_e32 v74, v48, v49
	v_pk_mul_f32 v[48:49], v[52:53], v[54:55]
	s_waitcnt lgkmcnt(0)
;     __device__ __forceinline__ void operator()(const AccT& acc, const Unit& u, int wr, int wc, int fr, int fq) const {
;     ...
;                 const int r = rbase + ai * 128 + m * 16;
;                 const int d = 4 * (2 * m + (fr >> 3)) + j;
; #pragma unroll
;                 for (int bj = 0; bj < 2; ++bj) {
;                     const int t0 = tb + bj * 128;
;                     float v[8];
; #pragma unroll
;                     for (int jj = 0; jj < 4; ++jj) { v[jj] = acc[ai][bj][m][0][jj]; v[4 + jj] = acc[ai][bj][m][1][jj]; }
;                     if constexpr (ROPE) {
;                         const int t = t0 & 2047;
; #pragma unroll
;                         for (int hf = 0; hf < 2; ++hf) {
;                             f32x4 cs, sn;
;                             if (m < 2) { const float c1 = ropeA[(t >> 6) * 16 + d], s1 = ropeA[1024 + (t >> 6) * 16 + d]; cs = (f32x4){c1, c1, c1, c1}; sn = (f32x4){s1, s1, s1, s1}; }
;                             else { const float* cb = ropeA + 2048 + (d - 16) * 64 + (t & 63) + 4 * hf; cs = *(const f32x4*)(cb); sn = *(const f32x4*)(cb + 1024); }
; #pragma unroll
;                             for (int jj = 0; jj < 4; ++jj) { const float pr = __shfl_xor(v[4 * hf + jj], 4); v[4 * hf + jj] = v[4 * hf + jj] * cs[jj] + sgn * pr * sn[jj]; }
;                             __builtin_amdgcn_sched_barrier(0);
;                         }
;                     }
;                     float zf[8], zb[8]; zf[0] = zf0; zb[0] = zb0;
; #pragma unroll
;                     for (int jj = 1; jj < 8; ++jj) { zf[jj] = zf[jj - 1] * zfs; zb[jj] = zb[jj - 1] * zbs; }
;                     u32x4 wf, wb;
;                     wf.x = cvt_pk_bf16(v[0] * zf[0], v[1] * zf[1]); wf.y = cvt_pk_bf16(v[2] * zf[2], v[3] * zf[3]); wf.z = cvt_pk_bf16(v[4] * zf[4], v[5] * zf[5]); wf.w = cvt_pk_bf16(v[6] * zf[6], v[7] * zf[7]);
;                     wb.x = cvt_pk_bf16(v[0] * zb[0], v[1] * zb[1]); wb.y = cvt_pk_bf16(v[2] * zb[2], v[3] * zb[3]); wb.z = cvt_pk_bf16(v[4] * zb[4], v[5] * zb[5]); wb.w = cvt_pk_bf16(v[6] * zb[6], v[7] * zb[7]);
;                     *(u32x4*)(KTZ + (size_t)r * NT + t0) = wf;
;                     *(u32x4*)(KTZ + (size_t)(256 + r) * NT + t0) = wb;
;                     __builtin_amdgcn_sched_barrier(0);
	v_cndmask_b32_e64 v55, v89, -v89, vcc
	v_mov_b32_e32 v52, v51
	v_add_f32_e32 v89, v48, v49
	v_pk_mul_f32 v[48:49], v[52:53], v[54:55]
	v_add_f32_e32 v90, v90, v91
	v_add_f32_e32 v55, v48, v49
	v_mul_f32_e32 v48, v63, v61
	v_mul_f32_e32 v49, v75, v62
	v_cvt_pk_bf16_f32 v48, v48, v49
	v_mul_f32_e32 v49, v84, v69
	v_mul_f32_e32 v50, v86, v73
	v_cvt_pk_bf16_f32 v49, v49, v50
	v_mul_f32_e32 v50, v85, v90
	v_mul_f32_e32 v51, v88, v74
	v_cvt_pk_bf16_f32 v50, v50, v51
	v_mul_f32_e32 v51, v87, v89
	v_mul_f32_e32 v52, v71, v55
	v_cvt_pk_bf16_f32 v51, v51, v52
	v_mul_f32_e32 v52, v64, v61
	v_mul_f32_e32 v53, v60, v62
	v_cvt_pk_bf16_f32 v52, v52, v53
	v_mul_f32_e32 v53, v66, v69
	v_mul_f32_e32 v54, v68, v73
	v_cvt_pk_bf16_f32 v53, v53, v54
	v_mul_f32_e32 v54, v70, v90
	v_mul_f32_e32 v61, v72, v74
	v_mul_f32_e32 v55, v67, v55
	v_cvt_pk_bf16_f32 v54, v54, v61
	v_mul_f32_e32 v61, v65, v89
	v_cvt_pk_bf16_f32 v55, v61, v55
	global_store_dwordx4 v[56:57], v[48:51], off offset:256
	global_store_dwordx4 v[58:59], v[52:55], off offset:256
	global_load_dword v49, v[112:113], off
	s_nop 0
	global_load_dword v50, v[114:115], off
	ds_bpermute_b32 v51, v177, v44
	v_mov_b32_e32 v48, v44
	ds_bpermute_b32 v44, v177, v45
	ds_bpermute_b32 v54, v177, v46
	ds_bpermute_b32 v55, v177, v47
	s_waitcnt lgkmcnt(3)
	v_cndmask_b32_e64 v51, v51, -v51, vcc
	s_waitcnt vmcnt(0)
	v_pk_mul_f32 v[52:53], v[48:49], v[50:51]
	s_waitcnt lgkmcnt(2)
	v_cndmask_b32_e64 v51, v44, -v44, vcc
	v_mov_b32_e32 v48, v45
	v_pk_mul_f32 v[44:45], v[48:49], v[50:51]
	s_waitcnt lgkmcnt(1)
	v_cndmask_b32_e64 v51, v54, -v54, vcc
	v_mov_b32_e32 v48, v46
	v_add_f32_e32 v52, v52, v53
	v_add_f32_e32 v53, v44, v45
	v_pk_mul_f32 v[44:45], v[48:49], v[50:51]
	s_waitcnt lgkmcnt(0)
	v_cndmask_b32_e64 v51, v55, -v55, vcc
	v_mov_b32_e32 v48, v47
	v_add_f32_e32 v54, v44, v45
	v_pk_mul_f32 v[44:45], v[48:49], v[50:51]
	s_nop 0
	v_add_f32_e32 v50, v44, v45
	global_load_dword v45, v[112:113], off
	global_load_dword v46, v[114:115], off
	ds_bpermute_b32 v47, v177, v40
	v_mov_b32_e32 v44, v40
	ds_bpermute_b32 v40, v177, v41
	ds_bpermute_b32 v51, v177, v42
	ds_bpermute_b32 v55, v177, v43
	s_waitcnt lgkmcnt(3)
	v_cndmask_b32_e64 v47, v47, -v47, vcc
	s_waitcnt vmcnt(0)
	v_pk_mul_f32 v[48:49], v[44:45], v[46:47]
	s_waitcnt lgkmcnt(2)
	v_cndmask_b32_e64 v47, v40, -v40, vcc
	v_mov_b32_e32 v44, v41
	v_pk_mul_f32 v[40:41], v[44:45], v[46:47]
	s_waitcnt lgkmcnt(1)
	v_cndmask_b32_e64 v47, v51, -v51, vcc
	v_mov_b32_e32 v44, v42
	v_add_f32_e32 v48, v48, v49
	v_add_f32_e32 v49, v40, v41
	v_pk_mul_f32 v[40:41], v[44:45], v[46:47]
	s_waitcnt lgkmcnt(0)
	v_cndmask_b32_e64 v47, v55, -v55, vcc
	v_mov_b32_e32 v44, v43
	v_add_f32_e32 v51, v40, v41
	v_pk_mul_f32 v[40:41], v[44:45], v[46:47]
	s_nop 0
	v_add_f32_e32 v40, v40, v41
	v_mul_f32_e32 v41, v63, v52
	v_mul_f32_e32 v42, v75, v53
	v_cvt_pk_bf16_f32 v42, v41, v42
	v_mul_f32_e32 v41, v84, v54
	v_mul_f32_e32 v43, v86, v50
	v_cvt_pk_bf16_f32 v43, v41, v43
	v_mul_f32_e32 v41, v85, v48
	v_mul_f32_e32 v44, v88, v49
	v_cvt_pk_bf16_f32 v44, v41, v44
	v_mul_f32_e32 v41, v87, v51
	v_mul_f32_e32 v45, v71, v40
	v_cvt_pk_bf16_f32 v45, v41, v45
	v_mul_f32_e32 v41, v64, v52
	v_mul_f32_e32 v46, v60, v53
	v_cvt_pk_bf16_f32 v46, v41, v46
	v_mul_f32_e32 v41, v66, v54
	v_mul_f32_e32 v47, v68, v50
	v_cvt_pk_bf16_f32 v47, v41, v47
	v_mul_f32_e32 v41, v70, v48
	v_mul_f32_e32 v48, v72, v49
	v_cvt_pk_bf16_f32 v48, v41, v48
	v_mul_f32_e32 v41, v65, v51
	v_mul_f32_e32 v40, v67, v40
	s_mov_b64 s[0:1], 0x1200000
	v_cvt_pk_bf16_f32 v49, v41, v40
	v_lshl_add_u64 v[40:41], v[120:121], 0, s[0:1]
	s_mov_b32 s0, 0x1200000
	v_add_co_u32_e64 v50, s[4:5], s0, v120
	s_mov_b64 s[0:1], 0x3200000
	s_nop 0
	v_addc_co_u32_e64 v51, s[4:5], 0, v121, s[4:5]
	global_store_dwordx4 v[50:51], v[42:45], off
	s_nop 1
	v_lshl_add_u64 v[42:43], v[120:121], 0, s[0:1]
	s_mov_b32 s0, 0x3200000
	v_add_co_u32_e64 v44, s[4:5], s0, v120
	s_nop 1
	v_addc_co_u32_e64 v45, s[4:5], 0, v121, s[4:5]
	global_store_dwordx4 v[44:45], v[46:49], off
	global_load_dword v45, v[104:105], off
	s_nop 0
	global_load_dword v46, v[106:107], off
	ds_bpermute_b32 v47, v177, v36
	v_mov_b32_e32 v44, v36
	ds_bpermute_b32 v36, v177, v37
	ds_bpermute_b32 v50, v177, v38
	ds_bpermute_b32 v51, v177, v39
	s_waitcnt lgkmcnt(3)
	v_cndmask_b32_e64 v47, v47, -v47, vcc
	s_waitcnt vmcnt(0)
	v_pk_mul_f32 v[48:49], v[44:45], v[46:47]
	s_waitcnt lgkmcnt(2)
	v_cndmask_b32_e64 v47, v36, -v36, vcc
	v_mov_b32_e32 v44, v37
	v_pk_mul_f32 v[36:37], v[44:45], v[46:47]
	s_waitcnt lgkmcnt(1)
	v_cndmask_b32_e64 v47, v50, -v50, vcc
	v_mov_b32_e32 v44, v38
	v_add_f32_e32 v48, v48, v49
	v_add_f32_e32 v49, v36, v37
	v_pk_mul_f32 v[36:37], v[44:45], v[46:47]
	s_waitcnt lgkmcnt(0)
	v_cndmask_b32_e64 v47, v51, -v51, vcc
	v_mov_b32_e32 v44, v39
	v_add_f32_e32 v50, v36, v37
	v_pk_mul_f32 v[36:37], v[44:45], v[46:47]
	s_nop 0
	v_add_f32_e32 v46, v36, v37
	global_load_dword v37, v[104:105], off
	global_load_dword v38, v[106:107], off
	ds_bpermute_b32 v39, v177, v32
	v_mov_b32_e32 v36, v32
	ds_bpermute_b32 v32, v177, v33
	ds_bpermute_b32 v47, v177, v34
	ds_bpermute_b32 v51, v177, v35
	s_waitcnt lgkmcnt(3)
	v_cndmask_b32_e64 v39, v39, -v39, vcc
	s_waitcnt vmcnt(0)
	v_pk_mul_f32 v[44:45], v[36:37], v[38:39]
	s_waitcnt lgkmcnt(2)
	v_cndmask_b32_e64 v39, v32, -v32, vcc
	v_mov_b32_e32 v36, v33
	v_pk_mul_f32 v[32:33], v[36:37], v[38:39]
	s_waitcnt lgkmcnt(1)
	v_cndmask_b32_e64 v39, v47, -v47, vcc
	v_mov_b32_e32 v36, v34
	v_add_f32_e32 v44, v44, v45
	v_add_f32_e32 v45, v32, v33
	v_pk_mul_f32 v[32:33], v[36:37], v[38:39]
	s_waitcnt lgkmcnt(0)
; __device__ __forceinline__ unsigned cvt_pk_bf16(float lo, float hi) { unsigned r; asm volatile("v_cvt_pk_bf16_f32 %0, %1, %2" : "=v"(r) : "v"(lo), "v"(hi)); return r; }
;     __device__ __forceinline__ void operator()(const AccT& acc, const Unit& u, int wr, int wc, int fr, int fq) const {
;     ...
;                         const int t = t0 & 2047;
; #pragma unroll
;                         for (int hf = 0; hf < 2; ++hf) {
;                             f32x4 cs, sn;
;                             if (m < 2) { const float c1 = ropeA[(t >> 6) * 16 + d], s1 = ropeA[1024 + (t >> 6) * 16 + d]; cs = (f32x4){c1, c1, c1, c1}; sn = (f32x4){s1, s1, s1, s1}; }
;                             else { const float* cb = ropeA + 2048 + (d - 16) * 64 + (t & 63) + 4 * hf; cs = *(const f32x4*)(cb); sn = *(const f32x4*)(cb + 1024); }
; #pragma unroll
;                             for (int jj = 0; jj < 4; ++jj) { const float pr = __shfl_xor(v[4 * hf + jj], 4); v[4 * hf + jj] = v[4 * hf + jj] * cs[jj] + sgn * pr * sn[jj]; }
;                             __builtin_amdgcn_sched_barrier(0);
;                         }
;                     }
;                     float zf[8], zb[8]; zf[0] = zf0; zb[0] = zb0;
; #pragma unroll
;                     for (int jj = 1; jj < 8; ++jj) { zf[jj] = zf[jj - 1] * zfs; zb[jj] = zb[jj - 1] * zbs; }
;                     u32x4 wf, wb;
;                     wf.x = cvt_pk_bf16(v[0] * zf[0], v[1] * zf[1]); wf.y = cvt_pk_bf16(v[2] * zf[2], v[3] * zf[3]); wf.z = cvt_pk_bf16(v[4] * zf[4], v[5] * zf[5]); wf.w = cvt_pk_bf16(v[6] * zf[6], v[7] * zf[7]);
;                     wb.x = cvt_pk_bf16(v[0] * zb[0], v[1] * zb[1]); wb.y = cvt_pk_bf16(v[2] * zb[2], v[3] * zb[3]); wb.z = cvt_pk_bf16(v[4] * zb[4], v[5] * zb[5]); wb.w = cvt_pk_bf16(v[6] * zb[6], v[7] * zb[7]);
;                     *(u32x4*)(KTZ + (size_t)r * NT + t0) = wf;
;                     *(u32x4*)(KTZ + (size_t)(256 + r) * NT + t0) = wb;
;                     __builtin_amdgcn_sched_barrier(0);
	v_cndmask_b32_e64 v39, v51, -v51, vcc
	v_mov_b32_e32 v36, v35
	v_add_f32_e32 v47, v32, v33
	v_pk_mul_f32 v[32:33], v[36:37], v[38:39]
	s_nop 0
	v_add_f32_e32 v39, v32, v33
	v_mul_f32_e32 v32, v63, v48
	v_mul_f32_e32 v33, v75, v49
	v_cvt_pk_bf16_f32 v32, v32, v33
	v_mul_f32_e32 v33, v84, v50
	v_mul_f32_e32 v34, v86, v46
	v_cvt_pk_bf16_f32 v33, v33, v34
	v_mul_f32_e32 v34, v85, v44
	v_mul_f32_e32 v35, v88, v45
	v_cvt_pk_bf16_f32 v34, v34, v35
	v_mul_f32_e32 v35, v87, v47
	v_mul_f32_e32 v36, v71, v39
	v_cvt_pk_bf16_f32 v35, v35, v36
	v_mul_f32_e32 v36, v64, v48
	v_mul_f32_e32 v37, v60, v49
	v_cvt_pk_bf16_f32 v36, v36, v37
	v_mul_f32_e32 v37, v66, v50
	v_mul_f32_e32 v38, v68, v46
	v_cvt_pk_bf16_f32 v37, v37, v38
	v_mul_f32_e32 v38, v70, v44
	v_mul_f32_e32 v44, v72, v45
	v_mul_f32_e32 v39, v67, v39
	v_cvt_pk_bf16_f32 v38, v38, v44
	v_mul_f32_e32 v44, v65, v47
	v_cvt_pk_bf16_f32 v39, v44, v39
	global_store_dwordx4 v[40:41], v[32:35], off offset:256
	global_store_dwordx4 v[42:43], v[36:39], off offset:256
	global_load_dwordx4 v[32:35], v[98:99], off
	s_nop 0
	global_load_dwordx4 v[36:39], v[96:97], off
	ds_bpermute_b32 v41, v177, v28
	ds_bpermute_b32 v42, v177, v29
	ds_bpermute_b32 v44, v177, v30
	ds_bpermute_b32 v46, v177, v31
	v_mov_b32_e32 v40, v28
	v_mov_b32_e32 v28, v30
	s_waitcnt lgkmcnt(3)
	v_cndmask_b32_e64 v43, v41, -v41, vcc
	s_waitcnt lgkmcnt(2)
	v_cndmask_b32_e64 v45, v42, -v42, vcc
	s_waitcnt lgkmcnt(1)
	v_cndmask_b32_e64 v47, v44, -v44, vcc
	s_waitcnt lgkmcnt(0)
	v_cndmask_b32_e64 v49, v46, -v46, vcc
	s_waitcnt vmcnt(1)
	v_mov_b32_e32 v41, v32
	s_waitcnt vmcnt(0)
	v_mov_b32_e32 v42, v36
	v_mov_b32_e32 v32, v29
	v_mov_b32_e32 v44, v37
	v_mov_b32_e32 v29, v34
	v_mov_b32_e32 v46, v38
	v_mov_b32_e32 v34, v31
	v_mov_b32_e32 v48, v39
	v_pk_mul_f32 v[30:31], v[40:41], v[42:43]
	v_pk_mul_f32 v[32:33], v[32:33], v[44:45]
	v_pk_mul_f32 v[28:29], v[28:29], v[46:47]
	v_pk_mul_f32 v[34:35], v[34:35], v[48:49]
	v_add_f32_e32 v46, v30, v31
	v_add_f32_e32 v47, v32, v33
	v_add_f32_e32 v48, v28, v29
	v_add_f32_e32 v49, v34, v35
	global_load_dwordx4 v[28:31], v[92:93], off offset:16
	global_load_dwordx4 v[32:35], v[94:95], off offset:16
	ds_bpermute_b32 v37, v177, v24
	ds_bpermute_b32 v38, v177, v25
	ds_bpermute_b32 v40, v177, v26
	ds_bpermute_b32 v42, v177, v27
	v_mov_b32_e32 v36, v24
	v_mov_b32_e32 v24, v26
	s_waitcnt lgkmcnt(3)
	v_cndmask_b32_e64 v39, v37, -v37, vcc
	s_waitcnt lgkmcnt(2)
	v_cndmask_b32_e64 v41, v38, -v38, vcc
	s_waitcnt lgkmcnt(1)
	v_cndmask_b32_e64 v43, v40, -v40, vcc
	s_waitcnt lgkmcnt(0)
	v_cndmask_b32_e64 v45, v42, -v42, vcc
	s_waitcnt vmcnt(1)
	v_mov_b32_e32 v37, v28
	s_waitcnt vmcnt(0)
	v_mov_b32_e32 v38, v32
	v_mov_b32_e32 v28, v25
	v_mov_b32_e32 v40, v33
	v_mov_b32_e32 v25, v30
	v_mov_b32_e32 v42, v34
	v_mov_b32_e32 v30, v27
	v_mov_b32_e32 v44, v35
	v_pk_mul_f32 v[26:27], v[36:37], v[38:39]
	v_pk_mul_f32 v[28:29], v[28:29], v[40:41]
	v_pk_mul_f32 v[24:25], v[24:25], v[42:43]
	v_pk_mul_f32 v[30:31], v[30:31], v[44:45]
	v_add_f32_e32 v32, v26, v27
	v_add_f32_e32 v33, v28, v29
	v_add_f32_e32 v24, v24, v25
	v_add_f32_e32 v25, v30, v31
	v_mul_f32_e32 v26, v63, v46
	v_mul_f32_e32 v27, v75, v47
	v_cvt_pk_bf16_f32 v26, v26, v27
	v_mul_f32_e32 v27, v84, v48
	v_mul_f32_e32 v28, v86, v49
	v_cvt_pk_bf16_f32 v27, v27, v28
	v_mul_f32_e32 v28, v85, v32
	v_mul_f32_e32 v29, v88, v33
	v_cvt_pk_bf16_f32 v28, v28, v29
	v_mul_f32_e32 v29, v87, v24
	v_mul_f32_e32 v30, v71, v25
	v_cvt_pk_bf16_f32 v29, v29, v30
	v_mul_f32_e32 v30, v64, v46
	v_mul_f32_e32 v31, v60, v47
	v_cvt_pk_bf16_f32 v30, v30, v31
	v_mul_f32_e32 v31, v66, v48
	v_mul_f32_e32 v32, v70, v32
	v_mul_f32_e32 v33, v72, v33
	v_mul_f32_e32 v24, v65, v24
	v_mul_f32_e32 v25, v67, v25
	s_mov_b64 s[0:1], 0x1400000
	v_mul_f32_e32 v34, v68, v49
	v_cvt_pk_bf16_f32 v31, v31, v34
	v_cvt_pk_bf16_f32 v32, v32, v33
	v_cvt_pk_bf16_f32 v33, v24, v25
	v_lshl_add_u64 v[24:25], v[120:121], 0, s[0:1]
	s_mov_b32 s0, 0x1400000
	v_add_co_u32_e64 v34, s[4:5], s0, v120
	s_mov_b64 s[0:1], 0x3400000
	s_nop 0
	v_addc_co_u32_e64 v35, s[4:5], 0, v121, s[4:5]
	global_store_dwordx4 v[34:35], v[26:29], off
	s_nop 1
	v_lshl_add_u64 v[26:27], v[120:121], 0, s[0:1]
	s_mov_b32 s0, 0x3400000
	v_add_co_u32_e64 v28, s[4:5], s0, v120
	s_nop 1
	v_addc_co_u32_e64 v29, s[4:5], 0, v121, s[4:5]
	global_store_dwordx4 v[28:29], v[30:33], off
	global_load_dwordx4 v[28:31], v[98:99], off
	s_nop 0
	global_load_dwordx4 v[32:35], v[96:97], off
	ds_bpermute_b32 v37, v177, v20
	ds_bpermute_b32 v38, v177, v21
	ds_bpermute_b32 v40, v177, v22
	ds_bpermute_b32 v42, v177, v23
	v_mov_b32_e32 v36, v20
	v_mov_b32_e32 v20, v22
	s_waitcnt lgkmcnt(3)
	v_cndmask_b32_e64 v39, v37, -v37, vcc
	s_waitcnt lgkmcnt(2)
	v_cndmask_b32_e64 v41, v38, -v38, vcc
	s_waitcnt lgkmcnt(1)
	v_cndmask_b32_e64 v43, v40, -v40, vcc
	s_waitcnt lgkmcnt(0)
	v_cndmask_b32_e64 v45, v42, -v42, vcc
	s_waitcnt vmcnt(1)
	v_mov_b32_e32 v37, v28
	s_waitcnt vmcnt(0)
	v_mov_b32_e32 v38, v32
	v_mov_b32_e32 v28, v21
	v_mov_b32_e32 v40, v33
	v_mov_b32_e32 v21, v30
	v_mov_b32_e32 v42, v34
	v_mov_b32_e32 v30, v23
	v_mov_b32_e32 v44, v35
	v_pk_mul_f32 v[22:23], v[36:37], v[38:39]
	v_pk_mul_f32 v[28:29], v[28:29], v[40:41]
	v_pk_mul_f32 v[20:21], v[20:21], v[42:43]
	v_pk_mul_f32 v[30:31], v[30:31], v[44:45]
	v_add_f32_e32 v42, v22, v23
	v_add_f32_e32 v43, v28, v29
	v_add_f32_e32 v44, v20, v21
	v_add_f32_e32 v45, v30, v31
	global_load_dwordx4 v[20:23], v[92:93], off offset:16
	global_load_dwordx4 v[28:31], v[94:95], off offset:16
	ds_bpermute_b32 v33, v177, v16
	ds_bpermute_b32 v34, v177, v17
	ds_bpermute_b32 v36, v177, v18
	ds_bpermute_b32 v38, v177, v19
	v_mov_b32_e32 v32, v16
	v_mov_b32_e32 v16, v18
	s_waitcnt lgkmcnt(3)
; __device__ __forceinline__ unsigned cvt_pk_bf16(float lo, float hi) { unsigned r; asm volatile("v_cvt_pk_bf16_f32 %0, %1, %2" : "=v"(r) : "v"(lo), "v"(hi)); return r; }
;     __device__ __forceinline__ void operator()(const AccT& acc, const Unit& u, int wr, int wc, int fr, int fq) const {
;     ...
;                         const int t = t0 & 2047;
; #pragma unroll
;                         for (int hf = 0; hf < 2; ++hf) {
;                             f32x4 cs, sn;
;                             if (m < 2) { const float c1 = ropeA[(t >> 6) * 16 + d], s1 = ropeA[1024 + (t >> 6) * 16 + d]; cs = (f32x4){c1, c1, c1, c1}; sn = (f32x4){s1, s1, s1, s1}; }
;                             else { const float* cb = ropeA + 2048 + (d - 16) * 64 + (t & 63) + 4 * hf; cs = *(const f32x4*)(cb); sn = *(const f32x4*)(cb + 1024); }
; #pragma unroll
;                             for (int jj = 0; jj < 4; ++jj) { const float pr = __shfl_xor(v[4 * hf + jj], 4); v[4 * hf + jj] = v[4 * hf + jj] * cs[jj] + sgn * pr * sn[jj]; }
;                             __builtin_amdgcn_sched_barrier(0);
;                         }
;                     }
;                     float zf[8], zb[8]; zf[0] = zf0; zb[0] = zb0;
; #pragma unroll
;                     for (int jj = 1; jj < 8; ++jj) { zf[jj] = zf[jj - 1] * zfs; zb[jj] = zb[jj - 1] * zbs; }
;                     u32x4 wf, wb;
;                     wf.x = cvt_pk_bf16(v[0] * zf[0], v[1] * zf[1]); wf.y = cvt_pk_bf16(v[2] * zf[2], v[3] * zf[3]); wf.z = cvt_pk_bf16(v[4] * zf[4], v[5] * zf[5]); wf.w = cvt_pk_bf16(v[6] * zf[6], v[7] * zf[7]);
;                     wb.x = cvt_pk_bf16(v[0] * zb[0], v[1] * zb[1]); wb.y = cvt_pk_bf16(v[2] * zb[2], v[3] * zb[3]); wb.z = cvt_pk_bf16(v[4] * zb[4], v[5] * zb[5]); wb.w = cvt_pk_bf16(v[6] * zb[6], v[7] * zb[7]);
;                     *(u32x4*)(KTZ + (size_t)r * NT + t0) = wf;
;                     *(u32x4*)(KTZ + (size_t)(256 + r) * NT + t0) = wb;
;                     __builtin_amdgcn_sched_barrier(0);
	v_cndmask_b32_e64 v35, v33, -v33, vcc
	s_waitcnt lgkmcnt(2)
	v_cndmask_b32_e64 v37, v34, -v34, vcc
	s_waitcnt lgkmcnt(1)
	v_cndmask_b32_e64 v39, v36, -v36, vcc
	s_waitcnt lgkmcnt(0)
	v_cndmask_b32_e64 v41, v38, -v38, vcc
	s_waitcnt vmcnt(1)
	v_mov_b32_e32 v33, v20
	s_waitcnt vmcnt(0)
	v_mov_b32_e32 v34, v28
	v_mov_b32_e32 v20, v17
	v_mov_b32_e32 v36, v29
	v_mov_b32_e32 v17, v22
	v_mov_b32_e32 v38, v30
	v_mov_b32_e32 v22, v19
	v_mov_b32_e32 v40, v31
	v_pk_mul_f32 v[18:19], v[32:33], v[34:35]
	v_pk_mul_f32 v[20:21], v[20:21], v[36:37]
	v_pk_mul_f32 v[16:17], v[16:17], v[38:39]
	v_pk_mul_f32 v[22:23], v[22:23], v[40:41]
	v_add_f32_e32 v28, v18, v19
	v_add_f32_e32 v29, v20, v21
	v_add_f32_e32 v30, v16, v17
	v_add_f32_e32 v23, v22, v23
	v_mul_f32_e32 v16, v63, v42
	v_mul_f32_e32 v17, v75, v43
	v_cvt_pk_bf16_f32 v16, v16, v17
	v_mul_f32_e32 v17, v84, v44
	v_mul_f32_e32 v18, v86, v45
	v_cvt_pk_bf16_f32 v17, v17, v18
	v_mul_f32_e32 v18, v85, v28
	v_mul_f32_e32 v19, v88, v29
	v_cvt_pk_bf16_f32 v18, v18, v19
	v_mul_f32_e32 v19, v87, v30
	v_mul_f32_e32 v20, v71, v23
	v_cvt_pk_bf16_f32 v19, v19, v20
	v_mul_f32_e32 v20, v64, v42
	v_mul_f32_e32 v21, v60, v43
	v_cvt_pk_bf16_f32 v20, v20, v21
	v_mul_f32_e32 v21, v66, v44
	v_mul_f32_e32 v22, v68, v45
	v_cvt_pk_bf16_f32 v21, v21, v22
	v_mul_f32_e32 v22, v70, v28
	v_mul_f32_e32 v28, v72, v29
	v_mul_f32_e32 v23, v67, v23
	v_cvt_pk_bf16_f32 v22, v22, v28
	v_mul_f32_e32 v28, v65, v30
	v_cvt_pk_bf16_f32 v23, v28, v23
	global_store_dwordx4 v[24:25], v[16:19], off offset:256
	global_store_dwordx4 v[26:27], v[20:23], off offset:256
	global_load_dwordx4 v[16:19], v[82:83], off
	s_nop 0
	global_load_dwordx4 v[20:23], v[80:81], off
	ds_bpermute_b32 v25, v177, v12
	ds_bpermute_b32 v26, v177, v13
	ds_bpermute_b32 v28, v177, v14
	ds_bpermute_b32 v30, v177, v15
	v_mov_b32_e32 v24, v12
	v_mov_b32_e32 v12, v14
	s_waitcnt lgkmcnt(3)
	v_cndmask_b32_e64 v27, v25, -v25, vcc
	s_waitcnt lgkmcnt(2)
	v_cndmask_b32_e64 v29, v26, -v26, vcc
	s_waitcnt lgkmcnt(1)
	v_cndmask_b32_e64 v31, v28, -v28, vcc
	s_waitcnt lgkmcnt(0)
	v_cndmask_b32_e64 v33, v30, -v30, vcc
	s_waitcnt vmcnt(1)
	v_mov_b32_e32 v25, v16
	s_waitcnt vmcnt(0)
	v_mov_b32_e32 v26, v20
	v_mov_b32_e32 v16, v13
	v_mov_b32_e32 v28, v21
	v_mov_b32_e32 v13, v18
	v_mov_b32_e32 v30, v22
	v_mov_b32_e32 v18, v15
	v_mov_b32_e32 v32, v23
	v_pk_mul_f32 v[14:15], v[24:25], v[26:27]
	v_pk_mul_f32 v[16:17], v[16:17], v[28:29]
	v_pk_mul_f32 v[12:13], v[12:13], v[30:31]
	v_pk_mul_f32 v[18:19], v[18:19], v[32:33]
	v_add_f32_e32 v30, v14, v15
	v_add_f32_e32 v31, v16, v17
	v_add_f32_e32 v32, v12, v13
	v_add_f32_e32 v33, v18, v19
	global_load_dwordx4 v[12:15], v[76:77], off offset:16
	global_load_dwordx4 v[16:19], v[78:79], off offset:16
	ds_bpermute_b32 v21, v177, v8
	ds_bpermute_b32 v22, v177, v9
	ds_bpermute_b32 v24, v177, v10
	ds_bpermute_b32 v26, v177, v11
	v_mov_b32_e32 v20, v8
	v_mov_b32_e32 v8, v10
	s_waitcnt lgkmcnt(3)
	v_cndmask_b32_e64 v23, v21, -v21, vcc
	s_waitcnt lgkmcnt(2)
	v_cndmask_b32_e64 v25, v22, -v22, vcc
	s_waitcnt lgkmcnt(1)
	v_cndmask_b32_e64 v27, v24, -v24, vcc
	s_waitcnt lgkmcnt(0)
	v_cndmask_b32_e64 v29, v26, -v26, vcc
	s_waitcnt vmcnt(1)
	v_mov_b32_e32 v21, v12
	s_waitcnt vmcnt(0)
	v_mov_b32_e32 v22, v16
	v_mov_b32_e32 v12, v9
	v_mov_b32_e32 v24, v17
	v_mov_b32_e32 v9, v14
	v_mov_b32_e32 v26, v18
	v_mov_b32_e32 v14, v11
	v_mov_b32_e32 v28, v19
	v_pk_mul_f32 v[10:11], v[20:21], v[22:23]
	v_pk_mul_f32 v[12:13], v[12:13], v[24:25]
	v_pk_mul_f32 v[8:9], v[8:9], v[26:27]
	v_pk_mul_f32 v[14:15], v[14:15], v[28:29]
	v_add_f32_e32 v16, v10, v11
	v_add_f32_e32 v17, v12, v13
	v_add_f32_e32 v8, v8, v9
	v_add_f32_e32 v9, v14, v15
	v_mul_f32_e32 v10, v63, v30
	v_mul_f32_e32 v11, v75, v31
	v_cvt_pk_bf16_f32 v10, v10, v11
	v_mul_f32_e32 v11, v84, v32
	v_mul_f32_e32 v12, v86, v33
	v_cvt_pk_bf16_f32 v11, v11, v12
	v_mul_f32_e32 v12, v85, v16
	v_mul_f32_e32 v13, v88, v17
	v_cvt_pk_bf16_f32 v12, v12, v13
	v_mul_f32_e32 v13, v87, v8
	v_mul_f32_e32 v14, v71, v9
	v_cvt_pk_bf16_f32 v13, v13, v14
	v_mul_f32_e32 v14, v64, v30
	v_mul_f32_e32 v15, v60, v31
	v_cvt_pk_bf16_f32 v14, v14, v15
	v_mul_f32_e32 v15, v66, v32
	v_mul_f32_e32 v18, v68, v33
	v_cvt_pk_bf16_f32 v15, v15, v18
	v_add_co_u32_e64 v18, s[4:5], s63, v120
	v_mul_f32_e32 v16, v70, v16
	v_mul_f32_e32 v17, v72, v17
	v_addc_co_u32_e64 v19, s[4:5], 0, v121, s[4:5]
	v_cvt_pk_bf16_f32 v16, v16, v17
	v_mul_f32_e32 v8, v65, v8
	v_mul_f32_e32 v9, v67, v9
	v_cvt_pk_bf16_f32 v17, v8, v9
	global_store_dwordx4 v[18:19], v[10:13], off
	v_lshl_add_u64 v[8:9], v[120:121], 0, s[26:27]
	s_nop 0
	v_add_co_u32_e64 v12, s[4:5], s64, v120
	v_lshl_add_u64 v[10:11], v[120:121], 0, s[28:29]
	s_nop 0
	v_addc_co_u32_e64 v13, s[4:5], 0, v121, s[4:5]
	global_store_dwordx4 v[12:13], v[14:17], off
	global_load_dwordx4 v[12:15], v[82:83], off
	s_nop 0
	global_load_dwordx4 v[16:19], v[80:81], off
	ds_bpermute_b32 v34, v177, v4
	ds_bpermute_b32 v32, v177, v5
	ds_bpermute_b32 v33, v177, v6
	ds_bpermute_b32 v28, v177, v7
	global_load_dwordx4 v[20:23], v[76:77], off offset:16
	global_load_dwordx4 v[24:27], v[78:79], off offset:16
	s_waitcnt lgkmcnt(0)
	v_cndmask_b32_e64 v29, v28, -v28, vcc
	v_mov_b32_e32 v30, v7
	s_waitcnt vmcnt(3)
	v_mov_b32_e32 v31, v15
	s_waitcnt vmcnt(2)
	v_mov_b32_e32 v28, v19
	v_cndmask_b32_e64 v19, v33, -v33, vcc
	v_mov_b32_e32 v7, v14
	v_cndmask_b32_e64 v15, v32, -v32, vcc
	v_mov_b32_e32 v32, v5
	v_mov_b32_e32 v33, v13
	v_mov_b32_e32 v14, v17
	v_cndmask_b32_e64 v17, v34, -v34, vcc
	v_mov_b32_e32 v5, v12
	ds_bpermute_b32 v13, v177, v0
	v_mov_b32_e32 v12, v0
	ds_bpermute_b32 v34, v177, v1
	ds_bpermute_b32 v35, v177, v2
	v_mov_b32_e32 v0, v2
	ds_bpermute_b32 v2, v177, v3
	v_pk_mul_f32 v[28:29], v[30:31], v[28:29]
	v_pk_mul_f32 v[6:7], v[6:7], v[18:19]
	v_pk_mul_f32 v[14:15], v[32:33], v[14:15]
	v_pk_mul_f32 v[4:5], v[4:5], v[16:17]
	v_add_f32_e32 v18, v28, v29
	v_add_f32_e32 v19, v6, v7
	v_add_f32_e32 v28, v14, v15
	v_add_f32_e32 v29, v4, v5
	s_waitcnt lgkmcnt(3)
; template <class Epi, class Sched>
; __device__ __forceinline__ void gemm_phase(LAS unsigned char* lds, const Gemm g, const Sched& S, const Epi& E) {
;     ...
;         E(acc, cur, wr, wc, fr, fq);
;         if (!has_next) break;
; #pragma unroll
;         for (int a = 0; a < 2; ++a)
; #pragma unroll
;             for (int b = 0; b < 2; ++b)
; #pragma unroll
;                 for (int m = 0; m < 4; ++m)
; #pragma unroll
;                     for (int n = 0; n < 2; ++n) acc[a][b][m][n] = (f32x4){0.f, 0.f, 0.f, 0.f};
;         cur = nxt; cA = nA; cB = nB; ++ui;
;     __device__ __forceinline__ void operator()(const AccT& acc, const Unit& u, int wr, int wc, int fr, int fq) const {
;     ...
;         const int rbase = wr * 64 + fr;
;         const int tb = u.pn * 256 + wc * 32 + 8 * fq;
;         const int o0 = wc * 32 + 8 * fq;
;         const int j = fr & 3; const float sgn = ((fr >> 2) & 1) ? 1.0f : -1.0f;
; #pragma unroll
;         for (int ai = 0; ai < 2; ++ai) {
;             const int hh = 2 * ai + wr;
;             const float l2f = lgd[hh] * 1.4426950408889634f, l2b = lgd[4 + hh] * 1.4426950408889634f;
;             const float zf0 = exp2f((float)(127 - o0) * l2f), zfs = exp2f(-l2f), zb0 = exp2f((float)o0 * l2b), zbs = exp2f(l2b);
; #pragma unroll
;             for (int m = 0; m < 4; ++m) {
;                 const int r = rbase + ai * 128 + m * 16;
;                 const int d = 4 * (2 * m + (fr >> 3)) + j;
; #pragma unroll
;                 for (int bj = 0; bj < 2; ++bj) {
;                     const int t0 = tb + bj * 128;
;                     float v[8];
; #pragma unroll
;                     for (int jj = 0; jj < 4; ++jj) { v[jj] = acc[ai][bj][m][0][jj]; v[4 + jj] = acc[ai][bj][m][1][jj]; }
;                     if constexpr (ROPE) {
;                         const int t = t0 & 2047;
; #pragma unroll
;                         for (int hf = 0; hf < 2; ++hf) {
;                             f32x4 cs, sn;
;                             if (m < 2) { const float c1 = ropeA[(t >> 6) * 16 + d], s1 = ropeA[1024 + (t >> 6) * 16 + d]; cs = (f32x4){c1, c1, c1, c1}; sn = (f32x4){s1, s1, s1, s1}; }
;                             else { const float* cb = ropeA + 2048 + (d - 16) * 64 + (t & 63) + 4 * hf; cs = *(const f32x4*)(cb); sn = *(const f32x4*)(cb + 1024); }
; #pragma unroll
	v_cndmask_b32_e64 v5, v13, -v13, vcc
	s_waitcnt lgkmcnt(2)
	v_cndmask_b32_e64 v7, v34, -v34, vcc
	s_waitcnt lgkmcnt(1)
	v_cndmask_b32_e64 v15, v35, -v35, vcc
	s_waitcnt lgkmcnt(0)
	v_cndmask_b32_e64 v17, v2, -v2, vcc
	s_waitcnt vmcnt(1)
	v_mov_b32_e32 v13, v20
	s_waitcnt vmcnt(0)
	v_mov_b32_e32 v4, v24
	v_mov_b32_e32 v20, v1
	v_mov_b32_e32 v6, v25
	v_mov_b32_e32 v1, v22
	v_mov_b32_e32 v14, v26
	v_mov_b32_e32 v22, v3
	v_mov_b32_e32 v16, v27
	v_pk_mul_f32 v[2:3], v[12:13], v[4:5]
	v_pk_mul_f32 v[4:5], v[20:21], v[6:7]
	v_pk_mul_f32 v[0:1], v[0:1], v[14:15]
	v_pk_mul_f32 v[6:7], v[22:23], v[16:17]
	v_add_f32_e32 v12, v2, v3
	v_add_f32_e32 v13, v4, v5
	v_add_f32_e32 v14, v0, v1
	v_add_f32_e32 v7, v6, v7
	v_mul_f32_e32 v0, v63, v29
	v_mul_f32_e32 v1, v75, v28
	v_cvt_pk_bf16_f32 v0, v0, v1
	v_mul_f32_e32 v1, v84, v19
	v_mul_f32_e32 v2, v86, v18
	v_cvt_pk_bf16_f32 v1, v1, v2
	v_mul_f32_e32 v2, v85, v12
	v_mul_f32_e32 v3, v88, v13
	v_cvt_pk_bf16_f32 v2, v2, v3
	v_mul_f32_e32 v3, v87, v14
	v_mul_f32_e32 v4, v71, v7
	v_cvt_pk_bf16_f32 v3, v3, v4
	v_mul_f32_e32 v4, v64, v29
	v_mul_f32_e32 v5, v60, v28
	v_cvt_pk_bf16_f32 v4, v4, v5
	v_mul_f32_e32 v5, v66, v19
	v_mul_f32_e32 v6, v68, v18
	v_cvt_pk_bf16_f32 v5, v5, v6
	v_mul_f32_e32 v6, v70, v12
	v_mul_f32_e32 v12, v72, v13
	v_mul_f32_e32 v7, v67, v7
	v_cvt_pk_bf16_f32 v6, v6, v12
	v_mul_f32_e32 v12, v65, v14
	v_cvt_pk_bf16_f32 v7, v12, v7
	global_store_dwordx4 v[8:9], v[0:3], off offset:256
	global_store_dwordx4 v[10:11], v[4:7], off offset:256
	s_and_b64 vcc, exec, s[2:3]
	s_mov_b32 s33, s30
	s_mov_b64 s[4:5], s[38:39]
	s_mov_b64 s[0:1], s[36:37]
	s_cbranch_vccz .LBB0_606
	s_branch .Lconc_end_g3
.Lconc_epi1_g3:
	v_mov_b32_e32 v136, v169
	v_mov_b32_e32 v150, v168
	s_lshl_b32 s0, s33, 8
	global_load_dword v154, v137, s[22:23]
	global_load_dword v155, v137, s[22:23] offset:16
	s_or_b32 s0, s0, s53
	v_lshlrev_b32_e32 v151, 3, v136
	v_ashrrev_i32_e32 v136, 1, v150
	v_add_u32_e32 v162, s0, v151
	v_bfi_b32 v136, -4, v136, v150
	v_lshrrev_b32_e32 v146, 2, v162
	v_add_u32_e32 v192, 0x400, v136
	v_and_b32_e32 v187, 0x1f0, v146
	v_add_u32_e32 v146, v192, v187
	v_add_u32_e32 v148, v187, v136
	v_ashrrev_i32_e32 v147, 31, v146
	v_ashrrev_i32_e32 v149, 31, v148
	v_lshl_add_u64 v[146:147], v[146:147], 2, s[16:17]
	v_lshl_add_u64 v[148:149], v[148:149], 2, s[16:17]
	global_load_dword v153, v[146:147], off
	global_load_dword v166, v[148:149], off
	v_and_b32_e32 v157, 64, v174
	v_xor_b32_e32 v156, 4, v174
	v_add_u32_e32 v157, 64, v157
	v_cmp_lt_i32_e32 vcc, v156, v157
	v_mov_b32_e32 v152, v124
	v_add_u32_e32 v151, s53, v151
	v_cndmask_b32_e32 v156, v174, v156, vcc
	v_lshlrev_b32_e32 v177, 2, v156
	ds_bpermute_b32 v124, v177, v124
	v_sub_u32_e32 v156, 0x7f, v151
	v_add_u32_e32 v164, s52, v150
	v_and_b32_e32 v150, 4, v150
	v_cvt_f32_i32_e32 v179, v156
	v_cvt_f32_i32_e32 v178, v151
	v_cmp_eq_u32_e32 vcc, 0, v150
	ds_bpermute_b32 v157, v177, v125
	ds_bpermute_b32 v158, v177, v127
	s_waitcnt lgkmcnt(0)
	v_cndmask_b32_e64 v167, v124, -v124, vcc
	ds_bpermute_b32 v151, v177, v126
	v_ashrrev_i32_e32 v165, 31, v164
	v_and_b32_e32 v186, 56, v162
	s_waitcnt lgkmcnt(0)
	v_cndmask_b32_e64 v151, v151, -v151, vcc
	s_waitcnt vmcnt(0)
	v_mul_f32_e32 v124, 0x3fb8aa3b, v154
	v_mul_f32_e32 v150, 0x3fb8aa3b, v155
	v_cmp_lt_f32_e64 s[4:5], s60, v124
	v_mul_f32_e32 v156, v124, v179
	v_cmp_gt_f32_e64 s[6:7], s59, v150
	v_cndmask_b32_e64 v159, 0, v176, s[4:5]
	v_mul_f32_e32 v160, v150, v178
	v_cndmask_b32_e64 v161, 0, v176, s[6:7]
	v_cmp_gt_f32_e64 s[8:9], s59, v156
	v_fmac_f32_e32 v159, 0xbfb8aa3b, v154
	s_and_b64 s[0:1], s[4:5], exec
	v_cmp_gt_f32_e64 s[4:5], s59, v160
	v_fmac_f32_e32 v161, 0x3fb8aa3b, v155
	v_cndmask_b32_e64 v154, 0, v176, s[8:9]
	v_exp_f32_e32 v155, v159
	v_cndmask_b32_e64 v159, 0, v176, s[4:5]
	v_fmac_f32_e32 v154, v124, v179
	v_fmac_f32_e32 v159, v150, v178
	v_exp_f32_e32 v150, v154
	v_cndmask_b32_e64 v156, 0, v175, s[8:9]
	s_cselect_b32 s8, 0xffffffc0, 0
	v_exp_f32_e32 v161, v161
	v_exp_f32_e32 v159, v159
	v_ldexp_f32 v163, v155, s8
	v_pk_mul_f32 v[154:155], v[152:153], v[166:167]
	v_cndmask_b32_e64 v167, v157, -v157, vcc
	v_mov_b32_e32 v152, v125
	s_and_b64 s[0:1], s[6:7], exec
	v_add_f32_e32 v190, v154, v155
	v_pk_mul_f32 v[154:155], v[152:153], v[166:167]
	v_cndmask_b32_e64 v167, v158, -v158, vcc
	v_mov_b32_e32 v152, v127
	v_cndmask_b32_e64 v160, 0, v175, s[4:5]
	s_cselect_b32 s0, 0xffffffc0, 0
	v_ldexp_f32 v180, v150, v156
	v_add_f32_e32 v191, v154, v155
	v_pk_mul_f32 v[154:155], v[152:153], v[166:167]
	v_ldexp_f32 v124, v161, s0
	v_mul_f32_e32 v161, v126, v166
	v_ldexp_f32 v150, v159, v160
	v_mul_f32_e32 v181, v163, v180
	v_add_f32_e32 v193, v154, v155
	global_load_dword v188, v[148:149], off
	global_load_dword v157, v[146:147], off
	ds_bpermute_b32 v127, v177, v121
	v_mov_b32_e32 v156, v121
	ds_bpermute_b32 v121, v177, v123
	ds_bpermute_b32 v125, v177, v120
	ds_bpermute_b32 v152, v177, v122
	s_waitcnt lgkmcnt(3)
	v_cndmask_b32_e64 v189, v127, -v127, vcc
	s_waitcnt lgkmcnt(1)
	v_cndmask_b32_e64 v158, v125, -v125, vcc
	s_waitcnt lgkmcnt(0)
	v_cndmask_b32_e64 v127, v152, -v152, vcc
	s_waitcnt vmcnt(1)
	v_mul_f32_e32 v159, v120, v188
	s_waitcnt vmcnt(0)
;     __device__ __forceinline__ void operator()(const AccT& acc, const Unit& u, int wr, int wc, int fr, int fq) const {
;     ...
;                 const int r = rbase + ai * 128 + m * 16;
;                 const int d = 4 * (2 * m + (fr >> 3)) + j;
; #pragma unroll
;                 for (int bj = 0; bj < 2; ++bj) {
;                     const int t0 = tb + bj * 128;
;                     float v[8];
; #pragma unroll
;                     for (int jj = 0; jj < 4; ++jj) { v[jj] = acc[ai][bj][m][0][jj]; v[4 + jj] = acc[ai][bj][m][1][jj]; }
;                     if constexpr (ROPE) {
;                         const int t = t0 & 2047;
; #pragma unroll
;                         for (int hf = 0; hf < 2; ++hf) {
;                             f32x4 cs, sn;
;                             if (m < 2) { const float c1 = ropeA[(t >> 6) * 16 + d], s1 = ropeA[1024 + (t >> 6) * 16 + d]; cs = (f32x4){c1, c1, c1, c1}; sn = (f32x4){s1, s1, s1, s1}; }
;                             else { const float* cb = ropeA + 2048 + (d - 16) * 64 + (t & 63) + 4 * hf; cs = *(const f32x4*)(cb); sn = *(const f32x4*)(cb + 1024); }
; #pragma unroll
;                             for (int jj = 0; jj < 4; ++jj) { const float pr = __shfl_xor(v[4 * hf + jj], 4); v[4 * hf + jj] = v[4 * hf + jj] * cs[jj] + sgn * pr * sn[jj]; }
;                             __builtin_amdgcn_sched_barrier(0);
;                         }
;                     }
;                     float zf[8], zb[8]; zf[0] = zf0; zb[0] = zb0;
; #pragma unroll
;                     for (int jj = 1; jj < 8; ++jj) { zf[jj] = zf[jj - 1] * zfs; zb[jj] = zb[jj - 1] * zbs; }
;                     u32x4 wf, wb;
;                     wf.x = cvt_pk_bf16(v[0] * zf[0], v[1] * zf[1]); wf.y = cvt_pk_bf16(v[2] * zf[2], v[3] * zf[3]); wf.z = cvt_pk_bf16(v[4] * zf[4], v[5] * zf[5]); wf.w = cvt_pk_bf16(v[6] * zf[6], v[7] * zf[7]);
;                     wb.x = cvt_pk_bf16(v[0] * zb[0], v[1] * zb[1]); wb.y = cvt_pk_bf16(v[2] * zb[2], v[3] * zb[3]); wb.z = cvt_pk_bf16(v[4] * zb[4], v[5] * zb[5]); wb.w = cvt_pk_bf16(v[6] * zb[6], v[7] * zb[7]);
;                     *(u32x4*)(KTZ + (size_t)r * NT + t0) = wf;
;                     *(u32x4*)(KTZ + (size_t)(256 + r) * NT + t0) = wb;
;                     __builtin_amdgcn_sched_barrier(0);
	v_pk_mul_f32 v[154:155], v[156:157], v[188:189]
	v_cndmask_b32_e64 v189, v121, -v121, vcc
	v_mov_b32_e32 v156, v123
	v_add_f32_e32 v121, v154, v155
	v_pk_mul_f32 v[154:155], v[156:157], v[188:189]
	s_nop 0
	v_add_f32_e32 v123, v154, v155
	v_mov_b32_e32 v125, v153
	v_pk_mul_f32 v[152:153], v[124:125], v[150:151]
	v_mov_b32_e32 v125, v161
	v_pk_mul_f32 v[154:155], v[124:125], v[152:153]
	v_mov_b32_e32 v125, v157
	v_mov_b32_e32 v155, v158
	v_pk_mul_f32 v[156:157], v[124:125], v[154:155]
	v_mov_b32_e32 v158, v124
	v_pk_mul_f32 v[158:159], v[158:159], v[156:157]
	v_mul_f32_e32 v167, v163, v181
	v_mov_b32_e32 v159, v127
	v_mul_f32_e32 v183, v163, v167
	v_pk_mul_f32 v[160:161], v[124:125], v[158:159]
	v_mul_f32_e32 v182, v163, v183
	v_mul_f32_e32 v151, v124, v160
	v_mul_f32_e32 v185, v163, v182
	v_mul_f32_e32 v155, v124, v151
	v_mul_f32_e32 v124, v180, v190
	v_mul_f32_e32 v125, v181, v191
	v_fma_f32 v153, v126, v166, v153
	v_mul_f32_e32 v184, v163, v185
	v_cvt_pk_bf16_f32 v124, v124, v125
	v_mul_f32_e32 v125, v167, v153
	v_mul_f32_e32 v126, v183, v193
	v_fma_f32 v120, v120, v188, v157
	v_mul_f32_e32 v159, v163, v184
	v_cvt_pk_bf16_f32 v125, v125, v126
	v_mul_f32_e32 v126, v182, v120
	v_mul_f32_e32 v127, v185, v121
	v_fma_f32 v122, v122, v188, v161
	v_cvt_pk_bf16_f32 v126, v126, v127
	v_mul_f32_e32 v127, v184, v122
	v_mul_f32_e32 v157, v159, v123
	v_cvt_pk_bf16_f32 v127, v127, v157
	v_mul_f32_e32 v157, v150, v190
	v_mul_f32_e32 v120, v158, v120
	v_mul_f32_e32 v121, v160, v121
	v_mul_f32_e32 v161, v152, v191
	v_cvt_pk_bf16_f32 v188, v157, v161
	v_mul_f32_e32 v153, v154, v153
	v_mul_f32_e32 v157, v156, v193
	v_cvt_pk_bf16_f32 v189, v153, v157
	v_cvt_pk_bf16_f32 v190, v120, v121
	v_mul_f32_e32 v120, v151, v122
	v_mul_f32_e32 v121, v155, v123
	v_cvt_pk_bf16_f32 v191, v120, v121
	v_lshlrev_b64 v[120:121], 17, v[164:165]
	v_lshl_add_u64 v[120:121], s[80:81], 0, v[120:121]
	v_ashrrev_i32_e32 v163, 31, v162
	v_lshl_add_u64 v[120:121], v[162:163], 1, v[120:121]
	s_mov_b64 s[0:1], 0x2000000
	global_store_dwordx4 v[120:121], v[124:127], off
	s_nop 1
	v_lshl_add_u64 v[126:127], v[120:121], 0, s[0:1]
	s_brev_b32 s0, 64
	v_add_co_u32_e64 v122, s[4:5], s0, v120
	s_nop 1
	v_addc_co_u32_e64 v123, s[4:5], 0, v121, s[4:5]
	global_store_dwordx4 v[122:123], v[188:191], off
	v_add_u32_e32 v122, 0x80, v162
	v_lshrrev_b32_e32 v122, 2, v122
	v_and_b32_e32 v153, 0x1f0, v122
	v_add_u32_e32 v122, v153, v192
	v_add_u32_e32 v124, v153, v136
	v_ashrrev_i32_e32 v123, 31, v122
	v_ashrrev_i32_e32 v125, 31, v124
	v_lshl_add_u64 v[122:123], v[122:123], 2, s[16:17]
	v_lshl_add_u64 v[124:125], v[124:125], 2, s[16:17]
	global_load_dword v163, v[122:123], off
	global_load_dword v164, v[124:125], off
	ds_bpermute_b32 v157, v177, v116
	v_mov_b32_e32 v162, v116
	ds_bpermute_b32 v116, v177, v117
	ds_bpermute_b32 v161, v177, v118
	ds_bpermute_b32 v166, v177, v119
	s_waitcnt lgkmcnt(3)
	v_cndmask_b32_e64 v165, v157, -v157, vcc
	s_waitcnt vmcnt(0)
	v_pk_mul_f32 v[188:189], v[162:163], v[164:165]
	s_waitcnt lgkmcnt(2)
	v_cndmask_b32_e64 v165, v116, -v116, vcc
	v_mov_b32_e32 v162, v117
	v_pk_mul_f32 v[116:117], v[162:163], v[164:165]
	s_waitcnt lgkmcnt(1)
	v_cndmask_b32_e64 v165, v161, -v161, vcc
	v_mov_b32_e32 v162, v118
	v_add_f32_e32 v161, v116, v117
	v_pk_mul_f32 v[116:117], v[162:163], v[164:165]
	s_waitcnt lgkmcnt(0)
	v_cndmask_b32_e64 v165, v166, -v166, vcc
	v_mov_b32_e32 v162, v119
	v_add_f32_e32 v166, v116, v117
	v_pk_mul_f32 v[116:117], v[162:163], v[164:165]
	v_add_f32_e32 v157, v188, v189
	v_add_f32_e32 v164, v116, v117
	global_load_dword v117, v[122:123], off
	global_load_dword v118, v[124:125], off
	ds_bpermute_b32 v119, v177, v112
	v_mov_b32_e32 v116, v112
	ds_bpermute_b32 v112, v177, v113
	ds_bpermute_b32 v165, v177, v114
	ds_bpermute_b32 v188, v177, v115
	s_waitcnt lgkmcnt(3)
	v_cndmask_b32_e64 v119, v119, -v119, vcc
	s_waitcnt vmcnt(0)
	v_pk_mul_f32 v[162:163], v[116:117], v[118:119]
	s_waitcnt lgkmcnt(2)
	v_cndmask_b32_e64 v119, v112, -v112, vcc
	v_mov_b32_e32 v116, v113
	v_pk_mul_f32 v[112:113], v[116:117], v[118:119]
	s_waitcnt lgkmcnt(1)
	v_cndmask_b32_e64 v119, v165, -v165, vcc
	v_mov_b32_e32 v116, v114
	v_add_f32_e32 v162, v162, v163
	v_add_f32_e32 v163, v112, v113
	v_pk_mul_f32 v[112:113], v[116:117], v[118:119]
	s_waitcnt lgkmcnt(0)
	v_cndmask_b32_e64 v119, v188, -v188, vcc
	v_mov_b32_e32 v116, v115
	v_add_f32_e32 v165, v112, v113
	v_pk_mul_f32 v[112:113], v[116:117], v[118:119]
	s_nop 0
	v_add_f32_e32 v119, v112, v113
	v_mul_f32_e32 v112, v180, v157
	v_mul_f32_e32 v113, v181, v161
	v_cvt_pk_bf16_f32 v112, v112, v113
	v_mul_f32_e32 v113, v167, v166
	v_mul_f32_e32 v114, v183, v164
	v_cvt_pk_bf16_f32 v113, v113, v114
	v_mul_f32_e32 v114, v182, v162
	v_mul_f32_e32 v115, v185, v163
	v_cvt_pk_bf16_f32 v114, v114, v115
	v_mul_f32_e32 v115, v184, v165
	v_mul_f32_e32 v116, v159, v119
	v_cvt_pk_bf16_f32 v115, v115, v116
	v_mul_f32_e32 v116, v150, v157
	v_mul_f32_e32 v117, v152, v161
	v_cvt_pk_bf16_f32 v116, v116, v117
	v_mul_f32_e32 v117, v154, v166
	v_mul_f32_e32 v118, v156, v164
	v_cvt_pk_bf16_f32 v117, v117, v118
	v_mul_f32_e32 v118, v158, v162
	v_mul_f32_e32 v157, v160, v163
	v_mul_f32_e32 v119, v155, v119
	v_cvt_pk_bf16_f32 v118, v118, v157
	v_mul_f32_e32 v157, v151, v165
	v_cvt_pk_bf16_f32 v119, v157, v119
	global_store_dwordx4 v[120:121], v[112:115], off offset:256
	global_store_dwordx4 v[126:127], v[116:119], off offset:256
	v_add_u32_e32 v161, 0x408, v136
	v_add_u32_e32 v157, 8, v136
	v_add_u32_e32 v112, v161, v187
	v_add_u32_e32 v114, v187, v157
	v_ashrrev_i32_e32 v113, 31, v112
	v_ashrrev_i32_e32 v115, 31, v114
	v_lshl_add_u64 v[112:113], v[112:113], 2, s[16:17]
	v_lshl_add_u64 v[114:115], v[114:115], 2, s[16:17]
	global_load_dword v117, v[112:113], off
	global_load_dword v118, v[114:115], off
	ds_bpermute_b32 v119, v177, v108
	v_mov_b32_e32 v116, v108
	ds_bpermute_b32 v108, v177, v109
	ds_bpermute_b32 v162, v177, v110
	ds_bpermute_b32 v163, v177, v111
	s_waitcnt lgkmcnt(3)
;     __device__ __forceinline__ void operator()(const AccT& acc, const Unit& u, int wr, int wc, int fr, int fq) const {
;     ...
;                 const int r = rbase + ai * 128 + m * 16;
;                 const int d = 4 * (2 * m + (fr >> 3)) + j;
; #pragma unroll
;                 for (int bj = 0; bj < 2; ++bj) {
;                     const int t0 = tb + bj * 128;
;                     float v[8];
; #pragma unroll
;                     for (int jj = 0; jj < 4; ++jj) { v[jj] = acc[ai][bj][m][0][jj]; v[4 + jj] = acc[ai][bj][m][1][jj]; }
;                     if constexpr (ROPE) {
;                         const int t = t0 & 2047;
; #pragma unroll
;                         for (int hf = 0; hf < 2; ++hf) {
;                             f32x4 cs, sn;
;                             if (m < 2) { const float c1 = ropeA[(t >> 6) * 16 + d], s1 = ropeA[1024 + (t >> 6) * 16 + d]; cs = (f32x4){c1, c1, c1, c1}; sn = (f32x4){s1, s1, s1, s1}; }
;                             else { const float* cb = ropeA + 2048 + (d - 16) * 64 + (t & 63) + 4 * hf; cs = *(const f32x4*)(cb); sn = *(const f32x4*)(cb + 1024); }
; #pragma unroll
;                             for (int jj = 0; jj < 4; ++jj) { const float pr = __shfl_xor(v[4 * hf + jj], 4); v[4 * hf + jj] = v[4 * hf + jj] * cs[jj] + sgn * pr * sn[jj]; }
;                             __builtin_amdgcn_sched_barrier(0);
;                         }
;                     }
;                     float zf[8], zb[8]; zf[0] = zf0; zb[0] = zb0;
; #pragma unroll
;                     for (int jj = 1; jj < 8; ++jj) { zf[jj] = zf[jj - 1] * zfs; zb[jj] = zb[jj - 1] * zbs; }
;                     u32x4 wf, wb;
;                     wf.x = cvt_pk_bf16(v[0] * zf[0], v[1] * zf[1]); wf.y = cvt_pk_bf16(v[2] * zf[2], v[3] * zf[3]); wf.z = cvt_pk_bf16(v[4] * zf[4], v[5] * zf[5]); wf.w = cvt_pk_bf16(v[6] * zf[6], v[7] * zf[7]);
;                     wb.x = cvt_pk_bf16(v[0] * zb[0], v[1] * zb[1]); wb.y = cvt_pk_bf16(v[2] * zb[2], v[3] * zb[3]); wb.z = cvt_pk_bf16(v[4] * zb[4], v[5] * zb[5]); wb.w = cvt_pk_bf16(v[6] * zb[6], v[7] * zb[7]);
;                     *(u32x4*)(KTZ + (size_t)r * NT + t0) = wf;
;                     *(u32x4*)(KTZ + (size_t)(256 + r) * NT + t0) = wb;
;                     __builtin_amdgcn_sched_barrier(0);
	v_cndmask_b32_e64 v119, v119, -v119, vcc
	s_waitcnt vmcnt(0)
	v_pk_mul_f32 v[126:127], v[116:117], v[118:119]
	s_waitcnt lgkmcnt(2)
	v_cndmask_b32_e64 v119, v108, -v108, vcc
	v_mov_b32_e32 v116, v109
	v_pk_mul_f32 v[108:109], v[116:117], v[118:119]
	s_waitcnt lgkmcnt(1)
	v_cndmask_b32_e64 v119, v162, -v162, vcc
	v_mov_b32_e32 v116, v110
	v_add_f32_e32 v126, v126, v127
	v_add_f32_e32 v127, v108, v109
	v_pk_mul_f32 v[108:109], v[116:117], v[118:119]
	s_waitcnt lgkmcnt(0)
	v_cndmask_b32_e64 v119, v163, -v163, vcc
	v_mov_b32_e32 v116, v111
	v_add_f32_e32 v162, v108, v109
	v_pk_mul_f32 v[108:109], v[116:117], v[118:119]
	s_nop 0
	v_add_f32_e32 v118, v108, v109
	global_load_dword v109, v[112:113], off
	global_load_dword v110, v[114:115], off
	ds_bpermute_b32 v111, v177, v104
	v_mov_b32_e32 v108, v104
	ds_bpermute_b32 v104, v177, v105
	ds_bpermute_b32 v119, v177, v106
	ds_bpermute_b32 v163, v177, v107
	s_waitcnt lgkmcnt(3)
	v_cndmask_b32_e64 v111, v111, -v111, vcc
	s_waitcnt vmcnt(0)
	v_pk_mul_f32 v[116:117], v[108:109], v[110:111]
	s_waitcnt lgkmcnt(2)
	v_cndmask_b32_e64 v111, v104, -v104, vcc
	v_mov_b32_e32 v108, v105
	v_pk_mul_f32 v[104:105], v[108:109], v[110:111]
	s_waitcnt lgkmcnt(1)
	v_cndmask_b32_e64 v111, v119, -v119, vcc
	v_mov_b32_e32 v108, v106
	v_add_f32_e32 v119, v104, v105
	v_pk_mul_f32 v[104:105], v[108:109], v[110:111]
	s_waitcnt lgkmcnt(0)
	v_cndmask_b32_e64 v111, v163, -v163, vcc
	v_mov_b32_e32 v108, v107
	v_add_f32_e32 v163, v104, v105
	v_pk_mul_f32 v[104:105], v[108:109], v[110:111]
	v_add_f32_e32 v164, v116, v117
	v_add_f32_e32 v108, v104, v105
	v_mul_f32_e32 v104, v180, v126
	v_mul_f32_e32 v105, v181, v127
	v_cvt_pk_bf16_f32 v104, v104, v105
	v_mul_f32_e32 v105, v167, v162
	v_mul_f32_e32 v106, v183, v118
	v_cvt_pk_bf16_f32 v105, v105, v106
	v_mul_f32_e32 v106, v182, v164
	v_mul_f32_e32 v107, v185, v119
	v_cvt_pk_bf16_f32 v106, v106, v107
	v_mul_f32_e32 v107, v184, v163
	v_mul_f32_e32 v109, v159, v108
	v_cvt_pk_bf16_f32 v107, v107, v109
	v_mul_f32_e32 v109, v150, v126
	v_mul_f32_e32 v110, v152, v127
	v_cvt_pk_bf16_f32 v116, v109, v110
	v_mul_f32_e32 v109, v154, v162
	v_mul_f32_e32 v110, v156, v118
	v_cvt_pk_bf16_f32 v117, v109, v110
	v_mul_f32_e32 v109, v158, v164
	v_mul_f32_e32 v110, v160, v119
	v_cvt_pk_bf16_f32 v118, v109, v110
	v_mul_f32_e32 v109, v151, v163
	v_mul_f32_e32 v108, v155, v108
	s_mov_b64 s[0:1], 0x200000
	v_cvt_pk_bf16_f32 v119, v109, v108
	v_lshl_add_u64 v[108:109], v[120:121], 0, s[0:1]
	s_mov_b32 s0, 0x200000
	v_add_co_u32_e64 v110, s[4:5], s0, v120
	s_mov_b64 s[0:1], 0x2200000
	s_nop 0
	v_addc_co_u32_e64 v111, s[4:5], 0, v121, s[4:5]
	global_store_dwordx4 v[110:111], v[104:107], off
	v_lshl_add_u64 v[110:111], v[120:121], 0, s[0:1]
	s_mov_b32 s0, 0x2200000
	v_add_co_u32_e64 v104, s[4:5], s0, v120
	s_nop 1
	v_addc_co_u32_e64 v105, s[4:5], 0, v121, s[4:5]
	global_store_dwordx4 v[104:105], v[116:119], off
	v_add_u32_e32 v104, v153, v161
	v_add_u32_e32 v106, v153, v157
	v_ashrrev_i32_e32 v105, 31, v104
	v_ashrrev_i32_e32 v107, 31, v106
	v_lshl_add_u64 v[104:105], v[104:105], 2, s[16:17]
	v_lshl_add_u64 v[106:107], v[106:107], 2, s[16:17]
	global_load_dword v117, v[104:105], off
	global_load_dword v118, v[106:107], off
	ds_bpermute_b32 v119, v177, v100
	v_mov_b32_e32 v116, v100
	ds_bpermute_b32 v100, v177, v101
	ds_bpermute_b32 v153, v177, v102
	ds_bpermute_b32 v157, v177, v103
	s_waitcnt lgkmcnt(3)
	v_cndmask_b32_e64 v119, v119, -v119, vcc
	s_waitcnt vmcnt(0)
	v_pk_mul_f32 v[126:127], v[116:117], v[118:119]
	s_waitcnt lgkmcnt(2)
	v_cndmask_b32_e64 v119, v100, -v100, vcc
	v_mov_b32_e32 v116, v101
	v_pk_mul_f32 v[100:101], v[116:117], v[118:119]
	s_waitcnt lgkmcnt(1)
	v_cndmask_b32_e64 v119, v153, -v153, vcc
	v_mov_b32_e32 v116, v102
	v_add_f32_e32 v126, v126, v127
	v_add_f32_e32 v127, v100, v101
	v_pk_mul_f32 v[100:101], v[116:117], v[118:119]
	s_waitcnt lgkmcnt(0)
	v_cndmask_b32_e64 v119, v157, -v157, vcc
	v_mov_b32_e32 v116, v103
	v_add_f32_e32 v153, v100, v101
	v_pk_mul_f32 v[100:101], v[116:117], v[118:119]
	s_nop 0
	v_add_f32_e32 v118, v100, v101
	global_load_dword v101, v[104:105], off
	global_load_dword v102, v[106:107], off
	ds_bpermute_b32 v103, v177, v96
	v_mov_b32_e32 v100, v96
	ds_bpermute_b32 v96, v177, v97
	ds_bpermute_b32 v119, v177, v98
	ds_bpermute_b32 v157, v177, v99
	s_waitcnt lgkmcnt(3)
	v_cndmask_b32_e64 v103, v103, -v103, vcc
	s_waitcnt vmcnt(0)
	v_pk_mul_f32 v[116:117], v[100:101], v[102:103]
	s_waitcnt lgkmcnt(2)
	v_cndmask_b32_e64 v103, v96, -v96, vcc
	v_mov_b32_e32 v100, v97
	v_pk_mul_f32 v[96:97], v[100:101], v[102:103]
	s_waitcnt lgkmcnt(1)
	v_cndmask_b32_e64 v103, v119, -v119, vcc
	v_mov_b32_e32 v100, v98
	v_add_f32_e32 v116, v116, v117
	v_add_f32_e32 v117, v96, v97
	v_pk_mul_f32 v[96:97], v[100:101], v[102:103]
	s_waitcnt lgkmcnt(0)
; __device__ __forceinline__ unsigned cvt_pk_bf16(float lo, float hi) { unsigned r; asm volatile("v_cvt_pk_bf16_f32 %0, %1, %2" : "=v"(r) : "v"(lo), "v"(hi)); return r; }
;     __device__ __forceinline__ void operator()(const AccT& acc, const Unit& u, int wr, int wc, int fr, int fq) const {
;     ...
;                         const int t = t0 & 2047;
; #pragma unroll
;                         for (int hf = 0; hf < 2; ++hf) {
;                             f32x4 cs, sn;
;                             if (m < 2) { const float c1 = ropeA[(t >> 6) * 16 + d], s1 = ropeA[1024 + (t >> 6) * 16 + d]; cs = (f32x4){c1, c1, c1, c1}; sn = (f32x4){s1, s1, s1, s1}; }
;                             else { const float* cb = ropeA + 2048 + (d - 16) * 64 + (t & 63) + 4 * hf; cs = *(const f32x4*)(cb); sn = *(const f32x4*)(cb + 1024); }
; #pragma unroll
;                             for (int jj = 0; jj < 4; ++jj) { const float pr = __shfl_xor(v[4 * hf + jj], 4); v[4 * hf + jj] = v[4 * hf + jj] * cs[jj] + sgn * pr * sn[jj]; }
;                             __builtin_amdgcn_sched_barrier(0);
;                         }
;                     }
;                     float zf[8], zb[8]; zf[0] = zf0; zb[0] = zb0;
; #pragma unroll
;                     for (int jj = 1; jj < 8; ++jj) { zf[jj] = zf[jj - 1] * zfs; zb[jj] = zb[jj - 1] * zbs; }
;                     u32x4 wf, wb;
;                     wf.x = cvt_pk_bf16(v[0] * zf[0], v[1] * zf[1]); wf.y = cvt_pk_bf16(v[2] * zf[2], v[3] * zf[3]); wf.z = cvt_pk_bf16(v[4] * zf[4], v[5] * zf[5]); wf.w = cvt_pk_bf16(v[6] * zf[6], v[7] * zf[7]);
;                     wb.x = cvt_pk_bf16(v[0] * zb[0], v[1] * zb[1]); wb.y = cvt_pk_bf16(v[2] * zb[2], v[3] * zb[3]); wb.z = cvt_pk_bf16(v[4] * zb[4], v[5] * zb[5]); wb.w = cvt_pk_bf16(v[6] * zb[6], v[7] * zb[7]);
;                     *(u32x4*)(KTZ + (size_t)r * NT + t0) = wf;
;                     *(u32x4*)(KTZ + (size_t)(256 + r) * NT + t0) = wb;
;                     __builtin_amdgcn_sched_barrier(0);
	v_cndmask_b32_e64 v103, v157, -v157, vcc
	v_mov_b32_e32 v100, v99
	v_add_f32_e32 v119, v96, v97
	v_pk_mul_f32 v[96:97], v[100:101], v[102:103]
	s_nop 0
	v_add_f32_e32 v103, v96, v97
	v_mul_f32_e32 v96, v180, v126
	v_mul_f32_e32 v97, v181, v127
	v_cvt_pk_bf16_f32 v96, v96, v97
	v_mul_f32_e32 v97, v167, v153
	v_mul_f32_e32 v98, v183, v118
	v_cvt_pk_bf16_f32 v97, v97, v98
	v_mul_f32_e32 v98, v182, v116
	v_mul_f32_e32 v99, v185, v117
	v_cvt_pk_bf16_f32 v98, v98, v99
	v_mul_f32_e32 v99, v184, v119
	v_mul_f32_e32 v100, v159, v103
	v_cvt_pk_bf16_f32 v99, v99, v100
	v_mul_f32_e32 v100, v150, v126
	v_mul_f32_e32 v101, v152, v127
	v_cvt_pk_bf16_f32 v100, v100, v101
	v_mul_f32_e32 v101, v154, v153
	v_mul_f32_e32 v102, v156, v118
	v_cvt_pk_bf16_f32 v101, v101, v102
	v_mul_f32_e32 v102, v158, v116
	v_mul_f32_e32 v116, v160, v117
	v_mul_f32_e32 v103, v155, v103
	v_cvt_pk_bf16_f32 v102, v102, v116
	v_mul_f32_e32 v116, v151, v119
	v_cvt_pk_bf16_f32 v103, v116, v103
	global_store_dwordx4 v[108:109], v[96:99], off offset:256
	global_store_dwordx4 v[110:111], v[100:103], off offset:256
	s_nop 1
	v_lshlrev_b32_e32 v100, 6, v136
	v_ashrrev_i32_e32 v101, 31, v100
	v_lshlrev_b64 v[102:103], 2, v[100:101]
	v_lshl_add_u64 v[96:97], s[24:25], 0, v[102:103]
	v_lshlrev_b32_e32 v136, 2, v186
	v_lshl_add_u64 v[96:97], v[96:97], 0, v[136:137]
	v_add_co_u32_e64 v98, s[4:5], s61, v96
	ds_bpermute_b32 v101, v177, v92
	s_nop 0
	v_addc_co_u32_e64 v99, s[4:5], 0, v97, s[4:5]
	global_load_dwordx4 v[108:111], v[98:99], off
	global_load_dwordx4 v[116:119], v[96:97], off
	ds_bpermute_b32 v127, v177, v93
	ds_bpermute_b32 v153, v177, v94
	ds_bpermute_b32 v157, v177, v95
	v_mov_b32_e32 v126, v92
	v_mov_b32_e32 v92, v94
	s_waitcnt lgkmcnt(3)
	v_cndmask_b32_e64 v163, v101, -v101, vcc
	s_waitcnt lgkmcnt(2)
	v_cndmask_b32_e64 v165, v127, -v127, vcc
	s_waitcnt lgkmcnt(1)
	v_cndmask_b32_e64 v187, v153, -v153, vcc
	s_waitcnt lgkmcnt(0)
	v_cndmask_b32_e64 v189, v157, -v157, vcc
	s_waitcnt vmcnt(1)
	v_mov_b32_e32 v127, v108
	s_waitcnt vmcnt(0)
	v_mov_b32_e32 v162, v116
	v_mov_b32_e32 v108, v93
	v_mov_b32_e32 v164, v117
	v_mov_b32_e32 v93, v110
	v_mov_b32_e32 v186, v118
	v_mov_b32_e32 v110, v95
	v_mov_b32_e32 v188, v119
	v_pk_mul_f32 v[94:95], v[126:127], v[162:163]
	v_pk_mul_f32 v[108:109], v[108:109], v[164:165]
	v_pk_mul_f32 v[92:93], v[92:93], v[186:187]
	v_pk_mul_f32 v[110:111], v[110:111], v[188:189]
	v_add_f32_e32 v101, v94, v95
	v_add_f32_e32 v153, v108, v109
	v_add_f32_e32 v157, v92, v93
	v_add_f32_e32 v161, v110, v111
	v_lshl_add_u64 v[92:93], s[16:17], 0, v[102:103]
	v_lshl_add_u64 v[94:95], v[92:93], 0, v[136:137]
	v_add_co_u32_e64 v92, s[4:5], s62, v94
	ds_bpermute_b32 v103, v177, v88
	s_nop 0
	v_addc_co_u32_e64 v93, s[4:5], 0, v95, s[4:5]
	v_add_co_u32_e64 v94, s[4:5], s49, v94
	ds_bpermute_b32 v126, v177, v89
	s_nop 0
	v_addc_co_u32_e64 v95, s[4:5], 0, v95, s[4:5]
	global_load_dwordx4 v[108:111], v[92:93], off offset:16
	global_load_dwordx4 v[116:119], v[94:95], off offset:16
	ds_bpermute_b32 v162, v177, v90
	ds_bpermute_b32 v164, v177, v91
	v_mov_b32_e32 v102, v88
	v_mov_b32_e32 v88, v90
	s_waitcnt lgkmcnt(3)
	v_cndmask_b32_e64 v127, v103, -v103, vcc
	s_waitcnt lgkmcnt(2)
	v_cndmask_b32_e64 v163, v126, -v126, vcc
	s_waitcnt lgkmcnt(1)
	v_cndmask_b32_e64 v165, v162, -v162, vcc
	s_waitcnt lgkmcnt(0)
	v_cndmask_b32_e64 v187, v164, -v164, vcc
	s_waitcnt vmcnt(1)
	v_mov_b32_e32 v103, v108
	s_waitcnt vmcnt(0)
	v_mov_b32_e32 v126, v116
	v_mov_b32_e32 v108, v89
	v_mov_b32_e32 v162, v117
	v_mov_b32_e32 v89, v110
	v_mov_b32_e32 v164, v118
	v_mov_b32_e32 v110, v91
	v_mov_b32_e32 v186, v119
	v_pk_mul_f32 v[90:91], v[102:103], v[126:127]
	v_pk_mul_f32 v[102:103], v[108:109], v[162:163]
	v_pk_mul_f32 v[88:89], v[88:89], v[164:165]
	v_pk_mul_f32 v[108:109], v[110:111], v[186:187]
	v_add_f32_e32 v90, v90, v91
	v_add_f32_e32 v91, v102, v103
	v_add_f32_e32 v88, v88, v89
	v_add_f32_e32 v89, v108, v109
	v_mul_f32_e32 v102, v180, v101
	v_mul_f32_e32 v103, v181, v153
	v_cvt_pk_bf16_f32 v108, v102, v103
	v_mul_f32_e32 v102, v167, v157
	v_mul_f32_e32 v103, v183, v161
	v_cvt_pk_bf16_f32 v109, v102, v103
	v_mul_f32_e32 v102, v182, v90
	v_mul_f32_e32 v103, v185, v91
	v_cvt_pk_bf16_f32 v110, v102, v103
	v_mul_f32_e32 v102, v184, v88
	v_mul_f32_e32 v103, v159, v89
	v_cvt_pk_bf16_f32 v111, v102, v103
	v_mul_f32_e32 v101, v150, v101
	v_mul_f32_e32 v102, v152, v153
	v_mul_f32_e32 v88, v151, v88
	v_mul_f32_e32 v89, v155, v89
	s_mov_b64 s[0:1], 0x400000
	v_cvt_pk_bf16_f32 v116, v101, v102
	v_mul_f32_e32 v101, v154, v157
	v_mul_f32_e32 v102, v156, v161
	v_cvt_pk_bf16_f32 v117, v101, v102
	v_mul_f32_e32 v90, v158, v90
	v_mul_f32_e32 v91, v160, v91
	v_cvt_pk_bf16_f32 v118, v90, v91
	v_cvt_pk_bf16_f32 v119, v88, v89
	v_lshl_add_u64 v[88:89], v[120:121], 0, s[0:1]
	s_mov_b32 s0, 0x400000
	v_add_co_u32_e64 v90, s[4:5], s0, v120
	s_mov_b64 s[0:1], 0x2400000
	s_nop 0
	v_addc_co_u32_e64 v91, s[4:5], 0, v121, s[4:5]
	global_store_dwordx4 v[90:91], v[108:111], off
	v_lshl_add_u64 v[90:91], v[120:121], 0, s[0:1]
	s_mov_b32 s0, 0x2400000
	v_add_co_u32_e64 v102, s[4:5], s0, v120
	s_nop 1
	v_addc_co_u32_e64 v103, s[4:5], 0, v121, s[4:5]
	global_store_dwordx4 v[102:103], v[116:119], off
	global_load_dwordx4 v[108:111], v[98:99], off
	s_nop 0
	global_load_dwordx4 v[116:119], v[96:97], off
	ds_bpermute_b32 v101, v177, v84
	ds_bpermute_b32 v103, v177, v85
	ds_bpermute_b32 v126, v177, v86
	ds_bpermute_b32 v153, v177, v87
	v_mov_b32_e32 v102, v84
	v_mov_b32_e32 v84, v86
	s_waitcnt lgkmcnt(3)
	v_cndmask_b32_e64 v127, v101, -v101, vcc
	s_waitcnt lgkmcnt(2)
	v_cndmask_b32_e64 v163, v103, -v103, vcc
	s_waitcnt lgkmcnt(1)
; __device__ __forceinline__ unsigned cvt_pk_bf16(float lo, float hi) { unsigned r; asm volatile("v_cvt_pk_bf16_f32 %0, %1, %2" : "=v"(r) : "v"(lo), "v"(hi)); return r; }
;     __device__ __forceinline__ void operator()(const AccT& acc, const Unit& u, int wr, int wc, int fr, int fq) const {
;     ...
;                         const int t = t0 & 2047;
; #pragma unroll
;                         for (int hf = 0; hf < 2; ++hf) {
;                             f32x4 cs, sn;
;                             if (m < 2) { const float c1 = ropeA[(t >> 6) * 16 + d], s1 = ropeA[1024 + (t >> 6) * 16 + d]; cs = (f32x4){c1, c1, c1, c1}; sn = (f32x4){s1, s1, s1, s1}; }
;                             else { const float* cb = ropeA + 2048 + (d - 16) * 64 + (t & 63) + 4 * hf; cs = *(const f32x4*)(cb); sn = *(const f32x4*)(cb + 1024); }
; #pragma unroll
;                             for (int jj = 0; jj < 4; ++jj) { const float pr = __shfl_xor(v[4 * hf + jj], 4); v[4 * hf + jj] = v[4 * hf + jj] * cs[jj] + sgn * pr * sn[jj]; }
;                             __builtin_amdgcn_sched_barrier(0);
;                         }
;                     }
;                     float zf[8], zb[8]; zf[0] = zf0; zb[0] = zb0;
; #pragma unroll
;                     for (int jj = 1; jj < 8; ++jj) { zf[jj] = zf[jj - 1] * zfs; zb[jj] = zb[jj - 1] * zbs; }
;                     u32x4 wf, wb;
;                     wf.x = cvt_pk_bf16(v[0] * zf[0], v[1] * zf[1]); wf.y = cvt_pk_bf16(v[2] * zf[2], v[3] * zf[3]); wf.z = cvt_pk_bf16(v[4] * zf[4], v[5] * zf[5]); wf.w = cvt_pk_bf16(v[6] * zf[6], v[7] * zf[7]);
;                     wb.x = cvt_pk_bf16(v[0] * zb[0], v[1] * zb[1]); wb.y = cvt_pk_bf16(v[2] * zb[2], v[3] * zb[3]); wb.z = cvt_pk_bf16(v[4] * zb[4], v[5] * zb[5]); wb.w = cvt_pk_bf16(v[6] * zb[6], v[7] * zb[7]);
;                     *(u32x4*)(KTZ + (size_t)r * NT + t0) = wf;
;                     *(u32x4*)(KTZ + (size_t)(256 + r) * NT + t0) = wb;
;                     __builtin_amdgcn_sched_barrier(0);
	v_cndmask_b32_e64 v165, v126, -v126, vcc
	s_waitcnt lgkmcnt(0)
	v_cndmask_b32_e64 v187, v153, -v153, vcc
	s_waitcnt vmcnt(1)
	v_mov_b32_e32 v103, v108
	s_waitcnt vmcnt(0)
	v_mov_b32_e32 v126, v116
	v_mov_b32_e32 v108, v85
	v_mov_b32_e32 v162, v117
	v_mov_b32_e32 v85, v110
	v_mov_b32_e32 v164, v118
	v_mov_b32_e32 v110, v87
	v_mov_b32_e32 v186, v119
	v_pk_mul_f32 v[86:87], v[102:103], v[126:127]
	v_pk_mul_f32 v[102:103], v[108:109], v[162:163]
	v_pk_mul_f32 v[84:85], v[84:85], v[164:165]
	v_pk_mul_f32 v[108:109], v[110:111], v[186:187]
	v_add_f32_e32 v101, v86, v87
	v_add_f32_e32 v153, v102, v103
	v_add_f32_e32 v157, v84, v85
	v_add_f32_e32 v161, v108, v109
	global_load_dwordx4 v[84:87], v[92:93], off offset:16
	global_load_dwordx4 v[108:111], v[94:95], off offset:16
	ds_bpermute_b32 v103, v177, v80
	ds_bpermute_b32 v116, v177, v81
	ds_bpermute_b32 v118, v177, v82
	ds_bpermute_b32 v126, v177, v83
	v_mov_b32_e32 v102, v80
	v_mov_b32_e32 v80, v82
	s_waitcnt lgkmcnt(3)
	v_cndmask_b32_e64 v117, v103, -v103, vcc
	s_waitcnt lgkmcnt(2)
	v_cndmask_b32_e64 v119, v116, -v116, vcc
	s_waitcnt lgkmcnt(1)
	v_cndmask_b32_e64 v127, v118, -v118, vcc
	s_waitcnt lgkmcnt(0)
	v_cndmask_b32_e64 v163, v126, -v126, vcc
	s_waitcnt vmcnt(1)
	v_mov_b32_e32 v103, v84
	s_waitcnt vmcnt(0)
	v_mov_b32_e32 v116, v108
	v_mov_b32_e32 v84, v81
	v_mov_b32_e32 v118, v109
	v_mov_b32_e32 v81, v86
	v_mov_b32_e32 v126, v110
	v_mov_b32_e32 v86, v83
	v_mov_b32_e32 v162, v111
	v_pk_mul_f32 v[82:83], v[102:103], v[116:117]
	v_pk_mul_f32 v[84:85], v[84:85], v[118:119]
	v_pk_mul_f32 v[80:81], v[80:81], v[126:127]
	v_pk_mul_f32 v[86:87], v[86:87], v[162:163]
	v_add_f32_e32 v102, v82, v83
	v_add_f32_e32 v103, v84, v85
	v_add_f32_e32 v108, v80, v81
	v_add_f32_e32 v87, v86, v87
	v_mul_f32_e32 v80, v180, v101
	v_mul_f32_e32 v81, v181, v153
	v_cvt_pk_bf16_f32 v80, v80, v81
	v_mul_f32_e32 v81, v167, v157
	v_mul_f32_e32 v82, v183, v161
	v_cvt_pk_bf16_f32 v81, v81, v82
	v_mul_f32_e32 v82, v182, v102
	v_mul_f32_e32 v83, v185, v103
	v_cvt_pk_bf16_f32 v82, v82, v83
	v_mul_f32_e32 v83, v184, v108
	v_mul_f32_e32 v84, v159, v87
	v_cvt_pk_bf16_f32 v83, v83, v84
	v_mul_f32_e32 v84, v150, v101
	v_mul_f32_e32 v85, v152, v153
	v_cvt_pk_bf16_f32 v84, v84, v85
	v_mul_f32_e32 v85, v154, v157
	v_mul_f32_e32 v86, v156, v161
	v_cvt_pk_bf16_f32 v85, v85, v86
	v_mul_f32_e32 v86, v158, v102
	v_mul_f32_e32 v101, v160, v103
	v_mul_f32_e32 v87, v155, v87
	v_cvt_pk_bf16_f32 v86, v86, v101
	v_mul_f32_e32 v101, v151, v108
	v_cvt_pk_bf16_f32 v87, v101, v87
	global_store_dwordx4 v[88:89], v[80:83], off offset:256
	global_store_dwordx4 v[90:91], v[84:87], off offset:256
	s_nop 0
	v_add_u32_e32 v80, 0x200, v100
	v_ashrrev_i32_e32 v81, 31, v80
	v_lshl_add_u64 v[82:83], s[24:25], 0, v[136:137]
	v_lshlrev_b64 v[100:101], 2, v[80:81]
	v_lshl_add_u64 v[80:81], v[82:83], 0, v[100:101]
	v_add_co_u32_e64 v82, s[4:5], s61, v80
	ds_bpermute_b32 v103, v177, v76
	s_nop 0
	v_addc_co_u32_e64 v83, s[4:5], 0, v81, s[4:5]
	global_load_dwordx4 v[84:87], v[82:83], off
	global_load_dwordx4 v[88:91], v[80:81], off
	ds_bpermute_b32 v108, v177, v77
	ds_bpermute_b32 v110, v177, v78
	ds_bpermute_b32 v116, v177, v79
	v_mov_b32_e32 v102, v76
	v_mov_b32_e32 v76, v78
	s_waitcnt lgkmcnt(3)
	v_cndmask_b32_e64 v109, v103, -v103, vcc
	s_waitcnt lgkmcnt(2)
	v_cndmask_b32_e64 v111, v108, -v108, vcc
	s_waitcnt lgkmcnt(1)
	v_cndmask_b32_e64 v117, v110, -v110, vcc
	s_waitcnt lgkmcnt(0)
	v_cndmask_b32_e64 v119, v116, -v116, vcc
	s_waitcnt vmcnt(1)
	v_mov_b32_e32 v103, v84
	s_waitcnt vmcnt(0)
	v_mov_b32_e32 v108, v88
	v_mov_b32_e32 v84, v77
	v_mov_b32_e32 v110, v89
	v_mov_b32_e32 v77, v86
	v_mov_b32_e32 v116, v90
	v_mov_b32_e32 v86, v79
	v_mov_b32_e32 v118, v91
	v_pk_mul_f32 v[78:79], v[102:103], v[108:109]
	v_pk_mul_f32 v[84:85], v[84:85], v[110:111]
	v_pk_mul_f32 v[76:77], v[76:77], v[116:117]
	v_pk_mul_f32 v[86:87], v[86:87], v[118:119]
	v_add_f32_e32 v118, v78, v79
	v_add_f32_e32 v119, v84, v85
	v_add_f32_e32 v126, v76, v77
	v_add_f32_e32 v127, v86, v87
	v_lshl_add_u64 v[76:77], s[16:17], 0, v[100:101]
	v_lshl_add_u64 v[78:79], v[76:77], 0, v[136:137]
	v_add_co_u32_e64 v76, s[4:5], s62, v78
	ds_bpermute_b32 v101, v177, v72
	s_nop 0
	v_addc_co_u32_e64 v77, s[4:5], 0, v79, s[4:5]
	v_add_co_u32_e64 v78, s[4:5], s49, v78
	ds_bpermute_b32 v102, v177, v73
	s_nop 0
	v_addc_co_u32_e64 v79, s[4:5], 0, v79, s[4:5]
	global_load_dwordx4 v[84:87], v[76:77], off offset:16
	global_load_dwordx4 v[88:91], v[78:79], off offset:16
	ds_bpermute_b32 v108, v177, v74
	ds_bpermute_b32 v110, v177, v75
	v_mov_b32_e32 v100, v72
	v_mov_b32_e32 v72, v74
	s_waitcnt lgkmcnt(3)
	v_cndmask_b32_e64 v103, v101, -v101, vcc
	s_waitcnt lgkmcnt(2)
	v_cndmask_b32_e64 v109, v102, -v102, vcc
	s_waitcnt lgkmcnt(1)
	v_cndmask_b32_e64 v111, v108, -v108, vcc
	s_waitcnt lgkmcnt(0)
	v_cndmask_b32_e64 v117, v110, -v110, vcc
	s_waitcnt vmcnt(1)
	v_mov_b32_e32 v101, v84
	s_waitcnt vmcnt(0)
;     __device__ __forceinline__ void operator()(const AccT& acc, const Unit& u, int wr, int wc, int fr, int fq) const {
;     ...
;         for (int ai = 0; ai < 2; ++ai) {
;             const int hh = 2 * ai + wr;
;             const float l2f = lgd[hh] * 1.4426950408889634f, l2b = lgd[4 + hh] * 1.4426950408889634f;
;             const float zf0 = exp2f((float)(127 - o0) * l2f), zfs = exp2f(-l2f), zb0 = exp2f((float)o0 * l2b), zbs = exp2f(l2b);
; #pragma unroll
;             for (int m = 0; m < 4; ++m) {
;                 const int r = rbase + ai * 128 + m * 16;
;                 const int d = 4 * (2 * m + (fr >> 3)) + j;
; #pragma unroll
;                 for (int bj = 0; bj < 2; ++bj) {
;                     const int t0 = tb + bj * 128;
;                     float v[8];
; #pragma unroll
;                     for (int jj = 0; jj < 4; ++jj) { v[jj] = acc[ai][bj][m][0][jj]; v[4 + jj] = acc[ai][bj][m][1][jj]; }
;                     if constexpr (ROPE) {
;                         const int t = t0 & 2047;
; #pragma unroll
;                         for (int hf = 0; hf < 2; ++hf) {
;                             f32x4 cs, sn;
;                             if (m < 2) { const float c1 = ropeA[(t >> 6) * 16 + d], s1 = ropeA[1024 + (t >> 6) * 16 + d]; cs = (f32x4){c1, c1, c1, c1}; sn = (f32x4){s1, s1, s1, s1}; }
;                             else { const float* cb = ropeA + 2048 + (d - 16) * 64 + (t & 63) + 4 * hf; cs = *(const f32x4*)(cb); sn = *(const f32x4*)(cb + 1024); }
; #pragma unroll
;                             for (int jj = 0; jj < 4; ++jj) { const float pr = __shfl_xor(v[4 * hf + jj], 4); v[4 * hf + jj] = v[4 * hf + jj] * cs[jj] + sgn * pr * sn[jj]; }
;                             __builtin_amdgcn_sched_barrier(0);
;                         }
;                     }
;                     float zf[8], zb[8]; zf[0] = zf0; zb[0] = zb0;
; #pragma unroll
;                     for (int jj = 1; jj < 8; ++jj) { zf[jj] = zf[jj - 1] * zfs; zb[jj] = zb[jj - 1] * zbs; }
;                     u32x4 wf, wb;
;                     wf.x = cvt_pk_bf16(v[0] * zf[0], v[1] * zf[1]); wf.y = cvt_pk_bf16(v[2] * zf[2], v[3] * zf[3]); wf.z = cvt_pk_bf16(v[4] * zf[4], v[5] * zf[5]); wf.w = cvt_pk_bf16(v[6] * zf[6], v[7] * zf[7]);
	v_mov_b32_e32 v102, v88
	v_mov_b32_e32 v84, v73
	v_mov_b32_e32 v108, v89
	v_mov_b32_e32 v73, v86
	v_mov_b32_e32 v110, v90
	v_mov_b32_e32 v86, v75
	v_mov_b32_e32 v116, v91
	v_pk_mul_f32 v[74:75], v[100:101], v[102:103]
	v_pk_mul_f32 v[84:85], v[84:85], v[108:109]
	v_pk_mul_f32 v[72:73], v[72:73], v[110:111]
	v_pk_mul_f32 v[86:87], v[86:87], v[116:117]
	v_add_f32_e32 v74, v74, v75
	v_add_f32_e32 v75, v84, v85
	v_add_f32_e32 v72, v72, v73
	v_add_f32_e32 v73, v86, v87
	v_mul_f32_e32 v84, v180, v118
	v_mul_f32_e32 v85, v181, v119
	v_cvt_pk_bf16_f32 v84, v84, v85
	v_mul_f32_e32 v85, v167, v126
	v_mul_f32_e32 v86, v183, v127
	v_cvt_pk_bf16_f32 v85, v85, v86
	v_mul_f32_e32 v86, v182, v74
	v_mul_f32_e32 v87, v185, v75
	v_cvt_pk_bf16_f32 v86, v86, v87
	v_mul_f32_e32 v87, v184, v72
	v_mul_f32_e32 v88, v159, v73
	v_cvt_pk_bf16_f32 v87, v87, v88
	v_mul_f32_e32 v88, v150, v118
	v_mul_f32_e32 v89, v152, v119
	v_cvt_pk_bf16_f32 v88, v88, v89
	v_mul_f32_e32 v89, v154, v126
	v_mul_f32_e32 v90, v156, v127
	v_mul_f32_e32 v72, v151, v72
	v_mul_f32_e32 v73, v155, v73
	s_mov_b64 s[0:1], 0x600000
	v_cvt_pk_bf16_f32 v89, v89, v90
	v_mul_f32_e32 v74, v158, v74
	v_mul_f32_e32 v75, v160, v75
	v_cvt_pk_bf16_f32 v90, v74, v75
	v_cvt_pk_bf16_f32 v91, v72, v73
	v_lshl_add_u64 v[72:73], v[120:121], 0, s[0:1]
	s_mov_b32 s0, 0x600000
	v_add_co_u32_e64 v74, s[4:5], s0, v120
	s_mov_b64 s[0:1], 0x2600000
	s_nop 0
	v_addc_co_u32_e64 v75, s[4:5], 0, v121, s[4:5]
	global_store_dwordx4 v[74:75], v[84:87], off
	v_lshl_add_u64 v[74:75], v[120:121], 0, s[0:1]
	s_mov_b32 s0, 0x2600000
	v_add_co_u32_e64 v84, s[4:5], s0, v120
	s_nop 1
	v_addc_co_u32_e64 v85, s[4:5], 0, v121, s[4:5]
	global_store_dwordx4 v[84:85], v[88:91], off
	global_load_dwordx4 v[84:87], v[82:83], off
	s_nop 0
	global_load_dwordx4 v[88:91], v[80:81], off
	ds_bpermute_b32 v101, v177, v68
	ds_bpermute_b32 v102, v177, v69
	ds_bpermute_b32 v108, v177, v70
	ds_bpermute_b32 v110, v177, v71
	v_mov_b32_e32 v100, v68
	v_mov_b32_e32 v68, v70
	s_waitcnt lgkmcnt(3)
	v_cndmask_b32_e64 v103, v101, -v101, vcc
	s_waitcnt lgkmcnt(2)
	v_cndmask_b32_e64 v109, v102, -v102, vcc
	s_waitcnt lgkmcnt(1)
	v_cndmask_b32_e64 v111, v108, -v108, vcc
	s_waitcnt lgkmcnt(0)
	v_cndmask_b32_e64 v117, v110, -v110, vcc
	s_waitcnt vmcnt(1)
	v_mov_b32_e32 v101, v84
	s_waitcnt vmcnt(0)
	v_mov_b32_e32 v102, v88
	v_mov_b32_e32 v84, v69
	v_mov_b32_e32 v108, v89
	v_mov_b32_e32 v69, v86
	v_mov_b32_e32 v110, v90
	v_mov_b32_e32 v86, v71
	v_mov_b32_e32 v116, v91
	v_pk_mul_f32 v[70:71], v[100:101], v[102:103]
	v_pk_mul_f32 v[84:85], v[84:85], v[108:109]
	v_pk_mul_f32 v[68:69], v[68:69], v[110:111]
	v_pk_mul_f32 v[86:87], v[86:87], v[116:117]
	v_add_f32_e32 v110, v70, v71
	v_add_f32_e32 v111, v84, v85
	v_add_f32_e32 v116, v68, v69
	v_add_f32_e32 v117, v86, v87
	global_load_dwordx4 v[68:71], v[76:77], off offset:16
	global_load_dwordx4 v[84:87], v[78:79], off offset:16
	ds_bpermute_b32 v89, v177, v64
	ds_bpermute_b32 v90, v177, v65
	ds_bpermute_b32 v100, v177, v66
	ds_bpermute_b32 v102, v177, v67
	v_mov_b32_e32 v88, v64
	v_mov_b32_e32 v64, v66
	s_waitcnt lgkmcnt(3)
	v_cndmask_b32_e64 v91, v89, -v89, vcc
	s_waitcnt lgkmcnt(2)
	v_cndmask_b32_e64 v101, v90, -v90, vcc
	s_waitcnt lgkmcnt(1)
	v_cndmask_b32_e64 v103, v100, -v100, vcc
	s_waitcnt lgkmcnt(0)
	v_cndmask_b32_e64 v109, v102, -v102, vcc
	s_waitcnt vmcnt(1)
	v_mov_b32_e32 v89, v68
	s_waitcnt vmcnt(0)
	v_mov_b32_e32 v90, v84
	v_mov_b32_e32 v68, v65
	v_mov_b32_e32 v100, v85
	v_mov_b32_e32 v65, v70
	v_mov_b32_e32 v102, v86
	v_mov_b32_e32 v70, v67
	v_mov_b32_e32 v108, v87
	v_pk_mul_f32 v[66:67], v[88:89], v[90:91]
	v_pk_mul_f32 v[68:69], v[68:69], v[100:101]
	v_pk_mul_f32 v[64:65], v[64:65], v[102:103]
	v_pk_mul_f32 v[70:71], v[70:71], v[108:109]
	v_add_f32_e32 v84, v66, v67
	v_add_f32_e32 v85, v68, v69
	v_add_f32_e32 v86, v64, v65
	v_add_f32_e32 v71, v70, v71
	v_mul_f32_e32 v64, v180, v110
	v_mul_f32_e32 v65, v181, v111
	v_cvt_pk_bf16_f32 v64, v64, v65
	v_mul_f32_e32 v65, v167, v116
	v_mul_f32_e32 v66, v183, v117
	v_cvt_pk_bf16_f32 v65, v65, v66
	v_mul_f32_e32 v66, v182, v84
	v_mul_f32_e32 v67, v185, v85
	v_cvt_pk_bf16_f32 v66, v66, v67
	v_mul_f32_e32 v67, v184, v86
	v_mul_f32_e32 v68, v159, v71
	v_cvt_pk_bf16_f32 v67, v67, v68
	v_mul_f32_e32 v68, v150, v110
	v_mul_f32_e32 v69, v152, v111
	v_cvt_pk_bf16_f32 v68, v68, v69
	v_mul_f32_e32 v69, v154, v116
	v_mul_f32_e32 v70, v156, v117
	v_cvt_pk_bf16_f32 v69, v69, v70
	v_mul_f32_e32 v70, v158, v84
	v_mul_f32_e32 v84, v160, v85
	v_mul_f32_e32 v71, v155, v71
	v_cvt_pk_bf16_f32 v70, v70, v84
	v_mul_f32_e32 v84, v151, v86
	v_cvt_pk_bf16_f32 v71, v84, v71
	global_store_dwordx4 v[72:73], v[64:67], off offset:256
	global_store_dwordx4 v[74:75], v[68:71], off offset:256
	global_load_dword v64, v137, s[22:23] offset:8
	s_nop 0
	global_load_dword v70, v137, s[22:23] offset:24
	global_load_dword v67, v[146:147], off
	global_load_dword v74, v[148:149], off
	ds_bpermute_b32 v65, v177, v60
	ds_bpermute_b32 v68, v177, v62
	v_mov_b32_e32 v66, v60
	ds_bpermute_b32 v60, v177, v61
	ds_bpermute_b32 v71, v177, v63
	s_waitcnt lgkmcnt(3)
	v_cndmask_b32_e64 v75, v65, -v65, vcc
	s_waitcnt lgkmcnt(2)
	v_cndmask_b32_e64 v65, v68, -v68, vcc
	s_waitcnt vmcnt(3)
	v_mul_f32_e32 v72, 0x3fb8aa3b, v64
	s_waitcnt vmcnt(2)
	v_mul_f32_e32 v73, 0x3fb8aa3b, v70
	v_mul_f32_e32 v84, v72, v179
	s_waitcnt vmcnt(0)
	v_pk_mul_f32 v[68:69], v[66:67], v[74:75]
	s_waitcnt lgkmcnt(1)
	v_cndmask_b32_e64 v75, v60, -v60, vcc
	v_mov_b32_e32 v66, v61
	v_cmp_lt_f32_e64 s[4:5], s60, v72
	v_mul_f32_e32 v87, v73, v178
	v_pk_mul_f32 v[60:61], v[66:67], v[74:75]
	s_waitcnt lgkmcnt(0)
;     __device__ __forceinline__ void operator()(const AccT& acc, const Unit& u, int wr, int wc, int fr, int fq) const {
;     ...
;         for (int ai = 0; ai < 2; ++ai) {
;             const int hh = 2 * ai + wr;
;             const float l2f = lgd[hh] * 1.4426950408889634f, l2b = lgd[4 + hh] * 1.4426950408889634f;
;             const float zf0 = exp2f((float)(127 - o0) * l2f), zfs = exp2f(-l2f), zb0 = exp2f((float)o0 * l2b), zbs = exp2f(l2b);
; #pragma unroll
;             for (int m = 0; m < 4; ++m) {
;                 const int r = rbase + ai * 128 + m * 16;
;                 const int d = 4 * (2 * m + (fr >> 3)) + j;
; #pragma unroll
;                 for (int bj = 0; bj < 2; ++bj) {
;                     const int t0 = tb + bj * 128;
;                     float v[8];
; #pragma unroll
;                     for (int jj = 0; jj < 4; ++jj) { v[jj] = acc[ai][bj][m][0][jj]; v[4 + jj] = acc[ai][bj][m][1][jj]; }
;                     if constexpr (ROPE) {
;                         const int t = t0 & 2047;
; #pragma unroll
;                         for (int hf = 0; hf < 2; ++hf) {
;                             f32x4 cs, sn;
;                             if (m < 2) { const float c1 = ropeA[(t >> 6) * 16 + d], s1 = ropeA[1024 + (t >> 6) * 16 + d]; cs = (f32x4){c1, c1, c1, c1}; sn = (f32x4){s1, s1, s1, s1}; }
;                             else { const float* cb = ropeA + 2048 + (d - 16) * 64 + (t & 63) + 4 * hf; cs = *(const f32x4*)(cb); sn = *(const f32x4*)(cb + 1024); }
; #pragma unroll
;                             for (int jj = 0; jj < 4; ++jj) { const float pr = __shfl_xor(v[4 * hf + jj], 4); v[4 * hf + jj] = v[4 * hf + jj] * cs[jj] + sgn * pr * sn[jj]; }
;                             __builtin_amdgcn_sched_barrier(0);
;                         }
;                     }
;                     float zf[8], zb[8]; zf[0] = zf0; zb[0] = zb0;
; #pragma unroll
;                     for (int jj = 1; jj < 8; ++jj) { zf[jj] = zf[jj - 1] * zfs; zb[jj] = zb[jj - 1] * zbs; }
;                     u32x4 wf, wb;
;                     wf.x = cvt_pk_bf16(v[0] * zf[0], v[1] * zf[1]); wf.y = cvt_pk_bf16(v[2] * zf[2], v[3] * zf[3]); wf.z = cvt_pk_bf16(v[4] * zf[4], v[5] * zf[5]); wf.w = cvt_pk_bf16(v[6] * zf[6], v[7] * zf[7]);
	v_cndmask_b32_e64 v75, v71, -v71, vcc
	v_mov_b32_e32 v66, v63
	v_cmp_gt_f32_e64 s[8:9], s59, v84
	v_cndmask_b32_e64 v86, 0, v176, s[4:5]
	v_cmp_gt_f32_e64 s[6:7], s59, v73
	s_and_b64 s[0:1], s[4:5], exec
	v_cmp_gt_f32_e64 s[4:5], s59, v87
	v_add_f32_e32 v110, v60, v61
	v_pk_mul_f32 v[60:61], v[66:67], v[74:75]
	v_cndmask_b32_e64 v66, 0, v176, s[8:9]
	v_cndmask_b32_e64 v88, 0, v176, s[6:7]
	v_add_f32_e32 v89, v68, v69
	v_fmac_f32_e32 v86, 0xbfb8aa3b, v64
	v_cndmask_b32_e64 v69, 0, v176, s[4:5]
	v_fmac_f32_e32 v66, v72, v179
	v_fmac_f32_e32 v88, 0x3fb8aa3b, v70
	v_exp_f32_e32 v68, v86
	v_fmac_f32_e32 v69, v73, v178
	v_exp_f32_e32 v66, v66
	v_exp_f32_e32 v70, v88
	v_exp_f32_e32 v69, v69
	v_cndmask_b32_e64 v63, 0, v175, s[8:9]
	s_cselect_b32 s8, 0xffffffc0, 0
	s_and_b64 s[0:1], s[6:7], exec
	v_cndmask_b32_e64 v64, 0, v175, s[4:5]
	s_cselect_b32 s0, 0xffffffc0, 0
	v_ldexp_f32 v100, v68, s8
	v_ldexp_f32 v63, v66, v63
	v_mul_f32_e32 v85, v62, v74
	v_ldexp_f32 v90, v70, s0
	v_ldexp_f32 v64, v69, v64
	v_mul_f32_e32 v75, v100, v63
	v_add_f32_e32 v111, v60, v61
	global_load_dword v108, v[148:149], off
	global_load_dword v69, v[146:147], off
	ds_bpermute_b32 v61, v177, v57
	ds_bpermute_b32 v60, v177, v56
	v_mov_b32_e32 v68, v57
	ds_bpermute_b32 v57, v177, v59
	ds_bpermute_b32 v66, v177, v58
	s_waitcnt lgkmcnt(3)
	v_cndmask_b32_e64 v109, v61, -v61, vcc
	s_waitcnt lgkmcnt(2)
	v_cndmask_b32_e64 v70, v60, -v60, vcc
	s_waitcnt lgkmcnt(0)
	v_cndmask_b32_e64 v72, v66, -v66, vcc
	s_waitcnt vmcnt(1)
	v_mul_f32_e32 v71, v56, v108
	s_waitcnt vmcnt(0)
	v_pk_mul_f32 v[60:61], v[68:69], v[108:109]
	v_cndmask_b32_e64 v109, v57, -v57, vcc
	v_mov_b32_e32 v68, v59
	v_add_f32_e32 v57, v60, v61
	v_pk_mul_f32 v[60:61], v[68:69], v[108:109]
	s_nop 0
	v_add_f32_e32 v59, v60, v61
	v_mov_b32_e32 v91, v67
	v_pk_mul_f32 v[60:61], v[90:91], v[64:65]
	v_mov_b32_e32 v91, v85
	v_pk_mul_f32 v[66:67], v[90:91], v[60:61]
	v_mov_b32_e32 v91, v69
	v_mov_b32_e32 v67, v70
	v_mul_f32_e32 v84, v100, v75
	v_pk_mul_f32 v[68:69], v[90:91], v[66:67]
	v_mov_b32_e32 v70, v90
	v_mul_f32_e32 v86, v100, v84
	v_pk_mul_f32 v[70:71], v[70:71], v[68:69]
	v_mul_f32_e32 v85, v100, v86
	v_mov_b32_e32 v71, v72
	v_mul_f32_e32 v88, v100, v85
	v_pk_mul_f32 v[72:73], v[90:91], v[70:71]
	v_fma_f32 v61, v62, v74, v61
	v_mul_f32_e32 v87, v100, v88
	v_mul_f32_e32 v65, v90, v72
	v_mul_f32_e32 v62, v84, v61
	v_fma_f32 v56, v56, v108, v69
	v_mul_f32_e32 v71, v100, v87
	v_mul_f32_e32 v67, v90, v65
	v_mul_f32_e32 v90, v63, v89
	v_mul_f32_e32 v91, v75, v110
	v_cvt_pk_bf16_f32 v100, v90, v91
	v_mul_f32_e32 v74, v86, v111
	v_cvt_pk_bf16_f32 v101, v62, v74
	v_mul_f32_e32 v62, v85, v56
	v_fma_f32 v58, v58, v108, v73
	v_mul_f32_e32 v69, v88, v57
	v_cvt_pk_bf16_f32 v102, v62, v69
	v_mul_f32_e32 v62, v87, v58
	v_mul_f32_e32 v69, v71, v59
	v_cvt_pk_bf16_f32 v103, v62, v69
	v_mul_f32_e32 v62, v64, v89
	v_mul_f32_e32 v56, v70, v56
	v_mul_f32_e32 v57, v72, v57
	v_mul_f32_e32 v69, v60, v110
	v_cvt_pk_bf16_f32 v108, v62, v69
	v_mul_f32_e32 v61, v66, v61
	v_mul_f32_e32 v62, v68, v111
	v_cvt_pk_bf16_f32 v109, v61, v62
	v_cvt_pk_bf16_f32 v110, v56, v57
	v_mul_f32_e32 v56, v65, v58
	v_mul_f32_e32 v57, v67, v59
	s_mov_b64 s[0:1], 0x1000000
	v_cvt_pk_bf16_f32 v111, v56, v57
	v_lshl_add_u64 v[56:57], v[120:121], 0, s[0:1]
	s_mov_b32 s0, 0x1000000
	v_add_co_u32_e64 v58, s[4:5], s0, v120
	s_mov_b64 s[0:1], 0x3000000
	s_nop 0
	v_addc_co_u32_e64 v59, s[4:5], 0, v121, s[4:5]
	global_store_dwordx4 v[58:59], v[100:103], off
	v_lshl_add_u64 v[58:59], v[120:121], 0, s[0:1]
	s_mov_b32 s0, 0x3000000
	v_add_co_u32_e64 v90, s[4:5], s0, v120
	s_nop 1
	v_addc_co_u32_e64 v91, s[4:5], 0, v121, s[4:5]
	global_store_dwordx4 v[90:91], v[108:111], off
	global_load_dword v91, v[122:123], off
	s_nop 0
	global_load_dword v100, v[124:125], off
	ds_bpermute_b32 v61, v177, v52
	v_mov_b32_e32 v90, v52
	ds_bpermute_b32 v52, v177, v53
	ds_bpermute_b32 v62, v177, v54
	ds_bpermute_b32 v69, v177, v55
	s_waitcnt lgkmcnt(3)
	v_cndmask_b32_e64 v101, v61, -v61, vcc
	s_waitcnt vmcnt(0)
	v_pk_mul_f32 v[102:103], v[90:91], v[100:101]
	s_waitcnt lgkmcnt(2)
	v_cndmask_b32_e64 v101, v52, -v52, vcc
	v_mov_b32_e32 v90, v53
	v_pk_mul_f32 v[52:53], v[90:91], v[100:101]
	s_waitcnt lgkmcnt(1)
	v_cndmask_b32_e64 v101, v62, -v62, vcc
	v_mov_b32_e32 v90, v54
	v_add_f32_e32 v62, v52, v53
	v_pk_mul_f32 v[52:53], v[90:91], v[100:101]
	s_waitcnt lgkmcnt(0)
	v_cndmask_b32_e64 v101, v69, -v69, vcc
	v_mov_b32_e32 v90, v55
	v_add_f32_e32 v69, v52, v53
	v_pk_mul_f32 v[52:53], v[90:91], v[100:101]
	v_add_f32_e32 v61, v102, v103
	v_add_f32_e32 v73, v52, v53
	global_load_dword v53, v[122:123], off
	global_load_dword v54, v[124:125], off
	ds_bpermute_b32 v55, v177, v48
	v_mov_b32_e32 v52, v48
	ds_bpermute_b32 v48, v177, v49
	ds_bpermute_b32 v74, v177, v50
	ds_bpermute_b32 v89, v177, v51
	s_waitcnt lgkmcnt(3)
	v_cndmask_b32_e64 v55, v55, -v55, vcc
	s_waitcnt vmcnt(0)
	v_pk_mul_f32 v[90:91], v[52:53], v[54:55]
	s_waitcnt lgkmcnt(2)
	v_cndmask_b32_e64 v55, v48, -v48, vcc
	v_mov_b32_e32 v52, v49
	v_pk_mul_f32 v[48:49], v[52:53], v[54:55]
	s_waitcnt lgkmcnt(1)
	v_cndmask_b32_e64 v55, v74, -v74, vcc
	v_mov_b32_e32 v52, v50
	v_add_f32_e32 v74, v48, v49
	v_pk_mul_f32 v[48:49], v[52:53], v[54:55]
	s_waitcnt lgkmcnt(0)
; __device__ __forceinline__ unsigned cvt_pk_bf16(float lo, float hi) { unsigned r; asm volatile("v_cvt_pk_bf16_f32 %0, %1, %2" : "=v"(r) : "v"(lo), "v"(hi)); return r; }
;     __device__ __forceinline__ void operator()(const AccT& acc, const Unit& u, int wr, int wc, int fr, int fq) const {
;     ...
;                     for (int jj = 0; jj < 4; ++jj) { v[jj] = acc[ai][bj][m][0][jj]; v[4 + jj] = acc[ai][bj][m][1][jj]; }
;                     if constexpr (ROPE) {
;                         const int t = t0 & 2047;
; #pragma unroll
;                         for (int hf = 0; hf < 2; ++hf) {
;                             f32x4 cs, sn;
;                             if (m < 2) { const float c1 = ropeA[(t >> 6) * 16 + d], s1 = ropeA[1024 + (t >> 6) * 16 + d]; cs = (f32x4){c1, c1, c1, c1}; sn = (f32x4){s1, s1, s1, s1}; }
;                             else { const float* cb = ropeA + 2048 + (d - 16) * 64 + (t & 63) + 4 * hf; cs = *(const f32x4*)(cb); sn = *(const f32x4*)(cb + 1024); }
; #pragma unroll
;                             for (int jj = 0; jj < 4; ++jj) { const float pr = __shfl_xor(v[4 * hf + jj], 4); v[4 * hf + jj] = v[4 * hf + jj] * cs[jj] + sgn * pr * sn[jj]; }
;                             __builtin_amdgcn_sched_barrier(0);
;                         }
;                     }
;                     float zf[8], zb[8]; zf[0] = zf0; zb[0] = zb0;
; #pragma unroll
;                     for (int jj = 1; jj < 8; ++jj) { zf[jj] = zf[jj - 1] * zfs; zb[jj] = zb[jj - 1] * zbs; }
;                     u32x4 wf, wb;
;                     wf.x = cvt_pk_bf16(v[0] * zf[0], v[1] * zf[1]); wf.y = cvt_pk_bf16(v[2] * zf[2], v[3] * zf[3]); wf.z = cvt_pk_bf16(v[4] * zf[4], v[5] * zf[5]); wf.w = cvt_pk_bf16(v[6] * zf[6], v[7] * zf[7]);
;                     wb.x = cvt_pk_bf16(v[0] * zb[0], v[1] * zb[1]); wb.y = cvt_pk_bf16(v[2] * zb[2], v[3] * zb[3]); wb.z = cvt_pk_bf16(v[4] * zb[4], v[5] * zb[5]); wb.w = cvt_pk_bf16(v[6] * zb[6], v[7] * zb[7]);
;                     *(u32x4*)(KTZ + (size_t)r * NT + t0) = wf;
;                     *(u32x4*)(KTZ + (size_t)(256 + r) * NT + t0) = wb;
	v_cndmask_b32_e64 v55, v89, -v89, vcc
	v_mov_b32_e32 v52, v51
	v_add_f32_e32 v89, v48, v49
	v_pk_mul_f32 v[48:49], v[52:53], v[54:55]
	v_add_f32_e32 v90, v90, v91
	v_add_f32_e32 v55, v48, v49
	v_mul_f32_e32 v48, v63, v61
	v_mul_f32_e32 v49, v75, v62
	v_cvt_pk_bf16_f32 v48, v48, v49
	v_mul_f32_e32 v49, v84, v69
	v_mul_f32_e32 v50, v86, v73
	v_cvt_pk_bf16_f32 v49, v49, v50
	v_mul_f32_e32 v50, v85, v90
	v_mul_f32_e32 v51, v88, v74
	v_cvt_pk_bf16_f32 v50, v50, v51
	v_mul_f32_e32 v51, v87, v89
	v_mul_f32_e32 v52, v71, v55
	v_cvt_pk_bf16_f32 v51, v51, v52
	v_mul_f32_e32 v52, v64, v61
	v_mul_f32_e32 v53, v60, v62
	v_cvt_pk_bf16_f32 v52, v52, v53
	v_mul_f32_e32 v53, v66, v69
	v_mul_f32_e32 v54, v68, v73
	v_cvt_pk_bf16_f32 v53, v53, v54
	v_mul_f32_e32 v54, v70, v90
	v_mul_f32_e32 v61, v72, v74
	v_mul_f32_e32 v55, v67, v55
	v_cvt_pk_bf16_f32 v54, v54, v61
	v_mul_f32_e32 v61, v65, v89
	v_cvt_pk_bf16_f32 v55, v61, v55
	global_store_dwordx4 v[56:57], v[48:51], off offset:256
	global_store_dwordx4 v[58:59], v[52:55], off offset:256
	global_load_dword v49, v[112:113], off
	s_nop 0
	global_load_dword v50, v[114:115], off
	ds_bpermute_b32 v51, v177, v44
	v_mov_b32_e32 v48, v44
	ds_bpermute_b32 v44, v177, v45
	ds_bpermute_b32 v54, v177, v46
	ds_bpermute_b32 v55, v177, v47
	s_waitcnt lgkmcnt(3)
	v_cndmask_b32_e64 v51, v51, -v51, vcc
	s_waitcnt vmcnt(0)
	v_pk_mul_f32 v[52:53], v[48:49], v[50:51]
	s_waitcnt lgkmcnt(2)
	v_cndmask_b32_e64 v51, v44, -v44, vcc
	v_mov_b32_e32 v48, v45
	v_pk_mul_f32 v[44:45], v[48:49], v[50:51]
	s_waitcnt lgkmcnt(1)
	v_cndmask_b32_e64 v51, v54, -v54, vcc
	v_mov_b32_e32 v48, v46
	v_add_f32_e32 v52, v52, v53
	v_add_f32_e32 v53, v44, v45
	v_pk_mul_f32 v[44:45], v[48:49], v[50:51]
	s_waitcnt lgkmcnt(0)
	v_cndmask_b32_e64 v51, v55, -v55, vcc
	v_mov_b32_e32 v48, v47
	v_add_f32_e32 v54, v44, v45
	v_pk_mul_f32 v[44:45], v[48:49], v[50:51]
	s_nop 0
	v_add_f32_e32 v50, v44, v45
	global_load_dword v45, v[112:113], off
	global_load_dword v46, v[114:115], off
	ds_bpermute_b32 v47, v177, v40
	v_mov_b32_e32 v44, v40
	ds_bpermute_b32 v40, v177, v41
	ds_bpermute_b32 v51, v177, v42
	ds_bpermute_b32 v55, v177, v43
	s_waitcnt lgkmcnt(3)
	v_cndmask_b32_e64 v47, v47, -v47, vcc
	s_waitcnt vmcnt(0)
	v_pk_mul_f32 v[48:49], v[44:45], v[46:47]
	s_waitcnt lgkmcnt(2)
	v_cndmask_b32_e64 v47, v40, -v40, vcc
	v_mov_b32_e32 v44, v41
	v_pk_mul_f32 v[40:41], v[44:45], v[46:47]
	s_waitcnt lgkmcnt(1)
	v_cndmask_b32_e64 v47, v51, -v51, vcc
	v_mov_b32_e32 v44, v42
	v_add_f32_e32 v48, v48, v49
	v_add_f32_e32 v49, v40, v41
	v_pk_mul_f32 v[40:41], v[44:45], v[46:47]
	s_waitcnt lgkmcnt(0)
	v_cndmask_b32_e64 v47, v55, -v55, vcc
	v_mov_b32_e32 v44, v43
	v_add_f32_e32 v51, v40, v41
	v_pk_mul_f32 v[40:41], v[44:45], v[46:47]
	s_nop 0
	v_add_f32_e32 v40, v40, v41
	v_mul_f32_e32 v41, v63, v52
	v_mul_f32_e32 v42, v75, v53
	v_cvt_pk_bf16_f32 v42, v41, v42
	v_mul_f32_e32 v41, v84, v54
	v_mul_f32_e32 v43, v86, v50
	v_cvt_pk_bf16_f32 v43, v41, v43
	v_mul_f32_e32 v41, v85, v48
	v_mul_f32_e32 v44, v88, v49
	v_cvt_pk_bf16_f32 v44, v41, v44
	v_mul_f32_e32 v41, v87, v51
	v_mul_f32_e32 v45, v71, v40
	v_cvt_pk_bf16_f32 v45, v41, v45
	v_mul_f32_e32 v41, v64, v52
	v_mul_f32_e32 v46, v60, v53
	v_cvt_pk_bf16_f32 v46, v41, v46
	v_mul_f32_e32 v41, v66, v54
	v_mul_f32_e32 v47, v68, v50
	v_cvt_pk_bf16_f32 v47, v41, v47
	v_mul_f32_e32 v41, v70, v48
	v_mul_f32_e32 v48, v72, v49
	v_cvt_pk_bf16_f32 v48, v41, v48
	v_mul_f32_e32 v41, v65, v51
	v_mul_f32_e32 v40, v67, v40
	s_mov_b64 s[0:1], 0x1200000
	v_cvt_pk_bf16_f32 v49, v41, v40
	v_lshl_add_u64 v[40:41], v[120:121], 0, s[0:1]
	s_mov_b32 s0, 0x1200000
	v_add_co_u32_e64 v50, s[4:5], s0, v120
	s_mov_b64 s[0:1], 0x3200000
	s_nop 0
	v_addc_co_u32_e64 v51, s[4:5], 0, v121, s[4:5]
	global_store_dwordx4 v[50:51], v[42:45], off
	s_nop 1
	v_lshl_add_u64 v[42:43], v[120:121], 0, s[0:1]
	s_mov_b32 s0, 0x3200000
	v_add_co_u32_e64 v44, s[4:5], s0, v120
	s_nop 1
	v_addc_co_u32_e64 v45, s[4:5], 0, v121, s[4:5]
	global_store_dwordx4 v[44:45], v[46:49], off
	global_load_dword v45, v[104:105], off
	s_nop 0
	global_load_dword v46, v[106:107], off
	ds_bpermute_b32 v47, v177, v36
	v_mov_b32_e32 v44, v36
	ds_bpermute_b32 v36, v177, v37
	ds_bpermute_b32 v50, v177, v38
	ds_bpermute_b32 v51, v177, v39
	s_waitcnt lgkmcnt(3)
	v_cndmask_b32_e64 v47, v47, -v47, vcc
	s_waitcnt vmcnt(0)
	v_pk_mul_f32 v[48:49], v[44:45], v[46:47]
	s_waitcnt lgkmcnt(2)
	v_cndmask_b32_e64 v47, v36, -v36, vcc
	v_mov_b32_e32 v44, v37
	v_pk_mul_f32 v[36:37], v[44:45], v[46:47]
	s_waitcnt lgkmcnt(1)
	v_cndmask_b32_e64 v47, v50, -v50, vcc
	v_mov_b32_e32 v44, v38
	v_add_f32_e32 v48, v48, v49
	v_add_f32_e32 v49, v36, v37
	v_pk_mul_f32 v[36:37], v[44:45], v[46:47]
	s_waitcnt lgkmcnt(0)
	v_cndmask_b32_e64 v47, v51, -v51, vcc
	v_mov_b32_e32 v44, v39
	v_add_f32_e32 v50, v36, v37
	v_pk_mul_f32 v[36:37], v[44:45], v[46:47]
	s_nop 0
	v_add_f32_e32 v46, v36, v37
	global_load_dword v37, v[104:105], off
	global_load_dword v38, v[106:107], off
	ds_bpermute_b32 v39, v177, v32
	v_mov_b32_e32 v36, v32
	ds_bpermute_b32 v32, v177, v33
	ds_bpermute_b32 v47, v177, v34
	ds_bpermute_b32 v51, v177, v35
	s_waitcnt lgkmcnt(3)
	v_cndmask_b32_e64 v39, v39, -v39, vcc
	s_waitcnt vmcnt(0)
	v_pk_mul_f32 v[44:45], v[36:37], v[38:39]
	s_waitcnt lgkmcnt(2)
	v_cndmask_b32_e64 v39, v32, -v32, vcc
	v_mov_b32_e32 v36, v33
	v_pk_mul_f32 v[32:33], v[36:37], v[38:39]
	s_waitcnt lgkmcnt(1)
	v_cndmask_b32_e64 v39, v47, -v47, vcc
	v_mov_b32_e32 v36, v34
	v_add_f32_e32 v44, v44, v45
	v_add_f32_e32 v45, v32, v33
	v_pk_mul_f32 v[32:33], v[36:37], v[38:39]
	s_waitcnt lgkmcnt(0)
; __device__ __forceinline__ unsigned cvt_pk_bf16(float lo, float hi) { unsigned r; asm volatile("v_cvt_pk_bf16_f32 %0, %1, %2" : "=v"(r) : "v"(lo), "v"(hi)); return r; }
;     __device__ __forceinline__ void operator()(const AccT& acc, const Unit& u, int wr, int wc, int fr, int fq) const {
;     ...
;                         const int t = t0 & 2047;
; #pragma unroll
;                         for (int hf = 0; hf < 2; ++hf) {
;                             f32x4 cs, sn;
;                             if (m < 2) { const float c1 = ropeA[(t >> 6) * 16 + d], s1 = ropeA[1024 + (t >> 6) * 16 + d]; cs = (f32x4){c1, c1, c1, c1}; sn = (f32x4){s1, s1, s1, s1}; }
;                             else { const float* cb = ropeA + 2048 + (d - 16) * 64 + (t & 63) + 4 * hf; cs = *(const f32x4*)(cb); sn = *(const f32x4*)(cb + 1024); }
; #pragma unroll
;                             for (int jj = 0; jj < 4; ++jj) { const float pr = __shfl_xor(v[4 * hf + jj], 4); v[4 * hf + jj] = v[4 * hf + jj] * cs[jj] + sgn * pr * sn[jj]; }
;                             __builtin_amdgcn_sched_barrier(0);
;                         }
;                     }
;                     float zf[8], zb[8]; zf[0] = zf0; zb[0] = zb0;
; #pragma unroll
;                     for (int jj = 1; jj < 8; ++jj) { zf[jj] = zf[jj - 1] * zfs; zb[jj] = zb[jj - 1] * zbs; }
;                     u32x4 wf, wb;
;                     wf.x = cvt_pk_bf16(v[0] * zf[0], v[1] * zf[1]); wf.y = cvt_pk_bf16(v[2] * zf[2], v[3] * zf[3]); wf.z = cvt_pk_bf16(v[4] * zf[4], v[5] * zf[5]); wf.w = cvt_pk_bf16(v[6] * zf[6], v[7] * zf[7]);
;                     wb.x = cvt_pk_bf16(v[0] * zb[0], v[1] * zb[1]); wb.y = cvt_pk_bf16(v[2] * zb[2], v[3] * zb[3]); wb.z = cvt_pk_bf16(v[4] * zb[4], v[5] * zb[5]); wb.w = cvt_pk_bf16(v[6] * zb[6], v[7] * zb[7]);
;                     *(u32x4*)(KTZ + (size_t)r * NT + t0) = wf;
;                     *(u32x4*)(KTZ + (size_t)(256 + r) * NT + t0) = wb;
	v_cndmask_b32_e64 v39, v51, -v51, vcc
	v_mov_b32_e32 v36, v35
	v_add_f32_e32 v47, v32, v33
	v_pk_mul_f32 v[32:33], v[36:37], v[38:39]
	s_nop 0
	v_add_f32_e32 v39, v32, v33
	v_mul_f32_e32 v32, v63, v48
	v_mul_f32_e32 v33, v75, v49
	v_cvt_pk_bf16_f32 v32, v32, v33
	v_mul_f32_e32 v33, v84, v50
	v_mul_f32_e32 v34, v86, v46
	v_cvt_pk_bf16_f32 v33, v33, v34
	v_mul_f32_e32 v34, v85, v44
	v_mul_f32_e32 v35, v88, v45
	v_cvt_pk_bf16_f32 v34, v34, v35
	v_mul_f32_e32 v35, v87, v47
	v_mul_f32_e32 v36, v71, v39
	v_cvt_pk_bf16_f32 v35, v35, v36
	v_mul_f32_e32 v36, v64, v48
	v_mul_f32_e32 v37, v60, v49
	v_cvt_pk_bf16_f32 v36, v36, v37
	v_mul_f32_e32 v37, v66, v50
	v_mul_f32_e32 v38, v68, v46
	v_cvt_pk_bf16_f32 v37, v37, v38
	v_mul_f32_e32 v38, v70, v44
	v_mul_f32_e32 v44, v72, v45
	v_mul_f32_e32 v39, v67, v39
	v_cvt_pk_bf16_f32 v38, v38, v44
	v_mul_f32_e32 v44, v65, v47
	v_cvt_pk_bf16_f32 v39, v44, v39
	global_store_dwordx4 v[40:41], v[32:35], off offset:256
	global_store_dwordx4 v[42:43], v[36:39], off offset:256
	global_load_dwordx4 v[32:35], v[98:99], off
	s_nop 0
	global_load_dwordx4 v[36:39], v[96:97], off
	ds_bpermute_b32 v41, v177, v28
	ds_bpermute_b32 v42, v177, v29
	ds_bpermute_b32 v44, v177, v30
	ds_bpermute_b32 v46, v177, v31
	v_mov_b32_e32 v40, v28
	v_mov_b32_e32 v28, v30
	s_waitcnt lgkmcnt(3)
	v_cndmask_b32_e64 v43, v41, -v41, vcc
	s_waitcnt lgkmcnt(2)
	v_cndmask_b32_e64 v45, v42, -v42, vcc
	s_waitcnt lgkmcnt(1)
	v_cndmask_b32_e64 v47, v44, -v44, vcc
	s_waitcnt lgkmcnt(0)
	v_cndmask_b32_e64 v49, v46, -v46, vcc
	s_waitcnt vmcnt(1)
	v_mov_b32_e32 v41, v32
	s_waitcnt vmcnt(0)
	v_mov_b32_e32 v42, v36
	v_mov_b32_e32 v32, v29
	v_mov_b32_e32 v44, v37
	v_mov_b32_e32 v29, v34
	v_mov_b32_e32 v46, v38
	v_mov_b32_e32 v34, v31
	v_mov_b32_e32 v48, v39
	v_pk_mul_f32 v[30:31], v[40:41], v[42:43]
	v_pk_mul_f32 v[32:33], v[32:33], v[44:45]
	v_pk_mul_f32 v[28:29], v[28:29], v[46:47]
	v_pk_mul_f32 v[34:35], v[34:35], v[48:49]
	v_add_f32_e32 v46, v30, v31
	v_add_f32_e32 v47, v32, v33
	v_add_f32_e32 v48, v28, v29
	v_add_f32_e32 v49, v34, v35
	global_load_dwordx4 v[28:31], v[92:93], off offset:16
	global_load_dwordx4 v[32:35], v[94:95], off offset:16
	ds_bpermute_b32 v37, v177, v24
	ds_bpermute_b32 v38, v177, v25
	ds_bpermute_b32 v40, v177, v26
	ds_bpermute_b32 v42, v177, v27
	v_mov_b32_e32 v36, v24
	v_mov_b32_e32 v24, v26
	s_waitcnt lgkmcnt(3)
	v_cndmask_b32_e64 v39, v37, -v37, vcc
	s_waitcnt lgkmcnt(2)
	v_cndmask_b32_e64 v41, v38, -v38, vcc
	s_waitcnt lgkmcnt(1)
	v_cndmask_b32_e64 v43, v40, -v40, vcc
	s_waitcnt lgkmcnt(0)
	v_cndmask_b32_e64 v45, v42, -v42, vcc
	s_waitcnt vmcnt(1)
	v_mov_b32_e32 v37, v28
	s_waitcnt vmcnt(0)
	v_mov_b32_e32 v38, v32
	v_mov_b32_e32 v28, v25
	v_mov_b32_e32 v40, v33
	v_mov_b32_e32 v25, v30
	v_mov_b32_e32 v42, v34
	v_mov_b32_e32 v30, v27
	v_mov_b32_e32 v44, v35
	v_pk_mul_f32 v[26:27], v[36:37], v[38:39]
	v_pk_mul_f32 v[28:29], v[28:29], v[40:41]
	v_pk_mul_f32 v[24:25], v[24:25], v[42:43]
	v_pk_mul_f32 v[30:31], v[30:31], v[44:45]
	v_add_f32_e32 v32, v26, v27
	v_add_f32_e32 v33, v28, v29
	v_add_f32_e32 v24, v24, v25
	v_add_f32_e32 v25, v30, v31
	v_mul_f32_e32 v26, v63, v46
	v_mul_f32_e32 v27, v75, v47
	v_cvt_pk_bf16_f32 v26, v26, v27
	v_mul_f32_e32 v27, v84, v48
	v_mul_f32_e32 v28, v86, v49
	v_cvt_pk_bf16_f32 v27, v27, v28
	v_mul_f32_e32 v28, v85, v32
	v_mul_f32_e32 v29, v88, v33
	v_cvt_pk_bf16_f32 v28, v28, v29
	v_mul_f32_e32 v29, v87, v24
	v_mul_f32_e32 v30, v71, v25
	v_cvt_pk_bf16_f32 v29, v29, v30
	v_mul_f32_e32 v30, v64, v46
	v_mul_f32_e32 v31, v60, v47
	v_cvt_pk_bf16_f32 v30, v30, v31
	v_mul_f32_e32 v31, v66, v48
	v_mul_f32_e32 v32, v70, v32
	v_mul_f32_e32 v33, v72, v33
	v_mul_f32_e32 v24, v65, v24
	v_mul_f32_e32 v25, v67, v25
	s_mov_b64 s[0:1], 0x1400000
	v_mul_f32_e32 v34, v68, v49
	v_cvt_pk_bf16_f32 v31, v31, v34
	v_cvt_pk_bf16_f32 v32, v32, v33
	v_cvt_pk_bf16_f32 v33, v24, v25
	v_lshl_add_u64 v[24:25], v[120:121], 0, s[0:1]
	s_mov_b32 s0, 0x1400000
	v_add_co_u32_e64 v34, s[4:5], s0, v120
	s_mov_b64 s[0:1], 0x3400000
	s_nop 0
	v_addc_co_u32_e64 v35, s[4:5], 0, v121, s[4:5]
	global_store_dwordx4 v[34:35], v[26:29], off
	s_nop 1
	v_lshl_add_u64 v[26:27], v[120:121], 0, s[0:1]
	s_mov_b32 s0, 0x3400000
	v_add_co_u32_e64 v28, s[4:5], s0, v120
	s_nop 1
	v_addc_co_u32_e64 v29, s[4:5], 0, v121, s[4:5]
	global_store_dwordx4 v[28:29], v[30:33], off
	global_load_dwordx4 v[28:31], v[98:99], off
	s_nop 0
	global_load_dwordx4 v[32:35], v[96:97], off
	ds_bpermute_b32 v37, v177, v20
	ds_bpermute_b32 v38, v177, v21
	ds_bpermute_b32 v40, v177, v22
	ds_bpermute_b32 v42, v177, v23
	v_mov_b32_e32 v36, v20
	v_mov_b32_e32 v20, v22
	s_waitcnt lgkmcnt(3)
	v_cndmask_b32_e64 v39, v37, -v37, vcc
	s_waitcnt lgkmcnt(2)
	v_cndmask_b32_e64 v41, v38, -v38, vcc
	s_waitcnt lgkmcnt(1)
	v_cndmask_b32_e64 v43, v40, -v40, vcc
	s_waitcnt lgkmcnt(0)
	v_cndmask_b32_e64 v45, v42, -v42, vcc
	s_waitcnt vmcnt(1)
	v_mov_b32_e32 v37, v28
	s_waitcnt vmcnt(0)
	v_mov_b32_e32 v38, v32
	v_mov_b32_e32 v28, v21
	v_mov_b32_e32 v40, v33
	v_mov_b32_e32 v21, v30
	v_mov_b32_e32 v42, v34
	v_mov_b32_e32 v30, v23
	v_mov_b32_e32 v44, v35
	v_pk_mul_f32 v[22:23], v[36:37], v[38:39]
	v_pk_mul_f32 v[28:29], v[28:29], v[40:41]
	v_pk_mul_f32 v[20:21], v[20:21], v[42:43]
	v_pk_mul_f32 v[30:31], v[30:31], v[44:45]
	v_add_f32_e32 v42, v22, v23
	v_add_f32_e32 v43, v28, v29
	v_add_f32_e32 v44, v20, v21
	v_add_f32_e32 v45, v30, v31
	global_load_dwordx4 v[20:23], v[92:93], off offset:16
	global_load_dwordx4 v[28:31], v[94:95], off offset:16
	ds_bpermute_b32 v33, v177, v16
	ds_bpermute_b32 v34, v177, v17
	ds_bpermute_b32 v36, v177, v18
	ds_bpermute_b32 v38, v177, v19
	v_mov_b32_e32 v32, v16
	v_mov_b32_e32 v16, v18
	s_waitcnt lgkmcnt(3)
; __device__ __forceinline__ unsigned cvt_pk_bf16(float lo, float hi) { unsigned r; asm volatile("v_cvt_pk_bf16_f32 %0, %1, %2" : "=v"(r) : "v"(lo), "v"(hi)); return r; }
;     __device__ __forceinline__ void operator()(const AccT& acc, const Unit& u, int wr, int wc, int fr, int fq) const {
;     ...
;                         const int t = t0 & 2047;
; #pragma unroll
;                         for (int hf = 0; hf < 2; ++hf) {
;                             f32x4 cs, sn;
;                             if (m < 2) { const float c1 = ropeA[(t >> 6) * 16 + d], s1 = ropeA[1024 + (t >> 6) * 16 + d]; cs = (f32x4){c1, c1, c1, c1}; sn = (f32x4){s1, s1, s1, s1}; }
;                             else { const float* cb = ropeA + 2048 + (d - 16) * 64 + (t & 63) + 4 * hf; cs = *(const f32x4*)(cb); sn = *(const f32x4*)(cb + 1024); }
; #pragma unroll
;                             for (int jj = 0; jj < 4; ++jj) { const float pr = __shfl_xor(v[4 * hf + jj], 4); v[4 * hf + jj] = v[4 * hf + jj] * cs[jj] + sgn * pr * sn[jj]; }
;                             __builtin_amdgcn_sched_barrier(0);
;                         }
;                     }
;                     float zf[8], zb[8]; zf[0] = zf0; zb[0] = zb0;
; #pragma unroll
;                     for (int jj = 1; jj < 8; ++jj) { zf[jj] = zf[jj - 1] * zfs; zb[jj] = zb[jj - 1] * zbs; }
;                     u32x4 wf, wb;
;                     wf.x = cvt_pk_bf16(v[0] * zf[0], v[1] * zf[1]); wf.y = cvt_pk_bf16(v[2] * zf[2], v[3] * zf[3]); wf.z = cvt_pk_bf16(v[4] * zf[4], v[5] * zf[5]); wf.w = cvt_pk_bf16(v[6] * zf[6], v[7] * zf[7]);
;                     wb.x = cvt_pk_bf16(v[0] * zb[0], v[1] * zb[1]); wb.y = cvt_pk_bf16(v[2] * zb[2], v[3] * zb[3]); wb.z = cvt_pk_bf16(v[4] * zb[4], v[5] * zb[5]); wb.w = cvt_pk_bf16(v[6] * zb[6], v[7] * zb[7]);
;                     *(u32x4*)(KTZ + (size_t)r * NT + t0) = wf;
;                     *(u32x4*)(KTZ + (size_t)(256 + r) * NT + t0) = wb;
	v_cndmask_b32_e64 v35, v33, -v33, vcc
	s_waitcnt lgkmcnt(2)
	v_cndmask_b32_e64 v37, v34, -v34, vcc
	s_waitcnt lgkmcnt(1)
	v_cndmask_b32_e64 v39, v36, -v36, vcc
	s_waitcnt lgkmcnt(0)
	v_cndmask_b32_e64 v41, v38, -v38, vcc
	s_waitcnt vmcnt(1)
	v_mov_b32_e32 v33, v20
	s_waitcnt vmcnt(0)
	v_mov_b32_e32 v34, v28
	v_mov_b32_e32 v20, v17
	v_mov_b32_e32 v36, v29
	v_mov_b32_e32 v17, v22
	v_mov_b32_e32 v38, v30
	v_mov_b32_e32 v22, v19
	v_mov_b32_e32 v40, v31
	v_pk_mul_f32 v[18:19], v[32:33], v[34:35]
	v_pk_mul_f32 v[20:21], v[20:21], v[36:37]
	v_pk_mul_f32 v[16:17], v[16:17], v[38:39]
	v_pk_mul_f32 v[22:23], v[22:23], v[40:41]
	v_add_f32_e32 v28, v18, v19
	v_add_f32_e32 v29, v20, v21
	v_add_f32_e32 v30, v16, v17
	v_add_f32_e32 v23, v22, v23
	v_mul_f32_e32 v16, v63, v42
	v_mul_f32_e32 v17, v75, v43
	v_cvt_pk_bf16_f32 v16, v16, v17
	v_mul_f32_e32 v17, v84, v44
	v_mul_f32_e32 v18, v86, v45
	v_cvt_pk_bf16_f32 v17, v17, v18
	v_mul_f32_e32 v18, v85, v28
	v_mul_f32_e32 v19, v88, v29
	v_cvt_pk_bf16_f32 v18, v18, v19
	v_mul_f32_e32 v19, v87, v30
	v_mul_f32_e32 v20, v71, v23
	v_cvt_pk_bf16_f32 v19, v19, v20
	v_mul_f32_e32 v20, v64, v42
	v_mul_f32_e32 v21, v60, v43
	v_cvt_pk_bf16_f32 v20, v20, v21
	v_mul_f32_e32 v21, v66, v44
	v_mul_f32_e32 v22, v68, v45
	v_cvt_pk_bf16_f32 v21, v21, v22
	v_mul_f32_e32 v22, v70, v28
	v_mul_f32_e32 v28, v72, v29
	v_mul_f32_e32 v23, v67, v23
	v_cvt_pk_bf16_f32 v22, v22, v28
	v_mul_f32_e32 v28, v65, v30
	v_cvt_pk_bf16_f32 v23, v28, v23
	global_store_dwordx4 v[24:25], v[16:19], off offset:256
	global_store_dwordx4 v[26:27], v[20:23], off offset:256
	global_load_dwordx4 v[16:19], v[82:83], off
	s_nop 0
	global_load_dwordx4 v[20:23], v[80:81], off
	ds_bpermute_b32 v25, v177, v12
	ds_bpermute_b32 v26, v177, v13
	ds_bpermute_b32 v28, v177, v14
	ds_bpermute_b32 v30, v177, v15
	v_mov_b32_e32 v24, v12
	v_mov_b32_e32 v12, v14
	s_waitcnt lgkmcnt(3)
	v_cndmask_b32_e64 v27, v25, -v25, vcc
	s_waitcnt lgkmcnt(2)
	v_cndmask_b32_e64 v29, v26, -v26, vcc
	s_waitcnt lgkmcnt(1)
	v_cndmask_b32_e64 v31, v28, -v28, vcc
	s_waitcnt lgkmcnt(0)
	v_cndmask_b32_e64 v33, v30, -v30, vcc
	s_waitcnt vmcnt(1)
	v_mov_b32_e32 v25, v16
	s_waitcnt vmcnt(0)
	v_mov_b32_e32 v26, v20
	v_mov_b32_e32 v16, v13
	v_mov_b32_e32 v28, v21
	v_mov_b32_e32 v13, v18
	v_mov_b32_e32 v30, v22
	v_mov_b32_e32 v18, v15
	v_mov_b32_e32 v32, v23
	v_pk_mul_f32 v[14:15], v[24:25], v[26:27]
	v_pk_mul_f32 v[16:17], v[16:17], v[28:29]
	v_pk_mul_f32 v[12:13], v[12:13], v[30:31]
	v_pk_mul_f32 v[18:19], v[18:19], v[32:33]
	v_add_f32_e32 v30, v14, v15
	v_add_f32_e32 v31, v16, v17
	v_add_f32_e32 v32, v12, v13
	v_add_f32_e32 v33, v18, v19
	global_load_dwordx4 v[12:15], v[76:77], off offset:16
	global_load_dwordx4 v[16:19], v[78:79], off offset:16
	ds_bpermute_b32 v21, v177, v8
	ds_bpermute_b32 v22, v177, v9
	ds_bpermute_b32 v24, v177, v10
	ds_bpermute_b32 v26, v177, v11
	v_mov_b32_e32 v20, v8
	v_mov_b32_e32 v8, v10
	s_waitcnt lgkmcnt(3)
	v_cndmask_b32_e64 v23, v21, -v21, vcc
	s_waitcnt lgkmcnt(2)
	v_cndmask_b32_e64 v25, v22, -v22, vcc
	s_waitcnt lgkmcnt(1)
	v_cndmask_b32_e64 v27, v24, -v24, vcc
	s_waitcnt lgkmcnt(0)
	v_cndmask_b32_e64 v29, v26, -v26, vcc
	s_waitcnt vmcnt(1)
	v_mov_b32_e32 v21, v12
	s_waitcnt vmcnt(0)
; __device__ __forceinline__ unsigned cvt_pk_bf16(float lo, float hi) { unsigned r; asm volatile("v_cvt_pk_bf16_f32 %0, %1, %2" : "=v"(r) : "v"(lo), "v"(hi)); return r; }
; #define PG8_WAIT_V(n) asm volatile("s_waitcnt vmcnt(" #n ")" ::: "memory")
; #define PG8_BAR __builtin_amdgcn_s_barrier()
; template <class Epi, class Sched>
; __device__ __forceinline__ void gemm_phase(LAS unsigned char* lds, const Gemm g, const Sched& S, const Epi& E) {
;     ...
;     }
;     PG8_WAIT_V(0);
;     if (wr == 0) PG8_BAR;
;     __device__ __forceinline__ void operator()(const AccT& acc, const Unit& u, int wr, int wc, int fr, int fq) const {
;     ...
;                         const int t = t0 & 2047;
; #pragma unroll
;                         for (int hf = 0; hf < 2; ++hf) {
;                             f32x4 cs, sn;
;                             if (m < 2) { const float c1 = ropeA[(t >> 6) * 16 + d], s1 = ropeA[1024 + (t >> 6) * 16 + d]; cs = (f32x4){c1, c1, c1, c1}; sn = (f32x4){s1, s1, s1, s1}; }
;                             else { const float* cb = ropeA + 2048 + (d - 16) * 64 + (t & 63) + 4 * hf; cs = *(const f32x4*)(cb); sn = *(const f32x4*)(cb + 1024); }
; #pragma unroll
;                             for (int jj = 0; jj < 4; ++jj) { const float pr = __shfl_xor(v[4 * hf + jj], 4); v[4 * hf + jj] = v[4 * hf + jj] * cs[jj] + sgn * pr * sn[jj]; }
;                             __builtin_amdgcn_sched_barrier(0);
;                         }
;                     }
;                     float zf[8], zb[8]; zf[0] = zf0; zb[0] = zb0;
; #pragma unroll
;                     for (int jj = 1; jj < 8; ++jj) { zf[jj] = zf[jj - 1] * zfs; zb[jj] = zb[jj - 1] * zbs; }
;                     u32x4 wf, wb;
;                     wf.x = cvt_pk_bf16(v[0] * zf[0], v[1] * zf[1]); wf.y = cvt_pk_bf16(v[2] * zf[2], v[3] * zf[3]); wf.z = cvt_pk_bf16(v[4] * zf[4], v[5] * zf[5]); wf.w = cvt_pk_bf16(v[6] * zf[6], v[7] * zf[7]);
;                     wb.x = cvt_pk_bf16(v[0] * zb[0], v[1] * zb[1]); wb.y = cvt_pk_bf16(v[2] * zb[2], v[3] * zb[3]); wb.z = cvt_pk_bf16(v[4] * zb[4], v[5] * zb[5]); wb.w = cvt_pk_bf16(v[6] * zb[6], v[7] * zb[7]);
;                     *(u32x4*)(KTZ + (size_t)r * NT + t0) = wf;
;                     *(u32x4*)(KTZ + (size_t)(256 + r) * NT + t0) = wb;
	v_mov_b32_e32 v22, v16
	v_mov_b32_e32 v12, v9
	v_mov_b32_e32 v24, v17
	v_mov_b32_e32 v9, v14
	v_mov_b32_e32 v26, v18
	v_mov_b32_e32 v14, v11
	v_mov_b32_e32 v28, v19
	v_pk_mul_f32 v[10:11], v[20:21], v[22:23]
	v_pk_mul_f32 v[12:13], v[12:13], v[24:25]
	v_pk_mul_f32 v[8:9], v[8:9], v[26:27]
	v_pk_mul_f32 v[14:15], v[14:15], v[28:29]
	v_add_f32_e32 v16, v10, v11
	v_add_f32_e32 v17, v12, v13
	v_add_f32_e32 v8, v8, v9
	v_add_f32_e32 v9, v14, v15
	v_mul_f32_e32 v10, v63, v30
	v_mul_f32_e32 v11, v75, v31
	v_cvt_pk_bf16_f32 v10, v10, v11
	v_mul_f32_e32 v11, v84, v32
	v_mul_f32_e32 v12, v86, v33
	v_cvt_pk_bf16_f32 v11, v11, v12
	v_mul_f32_e32 v12, v85, v16
	v_mul_f32_e32 v13, v88, v17
	v_cvt_pk_bf16_f32 v12, v12, v13
	v_mul_f32_e32 v13, v87, v8
	v_mul_f32_e32 v14, v71, v9
	v_cvt_pk_bf16_f32 v13, v13, v14
	v_mul_f32_e32 v14, v64, v30
	v_mul_f32_e32 v15, v60, v31
	v_cvt_pk_bf16_f32 v14, v14, v15
	v_mul_f32_e32 v15, v66, v32
	v_mul_f32_e32 v18, v68, v33
	v_cvt_pk_bf16_f32 v15, v15, v18
	v_add_co_u32_e64 v18, s[4:5], s63, v120
	v_mul_f32_e32 v16, v70, v16
	v_mul_f32_e32 v17, v72, v17
	v_addc_co_u32_e64 v19, s[4:5], 0, v121, s[4:5]
	v_cvt_pk_bf16_f32 v16, v16, v17
	v_mul_f32_e32 v8, v65, v8
	v_mul_f32_e32 v9, v67, v9
	v_cvt_pk_bf16_f32 v17, v8, v9
	global_store_dwordx4 v[18:19], v[10:13], off
	v_lshl_add_u64 v[8:9], v[120:121], 0, s[26:27]
	s_nop 0
	v_add_co_u32_e64 v12, s[4:5], s64, v120
	v_lshl_add_u64 v[10:11], v[120:121], 0, s[28:29]
	s_nop 0
	v_addc_co_u32_e64 v13, s[4:5], 0, v121, s[4:5]
	global_store_dwordx4 v[12:13], v[14:17], off
	global_load_dwordx4 v[12:15], v[82:83], off
	s_nop 0
	global_load_dwordx4 v[16:19], v[80:81], off
	ds_bpermute_b32 v34, v177, v4
	ds_bpermute_b32 v32, v177, v5
	ds_bpermute_b32 v33, v177, v6
	ds_bpermute_b32 v28, v177, v7
	global_load_dwordx4 v[20:23], v[76:77], off offset:16
	global_load_dwordx4 v[24:27], v[78:79], off offset:16
	s_waitcnt lgkmcnt(0)
	v_cndmask_b32_e64 v29, v28, -v28, vcc
	v_mov_b32_e32 v30, v7
	s_waitcnt vmcnt(3)
	v_mov_b32_e32 v31, v15
	s_waitcnt vmcnt(2)
	v_mov_b32_e32 v28, v19
	v_cndmask_b32_e64 v19, v33, -v33, vcc
	v_mov_b32_e32 v7, v14
	v_cndmask_b32_e64 v15, v32, -v32, vcc
	v_mov_b32_e32 v32, v5
	v_mov_b32_e32 v33, v13
	v_mov_b32_e32 v14, v17
	v_cndmask_b32_e64 v17, v34, -v34, vcc
	v_mov_b32_e32 v5, v12
	ds_bpermute_b32 v13, v177, v0
	v_mov_b32_e32 v12, v0
	ds_bpermute_b32 v34, v177, v1
	ds_bpermute_b32 v35, v177, v2
	v_mov_b32_e32 v0, v2
	ds_bpermute_b32 v2, v177, v3
	v_pk_mul_f32 v[28:29], v[30:31], v[28:29]
	v_pk_mul_f32 v[6:7], v[6:7], v[18:19]
	v_pk_mul_f32 v[14:15], v[32:33], v[14:15]
	v_pk_mul_f32 v[4:5], v[4:5], v[16:17]
	v_add_f32_e32 v18, v28, v29
	v_add_f32_e32 v19, v6, v7
	v_add_f32_e32 v28, v14, v15
	v_add_f32_e32 v29, v4, v5
	s_waitcnt lgkmcnt(3)
	v_cndmask_b32_e64 v5, v13, -v13, vcc
	s_waitcnt lgkmcnt(2)
	v_cndmask_b32_e64 v7, v34, -v34, vcc
	s_waitcnt lgkmcnt(1)
	v_cndmask_b32_e64 v15, v35, -v35, vcc
	s_waitcnt lgkmcnt(0)
	v_cndmask_b32_e64 v17, v2, -v2, vcc
	s_waitcnt vmcnt(1)
	v_mov_b32_e32 v13, v20
	s_waitcnt vmcnt(0)
	v_mov_b32_e32 v4, v24
	v_mov_b32_e32 v20, v1
	v_mov_b32_e32 v6, v25
	v_mov_b32_e32 v1, v22
	v_mov_b32_e32 v14, v26
	v_mov_b32_e32 v22, v3
	v_mov_b32_e32 v16, v27
	v_pk_mul_f32 v[2:3], v[12:13], v[4:5]
	v_pk_mul_f32 v[4:5], v[20:21], v[6:7]
	v_pk_mul_f32 v[0:1], v[0:1], v[14:15]
	v_pk_mul_f32 v[6:7], v[22:23], v[16:17]
	v_add_f32_e32 v12, v2, v3
	v_add_f32_e32 v13, v4, v5
	v_add_f32_e32 v14, v0, v1
	v_add_f32_e32 v7, v6, v7
	v_mul_f32_e32 v0, v63, v29
	v_mul_f32_e32 v1, v75, v28
	v_cvt_pk_bf16_f32 v0, v0, v1
	v_mul_f32_e32 v1, v84, v19
	v_mul_f32_e32 v2, v86, v18
	v_cvt_pk_bf16_f32 v1, v1, v2
	v_mul_f32_e32 v2, v85, v12
	v_mul_f32_e32 v3, v88, v13
	v_cvt_pk_bf16_f32 v2, v2, v3
	v_mul_f32_e32 v3, v87, v14
	v_mul_f32_e32 v4, v71, v7
	v_cvt_pk_bf16_f32 v3, v3, v4
	v_mul_f32_e32 v4, v64, v29
	v_mul_f32_e32 v5, v60, v28
	v_cvt_pk_bf16_f32 v4, v4, v5
	v_mul_f32_e32 v5, v66, v19
	v_mul_f32_e32 v6, v68, v18
	v_cvt_pk_bf16_f32 v5, v5, v6
	v_mul_f32_e32 v6, v70, v12
	v_mul_f32_e32 v12, v72, v13
	v_mul_f32_e32 v7, v67, v7
	v_cvt_pk_bf16_f32 v6, v6, v12
	v_mul_f32_e32 v12, v65, v14
	v_cvt_pk_bf16_f32 v7, v12, v7
	global_store_dwordx4 v[8:9], v[0:3], off offset:256
	global_store_dwordx4 v[10:11], v[4:7], off offset:256
	s_and_b64 vcc, exec, s[2:3]
	s_mov_b32 s33, s30
	s_mov_b64 s[4:5], s[38:39]
	s_mov_b64 s[0:1], s[36:37]
	s_barrier
	s_cbranch_vccz .LBB0_606
.Lconc_end_g3:
	s_waitcnt vmcnt(0)
	s_cmpk_gt_u32 s42, 0xff
	s_cbranch_scc1 .LBB0_617
	s_barrier

; #define PG8_STAGE(bufoff, gbase, voff) do { _Pragma("unroll") for (int _i = 0; _i < 2; ++_i) \
;         __builtin_amdgcn_global_load_lds((const unsigned*)((const char*)(gbase) + (voff)[_i]), (LAS unsigned*)(lds + (bufoff) + ldsw + _i * 8192), 16, 0, 0); } while (0)
; #define PG8_LDA(dst, b, h) do { _Pragma("unroll") for (int m = 0; m < 4; ++m) _Pragma("unroll") for (int k = 0; k < 2; ++k) dst[m][k] = *(const LAS bf16x8*)(lds + PG8_SA(b, h) + aoff + m * 2048 + k * 1024); } while (0)
; #define PG8_LDB(dst, b, h) do { _Pragma("unroll") for (int n = 0; n < 2; ++n) _Pragma("unroll") for (int k = 0; k < 2; ++k) dst[n][k] = *(const LAS bf16x8*)(lds + PG8_SB(b, h) + boff + n * 2048 + k * 1024); } while (0)
; #define PG8_MMA(ai, bj, At, Bt) do { __builtin_amdgcn_s_setprio(1); _Pragma("unroll") for (int m = 0; m < 4; ++m) _Pragma("unroll") for (int n = 0; n < 2; ++n) _Pragma("unroll") for (int k = 0; k < 2; ++k) \
;         acc[ai][bj][m][n] = __builtin_amdgcn_mfma_f32_16x16x32_bf16(Bt[n][k], At[m][k], acc[ai][bj][m][n], 0, 0, 0); __builtin_amdgcn_s_setprio(0); } while (0)
; #define PG8_WAIT_V(n) asm volatile("s_waitcnt vmcnt(" #n ")" ::: "memory")
; #define PG8_WAIT_L(n) asm volatile("s_waitcnt lgkmcnt(" #n ")" ::: "memory")
; #define PG8_BAR __builtin_amdgcn_s_barrier()
; #define PG8_SCHED __builtin_amdgcn_sched_barrier(0)
; template <class Epi, class Sched>
; __device__ __forceinline__ void gemm_phase(LAS unsigned char* lds, const Gemm g, const Sched& S, const Epi& E) {
;     ...
;             PG8_LDB(B0, 0, 0); PG8_SCHED; PG8_LDA(At, 0, 0); PG8_STAGE(PG8_SA(1, 1), a1 + hstep, voffA);
;             PG8_WAIT_L(8); PG8_BAR; PG8_WAIT_L(0); PG8_MMA(0, 0, At, B0); PG8_BAR; PG8_SCHED;
;             PG8_LDB(B1, 0, 1); PG8_STAGE(PG8_SB(0, 0), b2, voffB);
;             PG8_BAR; PG8_WAIT_L(0); PG8_MMA(0, 1, At, B1); PG8_BAR;
;             PG8_LDA(At, 0, 1); PG8_STAGE(PG8_SA(0, 0), a2, voffA);
;             PG8_BAR; PG8_WAIT_L(0); PG8_MMA(1, 0, At, B0); PG8_BAR; PG8_SCHED;
;             PG8_STAGE(PG8_SB(0, 1), b2 + hstep, voffB);
;             PG8_WAIT_V(6); PG8_BAR; PG8_MMA(1, 1, At, B1); PG8_BAR;
.LBB0_633:
	ds_read_b128 v[150:153], v147
	ds_read_b128 v[154:157], v147 offset:1024
	ds_read_b128 v[158:161], v147 offset:2048
	ds_read_b128 v[162:165], v147 offset:3072
	s_add_u32 s34, s30, 0xfffc0080
	s_addc_u32 s35, s31, -1
	s_cmp_eq_u32 s65, 12
	s_cselect_b32 s37, s23, s35
	s_cselect_b32 s36, s61, s34
	s_cselect_b32 s35, s21, s64
	s_cselect_b32 s34, s62, s63
	s_add_i32 m0, s29, 0xc000
	ds_read_b128 v[166:169], v148
	ds_read_b128 v[170:173], v148 offset:1024
	ds_read_b128 v[174:177], v148 offset:2048
	ds_read_b128 v[178:181], v148 offset:3072
	ds_read_b128 v[182:185], v148 offset:4096
	ds_read_b128 v[186:189], v148 offset:5120
	ds_read_b128 v[190:193], v148 offset:6144
	ds_read_b128 v[194:197], v148 offset:7168
	global_load_lds_dwordx4 v136, s[30:31]
	s_add_i32 m0, s29, 0xe000
	s_nop 0
	global_load_lds_dwordx4 v138, s[30:31]
	s_waitcnt lgkmcnt(8)
	s_waitcnt vmcnt(10)
	s_barrier
	s_waitcnt lgkmcnt(0)
	s_setprio 1
	s_waitcnt lgkmcnt(0)
	v_mfma_f32_16x16x32_bf16 v[124:127], v[150:153], v[166:169], v[124:127]
	v_mfma_f32_16x16x32_bf16 v[120:123], v[158:161], v[166:169], v[120:123]
	v_mfma_f32_16x16x32_bf16 v[116:119], v[150:153], v[174:177], v[116:119]
	v_mfma_f32_16x16x32_bf16 v[108:111], v[158:161], v[174:177], v[108:111]
	v_mfma_f32_16x16x32_bf16 v[100:103], v[150:153], v[182:185], v[100:103]
	v_mfma_f32_16x16x32_bf16 v[92:95], v[158:161], v[182:185], v[92:95]
	v_mfma_f32_16x16x32_bf16 v[84:87], v[150:153], v[190:193], v[84:87]
	v_mfma_f32_16x16x32_bf16 v[76:79], v[158:161], v[190:193], v[76:79]
	v_mfma_f32_16x16x32_bf16 v[124:127], v[154:157], v[170:173], v[124:127]
	v_mfma_f32_16x16x32_bf16 v[120:123], v[162:165], v[170:173], v[120:123]
	v_mfma_f32_16x16x32_bf16 v[116:119], v[154:157], v[178:181], v[116:119]
	v_mfma_f32_16x16x32_bf16 v[108:111], v[162:165], v[178:181], v[108:111]
	v_mfma_f32_16x16x32_bf16 v[100:103], v[154:157], v[186:189], v[100:103]
	v_mfma_f32_16x16x32_bf16 v[92:95], v[162:165], v[186:189], v[92:95]
	v_mfma_f32_16x16x32_bf16 v[84:87], v[154:157], v[194:197], v[84:87]
	v_mfma_f32_16x16x32_bf16 v[76:79], v[162:165], v[194:197], v[76:79]
	s_setprio 0
	s_barrier
	s_add_i32 s66, s54, s43
	s_mov_b32 m0, s66
	ds_read_b128 v[202:205], v149
	ds_read_b128 v[206:209], v149 offset:1024
	ds_read_b128 v[210:213], v149 offset:2048
	ds_read_b128 v[214:217], v149 offset:3072
	global_load_lds_dwordx4 v130, s[34:35]
	s_add_i32 m0, s66, 0x2000
	s_nop 0
	global_load_lds_dwordx4 v134, s[34:35]
	s_waitcnt vmcnt(10)
	s_barrier
	s_waitcnt lgkmcnt(0)
	s_setprio 1
	s_waitcnt lgkmcnt(0)
	v_mfma_f32_16x16x32_bf16 v[112:115], v[202:205], v[166:169], v[112:115]
	v_mfma_f32_16x16x32_bf16 v[104:107], v[210:213], v[166:169], v[104:107]
	v_mfma_f32_16x16x32_bf16 v[96:99], v[202:205], v[174:177], v[96:99]
	v_mfma_f32_16x16x32_bf16 v[88:91], v[210:213], v[174:177], v[88:91]
	v_mfma_f32_16x16x32_bf16 v[80:83], v[202:205], v[182:185], v[80:83]
	v_mfma_f32_16x16x32_bf16 v[72:75], v[210:213], v[182:185], v[72:75]
	v_mfma_f32_16x16x32_bf16 v[68:71], v[202:205], v[190:193], v[68:71]
	v_mfma_f32_16x16x32_bf16 v[64:67], v[210:213], v[190:193], v[64:67]
	v_mfma_f32_16x16x32_bf16 v[112:115], v[206:209], v[170:173], v[112:115]
	v_mfma_f32_16x16x32_bf16 v[104:107], v[214:217], v[170:173], v[104:107]
	v_mfma_f32_16x16x32_bf16 v[96:99], v[206:209], v[178:181], v[96:99]
	v_mfma_f32_16x16x32_bf16 v[88:91], v[214:217], v[178:181], v[88:91]
	v_mfma_f32_16x16x32_bf16 v[80:83], v[206:209], v[186:189], v[80:83]
	v_mfma_f32_16x16x32_bf16 v[72:75], v[214:217], v[186:189], v[72:75]
	v_mfma_f32_16x16x32_bf16 v[68:71], v[206:209], v[194:197], v[68:71]
	v_mfma_f32_16x16x32_bf16 v[64:67], v[214:217], v[194:197], v[64:67]
	s_setprio 0
	s_mov_b32 m0, s29
	v_lshl_add_u64 v[220:221], s[36:37], 0, v[128:129]
	s_barrier
	ds_read_b128 v[166:169], v148 offset:16384
	ds_read_b128 v[170:173], v148 offset:17408
	ds_read_b128 v[174:177], v148 offset:18432
	ds_read_b128 v[178:181], v148 offset:19456
	ds_read_b128 v[182:185], v148 offset:20480
	ds_read_b128 v[186:189], v148 offset:21504
	ds_read_b128 v[190:193], v148 offset:22528
	ds_read_b128 v[194:197], v148 offset:23552
	global_load_lds_dwordx4 v128, s[36:37]
	v_lshl_add_u64 v[222:223], s[36:37], 0, v[132:133]
	s_mov_b32 m0, s44
	s_nop 0
	global_load_lds_dwordx4 v132, s[36:37]
	s_barrier
	s_waitcnt lgkmcnt(0)
	s_setprio 1
	s_waitcnt lgkmcnt(0)
	v_mfma_f32_16x16x32_bf16 v[60:63], v[150:153], v[166:169], v[60:63]
	v_mfma_f32_16x16x32_bf16 v[56:59], v[158:161], v[166:169], v[56:59]
	v_mfma_f32_16x16x32_bf16 v[52:55], v[150:153], v[174:177], v[52:55]
	v_mfma_f32_16x16x32_bf16 v[44:47], v[158:161], v[174:177], v[44:47]
	v_mfma_f32_16x16x32_bf16 v[36:39], v[150:153], v[182:185], v[36:39]
	v_mfma_f32_16x16x32_bf16 v[28:31], v[158:161], v[182:185], v[28:31]
	v_mfma_f32_16x16x32_bf16 v[20:23], v[150:153], v[190:193], v[20:23]
	v_mfma_f32_16x16x32_bf16 v[12:15], v[158:161], v[190:193], v[12:15]
	v_mfma_f32_16x16x32_bf16 v[60:63], v[154:157], v[170:173], v[60:63]
	v_mfma_f32_16x16x32_bf16 v[56:59], v[162:165], v[170:173], v[56:59]
	v_mfma_f32_16x16x32_bf16 v[52:55], v[154:157], v[178:181], v[52:55]
	v_mfma_f32_16x16x32_bf16 v[44:47], v[162:165], v[178:181], v[44:47]
	v_mfma_f32_16x16x32_bf16 v[36:39], v[154:157], v[186:189], v[36:39]
	v_mfma_f32_16x16x32_bf16 v[28:31], v[162:165], v[186:189], v[28:31]
	v_mfma_f32_16x16x32_bf16 v[20:23], v[154:157], v[194:197], v[20:23]
	v_mfma_f32_16x16x32_bf16 v[12:15], v[162:165], v[194:197], v[12:15]
	s_setprio 0
	s_barrier
; #define PG8_STAGE(bufoff, gbase, voff) do { _Pragma("unroll") for (int _i = 0; _i < 2; ++_i) \
;         __builtin_amdgcn_global_load_lds((const unsigned*)((const char*)(gbase) + (voff)[_i]), (LAS unsigned*)(lds + (bufoff) + ldsw + _i * 8192), 16, 0, 0); } while (0)
; #define PG8_LDA(dst, b, h) do { _Pragma("unroll") for (int m = 0; m < 4; ++m) _Pragma("unroll") for (int k = 0; k < 2; ++k) dst[m][k] = *(const LAS bf16x8*)(lds + PG8_SA(b, h) + aoff + m * 2048 + k * 1024); } while (0)
; #define PG8_LDB(dst, b, h) do { _Pragma("unroll") for (int n = 0; n < 2; ++n) _Pragma("unroll") for (int k = 0; k < 2; ++k) dst[n][k] = *(const LAS bf16x8*)(lds + PG8_SB(b, h) + boff + n * 2048 + k * 1024); } while (0)
; #define PG8_MMA(ai, bj, At, Bt) do { __builtin_amdgcn_s_setprio(1); _Pragma("unroll") for (int m = 0; m < 4; ++m) _Pragma("unroll") for (int n = 0; n < 2; ++n) _Pragma("unroll") for (int k = 0; k < 2; ++k) \
;         acc[ai][bj][m][n] = __builtin_amdgcn_mfma_f32_16x16x32_bf16(Bt[n][k], At[m][k], acc[ai][bj][m][n], 0, 0, 0); __builtin_amdgcn_s_setprio(0); } while (0)
; #define PG8_WAIT_V(n) asm volatile("s_waitcnt vmcnt(" #n ")" ::: "memory")
; #define PG8_WAIT_L(n) asm volatile("s_waitcnt lgkmcnt(" #n ")" ::: "memory")
; #define PG8_BAR __builtin_amdgcn_s_barrier()
; #define PG8_SCHED __builtin_amdgcn_sched_barrier(0)
; template <class Epi, class Sched>
; __device__ __forceinline__ void gemm_phase(LAS unsigned char* lds, const Gemm g, const Sched& S, const Epi& E) {
;     ...
;             PG8_STAGE(PG8_SB(0, 1), b2 + hstep, voffB);
;             PG8_WAIT_V(6); PG8_BAR; PG8_MMA(1, 1, At, B1); PG8_BAR;
;             PG8_LDB(B0, 1, 0); PG8_SCHED; PG8_LDA(At, 1, 0); PG8_STAGE(PG8_SA(0, 1), a2 + hstep, voffA);
;             PG8_WAIT_L(8); PG8_BAR; PG8_WAIT_L(0); PG8_MMA(0, 0, At, B0); PG8_BAR; PG8_SCHED;
;             PG8_LDB(B1, 1, 1); PG8_STAGE(PG8_SB(1, 0), b3, voffB);
;             PG8_BAR; PG8_WAIT_L(0); PG8_MMA(0, 1, At, B1); PG8_BAR;
;             PG8_LDA(At, 1, 1); PG8_STAGE(PG8_SA(1, 0), a3, voffA);
;             PG8_BAR; PG8_WAIT_L(0); PG8_MMA(1, 0, At, B0); PG8_BAR; PG8_SCHED;
	s_add_u32 s66, s34, 0x40000
	s_addc_u32 s67, s35, 0
	s_add_i32 s68, s55, s43
	s_mov_b32 m0, s68
	s_nop 0
	global_load_lds_dwordx4 v130, s[66:67]
	s_add_i32 m0, s68, 0x2000
	s_nop 0
	global_load_lds_dwordx4 v134, s[66:67]
	s_add_u32 s36, s36, 0x40000
	s_addc_u32 s37, s37, 0
	s_mov_b32 m0, s45
	s_nop 0
	global_load_lds_dwordx4 v128, s[36:37]
	s_mov_b32 m0, s46
	s_nop 0
	global_load_lds_dwordx4 v132, s[36:37]
	s_waitcnt vmcnt(12)
	s_barrier
	s_setprio 1
	v_mfma_f32_16x16x32_bf16 v[48:51], v[202:205], v[166:169], v[48:51]
	v_mfma_f32_16x16x32_bf16 v[40:43], v[210:213], v[166:169], v[40:43]
	v_mfma_f32_16x16x32_bf16 v[32:35], v[202:205], v[174:177], v[32:35]
	v_mfma_f32_16x16x32_bf16 v[24:27], v[210:213], v[174:177], v[24:27]
	v_mfma_f32_16x16x32_bf16 v[16:19], v[202:205], v[182:185], v[16:19]
	v_mfma_f32_16x16x32_bf16 v[8:11], v[210:213], v[182:185], v[8:11]
	v_mfma_f32_16x16x32_bf16 v[4:7], v[202:205], v[190:193], v[4:7]
	v_mfma_f32_16x16x32_bf16 v[0:3], v[210:213], v[190:193], v[0:3]
	v_mfma_f32_16x16x32_bf16 v[48:51], v[206:209], v[170:173], v[48:51]
	v_mfma_f32_16x16x32_bf16 v[40:43], v[214:217], v[170:173], v[40:43]
	v_mfma_f32_16x16x32_bf16 v[32:35], v[206:209], v[178:181], v[32:35]
	v_mfma_f32_16x16x32_bf16 v[24:27], v[214:217], v[178:181], v[24:27]
	v_mfma_f32_16x16x32_bf16 v[16:19], v[206:209], v[186:189], v[16:19]
	v_mfma_f32_16x16x32_bf16 v[8:11], v[214:217], v[186:189], v[8:11]
	v_mfma_f32_16x16x32_bf16 v[4:7], v[206:209], v[194:197], v[4:7]
	v_mfma_f32_16x16x32_bf16 v[0:3], v[214:217], v[194:197], v[0:3]
	s_setprio 0
	s_add_i32 s66, 0, 0x18000
	v_add_u32_e32 v162, s66, v146
	s_barrier
	ds_read_b128 v[150:153], v162
	ds_read_b128 v[154:157], v162 offset:1024
	ds_read_b128 v[158:161], v162 offset:2048
	ds_read_b128 v[162:165], v162 offset:3072
	ds_read_b128 v[166:169], v148 offset:32768
	ds_read_b128 v[170:173], v148 offset:33792
	ds_read_b128 v[174:177], v148 offset:34816
	ds_read_b128 v[178:181], v148 offset:35840
	ds_read_b128 v[182:185], v148 offset:36864
	ds_read_b128 v[186:189], v148 offset:37888
	ds_read_b128 v[190:193], v148 offset:38912
	ds_read_b128 v[194:197], v148 offset:39936
	s_waitcnt lgkmcnt(8)
	s_waitcnt vmcnt(10)
	s_barrier
	s_waitcnt lgkmcnt(0)
	s_setprio 1
	s_waitcnt lgkmcnt(0)
	v_mfma_f32_16x16x32_bf16 v[124:127], v[150:153], v[166:169], v[124:127]
	v_mfma_f32_16x16x32_bf16 v[120:123], v[158:161], v[166:169], v[120:123]
	v_mfma_f32_16x16x32_bf16 v[116:119], v[150:153], v[174:177], v[116:119]
	v_mfma_f32_16x16x32_bf16 v[108:111], v[158:161], v[174:177], v[108:111]
	v_mfma_f32_16x16x32_bf16 v[100:103], v[150:153], v[182:185], v[100:103]
	v_mfma_f32_16x16x32_bf16 v[92:95], v[158:161], v[182:185], v[92:95]
	v_mfma_f32_16x16x32_bf16 v[84:87], v[150:153], v[190:193], v[84:87]
	v_mfma_f32_16x16x32_bf16 v[76:79], v[158:161], v[190:193], v[76:79]
	v_mfma_f32_16x16x32_bf16 v[124:127], v[154:157], v[170:173], v[124:127]
	v_mfma_f32_16x16x32_bf16 v[120:123], v[162:165], v[170:173], v[120:123]
	v_mfma_f32_16x16x32_bf16 v[116:119], v[154:157], v[178:181], v[116:119]
	v_mfma_f32_16x16x32_bf16 v[108:111], v[162:165], v[178:181], v[108:111]
	v_mfma_f32_16x16x32_bf16 v[100:103], v[154:157], v[186:189], v[100:103]
	v_mfma_f32_16x16x32_bf16 v[92:95], v[162:165], v[186:189], v[92:95]
	v_mfma_f32_16x16x32_bf16 v[84:87], v[154:157], v[194:197], v[84:87]
	v_mfma_f32_16x16x32_bf16 v[76:79], v[162:165], v[194:197], v[76:79]
	s_setprio 0
	s_barrier
	s_add_i32 s36, 0, 0x1c000
	s_add_i32 s37, s66, s43
	v_add_u32_e32 v214, s36, v146
	s_add_u32 s4, s34, 0x80
	s_addc_u32 s5, s35, 0
	s_mov_b32 m0, s37
	ds_read_b128 v[202:205], v214
	ds_read_b128 v[206:209], v214 offset:1024
	ds_read_b128 v[210:213], v214 offset:2048
	ds_read_b128 v[214:217], v214 offset:3072
	global_load_lds_dwordx4 v130, s[4:5]
	s_add_i32 m0, s37, 0x2000
	s_nop 0
	global_load_lds_dwordx4 v134, s[4:5]
	s_waitcnt vmcnt(10)
	s_barrier
	s_waitcnt lgkmcnt(0)
	s_setprio 1
	s_waitcnt lgkmcnt(0)
	v_mfma_f32_16x16x32_bf16 v[112:115], v[202:205], v[166:169], v[112:115]
	v_mfma_f32_16x16x32_bf16 v[104:107], v[210:213], v[166:169], v[104:107]
	v_mfma_f32_16x16x32_bf16 v[96:99], v[202:205], v[174:177], v[96:99]
	v_mfma_f32_16x16x32_bf16 v[88:91], v[210:213], v[174:177], v[88:91]
	v_mfma_f32_16x16x32_bf16 v[80:83], v[202:205], v[182:185], v[80:83]
	v_mfma_f32_16x16x32_bf16 v[72:75], v[210:213], v[182:185], v[72:75]
	v_mfma_f32_16x16x32_bf16 v[68:71], v[202:205], v[190:193], v[68:71]
	v_mfma_f32_16x16x32_bf16 v[64:67], v[210:213], v[190:193], v[64:67]
	v_mfma_f32_16x16x32_bf16 v[112:115], v[206:209], v[170:173], v[112:115]
	v_mfma_f32_16x16x32_bf16 v[104:107], v[214:217], v[170:173], v[104:107]
	v_mfma_f32_16x16x32_bf16 v[96:99], v[206:209], v[178:181], v[96:99]
	v_mfma_f32_16x16x32_bf16 v[88:91], v[214:217], v[178:181], v[88:91]
	v_mfma_f32_16x16x32_bf16 v[80:83], v[206:209], v[186:189], v[80:83]
	v_mfma_f32_16x16x32_bf16 v[72:75], v[214:217], v[186:189], v[72:75]
	v_mfma_f32_16x16x32_bf16 v[68:71], v[206:209], v[194:197], v[68:71]
	v_mfma_f32_16x16x32_bf16 v[64:67], v[214:217], v[194:197], v[64:67]
	s_setprio 0
	s_mov_b32 m0, s51
	s_mov_b64 s[4:5], 0x80
	v_lshl_add_u64 v[198:199], v[220:221], 0, s[4:5]
	s_barrier
	ds_read_b128 v[166:169], v148 offset:49152
	ds_read_b128 v[170:173], v148 offset:50176
	ds_read_b128 v[174:177], v148 offset:51200
	ds_read_b128 v[178:181], v148 offset:52224
	ds_read_b128 v[182:185], v148 offset:53248
	ds_read_b128 v[186:189], v148 offset:54272
	ds_read_b128 v[190:193], v148 offset:55296
	ds_read_b128 v[194:197], v148 offset:56320
	global_load_lds_dwordx4 v[198:199], off
	v_lshl_add_u64 v[198:199], v[222:223], 0, s[4:5]
	s_mov_b32 m0, s52
	s_nop 0
	global_load_lds_dwordx4 v[198:199], off
	s_barrier
; __device__ __forceinline__ unsigned cvt_pk_bf16(float lo, float hi) { unsigned r; asm volatile("v_cvt_pk_bf16_f32 %0, %1, %2" : "=v"(r) : "v"(lo), "v"(hi)); return r; }
; #define PG8_STAGE(bufoff, gbase, voff) do { _Pragma("unroll") for (int _i = 0; _i < 2; ++_i) \
;         __builtin_amdgcn_global_load_lds((const unsigned*)((const char*)(gbase) + (voff)[_i]), (LAS unsigned*)(lds + (bufoff) + ldsw + _i * 8192), 16, 0, 0); } while (0)
; #define PG8_MMA(ai, bj, At, Bt) do { __builtin_amdgcn_s_setprio(1); _Pragma("unroll") for (int m = 0; m < 4; ++m) _Pragma("unroll") for (int n = 0; n < 2; ++n) _Pragma("unroll") for (int k = 0; k < 2; ++k) \
;         acc[ai][bj][m][n] = __builtin_amdgcn_mfma_f32_16x16x32_bf16(Bt[n][k], At[m][k], acc[ai][bj][m][n], 0, 0, 0); __builtin_amdgcn_s_setprio(0); } while (0)
; #define PG8_WAIT_V(n) asm volatile("s_waitcnt vmcnt(" #n ")" ::: "memory")
; #define PG8_WAIT_L(n) asm volatile("s_waitcnt lgkmcnt(" #n ")" ::: "memory")
; #define PG8_BAR __builtin_amdgcn_s_barrier()
; #define PG8_SCHED __builtin_amdgcn_sched_barrier(0)
; template <class Epi, class Sched>
; __device__ __forceinline__ void gemm_phase(LAS unsigned char* lds, const Gemm g, const Sched& S, const Epi& E) {
;     ...
;             PG8_BAR; PG8_WAIT_L(0); PG8_MMA(1, 0, At, B0); PG8_BAR; PG8_SCHED;
;             PG8_STAGE(PG8_SB(1, 1), b3 + hstep, voffB);
;             PG8_WAIT_V(6); PG8_BAR; PG8_MMA(1, 1, At, B1); PG8_BAR;
;     __device__ __forceinline__ void operator()(const AccT& acc, const Unit& u, int wr, int wc, int fr, int fq) const {
;     ...
; #pragma unroll
;         for (int ai = 0; ai < 2; ++ai)
; #pragma unroll
;             for (int m = 0; m < 4; ++m) {
;                 const int r = rbase + ai * 128 + m * 16;
; #pragma unroll
;                 for (int bj = 0; bj < 2; ++bj) {
;                     const int t0 = tb + bj * 128;
;                     const f32x4 v0 = acc[ai][bj][m][0], v1 = acc[ai][bj][m][1];
;                     u32x4 w; w.x = cvt_pk_bf16(v0[0], v0[1]); w.y = cvt_pk_bf16(v0[2], v0[3]); w.z = cvt_pk_bf16(v1[0], v1[1]); w.w = cvt_pk_bf16(v1[2], v1[3]);
;                     *(u32x4*)(VT + (size_t)r * NT + t0) = w;
;                 }
	s_waitcnt lgkmcnt(0)
	s_setprio 1
	s_waitcnt lgkmcnt(0)
	v_mfma_f32_16x16x32_bf16 v[60:63], v[150:153], v[166:169], v[60:63]
	v_mfma_f32_16x16x32_bf16 v[56:59], v[158:161], v[166:169], v[56:59]
	v_mfma_f32_16x16x32_bf16 v[52:55], v[150:153], v[174:177], v[52:55]
	v_mfma_f32_16x16x32_bf16 v[44:47], v[158:161], v[174:177], v[44:47]
	v_mfma_f32_16x16x32_bf16 v[36:39], v[150:153], v[182:185], v[36:39]
	v_mfma_f32_16x16x32_bf16 v[28:31], v[158:161], v[182:185], v[28:31]
	v_mfma_f32_16x16x32_bf16 v[20:23], v[150:153], v[190:193], v[20:23]
	v_mfma_f32_16x16x32_bf16 v[12:15], v[158:161], v[190:193], v[12:15]
	v_mfma_f32_16x16x32_bf16 v[60:63], v[154:157], v[170:173], v[60:63]
	v_mfma_f32_16x16x32_bf16 v[56:59], v[162:165], v[170:173], v[56:59]
	v_mfma_f32_16x16x32_bf16 v[52:55], v[154:157], v[178:181], v[52:55]
	v_mfma_f32_16x16x32_bf16 v[44:47], v[162:165], v[178:181], v[44:47]
	v_mfma_f32_16x16x32_bf16 v[36:39], v[154:157], v[186:189], v[36:39]
	v_mfma_f32_16x16x32_bf16 v[28:31], v[162:165], v[186:189], v[28:31]
	v_mfma_f32_16x16x32_bf16 v[20:23], v[154:157], v[194:197], v[20:23]
	v_mfma_f32_16x16x32_bf16 v[12:15], v[162:165], v[194:197], v[12:15]
	s_setprio 0
	s_barrier
	s_add_u32 s34, s34, 0x40080
	s_addc_u32 s35, s35, 0
	s_add_i32 s36, s36, s43
	s_mov_b32 m0, s36
	s_nop 0
	global_load_lds_dwordx4 v130, s[34:35]
	s_add_i32 m0, s36, 0x2000
	s_nop 0
	global_load_lds_dwordx4 v134, s[34:35]
	s_waitcnt vmcnt(10)
	s_barrier
	s_setprio 1
	v_mfma_f32_16x16x32_bf16 v[48:51], v[202:205], v[166:169], v[48:51]
	v_mfma_f32_16x16x32_bf16 v[40:43], v[210:213], v[166:169], v[40:43]
	v_mfma_f32_16x16x32_bf16 v[32:35], v[202:205], v[174:177], v[32:35]
	v_mfma_f32_16x16x32_bf16 v[24:27], v[210:213], v[174:177], v[24:27]
	v_mfma_f32_16x16x32_bf16 v[16:19], v[202:205], v[182:185], v[16:19]
	v_mfma_f32_16x16x32_bf16 v[8:11], v[210:213], v[182:185], v[8:11]
	v_mfma_f32_16x16x32_bf16 v[4:7], v[202:205], v[190:193], v[4:7]
	v_mfma_f32_16x16x32_bf16 v[0:3], v[210:213], v[190:193], v[0:3]
	v_mfma_f32_16x16x32_bf16 v[48:51], v[206:209], v[170:173], v[48:51]
	v_mfma_f32_16x16x32_bf16 v[40:43], v[214:217], v[170:173], v[40:43]
	v_mfma_f32_16x16x32_bf16 v[32:35], v[206:209], v[178:181], v[32:35]
	v_mfma_f32_16x16x32_bf16 v[24:27], v[214:217], v[178:181], v[24:27]
	v_mfma_f32_16x16x32_bf16 v[16:19], v[206:209], v[186:189], v[16:19]
	v_mfma_f32_16x16x32_bf16 v[8:11], v[214:217], v[186:189], v[8:11]
	v_mfma_f32_16x16x32_bf16 v[4:7], v[206:209], v[194:197], v[4:7]
	v_mfma_f32_16x16x32_bf16 v[0:3], v[214:217], v[194:197], v[0:3]
	s_setprio 0
	s_add_i32 s65, s65, 2
	s_add_u32 s30, s30, 0x100
	s_addc_u32 s31, s31, 0
	s_add_u32 s63, s63, 0x100
	s_addc_u32 s64, s64, 0
	s_cmp_gt_u32 s65, 13
	s_cbranch_scc1 .Lconc_last_g4
	s_barrier
	s_branch .LBB0_633
.Lconc_last_g4:
	v_readfirstlane_b32 s21, v200
	s_nop 3
	s_cmp_gt_u32 s21, 0xff
	s_cbranch_scc1 .Lconc_epi1_g4
	s_barrier
	v_mov_b32_e32 v150, v144
	v_mov_b32_e32 v151, v145
	s_lshl_b32 s21, s28, 8
	s_add_i32 s21, s21, s48
	v_add_u32_e32 v150, s21, v150
	s_lshl_b32 s21, s60, 8
	s_or_b32 s21, s21, s49
	v_lshl_add_u32 v152, v151, 3, s21
	v_ashrrev_i32_e32 v151, 31, v150
	v_cvt_pk_bf16_f32 v124, v124, v125
	v_cvt_pk_bf16_f32 v125, v126, v127
	v_cvt_pk_bf16_f32 v126, v120, v121
	v_lshlrev_b64 v[120:121], 17, v[150:151]
	v_lshl_add_u64 v[120:121], s[0:1], 0, v[120:121]
	v_ashrrev_i32_e32 v153, 31, v152
	v_lshl_add_u64 v[120:121], v[152:153], 1, v[120:121]
	s_mov_b32 s21, 0x200000
	v_cvt_pk_bf16_f32 v127, v122, v123
	global_store_dwordx4 v[120:121], v[124:127], off
	v_cvt_pk_bf16_f32 v112, v112, v113
	v_cvt_pk_bf16_f32 v113, v114, v115
	v_cvt_pk_bf16_f32 v114, v104, v105
	v_cvt_pk_bf16_f32 v115, v106, v107
	global_store_dwordx4 v[120:121], v[112:115], off offset:256
	v_cvt_pk_bf16_f32 v104, v116, v117
	v_cvt_pk_bf16_f32 v105, v118, v119
	v_cvt_pk_bf16_f32 v106, v108, v109
	v_cvt_pk_bf16_f32 v107, v110, v111
	s_mov_b64 s[30:31], 0x200000
	v_add_co_u32_e32 v110, vcc, s21, v120
	v_lshl_add_u64 v[108:109], v[120:121], 0, s[30:31]
	s_nop 0
	v_addc_co_u32_e32 v111, vcc, 0, v121, vcc
	s_mov_b32 s21, 0x400000
	global_store_dwordx4 v[110:111], v[104:107], off
	v_cvt_pk_bf16_f32 v96, v96, v97
	v_cvt_pk_bf16_f32 v97, v98, v99
	v_cvt_pk_bf16_f32 v98, v88, v89
	v_cvt_pk_bf16_f32 v99, v90, v91
	global_store_dwordx4 v[108:109], v[96:99], off offset:256
	v_cvt_pk_bf16_f32 v88, v100, v101
	v_cvt_pk_bf16_f32 v89, v102, v103
	v_cvt_pk_bf16_f32 v90, v92, v93
	v_cvt_pk_bf16_f32 v91, v94, v95
	s_mov_b64 s[30:31], 0x400000
	v_add_co_u32_e32 v94, vcc, s21, v120
	v_lshl_add_u64 v[92:93], v[120:121], 0, s[30:31]
	s_nop 0
	v_addc_co_u32_e32 v95, vcc, 0, v121, vcc
	s_mov_b32 s21, 0x600000
	global_store_dwordx4 v[94:95], v[88:91], off
	v_cvt_pk_bf16_f32 v80, v80, v81
	v_cvt_pk_bf16_f32 v81, v82, v83
	v_cvt_pk_bf16_f32 v82, v72, v73
	v_cvt_pk_bf16_f32 v83, v74, v75
	global_store_dwordx4 v[92:93], v[80:83], off offset:256
	v_cvt_pk_bf16_f32 v72, v84, v85
	v_cvt_pk_bf16_f32 v73, v86, v87
	v_cvt_pk_bf16_f32 v74, v76, v77
	v_cvt_pk_bf16_f32 v75, v78, v79
	s_mov_b64 s[30:31], 0x600000
	v_add_co_u32_e32 v78, vcc, s21, v120
	v_lshl_add_u64 v[76:77], v[120:121], 0, s[30:31]
	s_nop 0
	v_addc_co_u32_e32 v79, vcc, 0, v121, vcc
	global_store_dwordx4 v[78:79], v[72:75], off
	v_cvt_pk_bf16_f32 v68, v68, v69
	v_cvt_pk_bf16_f32 v69, v70, v71
	v_cvt_pk_bf16_f32 v70, v64, v65
	v_cvt_pk_bf16_f32 v71, v66, v67
	global_store_dwordx4 v[76:77], v[68:71], off offset:256
	v_cvt_pk_bf16_f32 v60, v60, v61
	v_cvt_pk_bf16_f32 v61, v62, v63
	v_cvt_pk_bf16_f32 v62, v56, v57
	v_cvt_pk_bf16_f32 v63, v58, v59
	s_mov_b64 s[30:31], 0x1000000
	v_add_co_u32_e32 v58, vcc, s56, v120
; __device__ __forceinline__ unsigned cvt_pk_bf16(float lo, float hi) { unsigned r; asm volatile("v_cvt_pk_bf16_f32 %0, %1, %2" : "=v"(r) : "v"(lo), "v"(hi)); return r; }
;     __device__ __forceinline__ void operator()(const AccT& acc, const Unit& u, int wr, int wc, int fr, int fq) const {
;     ...
; #pragma unroll
;         for (int ai = 0; ai < 2; ++ai)
; #pragma unroll
;             for (int m = 0; m < 4; ++m) {
;                 const int r = rbase + ai * 128 + m * 16;
; #pragma unroll
;                 for (int bj = 0; bj < 2; ++bj) {
;                     const int t0 = tb + bj * 128;
;                     const f32x4 v0 = acc[ai][bj][m][0], v1 = acc[ai][bj][m][1];
;                     u32x4 w; w.x = cvt_pk_bf16(v0[0], v0[1]); w.y = cvt_pk_bf16(v0[2], v0[3]); w.z = cvt_pk_bf16(v1[0], v1[1]); w.w = cvt_pk_bf16(v1[2], v1[3]);
;                     *(u32x4*)(VT + (size_t)r * NT + t0) = w;
;                 }
	v_lshl_add_u64 v[56:57], v[120:121], 0, s[30:31]
	s_nop 0
	v_addc_co_u32_e32 v59, vcc, 0, v121, vcc
	global_store_dwordx4 v[58:59], v[60:63], off
	v_cvt_pk_bf16_f32 v48, v48, v49
	v_cvt_pk_bf16_f32 v49, v50, v51
	v_cvt_pk_bf16_f32 v50, v40, v41
	v_cvt_pk_bf16_f32 v51, v42, v43
	global_store_dwordx4 v[56:57], v[48:51], off offset:256
	v_cvt_pk_bf16_f32 v40, v52, v53
	v_cvt_pk_bf16_f32 v41, v54, v55
	v_cvt_pk_bf16_f32 v42, v44, v45
	v_cvt_pk_bf16_f32 v43, v46, v47
	v_add_co_u32_e32 v46, vcc, s57, v120
	v_lshl_add_u64 v[44:45], v[120:121], 0, s[6:7]
	s_nop 0
	v_addc_co_u32_e32 v47, vcc, 0, v121, vcc
	global_store_dwordx4 v[46:47], v[40:43], off
	v_cvt_pk_bf16_f32 v32, v32, v33
	v_cvt_pk_bf16_f32 v33, v34, v35
	v_cvt_pk_bf16_f32 v34, v24, v25
	v_cvt_pk_bf16_f32 v35, v26, v27
	global_store_dwordx4 v[44:45], v[32:35], off offset:256
	v_cvt_pk_bf16_f32 v24, v36, v37
	v_cvt_pk_bf16_f32 v25, v38, v39
	v_cvt_pk_bf16_f32 v26, v28, v29
	v_cvt_pk_bf16_f32 v27, v30, v31
	v_add_co_u32_e32 v30, vcc, s58, v120
	v_lshl_add_u64 v[28:29], v[120:121], 0, s[8:9]
	s_nop 0
	v_addc_co_u32_e32 v31, vcc, 0, v121, vcc
	global_store_dwordx4 v[30:31], v[24:27], off
	v_cvt_pk_bf16_f32 v16, v16, v17
	v_cvt_pk_bf16_f32 v17, v18, v19
	v_cvt_pk_bf16_f32 v18, v8, v9
	v_cvt_pk_bf16_f32 v19, v10, v11
	global_store_dwordx4 v[28:29], v[16:19], off offset:256
	v_cvt_pk_bf16_f32 v8, v20, v21
	v_cvt_pk_bf16_f32 v9, v22, v23
	v_cvt_pk_bf16_f32 v10, v12, v13
	v_cvt_pk_bf16_f32 v11, v14, v15
	v_add_co_u32_e32 v14, vcc, s59, v120
	v_lshl_add_u64 v[12:13], v[120:121], 0, s[16:17]
	s_nop 0
	v_addc_co_u32_e32 v15, vcc, 0, v121, vcc
	s_and_b64 vcc, exec, s[2:3]
	s_mov_b32 s60, s20
	s_mov_b32 s28, s22
	s_mov_b64 s[34:35], s[26:27]
	s_mov_b64 s[30:31], s[24:25]
	global_store_dwordx4 v[14:15], v[8:11], off
	v_cvt_pk_bf16_f32 v4, v4, v5
	v_cvt_pk_bf16_f32 v5, v6, v7
	v_cvt_pk_bf16_f32 v6, v0, v1
	v_cvt_pk_bf16_f32 v7, v2, v3
	global_store_dwordx4 v[12:13], v[4:7], off offset:256
	s_cbranch_vccz .LBB0_626
	s_branch .Lconc_end_g4
.Lconc_epi1_g4:
	v_mov_b32_e32 v150, v144
	v_mov_b32_e32 v151, v145
	s_lshl_b32 s21, s28, 8
	s_add_i32 s21, s21, s48
	v_add_u32_e32 v150, s21, v150
	s_lshl_b32 s21, s60, 8
	s_or_b32 s21, s21, s49
	v_lshl_add_u32 v152, v151, 3, s21
	v_ashrrev_i32_e32 v151, 31, v150
	v_cvt_pk_bf16_f32 v124, v124, v125
	v_cvt_pk_bf16_f32 v125, v126, v127
	v_cvt_pk_bf16_f32 v126, v120, v121
	v_lshlrev_b64 v[120:121], 17, v[150:151]
	v_lshl_add_u64 v[120:121], s[0:1], 0, v[120:121]
	v_ashrrev_i32_e32 v153, 31, v152
	v_lshl_add_u64 v[120:121], v[152:153], 1, v[120:121]
	s_mov_b32 s21, 0x200000
	v_cvt_pk_bf16_f32 v127, v122, v123
	global_store_dwordx4 v[120:121], v[124:127], off
	v_cvt_pk_bf16_f32 v112, v112, v113
	v_cvt_pk_bf16_f32 v113, v114, v115
	v_cvt_pk_bf16_f32 v114, v104, v105
	v_cvt_pk_bf16_f32 v115, v106, v107
	global_store_dwordx4 v[120:121], v[112:115], off offset:256
	v_cvt_pk_bf16_f32 v104, v116, v117
	v_cvt_pk_bf16_f32 v105, v118, v119
	v_cvt_pk_bf16_f32 v106, v108, v109
	v_cvt_pk_bf16_f32 v107, v110, v111
	s_mov_b64 s[30:31], 0x200000
	v_add_co_u32_e32 v110, vcc, s21, v120
	v_lshl_add_u64 v[108:109], v[120:121], 0, s[30:31]
	s_nop 0
	v_addc_co_u32_e32 v111, vcc, 0, v121, vcc
	s_mov_b32 s21, 0x400000
	global_store_dwordx4 v[110:111], v[104:107], off
	v_cvt_pk_bf16_f32 v96, v96, v97
	v_cvt_pk_bf16_f32 v97, v98, v99
	v_cvt_pk_bf16_f32 v98, v88, v89
	v_cvt_pk_bf16_f32 v99, v90, v91
	global_store_dwordx4 v[108:109], v[96:99], off offset:256
	v_cvt_pk_bf16_f32 v88, v100, v101
	v_cvt_pk_bf16_f32 v89, v102, v103
	v_cvt_pk_bf16_f32 v90, v92, v93
	v_cvt_pk_bf16_f32 v91, v94, v95
	s_mov_b64 s[30:31], 0x400000
	v_add_co_u32_e32 v94, vcc, s21, v120
	v_lshl_add_u64 v[92:93], v[120:121], 0, s[30:31]
	s_nop 0
	v_addc_co_u32_e32 v95, vcc, 0, v121, vcc
	s_mov_b32 s21, 0x600000
	global_store_dwordx4 v[94:95], v[88:91], off
	v_cvt_pk_bf16_f32 v80, v80, v81
	v_cvt_pk_bf16_f32 v81, v82, v83
	v_cvt_pk_bf16_f32 v82, v72, v73
	v_cvt_pk_bf16_f32 v83, v74, v75
	global_store_dwordx4 v[92:93], v[80:83], off offset:256
	v_cvt_pk_bf16_f32 v72, v84, v85
	v_cvt_pk_bf16_f32 v73, v86, v87
	v_cvt_pk_bf16_f32 v74, v76, v77
	v_cvt_pk_bf16_f32 v75, v78, v79
	s_mov_b64 s[30:31], 0x600000
	v_add_co_u32_e32 v78, vcc, s21, v120
	v_lshl_add_u64 v[76:77], v[120:121], 0, s[30:31]
	s_nop 0
	v_addc_co_u32_e32 v79, vcc, 0, v121, vcc
	global_store_dwordx4 v[78:79], v[72:75], off
	v_cvt_pk_bf16_f32 v68, v68, v69
	v_cvt_pk_bf16_f32 v69, v70, v71
	v_cvt_pk_bf16_f32 v70, v64, v65
	v_cvt_pk_bf16_f32 v71, v66, v67
	global_store_dwordx4 v[76:77], v[68:71], off offset:256
	v_cvt_pk_bf16_f32 v60, v60, v61
	v_cvt_pk_bf16_f32 v61, v62, v63
	v_cvt_pk_bf16_f32 v62, v56, v57
	v_cvt_pk_bf16_f32 v63, v58, v59
	s_mov_b64 s[30:31], 0x1000000
	v_add_co_u32_e32 v58, vcc, s56, v120
	v_lshl_add_u64 v[56:57], v[120:121], 0, s[30:31]
	s_nop 0
	v_addc_co_u32_e32 v59, vcc, 0, v121, vcc
	global_store_dwordx4 v[58:59], v[60:63], off
	v_cvt_pk_bf16_f32 v48, v48, v49
	v_cvt_pk_bf16_f32 v49, v50, v51
	v_cvt_pk_bf16_f32 v50, v40, v41
	v_cvt_pk_bf16_f32 v51, v42, v43
	global_store_dwordx4 v[56:57], v[48:51], off offset:256
	v_cvt_pk_bf16_f32 v40, v52, v53
	v_cvt_pk_bf16_f32 v41, v54, v55
	v_cvt_pk_bf16_f32 v42, v44, v45
	v_cvt_pk_bf16_f32 v43, v46, v47
	v_add_co_u32_e32 v46, vcc, s57, v120
	v_lshl_add_u64 v[44:45], v[120:121], 0, s[6:7]
	s_nop 0
	v_addc_co_u32_e32 v47, vcc, 0, v121, vcc
	global_store_dwordx4 v[46:47], v[40:43], off
	v_cvt_pk_bf16_f32 v32, v32, v33
	v_cvt_pk_bf16_f32 v33, v34, v35
	v_cvt_pk_bf16_f32 v34, v24, v25
	v_cvt_pk_bf16_f32 v35, v26, v27
	global_store_dwordx4 v[44:45], v[32:35], off offset:256
	v_cvt_pk_bf16_f32 v24, v36, v37
	v_cvt_pk_bf16_f32 v25, v38, v39
	v_cvt_pk_bf16_f32 v26, v28, v29
	v_cvt_pk_bf16_f32 v27, v30, v31
	v_add_co_u32_e32 v30, vcc, s58, v120
	v_lshl_add_u64 v[28:29], v[120:121], 0, s[8:9]
	s_nop 0
	v_addc_co_u32_e32 v31, vcc, 0, v121, vcc
	global_store_dwordx4 v[30:31], v[24:27], off
	v_cvt_pk_bf16_f32 v16, v16, v17
	v_cvt_pk_bf16_f32 v17, v18, v19
	v_cvt_pk_bf16_f32 v18, v8, v9
	v_cvt_pk_bf16_f32 v19, v10, v11
	global_store_dwordx4 v[28:29], v[16:19], off offset:256
	v_cvt_pk_bf16_f32 v8, v20, v21
	v_cvt_pk_bf16_f32 v9, v22, v23
	v_cvt_pk_bf16_f32 v10, v12, v13
	v_cvt_pk_bf16_f32 v11, v14, v15
	v_add_co_u32_e32 v14, vcc, s59, v120
	v_lshl_add_u64 v[12:13], v[120:121], 0, s[16:17]
	s_nop 0
	v_addc_co_u32_e32 v15, vcc, 0, v121, vcc
	s_and_b64 vcc, exec, s[2:3]
	s_mov_b32 s60, s20
	s_mov_b32 s28, s22
	s_mov_b64 s[34:35], s[26:27]
	s_mov_b64 s[30:31], s[24:25]
	global_store_dwordx4 v[14:15], v[8:11], off
	v_cvt_pk_bf16_f32 v4, v4, v5
	v_cvt_pk_bf16_f32 v5, v6, v7
	v_cvt_pk_bf16_f32 v6, v0, v1
	v_cvt_pk_bf16_f32 v7, v2, v3
	global_store_dwordx4 v[12:13], v[4:7], off offset:256
	s_barrier
	s_cbranch_vccz .LBB0_626

; #define PG8_STAGE(bufoff, gbase, voff) do { _Pragma("unroll") for (int _i = 0; _i < 2; ++_i) \
;         __builtin_amdgcn_global_load_lds((const unsigned*)((const char*)(gbase) + (voff)[_i]), (LAS unsigned*)(lds + (bufoff) + ldsw + _i * 8192), 16, 0, 0); } while (0)
; #define PG8_LDA(dst, b, h) do { _Pragma("unroll") for (int m = 0; m < 4; ++m) _Pragma("unroll") for (int k = 0; k < 2; ++k) dst[m][k] = *(const LAS bf16x8*)(lds + PG8_SA(b, h) + aoff + m * 2048 + k * 1024); } while (0)
; #define PG8_LDB(dst, b, h) do { _Pragma("unroll") for (int n = 0; n < 2; ++n) _Pragma("unroll") for (int k = 0; k < 2; ++k) dst[n][k] = *(const LAS bf16x8*)(lds + PG8_SB(b, h) + boff + n * 2048 + k * 1024); } while (0)
; #define PG8_MMA(ai, bj, At, Bt) do { __builtin_amdgcn_s_setprio(1); _Pragma("unroll") for (int m = 0; m < 4; ++m) _Pragma("unroll") for (int n = 0; n < 2; ++n) _Pragma("unroll") for (int k = 0; k < 2; ++k) \
;         acc[ai][bj][m][n] = __builtin_amdgcn_mfma_f32_16x16x32_bf16(Bt[n][k], At[m][k], acc[ai][bj][m][n], 0, 0, 0); __builtin_amdgcn_s_setprio(0); } while (0)
; #define PG8_WAIT_V(n) asm volatile("s_waitcnt vmcnt(" #n ")" ::: "memory")
; #define PG8_WAIT_L(n) asm volatile("s_waitcnt lgkmcnt(" #n ")" ::: "memory")
; #define PG8_BAR __builtin_amdgcn_s_barrier()
; #define PG8_SCHED __builtin_amdgcn_sched_barrier(0)
; template <class Epi, class Sched>
; __device__ __forceinline__ void gemm_phase(LAS unsigned char* lds, const Gemm g, const Sched& S, const Epi& E) {
;     ...
;             PG8_LDB(B0, 0, 0); PG8_SCHED; PG8_LDA(At, 0, 0); PG8_STAGE(PG8_SA(1, 1), a1 + hstep, voffA);
;             PG8_WAIT_L(8); PG8_BAR; PG8_WAIT_L(0); PG8_MMA(0, 0, At, B0); PG8_BAR; PG8_SCHED;
;             PG8_LDB(B1, 0, 1); PG8_STAGE(PG8_SB(0, 0), b2, voffB);
;             PG8_BAR; PG8_WAIT_L(0); PG8_MMA(0, 1, At, B1); PG8_BAR;
;             PG8_LDA(At, 0, 1); PG8_STAGE(PG8_SA(0, 0), a2, voffA);
;             PG8_BAR; PG8_WAIT_L(0); PG8_MMA(1, 0, At, B0); PG8_BAR; PG8_SCHED;
;             PG8_STAGE(PG8_SB(0, 1), b2 + hstep, voffB);
;             PG8_WAIT_V(6); PG8_BAR; PG8_MMA(1, 1, At, B1); PG8_BAR;
.LBB0_653:
	ds_read_b128 v[152:155], v149
	ds_read_b128 v[156:159], v149 offset:1024
	ds_read_b128 v[160:163], v149 offset:2048
	ds_read_b128 v[164:167], v149 offset:3072
	s_add_u32 s24, s22, 0xfffc0080
	s_addc_u32 s25, s23, -1
	s_cmp_eq_u32 s53, 12
	s_cselect_b32 s27, s9, s25
	s_cselect_b32 s26, s48, s24
	s_cselect_b32 s25, s7, s52
	s_cselect_b32 s24, s49, s51
	s_add_i32 m0, s21, 0xc000
	ds_read_b128 v[168:171], v150
	ds_read_b128 v[172:175], v150 offset:1024
	ds_read_b128 v[176:179], v150 offset:2048
	ds_read_b128 v[180:183], v150 offset:3072
	ds_read_b128 v[184:187], v150 offset:4096
	ds_read_b128 v[188:191], v150 offset:5120
	ds_read_b128 v[192:195], v150 offset:6144
	ds_read_b128 v[196:199], v150 offset:7168
	global_load_lds_dwordx4 v138, s[22:23]
	s_add_i32 m0, s21, 0xe000
	s_nop 0
	global_load_lds_dwordx4 v140, s[22:23]
	s_waitcnt lgkmcnt(8)
	s_waitcnt vmcnt(10)
	s_barrier
	s_waitcnt lgkmcnt(0)
	s_setprio 1
	s_waitcnt lgkmcnt(0)
	v_mfma_f32_16x16x32_bf16 v[124:127], v[152:155], v[168:171], v[124:127]
	v_mfma_f32_16x16x32_bf16 v[120:123], v[160:163], v[168:171], v[120:123]
	v_mfma_f32_16x16x32_bf16 v[112:115], v[152:155], v[176:179], v[112:115]
	v_mfma_f32_16x16x32_bf16 v[104:107], v[160:163], v[176:179], v[104:107]
	v_mfma_f32_16x16x32_bf16 v[96:99], v[152:155], v[184:187], v[96:99]
	v_mfma_f32_16x16x32_bf16 v[88:91], v[160:163], v[184:187], v[88:91]
	v_mfma_f32_16x16x32_bf16 v[80:83], v[152:155], v[192:195], v[80:83]
	v_mfma_f32_16x16x32_bf16 v[72:75], v[160:163], v[192:195], v[72:75]
	v_mfma_f32_16x16x32_bf16 v[124:127], v[156:159], v[172:175], v[124:127]
	v_mfma_f32_16x16x32_bf16 v[120:123], v[164:167], v[172:175], v[120:123]
	v_mfma_f32_16x16x32_bf16 v[112:115], v[156:159], v[180:183], v[112:115]
	v_mfma_f32_16x16x32_bf16 v[104:107], v[164:167], v[180:183], v[104:107]
	v_mfma_f32_16x16x32_bf16 v[96:99], v[156:159], v[188:191], v[96:99]
	v_mfma_f32_16x16x32_bf16 v[88:91], v[164:167], v[188:191], v[88:91]
	v_mfma_f32_16x16x32_bf16 v[80:83], v[156:159], v[196:199], v[80:83]
	v_mfma_f32_16x16x32_bf16 v[72:75], v[164:167], v[196:199], v[72:75]
	s_setprio 0
	s_barrier
	s_add_i32 s54, s45, s30
	s_mov_b32 m0, s54
	ds_read_b128 v[202:205], v151
	ds_read_b128 v[206:209], v151 offset:1024
	ds_read_b128 v[210:213], v151 offset:2048
	ds_read_b128 v[214:217], v151 offset:3072
	global_load_lds_dwordx4 v130, s[24:25]
	s_add_i32 m0, s54, 0x2000
	s_nop 0
	global_load_lds_dwordx4 v134, s[24:25]
	s_waitcnt vmcnt(10)
	s_barrier
	s_waitcnt lgkmcnt(0)
	s_setprio 1
	s_waitcnt lgkmcnt(0)
	v_mfma_f32_16x16x32_bf16 v[116:119], v[202:205], v[168:171], v[116:119]
	v_mfma_f32_16x16x32_bf16 v[108:111], v[210:213], v[168:171], v[108:111]
	v_mfma_f32_16x16x32_bf16 v[100:103], v[202:205], v[176:179], v[100:103]
	v_mfma_f32_16x16x32_bf16 v[92:95], v[210:213], v[176:179], v[92:95]
	v_mfma_f32_16x16x32_bf16 v[84:87], v[202:205], v[184:187], v[84:87]
	v_mfma_f32_16x16x32_bf16 v[76:79], v[210:213], v[184:187], v[76:79]
	v_mfma_f32_16x16x32_bf16 v[68:71], v[202:205], v[192:195], v[68:71]
	v_mfma_f32_16x16x32_bf16 v[64:67], v[210:213], v[192:195], v[64:67]
	v_mfma_f32_16x16x32_bf16 v[116:119], v[206:209], v[172:175], v[116:119]
	v_mfma_f32_16x16x32_bf16 v[108:111], v[214:217], v[172:175], v[108:111]
	v_mfma_f32_16x16x32_bf16 v[100:103], v[206:209], v[180:183], v[100:103]
	v_mfma_f32_16x16x32_bf16 v[92:95], v[214:217], v[180:183], v[92:95]
	v_mfma_f32_16x16x32_bf16 v[84:87], v[206:209], v[188:191], v[84:87]
	v_mfma_f32_16x16x32_bf16 v[76:79], v[214:217], v[188:191], v[76:79]
	v_mfma_f32_16x16x32_bf16 v[68:71], v[206:209], v[196:199], v[68:71]
	v_mfma_f32_16x16x32_bf16 v[64:67], v[214:217], v[196:199], v[64:67]
	s_setprio 0
	s_mov_b32 m0, s21
	v_lshl_add_u64 v[222:223], s[26:27], 0, v[128:129]
	s_barrier
	ds_read_b128 v[168:171], v150 offset:16384
	ds_read_b128 v[172:175], v150 offset:17408
	ds_read_b128 v[176:179], v150 offset:18432
	ds_read_b128 v[180:183], v150 offset:19456
	ds_read_b128 v[184:187], v150 offset:20480
	ds_read_b128 v[188:191], v150 offset:21504
	ds_read_b128 v[192:195], v150 offset:22528
	ds_read_b128 v[196:199], v150 offset:23552
	global_load_lds_dwordx4 v128, s[26:27]
	v_lshl_add_u64 v[224:225], s[26:27], 0, v[132:133]
	s_mov_b32 m0, s31
	s_nop 0
	global_load_lds_dwordx4 v132, s[26:27]
	s_barrier
	s_waitcnt lgkmcnt(0)
	s_setprio 1
	s_waitcnt lgkmcnt(0)
	v_mfma_f32_16x16x32_bf16 v[60:63], v[152:155], v[168:171], v[60:63]
	v_mfma_f32_16x16x32_bf16 v[56:59], v[160:163], v[168:171], v[56:59]
	v_mfma_f32_16x16x32_bf16 v[48:51], v[152:155], v[176:179], v[48:51]
	v_mfma_f32_16x16x32_bf16 v[40:43], v[160:163], v[176:179], v[40:43]
	v_mfma_f32_16x16x32_bf16 v[32:35], v[152:155], v[184:187], v[32:35]
	v_mfma_f32_16x16x32_bf16 v[24:27], v[160:163], v[184:187], v[24:27]
	v_mfma_f32_16x16x32_bf16 v[16:19], v[152:155], v[192:195], v[16:19]
	v_mfma_f32_16x16x32_bf16 v[8:11], v[160:163], v[192:195], v[8:11]
	v_mfma_f32_16x16x32_bf16 v[60:63], v[156:159], v[172:175], v[60:63]
	v_mfma_f32_16x16x32_bf16 v[56:59], v[164:167], v[172:175], v[56:59]
	v_mfma_f32_16x16x32_bf16 v[48:51], v[156:159], v[180:183], v[48:51]
	v_mfma_f32_16x16x32_bf16 v[40:43], v[164:167], v[180:183], v[40:43]
	v_mfma_f32_16x16x32_bf16 v[32:35], v[156:159], v[188:191], v[32:35]
	v_mfma_f32_16x16x32_bf16 v[24:27], v[164:167], v[188:191], v[24:27]
	v_mfma_f32_16x16x32_bf16 v[16:19], v[156:159], v[196:199], v[16:19]
	v_mfma_f32_16x16x32_bf16 v[8:11], v[164:167], v[196:199], v[8:11]
	s_setprio 0
	s_barrier
; #define PG8_STAGE(bufoff, gbase, voff) do { _Pragma("unroll") for (int _i = 0; _i < 2; ++_i) \
;         __builtin_amdgcn_global_load_lds((const unsigned*)((const char*)(gbase) + (voff)[_i]), (LAS unsigned*)(lds + (bufoff) + ldsw + _i * 8192), 16, 0, 0); } while (0)
; #define PG8_LDA(dst, b, h) do { _Pragma("unroll") for (int m = 0; m < 4; ++m) _Pragma("unroll") for (int k = 0; k < 2; ++k) dst[m][k] = *(const LAS bf16x8*)(lds + PG8_SA(b, h) + aoff + m * 2048 + k * 1024); } while (0)
; #define PG8_LDB(dst, b, h) do { _Pragma("unroll") for (int n = 0; n < 2; ++n) _Pragma("unroll") for (int k = 0; k < 2; ++k) dst[n][k] = *(const LAS bf16x8*)(lds + PG8_SB(b, h) + boff + n * 2048 + k * 1024); } while (0)
; #define PG8_MMA(ai, bj, At, Bt) do { __builtin_amdgcn_s_setprio(1); _Pragma("unroll") for (int m = 0; m < 4; ++m) _Pragma("unroll") for (int n = 0; n < 2; ++n) _Pragma("unroll") for (int k = 0; k < 2; ++k) \
;         acc[ai][bj][m][n] = __builtin_amdgcn_mfma_f32_16x16x32_bf16(Bt[n][k], At[m][k], acc[ai][bj][m][n], 0, 0, 0); __builtin_amdgcn_s_setprio(0); } while (0)
; #define PG8_WAIT_V(n) asm volatile("s_waitcnt vmcnt(" #n ")" ::: "memory")
; #define PG8_WAIT_L(n) asm volatile("s_waitcnt lgkmcnt(" #n ")" ::: "memory")
; #define PG8_BAR __builtin_amdgcn_s_barrier()
; #define PG8_SCHED __builtin_amdgcn_sched_barrier(0)
; template <class Epi, class Sched>
; __device__ __forceinline__ void gemm_phase(LAS unsigned char* lds, const Gemm g, const Sched& S, const Epi& E) {
;     ...
;             PG8_STAGE(PG8_SB(0, 1), b2 + hstep, voffB);
;             PG8_WAIT_V(6); PG8_BAR; PG8_MMA(1, 1, At, B1); PG8_BAR;
;             PG8_LDB(B0, 1, 0); PG8_SCHED; PG8_LDA(At, 1, 0); PG8_STAGE(PG8_SA(0, 1), a2 + hstep, voffA);
;             PG8_WAIT_L(8); PG8_BAR; PG8_WAIT_L(0); PG8_MMA(0, 0, At, B0); PG8_BAR; PG8_SCHED;
;             PG8_LDB(B1, 1, 1); PG8_STAGE(PG8_SB(1, 0), b3, voffB);
;             PG8_BAR; PG8_WAIT_L(0); PG8_MMA(0, 1, At, B1); PG8_BAR;
;             PG8_LDA(At, 1, 1); PG8_STAGE(PG8_SA(1, 0), a3, voffA);
;             PG8_BAR; PG8_WAIT_L(0); PG8_MMA(1, 0, At, B0); PG8_BAR; PG8_SCHED;
	s_add_u32 s54, s24, 0x40000
	s_addc_u32 s55, s25, 0
	s_add_i32 s56, s46, s30
	s_mov_b32 m0, s56
	s_nop 0
	global_load_lds_dwordx4 v130, s[54:55]
	s_add_i32 m0, s56, 0x2000
	s_nop 0
	global_load_lds_dwordx4 v134, s[54:55]
	s_add_u32 s26, s26, 0x40000
	s_addc_u32 s27, s27, 0
	s_mov_b32 m0, s33
	s_nop 0
	global_load_lds_dwordx4 v128, s[26:27]
	s_mov_b32 m0, s34
	s_nop 0
	global_load_lds_dwordx4 v132, s[26:27]
	s_waitcnt vmcnt(12)
	s_barrier
	s_setprio 1
	v_mfma_f32_16x16x32_bf16 v[52:55], v[202:205], v[168:171], v[52:55]
	v_mfma_f32_16x16x32_bf16 v[44:47], v[210:213], v[168:171], v[44:47]
	v_mfma_f32_16x16x32_bf16 v[36:39], v[202:205], v[176:179], v[36:39]
	v_mfma_f32_16x16x32_bf16 v[28:31], v[210:213], v[176:179], v[28:31]
	v_mfma_f32_16x16x32_bf16 v[20:23], v[202:205], v[184:187], v[20:23]
	v_mfma_f32_16x16x32_bf16 v[12:15], v[210:213], v[184:187], v[12:15]
	v_mfma_f32_16x16x32_bf16 v[4:7], v[202:205], v[192:195], v[4:7]
	v_mfma_f32_16x16x32_bf16 v[0:3], v[210:213], v[192:195], v[0:3]
	v_mfma_f32_16x16x32_bf16 v[52:55], v[206:209], v[172:175], v[52:55]
	v_mfma_f32_16x16x32_bf16 v[44:47], v[214:217], v[172:175], v[44:47]
	v_mfma_f32_16x16x32_bf16 v[36:39], v[206:209], v[180:183], v[36:39]
	v_mfma_f32_16x16x32_bf16 v[28:31], v[214:217], v[180:183], v[28:31]
	v_mfma_f32_16x16x32_bf16 v[20:23], v[206:209], v[188:191], v[20:23]
	v_mfma_f32_16x16x32_bf16 v[12:15], v[214:217], v[188:191], v[12:15]
	v_mfma_f32_16x16x32_bf16 v[4:7], v[206:209], v[196:199], v[4:7]
	v_mfma_f32_16x16x32_bf16 v[0:3], v[214:217], v[196:199], v[0:3]
	s_setprio 0
	s_add_i32 s54, 0, 0x18000
	v_add_u32_e32 v136, s54, v148
	s_barrier
	ds_read_b128 v[152:155], v136
	ds_read_b128 v[156:159], v136 offset:1024
	ds_read_b128 v[160:163], v136 offset:2048
	ds_read_b128 v[164:167], v136 offset:3072
	ds_read_b128 v[168:171], v150 offset:32768
	ds_read_b128 v[172:175], v150 offset:33792
	ds_read_b128 v[176:179], v150 offset:34816
	ds_read_b128 v[180:183], v150 offset:35840
	ds_read_b128 v[184:187], v150 offset:36864
	ds_read_b128 v[188:191], v150 offset:37888
	ds_read_b128 v[192:195], v150 offset:38912
	ds_read_b128 v[196:199], v150 offset:39936
	s_waitcnt lgkmcnt(8)
	s_waitcnt vmcnt(10)
	s_barrier
	s_waitcnt lgkmcnt(0)
	s_setprio 1
	s_waitcnt lgkmcnt(0)
	v_mfma_f32_16x16x32_bf16 v[124:127], v[152:155], v[168:171], v[124:127]
	v_mfma_f32_16x16x32_bf16 v[120:123], v[160:163], v[168:171], v[120:123]
	v_mfma_f32_16x16x32_bf16 v[112:115], v[152:155], v[176:179], v[112:115]
	v_mfma_f32_16x16x32_bf16 v[104:107], v[160:163], v[176:179], v[104:107]
	v_mfma_f32_16x16x32_bf16 v[96:99], v[152:155], v[184:187], v[96:99]
	v_mfma_f32_16x16x32_bf16 v[88:91], v[160:163], v[184:187], v[88:91]
	v_mfma_f32_16x16x32_bf16 v[80:83], v[152:155], v[192:195], v[80:83]
	v_mfma_f32_16x16x32_bf16 v[72:75], v[160:163], v[192:195], v[72:75]
	v_mfma_f32_16x16x32_bf16 v[124:127], v[156:159], v[172:175], v[124:127]
	v_mfma_f32_16x16x32_bf16 v[120:123], v[164:167], v[172:175], v[120:123]
	v_mfma_f32_16x16x32_bf16 v[112:115], v[156:159], v[180:183], v[112:115]
	v_mfma_f32_16x16x32_bf16 v[104:107], v[164:167], v[180:183], v[104:107]
	v_mfma_f32_16x16x32_bf16 v[96:99], v[156:159], v[188:191], v[96:99]
	v_mfma_f32_16x16x32_bf16 v[88:91], v[164:167], v[188:191], v[88:91]
	v_mfma_f32_16x16x32_bf16 v[80:83], v[156:159], v[196:199], v[80:83]
	v_mfma_f32_16x16x32_bf16 v[72:75], v[164:167], v[196:199], v[72:75]
	s_setprio 0
	s_barrier
	s_add_i32 s26, 0, 0x1c000
	s_add_i32 s27, s54, s30
	v_add_u32_e32 v136, s26, v148
	s_add_u32 s0, s24, 0x80
	s_addc_u32 s1, s25, 0
	s_mov_b32 m0, s27
	ds_read_b128 v[202:205], v136
	ds_read_b128 v[206:209], v136 offset:1024
	ds_read_b128 v[210:213], v136 offset:2048
	ds_read_b128 v[214:217], v136 offset:3072
	global_load_lds_dwordx4 v130, s[0:1]
	s_add_i32 m0, s27, 0x2000
	s_nop 0
	global_load_lds_dwordx4 v134, s[0:1]
	s_waitcnt vmcnt(10)
	s_barrier
	s_waitcnt lgkmcnt(0)
	s_setprio 1
	s_waitcnt lgkmcnt(0)
	v_mfma_f32_16x16x32_bf16 v[116:119], v[202:205], v[168:171], v[116:119]
	v_mfma_f32_16x16x32_bf16 v[108:111], v[210:213], v[168:171], v[108:111]
	v_mfma_f32_16x16x32_bf16 v[100:103], v[202:205], v[176:179], v[100:103]
	v_mfma_f32_16x16x32_bf16 v[92:95], v[210:213], v[176:179], v[92:95]
	v_mfma_f32_16x16x32_bf16 v[84:87], v[202:205], v[184:187], v[84:87]
	v_mfma_f32_16x16x32_bf16 v[76:79], v[210:213], v[184:187], v[76:79]
	v_mfma_f32_16x16x32_bf16 v[68:71], v[202:205], v[192:195], v[68:71]
	v_mfma_f32_16x16x32_bf16 v[64:67], v[210:213], v[192:195], v[64:67]
	v_mfma_f32_16x16x32_bf16 v[116:119], v[206:209], v[172:175], v[116:119]
	v_mfma_f32_16x16x32_bf16 v[108:111], v[214:217], v[172:175], v[108:111]
	v_mfma_f32_16x16x32_bf16 v[100:103], v[206:209], v[180:183], v[100:103]
	v_mfma_f32_16x16x32_bf16 v[92:95], v[214:217], v[180:183], v[92:95]
	v_mfma_f32_16x16x32_bf16 v[84:87], v[206:209], v[188:191], v[84:87]
	v_mfma_f32_16x16x32_bf16 v[76:79], v[214:217], v[188:191], v[76:79]
	v_mfma_f32_16x16x32_bf16 v[68:71], v[206:209], v[196:199], v[68:71]
	v_mfma_f32_16x16x32_bf16 v[64:67], v[214:217], v[196:199], v[64:67]
	s_setprio 0
	s_mov_b32 m0, s42
	s_mov_b64 s[0:1], 0x80
	v_lshl_add_u64 v[218:219], v[222:223], 0, s[0:1]
	s_barrier
	ds_read_b128 v[168:171], v150 offset:49152
	ds_read_b128 v[172:175], v150 offset:50176
	ds_read_b128 v[176:179], v150 offset:51200
	ds_read_b128 v[180:183], v150 offset:52224
	ds_read_b128 v[184:187], v150 offset:53248
	ds_read_b128 v[188:191], v150 offset:54272
	ds_read_b128 v[192:195], v150 offset:55296
	ds_read_b128 v[196:199], v150 offset:56320
	global_load_lds_dwordx4 v[218:219], off
	v_lshl_add_u64 v[218:219], v[224:225], 0, s[0:1]
	s_mov_b32 m0, s43
	s_nop 0
	global_load_lds_dwordx4 v[218:219], off
	s_barrier
; __device__ __forceinline__ unsigned cvt_pk_bf16(float lo, float hi) { unsigned r; asm volatile("v_cvt_pk_bf16_f32 %0, %1, %2" : "=v"(r) : "v"(lo), "v"(hi)); return r; }
; #define PG8_STAGE(bufoff, gbase, voff) do { _Pragma("unroll") for (int _i = 0; _i < 2; ++_i) \
;         __builtin_amdgcn_global_load_lds((const unsigned*)((const char*)(gbase) + (voff)[_i]), (LAS unsigned*)(lds + (bufoff) + ldsw + _i * 8192), 16, 0, 0); } while (0)
; #define PG8_MMA(ai, bj, At, Bt) do { __builtin_amdgcn_s_setprio(1); _Pragma("unroll") for (int m = 0; m < 4; ++m) _Pragma("unroll") for (int n = 0; n < 2; ++n) _Pragma("unroll") for (int k = 0; k < 2; ++k) \
;         acc[ai][bj][m][n] = __builtin_amdgcn_mfma_f32_16x16x32_bf16(Bt[n][k], At[m][k], acc[ai][bj][m][n], 0, 0, 0); __builtin_amdgcn_s_setprio(0); } while (0)
; #define PG8_WAIT_V(n) asm volatile("s_waitcnt vmcnt(" #n ")" ::: "memory")
; #define PG8_WAIT_L(n) asm volatile("s_waitcnt lgkmcnt(" #n ")" ::: "memory")
; #define PG8_BAR __builtin_amdgcn_s_barrier()
; #define PG8_SCHED __builtin_amdgcn_sched_barrier(0)
; template <class Epi, class Sched>
; __device__ __forceinline__ void gemm_phase(LAS unsigned char* lds, const Gemm g, const Sched& S, const Epi& E) {
;     ...
;             PG8_BAR; PG8_WAIT_L(0); PG8_MMA(1, 0, At, B0); PG8_BAR; PG8_SCHED;
;             PG8_STAGE(PG8_SB(1, 1), b3 + hstep, voffB);
;             PG8_WAIT_V(6); PG8_BAR; PG8_MMA(1, 1, At, B1); PG8_BAR;
;     __device__ __forceinline__ void operator()(const AccT& acc, const Unit& u, int wr, int wc, int fr, int fq) const {
;     ...
; #pragma unroll
;         for (int ai = 0; ai < 2; ++ai)
; #pragma unroll
;             for (int m = 0; m < 4; ++m) {
;                 const int gm = rbase + ai * 128 + m * 16;
; #pragma unroll
;                 for (int bj = 0; bj < 2; ++bj) {
;                     const int t0 = tb + bj * 128;
;                     const f32x4 v0 = acc[ai][bj][m][0], v1 = acc[ai][bj][m][1];
;                     u32x4 w; w.x = cvt_pk_bf16(v0[0], v0[1]); w.y = cvt_pk_bf16(v0[2], v0[3]); w.z = cvt_pk_bf16(v1[0], v1[1]); w.w = cvt_pk_bf16(v1[2], v1[3]);
;                     *(u32x4*)(YT + ((size_t)((t0 >> 10) * 512 + gm)) * 2048 + part * 1024 + (t0 & 1023)) = w;
;                 }
	s_waitcnt lgkmcnt(0)
	s_setprio 1
	s_waitcnt lgkmcnt(0)
	v_mfma_f32_16x16x32_bf16 v[60:63], v[152:155], v[168:171], v[60:63]
	v_mfma_f32_16x16x32_bf16 v[56:59], v[160:163], v[168:171], v[56:59]
	v_mfma_f32_16x16x32_bf16 v[48:51], v[152:155], v[176:179], v[48:51]
	v_mfma_f32_16x16x32_bf16 v[40:43], v[160:163], v[176:179], v[40:43]
	v_mfma_f32_16x16x32_bf16 v[32:35], v[152:155], v[184:187], v[32:35]
	v_mfma_f32_16x16x32_bf16 v[24:27], v[160:163], v[184:187], v[24:27]
	v_mfma_f32_16x16x32_bf16 v[16:19], v[152:155], v[192:195], v[16:19]
	v_mfma_f32_16x16x32_bf16 v[8:11], v[160:163], v[192:195], v[8:11]
	v_mfma_f32_16x16x32_bf16 v[60:63], v[156:159], v[172:175], v[60:63]
	v_mfma_f32_16x16x32_bf16 v[56:59], v[164:167], v[172:175], v[56:59]
	v_mfma_f32_16x16x32_bf16 v[48:51], v[156:159], v[180:183], v[48:51]
	v_mfma_f32_16x16x32_bf16 v[40:43], v[164:167], v[180:183], v[40:43]
	v_mfma_f32_16x16x32_bf16 v[32:35], v[156:159], v[188:191], v[32:35]
	v_mfma_f32_16x16x32_bf16 v[24:27], v[164:167], v[188:191], v[24:27]
	v_mfma_f32_16x16x32_bf16 v[16:19], v[156:159], v[196:199], v[16:19]
	v_mfma_f32_16x16x32_bf16 v[8:11], v[164:167], v[196:199], v[8:11]
	s_setprio 0
	s_barrier
	s_add_u32 s24, s24, 0x40080
	s_addc_u32 s25, s25, 0
	s_add_i32 s26, s26, s30
	s_mov_b32 m0, s26
	s_nop 0
	global_load_lds_dwordx4 v130, s[24:25]
	s_add_i32 m0, s26, 0x2000
	s_nop 0
	global_load_lds_dwordx4 v134, s[24:25]
	s_waitcnt vmcnt(10)
	s_barrier
	s_setprio 1
	v_mfma_f32_16x16x32_bf16 v[52:55], v[202:205], v[168:171], v[52:55]
	v_mfma_f32_16x16x32_bf16 v[44:47], v[210:213], v[168:171], v[44:47]
	v_mfma_f32_16x16x32_bf16 v[36:39], v[202:205], v[176:179], v[36:39]
	v_mfma_f32_16x16x32_bf16 v[28:31], v[210:213], v[176:179], v[28:31]
	v_mfma_f32_16x16x32_bf16 v[20:23], v[202:205], v[184:187], v[20:23]
	v_mfma_f32_16x16x32_bf16 v[12:15], v[210:213], v[184:187], v[12:15]
	v_mfma_f32_16x16x32_bf16 v[4:7], v[202:205], v[192:195], v[4:7]
	v_mfma_f32_16x16x32_bf16 v[0:3], v[210:213], v[192:195], v[0:3]
	v_mfma_f32_16x16x32_bf16 v[52:55], v[206:209], v[172:175], v[52:55]
	v_mfma_f32_16x16x32_bf16 v[44:47], v[214:217], v[172:175], v[44:47]
	v_mfma_f32_16x16x32_bf16 v[36:39], v[206:209], v[180:183], v[36:39]
	v_mfma_f32_16x16x32_bf16 v[28:31], v[214:217], v[180:183], v[28:31]
	v_mfma_f32_16x16x32_bf16 v[20:23], v[206:209], v[188:191], v[20:23]
	v_mfma_f32_16x16x32_bf16 v[12:15], v[214:217], v[188:191], v[12:15]
	v_mfma_f32_16x16x32_bf16 v[4:7], v[206:209], v[196:199], v[4:7]
	v_mfma_f32_16x16x32_bf16 v[0:3], v[214:217], v[196:199], v[0:3]
	s_setprio 0
	s_add_i32 s53, s53, 2
	s_add_u32 s22, s22, 0x100
	s_addc_u32 s23, s23, 0
	s_add_u32 s51, s51, 0x100
	s_addc_u32 s52, s52, 0
	s_cmp_gt_u32 s53, 13
	s_cbranch_scc1 .Lconc_last_g5
	s_barrier
	s_branch .LBB0_653
.Lconc_last_g5:
	v_readfirstlane_b32 s7, v200
	s_nop 3
	s_cmp_gt_u32 s7, 0xff
	s_cbranch_scc1 .Lconc_epi1_g5
	s_barrier
	v_mov_b32_e32 v136, v147
	v_mov_b32_e32 v152, v146
	s_lshl_b32 s7, s20, 8
	s_add_i32 s7, s7, s36
	v_add_u32_e32 v152, s7, v152
	s_lshl_b32 s7, s47, 8
	s_or_b32 s7, s7, s37
	v_lshl_add_u32 v153, v136, 3, s7
	v_cvt_pk_bf16_f32 v124, v124, v125
	v_cvt_pk_bf16_f32 v125, v126, v127
	v_cvt_pk_bf16_f32 v126, v120, v121
	v_ashrrev_i32_e32 v120, 1, v153
	v_cvt_pk_bf16_f32 v127, v122, v123
	v_and_b32_e32 v122, 0xfffffe00, v120
	v_add_u32_e32 v120, v122, v152
	v_ashrrev_i32_e32 v121, 31, v120
	v_lshlrev_b64 v[120:121], 12, v[120:121]
	v_and_b32_e32 v123, 0x3f8, v153
	v_lshl_add_u64 v[120:121], s[68:69], 0, v[120:121]
	v_lshlrev_b32_e32 v136, 1, v123
	v_lshl_add_u64 v[120:121], v[120:121], 0, v[136:137]
	global_store_dwordx4 v[120:121], v[124:127], off
	v_add_u32_e32 v120, 0x80, v153
	v_cvt_pk_bf16_f32 v116, v116, v117
	v_cvt_pk_bf16_f32 v117, v118, v119
	v_cvt_pk_bf16_f32 v118, v108, v109
	v_ashrrev_i32_e32 v108, 1, v120
	v_and_b32_e32 v121, 0xfffffe00, v108
	v_add_u32_e32 v108, v121, v152
	v_ashrrev_i32_e32 v109, 31, v108
	v_lshlrev_b64 v[108:109], 12, v[108:109]
	v_cvt_pk_bf16_f32 v119, v110, v111
	v_lshl_add_u64 v[110:111], s[68:69], 0, v[108:109]
	v_and_b32_e32 v108, 0x3f8, v120
	v_lshlrev_b32_e32 v108, 1, v108
	v_mov_b32_e32 v109, v137
	v_lshl_add_u64 v[110:111], v[110:111], 0, v[108:109]
	global_store_dwordx4 v[110:111], v[116:119], off
	v_cvt_pk_bf16_f32 v110, v112, v113
	v_cvt_pk_bf16_f32 v111, v114, v115
	v_cvt_pk_bf16_f32 v112, v104, v105
	v_cvt_pk_bf16_f32 v113, v106, v107
	s_and_b64 vcc, exec, s[4:5]
	s_nop 0
	v_add_u32_e32 v116, 16, v152
	v_add_u32_e32 v104, v122, v116
	v_ashrrev_i32_e32 v105, 31, v104
	v_lshlrev_b64 v[104:105], 12, v[104:105]
	v_lshl_add_u64 v[104:105], s[68:69], 0, v[104:105]
	v_lshl_add_u64 v[104:105], v[104:105], 0, v[136:137]
	global_store_dwordx4 v[104:105], v[110:113], off
	v_cvt_pk_bf16_f32 v100, v100, v101
	v_cvt_pk_bf16_f32 v101, v102, v103
	v_cvt_pk_bf16_f32 v102, v92, v93
	v_add_u32_e32 v92, v121, v116
	v_ashrrev_i32_e32 v93, 31, v92
	v_lshlrev_b64 v[92:93], 12, v[92:93]
	v_lshl_add_u64 v[92:93], s[68:69], 0, v[92:93]
	v_lshl_add_u64 v[92:93], v[92:93], 0, v[108:109]
	v_cvt_pk_bf16_f32 v103, v94, v95
	global_store_dwordx4 v[92:93], v[100:103], off
	v_cvt_pk_bf16_f32 v92, v96, v97
	v_cvt_pk_bf16_f32 v93, v98, v99
	v_cvt_pk_bf16_f32 v94, v88, v89
	v_cvt_pk_bf16_f32 v95, v90, v91
	s_mov_b32 s47, s6
	s_nop 0
	v_add_u32_e32 v100, 32, v152
	v_add_u32_e32 v88, v122, v100
	v_ashrrev_i32_e32 v89, 31, v88
	v_lshlrev_b64 v[88:89], 12, v[88:89]
	v_lshl_add_u64 v[88:89], s[68:69], 0, v[88:89]
	v_lshl_add_u64 v[88:89], v[88:89], 0, v[136:137]
	global_store_dwordx4 v[88:89], v[92:95], off
	v_cvt_pk_bf16_f32 v84, v84, v85
	v_cvt_pk_bf16_f32 v85, v86, v87
	v_cvt_pk_bf16_f32 v86, v76, v77
; __device__ __forceinline__ unsigned cvt_pk_bf16(float lo, float hi) { unsigned r; asm volatile("v_cvt_pk_bf16_f32 %0, %1, %2" : "=v"(r) : "v"(lo), "v"(hi)); return r; }
;     __device__ __forceinline__ void operator()(const AccT& acc, const Unit& u, int wr, int wc, int fr, int fq) const {
;     ...
; #pragma unroll
;         for (int ai = 0; ai < 2; ++ai)
; #pragma unroll
;             for (int m = 0; m < 4; ++m) {
;                 const int gm = rbase + ai * 128 + m * 16;
; #pragma unroll
;                 for (int bj = 0; bj < 2; ++bj) {
;                     const int t0 = tb + bj * 128;
;                     const f32x4 v0 = acc[ai][bj][m][0], v1 = acc[ai][bj][m][1];
;                     u32x4 w; w.x = cvt_pk_bf16(v0[0], v0[1]); w.y = cvt_pk_bf16(v0[2], v0[3]); w.z = cvt_pk_bf16(v1[0], v1[1]); w.w = cvt_pk_bf16(v1[2], v1[3]);
;                     *(u32x4*)(YT + ((size_t)((t0 >> 10) * 512 + gm)) * 2048 + part * 1024 + (t0 & 1023)) = w;
;                 }
	v_add_u32_e32 v76, v121, v100
	v_ashrrev_i32_e32 v77, 31, v76
	v_lshlrev_b64 v[76:77], 12, v[76:77]
	v_lshl_add_u64 v[76:77], s[68:69], 0, v[76:77]
	v_lshl_add_u64 v[76:77], v[76:77], 0, v[108:109]
	v_cvt_pk_bf16_f32 v87, v78, v79
	global_store_dwordx4 v[76:77], v[84:87], off
	v_cvt_pk_bf16_f32 v76, v80, v81
	v_cvt_pk_bf16_f32 v77, v82, v83
	v_cvt_pk_bf16_f32 v78, v72, v73
	v_cvt_pk_bf16_f32 v79, v74, v75
	s_mov_b32 s20, s8
	s_nop 0
	v_add_u32_e32 v84, 48, v152
	v_add_u32_e32 v72, v122, v84
	v_ashrrev_i32_e32 v73, 31, v72
	v_lshlrev_b64 v[72:73], 12, v[72:73]
	v_lshl_add_u64 v[72:73], s[68:69], 0, v[72:73]
	v_lshl_add_u64 v[72:73], v[72:73], 0, v[136:137]
	global_store_dwordx4 v[72:73], v[76:79], off
	v_cvt_pk_bf16_f32 v68, v68, v69
	v_cvt_pk_bf16_f32 v69, v70, v71
	v_cvt_pk_bf16_f32 v70, v64, v65
	v_add_u32_e32 v64, v121, v84
	v_ashrrev_i32_e32 v65, 31, v64
	v_lshlrev_b64 v[64:65], 12, v[64:65]
	v_lshl_add_u64 v[64:65], s[68:69], 0, v[64:65]
	v_lshl_add_u64 v[64:65], v[64:65], 0, v[108:109]
	v_cvt_pk_bf16_f32 v71, v66, v67
	global_store_dwordx4 v[64:65], v[68:71], off
	v_add_u32_e32 v64, 0x80, v152
	v_cvt_pk_bf16_f32 v60, v60, v61
	v_cvt_pk_bf16_f32 v61, v62, v63
	v_cvt_pk_bf16_f32 v62, v56, v57
	v_add_u32_e32 v56, v122, v64
	v_ashrrev_i32_e32 v57, 31, v56
	v_lshlrev_b64 v[56:57], 12, v[56:57]
	v_lshl_add_u64 v[56:57], s[68:69], 0, v[56:57]
	v_lshl_add_u64 v[56:57], v[56:57], 0, v[136:137]
	v_cvt_pk_bf16_f32 v63, v58, v59
	global_store_dwordx4 v[56:57], v[60:63], off
	v_cvt_pk_bf16_f32 v52, v52, v53
	v_cvt_pk_bf16_f32 v53, v54, v55
	v_cvt_pk_bf16_f32 v54, v44, v45
	v_add_u32_e32 v44, v121, v64
	v_ashrrev_i32_e32 v45, 31, v44
	v_lshlrev_b64 v[44:45], 12, v[44:45]
	v_lshl_add_u64 v[44:45], s[68:69], 0, v[44:45]
	v_lshl_add_u64 v[44:45], v[44:45], 0, v[108:109]
	v_cvt_pk_bf16_f32 v55, v46, v47
	global_store_dwordx4 v[44:45], v[52:55], off
	v_cvt_pk_bf16_f32 v44, v48, v49
	v_cvt_pk_bf16_f32 v45, v50, v51
	v_cvt_pk_bf16_f32 v46, v40, v41
	v_cvt_pk_bf16_f32 v47, v42, v43
	s_mov_b64 s[24:25], s[18:19]
	s_nop 0
	v_add_u32_e32 v52, 0x90, v152
	v_add_u32_e32 v40, v122, v52
	v_ashrrev_i32_e32 v41, 31, v40
	v_lshlrev_b64 v[40:41], 12, v[40:41]
	v_lshl_add_u64 v[40:41], s[68:69], 0, v[40:41]
	v_lshl_add_u64 v[40:41], v[40:41], 0, v[136:137]
	global_store_dwordx4 v[40:41], v[44:47], off
	v_cvt_pk_bf16_f32 v36, v36, v37
	v_cvt_pk_bf16_f32 v37, v38, v39
	v_cvt_pk_bf16_f32 v38, v28, v29
	v_add_u32_e32 v28, v121, v52
	v_ashrrev_i32_e32 v29, 31, v28
	v_lshlrev_b64 v[28:29], 12, v[28:29]
	v_lshl_add_u64 v[28:29], s[68:69], 0, v[28:29]
	v_lshl_add_u64 v[28:29], v[28:29], 0, v[108:109]
	v_cvt_pk_bf16_f32 v39, v30, v31
	global_store_dwordx4 v[28:29], v[36:39], off
	v_cvt_pk_bf16_f32 v28, v32, v33
	v_cvt_pk_bf16_f32 v29, v34, v35
	v_cvt_pk_bf16_f32 v30, v24, v25
	v_cvt_pk_bf16_f32 v31, v26, v27
	s_mov_b64 s[22:23], s[16:17]
	s_nop 0
	v_add_u32_e32 v36, 0xa0, v152
	v_add_u32_e32 v24, v122, v36
	v_ashrrev_i32_e32 v25, 31, v24
	v_lshlrev_b64 v[24:25], 12, v[24:25]
	v_lshl_add_u64 v[24:25], s[68:69], 0, v[24:25]
	v_lshl_add_u64 v[24:25], v[24:25], 0, v[136:137]
	global_store_dwordx4 v[24:25], v[28:31], off
	v_cvt_pk_bf16_f32 v20, v20, v21
	v_cvt_pk_bf16_f32 v21, v22, v23
	v_cvt_pk_bf16_f32 v22, v12, v13
	v_add_u32_e32 v12, v121, v36
	v_ashrrev_i32_e32 v13, 31, v12
	v_lshlrev_b64 v[12:13], 12, v[12:13]
	v_lshl_add_u64 v[12:13], s[68:69], 0, v[12:13]
	v_lshl_add_u64 v[12:13], v[12:13], 0, v[108:109]
	v_cvt_pk_bf16_f32 v23, v14, v15
	global_store_dwordx4 v[12:13], v[20:23], off
	v_cvt_pk_bf16_f32 v12, v16, v17
	v_cvt_pk_bf16_f32 v13, v18, v19
	v_cvt_pk_bf16_f32 v14, v8, v9
	v_cvt_pk_bf16_f32 v15, v10, v11
	s_nop 1
	v_add_u32_e32 v20, 0xb0, v152
	v_add_u32_e32 v8, v122, v20
	v_ashrrev_i32_e32 v9, 31, v8
	v_lshlrev_b64 v[8:9], 12, v[8:9]
	v_lshl_add_u64 v[8:9], s[68:69], 0, v[8:9]
	v_lshl_add_u64 v[8:9], v[8:9], 0, v[136:137]
	global_store_dwordx4 v[8:9], v[12:15], off
	v_cvt_pk_bf16_f32 v4, v4, v5
	v_cvt_pk_bf16_f32 v5, v6, v7
	v_cvt_pk_bf16_f32 v6, v0, v1
	v_add_u32_e32 v0, v121, v20
	v_ashrrev_i32_e32 v1, 31, v0
	v_lshlrev_b64 v[0:1], 12, v[0:1]
	v_lshl_add_u64 v[0:1], s[68:69], 0, v[0:1]
	v_lshl_add_u64 v[0:1], v[0:1], 0, v[108:109]
	v_cvt_pk_bf16_f32 v7, v2, v3
	global_store_dwordx4 v[0:1], v[4:7], off
	s_cbranch_vccz .LBB0_646
	s_branch .Lconc_end_g5
; __device__ __forceinline__ unsigned cvt_pk_bf16(float lo, float hi) { unsigned r; asm volatile("v_cvt_pk_bf16_f32 %0, %1, %2" : "=v"(r) : "v"(lo), "v"(hi)); return r; }
;     __device__ __forceinline__ void operator()(const AccT& acc, const Unit& u, int wr, int wc, int fr, int fq) const {
;     ...
; #pragma unroll
;         for (int ai = 0; ai < 2; ++ai)
; #pragma unroll
;             for (int m = 0; m < 4; ++m) {
;                 const int gm = rbase + ai * 128 + m * 16;
; #pragma unroll
;                 for (int bj = 0; bj < 2; ++bj) {
;                     const int t0 = tb + bj * 128;
;                     const f32x4 v0 = acc[ai][bj][m][0], v1 = acc[ai][bj][m][1];
;                     u32x4 w; w.x = cvt_pk_bf16(v0[0], v0[1]); w.y = cvt_pk_bf16(v0[2], v0[3]); w.z = cvt_pk_bf16(v1[0], v1[1]); w.w = cvt_pk_bf16(v1[2], v1[3]);
;                     *(u32x4*)(YT + ((size_t)((t0 >> 10) * 512 + gm)) * 2048 + part * 1024 + (t0 & 1023)) = w;
;                 }
.Lconc_epi1_g5:
	v_mov_b32_e32 v136, v147
	v_mov_b32_e32 v152, v146
	s_lshl_b32 s7, s20, 8
	s_add_i32 s7, s7, s36
	v_add_u32_e32 v152, s7, v152
	s_lshl_b32 s7, s47, 8
	s_or_b32 s7, s7, s37
	v_lshl_add_u32 v153, v136, 3, s7
	v_cvt_pk_bf16_f32 v124, v124, v125
	v_cvt_pk_bf16_f32 v125, v126, v127
	v_cvt_pk_bf16_f32 v126, v120, v121
	v_ashrrev_i32_e32 v120, 1, v153
	v_cvt_pk_bf16_f32 v127, v122, v123
	v_and_b32_e32 v122, 0xfffffe00, v120
	v_add_u32_e32 v120, v122, v152
	v_ashrrev_i32_e32 v121, 31, v120
	v_lshlrev_b64 v[120:121], 12, v[120:121]
	v_and_b32_e32 v123, 0x3f8, v153
	v_lshl_add_u64 v[120:121], s[68:69], 0, v[120:121]
	v_lshlrev_b32_e32 v136, 1, v123
	v_lshl_add_u64 v[120:121], v[120:121], 0, v[136:137]
	global_store_dwordx4 v[120:121], v[124:127], off
	v_add_u32_e32 v120, 0x80, v153
	v_cvt_pk_bf16_f32 v116, v116, v117
	v_cvt_pk_bf16_f32 v117, v118, v119
	v_cvt_pk_bf16_f32 v118, v108, v109
	v_ashrrev_i32_e32 v108, 1, v120
	v_and_b32_e32 v121, 0xfffffe00, v108
	v_add_u32_e32 v108, v121, v152
	v_ashrrev_i32_e32 v109, 31, v108
	v_lshlrev_b64 v[108:109], 12, v[108:109]
	v_cvt_pk_bf16_f32 v119, v110, v111
	v_lshl_add_u64 v[110:111], s[68:69], 0, v[108:109]
	v_and_b32_e32 v108, 0x3f8, v120
	v_lshlrev_b32_e32 v108, 1, v108
	v_mov_b32_e32 v109, v137
	v_lshl_add_u64 v[110:111], v[110:111], 0, v[108:109]
	global_store_dwordx4 v[110:111], v[116:119], off
	v_cvt_pk_bf16_f32 v110, v112, v113
	v_cvt_pk_bf16_f32 v111, v114, v115
	v_cvt_pk_bf16_f32 v112, v104, v105
	v_cvt_pk_bf16_f32 v113, v106, v107
	s_and_b64 vcc, exec, s[4:5]
	s_nop 0
	v_add_u32_e32 v116, 16, v152
	v_add_u32_e32 v104, v122, v116
	v_ashrrev_i32_e32 v105, 31, v104
	v_lshlrev_b64 v[104:105], 12, v[104:105]
	v_lshl_add_u64 v[104:105], s[68:69], 0, v[104:105]
	v_lshl_add_u64 v[104:105], v[104:105], 0, v[136:137]
	global_store_dwordx4 v[104:105], v[110:113], off
	v_cvt_pk_bf16_f32 v100, v100, v101
	v_cvt_pk_bf16_f32 v101, v102, v103
	v_cvt_pk_bf16_f32 v102, v92, v93
	v_add_u32_e32 v92, v121, v116
	v_ashrrev_i32_e32 v93, 31, v92
	v_lshlrev_b64 v[92:93], 12, v[92:93]
	v_lshl_add_u64 v[92:93], s[68:69], 0, v[92:93]
	v_lshl_add_u64 v[92:93], v[92:93], 0, v[108:109]
	v_cvt_pk_bf16_f32 v103, v94, v95
	global_store_dwordx4 v[92:93], v[100:103], off
	v_cvt_pk_bf16_f32 v92, v96, v97
	v_cvt_pk_bf16_f32 v93, v98, v99
	v_cvt_pk_bf16_f32 v94, v88, v89
	v_cvt_pk_bf16_f32 v95, v90, v91
	s_mov_b32 s47, s6
	s_nop 0
	v_add_u32_e32 v100, 32, v152
	v_add_u32_e32 v88, v122, v100
	v_ashrrev_i32_e32 v89, 31, v88
	v_lshlrev_b64 v[88:89], 12, v[88:89]
	v_lshl_add_u64 v[88:89], s[68:69], 0, v[88:89]
	v_lshl_add_u64 v[88:89], v[88:89], 0, v[136:137]
	global_store_dwordx4 v[88:89], v[92:95], off
	v_cvt_pk_bf16_f32 v84, v84, v85
	v_cvt_pk_bf16_f32 v85, v86, v87
	v_cvt_pk_bf16_f32 v86, v76, v77
	v_add_u32_e32 v76, v121, v100
	v_ashrrev_i32_e32 v77, 31, v76
	v_lshlrev_b64 v[76:77], 12, v[76:77]
	v_lshl_add_u64 v[76:77], s[68:69], 0, v[76:77]
	v_lshl_add_u64 v[76:77], v[76:77], 0, v[108:109]
	v_cvt_pk_bf16_f32 v87, v78, v79
	global_store_dwordx4 v[76:77], v[84:87], off
	v_cvt_pk_bf16_f32 v76, v80, v81
	v_cvt_pk_bf16_f32 v77, v82, v83
	v_cvt_pk_bf16_f32 v78, v72, v73
	v_cvt_pk_bf16_f32 v79, v74, v75
	s_mov_b32 s20, s8
	s_nop 0
	v_add_u32_e32 v84, 48, v152
	v_add_u32_e32 v72, v122, v84
	v_ashrrev_i32_e32 v73, 31, v72
	v_lshlrev_b64 v[72:73], 12, v[72:73]
	v_lshl_add_u64 v[72:73], s[68:69], 0, v[72:73]
	v_lshl_add_u64 v[72:73], v[72:73], 0, v[136:137]
	global_store_dwordx4 v[72:73], v[76:79], off
	v_cvt_pk_bf16_f32 v68, v68, v69
	v_cvt_pk_bf16_f32 v69, v70, v71
	v_cvt_pk_bf16_f32 v70, v64, v65
	v_add_u32_e32 v64, v121, v84
	v_ashrrev_i32_e32 v65, 31, v64
	v_lshlrev_b64 v[64:65], 12, v[64:65]
	v_lshl_add_u64 v[64:65], s[68:69], 0, v[64:65]
	v_lshl_add_u64 v[64:65], v[64:65], 0, v[108:109]
	v_cvt_pk_bf16_f32 v71, v66, v67
	global_store_dwordx4 v[64:65], v[68:71], off
	v_add_u32_e32 v64, 0x80, v152
	v_cvt_pk_bf16_f32 v60, v60, v61
	v_cvt_pk_bf16_f32 v61, v62, v63
	v_cvt_pk_bf16_f32 v62, v56, v57
	v_add_u32_e32 v56, v122, v64
	v_ashrrev_i32_e32 v57, 31, v56
	v_lshlrev_b64 v[56:57], 12, v[56:57]
	v_lshl_add_u64 v[56:57], s[68:69], 0, v[56:57]
	v_lshl_add_u64 v[56:57], v[56:57], 0, v[136:137]
	v_cvt_pk_bf16_f32 v63, v58, v59
	global_store_dwordx4 v[56:57], v[60:63], off
	v_cvt_pk_bf16_f32 v52, v52, v53
	v_cvt_pk_bf16_f32 v53, v54, v55
	v_cvt_pk_bf16_f32 v54, v44, v45
	v_add_u32_e32 v44, v121, v64
	v_ashrrev_i32_e32 v45, 31, v44
	v_lshlrev_b64 v[44:45], 12, v[44:45]
	v_lshl_add_u64 v[44:45], s[68:69], 0, v[44:45]
	v_lshl_add_u64 v[44:45], v[44:45], 0, v[108:109]
	v_cvt_pk_bf16_f32 v55, v46, v47
	global_store_dwordx4 v[44:45], v[52:55], off
	v_cvt_pk_bf16_f32 v44, v48, v49
	v_cvt_pk_bf16_f32 v45, v50, v51
	v_cvt_pk_bf16_f32 v46, v40, v41
	v_cvt_pk_bf16_f32 v47, v42, v43
	s_mov_b64 s[24:25], s[18:19]
	s_nop 0
	v_add_u32_e32 v52, 0x90, v152
	v_add_u32_e32 v40, v122, v52
	v_ashrrev_i32_e32 v41, 31, v40
	v_lshlrev_b64 v[40:41], 12, v[40:41]
	v_lshl_add_u64 v[40:41], s[68:69], 0, v[40:41]
	v_lshl_add_u64 v[40:41], v[40:41], 0, v[136:137]
	global_store_dwordx4 v[40:41], v[44:47], off
	v_cvt_pk_bf16_f32 v36, v36, v37
	v_cvt_pk_bf16_f32 v37, v38, v39
	v_cvt_pk_bf16_f32 v38, v28, v29
	v_add_u32_e32 v28, v121, v52
	v_ashrrev_i32_e32 v29, 31, v28
	v_lshlrev_b64 v[28:29], 12, v[28:29]
	v_lshl_add_u64 v[28:29], s[68:69], 0, v[28:29]
	v_lshl_add_u64 v[28:29], v[28:29], 0, v[108:109]
	v_cvt_pk_bf16_f32 v39, v30, v31
	global_store_dwordx4 v[28:29], v[36:39], off
	v_cvt_pk_bf16_f32 v28, v32, v33
	v_cvt_pk_bf16_f32 v29, v34, v35
	v_cvt_pk_bf16_f32 v30, v24, v25
	v_cvt_pk_bf16_f32 v31, v26, v27
	s_mov_b64 s[22:23], s[16:17]
	s_nop 0
	v_add_u32_e32 v36, 0xa0, v152
	v_add_u32_e32 v24, v122, v36
	v_ashrrev_i32_e32 v25, 31, v24
	v_lshlrev_b64 v[24:25], 12, v[24:25]
	v_lshl_add_u64 v[24:25], s[68:69], 0, v[24:25]
	v_lshl_add_u64 v[24:25], v[24:25], 0, v[136:137]
	global_store_dwordx4 v[24:25], v[28:31], off
	v_cvt_pk_bf16_f32 v20, v20, v21
	v_cvt_pk_bf16_f32 v21, v22, v23
	v_cvt_pk_bf16_f32 v22, v12, v13
	v_add_u32_e32 v12, v121, v36
	v_ashrrev_i32_e32 v13, 31, v12
	v_lshlrev_b64 v[12:13], 12, v[12:13]
	v_lshl_add_u64 v[12:13], s[68:69], 0, v[12:13]
	v_lshl_add_u64 v[12:13], v[12:13], 0, v[108:109]
	v_cvt_pk_bf16_f32 v23, v14, v15
	global_store_dwordx4 v[12:13], v[20:23], off
	v_cvt_pk_bf16_f32 v12, v16, v17
	v_cvt_pk_bf16_f32 v13, v18, v19
	v_cvt_pk_bf16_f32 v14, v8, v9
	v_cvt_pk_bf16_f32 v15, v10, v11
	s_nop 1
	v_add_u32_e32 v20, 0xb0, v152
	v_add_u32_e32 v8, v122, v20
	v_ashrrev_i32_e32 v9, 31, v8
	v_lshlrev_b64 v[8:9], 12, v[8:9]
	v_lshl_add_u64 v[8:9], s[68:69], 0, v[8:9]
	v_lshl_add_u64 v[8:9], v[8:9], 0, v[136:137]
	global_store_dwordx4 v[8:9], v[12:15], off
	v_cvt_pk_bf16_f32 v4, v4, v5
	v_cvt_pk_bf16_f32 v5, v6, v7
	v_cvt_pk_bf16_f32 v6, v0, v1
	v_add_u32_e32 v0, v121, v20
	v_ashrrev_i32_e32 v1, 31, v0
	v_lshlrev_b64 v[0:1], 12, v[0:1]
	v_lshl_add_u64 v[0:1], s[68:69], 0, v[0:1]
	v_lshl_add_u64 v[0:1], v[0:1], 0, v[108:109]
	v_cvt_pk_bf16_f32 v7, v2, v3
	global_store_dwordx4 v[0:1], v[4:7], off
	s_barrier
; #define PG8_WAIT_V(n) asm volatile("s_waitcnt vmcnt(" #n ")" ::: "memory")
; #define PG8_BAR __builtin_amdgcn_s_barrier()
; template <class Epi, class Sched>
; __device__ __forceinline__ void gemm_phase(LAS unsigned char* lds, const Gemm g, const Sched& S, const Epi& E) {
;     ...
;     }
;     PG8_WAIT_V(0);
;     if (wr == 0) PG8_BAR;
	s_cbranch_vccz .LBB0_646
.Lconc_end_g5:
	s_waitcnt vmcnt(0)
	s_cmpk_gt_u32 s28, 0xff
	s_cbranch_scc1 .LBB0_657
	s_barrier

; #define PG8_STAGE(bufoff, gbase, voff) do { _Pragma("unroll") for (int _i = 0; _i < 2; ++_i) \
;         __builtin_amdgcn_global_load_lds((const unsigned*)((const char*)(gbase) + (voff)[_i]), (LAS unsigned*)(lds + (bufoff) + ldsw + _i * 8192), 16, 0, 0); } while (0)
; #define PG8_LDA(dst, b, h) do { _Pragma("unroll") for (int m = 0; m < 4; ++m) _Pragma("unroll") for (int k = 0; k < 2; ++k) dst[m][k] = *(const LAS bf16x8*)(lds + PG8_SA(b, h) + aoff + m * 2048 + k * 1024); } while (0)
; #define PG8_LDB(dst, b, h) do { _Pragma("unroll") for (int n = 0; n < 2; ++n) _Pragma("unroll") for (int k = 0; k < 2; ++k) dst[n][k] = *(const LAS bf16x8*)(lds + PG8_SB(b, h) + boff + n * 2048 + k * 1024); } while (0)
; #define PG8_MMA(ai, bj, At, Bt) do { __builtin_amdgcn_s_setprio(1); _Pragma("unroll") for (int m = 0; m < 4; ++m) _Pragma("unroll") for (int n = 0; n < 2; ++n) _Pragma("unroll") for (int k = 0; k < 2; ++k) \
;         acc[ai][bj][m][n] = __builtin_amdgcn_mfma_f32_16x16x32_bf16(Bt[n][k], At[m][k], acc[ai][bj][m][n], 0, 0, 0); __builtin_amdgcn_s_setprio(0); } while (0)
; #define PG8_WAIT_V(n) asm volatile("s_waitcnt vmcnt(" #n ")" ::: "memory")
; #define PG8_WAIT_L(n) asm volatile("s_waitcnt lgkmcnt(" #n ")" ::: "memory")
; #define PG8_BAR __builtin_amdgcn_s_barrier()
; #define PG8_SCHED __builtin_amdgcn_sched_barrier(0)
; template <class Epi, class Sched>
; __device__ __forceinline__ void gemm_phase(LAS unsigned char* lds, const Gemm g, const Sched& S, const Epi& E) {
;     ...
;             PG8_LDB(B0, 0, 0); PG8_SCHED; PG8_LDA(At, 0, 0); PG8_STAGE(PG8_SA(1, 1), a1 + hstep, voffA);
;             PG8_WAIT_L(8); PG8_BAR; PG8_WAIT_L(0); PG8_MMA(0, 0, At, B0); PG8_BAR; PG8_SCHED;
;             PG8_LDB(B1, 0, 1); PG8_STAGE(PG8_SB(0, 0), b2, voffB);
;             PG8_BAR; PG8_WAIT_L(0); PG8_MMA(0, 1, At, B1); PG8_BAR;
;             PG8_LDA(At, 0, 1); PG8_STAGE(PG8_SA(0, 0), a2, voffA);
;             PG8_BAR; PG8_WAIT_L(0); PG8_MMA(1, 0, At, B0); PG8_BAR; PG8_SCHED;
;             PG8_STAGE(PG8_SB(0, 1), b2 + hstep, voffB);
;             PG8_WAIT_V(6); PG8_BAR; PG8_MMA(1, 1, At, B1); PG8_BAR;
.LBB0_673:
	ds_read_b128 v[152:155], v149
	ds_read_b128 v[156:159], v149 offset:1024
	ds_read_b128 v[160:163], v149 offset:2048
	ds_read_b128 v[164:167], v149 offset:3072
	s_add_u32 s20, s18, 0xfffc0080
	s_addc_u32 s21, s19, -1
	s_cmp_eq_u32 s51, 12
	s_cselect_b32 s23, s9, s21
	s_cselect_b32 s22, s46, s20
	s_cselect_b32 s21, s7, s49
	s_cselect_b32 s20, s47, s48
	s_add_i32 m0, s17, 0xc000
	ds_read_b128 v[168:171], v150
	ds_read_b128 v[172:175], v150 offset:1024
	ds_read_b128 v[176:179], v150 offset:2048
	ds_read_b128 v[180:183], v150 offset:3072
	ds_read_b128 v[184:187], v150 offset:4096
	ds_read_b128 v[188:191], v150 offset:5120
	ds_read_b128 v[192:195], v150 offset:6144
	ds_read_b128 v[196:199], v150 offset:7168
	global_load_lds_dwordx4 v138, s[18:19]
	s_add_i32 m0, s17, 0xe000
	s_nop 0
	global_load_lds_dwordx4 v140, s[18:19]
	s_waitcnt lgkmcnt(8)
	s_waitcnt vmcnt(10)
	s_barrier
	s_waitcnt lgkmcnt(0)
	s_setprio 1
	s_waitcnt lgkmcnt(0)
	v_mfma_f32_16x16x32_bf16 v[124:127], v[152:155], v[168:171], v[124:127]
	v_mfma_f32_16x16x32_bf16 v[120:123], v[160:163], v[168:171], v[120:123]
	v_mfma_f32_16x16x32_bf16 v[112:115], v[152:155], v[176:179], v[112:115]
	v_mfma_f32_16x16x32_bf16 v[104:107], v[160:163], v[176:179], v[104:107]
	v_mfma_f32_16x16x32_bf16 v[96:99], v[152:155], v[184:187], v[96:99]
	v_mfma_f32_16x16x32_bf16 v[88:91], v[160:163], v[184:187], v[88:91]
	v_mfma_f32_16x16x32_bf16 v[80:83], v[152:155], v[192:195], v[80:83]
	v_mfma_f32_16x16x32_bf16 v[72:75], v[160:163], v[192:195], v[72:75]
	v_mfma_f32_16x16x32_bf16 v[124:127], v[156:159], v[172:175], v[124:127]
	v_mfma_f32_16x16x32_bf16 v[120:123], v[164:167], v[172:175], v[120:123]
	v_mfma_f32_16x16x32_bf16 v[112:115], v[156:159], v[180:183], v[112:115]
	v_mfma_f32_16x16x32_bf16 v[104:107], v[164:167], v[180:183], v[104:107]
	v_mfma_f32_16x16x32_bf16 v[96:99], v[156:159], v[188:191], v[96:99]
	v_mfma_f32_16x16x32_bf16 v[88:91], v[164:167], v[188:191], v[88:91]
	v_mfma_f32_16x16x32_bf16 v[80:83], v[156:159], v[196:199], v[80:83]
	v_mfma_f32_16x16x32_bf16 v[72:75], v[164:167], v[196:199], v[72:75]
	s_setprio 0
	s_barrier
	s_add_i32 s52, s43, s28
	s_mov_b32 m0, s52
	ds_read_b128 v[202:205], v151
	ds_read_b128 v[206:209], v151 offset:1024
	ds_read_b128 v[210:213], v151 offset:2048
	ds_read_b128 v[214:217], v151 offset:3072
	global_load_lds_dwordx4 v130, s[20:21]
	s_add_i32 m0, s52, 0x2000
	s_nop 0
	global_load_lds_dwordx4 v134, s[20:21]
	s_waitcnt vmcnt(10)
	s_barrier
	s_waitcnt lgkmcnt(0)
	s_setprio 1
	s_waitcnt lgkmcnt(0)
	v_mfma_f32_16x16x32_bf16 v[116:119], v[202:205], v[168:171], v[116:119]
	v_mfma_f32_16x16x32_bf16 v[108:111], v[210:213], v[168:171], v[108:111]
	v_mfma_f32_16x16x32_bf16 v[100:103], v[202:205], v[176:179], v[100:103]
	v_mfma_f32_16x16x32_bf16 v[92:95], v[210:213], v[176:179], v[92:95]
	v_mfma_f32_16x16x32_bf16 v[84:87], v[202:205], v[184:187], v[84:87]
	v_mfma_f32_16x16x32_bf16 v[76:79], v[210:213], v[184:187], v[76:79]
	v_mfma_f32_16x16x32_bf16 v[68:71], v[202:205], v[192:195], v[68:71]
	v_mfma_f32_16x16x32_bf16 v[64:67], v[210:213], v[192:195], v[64:67]
	v_mfma_f32_16x16x32_bf16 v[116:119], v[206:209], v[172:175], v[116:119]
	v_mfma_f32_16x16x32_bf16 v[108:111], v[214:217], v[172:175], v[108:111]
	v_mfma_f32_16x16x32_bf16 v[100:103], v[206:209], v[180:183], v[100:103]
	v_mfma_f32_16x16x32_bf16 v[92:95], v[214:217], v[180:183], v[92:95]
	v_mfma_f32_16x16x32_bf16 v[84:87], v[206:209], v[188:191], v[84:87]
	v_mfma_f32_16x16x32_bf16 v[76:79], v[214:217], v[188:191], v[76:79]
	v_mfma_f32_16x16x32_bf16 v[68:71], v[206:209], v[196:199], v[68:71]
	v_mfma_f32_16x16x32_bf16 v[64:67], v[214:217], v[196:199], v[64:67]
	s_setprio 0
	s_mov_b32 m0, s17
	v_lshl_add_u64 v[222:223], s[22:23], 0, v[128:129]
	s_barrier
	ds_read_b128 v[168:171], v150 offset:16384
	ds_read_b128 v[172:175], v150 offset:17408
	ds_read_b128 v[176:179], v150 offset:18432
	ds_read_b128 v[180:183], v150 offset:19456
	ds_read_b128 v[184:187], v150 offset:20480
	ds_read_b128 v[188:191], v150 offset:21504
	ds_read_b128 v[192:195], v150 offset:22528
	ds_read_b128 v[196:199], v150 offset:23552
	global_load_lds_dwordx4 v128, s[22:23]
	v_lshl_add_u64 v[224:225], s[22:23], 0, v[132:133]
	s_mov_b32 m0, s29
	s_nop 0
	global_load_lds_dwordx4 v132, s[22:23]
	s_barrier
	s_waitcnt lgkmcnt(0)
	s_setprio 1
	s_waitcnt lgkmcnt(0)
	v_mfma_f32_16x16x32_bf16 v[60:63], v[152:155], v[168:171], v[60:63]
	v_mfma_f32_16x16x32_bf16 v[56:59], v[160:163], v[168:171], v[56:59]
	v_mfma_f32_16x16x32_bf16 v[48:51], v[152:155], v[176:179], v[48:51]
	v_mfma_f32_16x16x32_bf16 v[40:43], v[160:163], v[176:179], v[40:43]
	v_mfma_f32_16x16x32_bf16 v[32:35], v[152:155], v[184:187], v[32:35]
	v_mfma_f32_16x16x32_bf16 v[24:27], v[160:163], v[184:187], v[24:27]
	v_mfma_f32_16x16x32_bf16 v[16:19], v[152:155], v[192:195], v[16:19]
	v_mfma_f32_16x16x32_bf16 v[8:11], v[160:163], v[192:195], v[8:11]
	v_mfma_f32_16x16x32_bf16 v[60:63], v[156:159], v[172:175], v[60:63]
	v_mfma_f32_16x16x32_bf16 v[56:59], v[164:167], v[172:175], v[56:59]
	v_mfma_f32_16x16x32_bf16 v[48:51], v[156:159], v[180:183], v[48:51]
	v_mfma_f32_16x16x32_bf16 v[40:43], v[164:167], v[180:183], v[40:43]
	v_mfma_f32_16x16x32_bf16 v[32:35], v[156:159], v[188:191], v[32:35]
	v_mfma_f32_16x16x32_bf16 v[24:27], v[164:167], v[188:191], v[24:27]
	v_mfma_f32_16x16x32_bf16 v[16:19], v[156:159], v[196:199], v[16:19]
	v_mfma_f32_16x16x32_bf16 v[8:11], v[164:167], v[196:199], v[8:11]
	s_setprio 0
	s_barrier
; #define PG8_STAGE(bufoff, gbase, voff) do { _Pragma("unroll") for (int _i = 0; _i < 2; ++_i) \
;         __builtin_amdgcn_global_load_lds((const unsigned*)((const char*)(gbase) + (voff)[_i]), (LAS unsigned*)(lds + (bufoff) + ldsw + _i * 8192), 16, 0, 0); } while (0)
; #define PG8_LDA(dst, b, h) do { _Pragma("unroll") for (int m = 0; m < 4; ++m) _Pragma("unroll") for (int k = 0; k < 2; ++k) dst[m][k] = *(const LAS bf16x8*)(lds + PG8_SA(b, h) + aoff + m * 2048 + k * 1024); } while (0)
; #define PG8_LDB(dst, b, h) do { _Pragma("unroll") for (int n = 0; n < 2; ++n) _Pragma("unroll") for (int k = 0; k < 2; ++k) dst[n][k] = *(const LAS bf16x8*)(lds + PG8_SB(b, h) + boff + n * 2048 + k * 1024); } while (0)
; #define PG8_MMA(ai, bj, At, Bt) do { __builtin_amdgcn_s_setprio(1); _Pragma("unroll") for (int m = 0; m < 4; ++m) _Pragma("unroll") for (int n = 0; n < 2; ++n) _Pragma("unroll") for (int k = 0; k < 2; ++k) \
;         acc[ai][bj][m][n] = __builtin_amdgcn_mfma_f32_16x16x32_bf16(Bt[n][k], At[m][k], acc[ai][bj][m][n], 0, 0, 0); __builtin_amdgcn_s_setprio(0); } while (0)
; #define PG8_WAIT_V(n) asm volatile("s_waitcnt vmcnt(" #n ")" ::: "memory")
; #define PG8_WAIT_L(n) asm volatile("s_waitcnt lgkmcnt(" #n ")" ::: "memory")
; #define PG8_BAR __builtin_amdgcn_s_barrier()
; #define PG8_SCHED __builtin_amdgcn_sched_barrier(0)
; template <class Epi, class Sched>
; __device__ __forceinline__ void gemm_phase(LAS unsigned char* lds, const Gemm g, const Sched& S, const Epi& E) {
;     ...
;             PG8_STAGE(PG8_SB(0, 1), b2 + hstep, voffB);
;             PG8_WAIT_V(6); PG8_BAR; PG8_MMA(1, 1, At, B1); PG8_BAR;
;             PG8_LDB(B0, 1, 0); PG8_SCHED; PG8_LDA(At, 1, 0); PG8_STAGE(PG8_SA(0, 1), a2 + hstep, voffA);
;             PG8_WAIT_L(8); PG8_BAR; PG8_WAIT_L(0); PG8_MMA(0, 0, At, B0); PG8_BAR; PG8_SCHED;
;             PG8_LDB(B1, 1, 1); PG8_STAGE(PG8_SB(1, 0), b3, voffB);
;             PG8_BAR; PG8_WAIT_L(0); PG8_MMA(0, 1, At, B1); PG8_BAR;
;             PG8_LDA(At, 1, 1); PG8_STAGE(PG8_SA(1, 0), a3, voffA);
;             PG8_BAR; PG8_WAIT_L(0); PG8_MMA(1, 0, At, B0); PG8_BAR; PG8_SCHED;
	s_add_u32 s52, s20, 0x40000
	s_addc_u32 s53, s21, 0
	s_add_i32 s54, s44, s28
	s_mov_b32 m0, s54
	s_nop 0
	global_load_lds_dwordx4 v130, s[52:53]
	s_add_i32 m0, s54, 0x2000
	s_nop 0
	global_load_lds_dwordx4 v134, s[52:53]
	s_add_u32 s22, s22, 0x40000
	s_addc_u32 s23, s23, 0
	s_mov_b32 m0, s30
	s_nop 0
	global_load_lds_dwordx4 v128, s[22:23]
	s_mov_b32 m0, s31
	s_nop 0
	global_load_lds_dwordx4 v132, s[22:23]
	s_waitcnt vmcnt(12)
	s_barrier
	s_setprio 1
	v_mfma_f32_16x16x32_bf16 v[52:55], v[202:205], v[168:171], v[52:55]
	v_mfma_f32_16x16x32_bf16 v[44:47], v[210:213], v[168:171], v[44:47]
	v_mfma_f32_16x16x32_bf16 v[36:39], v[202:205], v[176:179], v[36:39]
	v_mfma_f32_16x16x32_bf16 v[28:31], v[210:213], v[176:179], v[28:31]
	v_mfma_f32_16x16x32_bf16 v[20:23], v[202:205], v[184:187], v[20:23]
	v_mfma_f32_16x16x32_bf16 v[12:15], v[210:213], v[184:187], v[12:15]
	v_mfma_f32_16x16x32_bf16 v[4:7], v[202:205], v[192:195], v[4:7]
	v_mfma_f32_16x16x32_bf16 v[0:3], v[210:213], v[192:195], v[0:3]
	v_mfma_f32_16x16x32_bf16 v[52:55], v[206:209], v[172:175], v[52:55]
	v_mfma_f32_16x16x32_bf16 v[44:47], v[214:217], v[172:175], v[44:47]
	v_mfma_f32_16x16x32_bf16 v[36:39], v[206:209], v[180:183], v[36:39]
	v_mfma_f32_16x16x32_bf16 v[28:31], v[214:217], v[180:183], v[28:31]
	v_mfma_f32_16x16x32_bf16 v[20:23], v[206:209], v[188:191], v[20:23]
	v_mfma_f32_16x16x32_bf16 v[12:15], v[214:217], v[188:191], v[12:15]
	v_mfma_f32_16x16x32_bf16 v[4:7], v[206:209], v[196:199], v[4:7]
	v_mfma_f32_16x16x32_bf16 v[0:3], v[214:217], v[196:199], v[0:3]
	s_setprio 0
	s_add_i32 s52, 0, 0x18000
	v_add_u32_e32 v136, s52, v148
	s_barrier
	ds_read_b128 v[152:155], v136
	ds_read_b128 v[156:159], v136 offset:1024
	ds_read_b128 v[160:163], v136 offset:2048
	ds_read_b128 v[164:167], v136 offset:3072
	ds_read_b128 v[168:171], v150 offset:32768
	ds_read_b128 v[172:175], v150 offset:33792
	ds_read_b128 v[176:179], v150 offset:34816
	ds_read_b128 v[180:183], v150 offset:35840
	ds_read_b128 v[184:187], v150 offset:36864
	ds_read_b128 v[188:191], v150 offset:37888
	ds_read_b128 v[192:195], v150 offset:38912
	ds_read_b128 v[196:199], v150 offset:39936
	s_waitcnt lgkmcnt(8)
	s_waitcnt vmcnt(10)
	s_barrier
	s_waitcnt lgkmcnt(0)
	s_setprio 1
	s_waitcnt lgkmcnt(0)
	v_mfma_f32_16x16x32_bf16 v[124:127], v[152:155], v[168:171], v[124:127]
	v_mfma_f32_16x16x32_bf16 v[120:123], v[160:163], v[168:171], v[120:123]
	v_mfma_f32_16x16x32_bf16 v[112:115], v[152:155], v[176:179], v[112:115]
	v_mfma_f32_16x16x32_bf16 v[104:107], v[160:163], v[176:179], v[104:107]
	v_mfma_f32_16x16x32_bf16 v[96:99], v[152:155], v[184:187], v[96:99]
	v_mfma_f32_16x16x32_bf16 v[88:91], v[160:163], v[184:187], v[88:91]
	v_mfma_f32_16x16x32_bf16 v[80:83], v[152:155], v[192:195], v[80:83]
	v_mfma_f32_16x16x32_bf16 v[72:75], v[160:163], v[192:195], v[72:75]
	v_mfma_f32_16x16x32_bf16 v[124:127], v[156:159], v[172:175], v[124:127]
	v_mfma_f32_16x16x32_bf16 v[120:123], v[164:167], v[172:175], v[120:123]
	v_mfma_f32_16x16x32_bf16 v[112:115], v[156:159], v[180:183], v[112:115]
	v_mfma_f32_16x16x32_bf16 v[104:107], v[164:167], v[180:183], v[104:107]
	v_mfma_f32_16x16x32_bf16 v[96:99], v[156:159], v[188:191], v[96:99]
	v_mfma_f32_16x16x32_bf16 v[88:91], v[164:167], v[188:191], v[88:91]
	v_mfma_f32_16x16x32_bf16 v[80:83], v[156:159], v[196:199], v[80:83]
	v_mfma_f32_16x16x32_bf16 v[72:75], v[164:167], v[196:199], v[72:75]
	s_setprio 0
	s_barrier
	s_add_i32 s22, 0, 0x1c000
	s_add_i32 s23, s52, s28
	v_add_u32_e32 v136, s22, v148
	s_add_u32 s0, s20, 0x80
	s_addc_u32 s1, s21, 0
	s_mov_b32 m0, s23
	ds_read_b128 v[202:205], v136
	ds_read_b128 v[206:209], v136 offset:1024
	ds_read_b128 v[210:213], v136 offset:2048
	ds_read_b128 v[214:217], v136 offset:3072
	global_load_lds_dwordx4 v130, s[0:1]
	s_add_i32 m0, s23, 0x2000
	s_nop 0
	global_load_lds_dwordx4 v134, s[0:1]
	s_waitcnt vmcnt(10)
	s_barrier
	s_waitcnt lgkmcnt(0)
	s_setprio 1
	s_waitcnt lgkmcnt(0)
	v_mfma_f32_16x16x32_bf16 v[116:119], v[202:205], v[168:171], v[116:119]
	v_mfma_f32_16x16x32_bf16 v[108:111], v[210:213], v[168:171], v[108:111]
	v_mfma_f32_16x16x32_bf16 v[100:103], v[202:205], v[176:179], v[100:103]
	v_mfma_f32_16x16x32_bf16 v[92:95], v[210:213], v[176:179], v[92:95]
	v_mfma_f32_16x16x32_bf16 v[84:87], v[202:205], v[184:187], v[84:87]
	v_mfma_f32_16x16x32_bf16 v[76:79], v[210:213], v[184:187], v[76:79]
	v_mfma_f32_16x16x32_bf16 v[68:71], v[202:205], v[192:195], v[68:71]
	v_mfma_f32_16x16x32_bf16 v[64:67], v[210:213], v[192:195], v[64:67]
	v_mfma_f32_16x16x32_bf16 v[116:119], v[206:209], v[172:175], v[116:119]
	v_mfma_f32_16x16x32_bf16 v[108:111], v[214:217], v[172:175], v[108:111]
	v_mfma_f32_16x16x32_bf16 v[100:103], v[206:209], v[180:183], v[100:103]
	v_mfma_f32_16x16x32_bf16 v[92:95], v[214:217], v[180:183], v[92:95]
	v_mfma_f32_16x16x32_bf16 v[84:87], v[206:209], v[188:191], v[84:87]
	v_mfma_f32_16x16x32_bf16 v[76:79], v[214:217], v[188:191], v[76:79]
	v_mfma_f32_16x16x32_bf16 v[68:71], v[206:209], v[196:199], v[68:71]
	v_mfma_f32_16x16x32_bf16 v[64:67], v[214:217], v[196:199], v[64:67]
	s_setprio 0
	s_mov_b32 m0, s36
	s_mov_b64 s[0:1], 0x80
	v_lshl_add_u64 v[218:219], v[222:223], 0, s[0:1]
	s_barrier
	ds_read_b128 v[168:171], v150 offset:49152
	ds_read_b128 v[172:175], v150 offset:50176
	ds_read_b128 v[176:179], v150 offset:51200
	ds_read_b128 v[180:183], v150 offset:52224
	ds_read_b128 v[184:187], v150 offset:53248
	ds_read_b128 v[188:191], v150 offset:54272
	ds_read_b128 v[192:195], v150 offset:55296
	ds_read_b128 v[196:199], v150 offset:56320
	global_load_lds_dwordx4 v[218:219], off
	v_lshl_add_u64 v[218:219], v[224:225], 0, s[0:1]
	s_mov_b32 m0, s37
	s_nop 0
	global_load_lds_dwordx4 v[218:219], off
	s_barrier
; __device__ __forceinline__ unsigned cvt_pk_bf16(float lo, float hi) { unsigned r; asm volatile("v_cvt_pk_bf16_f32 %0, %1, %2" : "=v"(r) : "v"(lo), "v"(hi)); return r; }
; #define PG8_STAGE(bufoff, gbase, voff) do { _Pragma("unroll") for (int _i = 0; _i < 2; ++_i) \
;         __builtin_amdgcn_global_load_lds((const unsigned*)((const char*)(gbase) + (voff)[_i]), (LAS unsigned*)(lds + (bufoff) + ldsw + _i * 8192), 16, 0, 0); } while (0)
; #define PG8_MMA(ai, bj, At, Bt) do { __builtin_amdgcn_s_setprio(1); _Pragma("unroll") for (int m = 0; m < 4; ++m) _Pragma("unroll") for (int n = 0; n < 2; ++n) _Pragma("unroll") for (int k = 0; k < 2; ++k) \
;         acc[ai][bj][m][n] = __builtin_amdgcn_mfma_f32_16x16x32_bf16(Bt[n][k], At[m][k], acc[ai][bj][m][n], 0, 0, 0); __builtin_amdgcn_s_setprio(0); } while (0)
; #define PG8_WAIT_V(n) asm volatile("s_waitcnt vmcnt(" #n ")" ::: "memory")
; #define PG8_WAIT_L(n) asm volatile("s_waitcnt lgkmcnt(" #n ")" ::: "memory")
; #define PG8_BAR __builtin_amdgcn_s_barrier()
; #define PG8_SCHED __builtin_amdgcn_sched_barrier(0)
; template <class Epi, class Sched>
; __device__ __forceinline__ void gemm_phase(LAS unsigned char* lds, const Gemm g, const Sched& S, const Epi& E) {
;     ...
;             PG8_BAR; PG8_WAIT_L(0); PG8_MMA(1, 0, At, B0); PG8_BAR; PG8_SCHED;
;             PG8_STAGE(PG8_SB(1, 1), b3 + hstep, voffB);
;             PG8_WAIT_V(6); PG8_BAR; PG8_MMA(1, 1, At, B1); PG8_BAR;
;     __device__ __forceinline__ void operator()(const AccT& acc, const Unit& u, int wr, int wc, int fr, int fq) const {
;     ...
; #pragma unroll
;         for (int ai = 0; ai < 2; ++ai)
; #pragma unroll
;             for (int m = 0; m < 4; ++m) {
;                 const int gm = rbase + ai * 128 + m * 16;
; #pragma unroll
;                 for (int bj = 0; bj < 2; ++bj) {
;                     const int t0 = tb + bj * 128;
;                     const f32x4 v0 = acc[ai][bj][m][0], v1 = acc[ai][bj][m][1];
;                     u32x4 w; w.x = cvt_pk_bf16(v0[0], v0[1]); w.y = cvt_pk_bf16(v0[2], v0[3]); w.z = cvt_pk_bf16(v1[0], v1[1]); w.w = cvt_pk_bf16(v1[2], v1[3]);
;                     *(u32x4*)(YT + ((size_t)((t0 >> 10) * 512 + gm)) * 2048 + part * 1024 + (t0 & 1023)) = w;
;                 }
	s_waitcnt lgkmcnt(0)
	s_setprio 1
	s_waitcnt lgkmcnt(0)
	v_mfma_f32_16x16x32_bf16 v[60:63], v[152:155], v[168:171], v[60:63]
	v_mfma_f32_16x16x32_bf16 v[56:59], v[160:163], v[168:171], v[56:59]
	v_mfma_f32_16x16x32_bf16 v[48:51], v[152:155], v[176:179], v[48:51]
	v_mfma_f32_16x16x32_bf16 v[40:43], v[160:163], v[176:179], v[40:43]
	v_mfma_f32_16x16x32_bf16 v[32:35], v[152:155], v[184:187], v[32:35]
	v_mfma_f32_16x16x32_bf16 v[24:27], v[160:163], v[184:187], v[24:27]
	v_mfma_f32_16x16x32_bf16 v[16:19], v[152:155], v[192:195], v[16:19]
	v_mfma_f32_16x16x32_bf16 v[8:11], v[160:163], v[192:195], v[8:11]
	v_mfma_f32_16x16x32_bf16 v[60:63], v[156:159], v[172:175], v[60:63]
	v_mfma_f32_16x16x32_bf16 v[56:59], v[164:167], v[172:175], v[56:59]
	v_mfma_f32_16x16x32_bf16 v[48:51], v[156:159], v[180:183], v[48:51]
	v_mfma_f32_16x16x32_bf16 v[40:43], v[164:167], v[180:183], v[40:43]
	v_mfma_f32_16x16x32_bf16 v[32:35], v[156:159], v[188:191], v[32:35]
	v_mfma_f32_16x16x32_bf16 v[24:27], v[164:167], v[188:191], v[24:27]
	v_mfma_f32_16x16x32_bf16 v[16:19], v[156:159], v[196:199], v[16:19]
	v_mfma_f32_16x16x32_bf16 v[8:11], v[164:167], v[196:199], v[8:11]
	s_setprio 0
	s_barrier
	s_add_u32 s20, s20, 0x40080
	s_addc_u32 s21, s21, 0
	s_add_i32 s22, s22, s28
	s_mov_b32 m0, s22
	s_nop 0
	global_load_lds_dwordx4 v130, s[20:21]
	s_add_i32 m0, s22, 0x2000
	s_nop 0
	global_load_lds_dwordx4 v134, s[20:21]
	s_waitcnt vmcnt(10)
	s_barrier
	s_setprio 1
	v_mfma_f32_16x16x32_bf16 v[52:55], v[202:205], v[168:171], v[52:55]
	v_mfma_f32_16x16x32_bf16 v[44:47], v[210:213], v[168:171], v[44:47]
	v_mfma_f32_16x16x32_bf16 v[36:39], v[202:205], v[176:179], v[36:39]
	v_mfma_f32_16x16x32_bf16 v[28:31], v[210:213], v[176:179], v[28:31]
	v_mfma_f32_16x16x32_bf16 v[20:23], v[202:205], v[184:187], v[20:23]
	v_mfma_f32_16x16x32_bf16 v[12:15], v[210:213], v[184:187], v[12:15]
	v_mfma_f32_16x16x32_bf16 v[4:7], v[202:205], v[192:195], v[4:7]
	v_mfma_f32_16x16x32_bf16 v[0:3], v[210:213], v[192:195], v[0:3]
	v_mfma_f32_16x16x32_bf16 v[52:55], v[206:209], v[172:175], v[52:55]
	v_mfma_f32_16x16x32_bf16 v[44:47], v[214:217], v[172:175], v[44:47]
	v_mfma_f32_16x16x32_bf16 v[36:39], v[206:209], v[180:183], v[36:39]
	v_mfma_f32_16x16x32_bf16 v[28:31], v[214:217], v[180:183], v[28:31]
	v_mfma_f32_16x16x32_bf16 v[20:23], v[206:209], v[188:191], v[20:23]
	v_mfma_f32_16x16x32_bf16 v[12:15], v[214:217], v[188:191], v[12:15]
	v_mfma_f32_16x16x32_bf16 v[4:7], v[206:209], v[196:199], v[4:7]
	v_mfma_f32_16x16x32_bf16 v[0:3], v[214:217], v[196:199], v[0:3]
	s_setprio 0
	s_add_i32 s51, s51, 2
	s_add_u32 s18, s18, 0x100
	s_addc_u32 s19, s19, 0
	s_add_u32 s48, s48, 0x100
	s_addc_u32 s49, s49, 0
	s_cmp_gt_u32 s51, 13
	s_cbranch_scc1 .Lconc_last_g6
	s_barrier
	s_branch .LBB0_673
.Lconc_last_g6:
	v_readfirstlane_b32 s7, v200
	s_nop 3
	s_cmp_gt_u32 s7, 0xff
	s_cbranch_scc1 .Lconc_epi1_g6
	s_barrier
	v_mov_b32_e32 v136, v147
	v_mov_b32_e32 v152, v146
	s_lshl_b32 s7, s16, 8
	s_add_i32 s7, s7, s34
	v_add_u32_e32 v152, s7, v152
	s_lshl_b32 s7, s45, 8
	s_or_b32 s7, s7, s35
	v_lshl_add_u32 v153, v136, 3, s7
	v_cvt_pk_bf16_f32 v124, v124, v125
	v_cvt_pk_bf16_f32 v125, v126, v127
	v_cvt_pk_bf16_f32 v126, v120, v121
	v_ashrrev_i32_e32 v120, 1, v153
	v_cvt_pk_bf16_f32 v127, v122, v123
	v_and_b32_e32 v122, 0xfffffe00, v120
	v_add_u32_e32 v120, v122, v152
	v_ashrrev_i32_e32 v121, 31, v120
	v_lshlrev_b64 v[120:121], 12, v[120:121]
	v_and_b32_e32 v123, 0x3f8, v153
	v_lshl_add_u64 v[120:121], s[4:5], 0, v[120:121]
	v_lshlrev_b32_e32 v136, 1, v123
	v_lshl_add_u64 v[120:121], v[120:121], 0, v[136:137]
	global_store_dwordx4 v[120:121], v[124:127], off
	v_add_u32_e32 v120, 0x80, v153
	v_cvt_pk_bf16_f32 v116, v116, v117
	v_cvt_pk_bf16_f32 v117, v118, v119
	v_cvt_pk_bf16_f32 v118, v108, v109
	v_ashrrev_i32_e32 v108, 1, v120
	v_and_b32_e32 v121, 0xfffffe00, v108
	v_add_u32_e32 v108, v121, v152
	v_ashrrev_i32_e32 v109, 31, v108
	v_lshlrev_b64 v[108:109], 12, v[108:109]
	v_cvt_pk_bf16_f32 v119, v110, v111
	v_lshl_add_u64 v[110:111], s[4:5], 0, v[108:109]
	v_and_b32_e32 v108, 0x3f8, v120
	v_lshlrev_b32_e32 v108, 1, v108
	v_mov_b32_e32 v109, v137
	v_lshl_add_u64 v[110:111], v[110:111], 0, v[108:109]
	global_store_dwordx4 v[110:111], v[116:119], off
	v_cvt_pk_bf16_f32 v110, v112, v113
	v_cvt_pk_bf16_f32 v111, v114, v115
	v_cvt_pk_bf16_f32 v112, v104, v105
	v_cvt_pk_bf16_f32 v113, v106, v107
	s_and_b64 vcc, exec, s[2:3]
	s_nop 0
	v_add_u32_e32 v116, 16, v152
	v_add_u32_e32 v104, v122, v116
	v_ashrrev_i32_e32 v105, 31, v104
	v_lshlrev_b64 v[104:105], 12, v[104:105]
	v_lshl_add_u64 v[104:105], s[4:5], 0, v[104:105]
	v_lshl_add_u64 v[104:105], v[104:105], 0, v[136:137]
	global_store_dwordx4 v[104:105], v[110:113], off
	v_cvt_pk_bf16_f32 v100, v100, v101
	v_cvt_pk_bf16_f32 v101, v102, v103
	v_cvt_pk_bf16_f32 v102, v92, v93
	v_add_u32_e32 v92, v121, v116
	v_ashrrev_i32_e32 v93, 31, v92
	v_lshlrev_b64 v[92:93], 12, v[92:93]
	v_lshl_add_u64 v[92:93], s[4:5], 0, v[92:93]
	v_lshl_add_u64 v[92:93], v[92:93], 0, v[108:109]
	v_cvt_pk_bf16_f32 v103, v94, v95
	global_store_dwordx4 v[92:93], v[100:103], off
	v_cvt_pk_bf16_f32 v92, v96, v97
	v_cvt_pk_bf16_f32 v93, v98, v99
	v_cvt_pk_bf16_f32 v94, v88, v89
	v_cvt_pk_bf16_f32 v95, v90, v91
	s_mov_b32 s45, s6
	s_nop 0
	v_add_u32_e32 v100, 32, v152
	v_add_u32_e32 v88, v122, v100
	v_ashrrev_i32_e32 v89, 31, v88
	v_lshlrev_b64 v[88:89], 12, v[88:89]
	v_lshl_add_u64 v[88:89], s[4:5], 0, v[88:89]
	v_lshl_add_u64 v[88:89], v[88:89], 0, v[136:137]
	global_store_dwordx4 v[88:89], v[92:95], off
	v_cvt_pk_bf16_f32 v84, v84, v85
	v_cvt_pk_bf16_f32 v85, v86, v87
	v_cvt_pk_bf16_f32 v86, v76, v77
	v_add_u32_e32 v76, v121, v100
; __device__ __forceinline__ unsigned cvt_pk_bf16(float lo, float hi) { unsigned r; asm volatile("v_cvt_pk_bf16_f32 %0, %1, %2" : "=v"(r) : "v"(lo), "v"(hi)); return r; }
;     __device__ __forceinline__ void operator()(const AccT& acc, const Unit& u, int wr, int wc, int fr, int fq) const {
;     ...
; #pragma unroll
;         for (int ai = 0; ai < 2; ++ai)
; #pragma unroll
;             for (int m = 0; m < 4; ++m) {
;                 const int gm = rbase + ai * 128 + m * 16;
; #pragma unroll
;                 for (int bj = 0; bj < 2; ++bj) {
;                     const int t0 = tb + bj * 128;
;                     const f32x4 v0 = acc[ai][bj][m][0], v1 = acc[ai][bj][m][1];
;                     u32x4 w; w.x = cvt_pk_bf16(v0[0], v0[1]); w.y = cvt_pk_bf16(v0[2], v0[3]); w.z = cvt_pk_bf16(v1[0], v1[1]); w.w = cvt_pk_bf16(v1[2], v1[3]);
;                     *(u32x4*)(YT + ((size_t)((t0 >> 10) * 512 + gm)) * 2048 + part * 1024 + (t0 & 1023)) = w;
;                 }
	v_ashrrev_i32_e32 v77, 31, v76
	v_lshlrev_b64 v[76:77], 12, v[76:77]
	v_lshl_add_u64 v[76:77], s[4:5], 0, v[76:77]
	v_lshl_add_u64 v[76:77], v[76:77], 0, v[108:109]
	v_cvt_pk_bf16_f32 v87, v78, v79
	global_store_dwordx4 v[76:77], v[84:87], off
	v_cvt_pk_bf16_f32 v76, v80, v81
	v_cvt_pk_bf16_f32 v77, v82, v83
	v_cvt_pk_bf16_f32 v78, v72, v73
	v_cvt_pk_bf16_f32 v79, v74, v75
	s_mov_b32 s16, s8
	s_nop 0
	v_add_u32_e32 v84, 48, v152
	v_add_u32_e32 v72, v122, v84
	v_ashrrev_i32_e32 v73, 31, v72
	v_lshlrev_b64 v[72:73], 12, v[72:73]
	v_lshl_add_u64 v[72:73], s[4:5], 0, v[72:73]
	v_lshl_add_u64 v[72:73], v[72:73], 0, v[136:137]
	global_store_dwordx4 v[72:73], v[76:79], off
	v_cvt_pk_bf16_f32 v68, v68, v69
	v_cvt_pk_bf16_f32 v69, v70, v71
	v_cvt_pk_bf16_f32 v70, v64, v65
	v_add_u32_e32 v64, v121, v84
	v_ashrrev_i32_e32 v65, 31, v64
	v_lshlrev_b64 v[64:65], 12, v[64:65]
	v_lshl_add_u64 v[64:65], s[4:5], 0, v[64:65]
	v_lshl_add_u64 v[64:65], v[64:65], 0, v[108:109]
	v_cvt_pk_bf16_f32 v71, v66, v67
	global_store_dwordx4 v[64:65], v[68:71], off
	v_add_u32_e32 v64, 0x80, v152
	v_cvt_pk_bf16_f32 v60, v60, v61
	v_cvt_pk_bf16_f32 v61, v62, v63
	v_cvt_pk_bf16_f32 v62, v56, v57
	v_add_u32_e32 v56, v122, v64
	v_ashrrev_i32_e32 v57, 31, v56
	v_lshlrev_b64 v[56:57], 12, v[56:57]
	v_lshl_add_u64 v[56:57], s[4:5], 0, v[56:57]
	v_lshl_add_u64 v[56:57], v[56:57], 0, v[136:137]
	v_cvt_pk_bf16_f32 v63, v58, v59
	global_store_dwordx4 v[56:57], v[60:63], off
	v_cvt_pk_bf16_f32 v52, v52, v53
	v_cvt_pk_bf16_f32 v53, v54, v55
	v_cvt_pk_bf16_f32 v54, v44, v45
	v_add_u32_e32 v44, v121, v64
	v_ashrrev_i32_e32 v45, 31, v44
	v_lshlrev_b64 v[44:45], 12, v[44:45]
	v_lshl_add_u64 v[44:45], s[4:5], 0, v[44:45]
	v_lshl_add_u64 v[44:45], v[44:45], 0, v[108:109]
	v_cvt_pk_bf16_f32 v55, v46, v47
	global_store_dwordx4 v[44:45], v[52:55], off
	v_cvt_pk_bf16_f32 v44, v48, v49
	v_cvt_pk_bf16_f32 v45, v50, v51
	v_cvt_pk_bf16_f32 v46, v40, v41
	v_cvt_pk_bf16_f32 v47, v42, v43
	s_mov_b64 s[20:21], s[14:15]
	s_nop 0
	v_add_u32_e32 v52, 0x90, v152
	v_add_u32_e32 v40, v122, v52
	v_ashrrev_i32_e32 v41, 31, v40
	v_lshlrev_b64 v[40:41], 12, v[40:41]
	v_lshl_add_u64 v[40:41], s[4:5], 0, v[40:41]
	v_lshl_add_u64 v[40:41], v[40:41], 0, v[136:137]
	global_store_dwordx4 v[40:41], v[44:47], off
	v_cvt_pk_bf16_f32 v36, v36, v37
	v_cvt_pk_bf16_f32 v37, v38, v39
	v_cvt_pk_bf16_f32 v38, v28, v29
	v_add_u32_e32 v28, v121, v52
	v_ashrrev_i32_e32 v29, 31, v28
	v_lshlrev_b64 v[28:29], 12, v[28:29]
	v_lshl_add_u64 v[28:29], s[4:5], 0, v[28:29]
	v_lshl_add_u64 v[28:29], v[28:29], 0, v[108:109]
	v_cvt_pk_bf16_f32 v39, v30, v31
	global_store_dwordx4 v[28:29], v[36:39], off
	v_cvt_pk_bf16_f32 v28, v32, v33
	v_cvt_pk_bf16_f32 v29, v34, v35
	v_cvt_pk_bf16_f32 v30, v24, v25
	v_cvt_pk_bf16_f32 v31, v26, v27
	s_mov_b64 s[18:19], s[12:13]
	s_nop 0
	v_add_u32_e32 v36, 0xa0, v152
	v_add_u32_e32 v24, v122, v36
	v_ashrrev_i32_e32 v25, 31, v24
	v_lshlrev_b64 v[24:25], 12, v[24:25]
	v_lshl_add_u64 v[24:25], s[4:5], 0, v[24:25]
	v_lshl_add_u64 v[24:25], v[24:25], 0, v[136:137]
	global_store_dwordx4 v[24:25], v[28:31], off
	v_cvt_pk_bf16_f32 v20, v20, v21
	v_cvt_pk_bf16_f32 v21, v22, v23
	v_cvt_pk_bf16_f32 v22, v12, v13
	v_add_u32_e32 v12, v121, v36
	v_ashrrev_i32_e32 v13, 31, v12
	v_lshlrev_b64 v[12:13], 12, v[12:13]
	v_lshl_add_u64 v[12:13], s[4:5], 0, v[12:13]
	v_lshl_add_u64 v[12:13], v[12:13], 0, v[108:109]
	v_cvt_pk_bf16_f32 v23, v14, v15
	global_store_dwordx4 v[12:13], v[20:23], off
	v_cvt_pk_bf16_f32 v12, v16, v17
	v_cvt_pk_bf16_f32 v13, v18, v19
	v_cvt_pk_bf16_f32 v14, v8, v9
	v_cvt_pk_bf16_f32 v15, v10, v11
	s_nop 1
	v_add_u32_e32 v20, 0xb0, v152
	v_add_u32_e32 v8, v122, v20
	v_ashrrev_i32_e32 v9, 31, v8
	v_lshlrev_b64 v[8:9], 12, v[8:9]
	v_lshl_add_u64 v[8:9], s[4:5], 0, v[8:9]
	v_lshl_add_u64 v[8:9], v[8:9], 0, v[136:137]
	global_store_dwordx4 v[8:9], v[12:15], off
	v_cvt_pk_bf16_f32 v4, v4, v5
	v_cvt_pk_bf16_f32 v5, v6, v7
	v_cvt_pk_bf16_f32 v6, v0, v1
	v_add_u32_e32 v0, v121, v20
	v_ashrrev_i32_e32 v1, 31, v0
	v_lshlrev_b64 v[0:1], 12, v[0:1]
	v_lshl_add_u64 v[0:1], s[4:5], 0, v[0:1]
	v_lshl_add_u64 v[0:1], v[0:1], 0, v[108:109]
	v_cvt_pk_bf16_f32 v7, v2, v3
	global_store_dwordx4 v[0:1], v[4:7], off
	s_cbranch_vccz .LBB0_666
	s_branch .Lconc_end_g6
; __device__ __forceinline__ unsigned cvt_pk_bf16(float lo, float hi) { unsigned r; asm volatile("v_cvt_pk_bf16_f32 %0, %1, %2" : "=v"(r) : "v"(lo), "v"(hi)); return r; }
;     __device__ __forceinline__ void operator()(const AccT& acc, const Unit& u, int wr, int wc, int fr, int fq) const {
;     ...
; #pragma unroll
;         for (int ai = 0; ai < 2; ++ai)
; #pragma unroll
;             for (int m = 0; m < 4; ++m) {
;                 const int gm = rbase + ai * 128 + m * 16;
; #pragma unroll
;                 for (int bj = 0; bj < 2; ++bj) {
;                     const int t0 = tb + bj * 128;
;                     const f32x4 v0 = acc[ai][bj][m][0], v1 = acc[ai][bj][m][1];
;                     u32x4 w; w.x = cvt_pk_bf16(v0[0], v0[1]); w.y = cvt_pk_bf16(v0[2], v0[3]); w.z = cvt_pk_bf16(v1[0], v1[1]); w.w = cvt_pk_bf16(v1[2], v1[3]);
;                     *(u32x4*)(YT + ((size_t)((t0 >> 10) * 512 + gm)) * 2048 + part * 1024 + (t0 & 1023)) = w;
;                 }
.Lconc_epi1_g6:
	v_mov_b32_e32 v136, v147
	v_mov_b32_e32 v152, v146
	s_lshl_b32 s7, s16, 8
	s_add_i32 s7, s7, s34
	v_add_u32_e32 v152, s7, v152
	s_lshl_b32 s7, s45, 8
	s_or_b32 s7, s7, s35
	v_lshl_add_u32 v153, v136, 3, s7
	v_cvt_pk_bf16_f32 v124, v124, v125
	v_cvt_pk_bf16_f32 v125, v126, v127
	v_cvt_pk_bf16_f32 v126, v120, v121
	v_ashrrev_i32_e32 v120, 1, v153
	v_cvt_pk_bf16_f32 v127, v122, v123
	v_and_b32_e32 v122, 0xfffffe00, v120
	v_add_u32_e32 v120, v122, v152
	v_ashrrev_i32_e32 v121, 31, v120
	v_lshlrev_b64 v[120:121], 12, v[120:121]
	v_and_b32_e32 v123, 0x3f8, v153
	v_lshl_add_u64 v[120:121], s[4:5], 0, v[120:121]
	v_lshlrev_b32_e32 v136, 1, v123
	v_lshl_add_u64 v[120:121], v[120:121], 0, v[136:137]
	global_store_dwordx4 v[120:121], v[124:127], off
	v_add_u32_e32 v120, 0x80, v153
	v_cvt_pk_bf16_f32 v116, v116, v117
	v_cvt_pk_bf16_f32 v117, v118, v119
	v_cvt_pk_bf16_f32 v118, v108, v109
	v_ashrrev_i32_e32 v108, 1, v120
	v_and_b32_e32 v121, 0xfffffe00, v108
	v_add_u32_e32 v108, v121, v152
	v_ashrrev_i32_e32 v109, 31, v108
	v_lshlrev_b64 v[108:109], 12, v[108:109]
	v_cvt_pk_bf16_f32 v119, v110, v111
	v_lshl_add_u64 v[110:111], s[4:5], 0, v[108:109]
	v_and_b32_e32 v108, 0x3f8, v120
	v_lshlrev_b32_e32 v108, 1, v108
	v_mov_b32_e32 v109, v137
	v_lshl_add_u64 v[110:111], v[110:111], 0, v[108:109]
	global_store_dwordx4 v[110:111], v[116:119], off
	v_cvt_pk_bf16_f32 v110, v112, v113
	v_cvt_pk_bf16_f32 v111, v114, v115
	v_cvt_pk_bf16_f32 v112, v104, v105
	v_cvt_pk_bf16_f32 v113, v106, v107
	s_and_b64 vcc, exec, s[2:3]
	s_nop 0
	v_add_u32_e32 v116, 16, v152
	v_add_u32_e32 v104, v122, v116
	v_ashrrev_i32_e32 v105, 31, v104
	v_lshlrev_b64 v[104:105], 12, v[104:105]
	v_lshl_add_u64 v[104:105], s[4:5], 0, v[104:105]
	v_lshl_add_u64 v[104:105], v[104:105], 0, v[136:137]
	global_store_dwordx4 v[104:105], v[110:113], off
	v_cvt_pk_bf16_f32 v100, v100, v101
	v_cvt_pk_bf16_f32 v101, v102, v103
	v_cvt_pk_bf16_f32 v102, v92, v93
	v_add_u32_e32 v92, v121, v116
	v_ashrrev_i32_e32 v93, 31, v92
	v_lshlrev_b64 v[92:93], 12, v[92:93]
	v_lshl_add_u64 v[92:93], s[4:5], 0, v[92:93]
	v_lshl_add_u64 v[92:93], v[92:93], 0, v[108:109]
	v_cvt_pk_bf16_f32 v103, v94, v95
	global_store_dwordx4 v[92:93], v[100:103], off
	v_cvt_pk_bf16_f32 v92, v96, v97
	v_cvt_pk_bf16_f32 v93, v98, v99
	v_cvt_pk_bf16_f32 v94, v88, v89
	v_cvt_pk_bf16_f32 v95, v90, v91
	s_mov_b32 s45, s6
	s_nop 0
	v_add_u32_e32 v100, 32, v152
	v_add_u32_e32 v88, v122, v100
	v_ashrrev_i32_e32 v89, 31, v88
	v_lshlrev_b64 v[88:89], 12, v[88:89]
	v_lshl_add_u64 v[88:89], s[4:5], 0, v[88:89]
	v_lshl_add_u64 v[88:89], v[88:89], 0, v[136:137]
	global_store_dwordx4 v[88:89], v[92:95], off
	v_cvt_pk_bf16_f32 v84, v84, v85
	v_cvt_pk_bf16_f32 v85, v86, v87
	v_cvt_pk_bf16_f32 v86, v76, v77
	v_add_u32_e32 v76, v121, v100
	v_ashrrev_i32_e32 v77, 31, v76
	v_lshlrev_b64 v[76:77], 12, v[76:77]
	v_lshl_add_u64 v[76:77], s[4:5], 0, v[76:77]
	v_lshl_add_u64 v[76:77], v[76:77], 0, v[108:109]
	v_cvt_pk_bf16_f32 v87, v78, v79
	global_store_dwordx4 v[76:77], v[84:87], off
	v_cvt_pk_bf16_f32 v76, v80, v81
	v_cvt_pk_bf16_f32 v77, v82, v83
	v_cvt_pk_bf16_f32 v78, v72, v73
	v_cvt_pk_bf16_f32 v79, v74, v75
	s_mov_b32 s16, s8
	s_nop 0
	v_add_u32_e32 v84, 48, v152
	v_add_u32_e32 v72, v122, v84
	v_ashrrev_i32_e32 v73, 31, v72
	v_lshlrev_b64 v[72:73], 12, v[72:73]
	v_lshl_add_u64 v[72:73], s[4:5], 0, v[72:73]
	v_lshl_add_u64 v[72:73], v[72:73], 0, v[136:137]
	global_store_dwordx4 v[72:73], v[76:79], off
	v_cvt_pk_bf16_f32 v68, v68, v69
	v_cvt_pk_bf16_f32 v69, v70, v71
	v_cvt_pk_bf16_f32 v70, v64, v65
	v_add_u32_e32 v64, v121, v84
	v_ashrrev_i32_e32 v65, 31, v64
	v_lshlrev_b64 v[64:65], 12, v[64:65]
	v_lshl_add_u64 v[64:65], s[4:5], 0, v[64:65]
	v_lshl_add_u64 v[64:65], v[64:65], 0, v[108:109]
	v_cvt_pk_bf16_f32 v71, v66, v67
	global_store_dwordx4 v[64:65], v[68:71], off
	v_add_u32_e32 v64, 0x80, v152
	v_cvt_pk_bf16_f32 v60, v60, v61
	v_cvt_pk_bf16_f32 v61, v62, v63
	v_cvt_pk_bf16_f32 v62, v56, v57
	v_add_u32_e32 v56, v122, v64
	v_ashrrev_i32_e32 v57, 31, v56
	v_lshlrev_b64 v[56:57], 12, v[56:57]
	v_lshl_add_u64 v[56:57], s[4:5], 0, v[56:57]
	v_lshl_add_u64 v[56:57], v[56:57], 0, v[136:137]
	v_cvt_pk_bf16_f32 v63, v58, v59
	global_store_dwordx4 v[56:57], v[60:63], off
	v_cvt_pk_bf16_f32 v52, v52, v53
	v_cvt_pk_bf16_f32 v53, v54, v55
	v_cvt_pk_bf16_f32 v54, v44, v45
	v_add_u32_e32 v44, v121, v64
	v_ashrrev_i32_e32 v45, 31, v44
	v_lshlrev_b64 v[44:45], 12, v[44:45]
	v_lshl_add_u64 v[44:45], s[4:5], 0, v[44:45]
	v_lshl_add_u64 v[44:45], v[44:45], 0, v[108:109]
	v_cvt_pk_bf16_f32 v55, v46, v47
	global_store_dwordx4 v[44:45], v[52:55], off
	v_cvt_pk_bf16_f32 v44, v48, v49
	v_cvt_pk_bf16_f32 v45, v50, v51
	v_cvt_pk_bf16_f32 v46, v40, v41
	v_cvt_pk_bf16_f32 v47, v42, v43
	s_mov_b64 s[20:21], s[14:15]
	s_nop 0
	v_add_u32_e32 v52, 0x90, v152
	v_add_u32_e32 v40, v122, v52
	v_ashrrev_i32_e32 v41, 31, v40
	v_lshlrev_b64 v[40:41], 12, v[40:41]
	v_lshl_add_u64 v[40:41], s[4:5], 0, v[40:41]
	v_lshl_add_u64 v[40:41], v[40:41], 0, v[136:137]
	global_store_dwordx4 v[40:41], v[44:47], off
	v_cvt_pk_bf16_f32 v36, v36, v37
	v_cvt_pk_bf16_f32 v37, v38, v39
	v_cvt_pk_bf16_f32 v38, v28, v29
	v_add_u32_e32 v28, v121, v52
	v_ashrrev_i32_e32 v29, 31, v28
	v_lshlrev_b64 v[28:29], 12, v[28:29]
	v_lshl_add_u64 v[28:29], s[4:5], 0, v[28:29]
	v_lshl_add_u64 v[28:29], v[28:29], 0, v[108:109]
	v_cvt_pk_bf16_f32 v39, v30, v31
	global_store_dwordx4 v[28:29], v[36:39], off
	v_cvt_pk_bf16_f32 v28, v32, v33
	v_cvt_pk_bf16_f32 v29, v34, v35
	v_cvt_pk_bf16_f32 v30, v24, v25
	v_cvt_pk_bf16_f32 v31, v26, v27
	s_mov_b64 s[18:19], s[12:13]
	s_nop 0
	v_add_u32_e32 v36, 0xa0, v152
	v_add_u32_e32 v24, v122, v36
	v_ashrrev_i32_e32 v25, 31, v24
	v_lshlrev_b64 v[24:25], 12, v[24:25]
	v_lshl_add_u64 v[24:25], s[4:5], 0, v[24:25]
	v_lshl_add_u64 v[24:25], v[24:25], 0, v[136:137]
	global_store_dwordx4 v[24:25], v[28:31], off
	v_cvt_pk_bf16_f32 v20, v20, v21
	v_cvt_pk_bf16_f32 v21, v22, v23
	v_cvt_pk_bf16_f32 v22, v12, v13
	v_add_u32_e32 v12, v121, v36
	v_ashrrev_i32_e32 v13, 31, v12
	v_lshlrev_b64 v[12:13], 12, v[12:13]
	v_lshl_add_u64 v[12:13], s[4:5], 0, v[12:13]
	v_lshl_add_u64 v[12:13], v[12:13], 0, v[108:109]
	v_cvt_pk_bf16_f32 v23, v14, v15
	global_store_dwordx4 v[12:13], v[20:23], off
	v_cvt_pk_bf16_f32 v12, v16, v17
	v_cvt_pk_bf16_f32 v13, v18, v19
	v_cvt_pk_bf16_f32 v14, v8, v9
	v_cvt_pk_bf16_f32 v15, v10, v11
	s_nop 1
	v_add_u32_e32 v20, 0xb0, v152
	v_add_u32_e32 v8, v122, v20
	v_ashrrev_i32_e32 v9, 31, v8
	v_lshlrev_b64 v[8:9], 12, v[8:9]
	v_lshl_add_u64 v[8:9], s[4:5], 0, v[8:9]
	v_lshl_add_u64 v[8:9], v[8:9], 0, v[136:137]
	global_store_dwordx4 v[8:9], v[12:15], off
	v_cvt_pk_bf16_f32 v4, v4, v5
	v_cvt_pk_bf16_f32 v5, v6, v7
	v_cvt_pk_bf16_f32 v6, v0, v1
	v_add_u32_e32 v0, v121, v20
	v_ashrrev_i32_e32 v1, 31, v0
	v_lshlrev_b64 v[0:1], 12, v[0:1]
	v_lshl_add_u64 v[0:1], s[4:5], 0, v[0:1]
	v_lshl_add_u64 v[0:1], v[0:1], 0, v[108:109]
	v_cvt_pk_bf16_f32 v7, v2, v3
	global_store_dwordx4 v[0:1], v[4:7], off
	s_barrier
	s_cbranch_vccz .LBB0_666

; #define PG8_STAGE(bufoff, gbase, voff) do { _Pragma("unroll") for (int _i = 0; _i < 2; ++_i) \
;         __builtin_amdgcn_global_load_lds((const unsigned*)((const char*)(gbase) + (voff)[_i]), (LAS unsigned*)(lds + (bufoff) + ldsw + _i * 8192), 16, 0, 0); } while (0)
; #define PG8_LDA(dst, b, h) do { _Pragma("unroll") for (int m = 0; m < 4; ++m) _Pragma("unroll") for (int k = 0; k < 2; ++k) dst[m][k] = *(const LAS bf16x8*)(lds + PG8_SA(b, h) + aoff + m * 2048 + k * 1024); } while (0)
; #define PG8_LDB(dst, b, h) do { _Pragma("unroll") for (int n = 0; n < 2; ++n) _Pragma("unroll") for (int k = 0; k < 2; ++k) dst[n][k] = *(const LAS bf16x8*)(lds + PG8_SB(b, h) + boff + n * 2048 + k * 1024); } while (0)
; #define PG8_MMA(ai, bj, At, Bt) do { __builtin_amdgcn_s_setprio(1); _Pragma("unroll") for (int m = 0; m < 4; ++m) _Pragma("unroll") for (int n = 0; n < 2; ++n) _Pragma("unroll") for (int k = 0; k < 2; ++k) \
;         acc[ai][bj][m][n] = __builtin_amdgcn_mfma_f32_16x16x32_bf16(Bt[n][k], At[m][k], acc[ai][bj][m][n], 0, 0, 0); __builtin_amdgcn_s_setprio(0); } while (0)
; #define PG8_WAIT_V(n) asm volatile("s_waitcnt vmcnt(" #n ")" ::: "memory")
; #define PG8_WAIT_L(n) asm volatile("s_waitcnt lgkmcnt(" #n ")" ::: "memory")
; #define PG8_BAR __builtin_amdgcn_s_barrier()
; #define PG8_SCHED __builtin_amdgcn_sched_barrier(0)
; template <class Epi, class Sched>
; __device__ __forceinline__ void gemm_phase(LAS unsigned char* lds, const Gemm g, const Sched& S, const Epi& E) {
;     ...
;             PG8_LDB(B0, 0, 0); PG8_SCHED; PG8_LDA(At, 0, 0); PG8_STAGE(PG8_SA(1, 1), a1 + hstep, voffA);
;             PG8_WAIT_L(8); PG8_BAR; PG8_WAIT_L(0); PG8_MMA(0, 0, At, B0); PG8_BAR; PG8_SCHED;
;             PG8_LDB(B1, 0, 1); PG8_STAGE(PG8_SB(0, 0), b2, voffB);
;             PG8_BAR; PG8_WAIT_L(0); PG8_MMA(0, 1, At, B1); PG8_BAR;
;             PG8_LDA(At, 0, 1); PG8_STAGE(PG8_SA(0, 0), a2, voffA);
;             PG8_BAR; PG8_WAIT_L(0); PG8_MMA(1, 0, At, B0); PG8_BAR; PG8_SCHED;
;             PG8_STAGE(PG8_SB(0, 1), b2 + hstep, voffB);
;             PG8_WAIT_V(6); PG8_BAR; PG8_MMA(1, 1, At, B1); PG8_BAR;
.LBB0_693:
	ds_read_b128 v[140:143], v149
	ds_read_b128 v[154:157], v149 offset:1024
	ds_read_b128 v[158:161], v149 offset:2048
	ds_read_b128 v[162:165], v149 offset:3072
	s_add_u32 s4, s2, 0xfffc0080
	s_addc_u32 s5, s3, -1
	s_cmp_eq_u32 s61, 12
	s_cselect_b32 s25, s19, s5
	s_cselect_b32 s24, s57, s4
	s_cselect_b32 s5, s17, s60
	s_cselect_b32 s4, s58, s59
	s_add_i32 m0, s33, 0xc000
	ds_read_b128 v[166:169], v150
	ds_read_b128 v[170:173], v150 offset:1024
	ds_read_b128 v[174:177], v150 offset:2048
	ds_read_b128 v[178:181], v150 offset:3072
	ds_read_b128 v[182:185], v150 offset:4096
	ds_read_b128 v[186:189], v150 offset:5120
	ds_read_b128 v[190:193], v150 offset:6144
	ds_read_b128 v[194:197], v150 offset:7168
	global_load_lds_dwordx4 v136, s[2:3]
	s_add_i32 m0, s33, 0xe000
	s_nop 0
	global_load_lds_dwordx4 v138, s[2:3]
	s_waitcnt lgkmcnt(8)
	s_waitcnt vmcnt(10)
	s_barrier
	s_waitcnt lgkmcnt(0)
	s_setprio 1
	s_waitcnt lgkmcnt(0)
	v_mfma_f32_16x16x32_bf16 v[124:127], v[140:143], v[166:169], v[124:127]
	v_mfma_f32_16x16x32_bf16 v[120:123], v[158:161], v[166:169], v[120:123]
	v_mfma_f32_16x16x32_bf16 v[108:111], v[140:143], v[174:177], v[108:111]
	v_mfma_f32_16x16x32_bf16 v[104:107], v[158:161], v[174:177], v[104:107]
	v_mfma_f32_16x16x32_bf16 v[92:95], v[140:143], v[182:185], v[92:95]
	v_mfma_f32_16x16x32_bf16 v[88:91], v[158:161], v[182:185], v[88:91]
	v_mfma_f32_16x16x32_bf16 v[76:79], v[140:143], v[190:193], v[76:79]
	v_mfma_f32_16x16x32_bf16 v[72:75], v[158:161], v[190:193], v[72:75]
	v_mfma_f32_16x16x32_bf16 v[124:127], v[154:157], v[170:173], v[124:127]
	v_mfma_f32_16x16x32_bf16 v[120:123], v[162:165], v[170:173], v[120:123]
	v_mfma_f32_16x16x32_bf16 v[108:111], v[154:157], v[178:181], v[108:111]
	v_mfma_f32_16x16x32_bf16 v[104:107], v[162:165], v[178:181], v[104:107]
	v_mfma_f32_16x16x32_bf16 v[92:95], v[154:157], v[186:189], v[92:95]
	v_mfma_f32_16x16x32_bf16 v[88:91], v[162:165], v[186:189], v[88:91]
	v_mfma_f32_16x16x32_bf16 v[76:79], v[154:157], v[194:197], v[76:79]
	v_mfma_f32_16x16x32_bf16 v[72:75], v[162:165], v[194:197], v[72:75]
	s_setprio 0
	s_barrier
	s_add_i32 s62, s47, s31
	s_mov_b32 m0, s62
	ds_read_b128 v[202:205], v151
	ds_read_b128 v[206:209], v151 offset:1024
	ds_read_b128 v[210:213], v151 offset:2048
	ds_read_b128 v[214:217], v151 offset:3072
	global_load_lds_dwordx4 v130, s[4:5]
	s_add_i32 m0, s62, 0x2000
	s_nop 0
	global_load_lds_dwordx4 v134, s[4:5]
	s_waitcnt vmcnt(10)
	s_barrier
	s_waitcnt lgkmcnt(0)
	s_setprio 1
	s_waitcnt lgkmcnt(0)
	v_mfma_f32_16x16x32_bf16 v[116:119], v[202:205], v[166:169], v[116:119]
	v_mfma_f32_16x16x32_bf16 v[112:115], v[210:213], v[166:169], v[112:115]
	v_mfma_f32_16x16x32_bf16 v[100:103], v[202:205], v[174:177], v[100:103]
	v_mfma_f32_16x16x32_bf16 v[96:99], v[210:213], v[174:177], v[96:99]
	v_mfma_f32_16x16x32_bf16 v[84:87], v[202:205], v[182:185], v[84:87]
	v_mfma_f32_16x16x32_bf16 v[80:83], v[210:213], v[182:185], v[80:83]
	v_mfma_f32_16x16x32_bf16 v[68:71], v[202:205], v[190:193], v[68:71]
	v_mfma_f32_16x16x32_bf16 v[64:67], v[210:213], v[190:193], v[64:67]
	v_mfma_f32_16x16x32_bf16 v[116:119], v[206:209], v[170:173], v[116:119]
	v_mfma_f32_16x16x32_bf16 v[112:115], v[214:217], v[170:173], v[112:115]
	v_mfma_f32_16x16x32_bf16 v[100:103], v[206:209], v[178:181], v[100:103]
	v_mfma_f32_16x16x32_bf16 v[96:99], v[214:217], v[178:181], v[96:99]
	v_mfma_f32_16x16x32_bf16 v[84:87], v[206:209], v[186:189], v[84:87]
	v_mfma_f32_16x16x32_bf16 v[80:83], v[214:217], v[186:189], v[80:83]
	v_mfma_f32_16x16x32_bf16 v[68:71], v[206:209], v[194:197], v[68:71]
	v_mfma_f32_16x16x32_bf16 v[64:67], v[214:217], v[194:197], v[64:67]
	s_setprio 0
	s_mov_b32 m0, s33
	v_lshl_add_u64 v[218:219], s[24:25], 0, v[128:129]
	s_barrier
	ds_read_b128 v[166:169], v150 offset:16384
	ds_read_b128 v[170:173], v150 offset:17408
	ds_read_b128 v[174:177], v150 offset:18432
	ds_read_b128 v[178:181], v150 offset:19456
	ds_read_b128 v[182:185], v150 offset:20480
	ds_read_b128 v[186:189], v150 offset:21504
	ds_read_b128 v[190:193], v150 offset:22528
	ds_read_b128 v[194:197], v150 offset:23552
	global_load_lds_dwordx4 v128, s[24:25]
	v_lshl_add_u64 v[220:221], s[24:25], 0, v[132:133]
	s_mov_b32 m0, s34
	s_nop 0
	global_load_lds_dwordx4 v132, s[24:25]
	s_barrier
	s_waitcnt lgkmcnt(0)
	s_setprio 1
	s_waitcnt lgkmcnt(0)
	v_mfma_f32_16x16x32_bf16 v[60:63], v[140:143], v[166:169], v[60:63]
	v_mfma_f32_16x16x32_bf16 v[56:59], v[158:161], v[166:169], v[56:59]
	v_mfma_f32_16x16x32_bf16 v[44:47], v[140:143], v[174:177], v[44:47]
	v_mfma_f32_16x16x32_bf16 v[40:43], v[158:161], v[174:177], v[40:43]
	v_mfma_f32_16x16x32_bf16 v[28:31], v[140:143], v[182:185], v[28:31]
	v_mfma_f32_16x16x32_bf16 v[24:27], v[158:161], v[182:185], v[24:27]
	v_mfma_f32_16x16x32_bf16 v[12:15], v[140:143], v[190:193], v[12:15]
	v_mfma_f32_16x16x32_bf16 v[8:11], v[158:161], v[190:193], v[8:11]
	v_mfma_f32_16x16x32_bf16 v[60:63], v[154:157], v[170:173], v[60:63]
	v_mfma_f32_16x16x32_bf16 v[56:59], v[162:165], v[170:173], v[56:59]
	v_mfma_f32_16x16x32_bf16 v[44:47], v[154:157], v[178:181], v[44:47]
	v_mfma_f32_16x16x32_bf16 v[40:43], v[162:165], v[178:181], v[40:43]
	v_mfma_f32_16x16x32_bf16 v[28:31], v[154:157], v[186:189], v[28:31]
	v_mfma_f32_16x16x32_bf16 v[24:27], v[162:165], v[186:189], v[24:27]
	v_mfma_f32_16x16x32_bf16 v[12:15], v[154:157], v[194:197], v[12:15]
	v_mfma_f32_16x16x32_bf16 v[8:11], v[162:165], v[194:197], v[8:11]
	s_setprio 0
	s_barrier
; #define PG8_STAGE(bufoff, gbase, voff) do { _Pragma("unroll") for (int _i = 0; _i < 2; ++_i) \
;         __builtin_amdgcn_global_load_lds((const unsigned*)((const char*)(gbase) + (voff)[_i]), (LAS unsigned*)(lds + (bufoff) + ldsw + _i * 8192), 16, 0, 0); } while (0)
; #define PG8_LDA(dst, b, h) do { _Pragma("unroll") for (int m = 0; m < 4; ++m) _Pragma("unroll") for (int k = 0; k < 2; ++k) dst[m][k] = *(const LAS bf16x8*)(lds + PG8_SA(b, h) + aoff + m * 2048 + k * 1024); } while (0)
; #define PG8_LDB(dst, b, h) do { _Pragma("unroll") for (int n = 0; n < 2; ++n) _Pragma("unroll") for (int k = 0; k < 2; ++k) dst[n][k] = *(const LAS bf16x8*)(lds + PG8_SB(b, h) + boff + n * 2048 + k * 1024); } while (0)
; #define PG8_MMA(ai, bj, At, Bt) do { __builtin_amdgcn_s_setprio(1); _Pragma("unroll") for (int m = 0; m < 4; ++m) _Pragma("unroll") for (int n = 0; n < 2; ++n) _Pragma("unroll") for (int k = 0; k < 2; ++k) \
;         acc[ai][bj][m][n] = __builtin_amdgcn_mfma_f32_16x16x32_bf16(Bt[n][k], At[m][k], acc[ai][bj][m][n], 0, 0, 0); __builtin_amdgcn_s_setprio(0); } while (0)
; #define PG8_WAIT_V(n) asm volatile("s_waitcnt vmcnt(" #n ")" ::: "memory")
; #define PG8_WAIT_L(n) asm volatile("s_waitcnt lgkmcnt(" #n ")" ::: "memory")
; #define PG8_BAR __builtin_amdgcn_s_barrier()
; #define PG8_SCHED __builtin_amdgcn_sched_barrier(0)
; template <class Epi, class Sched>
; __device__ __forceinline__ void gemm_phase(LAS unsigned char* lds, const Gemm g, const Sched& S, const Epi& E) {
;     ...
;             PG8_STAGE(PG8_SB(0, 1), b2 + hstep, voffB);
;             PG8_WAIT_V(6); PG8_BAR; PG8_MMA(1, 1, At, B1); PG8_BAR;
;             PG8_LDB(B0, 1, 0); PG8_SCHED; PG8_LDA(At, 1, 0); PG8_STAGE(PG8_SA(0, 1), a2 + hstep, voffA);
;             PG8_WAIT_L(8); PG8_BAR; PG8_WAIT_L(0); PG8_MMA(0, 0, At, B0); PG8_BAR; PG8_SCHED;
;             PG8_LDB(B1, 1, 1); PG8_STAGE(PG8_SB(1, 0), b3, voffB);
;             PG8_BAR; PG8_WAIT_L(0); PG8_MMA(0, 1, At, B1); PG8_BAR;
;             PG8_LDA(At, 1, 1); PG8_STAGE(PG8_SA(1, 0), a3, voffA);
;             PG8_BAR; PG8_WAIT_L(0); PG8_MMA(1, 0, At, B0); PG8_BAR; PG8_SCHED;
	s_add_u32 s62, s4, 0x40000
	s_addc_u32 s63, s5, 0
	s_add_i32 s64, s48, s31
	s_mov_b32 m0, s64
	s_nop 0
	global_load_lds_dwordx4 v130, s[62:63]
	s_add_i32 m0, s64, 0x2000
	s_nop 0
	global_load_lds_dwordx4 v134, s[62:63]
	s_add_u32 s24, s24, 0x40000
	s_addc_u32 s25, s25, 0
	s_mov_b32 m0, s35
	s_nop 0
	global_load_lds_dwordx4 v128, s[24:25]
	s_mov_b32 m0, s36
	s_nop 0
	global_load_lds_dwordx4 v132, s[24:25]
	s_waitcnt vmcnt(12)
	s_barrier
	s_setprio 1
	v_mfma_f32_16x16x32_bf16 v[52:55], v[202:205], v[166:169], v[52:55]
	v_mfma_f32_16x16x32_bf16 v[48:51], v[210:213], v[166:169], v[48:51]
	v_mfma_f32_16x16x32_bf16 v[36:39], v[202:205], v[174:177], v[36:39]
	v_mfma_f32_16x16x32_bf16 v[32:35], v[210:213], v[174:177], v[32:35]
	v_mfma_f32_16x16x32_bf16 v[20:23], v[202:205], v[182:185], v[20:23]
	v_mfma_f32_16x16x32_bf16 v[16:19], v[210:213], v[182:185], v[16:19]
	v_mfma_f32_16x16x32_bf16 v[4:7], v[202:205], v[190:193], v[4:7]
	v_mfma_f32_16x16x32_bf16 v[0:3], v[210:213], v[190:193], v[0:3]
	v_mfma_f32_16x16x32_bf16 v[52:55], v[206:209], v[170:173], v[52:55]
	v_mfma_f32_16x16x32_bf16 v[48:51], v[214:217], v[170:173], v[48:51]
	v_mfma_f32_16x16x32_bf16 v[36:39], v[206:209], v[178:181], v[36:39]
	v_mfma_f32_16x16x32_bf16 v[32:35], v[214:217], v[178:181], v[32:35]
	v_mfma_f32_16x16x32_bf16 v[20:23], v[206:209], v[186:189], v[20:23]
	v_mfma_f32_16x16x32_bf16 v[16:19], v[214:217], v[186:189], v[16:19]
	v_mfma_f32_16x16x32_bf16 v[4:7], v[206:209], v[194:197], v[4:7]
	v_mfma_f32_16x16x32_bf16 v[0:3], v[214:217], v[194:197], v[0:3]
	s_setprio 0
	s_add_i32 s62, 0, 0x18000
	v_add_u32_e32 v162, s62, v148
	s_barrier
	ds_read_b128 v[140:143], v162
	ds_read_b128 v[154:157], v162 offset:1024
	ds_read_b128 v[158:161], v162 offset:2048
	ds_read_b128 v[162:165], v162 offset:3072
	ds_read_b128 v[166:169], v150 offset:32768
	ds_read_b128 v[170:173], v150 offset:33792
	ds_read_b128 v[174:177], v150 offset:34816
	ds_read_b128 v[178:181], v150 offset:35840
	ds_read_b128 v[182:185], v150 offset:36864
	ds_read_b128 v[186:189], v150 offset:37888
	ds_read_b128 v[190:193], v150 offset:38912
	ds_read_b128 v[194:197], v150 offset:39936
	s_waitcnt lgkmcnt(8)
	s_waitcnt vmcnt(10)
	s_barrier
	s_waitcnt lgkmcnt(0)
	s_setprio 1
	s_waitcnt lgkmcnt(0)
	v_mfma_f32_16x16x32_bf16 v[124:127], v[140:143], v[166:169], v[124:127]
	v_mfma_f32_16x16x32_bf16 v[120:123], v[158:161], v[166:169], v[120:123]
	v_mfma_f32_16x16x32_bf16 v[108:111], v[140:143], v[174:177], v[108:111]
	v_mfma_f32_16x16x32_bf16 v[104:107], v[158:161], v[174:177], v[104:107]
	v_mfma_f32_16x16x32_bf16 v[92:95], v[140:143], v[182:185], v[92:95]
	v_mfma_f32_16x16x32_bf16 v[88:91], v[158:161], v[182:185], v[88:91]
	v_mfma_f32_16x16x32_bf16 v[76:79], v[140:143], v[190:193], v[76:79]
	v_mfma_f32_16x16x32_bf16 v[72:75], v[158:161], v[190:193], v[72:75]
	v_mfma_f32_16x16x32_bf16 v[124:127], v[154:157], v[170:173], v[124:127]
	v_mfma_f32_16x16x32_bf16 v[120:123], v[162:165], v[170:173], v[120:123]
	v_mfma_f32_16x16x32_bf16 v[108:111], v[154:157], v[178:181], v[108:111]
	v_mfma_f32_16x16x32_bf16 v[104:107], v[162:165], v[178:181], v[104:107]
	v_mfma_f32_16x16x32_bf16 v[92:95], v[154:157], v[186:189], v[92:95]
	v_mfma_f32_16x16x32_bf16 v[88:91], v[162:165], v[186:189], v[88:91]
	v_mfma_f32_16x16x32_bf16 v[76:79], v[154:157], v[194:197], v[76:79]
	v_mfma_f32_16x16x32_bf16 v[72:75], v[162:165], v[194:197], v[72:75]
	s_setprio 0
	s_barrier
	s_add_i32 s24, 0, 0x1c000
	s_add_i32 s25, s62, s31
	v_add_u32_e32 v214, s24, v148
	s_add_u32 s0, s4, 0x80
	s_addc_u32 s1, s5, 0
	s_mov_b32 m0, s25
	ds_read_b128 v[202:205], v214
	ds_read_b128 v[206:209], v214 offset:1024
	ds_read_b128 v[210:213], v214 offset:2048
	ds_read_b128 v[214:217], v214 offset:3072
	global_load_lds_dwordx4 v130, s[0:1]
	s_add_i32 m0, s25, 0x2000
	s_nop 0
	global_load_lds_dwordx4 v134, s[0:1]
	s_waitcnt vmcnt(10)
	s_barrier
	s_waitcnt lgkmcnt(0)
	s_setprio 1
	s_waitcnt lgkmcnt(0)
	v_mfma_f32_16x16x32_bf16 v[116:119], v[202:205], v[166:169], v[116:119]
	v_mfma_f32_16x16x32_bf16 v[112:115], v[210:213], v[166:169], v[112:115]
	v_mfma_f32_16x16x32_bf16 v[100:103], v[202:205], v[174:177], v[100:103]
	v_mfma_f32_16x16x32_bf16 v[96:99], v[210:213], v[174:177], v[96:99]
	v_mfma_f32_16x16x32_bf16 v[84:87], v[202:205], v[182:185], v[84:87]
	v_mfma_f32_16x16x32_bf16 v[80:83], v[210:213], v[182:185], v[80:83]
	v_mfma_f32_16x16x32_bf16 v[68:71], v[202:205], v[190:193], v[68:71]
	v_mfma_f32_16x16x32_bf16 v[64:67], v[210:213], v[190:193], v[64:67]
	v_mfma_f32_16x16x32_bf16 v[116:119], v[206:209], v[170:173], v[116:119]
	v_mfma_f32_16x16x32_bf16 v[112:115], v[214:217], v[170:173], v[112:115]
	v_mfma_f32_16x16x32_bf16 v[100:103], v[206:209], v[178:181], v[100:103]
	v_mfma_f32_16x16x32_bf16 v[96:99], v[214:217], v[178:181], v[96:99]
	v_mfma_f32_16x16x32_bf16 v[84:87], v[206:209], v[186:189], v[84:87]
	v_mfma_f32_16x16x32_bf16 v[80:83], v[214:217], v[186:189], v[80:83]
	v_mfma_f32_16x16x32_bf16 v[68:71], v[206:209], v[194:197], v[68:71]
	v_mfma_f32_16x16x32_bf16 v[64:67], v[214:217], v[194:197], v[64:67]
	s_setprio 0
	s_mov_b32 m0, s44
	s_mov_b64 s[0:1], 0x80
	v_lshl_add_u64 v[144:145], v[218:219], 0, s[0:1]
	s_barrier
	ds_read_b128 v[166:169], v150 offset:49152
	ds_read_b128 v[170:173], v150 offset:50176
	ds_read_b128 v[174:177], v150 offset:51200
	ds_read_b128 v[178:181], v150 offset:52224
	ds_read_b128 v[182:185], v150 offset:53248
	ds_read_b128 v[186:189], v150 offset:54272
	ds_read_b128 v[190:193], v150 offset:55296
	ds_read_b128 v[194:197], v150 offset:56320
	global_load_lds_dwordx4 v[144:145], off
	v_lshl_add_u64 v[144:145], v[220:221], 0, s[0:1]
	s_mov_b32 m0, s45
	s_nop 0
	global_load_lds_dwordx4 v[144:145], off
	s_barrier
; template <class Epi, class Sched>
; __device__ __forceinline__ void gemm_phase(LAS unsigned char* lds, const Gemm g, const Sched& S, const Epi& E) {
;     ...
;             PG8_BAR; PG8_WAIT_L(0); PG8_MMA(1, 0, At, B0); PG8_BAR; PG8_SCHED;
;             PG8_STAGE(PG8_SB(1, 1), b3 + hstep, voffB);
;             PG8_WAIT_V(6); PG8_BAR; PG8_MMA(1, 1, At, B1); PG8_BAR;
;     __device__ __forceinline__ void operator()(const AccT& acc, const Unit& u, int wr, int wc, int fr, int fq) const {
;     ...
; #pragma unroll
;         for (int ai = 0; ai < 2; ++ai) {
;             const int hh = 2 * ai + wr;
;             const float l2f = lgd[hh] * 1.4426950408889634f, l2b = lgd[4 + hh] * 1.4426950408889634f;
;             const float zf0 = exp2f((float)(127 - o0) * l2f), zfs = exp2f(-l2f), zb0 = exp2f((float)o0 * l2b), zbs = exp2f(l2b);
; #pragma unroll
;             for (int m = 0; m < 4; ++m) {
;                 const int r = rbase + ai * 128 + m * 16;
;                 const int d = 4 * (2 * m + (fr >> 3)) + j;
; #pragma unroll
;                 for (int bj = 0; bj < 2; ++bj) {
;                     const int t0 = tb + bj * 128;
;                     float v[8];
; #pragma unroll
;                     for (int jj = 0; jj < 4; ++jj) { v[jj] = acc[ai][bj][m][0][jj]; v[4 + jj] = acc[ai][bj][m][1][jj]; }
;                     if constexpr (ROPE) {
;                         const int t = t0 & 2047;
; #pragma unroll
;                         for (int hf = 0; hf < 2; ++hf) {
;                             f32x4 cs, sn;
;                             if (m < 2) { const float c1 = ropeA[(t >> 6) * 16 + d], s1 = ropeA[1024 + (t >> 6) * 16 + d]; cs = (f32x4){c1, c1, c1, c1}; sn = (f32x4){s1, s1, s1, s1}; }
;                             else { const float* cb = ropeA + 2048 + (d - 16) * 64 + (t & 63) + 4 * hf; cs = *(const f32x4*)(cb); sn = *(const f32x4*)(cb + 1024); }
; #pragma unroll
;                             for (int jj = 0; jj < 4; ++jj) { const float pr = __shfl_xor(v[4 * hf + jj], 4); v[4 * hf + jj] = v[4 * hf + jj] * cs[jj] + sgn * pr * sn[jj]; }
;                             __builtin_amdgcn_sched_barrier(0);
;                         }
;                     }
;                     float zf[8], zb[8]; zf[0] = zf0; zb[0] = zb0;
; #pragma unroll
;                     for (int jj = 1; jj < 8; ++jj) { zf[jj] = zf[jj - 1] * zfs; zb[jj] = zb[jj - 1] * zbs; }
	s_waitcnt lgkmcnt(0)
	s_setprio 1
	s_waitcnt lgkmcnt(0)
	v_mfma_f32_16x16x32_bf16 v[60:63], v[140:143], v[166:169], v[60:63]
	v_mfma_f32_16x16x32_bf16 v[56:59], v[158:161], v[166:169], v[56:59]
	v_mfma_f32_16x16x32_bf16 v[44:47], v[140:143], v[174:177], v[44:47]
	v_mfma_f32_16x16x32_bf16 v[40:43], v[158:161], v[174:177], v[40:43]
	v_mfma_f32_16x16x32_bf16 v[28:31], v[140:143], v[182:185], v[28:31]
	v_mfma_f32_16x16x32_bf16 v[24:27], v[158:161], v[182:185], v[24:27]
	v_mfma_f32_16x16x32_bf16 v[12:15], v[140:143], v[190:193], v[12:15]
	v_mfma_f32_16x16x32_bf16 v[8:11], v[158:161], v[190:193], v[8:11]
	v_mfma_f32_16x16x32_bf16 v[60:63], v[154:157], v[170:173], v[60:63]
	v_mfma_f32_16x16x32_bf16 v[56:59], v[162:165], v[170:173], v[56:59]
	v_mfma_f32_16x16x32_bf16 v[44:47], v[154:157], v[178:181], v[44:47]
	v_mfma_f32_16x16x32_bf16 v[40:43], v[162:165], v[178:181], v[40:43]
	v_mfma_f32_16x16x32_bf16 v[28:31], v[154:157], v[186:189], v[28:31]
	v_mfma_f32_16x16x32_bf16 v[24:27], v[162:165], v[186:189], v[24:27]
	v_mfma_f32_16x16x32_bf16 v[12:15], v[154:157], v[194:197], v[12:15]
	v_mfma_f32_16x16x32_bf16 v[8:11], v[162:165], v[194:197], v[8:11]
	s_setprio 0
	s_barrier
	s_add_u32 s4, s4, 0x40080
	s_addc_u32 s5, s5, 0
	s_add_i32 s24, s24, s31
	s_mov_b32 m0, s24
	s_nop 0
	global_load_lds_dwordx4 v130, s[4:5]
	s_add_i32 m0, s24, 0x2000
	s_nop 0
	global_load_lds_dwordx4 v134, s[4:5]
	s_waitcnt vmcnt(10)
	s_barrier
	s_setprio 1
	v_mfma_f32_16x16x32_bf16 v[52:55], v[202:205], v[166:169], v[52:55]
	v_mfma_f32_16x16x32_bf16 v[48:51], v[210:213], v[166:169], v[48:51]
	v_mfma_f32_16x16x32_bf16 v[36:39], v[202:205], v[174:177], v[36:39]
	v_mfma_f32_16x16x32_bf16 v[32:35], v[210:213], v[174:177], v[32:35]
	v_mfma_f32_16x16x32_bf16 v[20:23], v[202:205], v[182:185], v[20:23]
	v_mfma_f32_16x16x32_bf16 v[16:19], v[210:213], v[182:185], v[16:19]
	v_mfma_f32_16x16x32_bf16 v[4:7], v[202:205], v[190:193], v[4:7]
	v_mfma_f32_16x16x32_bf16 v[0:3], v[210:213], v[190:193], v[0:3]
	v_mfma_f32_16x16x32_bf16 v[52:55], v[206:209], v[170:173], v[52:55]
	v_mfma_f32_16x16x32_bf16 v[48:51], v[214:217], v[170:173], v[48:51]
	v_mfma_f32_16x16x32_bf16 v[36:39], v[206:209], v[178:181], v[36:39]
	v_mfma_f32_16x16x32_bf16 v[32:35], v[214:217], v[178:181], v[32:35]
	v_mfma_f32_16x16x32_bf16 v[20:23], v[206:209], v[186:189], v[20:23]
	v_mfma_f32_16x16x32_bf16 v[16:19], v[214:217], v[186:189], v[16:19]
	v_mfma_f32_16x16x32_bf16 v[4:7], v[206:209], v[194:197], v[4:7]
	v_mfma_f32_16x16x32_bf16 v[0:3], v[214:217], v[194:197], v[0:3]
	s_setprio 0
	s_add_i32 s61, s61, 2
	s_add_u32 s2, s2, 0x100
	s_addc_u32 s3, s3, 0
	s_add_u32 s59, s59, 0x100
	s_addc_u32 s60, s60, 0
	s_cmp_gt_u32 s61, 13
	s_cbranch_scc1 .Lconc_last_g7
	s_barrier
	s_branch .LBB0_693
.Lconc_last_g7:
	v_readfirstlane_b32 s2, v200
	s_nop 3
	s_cmp_gt_u32 s2, 0xff
	s_cbranch_scc1 .Lconc_epi1_g7
	s_barrier
	v_mov_b32_e32 v141, v147
	v_mov_b32_e32 v140, v146
	global_load_dword v156, v131, s[6:7]
	global_load_dword v157, v131, s[6:7] offset:16
	s_lshl_b32 s2, s56, 8
	s_or_b32 s2, s2, s43
	v_add_u32_e32 v140, s42, v140
	v_lshlrev_b32_e32 v141, 3, v141
	v_add_u32_e32 v142, s2, v141
	v_add_u32_e32 v143, s43, v141
	v_ashrrev_i32_e32 v141, 31, v140
	v_sub_u32_e32 v144, 0x7f, v143
	v_lshlrev_b64 v[140:141], 14, v[140:141]
	v_cvt_f32_i32_e32 v154, v143
	v_ashrrev_i32_e32 v143, 31, v142
	v_cvt_f32_i32_e32 v155, v144
	v_lshl_add_u64 v[140:141], s[70:71], 0, v[140:141]
	s_mov_b32 s3, 0x400000
	v_lshl_add_u64 v[140:141], v[142:143], 1, v[140:141]
	v_add_co_u32_e32 v144, vcc, s3, v140
	s_mov_b64 s[4:5], 0x400000
	s_nop 0
	v_addc_co_u32_e32 v145, vcc, 0, v141, vcc
	v_lshl_add_u64 v[142:143], v[140:141], 0, s[4:5]
	s_waitcnt vmcnt(0)
	v_mul_f32_e32 v158, 0x3fb8aa3b, v156
	v_mul_f32_e32 v159, 0x3fb8aa3b, v157
	v_mul_f32_e32 v160, v158, v155
	v_cmp_lt_f32_e32 vcc, s51, v158
	v_mul_f32_e32 v162, v159, v154
	v_cmp_gt_f32_e64 s[2:3], s49, v159
	v_cndmask_b32_e32 v161, 0, v153, vcc
	v_cmp_gt_f32_e64 s[4:5], s49, v160
	v_cndmask_b32_e64 v163, 0, v153, s[2:3]
	s_and_b64 s[24:25], vcc, exec
	v_cmp_gt_f32_e32 vcc, s49, v162
	v_fmac_f32_e32 v163, 0x3fb8aa3b, v157
	v_cndmask_b32_e64 v157, 0, v153, s[4:5]
	v_cndmask_b32_e32 v162, 0, v153, vcc
	v_fmac_f32_e32 v161, 0xbfb8aa3b, v156
	v_fmac_f32_e32 v157, v158, v155
	v_fmac_f32_e32 v162, v159, v154
	v_exp_f32_e32 v161, v161
	v_exp_f32_e32 v163, v163
	v_exp_f32_e32 v157, v157
	v_exp_f32_e32 v158, v162
	v_cndmask_b32_e64 v160, 0, v152, s[4:5]
	s_cselect_b32 s4, 0xffffffc0, 0
	s_and_b64 s[2:3], s[2:3], exec
	v_cndmask_b32_e32 v156, 0, v152, vcc
	s_cselect_b32 s2, 0xffffffc0, 0
	v_ldexp_f32 v161, v161, s4
	v_ldexp_f32 v162, v163, s2
	v_ldexp_f32 v163, v157, v160
	v_ldexp_f32 v156, v158, v156
	v_mul_f32_e32 v164, v161, v163
	v_mul_f32_e32 v157, v162, v156
	v_mul_f32_e32 v158, v124, v163
	v_mul_f32_e32 v165, v124, v156
	v_mul_f32_e32 v166, v161, v164
	v_mul_f32_e32 v124, v162, v157
	v_mul_f32_e32 v159, v125, v164
	v_mul_f32_e32 v167, v125, v157
	v_mul_f32_e32 v168, v161, v166
	v_mul_f32_e32 v125, v162, v124
	v_cvt_pk_bf16_f32 v158, v158, v159
	v_mul_f32_e32 v159, v126, v166
	v_mul_f32_e32 v169, v126, v124
	v_mul_f32_e32 v170, v161, v168
	v_mul_f32_e32 v126, v162, v125
	v_mul_f32_e32 v171, v161, v170
	v_mul_f32_e32 v172, v162, v126
	v_mul_f32_e32 v160, v127, v168
	v_mul_f32_e32 v174, v161, v171
	v_mul_f32_e32 v175, v162, v172
	v_cvt_pk_bf16_f32 v159, v159, v160
	v_mul_f32_e32 v160, v120, v170
	v_mul_f32_e32 v173, v120, v126
	v_mul_f32_e32 v120, v121, v171
	v_mul_f32_e32 v177, v161, v174
	v_mul_f32_e32 v162, v162, v175
	v_mul_f32_e32 v176, v121, v172
	v_cvt_pk_bf16_f32 v160, v160, v120
	v_mul_f32_e32 v120, v122, v174
; __device__ __forceinline__ unsigned cvt_pk_bf16(float lo, float hi) { unsigned r; asm volatile("v_cvt_pk_bf16_f32 %0, %1, %2" : "=v"(r) : "v"(lo), "v"(hi)); return r; }
;     __device__ __forceinline__ void operator()(const AccT& acc, const Unit& u, int wr, int wc, int fr, int fq) const {
;     ...
;                     float zf[8], zb[8]; zf[0] = zf0; zb[0] = zb0;
; #pragma unroll
;                     for (int jj = 1; jj < 8; ++jj) { zf[jj] = zf[jj - 1] * zfs; zb[jj] = zb[jj - 1] * zbs; }
;                     u32x4 wf, wb;
;                     wf.x = cvt_pk_bf16(v[0] * zf[0], v[1] * zf[1]); wf.y = cvt_pk_bf16(v[2] * zf[2], v[3] * zf[3]); wf.z = cvt_pk_bf16(v[4] * zf[4], v[5] * zf[5]); wf.w = cvt_pk_bf16(v[6] * zf[6], v[7] * zf[7]);
;                     wb.x = cvt_pk_bf16(v[0] * zb[0], v[1] * zb[1]); wb.y = cvt_pk_bf16(v[2] * zb[2], v[3] * zb[3]); wb.z = cvt_pk_bf16(v[4] * zb[4], v[5] * zb[5]); wb.w = cvt_pk_bf16(v[6] * zb[6], v[7] * zb[7]);
;                     *(u32x4*)(KTZ + (size_t)r * NT + t0) = wf;
;                     *(u32x4*)(KTZ + (size_t)(256 + r) * NT + t0) = wb;
	v_mul_f32_e32 v121, v123, v177
	v_mul_f32_e32 v123, v123, v162
	v_cvt_pk_bf16_f32 v161, v120, v121
	v_mul_f32_e32 v127, v127, v125
	v_mul_f32_e32 v178, v122, v175
	v_cvt_pk_bf16_f32 v120, v165, v167
	v_cvt_pk_bf16_f32 v121, v169, v127
	v_cvt_pk_bf16_f32 v122, v173, v176
	v_cvt_pk_bf16_f32 v123, v178, v123
	global_store_dwordx4 v[140:141], v[158:161], off
	global_store_dwordx4 v[144:145], v[120:123], off
	s_nop 1
	v_mul_f32_e32 v120, v116, v163
	v_mul_f32_e32 v121, v117, v164
	v_cvt_pk_bf16_f32 v120, v120, v121
	v_mul_f32_e32 v121, v118, v166
	v_mul_f32_e32 v122, v119, v168
	v_cvt_pk_bf16_f32 v121, v121, v122
	v_mul_f32_e32 v122, v112, v170
	v_mul_f32_e32 v123, v113, v171
	v_cvt_pk_bf16_f32 v122, v122, v123
	v_mul_f32_e32 v123, v114, v174
	v_mul_f32_e32 v116, v116, v156
	v_mul_f32_e32 v117, v117, v157
	v_mul_f32_e32 v127, v115, v177
	v_cvt_pk_bf16_f32 v123, v123, v127
	v_cvt_pk_bf16_f32 v116, v116, v117
	v_mul_f32_e32 v117, v118, v124
	v_mul_f32_e32 v118, v119, v125
	v_mul_f32_e32 v112, v112, v126
	v_mul_f32_e32 v113, v113, v172
	v_cvt_pk_bf16_f32 v117, v117, v118
	v_cvt_pk_bf16_f32 v118, v112, v113
	v_mul_f32_e32 v112, v114, v175
	v_mul_f32_e32 v113, v115, v162
	v_cvt_pk_bf16_f32 v119, v112, v113
	global_store_dwordx4 v[140:141], v[120:123], off offset:256
	global_store_dwordx4 v[142:143], v[116:119], off offset:256
	v_mul_f32_e32 v112, v108, v163
	v_mul_f32_e32 v113, v109, v164
	v_cvt_pk_bf16_f32 v112, v112, v113
	v_mul_f32_e32 v113, v110, v166
	v_mul_f32_e32 v114, v111, v168
	v_cvt_pk_bf16_f32 v113, v113, v114
	v_mul_f32_e32 v114, v104, v170
	v_mul_f32_e32 v115, v105, v171
	v_cvt_pk_bf16_f32 v114, v114, v115
	v_mul_f32_e32 v115, v106, v174
	v_mul_f32_e32 v108, v108, v156
	v_mul_f32_e32 v109, v109, v157
	v_mul_f32_e32 v116, v107, v177
	v_cvt_pk_bf16_f32 v115, v115, v116
	v_cvt_pk_bf16_f32 v108, v108, v109
	v_mul_f32_e32 v109, v110, v124
	v_mul_f32_e32 v110, v111, v125
	v_mul_f32_e32 v104, v104, v126
	s_mov_b64 s[2:3], 0x40000
	v_cvt_pk_bf16_f32 v109, v109, v110
	v_mul_f32_e32 v105, v105, v172
	v_cvt_pk_bf16_f32 v110, v104, v105
	v_mul_f32_e32 v104, v106, v175
	v_lshl_add_u64 v[116:117], v[140:141], 0, s[2:3]
	s_mov_b32 s2, 0x40000
	v_mul_f32_e32 v105, v107, v162
	v_cvt_pk_bf16_f32 v111, v104, v105
	v_add_co_u32_e32 v104, vcc, s2, v140
	s_mov_b64 s[2:3], 0x440000
	s_nop 0
	v_addc_co_u32_e32 v105, vcc, 0, v141, vcc
	global_store_dwordx4 v[104:105], v[112:115], off
	s_nop 1
	v_lshl_add_u64 v[112:113], v[140:141], 0, s[2:3]
	s_mov_b32 s2, 0x440000
	v_add_co_u32_e32 v104, vcc, s2, v140
	s_nop 1
	v_addc_co_u32_e32 v105, vcc, 0, v141, vcc
	global_store_dwordx4 v[104:105], v[108:111], off
	v_mul_f32_e32 v104, v100, v163
	v_mul_f32_e32 v105, v101, v164
	v_cvt_pk_bf16_f32 v104, v104, v105
	v_mul_f32_e32 v105, v102, v166
	v_mul_f32_e32 v106, v103, v168
	v_cvt_pk_bf16_f32 v105, v105, v106
	v_mul_f32_e32 v106, v96, v170
	v_mul_f32_e32 v107, v97, v171
	v_cvt_pk_bf16_f32 v106, v106, v107
	v_mul_f32_e32 v107, v98, v174
	v_mul_f32_e32 v100, v100, v156
	v_mul_f32_e32 v101, v101, v157
	v_mul_f32_e32 v108, v99, v177
	v_cvt_pk_bf16_f32 v107, v107, v108
	v_cvt_pk_bf16_f32 v100, v100, v101
	v_mul_f32_e32 v101, v102, v124
	v_mul_f32_e32 v102, v103, v125
	v_mul_f32_e32 v96, v96, v126
	v_mul_f32_e32 v97, v97, v172
	v_cvt_pk_bf16_f32 v101, v101, v102
	v_cvt_pk_bf16_f32 v102, v96, v97
	v_mul_f32_e32 v96, v98, v175
	v_mul_f32_e32 v97, v99, v162
	v_cvt_pk_bf16_f32 v103, v96, v97
	global_store_dwordx4 v[116:117], v[104:107], off offset:256
	global_store_dwordx4 v[112:113], v[100:103], off offset:256
	v_mul_f32_e32 v96, v92, v163
	v_mul_f32_e32 v97, v93, v164
	v_cvt_pk_bf16_f32 v96, v96, v97
	v_mul_f32_e32 v97, v94, v166
	v_mul_f32_e32 v98, v95, v168
	v_cvt_pk_bf16_f32 v97, v97, v98
	v_mul_f32_e32 v98, v88, v170
	v_mul_f32_e32 v99, v89, v171
	v_cvt_pk_bf16_f32 v98, v98, v99
	v_mul_f32_e32 v99, v90, v174
	v_mul_f32_e32 v92, v92, v156
	v_mul_f32_e32 v93, v93, v157
	v_mul_f32_e32 v100, v91, v177
	v_cvt_pk_bf16_f32 v99, v99, v100
	v_cvt_pk_bf16_f32 v92, v92, v93
	v_mul_f32_e32 v93, v94, v124
	v_mul_f32_e32 v94, v95, v125
	v_mul_f32_e32 v88, v88, v126
	s_mov_b64 s[2:3], 0x80000
	v_cvt_pk_bf16_f32 v93, v93, v94
	v_mul_f32_e32 v89, v89, v172
	v_cvt_pk_bf16_f32 v94, v88, v89
	v_mul_f32_e32 v88, v90, v175
	v_lshl_add_u64 v[100:101], v[140:141], 0, s[2:3]
	s_mov_b32 s2, 0x80000
	v_mul_f32_e32 v89, v91, v162
	v_cvt_pk_bf16_f32 v95, v88, v89
	v_add_co_u32_e32 v88, vcc, s2, v140
	s_mov_b64 s[2:3], 0x480000
	s_nop 0
	v_addc_co_u32_e32 v89, vcc, 0, v141, vcc
	global_store_dwordx4 v[88:89], v[96:99], off
	s_nop 1
	v_lshl_add_u64 v[96:97], v[140:141], 0, s[2:3]
	s_mov_b32 s2, 0x480000
	v_add_co_u32_e32 v88, vcc, s2, v140
	s_nop 1
	v_addc_co_u32_e32 v89, vcc, 0, v141, vcc
	global_store_dwordx4 v[88:89], v[92:95], off
	v_mul_f32_e32 v88, v84, v163
	v_mul_f32_e32 v89, v85, v164
	v_cvt_pk_bf16_f32 v88, v88, v89
	v_mul_f32_e32 v89, v86, v166
	v_mul_f32_e32 v90, v87, v168
	v_cvt_pk_bf16_f32 v89, v89, v90
	v_mul_f32_e32 v90, v80, v170
	v_mul_f32_e32 v91, v81, v171
	v_cvt_pk_bf16_f32 v90, v90, v91
	v_mul_f32_e32 v91, v82, v174
	v_mul_f32_e32 v84, v84, v156
	v_mul_f32_e32 v85, v85, v157
	v_mul_f32_e32 v92, v83, v177
	v_cvt_pk_bf16_f32 v91, v91, v92
	v_cvt_pk_bf16_f32 v84, v84, v85
	v_mul_f32_e32 v85, v86, v124
	v_mul_f32_e32 v86, v87, v125
	v_mul_f32_e32 v80, v80, v126
	v_mul_f32_e32 v81, v81, v172
	v_cvt_pk_bf16_f32 v85, v85, v86
	v_cvt_pk_bf16_f32 v86, v80, v81
	v_mul_f32_e32 v80, v82, v175
	v_mul_f32_e32 v81, v83, v162
	v_cvt_pk_bf16_f32 v87, v80, v81
	global_store_dwordx4 v[100:101], v[88:91], off offset:256
	global_store_dwordx4 v[96:97], v[84:87], off offset:256
	v_mul_f32_e32 v80, v76, v163
;     __device__ __forceinline__ void operator()(const AccT& acc, const Unit& u, int wr, int wc, int fr, int fq) const {
;     ...
;         for (int ai = 0; ai < 2; ++ai) {
;             const int hh = 2 * ai + wr;
;             const float l2f = lgd[hh] * 1.4426950408889634f, l2b = lgd[4 + hh] * 1.4426950408889634f;
;             const float zf0 = exp2f((float)(127 - o0) * l2f), zfs = exp2f(-l2f), zb0 = exp2f((float)o0 * l2b), zbs = exp2f(l2b);
; #pragma unroll
;             for (int m = 0; m < 4; ++m) {
;                 const int r = rbase + ai * 128 + m * 16;
;                 const int d = 4 * (2 * m + (fr >> 3)) + j;
; #pragma unroll
;                 for (int bj = 0; bj < 2; ++bj) {
;                     const int t0 = tb + bj * 128;
;                     float v[8];
; #pragma unroll
;                     for (int jj = 0; jj < 4; ++jj) { v[jj] = acc[ai][bj][m][0][jj]; v[4 + jj] = acc[ai][bj][m][1][jj]; }
;                     if constexpr (ROPE) {
;                         const int t = t0 & 2047;
; #pragma unroll
;                         for (int hf = 0; hf < 2; ++hf) {
;                             f32x4 cs, sn;
;                             if (m < 2) { const float c1 = ropeA[(t >> 6) * 16 + d], s1 = ropeA[1024 + (t >> 6) * 16 + d]; cs = (f32x4){c1, c1, c1, c1}; sn = (f32x4){s1, s1, s1, s1}; }
;                             else { const float* cb = ropeA + 2048 + (d - 16) * 64 + (t & 63) + 4 * hf; cs = *(const f32x4*)(cb); sn = *(const f32x4*)(cb + 1024); }
; #pragma unroll
;                             for (int jj = 0; jj < 4; ++jj) { const float pr = __shfl_xor(v[4 * hf + jj], 4); v[4 * hf + jj] = v[4 * hf + jj] * cs[jj] + sgn * pr * sn[jj]; }
;                             __builtin_amdgcn_sched_barrier(0);
;                         }
;                     }
;                     float zf[8], zb[8]; zf[0] = zf0; zb[0] = zb0;
; #pragma unroll
;                     for (int jj = 1; jj < 8; ++jj) { zf[jj] = zf[jj - 1] * zfs; zb[jj] = zb[jj - 1] * zbs; }
;                     u32x4 wf, wb;
;                     wf.x = cvt_pk_bf16(v[0] * zf[0], v[1] * zf[1]); wf.y = cvt_pk_bf16(v[2] * zf[2], v[3] * zf[3]); wf.z = cvt_pk_bf16(v[4] * zf[4], v[5] * zf[5]); wf.w = cvt_pk_bf16(v[6] * zf[6], v[7] * zf[7]);
	v_mul_f32_e32 v81, v77, v164
	v_cvt_pk_bf16_f32 v80, v80, v81
	v_mul_f32_e32 v81, v78, v166
	v_mul_f32_e32 v82, v79, v168
	v_cvt_pk_bf16_f32 v81, v81, v82
	v_mul_f32_e32 v82, v72, v170
	v_mul_f32_e32 v83, v73, v171
	v_cvt_pk_bf16_f32 v82, v82, v83
	v_mul_f32_e32 v83, v74, v174
	v_mul_f32_e32 v76, v76, v156
	v_mul_f32_e32 v77, v77, v157
	v_mul_f32_e32 v84, v75, v177
	v_cvt_pk_bf16_f32 v83, v83, v84
	v_cvt_pk_bf16_f32 v76, v76, v77
	v_mul_f32_e32 v77, v78, v124
	v_mul_f32_e32 v78, v79, v125
	v_mul_f32_e32 v72, v72, v126
	s_mov_b64 s[2:3], 0xc0000
	v_cvt_pk_bf16_f32 v77, v77, v78
	v_mul_f32_e32 v73, v73, v172
	v_cvt_pk_bf16_f32 v78, v72, v73
	v_mul_f32_e32 v72, v74, v175
	v_lshl_add_u64 v[84:85], v[140:141], 0, s[2:3]
	s_mov_b32 s2, 0xc0000
	v_mul_f32_e32 v73, v75, v162
	v_cvt_pk_bf16_f32 v79, v72, v73
	v_add_co_u32_e32 v72, vcc, s2, v140
	s_mov_b64 s[2:3], 0x4c0000
	s_nop 0
	v_addc_co_u32_e32 v73, vcc, 0, v141, vcc
	global_store_dwordx4 v[72:73], v[80:83], off
	s_nop 1
	v_lshl_add_u64 v[80:81], v[140:141], 0, s[2:3]
	s_mov_b32 s2, 0x4c0000
	v_add_co_u32_e32 v72, vcc, s2, v140
	s_nop 1
	v_addc_co_u32_e32 v73, vcc, 0, v141, vcc
	global_store_dwordx4 v[72:73], v[76:79], off
	v_mul_f32_e32 v72, v68, v163
	v_mul_f32_e32 v73, v69, v164
	v_cvt_pk_bf16_f32 v72, v72, v73
	v_mul_f32_e32 v73, v70, v166
	v_mul_f32_e32 v74, v71, v168
	v_cvt_pk_bf16_f32 v73, v73, v74
	v_mul_f32_e32 v74, v64, v170
	v_mul_f32_e32 v75, v65, v171
	v_cvt_pk_bf16_f32 v74, v74, v75
	v_mul_f32_e32 v75, v66, v174
	v_mul_f32_e32 v68, v68, v156
	v_mul_f32_e32 v69, v69, v157
	v_mul_f32_e32 v76, v67, v177
	v_cvt_pk_bf16_f32 v75, v75, v76
	v_cvt_pk_bf16_f32 v68, v68, v69
	v_mul_f32_e32 v69, v70, v124
	v_mul_f32_e32 v70, v71, v125
	v_mul_f32_e32 v64, v64, v126
	v_mul_f32_e32 v65, v65, v172
	v_cvt_pk_bf16_f32 v69, v69, v70
	v_cvt_pk_bf16_f32 v70, v64, v65
	v_mul_f32_e32 v64, v66, v175
	v_mul_f32_e32 v65, v67, v162
	v_cvt_pk_bf16_f32 v71, v64, v65
	global_store_dwordx4 v[84:85], v[72:75], off offset:256
	global_store_dwordx4 v[80:81], v[68:71], off offset:256
	global_load_dword v70, v131, s[6:7] offset:8
	s_nop 0
	global_load_dword v71, v131, s[6:7] offset:24
	s_mov_b32 s17, 0x200000
	v_add_co_u32_e32 v76, vcc, s17, v140
	s_mov_b32 s19, 0x600000
	s_nop 0
	v_addc_co_u32_e32 v77, vcc, 0, v141, vcc
	v_add_co_u32_e32 v68, vcc, s19, v140
	s_mov_b64 s[2:3], 0x200000
	s_nop 0
	v_addc_co_u32_e32 v69, vcc, 0, v141, vcc
	s_mov_b64 s[4:5], 0x600000
	v_lshl_add_u64 v[64:65], v[140:141], 0, s[2:3]
	v_lshl_add_u64 v[66:67], v[140:141], 0, s[4:5]
	s_waitcnt vmcnt(0)
	v_mul_f32_e32 v72, 0x3fb8aa3b, v70
	v_mul_f32_e32 v73, 0x3fb8aa3b, v71
	v_mul_f32_e32 v74, v72, v155
	v_cmp_lt_f32_e32 vcc, s51, v72
	v_mul_f32_e32 v78, v73, v154
	v_cmp_gt_f32_e64 s[2:3], s49, v73
	v_cndmask_b32_e32 v75, 0, v153, vcc
	v_cmp_gt_f32_e64 s[4:5], s49, v74
	v_cndmask_b32_e64 v79, 0, v153, s[2:3]
	s_and_b64 s[24:25], vcc, exec
	v_cmp_gt_f32_e32 vcc, s49, v78
	v_fmac_f32_e32 v79, 0x3fb8aa3b, v71
	v_cndmask_b32_e64 v71, 0, v153, s[4:5]
	v_cndmask_b32_e32 v78, 0, v153, vcc
	v_fmac_f32_e32 v75, 0xbfb8aa3b, v70
	v_fmac_f32_e32 v71, v72, v155
	v_fmac_f32_e32 v78, v73, v154
	v_exp_f32_e32 v75, v75
	v_exp_f32_e32 v79, v79
	v_exp_f32_e32 v71, v71
	v_exp_f32_e32 v72, v78
	v_cndmask_b32_e64 v74, 0, v152, s[4:5]
	s_cselect_b32 s4, 0xffffffc0, 0
	s_and_b64 s[2:3], s[2:3], exec
	v_cndmask_b32_e32 v70, 0, v152, vcc
	s_cselect_b32 s2, 0xffffffc0, 0
	v_ldexp_f32 v75, v75, s4
	v_ldexp_f32 v78, v79, s2
	v_ldexp_f32 v79, v71, v74
	v_ldexp_f32 v70, v72, v70
	v_mul_f32_e32 v80, v75, v79
	v_mul_f32_e32 v71, v78, v70
	v_mul_f32_e32 v72, v60, v79
	v_mul_f32_e32 v81, v60, v70
	v_mul_f32_e32 v82, v75, v80
	v_mul_f32_e32 v60, v78, v71
	v_mul_f32_e32 v83, v75, v82
	v_mul_f32_e32 v84, v78, v60
	v_mul_f32_e32 v85, v75, v83
	v_mul_f32_e32 v86, v78, v84
	v_mul_f32_e32 v73, v61, v80
	v_mul_f32_e32 v87, v75, v85
	v_mul_f32_e32 v88, v78, v86
	v_cvt_pk_bf16_f32 v72, v72, v73
	v_mul_f32_e32 v73, v62, v82
	v_mul_f32_e32 v74, v63, v83
	v_mul_f32_e32 v90, v75, v87
	v_mul_f32_e32 v91, v78, v88
	v_cvt_pk_bf16_f32 v73, v73, v74
	v_mul_f32_e32 v74, v56, v85
	v_mul_f32_e32 v89, v56, v86
	v_mul_f32_e32 v56, v57, v87
	v_mul_f32_e32 v93, v75, v90
	v_mul_f32_e32 v78, v78, v91
	v_mul_f32_e32 v92, v57, v88
	v_cvt_pk_bf16_f32 v74, v74, v56
	v_mul_f32_e32 v56, v58, v90
	v_mul_f32_e32 v57, v59, v93
	v_mul_f32_e32 v59, v59, v78
	v_cvt_pk_bf16_f32 v75, v56, v57
	v_mul_f32_e32 v61, v61, v71
	v_mul_f32_e32 v62, v62, v60
	v_mul_f32_e32 v63, v63, v84
	v_mul_f32_e32 v94, v58, v91
	v_cvt_pk_bf16_f32 v56, v81, v61
	v_cvt_pk_bf16_f32 v57, v62, v63
	v_cvt_pk_bf16_f32 v58, v89, v92
	v_cvt_pk_bf16_f32 v59, v94, v59
	global_store_dwordx4 v[76:77], v[72:75], off
	global_store_dwordx4 v[68:69], v[56:59], off
	s_nop 1
	v_mul_f32_e32 v56, v52, v79
	v_mul_f32_e32 v57, v53, v80
	v_cvt_pk_bf16_f32 v56, v56, v57
	v_mul_f32_e32 v57, v54, v82
	v_mul_f32_e32 v58, v55, v83
	v_cvt_pk_bf16_f32 v57, v57, v58
	v_mul_f32_e32 v58, v48, v85
	v_mul_f32_e32 v59, v49, v87
	v_cvt_pk_bf16_f32 v58, v58, v59
	v_mul_f32_e32 v59, v50, v90
	v_mul_f32_e32 v52, v52, v70
	v_mul_f32_e32 v53, v53, v71
	v_mul_f32_e32 v61, v51, v93
	v_cvt_pk_bf16_f32 v59, v59, v61
	v_cvt_pk_bf16_f32 v52, v52, v53
	v_mul_f32_e32 v53, v54, v60
	v_mul_f32_e32 v54, v55, v84
	v_mul_f32_e32 v48, v48, v86
	v_mul_f32_e32 v49, v49, v88
	v_cvt_pk_bf16_f32 v53, v53, v54
	v_cvt_pk_bf16_f32 v54, v48, v49
	v_mul_f32_e32 v48, v50, v91
	v_mul_f32_e32 v49, v51, v78
	v_cvt_pk_bf16_f32 v55, v48, v49
	global_store_dwordx4 v[64:65], v[56:59], off offset:256
	global_store_dwordx4 v[66:67], v[52:55], off offset:256
	v_mul_f32_e32 v48, v44, v79
	v_mul_f32_e32 v49, v45, v80
;     __device__ __forceinline__ void operator()(const AccT& acc, const Unit& u, int wr, int wc, int fr, int fq) const {
;     ...
;             for (int m = 0; m < 4; ++m) {
;                 const int r = rbase + ai * 128 + m * 16;
;                 const int d = 4 * (2 * m + (fr >> 3)) + j;
; #pragma unroll
;                 for (int bj = 0; bj < 2; ++bj) {
;                     const int t0 = tb + bj * 128;
;                     float v[8];
; #pragma unroll
;                     for (int jj = 0; jj < 4; ++jj) { v[jj] = acc[ai][bj][m][0][jj]; v[4 + jj] = acc[ai][bj][m][1][jj]; }
;                     if constexpr (ROPE) {
;                         const int t = t0 & 2047;
; #pragma unroll
;                         for (int hf = 0; hf < 2; ++hf) {
;                             f32x4 cs, sn;
;                             if (m < 2) { const float c1 = ropeA[(t >> 6) * 16 + d], s1 = ropeA[1024 + (t >> 6) * 16 + d]; cs = (f32x4){c1, c1, c1, c1}; sn = (f32x4){s1, s1, s1, s1}; }
;                             else { const float* cb = ropeA + 2048 + (d - 16) * 64 + (t & 63) + 4 * hf; cs = *(const f32x4*)(cb); sn = *(const f32x4*)(cb + 1024); }
; #pragma unroll
;                             for (int jj = 0; jj < 4; ++jj) { const float pr = __shfl_xor(v[4 * hf + jj], 4); v[4 * hf + jj] = v[4 * hf + jj] * cs[jj] + sgn * pr * sn[jj]; }
;                             __builtin_amdgcn_sched_barrier(0);
;                         }
;                     }
;                     float zf[8], zb[8]; zf[0] = zf0; zb[0] = zb0;
; #pragma unroll
;                     for (int jj = 1; jj < 8; ++jj) { zf[jj] = zf[jj - 1] * zfs; zb[jj] = zb[jj - 1] * zbs; }
;                     u32x4 wf, wb;
;                     wf.x = cvt_pk_bf16(v[0] * zf[0], v[1] * zf[1]); wf.y = cvt_pk_bf16(v[2] * zf[2], v[3] * zf[3]); wf.z = cvt_pk_bf16(v[4] * zf[4], v[5] * zf[5]); wf.w = cvt_pk_bf16(v[6] * zf[6], v[7] * zf[7]);
;                     wb.x = cvt_pk_bf16(v[0] * zb[0], v[1] * zb[1]); wb.y = cvt_pk_bf16(v[2] * zb[2], v[3] * zb[3]); wb.z = cvt_pk_bf16(v[4] * zb[4], v[5] * zb[5]); wb.w = cvt_pk_bf16(v[6] * zb[6], v[7] * zb[7]);
;                     *(u32x4*)(KTZ + (size_t)r * NT + t0) = wf;
;                     *(u32x4*)(KTZ + (size_t)(256 + r) * NT + t0) = wb;
;                     __builtin_amdgcn_sched_barrier(0);
	v_cvt_pk_bf16_f32 v48, v48, v49
	v_mul_f32_e32 v49, v46, v82
	v_mul_f32_e32 v50, v47, v83
	v_cvt_pk_bf16_f32 v49, v49, v50
	v_mul_f32_e32 v50, v40, v85
	v_mul_f32_e32 v51, v41, v87
	v_cvt_pk_bf16_f32 v50, v50, v51
	v_mul_f32_e32 v51, v42, v90
	v_mul_f32_e32 v44, v44, v70
	v_mul_f32_e32 v45, v45, v71
	v_mul_f32_e32 v52, v43, v93
	v_cvt_pk_bf16_f32 v51, v51, v52
	v_cvt_pk_bf16_f32 v44, v44, v45
	v_mul_f32_e32 v45, v46, v60
	v_mul_f32_e32 v46, v47, v84
	v_mul_f32_e32 v40, v40, v86
	s_mov_b64 s[2:3], 0x240000
	v_cvt_pk_bf16_f32 v45, v45, v46
	v_mul_f32_e32 v41, v41, v88
	v_cvt_pk_bf16_f32 v46, v40, v41
	v_mul_f32_e32 v40, v42, v91
	v_lshl_add_u64 v[52:53], v[140:141], 0, s[2:3]
	s_mov_b32 s2, 0x240000
	v_mul_f32_e32 v41, v43, v78
	v_cvt_pk_bf16_f32 v47, v40, v41
	v_add_co_u32_e32 v40, vcc, s2, v140
	s_mov_b64 s[2:3], 0x640000
	s_nop 0
	v_addc_co_u32_e32 v41, vcc, 0, v141, vcc
	global_store_dwordx4 v[40:41], v[48:51], off
	s_nop 1
	v_lshl_add_u64 v[48:49], v[140:141], 0, s[2:3]
	s_mov_b32 s2, 0x640000
	v_add_co_u32_e32 v40, vcc, s2, v140
	s_nop 1
	v_addc_co_u32_e32 v41, vcc, 0, v141, vcc
	global_store_dwordx4 v[40:41], v[44:47], off
	v_mul_f32_e32 v40, v36, v79
	v_mul_f32_e32 v41, v37, v80
	v_cvt_pk_bf16_f32 v40, v40, v41
	v_mul_f32_e32 v41, v38, v82
	v_mul_f32_e32 v42, v39, v83
	v_cvt_pk_bf16_f32 v41, v41, v42
	v_mul_f32_e32 v42, v32, v85
	v_mul_f32_e32 v43, v33, v87
	v_cvt_pk_bf16_f32 v42, v42, v43
	v_mul_f32_e32 v43, v34, v90
	v_mul_f32_e32 v36, v36, v70
	v_mul_f32_e32 v37, v37, v71
	v_mul_f32_e32 v44, v35, v93
	v_cvt_pk_bf16_f32 v43, v43, v44
	v_cvt_pk_bf16_f32 v36, v36, v37
	v_mul_f32_e32 v37, v38, v60
	v_mul_f32_e32 v38, v39, v84
	v_mul_f32_e32 v32, v32, v86
	v_mul_f32_e32 v33, v33, v88
	v_cvt_pk_bf16_f32 v37, v37, v38
	v_cvt_pk_bf16_f32 v38, v32, v33
	v_mul_f32_e32 v32, v34, v91
	v_mul_f32_e32 v33, v35, v78
	v_cvt_pk_bf16_f32 v39, v32, v33
	global_store_dwordx4 v[52:53], v[40:43], off offset:256
	global_store_dwordx4 v[48:49], v[36:39], off offset:256
	v_mul_f32_e32 v32, v28, v79
	v_mul_f32_e32 v33, v29, v80
	v_cvt_pk_bf16_f32 v32, v32, v33
	v_mul_f32_e32 v33, v30, v82
	v_mul_f32_e32 v34, v31, v83
	v_cvt_pk_bf16_f32 v33, v33, v34
	v_mul_f32_e32 v34, v24, v85
	v_mul_f32_e32 v35, v25, v87
	v_cvt_pk_bf16_f32 v34, v34, v35
	v_mul_f32_e32 v35, v26, v90
	v_mul_f32_e32 v28, v28, v70
	v_mul_f32_e32 v29, v29, v71
	v_mul_f32_e32 v36, v27, v93
	v_cvt_pk_bf16_f32 v35, v35, v36
	v_cvt_pk_bf16_f32 v28, v28, v29
	v_mul_f32_e32 v29, v30, v60
	v_mul_f32_e32 v30, v31, v84
	v_mul_f32_e32 v24, v24, v86
	v_cvt_pk_bf16_f32 v29, v29, v30
	v_mul_f32_e32 v25, v25, v88
	v_cvt_pk_bf16_f32 v30, v24, v25
	v_mul_f32_e32 v24, v26, v91
	v_mul_f32_e32 v25, v27, v78
	v_cvt_pk_bf16_f32 v31, v24, v25
	v_add_co_u32_e32 v24, vcc, s52, v140
	s_mov_b64 s[2:3], 0x280000
	s_nop 0
	v_addc_co_u32_e32 v25, vcc, 0, v141, vcc
	global_store_dwordx4 v[24:25], v[32:35], off
	v_add_co_u32_e32 v24, vcc, s53, v140
	v_lshl_add_u64 v[36:37], v[140:141], 0, s[2:3]
	s_nop 0
	v_addc_co_u32_e32 v25, vcc, 0, v141, vcc
	v_lshl_add_u64 v[32:33], v[140:141], 0, s[8:9]
	global_store_dwordx4 v[24:25], v[28:31], off
	v_mul_f32_e32 v24, v20, v79
	v_mul_f32_e32 v25, v21, v80
	v_cvt_pk_bf16_f32 v24, v24, v25
	v_mul_f32_e32 v25, v22, v82
	v_mul_f32_e32 v26, v23, v83
	v_cvt_pk_bf16_f32 v25, v25, v26
	v_mul_f32_e32 v26, v16, v85
	v_mul_f32_e32 v27, v17, v87
	v_cvt_pk_bf16_f32 v26, v26, v27
	v_mul_f32_e32 v27, v18, v90
	v_mul_f32_e32 v20, v20, v70
	v_mul_f32_e32 v21, v21, v71
	v_mul_f32_e32 v28, v19, v93
	v_cvt_pk_bf16_f32 v27, v27, v28
	v_cvt_pk_bf16_f32 v20, v20, v21
	v_mul_f32_e32 v21, v22, v60
	v_mul_f32_e32 v22, v23, v84
	v_mul_f32_e32 v16, v16, v86
	v_mul_f32_e32 v17, v17, v88
	v_cvt_pk_bf16_f32 v21, v21, v22
	v_cvt_pk_bf16_f32 v22, v16, v17
	v_mul_f32_e32 v16, v18, v91
	v_mul_f32_e32 v17, v19, v78
	v_cvt_pk_bf16_f32 v23, v16, v17
	global_store_dwordx4 v[36:37], v[24:27], off offset:256
	global_store_dwordx4 v[32:33], v[20:23], off offset:256
	v_mul_f32_e32 v16, v12, v79
	v_mul_f32_e32 v17, v13, v80
	v_cvt_pk_bf16_f32 v16, v16, v17
	v_mul_f32_e32 v17, v14, v82
	v_mul_f32_e32 v18, v15, v83
	v_cvt_pk_bf16_f32 v17, v17, v18
	v_mul_f32_e32 v18, v8, v85
	v_mul_f32_e32 v19, v9, v87
	v_cvt_pk_bf16_f32 v18, v18, v19
	v_mul_f32_e32 v19, v10, v90
	v_mul_f32_e32 v12, v12, v70
	v_mul_f32_e32 v13, v13, v71
	v_mul_f32_e32 v20, v11, v93
	v_cvt_pk_bf16_f32 v19, v19, v20
	v_cvt_pk_bf16_f32 v12, v12, v13
	v_mul_f32_e32 v13, v14, v60
	v_mul_f32_e32 v14, v15, v84
	v_mul_f32_e32 v8, v8, v86
	v_cvt_pk_bf16_f32 v13, v13, v14
	v_mul_f32_e32 v9, v9, v88
	v_cvt_pk_bf16_f32 v14, v8, v9
	v_mul_f32_e32 v8, v10, v91
	v_mul_f32_e32 v9, v11, v78
	v_cvt_pk_bf16_f32 v15, v8, v9
	v_add_co_u32_e32 v8, vcc, s54, v140
	v_lshl_add_u64 v[20:21], v[140:141], 0, s[10:11]
	s_nop 0
	v_addc_co_u32_e32 v9, vcc, 0, v141, vcc
	global_store_dwordx4 v[8:9], v[16:19], off
	v_add_co_u32_e32 v8, vcc, s55, v140
	s_nop 0
	v_lshl_add_u64 v[16:17], v[140:141], 0, s[12:13]
	v_addc_co_u32_e32 v9, vcc, 0, v141, vcc
	global_store_dwordx4 v[8:9], v[12:15], off
	v_mul_f32_e32 v8, v4, v79
	v_mul_f32_e32 v9, v5, v80
	v_cvt_pk_bf16_f32 v8, v8, v9
	v_mul_f32_e32 v9, v6, v82
	v_mul_f32_e32 v10, v7, v83
	v_cvt_pk_bf16_f32 v9, v9, v10
	v_mul_f32_e32 v10, v0, v85
	v_mul_f32_e32 v11, v1, v87
	v_cvt_pk_bf16_f32 v10, v10, v11
	v_mul_f32_e32 v11, v2, v90
	v_mul_f32_e32 v4, v4, v70
	v_mul_f32_e32 v5, v5, v71
	v_mul_f32_e32 v12, v3, v93
	v_cvt_pk_bf16_f32 v11, v11, v12
	v_cvt_pk_bf16_f32 v4, v4, v5
	v_mul_f32_e32 v5, v6, v60
	v_mul_f32_e32 v6, v7, v84
	v_mul_f32_e32 v0, v0, v86
	v_mul_f32_e32 v1, v1, v88
	v_cvt_pk_bf16_f32 v5, v5, v6
	v_cvt_pk_bf16_f32 v6, v0, v1
	v_mul_f32_e32 v0, v2, v91
	v_mul_f32_e32 v1, v3, v78
	v_cvt_pk_bf16_f32 v7, v0, v1
	global_store_dwordx4 v[20:21], v[8:11], off offset:256
	global_store_dwordx4 v[16:17], v[4:7], off offset:256
	s_and_b64 vcc, exec, s[14:15]
	s_mov_b32 s56, s16
	s_mov_b64 s[4:5], s[22:23]
	s_mov_b64 s[2:3], s[20:21]
	s_cbranch_vccz .LBB0_686
	s_branch .Lconc_end_g7
;     __device__ __forceinline__ void operator()(const AccT& acc, const Unit& u, int wr, int wc, int fr, int fq) const {
;         asm volatile("" : "+v"(fr), "+v"(fq));
;         const int rbase = wr * 64 + fr;
;         const int tb = u.pn * 256 + wc * 32 + 8 * fq;
;         const int o0 = wc * 32 + 8 * fq;
;         const int j = fr & 3; const float sgn = ((fr >> 2) & 1) ? 1.0f : -1.0f;
; #pragma unroll
;         for (int ai = 0; ai < 2; ++ai) {
;             const int hh = 2 * ai + wr;
;             const float l2f = lgd[hh] * 1.4426950408889634f, l2b = lgd[4 + hh] * 1.4426950408889634f;
;             const float zf0 = exp2f((float)(127 - o0) * l2f), zfs = exp2f(-l2f), zb0 = exp2f((float)o0 * l2b), zbs = exp2f(l2b);
; #pragma unroll
;             for (int m = 0; m < 4; ++m) {
;                 const int r = rbase + ai * 128 + m * 16;
;                 const int d = 4 * (2 * m + (fr >> 3)) + j;
; #pragma unroll
;                 for (int bj = 0; bj < 2; ++bj) {
;                     const int t0 = tb + bj * 128;
;                     float v[8];
; #pragma unroll
;                     for (int jj = 0; jj < 4; ++jj) { v[jj] = acc[ai][bj][m][0][jj]; v[4 + jj] = acc[ai][bj][m][1][jj]; }
;                     if constexpr (ROPE) {
;                         const int t = t0 & 2047;
; #pragma unroll
;                         for (int hf = 0; hf < 2; ++hf) {
;                             f32x4 cs, sn;
;                             if (m < 2) { const float c1 = ropeA[(t >> 6) * 16 + d], s1 = ropeA[1024 + (t >> 6) * 16 + d]; cs = (f32x4){c1, c1, c1, c1}; sn = (f32x4){s1, s1, s1, s1}; }
;                             else { const float* cb = ropeA + 2048 + (d - 16) * 64 + (t & 63) + 4 * hf; cs = *(const f32x4*)(cb); sn = *(const f32x4*)(cb + 1024); }
; #pragma unroll
;                             for (int jj = 0; jj < 4; ++jj) { const float pr = __shfl_xor(v[4 * hf + jj], 4); v[4 * hf + jj] = v[4 * hf + jj] * cs[jj] + sgn * pr * sn[jj]; }
;                             __builtin_amdgcn_sched_barrier(0);
;                         }
;                     }
;                     float zf[8], zb[8]; zf[0] = zf0; zb[0] = zb0;
; #pragma unroll
;                     for (int jj = 1; jj < 8; ++jj) { zf[jj] = zf[jj - 1] * zfs; zb[jj] = zb[jj - 1] * zbs; }
;                     u32x4 wf, wb;
.Lconc_epi1_g7:
	v_mov_b32_e32 v141, v147
	v_mov_b32_e32 v140, v146
	global_load_dword v156, v131, s[6:7]
	global_load_dword v157, v131, s[6:7] offset:16
	s_lshl_b32 s2, s56, 8
	s_or_b32 s2, s2, s43
	v_add_u32_e32 v140, s42, v140
	v_lshlrev_b32_e32 v141, 3, v141
	v_add_u32_e32 v142, s2, v141
	v_add_u32_e32 v143, s43, v141
	v_ashrrev_i32_e32 v141, 31, v140
	v_sub_u32_e32 v144, 0x7f, v143
	v_lshlrev_b64 v[140:141], 14, v[140:141]
	v_cvt_f32_i32_e32 v154, v143
	v_ashrrev_i32_e32 v143, 31, v142
	v_cvt_f32_i32_e32 v155, v144
	v_lshl_add_u64 v[140:141], s[70:71], 0, v[140:141]
	s_mov_b32 s3, 0x400000
	v_lshl_add_u64 v[140:141], v[142:143], 1, v[140:141]
	v_add_co_u32_e32 v144, vcc, s3, v140
	s_mov_b64 s[4:5], 0x400000
	s_nop 0
	v_addc_co_u32_e32 v145, vcc, 0, v141, vcc
	v_lshl_add_u64 v[142:143], v[140:141], 0, s[4:5]
	s_waitcnt vmcnt(0)
	v_mul_f32_e32 v158, 0x3fb8aa3b, v156
	v_mul_f32_e32 v159, 0x3fb8aa3b, v157
	v_mul_f32_e32 v160, v158, v155
	v_cmp_lt_f32_e32 vcc, s51, v158
	v_mul_f32_e32 v162, v159, v154
	v_cmp_gt_f32_e64 s[2:3], s49, v159
	v_cndmask_b32_e32 v161, 0, v153, vcc
	v_cmp_gt_f32_e64 s[4:5], s49, v160
	v_cndmask_b32_e64 v163, 0, v153, s[2:3]
	s_and_b64 s[24:25], vcc, exec
	v_cmp_gt_f32_e32 vcc, s49, v162
	v_fmac_f32_e32 v163, 0x3fb8aa3b, v157
	v_cndmask_b32_e64 v157, 0, v153, s[4:5]
	v_cndmask_b32_e32 v162, 0, v153, vcc
	v_fmac_f32_e32 v161, 0xbfb8aa3b, v156
	v_fmac_f32_e32 v157, v158, v155
	v_fmac_f32_e32 v162, v159, v154
	v_exp_f32_e32 v161, v161
	v_exp_f32_e32 v163, v163
	v_exp_f32_e32 v157, v157
	v_exp_f32_e32 v158, v162
	v_cndmask_b32_e64 v160, 0, v152, s[4:5]
	s_cselect_b32 s4, 0xffffffc0, 0
	s_and_b64 s[2:3], s[2:3], exec
	v_cndmask_b32_e32 v156, 0, v152, vcc
	s_cselect_b32 s2, 0xffffffc0, 0
	v_ldexp_f32 v161, v161, s4
	v_ldexp_f32 v162, v163, s2
	v_ldexp_f32 v163, v157, v160
	v_ldexp_f32 v156, v158, v156
	v_mul_f32_e32 v164, v161, v163
	v_mul_f32_e32 v157, v162, v156
	v_mul_f32_e32 v158, v124, v163
	v_mul_f32_e32 v165, v124, v156
	v_mul_f32_e32 v166, v161, v164
	v_mul_f32_e32 v124, v162, v157
	v_mul_f32_e32 v159, v125, v164
	v_mul_f32_e32 v167, v125, v157
	v_mul_f32_e32 v168, v161, v166
	v_mul_f32_e32 v125, v162, v124
	v_cvt_pk_bf16_f32 v158, v158, v159
	v_mul_f32_e32 v159, v126, v166
	v_mul_f32_e32 v169, v126, v124
	v_mul_f32_e32 v170, v161, v168
	v_mul_f32_e32 v126, v162, v125
	v_mul_f32_e32 v171, v161, v170
	v_mul_f32_e32 v172, v162, v126
	v_mul_f32_e32 v160, v127, v168
	v_mul_f32_e32 v174, v161, v171
	v_mul_f32_e32 v175, v162, v172
	v_cvt_pk_bf16_f32 v159, v159, v160
	v_mul_f32_e32 v160, v120, v170
	v_mul_f32_e32 v173, v120, v126
	v_mul_f32_e32 v120, v121, v171
	v_mul_f32_e32 v177, v161, v174
	v_mul_f32_e32 v162, v162, v175
	v_mul_f32_e32 v176, v121, v172
	v_cvt_pk_bf16_f32 v160, v160, v120
	v_mul_f32_e32 v120, v122, v174
	v_mul_f32_e32 v121, v123, v177
	v_mul_f32_e32 v123, v123, v162
	v_cvt_pk_bf16_f32 v161, v120, v121
	v_mul_f32_e32 v127, v127, v125
	v_mul_f32_e32 v178, v122, v175
	v_cvt_pk_bf16_f32 v120, v165, v167
	v_cvt_pk_bf16_f32 v121, v169, v127
	v_cvt_pk_bf16_f32 v122, v173, v176
	v_cvt_pk_bf16_f32 v123, v178, v123
	global_store_dwordx4 v[140:141], v[158:161], off
	global_store_dwordx4 v[144:145], v[120:123], off
	s_nop 1
	v_mul_f32_e32 v120, v116, v163
	v_mul_f32_e32 v121, v117, v164
	v_cvt_pk_bf16_f32 v120, v120, v121
	v_mul_f32_e32 v121, v118, v166
	v_mul_f32_e32 v122, v119, v168
	v_cvt_pk_bf16_f32 v121, v121, v122
	v_mul_f32_e32 v122, v112, v170
	v_mul_f32_e32 v123, v113, v171
	v_cvt_pk_bf16_f32 v122, v122, v123
	v_mul_f32_e32 v123, v114, v174
	v_mul_f32_e32 v116, v116, v156
	v_mul_f32_e32 v117, v117, v157
	v_mul_f32_e32 v127, v115, v177
	v_cvt_pk_bf16_f32 v123, v123, v127
	v_cvt_pk_bf16_f32 v116, v116, v117
	v_mul_f32_e32 v117, v118, v124
	v_mul_f32_e32 v118, v119, v125
	v_mul_f32_e32 v112, v112, v126
	v_mul_f32_e32 v113, v113, v172
	v_cvt_pk_bf16_f32 v117, v117, v118
	v_cvt_pk_bf16_f32 v118, v112, v113
	v_mul_f32_e32 v112, v114, v175
	v_mul_f32_e32 v113, v115, v162
	v_cvt_pk_bf16_f32 v119, v112, v113
	global_store_dwordx4 v[140:141], v[120:123], off offset:256
	global_store_dwordx4 v[142:143], v[116:119], off offset:256
	v_mul_f32_e32 v112, v108, v163
	v_mul_f32_e32 v113, v109, v164
	v_cvt_pk_bf16_f32 v112, v112, v113
	v_mul_f32_e32 v113, v110, v166
	v_mul_f32_e32 v114, v111, v168
	v_cvt_pk_bf16_f32 v113, v113, v114
	v_mul_f32_e32 v114, v104, v170
	v_mul_f32_e32 v115, v105, v171
	v_cvt_pk_bf16_f32 v114, v114, v115
	v_mul_f32_e32 v115, v106, v174
	v_mul_f32_e32 v108, v108, v156
	v_mul_f32_e32 v109, v109, v157
	v_mul_f32_e32 v116, v107, v177
	v_cvt_pk_bf16_f32 v115, v115, v116
	v_cvt_pk_bf16_f32 v108, v108, v109
	v_mul_f32_e32 v109, v110, v124
	v_mul_f32_e32 v110, v111, v125
	v_mul_f32_e32 v104, v104, v126
	s_mov_b64 s[2:3], 0x40000
	v_cvt_pk_bf16_f32 v109, v109, v110
	v_mul_f32_e32 v105, v105, v172
	v_cvt_pk_bf16_f32 v110, v104, v105
	v_mul_f32_e32 v104, v106, v175
	v_lshl_add_u64 v[116:117], v[140:141], 0, s[2:3]
	s_mov_b32 s2, 0x40000
	v_mul_f32_e32 v105, v107, v162
	v_cvt_pk_bf16_f32 v111, v104, v105
	v_add_co_u32_e32 v104, vcc, s2, v140
	s_mov_b64 s[2:3], 0x440000
	s_nop 0
	v_addc_co_u32_e32 v105, vcc, 0, v141, vcc
	global_store_dwordx4 v[104:105], v[112:115], off
	s_nop 1
	v_lshl_add_u64 v[112:113], v[140:141], 0, s[2:3]
	s_mov_b32 s2, 0x440000
	v_add_co_u32_e32 v104, vcc, s2, v140
	s_nop 1
	v_addc_co_u32_e32 v105, vcc, 0, v141, vcc
	global_store_dwordx4 v[104:105], v[108:111], off
	v_mul_f32_e32 v104, v100, v163
	v_mul_f32_e32 v105, v101, v164
	v_cvt_pk_bf16_f32 v104, v104, v105
	v_mul_f32_e32 v105, v102, v166
	v_mul_f32_e32 v106, v103, v168
	v_cvt_pk_bf16_f32 v105, v105, v106
	v_mul_f32_e32 v106, v96, v170
;     __device__ __forceinline__ void operator()(const AccT& acc, const Unit& u, int wr, int wc, int fr, int fq) const {
;     ...
;             for (int m = 0; m < 4; ++m) {
;                 const int r = rbase + ai * 128 + m * 16;
;                 const int d = 4 * (2 * m + (fr >> 3)) + j;
; #pragma unroll
;                 for (int bj = 0; bj < 2; ++bj) {
;                     const int t0 = tb + bj * 128;
;                     float v[8];
; #pragma unroll
;                     for (int jj = 0; jj < 4; ++jj) { v[jj] = acc[ai][bj][m][0][jj]; v[4 + jj] = acc[ai][bj][m][1][jj]; }
;                     if constexpr (ROPE) {
;                         const int t = t0 & 2047;
; #pragma unroll
;                         for (int hf = 0; hf < 2; ++hf) {
;                             f32x4 cs, sn;
;                             if (m < 2) { const float c1 = ropeA[(t >> 6) * 16 + d], s1 = ropeA[1024 + (t >> 6) * 16 + d]; cs = (f32x4){c1, c1, c1, c1}; sn = (f32x4){s1, s1, s1, s1}; }
;                             else { const float* cb = ropeA + 2048 + (d - 16) * 64 + (t & 63) + 4 * hf; cs = *(const f32x4*)(cb); sn = *(const f32x4*)(cb + 1024); }
; #pragma unroll
;                             for (int jj = 0; jj < 4; ++jj) { const float pr = __shfl_xor(v[4 * hf + jj], 4); v[4 * hf + jj] = v[4 * hf + jj] * cs[jj] + sgn * pr * sn[jj]; }
;                             __builtin_amdgcn_sched_barrier(0);
;                         }
;                     }
;                     float zf[8], zb[8]; zf[0] = zf0; zb[0] = zb0;
; #pragma unroll
;                     for (int jj = 1; jj < 8; ++jj) { zf[jj] = zf[jj - 1] * zfs; zb[jj] = zb[jj - 1] * zbs; }
;                     u32x4 wf, wb;
;                     wf.x = cvt_pk_bf16(v[0] * zf[0], v[1] * zf[1]); wf.y = cvt_pk_bf16(v[2] * zf[2], v[3] * zf[3]); wf.z = cvt_pk_bf16(v[4] * zf[4], v[5] * zf[5]); wf.w = cvt_pk_bf16(v[6] * zf[6], v[7] * zf[7]);
;                     wb.x = cvt_pk_bf16(v[0] * zb[0], v[1] * zb[1]); wb.y = cvt_pk_bf16(v[2] * zb[2], v[3] * zb[3]); wb.z = cvt_pk_bf16(v[4] * zb[4], v[5] * zb[5]); wb.w = cvt_pk_bf16(v[6] * zb[6], v[7] * zb[7]);
;                     *(u32x4*)(KTZ + (size_t)r * NT + t0) = wf;
;                     *(u32x4*)(KTZ + (size_t)(256 + r) * NT + t0) = wb;
;                     __builtin_amdgcn_sched_barrier(0);
	v_mul_f32_e32 v107, v97, v171
	v_cvt_pk_bf16_f32 v106, v106, v107
	v_mul_f32_e32 v107, v98, v174
	v_mul_f32_e32 v100, v100, v156
	v_mul_f32_e32 v101, v101, v157
	v_mul_f32_e32 v108, v99, v177
	v_cvt_pk_bf16_f32 v107, v107, v108
	v_cvt_pk_bf16_f32 v100, v100, v101
	v_mul_f32_e32 v101, v102, v124
	v_mul_f32_e32 v102, v103, v125
	v_mul_f32_e32 v96, v96, v126
	v_mul_f32_e32 v97, v97, v172
	v_cvt_pk_bf16_f32 v101, v101, v102
	v_cvt_pk_bf16_f32 v102, v96, v97
	v_mul_f32_e32 v96, v98, v175
	v_mul_f32_e32 v97, v99, v162
	v_cvt_pk_bf16_f32 v103, v96, v97
	global_store_dwordx4 v[116:117], v[104:107], off offset:256
	global_store_dwordx4 v[112:113], v[100:103], off offset:256
	v_mul_f32_e32 v96, v92, v163
	v_mul_f32_e32 v97, v93, v164
	v_cvt_pk_bf16_f32 v96, v96, v97
	v_mul_f32_e32 v97, v94, v166
	v_mul_f32_e32 v98, v95, v168
	v_cvt_pk_bf16_f32 v97, v97, v98
	v_mul_f32_e32 v98, v88, v170
	v_mul_f32_e32 v99, v89, v171
	v_cvt_pk_bf16_f32 v98, v98, v99
	v_mul_f32_e32 v99, v90, v174
	v_mul_f32_e32 v92, v92, v156
	v_mul_f32_e32 v93, v93, v157
	v_mul_f32_e32 v100, v91, v177
	v_cvt_pk_bf16_f32 v99, v99, v100
	v_cvt_pk_bf16_f32 v92, v92, v93
	v_mul_f32_e32 v93, v94, v124
	v_mul_f32_e32 v94, v95, v125
	v_mul_f32_e32 v88, v88, v126
	s_mov_b64 s[2:3], 0x80000
	v_cvt_pk_bf16_f32 v93, v93, v94
	v_mul_f32_e32 v89, v89, v172
	v_cvt_pk_bf16_f32 v94, v88, v89
	v_mul_f32_e32 v88, v90, v175
	v_lshl_add_u64 v[100:101], v[140:141], 0, s[2:3]
	s_mov_b32 s2, 0x80000
	v_mul_f32_e32 v89, v91, v162
	v_cvt_pk_bf16_f32 v95, v88, v89
	v_add_co_u32_e32 v88, vcc, s2, v140
	s_mov_b64 s[2:3], 0x480000
	s_nop 0
	v_addc_co_u32_e32 v89, vcc, 0, v141, vcc
	global_store_dwordx4 v[88:89], v[96:99], off
	s_nop 1
	v_lshl_add_u64 v[96:97], v[140:141], 0, s[2:3]
	s_mov_b32 s2, 0x480000
	v_add_co_u32_e32 v88, vcc, s2, v140
	s_nop 1
	v_addc_co_u32_e32 v89, vcc, 0, v141, vcc
	global_store_dwordx4 v[88:89], v[92:95], off
	v_mul_f32_e32 v88, v84, v163
	v_mul_f32_e32 v89, v85, v164
	v_cvt_pk_bf16_f32 v88, v88, v89
	v_mul_f32_e32 v89, v86, v166
	v_mul_f32_e32 v90, v87, v168
	v_cvt_pk_bf16_f32 v89, v89, v90
	v_mul_f32_e32 v90, v80, v170
	v_mul_f32_e32 v91, v81, v171
	v_cvt_pk_bf16_f32 v90, v90, v91
	v_mul_f32_e32 v91, v82, v174
	v_mul_f32_e32 v84, v84, v156
	v_mul_f32_e32 v85, v85, v157
	v_mul_f32_e32 v92, v83, v177
	v_cvt_pk_bf16_f32 v91, v91, v92
	v_cvt_pk_bf16_f32 v84, v84, v85
	v_mul_f32_e32 v85, v86, v124
	v_mul_f32_e32 v86, v87, v125
	v_mul_f32_e32 v80, v80, v126
	v_mul_f32_e32 v81, v81, v172
	v_cvt_pk_bf16_f32 v85, v85, v86
	v_cvt_pk_bf16_f32 v86, v80, v81
	v_mul_f32_e32 v80, v82, v175
	v_mul_f32_e32 v81, v83, v162
	v_cvt_pk_bf16_f32 v87, v80, v81
	global_store_dwordx4 v[100:101], v[88:91], off offset:256
	global_store_dwordx4 v[96:97], v[84:87], off offset:256
	v_mul_f32_e32 v80, v76, v163
	v_mul_f32_e32 v81, v77, v164
	v_cvt_pk_bf16_f32 v80, v80, v81
	v_mul_f32_e32 v81, v78, v166
	v_mul_f32_e32 v82, v79, v168
	v_cvt_pk_bf16_f32 v81, v81, v82
	v_mul_f32_e32 v82, v72, v170
	v_mul_f32_e32 v83, v73, v171
	v_cvt_pk_bf16_f32 v82, v82, v83
	v_mul_f32_e32 v83, v74, v174
	v_mul_f32_e32 v76, v76, v156
	v_mul_f32_e32 v77, v77, v157
	v_mul_f32_e32 v84, v75, v177
	v_cvt_pk_bf16_f32 v83, v83, v84
	v_cvt_pk_bf16_f32 v76, v76, v77
	v_mul_f32_e32 v77, v78, v124
	v_mul_f32_e32 v78, v79, v125
	v_mul_f32_e32 v72, v72, v126
	s_mov_b64 s[2:3], 0xc0000
	v_cvt_pk_bf16_f32 v77, v77, v78
	v_mul_f32_e32 v73, v73, v172
	v_cvt_pk_bf16_f32 v78, v72, v73
	v_mul_f32_e32 v72, v74, v175
	v_lshl_add_u64 v[84:85], v[140:141], 0, s[2:3]
	s_mov_b32 s2, 0xc0000
	v_mul_f32_e32 v73, v75, v162
	v_cvt_pk_bf16_f32 v79, v72, v73
	v_add_co_u32_e32 v72, vcc, s2, v140
	s_mov_b64 s[2:3], 0x4c0000
	s_nop 0
	v_addc_co_u32_e32 v73, vcc, 0, v141, vcc
	global_store_dwordx4 v[72:73], v[80:83], off
	s_nop 1
	v_lshl_add_u64 v[80:81], v[140:141], 0, s[2:3]
	s_mov_b32 s2, 0x4c0000
	v_add_co_u32_e32 v72, vcc, s2, v140
	s_nop 1
	v_addc_co_u32_e32 v73, vcc, 0, v141, vcc
	global_store_dwordx4 v[72:73], v[76:79], off
	v_mul_f32_e32 v72, v68, v163
	v_mul_f32_e32 v73, v69, v164
	v_cvt_pk_bf16_f32 v72, v72, v73
	v_mul_f32_e32 v73, v70, v166
	v_mul_f32_e32 v74, v71, v168
	v_cvt_pk_bf16_f32 v73, v73, v74
	v_mul_f32_e32 v74, v64, v170
	v_mul_f32_e32 v75, v65, v171
	v_cvt_pk_bf16_f32 v74, v74, v75
	v_mul_f32_e32 v75, v66, v174
	v_mul_f32_e32 v68, v68, v156
	v_mul_f32_e32 v69, v69, v157
	v_mul_f32_e32 v76, v67, v177
	v_cvt_pk_bf16_f32 v75, v75, v76
	v_cvt_pk_bf16_f32 v68, v68, v69
	v_mul_f32_e32 v69, v70, v124
	v_mul_f32_e32 v70, v71, v125
	v_mul_f32_e32 v64, v64, v126
	v_mul_f32_e32 v65, v65, v172
	v_cvt_pk_bf16_f32 v69, v69, v70
	v_cvt_pk_bf16_f32 v70, v64, v65
	v_mul_f32_e32 v64, v66, v175
	v_mul_f32_e32 v65, v67, v162
	v_cvt_pk_bf16_f32 v71, v64, v65
	global_store_dwordx4 v[84:85], v[72:75], off offset:256
	global_store_dwordx4 v[80:81], v[68:71], off offset:256
	global_load_dword v70, v131, s[6:7] offset:8
	s_nop 0
	global_load_dword v71, v131, s[6:7] offset:24
	s_mov_b32 s17, 0x200000
	v_add_co_u32_e32 v76, vcc, s17, v140
	s_mov_b32 s19, 0x600000
	s_nop 0
	v_addc_co_u32_e32 v77, vcc, 0, v141, vcc
	v_add_co_u32_e32 v68, vcc, s19, v140
	s_mov_b64 s[2:3], 0x200000
	s_nop 0
	v_addc_co_u32_e32 v69, vcc, 0, v141, vcc
	s_mov_b64 s[4:5], 0x600000
	v_lshl_add_u64 v[64:65], v[140:141], 0, s[2:3]
	v_lshl_add_u64 v[66:67], v[140:141], 0, s[4:5]
	s_waitcnt vmcnt(0)
; __device__ __forceinline__ unsigned cvt_pk_bf16(float lo, float hi) { unsigned r; asm volatile("v_cvt_pk_bf16_f32 %0, %1, %2" : "=v"(r) : "v"(lo), "v"(hi)); return r; }
;     __device__ __forceinline__ void operator()(const AccT& acc, const Unit& u, int wr, int wc, int fr, int fq) const {
;     ...
;             const int hh = 2 * ai + wr;
;             const float l2f = lgd[hh] * 1.4426950408889634f, l2b = lgd[4 + hh] * 1.4426950408889634f;
;             const float zf0 = exp2f((float)(127 - o0) * l2f), zfs = exp2f(-l2f), zb0 = exp2f((float)o0 * l2b), zbs = exp2f(l2b);
; #pragma unroll
;             for (int m = 0; m < 4; ++m) {
;                 const int r = rbase + ai * 128 + m * 16;
;                 const int d = 4 * (2 * m + (fr >> 3)) + j;
; #pragma unroll
;                 for (int bj = 0; bj < 2; ++bj) {
;                     const int t0 = tb + bj * 128;
;                     float v[8];
; #pragma unroll
;                     for (int jj = 0; jj < 4; ++jj) { v[jj] = acc[ai][bj][m][0][jj]; v[4 + jj] = acc[ai][bj][m][1][jj]; }
;                     if constexpr (ROPE) {
;                         const int t = t0 & 2047;
; #pragma unroll
;                         for (int hf = 0; hf < 2; ++hf) {
;                             f32x4 cs, sn;
;                             if (m < 2) { const float c1 = ropeA[(t >> 6) * 16 + d], s1 = ropeA[1024 + (t >> 6) * 16 + d]; cs = (f32x4){c1, c1, c1, c1}; sn = (f32x4){s1, s1, s1, s1}; }
;                             else { const float* cb = ropeA + 2048 + (d - 16) * 64 + (t & 63) + 4 * hf; cs = *(const f32x4*)(cb); sn = *(const f32x4*)(cb + 1024); }
; #pragma unroll
;                             for (int jj = 0; jj < 4; ++jj) { const float pr = __shfl_xor(v[4 * hf + jj], 4); v[4 * hf + jj] = v[4 * hf + jj] * cs[jj] + sgn * pr * sn[jj]; }
;                             __builtin_amdgcn_sched_barrier(0);
;                         }
;                     }
;                     float zf[8], zb[8]; zf[0] = zf0; zb[0] = zb0;
; #pragma unroll
;                     for (int jj = 1; jj < 8; ++jj) { zf[jj] = zf[jj - 1] * zfs; zb[jj] = zb[jj - 1] * zbs; }
;                     u32x4 wf, wb;
;                     wf.x = cvt_pk_bf16(v[0] * zf[0], v[1] * zf[1]); wf.y = cvt_pk_bf16(v[2] * zf[2], v[3] * zf[3]); wf.z = cvt_pk_bf16(v[4] * zf[4], v[5] * zf[5]); wf.w = cvt_pk_bf16(v[6] * zf[6], v[7] * zf[7]);
	v_mul_f32_e32 v72, 0x3fb8aa3b, v70
	v_mul_f32_e32 v73, 0x3fb8aa3b, v71
	v_mul_f32_e32 v74, v72, v155
	v_cmp_lt_f32_e32 vcc, s51, v72
	v_mul_f32_e32 v78, v73, v154
	v_cmp_gt_f32_e64 s[2:3], s49, v73
	v_cndmask_b32_e32 v75, 0, v153, vcc
	v_cmp_gt_f32_e64 s[4:5], s49, v74
	v_cndmask_b32_e64 v79, 0, v153, s[2:3]
	s_and_b64 s[24:25], vcc, exec
	v_cmp_gt_f32_e32 vcc, s49, v78
	v_fmac_f32_e32 v79, 0x3fb8aa3b, v71
	v_cndmask_b32_e64 v71, 0, v153, s[4:5]
	v_cndmask_b32_e32 v78, 0, v153, vcc
	v_fmac_f32_e32 v75, 0xbfb8aa3b, v70
	v_fmac_f32_e32 v71, v72, v155
	v_fmac_f32_e32 v78, v73, v154
	v_exp_f32_e32 v75, v75
	v_exp_f32_e32 v79, v79
	v_exp_f32_e32 v71, v71
	v_exp_f32_e32 v72, v78
	v_cndmask_b32_e64 v74, 0, v152, s[4:5]
	s_cselect_b32 s4, 0xffffffc0, 0
	s_and_b64 s[2:3], s[2:3], exec
	v_cndmask_b32_e32 v70, 0, v152, vcc
	s_cselect_b32 s2, 0xffffffc0, 0
	v_ldexp_f32 v75, v75, s4
	v_ldexp_f32 v78, v79, s2
	v_ldexp_f32 v79, v71, v74
	v_ldexp_f32 v70, v72, v70
	v_mul_f32_e32 v80, v75, v79
	v_mul_f32_e32 v71, v78, v70
	v_mul_f32_e32 v72, v60, v79
	v_mul_f32_e32 v81, v60, v70
	v_mul_f32_e32 v82, v75, v80
	v_mul_f32_e32 v60, v78, v71
	v_mul_f32_e32 v83, v75, v82
	v_mul_f32_e32 v84, v78, v60
	v_mul_f32_e32 v85, v75, v83
	v_mul_f32_e32 v86, v78, v84
	v_mul_f32_e32 v73, v61, v80
	v_mul_f32_e32 v87, v75, v85
	v_mul_f32_e32 v88, v78, v86
	v_cvt_pk_bf16_f32 v72, v72, v73
	v_mul_f32_e32 v73, v62, v82
	v_mul_f32_e32 v74, v63, v83
	v_mul_f32_e32 v90, v75, v87
	v_mul_f32_e32 v91, v78, v88
	v_cvt_pk_bf16_f32 v73, v73, v74
	v_mul_f32_e32 v74, v56, v85
	v_mul_f32_e32 v89, v56, v86
	v_mul_f32_e32 v56, v57, v87
	v_mul_f32_e32 v93, v75, v90
	v_mul_f32_e32 v78, v78, v91
	v_mul_f32_e32 v92, v57, v88
	v_cvt_pk_bf16_f32 v74, v74, v56
	v_mul_f32_e32 v56, v58, v90
	v_mul_f32_e32 v57, v59, v93
	v_mul_f32_e32 v59, v59, v78
	v_cvt_pk_bf16_f32 v75, v56, v57
	v_mul_f32_e32 v61, v61, v71
	v_mul_f32_e32 v62, v62, v60
	v_mul_f32_e32 v63, v63, v84
	v_mul_f32_e32 v94, v58, v91
	v_cvt_pk_bf16_f32 v56, v81, v61
	v_cvt_pk_bf16_f32 v57, v62, v63
	v_cvt_pk_bf16_f32 v58, v89, v92
	v_cvt_pk_bf16_f32 v59, v94, v59
	global_store_dwordx4 v[76:77], v[72:75], off
	global_store_dwordx4 v[68:69], v[56:59], off
	s_nop 1
	v_mul_f32_e32 v56, v52, v79
	v_mul_f32_e32 v57, v53, v80
	v_cvt_pk_bf16_f32 v56, v56, v57
	v_mul_f32_e32 v57, v54, v82
	v_mul_f32_e32 v58, v55, v83
	v_cvt_pk_bf16_f32 v57, v57, v58
	v_mul_f32_e32 v58, v48, v85
	v_mul_f32_e32 v59, v49, v87
	v_cvt_pk_bf16_f32 v58, v58, v59
	v_mul_f32_e32 v59, v50, v90
	v_mul_f32_e32 v52, v52, v70
	v_mul_f32_e32 v53, v53, v71
	v_mul_f32_e32 v61, v51, v93
	v_cvt_pk_bf16_f32 v59, v59, v61
	v_cvt_pk_bf16_f32 v52, v52, v53
	v_mul_f32_e32 v53, v54, v60
	v_mul_f32_e32 v54, v55, v84
	v_mul_f32_e32 v48, v48, v86
	v_mul_f32_e32 v49, v49, v88
	v_cvt_pk_bf16_f32 v53, v53, v54
	v_cvt_pk_bf16_f32 v54, v48, v49
	v_mul_f32_e32 v48, v50, v91
	v_mul_f32_e32 v49, v51, v78
	v_cvt_pk_bf16_f32 v55, v48, v49
	global_store_dwordx4 v[64:65], v[56:59], off offset:256
	global_store_dwordx4 v[66:67], v[52:55], off offset:256
	v_mul_f32_e32 v48, v44, v79
	v_mul_f32_e32 v49, v45, v80
	v_cvt_pk_bf16_f32 v48, v48, v49
	v_mul_f32_e32 v49, v46, v82
	v_mul_f32_e32 v50, v47, v83
	v_cvt_pk_bf16_f32 v49, v49, v50
	v_mul_f32_e32 v50, v40, v85
	v_mul_f32_e32 v51, v41, v87
	v_cvt_pk_bf16_f32 v50, v50, v51
	v_mul_f32_e32 v51, v42, v90
	v_mul_f32_e32 v44, v44, v70
	v_mul_f32_e32 v45, v45, v71
	v_mul_f32_e32 v52, v43, v93
	v_cvt_pk_bf16_f32 v51, v51, v52
	v_cvt_pk_bf16_f32 v44, v44, v45
	v_mul_f32_e32 v45, v46, v60
	v_mul_f32_e32 v46, v47, v84
	v_mul_f32_e32 v40, v40, v86
	s_mov_b64 s[2:3], 0x240000
	v_cvt_pk_bf16_f32 v45, v45, v46
	v_mul_f32_e32 v41, v41, v88
	v_cvt_pk_bf16_f32 v46, v40, v41
	v_mul_f32_e32 v40, v42, v91
	v_lshl_add_u64 v[52:53], v[140:141], 0, s[2:3]
	s_mov_b32 s2, 0x240000
	v_mul_f32_e32 v41, v43, v78
	v_cvt_pk_bf16_f32 v47, v40, v41
	v_add_co_u32_e32 v40, vcc, s2, v140
	s_mov_b64 s[2:3], 0x640000
	s_nop 0
	v_addc_co_u32_e32 v41, vcc, 0, v141, vcc
	global_store_dwordx4 v[40:41], v[48:51], off
	s_nop 1
	v_lshl_add_u64 v[48:49], v[140:141], 0, s[2:3]
	s_mov_b32 s2, 0x640000
	v_add_co_u32_e32 v40, vcc, s2, v140
	s_nop 1
	v_addc_co_u32_e32 v41, vcc, 0, v141, vcc
	global_store_dwordx4 v[40:41], v[44:47], off
	v_mul_f32_e32 v40, v36, v79
	v_mul_f32_e32 v41, v37, v80
	v_cvt_pk_bf16_f32 v40, v40, v41
	v_mul_f32_e32 v41, v38, v82
	v_mul_f32_e32 v42, v39, v83
	v_cvt_pk_bf16_f32 v41, v41, v42
	v_mul_f32_e32 v42, v32, v85
	v_mul_f32_e32 v43, v33, v87
	v_cvt_pk_bf16_f32 v42, v42, v43
	v_mul_f32_e32 v43, v34, v90
	v_mul_f32_e32 v36, v36, v70
;     __device__ __forceinline__ void operator()(const AccT& acc, const Unit& u, int wr, int wc, int fr, int fq) const {
;     ...
;             for (int m = 0; m < 4; ++m) {
;                 const int r = rbase + ai * 128 + m * 16;
;                 const int d = 4 * (2 * m + (fr >> 3)) + j;
; #pragma unroll
;                 for (int bj = 0; bj < 2; ++bj) {
;                     const int t0 = tb + bj * 128;
;                     float v[8];
; #pragma unroll
;                     for (int jj = 0; jj < 4; ++jj) { v[jj] = acc[ai][bj][m][0][jj]; v[4 + jj] = acc[ai][bj][m][1][jj]; }
;                     if constexpr (ROPE) {
;                         const int t = t0 & 2047;
; #pragma unroll
;                         for (int hf = 0; hf < 2; ++hf) {
;                             f32x4 cs, sn;
;                             if (m < 2) { const float c1 = ropeA[(t >> 6) * 16 + d], s1 = ropeA[1024 + (t >> 6) * 16 + d]; cs = (f32x4){c1, c1, c1, c1}; sn = (f32x4){s1, s1, s1, s1}; }
;                             else { const float* cb = ropeA + 2048 + (d - 16) * 64 + (t & 63) + 4 * hf; cs = *(const f32x4*)(cb); sn = *(const f32x4*)(cb + 1024); }
; #pragma unroll
;                             for (int jj = 0; jj < 4; ++jj) { const float pr = __shfl_xor(v[4 * hf + jj], 4); v[4 * hf + jj] = v[4 * hf + jj] * cs[jj] + sgn * pr * sn[jj]; }
;                             __builtin_amdgcn_sched_barrier(0);
;                         }
;                     }
;                     float zf[8], zb[8]; zf[0] = zf0; zb[0] = zb0;
; #pragma unroll
;                     for (int jj = 1; jj < 8; ++jj) { zf[jj] = zf[jj - 1] * zfs; zb[jj] = zb[jj - 1] * zbs; }
;                     u32x4 wf, wb;
;                     wf.x = cvt_pk_bf16(v[0] * zf[0], v[1] * zf[1]); wf.y = cvt_pk_bf16(v[2] * zf[2], v[3] * zf[3]); wf.z = cvt_pk_bf16(v[4] * zf[4], v[5] * zf[5]); wf.w = cvt_pk_bf16(v[6] * zf[6], v[7] * zf[7]);
;                     wb.x = cvt_pk_bf16(v[0] * zb[0], v[1] * zb[1]); wb.y = cvt_pk_bf16(v[2] * zb[2], v[3] * zb[3]); wb.z = cvt_pk_bf16(v[4] * zb[4], v[5] * zb[5]); wb.w = cvt_pk_bf16(v[6] * zb[6], v[7] * zb[7]);
;                     *(u32x4*)(KTZ + (size_t)r * NT + t0) = wf;
;                     *(u32x4*)(KTZ + (size_t)(256 + r) * NT + t0) = wb;
;                     __builtin_amdgcn_sched_barrier(0);
	v_mul_f32_e32 v37, v37, v71
	v_mul_f32_e32 v44, v35, v93
	v_cvt_pk_bf16_f32 v43, v43, v44
	v_cvt_pk_bf16_f32 v36, v36, v37
	v_mul_f32_e32 v37, v38, v60
	v_mul_f32_e32 v38, v39, v84
	v_mul_f32_e32 v32, v32, v86
	v_mul_f32_e32 v33, v33, v88
	v_cvt_pk_bf16_f32 v37, v37, v38
	v_cvt_pk_bf16_f32 v38, v32, v33
	v_mul_f32_e32 v32, v34, v91
	v_mul_f32_e32 v33, v35, v78
	v_cvt_pk_bf16_f32 v39, v32, v33
	global_store_dwordx4 v[52:53], v[40:43], off offset:256
	global_store_dwordx4 v[48:49], v[36:39], off offset:256
	v_mul_f32_e32 v32, v28, v79
	v_mul_f32_e32 v33, v29, v80
	v_cvt_pk_bf16_f32 v32, v32, v33
	v_mul_f32_e32 v33, v30, v82
	v_mul_f32_e32 v34, v31, v83
	v_cvt_pk_bf16_f32 v33, v33, v34
	v_mul_f32_e32 v34, v24, v85
	v_mul_f32_e32 v35, v25, v87
	v_cvt_pk_bf16_f32 v34, v34, v35
	v_mul_f32_e32 v35, v26, v90
	v_mul_f32_e32 v28, v28, v70
	v_mul_f32_e32 v29, v29, v71
	v_mul_f32_e32 v36, v27, v93
	v_cvt_pk_bf16_f32 v35, v35, v36
	v_cvt_pk_bf16_f32 v28, v28, v29
	v_mul_f32_e32 v29, v30, v60
	v_mul_f32_e32 v30, v31, v84
	v_mul_f32_e32 v24, v24, v86
	v_cvt_pk_bf16_f32 v29, v29, v30
	v_mul_f32_e32 v25, v25, v88
	v_cvt_pk_bf16_f32 v30, v24, v25
	v_mul_f32_e32 v24, v26, v91
	v_mul_f32_e32 v25, v27, v78
	v_cvt_pk_bf16_f32 v31, v24, v25
	v_add_co_u32_e32 v24, vcc, s52, v140
	s_mov_b64 s[2:3], 0x280000
	s_nop 0
	v_addc_co_u32_e32 v25, vcc, 0, v141, vcc
	global_store_dwordx4 v[24:25], v[32:35], off
	v_add_co_u32_e32 v24, vcc, s53, v140
	v_lshl_add_u64 v[36:37], v[140:141], 0, s[2:3]
	s_nop 0
	v_addc_co_u32_e32 v25, vcc, 0, v141, vcc
	v_lshl_add_u64 v[32:33], v[140:141], 0, s[8:9]
	global_store_dwordx4 v[24:25], v[28:31], off
	v_mul_f32_e32 v24, v20, v79
	v_mul_f32_e32 v25, v21, v80
	v_cvt_pk_bf16_f32 v24, v24, v25
	v_mul_f32_e32 v25, v22, v82
	v_mul_f32_e32 v26, v23, v83
	v_cvt_pk_bf16_f32 v25, v25, v26
	v_mul_f32_e32 v26, v16, v85
	v_mul_f32_e32 v27, v17, v87
	v_cvt_pk_bf16_f32 v26, v26, v27
	v_mul_f32_e32 v27, v18, v90
	v_mul_f32_e32 v20, v20, v70
	v_mul_f32_e32 v21, v21, v71
	v_mul_f32_e32 v28, v19, v93
	v_cvt_pk_bf16_f32 v27, v27, v28
	v_cvt_pk_bf16_f32 v20, v20, v21
	v_mul_f32_e32 v21, v22, v60
	v_mul_f32_e32 v22, v23, v84
	v_mul_f32_e32 v16, v16, v86
	v_mul_f32_e32 v17, v17, v88
	v_cvt_pk_bf16_f32 v21, v21, v22
	v_cvt_pk_bf16_f32 v22, v16, v17
	v_mul_f32_e32 v16, v18, v91
	v_mul_f32_e32 v17, v19, v78
	v_cvt_pk_bf16_f32 v23, v16, v17
	global_store_dwordx4 v[36:37], v[24:27], off offset:256
	global_store_dwordx4 v[32:33], v[20:23], off offset:256
	v_mul_f32_e32 v16, v12, v79
	v_mul_f32_e32 v17, v13, v80
	v_cvt_pk_bf16_f32 v16, v16, v17
	v_mul_f32_e32 v17, v14, v82
	v_mul_f32_e32 v18, v15, v83
	v_cvt_pk_bf16_f32 v17, v17, v18
	v_mul_f32_e32 v18, v8, v85
	v_mul_f32_e32 v19, v9, v87
	v_cvt_pk_bf16_f32 v18, v18, v19
	v_mul_f32_e32 v19, v10, v90
	v_mul_f32_e32 v12, v12, v70
	v_mul_f32_e32 v13, v13, v71
	v_mul_f32_e32 v20, v11, v93
	v_cvt_pk_bf16_f32 v19, v19, v20
	v_cvt_pk_bf16_f32 v12, v12, v13
	v_mul_f32_e32 v13, v14, v60
	v_mul_f32_e32 v14, v15, v84
	v_mul_f32_e32 v8, v8, v86
	v_cvt_pk_bf16_f32 v13, v13, v14
	v_mul_f32_e32 v9, v9, v88
	v_cvt_pk_bf16_f32 v14, v8, v9
	v_mul_f32_e32 v8, v10, v91
	v_mul_f32_e32 v9, v11, v78
	v_cvt_pk_bf16_f32 v15, v8, v9
	v_add_co_u32_e32 v8, vcc, s54, v140
	v_lshl_add_u64 v[20:21], v[140:141], 0, s[10:11]
	s_nop 0
	v_addc_co_u32_e32 v9, vcc, 0, v141, vcc
	global_store_dwordx4 v[8:9], v[16:19], off
	v_add_co_u32_e32 v8, vcc, s55, v140
	s_nop 0
	v_lshl_add_u64 v[16:17], v[140:141], 0, s[12:13]
	v_addc_co_u32_e32 v9, vcc, 0, v141, vcc
	global_store_dwordx4 v[8:9], v[12:15], off
	v_mul_f32_e32 v8, v4, v79
	v_mul_f32_e32 v9, v5, v80
	v_cvt_pk_bf16_f32 v8, v8, v9
	v_mul_f32_e32 v9, v6, v82
	v_mul_f32_e32 v10, v7, v83
	v_cvt_pk_bf16_f32 v9, v9, v10
	v_mul_f32_e32 v10, v0, v85
	v_mul_f32_e32 v11, v1, v87
	v_cvt_pk_bf16_f32 v10, v10, v11
	v_mul_f32_e32 v11, v2, v90
	v_mul_f32_e32 v4, v4, v70
	v_mul_f32_e32 v5, v5, v71
	v_mul_f32_e32 v12, v3, v93
	v_cvt_pk_bf16_f32 v11, v11, v12
	v_cvt_pk_bf16_f32 v4, v4, v5
	v_mul_f32_e32 v5, v6, v60
	v_mul_f32_e32 v6, v7, v84
	v_mul_f32_e32 v0, v0, v86
	v_mul_f32_e32 v1, v1, v88
	v_cvt_pk_bf16_f32 v5, v5, v6
	v_cvt_pk_bf16_f32 v6, v0, v1
	v_mul_f32_e32 v0, v2, v91
	v_mul_f32_e32 v1, v3, v78
	v_cvt_pk_bf16_f32 v7, v0, v1
	global_store_dwordx4 v[20:21], v[8:11], off offset:256
	global_store_dwordx4 v[16:17], v[4:7], off offset:256
	s_and_b64 vcc, exec, s[14:15]
	s_mov_b32 s56, s16
	s_mov_b64 s[4:5], s[22:23]
	s_mov_b64 s[2:3], s[20:21]
	s_barrier
	s_cbranch_vccz .LBB0_686
.Lconc_end_g7:
	s_waitcnt vmcnt(0)
	s_cmpk_gt_u32 s27, 0xff
	s_cbranch_scc1 .LBB0_697
	s_barrier

; #define PG8_STAGE(bufoff, gbase, voff) do { _Pragma("unroll") for (int _i = 0; _i < 2; ++_i) \
;         __builtin_amdgcn_global_load_lds((const unsigned*)((const char*)(gbase) + (voff)[_i]), (LAS unsigned*)(lds + (bufoff) + ldsw + _i * 8192), 16, 0, 0); } while (0)
; #define PG8_LDA(dst, b, h) do { _Pragma("unroll") for (int m = 0; m < 4; ++m) _Pragma("unroll") for (int k = 0; k < 2; ++k) dst[m][k] = *(const LAS bf16x8*)(lds + PG8_SA(b, h) + aoff + m * 2048 + k * 1024); } while (0)
; #define PG8_LDB(dst, b, h) do { _Pragma("unroll") for (int n = 0; n < 2; ++n) _Pragma("unroll") for (int k = 0; k < 2; ++k) dst[n][k] = *(const LAS bf16x8*)(lds + PG8_SB(b, h) + boff + n * 2048 + k * 1024); } while (0)
; #define PG8_MMA(ai, bj, At, Bt) do { __builtin_amdgcn_s_setprio(1); _Pragma("unroll") for (int m = 0; m < 4; ++m) _Pragma("unroll") for (int n = 0; n < 2; ++n) _Pragma("unroll") for (int k = 0; k < 2; ++k) \
;         acc[ai][bj][m][n] = __builtin_amdgcn_mfma_f32_16x16x32_bf16(Bt[n][k], At[m][k], acc[ai][bj][m][n], 0, 0, 0); __builtin_amdgcn_s_setprio(0); } while (0)
; #define PG8_WAIT_V(n) asm volatile("s_waitcnt vmcnt(" #n ")" ::: "memory")
; #define PG8_WAIT_L(n) asm volatile("s_waitcnt lgkmcnt(" #n ")" ::: "memory")
; #define PG8_BAR __builtin_amdgcn_s_barrier()
; #define PG8_SCHED __builtin_amdgcn_sched_barrier(0)
; template <class Epi, class Sched>
; __device__ __forceinline__ void gemm_phase(LAS unsigned char* lds, const Gemm g, const Sched& S, const Epi& E) {
;     ...
;             PG8_LDB(B0, 0, 0); PG8_SCHED; PG8_LDA(At, 0, 0); PG8_STAGE(PG8_SA(1, 1), a1 + hstep, voffA);
;             PG8_WAIT_L(8); PG8_BAR; PG8_WAIT_L(0); PG8_MMA(0, 0, At, B0); PG8_BAR; PG8_SCHED;
;             PG8_LDB(B1, 0, 1); PG8_STAGE(PG8_SB(0, 0), b2, voffB);
;             PG8_BAR; PG8_WAIT_L(0); PG8_MMA(0, 1, At, B1); PG8_BAR;
;             PG8_LDA(At, 0, 1); PG8_STAGE(PG8_SA(0, 0), a2, voffA);
;             PG8_BAR; PG8_WAIT_L(0); PG8_MMA(1, 0, At, B0); PG8_BAR; PG8_SCHED;
;             PG8_STAGE(PG8_SB(0, 1), b2 + hstep, voffB);
;             PG8_WAIT_V(6); PG8_BAR; PG8_MMA(1, 1, At, B1); PG8_BAR;
.LBB0_713:
	ds_read_b128 v[146:149], v143
	ds_read_b128 v[150:153], v143 offset:1024
	ds_read_b128 v[154:157], v143 offset:2048
	ds_read_b128 v[158:161], v143 offset:3072
	s_add_u32 s24, s22, 0xfffc0080
	s_addc_u32 s25, s23, -1
	s_cmp_eq_u32 s58, 12
	s_cselect_b32 s27, s15, s25
	s_cselect_b32 s26, s54, s24
	s_cselect_b32 s25, s13, s57
	s_cselect_b32 s24, s55, s56
	s_add_i32 m0, s21, 0xc000
	ds_read_b128 v[162:165], v144
	ds_read_b128 v[166:169], v144 offset:1024
	ds_read_b128 v[170:173], v144 offset:2048
	ds_read_b128 v[174:177], v144 offset:3072
	ds_read_b128 v[178:181], v144 offset:4096
	ds_read_b128 v[182:185], v144 offset:5120
	ds_read_b128 v[186:189], v144 offset:6144
	ds_read_b128 v[190:193], v144 offset:7168
	global_load_lds_dwordx4 v136, s[22:23]
	s_add_i32 m0, s21, 0xe000
	s_nop 0
	global_load_lds_dwordx4 v138, s[22:23]
	s_waitcnt lgkmcnt(8)
	s_waitcnt vmcnt(10)
	s_barrier
	s_waitcnt lgkmcnt(0)
	s_setprio 1
	s_waitcnt lgkmcnt(0)
	v_mfma_f32_16x16x32_bf16 v[124:127], v[146:149], v[162:165], v[124:127]
	v_mfma_f32_16x16x32_bf16 v[120:123], v[154:157], v[162:165], v[120:123]
	v_mfma_f32_16x16x32_bf16 v[116:119], v[146:149], v[170:173], v[116:119]
	v_mfma_f32_16x16x32_bf16 v[108:111], v[154:157], v[170:173], v[108:111]
	v_mfma_f32_16x16x32_bf16 v[100:103], v[146:149], v[178:181], v[100:103]
	v_mfma_f32_16x16x32_bf16 v[92:95], v[154:157], v[178:181], v[92:95]
	v_mfma_f32_16x16x32_bf16 v[84:87], v[146:149], v[186:189], v[84:87]
	v_mfma_f32_16x16x32_bf16 v[76:79], v[154:157], v[186:189], v[76:79]
	v_mfma_f32_16x16x32_bf16 v[124:127], v[150:153], v[166:169], v[124:127]
	v_mfma_f32_16x16x32_bf16 v[120:123], v[158:161], v[166:169], v[120:123]
	v_mfma_f32_16x16x32_bf16 v[116:119], v[150:153], v[174:177], v[116:119]
	v_mfma_f32_16x16x32_bf16 v[108:111], v[158:161], v[174:177], v[108:111]
	v_mfma_f32_16x16x32_bf16 v[100:103], v[150:153], v[182:185], v[100:103]
	v_mfma_f32_16x16x32_bf16 v[92:95], v[158:161], v[182:185], v[92:95]
	v_mfma_f32_16x16x32_bf16 v[84:87], v[150:153], v[190:193], v[84:87]
	v_mfma_f32_16x16x32_bf16 v[76:79], v[158:161], v[190:193], v[76:79]
	s_setprio 0
	s_barrier
	s_add_i32 s59, s46, s34
	s_mov_b32 m0, s59
	ds_read_b128 v[194:197], v145
	ds_read_b128 v[202:205], v145 offset:1024
	ds_read_b128 v[206:209], v145 offset:2048
	ds_read_b128 v[210:213], v145 offset:3072
	global_load_lds_dwordx4 v130, s[24:25]
	s_add_i32 m0, s59, 0x2000
	s_nop 0
	global_load_lds_dwordx4 v134, s[24:25]
	s_waitcnt vmcnt(10)
	s_barrier
	s_waitcnt lgkmcnt(0)
	s_setprio 1
	s_waitcnt lgkmcnt(0)
	v_mfma_f32_16x16x32_bf16 v[112:115], v[194:197], v[162:165], v[112:115]
	v_mfma_f32_16x16x32_bf16 v[104:107], v[206:209], v[162:165], v[104:107]
	v_mfma_f32_16x16x32_bf16 v[96:99], v[194:197], v[170:173], v[96:99]
	v_mfma_f32_16x16x32_bf16 v[88:91], v[206:209], v[170:173], v[88:91]
	v_mfma_f32_16x16x32_bf16 v[80:83], v[194:197], v[178:181], v[80:83]
	v_mfma_f32_16x16x32_bf16 v[72:75], v[206:209], v[178:181], v[72:75]
	v_mfma_f32_16x16x32_bf16 v[68:71], v[194:197], v[186:189], v[68:71]
	v_mfma_f32_16x16x32_bf16 v[64:67], v[206:209], v[186:189], v[64:67]
	v_mfma_f32_16x16x32_bf16 v[112:115], v[202:205], v[166:169], v[112:115]
	v_mfma_f32_16x16x32_bf16 v[104:107], v[210:213], v[166:169], v[104:107]
	v_mfma_f32_16x16x32_bf16 v[96:99], v[202:205], v[174:177], v[96:99]
	v_mfma_f32_16x16x32_bf16 v[88:91], v[210:213], v[174:177], v[88:91]
	v_mfma_f32_16x16x32_bf16 v[80:83], v[202:205], v[182:185], v[80:83]
	v_mfma_f32_16x16x32_bf16 v[72:75], v[210:213], v[182:185], v[72:75]
	v_mfma_f32_16x16x32_bf16 v[68:71], v[202:205], v[190:193], v[68:71]
	v_mfma_f32_16x16x32_bf16 v[64:67], v[210:213], v[190:193], v[64:67]
	s_setprio 0
	s_mov_b32 m0, s21
	v_lshl_add_u64 v[216:217], s[26:27], 0, v[128:129]
	s_barrier
	ds_read_b128 v[162:165], v144 offset:16384
	ds_read_b128 v[166:169], v144 offset:17408
	ds_read_b128 v[170:173], v144 offset:18432
	ds_read_b128 v[174:177], v144 offset:19456
	ds_read_b128 v[178:181], v144 offset:20480
	ds_read_b128 v[182:185], v144 offset:21504
	ds_read_b128 v[186:189], v144 offset:22528
	ds_read_b128 v[190:193], v144 offset:23552
	global_load_lds_dwordx4 v128, s[26:27]
	v_lshl_add_u64 v[218:219], s[26:27], 0, v[132:133]
	s_mov_b32 m0, s35
	s_nop 0
	global_load_lds_dwordx4 v132, s[26:27]
	s_barrier
	s_waitcnt lgkmcnt(0)
	s_setprio 1
	s_waitcnt lgkmcnt(0)
	v_mfma_f32_16x16x32_bf16 v[60:63], v[146:149], v[162:165], v[60:63]
	v_mfma_f32_16x16x32_bf16 v[56:59], v[154:157], v[162:165], v[56:59]
	v_mfma_f32_16x16x32_bf16 v[52:55], v[146:149], v[170:173], v[52:55]
	v_mfma_f32_16x16x32_bf16 v[44:47], v[154:157], v[170:173], v[44:47]
	v_mfma_f32_16x16x32_bf16 v[36:39], v[146:149], v[178:181], v[36:39]
	v_mfma_f32_16x16x32_bf16 v[28:31], v[154:157], v[178:181], v[28:31]
	v_mfma_f32_16x16x32_bf16 v[20:23], v[146:149], v[186:189], v[20:23]
	v_mfma_f32_16x16x32_bf16 v[12:15], v[154:157], v[186:189], v[12:15]
	v_mfma_f32_16x16x32_bf16 v[60:63], v[150:153], v[166:169], v[60:63]
	v_mfma_f32_16x16x32_bf16 v[56:59], v[158:161], v[166:169], v[56:59]
	v_mfma_f32_16x16x32_bf16 v[52:55], v[150:153], v[174:177], v[52:55]
	v_mfma_f32_16x16x32_bf16 v[44:47], v[158:161], v[174:177], v[44:47]
	v_mfma_f32_16x16x32_bf16 v[36:39], v[150:153], v[182:185], v[36:39]
	v_mfma_f32_16x16x32_bf16 v[28:31], v[158:161], v[182:185], v[28:31]
	v_mfma_f32_16x16x32_bf16 v[20:23], v[150:153], v[190:193], v[20:23]
	v_mfma_f32_16x16x32_bf16 v[12:15], v[158:161], v[190:193], v[12:15]
	s_setprio 0
	s_barrier
; #define PG8_STAGE(bufoff, gbase, voff) do { _Pragma("unroll") for (int _i = 0; _i < 2; ++_i) \
;         __builtin_amdgcn_global_load_lds((const unsigned*)((const char*)(gbase) + (voff)[_i]), (LAS unsigned*)(lds + (bufoff) + ldsw + _i * 8192), 16, 0, 0); } while (0)
; #define PG8_LDA(dst, b, h) do { _Pragma("unroll") for (int m = 0; m < 4; ++m) _Pragma("unroll") for (int k = 0; k < 2; ++k) dst[m][k] = *(const LAS bf16x8*)(lds + PG8_SA(b, h) + aoff + m * 2048 + k * 1024); } while (0)
; #define PG8_LDB(dst, b, h) do { _Pragma("unroll") for (int n = 0; n < 2; ++n) _Pragma("unroll") for (int k = 0; k < 2; ++k) dst[n][k] = *(const LAS bf16x8*)(lds + PG8_SB(b, h) + boff + n * 2048 + k * 1024); } while (0)
; #define PG8_MMA(ai, bj, At, Bt) do { __builtin_amdgcn_s_setprio(1); _Pragma("unroll") for (int m = 0; m < 4; ++m) _Pragma("unroll") for (int n = 0; n < 2; ++n) _Pragma("unroll") for (int k = 0; k < 2; ++k) \
;         acc[ai][bj][m][n] = __builtin_amdgcn_mfma_f32_16x16x32_bf16(Bt[n][k], At[m][k], acc[ai][bj][m][n], 0, 0, 0); __builtin_amdgcn_s_setprio(0); } while (0)
; #define PG8_WAIT_V(n) asm volatile("s_waitcnt vmcnt(" #n ")" ::: "memory")
; #define PG8_WAIT_L(n) asm volatile("s_waitcnt lgkmcnt(" #n ")" ::: "memory")
; #define PG8_BAR __builtin_amdgcn_s_barrier()
; #define PG8_SCHED __builtin_amdgcn_sched_barrier(0)
; template <class Epi, class Sched>
; __device__ __forceinline__ void gemm_phase(LAS unsigned char* lds, const Gemm g, const Sched& S, const Epi& E) {
;     ...
;             PG8_STAGE(PG8_SB(0, 1), b2 + hstep, voffB);
;             PG8_WAIT_V(6); PG8_BAR; PG8_MMA(1, 1, At, B1); PG8_BAR;
;             PG8_LDB(B0, 1, 0); PG8_SCHED; PG8_LDA(At, 1, 0); PG8_STAGE(PG8_SA(0, 1), a2 + hstep, voffA);
;             PG8_WAIT_L(8); PG8_BAR; PG8_WAIT_L(0); PG8_MMA(0, 0, At, B0); PG8_BAR; PG8_SCHED;
;             PG8_LDB(B1, 1, 1); PG8_STAGE(PG8_SB(1, 0), b3, voffB);
;             PG8_BAR; PG8_WAIT_L(0); PG8_MMA(0, 1, At, B1); PG8_BAR;
;             PG8_LDA(At, 1, 1); PG8_STAGE(PG8_SA(1, 0), a3, voffA);
;             PG8_BAR; PG8_WAIT_L(0); PG8_MMA(1, 0, At, B0); PG8_BAR; PG8_SCHED;
	s_add_u32 s60, s24, 0x40000
	s_addc_u32 s61, s25, 0
	s_add_i32 s59, s47, s34
	s_mov_b32 m0, s59
	s_nop 0
	global_load_lds_dwordx4 v130, s[60:61]
	s_add_i32 m0, s59, 0x2000
	s_nop 0
	global_load_lds_dwordx4 v134, s[60:61]
	s_add_u32 s26, s26, 0x40000
	s_addc_u32 s27, s27, 0
	s_mov_b32 m0, s36
	s_nop 0
	global_load_lds_dwordx4 v128, s[26:27]
	s_mov_b32 m0, s37
	s_nop 0
	global_load_lds_dwordx4 v132, s[26:27]
	s_waitcnt vmcnt(12)
	s_barrier
	s_setprio 1
	v_mfma_f32_16x16x32_bf16 v[48:51], v[194:197], v[162:165], v[48:51]
	v_mfma_f32_16x16x32_bf16 v[40:43], v[206:209], v[162:165], v[40:43]
	v_mfma_f32_16x16x32_bf16 v[32:35], v[194:197], v[170:173], v[32:35]
	v_mfma_f32_16x16x32_bf16 v[24:27], v[206:209], v[170:173], v[24:27]
	v_mfma_f32_16x16x32_bf16 v[16:19], v[194:197], v[178:181], v[16:19]
	v_mfma_f32_16x16x32_bf16 v[8:11], v[206:209], v[178:181], v[8:11]
	v_mfma_f32_16x16x32_bf16 v[4:7], v[194:197], v[186:189], v[4:7]
	v_mfma_f32_16x16x32_bf16 v[0:3], v[206:209], v[186:189], v[0:3]
	v_mfma_f32_16x16x32_bf16 v[48:51], v[202:205], v[166:169], v[48:51]
	v_mfma_f32_16x16x32_bf16 v[40:43], v[210:213], v[166:169], v[40:43]
	v_mfma_f32_16x16x32_bf16 v[32:35], v[202:205], v[174:177], v[32:35]
	v_mfma_f32_16x16x32_bf16 v[24:27], v[210:213], v[174:177], v[24:27]
	v_mfma_f32_16x16x32_bf16 v[16:19], v[202:205], v[182:185], v[16:19]
	v_mfma_f32_16x16x32_bf16 v[8:11], v[210:213], v[182:185], v[8:11]
	v_mfma_f32_16x16x32_bf16 v[4:7], v[202:205], v[190:193], v[4:7]
	v_mfma_f32_16x16x32_bf16 v[0:3], v[210:213], v[190:193], v[0:3]
	s_setprio 0
	s_add_i32 s59, 0, 0x18000
	v_add_u32_e32 v158, s59, v142
	s_barrier
	ds_read_b128 v[146:149], v158
	ds_read_b128 v[150:153], v158 offset:1024
	ds_read_b128 v[154:157], v158 offset:2048
	ds_read_b128 v[158:161], v158 offset:3072
	ds_read_b128 v[162:165], v144 offset:32768
	ds_read_b128 v[166:169], v144 offset:33792
	ds_read_b128 v[170:173], v144 offset:34816
	ds_read_b128 v[174:177], v144 offset:35840
	ds_read_b128 v[178:181], v144 offset:36864
	ds_read_b128 v[182:185], v144 offset:37888
	ds_read_b128 v[186:189], v144 offset:38912
	ds_read_b128 v[190:193], v144 offset:39936
	s_waitcnt lgkmcnt(8)
	s_waitcnt vmcnt(10)
	s_barrier
	s_waitcnt lgkmcnt(0)
	s_setprio 1
	s_waitcnt lgkmcnt(0)
	v_mfma_f32_16x16x32_bf16 v[124:127], v[146:149], v[162:165], v[124:127]
	v_mfma_f32_16x16x32_bf16 v[120:123], v[154:157], v[162:165], v[120:123]
	v_mfma_f32_16x16x32_bf16 v[116:119], v[146:149], v[170:173], v[116:119]
	v_mfma_f32_16x16x32_bf16 v[108:111], v[154:157], v[170:173], v[108:111]
	v_mfma_f32_16x16x32_bf16 v[100:103], v[146:149], v[178:181], v[100:103]
	v_mfma_f32_16x16x32_bf16 v[92:95], v[154:157], v[178:181], v[92:95]
	v_mfma_f32_16x16x32_bf16 v[84:87], v[146:149], v[186:189], v[84:87]
	v_mfma_f32_16x16x32_bf16 v[76:79], v[154:157], v[186:189], v[76:79]
	v_mfma_f32_16x16x32_bf16 v[124:127], v[150:153], v[166:169], v[124:127]
	v_mfma_f32_16x16x32_bf16 v[120:123], v[158:161], v[166:169], v[120:123]
	v_mfma_f32_16x16x32_bf16 v[116:119], v[150:153], v[174:177], v[116:119]
	v_mfma_f32_16x16x32_bf16 v[108:111], v[158:161], v[174:177], v[108:111]
	v_mfma_f32_16x16x32_bf16 v[100:103], v[150:153], v[182:185], v[100:103]
	v_mfma_f32_16x16x32_bf16 v[92:95], v[158:161], v[182:185], v[92:95]
	v_mfma_f32_16x16x32_bf16 v[84:87], v[150:153], v[190:193], v[84:87]
	v_mfma_f32_16x16x32_bf16 v[76:79], v[158:161], v[190:193], v[76:79]
	s_setprio 0
	s_barrier
	s_add_i32 s26, 0, 0x1c000
	s_add_i32 s27, s59, s34
	v_add_u32_e32 v210, s26, v142
	s_add_u32 s0, s24, 0x80
	s_addc_u32 s1, s25, 0
	s_mov_b32 m0, s27
	ds_read_b128 v[194:197], v210
	ds_read_b128 v[202:205], v210 offset:1024
	ds_read_b128 v[206:209], v210 offset:2048
	ds_read_b128 v[210:213], v210 offset:3072
	global_load_lds_dwordx4 v130, s[0:1]
	s_add_i32 m0, s27, 0x2000
	s_nop 0
	global_load_lds_dwordx4 v134, s[0:1]
	s_waitcnt vmcnt(10)
	s_barrier
	s_waitcnt lgkmcnt(0)
	s_setprio 1
	s_waitcnt lgkmcnt(0)
	v_mfma_f32_16x16x32_bf16 v[112:115], v[194:197], v[162:165], v[112:115]
	v_mfma_f32_16x16x32_bf16 v[104:107], v[206:209], v[162:165], v[104:107]
	v_mfma_f32_16x16x32_bf16 v[96:99], v[194:197], v[170:173], v[96:99]
	v_mfma_f32_16x16x32_bf16 v[88:91], v[206:209], v[170:173], v[88:91]
	v_mfma_f32_16x16x32_bf16 v[80:83], v[194:197], v[178:181], v[80:83]
	v_mfma_f32_16x16x32_bf16 v[72:75], v[206:209], v[178:181], v[72:75]
	v_mfma_f32_16x16x32_bf16 v[68:71], v[194:197], v[186:189], v[68:71]
	v_mfma_f32_16x16x32_bf16 v[64:67], v[206:209], v[186:189], v[64:67]
	v_mfma_f32_16x16x32_bf16 v[112:115], v[202:205], v[166:169], v[112:115]
	v_mfma_f32_16x16x32_bf16 v[104:107], v[210:213], v[166:169], v[104:107]
	v_mfma_f32_16x16x32_bf16 v[96:99], v[202:205], v[174:177], v[96:99]
	v_mfma_f32_16x16x32_bf16 v[88:91], v[210:213], v[174:177], v[88:91]
	v_mfma_f32_16x16x32_bf16 v[80:83], v[202:205], v[182:185], v[80:83]
	v_mfma_f32_16x16x32_bf16 v[72:75], v[210:213], v[182:185], v[72:75]
	v_mfma_f32_16x16x32_bf16 v[68:71], v[202:205], v[190:193], v[68:71]
	v_mfma_f32_16x16x32_bf16 v[64:67], v[210:213], v[190:193], v[64:67]
	s_setprio 0
	s_mov_b32 m0, s43
	s_mov_b64 s[0:1], 0x80
	v_lshl_add_u64 v[198:199], v[216:217], 0, s[0:1]
	s_barrier
	ds_read_b128 v[162:165], v144 offset:49152
	ds_read_b128 v[166:169], v144 offset:50176
	ds_read_b128 v[170:173], v144 offset:51200
	ds_read_b128 v[174:177], v144 offset:52224
	ds_read_b128 v[178:181], v144 offset:53248
	ds_read_b128 v[182:185], v144 offset:54272
	ds_read_b128 v[186:189], v144 offset:55296
	ds_read_b128 v[190:193], v144 offset:56320
	global_load_lds_dwordx4 v[198:199], off
	v_lshl_add_u64 v[198:199], v[218:219], 0, s[0:1]
	s_mov_b32 m0, s44
	s_nop 0
	global_load_lds_dwordx4 v[198:199], off
	s_barrier
; __device__ __forceinline__ unsigned cvt_pk_bf16(float lo, float hi) { unsigned r; asm volatile("v_cvt_pk_bf16_f32 %0, %1, %2" : "=v"(r) : "v"(lo), "v"(hi)); return r; }
; #define PG8_STAGE(bufoff, gbase, voff) do { _Pragma("unroll") for (int _i = 0; _i < 2; ++_i) \
;         __builtin_amdgcn_global_load_lds((const unsigned*)((const char*)(gbase) + (voff)[_i]), (LAS unsigned*)(lds + (bufoff) + ldsw + _i * 8192), 16, 0, 0); } while (0)
; #define PG8_MMA(ai, bj, At, Bt) do { __builtin_amdgcn_s_setprio(1); _Pragma("unroll") for (int m = 0; m < 4; ++m) _Pragma("unroll") for (int n = 0; n < 2; ++n) _Pragma("unroll") for (int k = 0; k < 2; ++k) \
;         acc[ai][bj][m][n] = __builtin_amdgcn_mfma_f32_16x16x32_bf16(Bt[n][k], At[m][k], acc[ai][bj][m][n], 0, 0, 0); __builtin_amdgcn_s_setprio(0); } while (0)
; #define PG8_WAIT_V(n) asm volatile("s_waitcnt vmcnt(" #n ")" ::: "memory")
; #define PG8_WAIT_L(n) asm volatile("s_waitcnt lgkmcnt(" #n ")" ::: "memory")
; #define PG8_BAR __builtin_amdgcn_s_barrier()
; #define PG8_SCHED __builtin_amdgcn_sched_barrier(0)
; template <class Epi, class Sched>
; __device__ __forceinline__ void gemm_phase(LAS unsigned char* lds, const Gemm g, const Sched& S, const Epi& E) {
;     ...
;             PG8_BAR; PG8_WAIT_L(0); PG8_MMA(1, 0, At, B0); PG8_BAR; PG8_SCHED;
;             PG8_STAGE(PG8_SB(1, 1), b3 + hstep, voffB);
;             PG8_WAIT_V(6); PG8_BAR; PG8_MMA(1, 1, At, B1); PG8_BAR;
;     __device__ __forceinline__ void operator()(const AccT& acc, const Unit& u, int wr, int wc, int fr, int fq) const {
;         asm volatile("" : "+v"(fr), "+v"(fq));
;         const int rbase = u.pm * 256 + wr * 64 + fr;
;         const int tb = u.pn * 256 + wc * 32 + 8 * fq;
; #pragma unroll
;         for (int ai = 0; ai < 2; ++ai)
; #pragma unroll
;             for (int m = 0; m < 4; ++m) {
;                 const int r = rbase + ai * 128 + m * 16;
; #pragma unroll
;                 for (int bj = 0; bj < 2; ++bj) {
;                     const int t0 = tb + bj * 128;
;                     const f32x4 v0 = acc[ai][bj][m][0], v1 = acc[ai][bj][m][1];
;                     u32x4 w; w.x = cvt_pk_bf16(v0[0], v0[1]); w.y = cvt_pk_bf16(v0[2], v0[3]); w.z = cvt_pk_bf16(v1[0], v1[1]); w.w = cvt_pk_bf16(v1[2], v1[3]);
;                     *(u32x4*)(VT + (size_t)r * NT + t0) = w;
;                 }
;             }
;     }
	s_waitcnt lgkmcnt(0)
	s_setprio 1
	s_waitcnt lgkmcnt(0)
	v_mfma_f32_16x16x32_bf16 v[60:63], v[146:149], v[162:165], v[60:63]
	v_mfma_f32_16x16x32_bf16 v[56:59], v[154:157], v[162:165], v[56:59]
	v_mfma_f32_16x16x32_bf16 v[52:55], v[146:149], v[170:173], v[52:55]
	v_mfma_f32_16x16x32_bf16 v[44:47], v[154:157], v[170:173], v[44:47]
	v_mfma_f32_16x16x32_bf16 v[36:39], v[146:149], v[178:181], v[36:39]
	v_mfma_f32_16x16x32_bf16 v[28:31], v[154:157], v[178:181], v[28:31]
	v_mfma_f32_16x16x32_bf16 v[20:23], v[146:149], v[186:189], v[20:23]
	v_mfma_f32_16x16x32_bf16 v[12:15], v[154:157], v[186:189], v[12:15]
	v_mfma_f32_16x16x32_bf16 v[60:63], v[150:153], v[166:169], v[60:63]
	v_mfma_f32_16x16x32_bf16 v[56:59], v[158:161], v[166:169], v[56:59]
	v_mfma_f32_16x16x32_bf16 v[52:55], v[150:153], v[174:177], v[52:55]
	v_mfma_f32_16x16x32_bf16 v[44:47], v[158:161], v[174:177], v[44:47]
	v_mfma_f32_16x16x32_bf16 v[36:39], v[150:153], v[182:185], v[36:39]
	v_mfma_f32_16x16x32_bf16 v[28:31], v[158:161], v[182:185], v[28:31]
	v_mfma_f32_16x16x32_bf16 v[20:23], v[150:153], v[190:193], v[20:23]
	v_mfma_f32_16x16x32_bf16 v[12:15], v[158:161], v[190:193], v[12:15]
	s_setprio 0
	s_barrier
	s_add_u32 s24, s24, 0x40080
	s_addc_u32 s25, s25, 0
	s_add_i32 s26, s26, s34
	s_mov_b32 m0, s26
	s_nop 0
	global_load_lds_dwordx4 v130, s[24:25]
	s_add_i32 m0, s26, 0x2000
	s_nop 0
	global_load_lds_dwordx4 v134, s[24:25]
	s_waitcnt vmcnt(10)
	s_barrier
	s_setprio 1
	v_mfma_f32_16x16x32_bf16 v[48:51], v[194:197], v[162:165], v[48:51]
	v_mfma_f32_16x16x32_bf16 v[40:43], v[206:209], v[162:165], v[40:43]
	v_mfma_f32_16x16x32_bf16 v[32:35], v[194:197], v[170:173], v[32:35]
	v_mfma_f32_16x16x32_bf16 v[24:27], v[206:209], v[170:173], v[24:27]
	v_mfma_f32_16x16x32_bf16 v[16:19], v[194:197], v[178:181], v[16:19]
	v_mfma_f32_16x16x32_bf16 v[8:11], v[206:209], v[178:181], v[8:11]
	v_mfma_f32_16x16x32_bf16 v[4:7], v[194:197], v[186:189], v[4:7]
	v_mfma_f32_16x16x32_bf16 v[0:3], v[206:209], v[186:189], v[0:3]
	v_mfma_f32_16x16x32_bf16 v[48:51], v[202:205], v[166:169], v[48:51]
	v_mfma_f32_16x16x32_bf16 v[40:43], v[210:213], v[166:169], v[40:43]
	v_mfma_f32_16x16x32_bf16 v[32:35], v[202:205], v[174:177], v[32:35]
	v_mfma_f32_16x16x32_bf16 v[24:27], v[210:213], v[174:177], v[24:27]
	v_mfma_f32_16x16x32_bf16 v[16:19], v[202:205], v[182:185], v[16:19]
	v_mfma_f32_16x16x32_bf16 v[8:11], v[210:213], v[182:185], v[8:11]
	v_mfma_f32_16x16x32_bf16 v[4:7], v[202:205], v[190:193], v[4:7]
	v_mfma_f32_16x16x32_bf16 v[0:3], v[210:213], v[190:193], v[0:3]
	s_setprio 0
	s_add_i32 s58, s58, 2
	s_add_u32 s22, s22, 0x100
	s_addc_u32 s23, s23, 0
	s_add_u32 s56, s56, 0x100
	s_addc_u32 s57, s57, 0
	s_cmp_gt_u32 s58, 13
	s_cbranch_scc1 .Lconc_last_g8
	s_barrier
	s_branch .LBB0_713
.Lconc_last_g8:
	v_readfirstlane_b32 s13, v200
	s_nop 3
	s_cmp_gt_u32 s13, 0xff
	s_cbranch_scc1 .Lconc_epi1_g8
	s_barrier
	v_mov_b32_e32 v146, v140
	v_mov_b32_e32 v147, v141
	s_lshl_b32 s13, s20, 8
	s_add_i32 s13, s13, s41
	v_add_u32_e32 v146, s13, v146
	s_lshl_b32 s13, s53, 8
	s_or_b32 s13, s13, s42
	v_lshl_add_u32 v148, v147, 3, s13
	v_ashrrev_i32_e32 v147, 31, v146
	v_cvt_pk_bf16_f32 v124, v124, v125
	v_cvt_pk_bf16_f32 v125, v126, v127
	v_cvt_pk_bf16_f32 v126, v120, v121
	v_lshlrev_b64 v[120:121], 14, v[146:147]
	v_lshl_add_u64 v[120:121], s[62:63], 0, v[120:121]
	v_ashrrev_i32_e32 v149, 31, v148
	v_lshl_add_u64 v[120:121], v[148:149], 1, v[120:121]
	s_mov_b32 s13, 0x40000
	v_cvt_pk_bf16_f32 v127, v122, v123
	global_store_dwordx4 v[120:121], v[124:127], off
	v_cvt_pk_bf16_f32 v112, v112, v113
	v_cvt_pk_bf16_f32 v113, v114, v115
	v_cvt_pk_bf16_f32 v114, v104, v105
	v_cvt_pk_bf16_f32 v115, v106, v107
	global_store_dwordx4 v[120:121], v[112:115], off offset:256
	v_cvt_pk_bf16_f32 v104, v116, v117
	v_cvt_pk_bf16_f32 v105, v118, v119
	v_cvt_pk_bf16_f32 v106, v108, v109
	v_cvt_pk_bf16_f32 v107, v110, v111
	s_mov_b64 s[22:23], 0x40000
	v_add_co_u32_e32 v110, vcc, s13, v120
	v_lshl_add_u64 v[108:109], v[120:121], 0, s[22:23]
	s_nop 0
	v_addc_co_u32_e32 v111, vcc, 0, v121, vcc
	s_mov_b32 s13, 0x80000
	global_store_dwordx4 v[110:111], v[104:107], off
	v_cvt_pk_bf16_f32 v96, v96, v97
	v_cvt_pk_bf16_f32 v97, v98, v99
	v_cvt_pk_bf16_f32 v98, v88, v89
	v_cvt_pk_bf16_f32 v99, v90, v91
	global_store_dwordx4 v[108:109], v[96:99], off offset:256
	v_cvt_pk_bf16_f32 v88, v100, v101
	v_cvt_pk_bf16_f32 v89, v102, v103
	v_cvt_pk_bf16_f32 v90, v92, v93
	v_cvt_pk_bf16_f32 v91, v94, v95
	s_mov_b64 s[22:23], 0x80000
	v_add_co_u32_e32 v94, vcc, s13, v120
	v_lshl_add_u64 v[92:93], v[120:121], 0, s[22:23]
	s_nop 0
	v_addc_co_u32_e32 v95, vcc, 0, v121, vcc
	global_store_dwordx4 v[94:95], v[88:91], off
	v_cvt_pk_bf16_f32 v80, v80, v81
	v_cvt_pk_bf16_f32 v81, v82, v83
	v_cvt_pk_bf16_f32 v82, v72, v73
	v_cvt_pk_bf16_f32 v83, v74, v75
	global_store_dwordx4 v[92:93], v[80:83], off offset:256
	v_cvt_pk_bf16_f32 v72, v84, v85
	v_cvt_pk_bf16_f32 v73, v86, v87
	v_cvt_pk_bf16_f32 v74, v76, v77
	v_cvt_pk_bf16_f32 v75, v78, v79
	s_mov_b64 s[22:23], 0xc0000
	v_add_co_u32_e32 v78, vcc, s48, v120
	v_lshl_add_u64 v[76:77], v[120:121], 0, s[22:23]
	s_nop 0
	v_addc_co_u32_e32 v79, vcc, 0, v121, vcc
	global_store_dwordx4 v[78:79], v[72:75], off
	v_cvt_pk_bf16_f32 v68, v68, v69
	v_cvt_pk_bf16_f32 v69, v70, v71
	v_cvt_pk_bf16_f32 v70, v64, v65
	v_cvt_pk_bf16_f32 v71, v66, v67
	global_store_dwordx4 v[76:77], v[68:71], off offset:256
	v_cvt_pk_bf16_f32 v60, v60, v61
	v_cvt_pk_bf16_f32 v61, v62, v63
	v_cvt_pk_bf16_f32 v62, v56, v57
	v_cvt_pk_bf16_f32 v63, v58, v59
	v_add_co_u32_e32 v58, vcc, s49, v120
	v_lshl_add_u64 v[56:57], v[120:121], 0, s[2:3]
	s_nop 0
	v_addc_co_u32_e32 v59, vcc, 0, v121, vcc
; __device__ __forceinline__ unsigned cvt_pk_bf16(float lo, float hi) { unsigned r; asm volatile("v_cvt_pk_bf16_f32 %0, %1, %2" : "=v"(r) : "v"(lo), "v"(hi)); return r; }
; #define PG8_WAIT_V(n) asm volatile("s_waitcnt vmcnt(" #n ")" ::: "memory")
; #define PG8_BAR __builtin_amdgcn_s_barrier()
; template <class Epi, class Sched>
; __device__ __forceinline__ void gemm_phase(LAS unsigned char* lds, const Gemm g, const Sched& S, const Epi& E) {
;     ...
;         E(acc, cur, wr, wc, fr, fq);
;         if (!has_next) break;
; #pragma unroll
;         for (int a = 0; a < 2; ++a)
; #pragma unroll
;             for (int b = 0; b < 2; ++b)
; #pragma unroll
;                 for (int m = 0; m < 4; ++m)
; #pragma unroll
;                     for (int n = 0; n < 2; ++n) acc[a][b][m][n] = (f32x4){0.f, 0.f, 0.f, 0.f};
;         cur = nxt; cA = nA; cB = nB; ++ui;
;     }
;     PG8_WAIT_V(0);
;     if (wr == 0) PG8_BAR;
;     PG8_BAR;
;     __device__ __forceinline__ void operator()(const AccT& acc, const Unit& u, int wr, int wc, int fr, int fq) const {
;         asm volatile("" : "+v"(fr), "+v"(fq));
;         const int rbase = u.pm * 256 + wr * 64 + fr;
;         const int tb = u.pn * 256 + wc * 32 + 8 * fq;
; #pragma unroll
;         for (int ai = 0; ai < 2; ++ai)
; #pragma unroll
;             for (int m = 0; m < 4; ++m) {
;                 const int r = rbase + ai * 128 + m * 16;
; #pragma unroll
;                 for (int bj = 0; bj < 2; ++bj) {
;                     const int t0 = tb + bj * 128;
;                     const f32x4 v0 = acc[ai][bj][m][0], v1 = acc[ai][bj][m][1];
;                     u32x4 w; w.x = cvt_pk_bf16(v0[0], v0[1]); w.y = cvt_pk_bf16(v0[2], v0[3]); w.z = cvt_pk_bf16(v1[0], v1[1]); w.w = cvt_pk_bf16(v1[2], v1[3]);
;                     *(u32x4*)(VT + (size_t)r * NT + t0) = w;
;                 }
;             }
;     }
	global_store_dwordx4 v[58:59], v[60:63], off
	v_cvt_pk_bf16_f32 v48, v48, v49
	v_cvt_pk_bf16_f32 v49, v50, v51
	v_cvt_pk_bf16_f32 v50, v40, v41
	v_cvt_pk_bf16_f32 v51, v42, v43
	global_store_dwordx4 v[56:57], v[48:51], off offset:256
	v_cvt_pk_bf16_f32 v40, v52, v53
	v_cvt_pk_bf16_f32 v41, v54, v55
	v_cvt_pk_bf16_f32 v42, v44, v45
	v_cvt_pk_bf16_f32 v43, v46, v47
	v_add_co_u32_e32 v46, vcc, s50, v120
	v_lshl_add_u64 v[44:45], v[120:121], 0, s[4:5]
	s_nop 0
	v_addc_co_u32_e32 v47, vcc, 0, v121, vcc
	global_store_dwordx4 v[46:47], v[40:43], off
	v_cvt_pk_bf16_f32 v32, v32, v33
	v_cvt_pk_bf16_f32 v33, v34, v35
	v_cvt_pk_bf16_f32 v34, v24, v25
	v_cvt_pk_bf16_f32 v35, v26, v27
	global_store_dwordx4 v[44:45], v[32:35], off offset:256
	v_cvt_pk_bf16_f32 v24, v36, v37
	v_cvt_pk_bf16_f32 v25, v38, v39
	v_cvt_pk_bf16_f32 v26, v28, v29
	v_cvt_pk_bf16_f32 v27, v30, v31
	v_add_co_u32_e32 v30, vcc, s51, v120
	v_lshl_add_u64 v[28:29], v[120:121], 0, s[6:7]
	s_nop 0
	v_addc_co_u32_e32 v31, vcc, 0, v121, vcc
	global_store_dwordx4 v[30:31], v[24:27], off
	v_cvt_pk_bf16_f32 v16, v16, v17
	v_cvt_pk_bf16_f32 v17, v18, v19
	v_cvt_pk_bf16_f32 v18, v8, v9
	v_cvt_pk_bf16_f32 v19, v10, v11
	global_store_dwordx4 v[28:29], v[16:19], off offset:256
	v_cvt_pk_bf16_f32 v8, v20, v21
	v_cvt_pk_bf16_f32 v9, v22, v23
	v_cvt_pk_bf16_f32 v10, v12, v13
	v_cvt_pk_bf16_f32 v11, v14, v15
	v_add_co_u32_e32 v14, vcc, s52, v120
	v_lshl_add_u64 v[12:13], v[120:121], 0, s[8:9]
	s_nop 0
	v_addc_co_u32_e32 v15, vcc, 0, v121, vcc
	s_and_b64 vcc, exec, s[10:11]
	s_mov_b32 s53, s12
	s_mov_b32 s20, s14
	s_mov_b64 s[24:25], s[18:19]
	s_mov_b64 s[22:23], s[16:17]
	global_store_dwordx4 v[14:15], v[8:11], off
	v_cvt_pk_bf16_f32 v4, v4, v5
	v_cvt_pk_bf16_f32 v5, v6, v7
	v_cvt_pk_bf16_f32 v6, v0, v1
	v_cvt_pk_bf16_f32 v7, v2, v3
	global_store_dwordx4 v[12:13], v[4:7], off offset:256
	s_cbranch_vccz .LBB0_706
	s_branch .Lconc_end_g8
.Lconc_epi1_g8:
	v_mov_b32_e32 v146, v140
	v_mov_b32_e32 v147, v141
	s_lshl_b32 s13, s20, 8
	s_add_i32 s13, s13, s41
	v_add_u32_e32 v146, s13, v146
	s_lshl_b32 s13, s53, 8
	s_or_b32 s13, s13, s42
	v_lshl_add_u32 v148, v147, 3, s13
	v_ashrrev_i32_e32 v147, 31, v146
	v_cvt_pk_bf16_f32 v124, v124, v125
	v_cvt_pk_bf16_f32 v125, v126, v127
	v_cvt_pk_bf16_f32 v126, v120, v121
	v_lshlrev_b64 v[120:121], 14, v[146:147]
	v_lshl_add_u64 v[120:121], s[62:63], 0, v[120:121]
	v_ashrrev_i32_e32 v149, 31, v148
	v_lshl_add_u64 v[120:121], v[148:149], 1, v[120:121]
	s_mov_b32 s13, 0x40000
	v_cvt_pk_bf16_f32 v127, v122, v123
	global_store_dwordx4 v[120:121], v[124:127], off
	v_cvt_pk_bf16_f32 v112, v112, v113
	v_cvt_pk_bf16_f32 v113, v114, v115
	v_cvt_pk_bf16_f32 v114, v104, v105
	v_cvt_pk_bf16_f32 v115, v106, v107
	global_store_dwordx4 v[120:121], v[112:115], off offset:256
	v_cvt_pk_bf16_f32 v104, v116, v117
	v_cvt_pk_bf16_f32 v105, v118, v119
	v_cvt_pk_bf16_f32 v106, v108, v109
	v_cvt_pk_bf16_f32 v107, v110, v111
	s_mov_b64 s[22:23], 0x40000
	v_add_co_u32_e32 v110, vcc, s13, v120
	v_lshl_add_u64 v[108:109], v[120:121], 0, s[22:23]
	s_nop 0
	v_addc_co_u32_e32 v111, vcc, 0, v121, vcc
	s_mov_b32 s13, 0x80000
	global_store_dwordx4 v[110:111], v[104:107], off
	v_cvt_pk_bf16_f32 v96, v96, v97
	v_cvt_pk_bf16_f32 v97, v98, v99
	v_cvt_pk_bf16_f32 v98, v88, v89
	v_cvt_pk_bf16_f32 v99, v90, v91
	global_store_dwordx4 v[108:109], v[96:99], off offset:256
	v_cvt_pk_bf16_f32 v88, v100, v101
	v_cvt_pk_bf16_f32 v89, v102, v103
	v_cvt_pk_bf16_f32 v90, v92, v93
	v_cvt_pk_bf16_f32 v91, v94, v95
	s_mov_b64 s[22:23], 0x80000
	v_add_co_u32_e32 v94, vcc, s13, v120
	v_lshl_add_u64 v[92:93], v[120:121], 0, s[22:23]
	s_nop 0
	v_addc_co_u32_e32 v95, vcc, 0, v121, vcc
	global_store_dwordx4 v[94:95], v[88:91], off
	v_cvt_pk_bf16_f32 v80, v80, v81
	v_cvt_pk_bf16_f32 v81, v82, v83
	v_cvt_pk_bf16_f32 v82, v72, v73
	v_cvt_pk_bf16_f32 v83, v74, v75
	global_store_dwordx4 v[92:93], v[80:83], off offset:256
	v_cvt_pk_bf16_f32 v72, v84, v85
	v_cvt_pk_bf16_f32 v73, v86, v87
	v_cvt_pk_bf16_f32 v74, v76, v77
	v_cvt_pk_bf16_f32 v75, v78, v79
	s_mov_b64 s[22:23], 0xc0000
	v_add_co_u32_e32 v78, vcc, s48, v120
	v_lshl_add_u64 v[76:77], v[120:121], 0, s[22:23]
	s_nop 0
	v_addc_co_u32_e32 v79, vcc, 0, v121, vcc
	global_store_dwordx4 v[78:79], v[72:75], off
	v_cvt_pk_bf16_f32 v68, v68, v69
	v_cvt_pk_bf16_f32 v69, v70, v71
	v_cvt_pk_bf16_f32 v70, v64, v65
	v_cvt_pk_bf16_f32 v71, v66, v67
	global_store_dwordx4 v[76:77], v[68:71], off offset:256
	v_cvt_pk_bf16_f32 v60, v60, v61
	v_cvt_pk_bf16_f32 v61, v62, v63
	v_cvt_pk_bf16_f32 v62, v56, v57
	v_cvt_pk_bf16_f32 v63, v58, v59
	v_add_co_u32_e32 v58, vcc, s49, v120
	v_lshl_add_u64 v[56:57], v[120:121], 0, s[2:3]
	s_nop 0
	v_addc_co_u32_e32 v59, vcc, 0, v121, vcc
	global_store_dwordx4 v[58:59], v[60:63], off
	v_cvt_pk_bf16_f32 v48, v48, v49
	v_cvt_pk_bf16_f32 v49, v50, v51
	v_cvt_pk_bf16_f32 v50, v40, v41
	v_cvt_pk_bf16_f32 v51, v42, v43
	global_store_dwordx4 v[56:57], v[48:51], off offset:256
	v_cvt_pk_bf16_f32 v40, v52, v53
	v_cvt_pk_bf16_f32 v41, v54, v55
	v_cvt_pk_bf16_f32 v42, v44, v45
	v_cvt_pk_bf16_f32 v43, v46, v47
	v_add_co_u32_e32 v46, vcc, s50, v120
	v_lshl_add_u64 v[44:45], v[120:121], 0, s[4:5]
	s_nop 0
	v_addc_co_u32_e32 v47, vcc, 0, v121, vcc
	global_store_dwordx4 v[46:47], v[40:43], off
	v_cvt_pk_bf16_f32 v32, v32, v33
	v_cvt_pk_bf16_f32 v33, v34, v35
	v_cvt_pk_bf16_f32 v34, v24, v25
	v_cvt_pk_bf16_f32 v35, v26, v27
	global_store_dwordx4 v[44:45], v[32:35], off offset:256
	v_cvt_pk_bf16_f32 v24, v36, v37
	v_cvt_pk_bf16_f32 v25, v38, v39
	v_cvt_pk_bf16_f32 v26, v28, v29
	v_cvt_pk_bf16_f32 v27, v30, v31
	v_add_co_u32_e32 v30, vcc, s51, v120
	v_lshl_add_u64 v[28:29], v[120:121], 0, s[6:7]
	s_nop 0
	v_addc_co_u32_e32 v31, vcc, 0, v121, vcc
	global_store_dwordx4 v[30:31], v[24:27], off
	v_cvt_pk_bf16_f32 v16, v16, v17
	v_cvt_pk_bf16_f32 v17, v18, v19
	v_cvt_pk_bf16_f32 v18, v8, v9
	v_cvt_pk_bf16_f32 v19, v10, v11
	global_store_dwordx4 v[28:29], v[16:19], off offset:256
	v_cvt_pk_bf16_f32 v8, v20, v21
	v_cvt_pk_bf16_f32 v9, v22, v23
	v_cvt_pk_bf16_f32 v10, v12, v13
	v_cvt_pk_bf16_f32 v11, v14, v15
	v_add_co_u32_e32 v14, vcc, s52, v120
	v_lshl_add_u64 v[12:13], v[120:121], 0, s[8:9]
	s_nop 0
	v_addc_co_u32_e32 v15, vcc, 0, v121, vcc
	s_and_b64 vcc, exec, s[10:11]
	s_mov_b32 s53, s12
	s_mov_b32 s20, s14
	s_mov_b64 s[24:25], s[18:19]
	s_mov_b64 s[22:23], s[16:17]
	global_store_dwordx4 v[14:15], v[8:11], off
	v_cvt_pk_bf16_f32 v4, v4, v5
	v_cvt_pk_bf16_f32 v5, v6, v7
	v_cvt_pk_bf16_f32 v6, v0, v1
	v_cvt_pk_bf16_f32 v7, v2, v3
	global_store_dwordx4 v[12:13], v[4:7], off offset:256
	s_barrier
	s_cbranch_vccz .LBB0_706
.Lconc_end_g8:
	s_waitcnt vmcnt(0)
	s_cmpk_gt_u32 s31, 0xff
	s_cbranch_scc1 .LBB0_717
	s_barrier

; #define PG8_STAGE(bufoff, gbase, voff) do { _Pragma("unroll") for (int _i = 0; _i < 2; ++_i) \
;         __builtin_amdgcn_global_load_lds((const unsigned*)((const char*)(gbase) + (voff)[_i]), (LAS unsigned*)(lds + (bufoff) + ldsw + _i * 8192), 16, 0, 0); } while (0)
; #define PG8_LDA(dst, b, h) do { _Pragma("unroll") for (int m = 0; m < 4; ++m) _Pragma("unroll") for (int k = 0; k < 2; ++k) dst[m][k] = *(const LAS bf16x8*)(lds + PG8_SA(b, h) + aoff + m * 2048 + k * 1024); } while (0)
; #define PG8_LDB(dst, b, h) do { _Pragma("unroll") for (int n = 0; n < 2; ++n) _Pragma("unroll") for (int k = 0; k < 2; ++k) dst[n][k] = *(const LAS bf16x8*)(lds + PG8_SB(b, h) + boff + n * 2048 + k * 1024); } while (0)
; #define PG8_MMA(ai, bj, At, Bt) do { __builtin_amdgcn_s_setprio(1); _Pragma("unroll") for (int m = 0; m < 4; ++m) _Pragma("unroll") for (int n = 0; n < 2; ++n) _Pragma("unroll") for (int k = 0; k < 2; ++k) \
;         acc[ai][bj][m][n] = __builtin_amdgcn_mfma_f32_16x16x32_bf16(Bt[n][k], At[m][k], acc[ai][bj][m][n], 0, 0, 0); __builtin_amdgcn_s_setprio(0); } while (0)
; #define PG8_WAIT_V(n) asm volatile("s_waitcnt vmcnt(" #n ")" ::: "memory")
; #define PG8_WAIT_L(n) asm volatile("s_waitcnt lgkmcnt(" #n ")" ::: "memory")
; #define PG8_BAR __builtin_amdgcn_s_barrier()
; #define PG8_SCHED __builtin_amdgcn_sched_barrier(0)
; template <class Epi, class Sched>
; __device__ __forceinline__ void gemm_phase(LAS unsigned char* lds, const Gemm g, const Sched& S, const Epi& E) {
;     ...
;             PG8_LDB(B0, 0, 0); PG8_SCHED; PG8_LDA(At, 0, 0); PG8_STAGE(PG8_SA(1, 1), a1 + hstep, voffA);
;             PG8_WAIT_L(8); PG8_BAR; PG8_WAIT_L(0); PG8_MMA(0, 0, At, B0); PG8_BAR; PG8_SCHED;
;             PG8_LDB(B1, 0, 1); PG8_STAGE(PG8_SB(0, 0), b2, voffB);
;             PG8_BAR; PG8_WAIT_L(0); PG8_MMA(0, 1, At, B1); PG8_BAR;
;             PG8_LDA(At, 0, 1); PG8_STAGE(PG8_SA(0, 0), a2, voffA);
;             PG8_BAR; PG8_WAIT_L(0); PG8_MMA(1, 0, At, B0); PG8_BAR; PG8_SCHED;
;             PG8_STAGE(PG8_SB(0, 1), b2 + hstep, voffB);
;             PG8_WAIT_V(6); PG8_BAR; PG8_MMA(1, 1, At, B1); PG8_BAR;
.LBB0_826:
	ds_read_b128 v[128:131], v168
	ds_read_b128 v[132:135], v168 offset:1024
	ds_read_b128 v[136:139], v168 offset:2048
	ds_read_b128 v[140:143], v168 offset:3072
	s_add_u32 s16, s14, 0xfff80080
	s_addc_u32 s17, s15, -1
	s_cmp_eq_u32 s43, 28
	s_cselect_b32 s19, s7, s17
	s_cselect_b32 s18, s39, s16
	s_cselect_b32 s17, s5, s42
	s_cselect_b32 s16, s40, s41
	s_add_i32 m0, s13, 0xc000
	ds_read_b128 v[162:165], v169
	ds_read_b128 v[172:175], v169 offset:1024
	ds_read_b128 v[176:179], v169 offset:2048
	ds_read_b128 v[180:183], v169 offset:3072
	ds_read_b128 v[184:187], v169 offset:4096
	ds_read_b128 v[188:191], v169 offset:5120
	ds_read_b128 v[192:195], v169 offset:6144
	ds_read_b128 v[196:199], v169 offset:7168
	global_load_lds_dwordx4 v152, s[14:15]
	s_add_i32 m0, s13, 0xe000
	s_nop 0
	global_load_lds_dwordx4 v154, s[14:15]
	s_waitcnt lgkmcnt(8)
	s_waitcnt vmcnt(10)
	s_barrier
	s_waitcnt lgkmcnt(0)
	s_setprio 1
	s_waitcnt lgkmcnt(0)
	v_mfma_f32_16x16x32_bf16 v[124:127], v[128:131], v[162:165], v[124:127]
	v_mfma_f32_16x16x32_bf16 v[120:123], v[136:139], v[162:165], v[120:123]
	v_mfma_f32_16x16x32_bf16 v[116:119], v[128:131], v[176:179], v[116:119]
	v_mfma_f32_16x16x32_bf16 v[112:115], v[136:139], v[176:179], v[112:115]
	v_mfma_f32_16x16x32_bf16 v[108:111], v[128:131], v[184:187], v[108:111]
	v_mfma_f32_16x16x32_bf16 v[100:103], v[136:139], v[184:187], v[100:103]
	v_mfma_f32_16x16x32_bf16 v[76:79], v[128:131], v[192:195], v[76:79]
	v_mfma_f32_16x16x32_bf16 v[72:75], v[136:139], v[192:195], v[72:75]
	v_mfma_f32_16x16x32_bf16 v[124:127], v[132:135], v[172:175], v[124:127]
	v_mfma_f32_16x16x32_bf16 v[120:123], v[140:143], v[172:175], v[120:123]
	v_mfma_f32_16x16x32_bf16 v[116:119], v[132:135], v[180:183], v[116:119]
	v_mfma_f32_16x16x32_bf16 v[112:115], v[140:143], v[180:183], v[112:115]
	v_mfma_f32_16x16x32_bf16 v[108:111], v[132:135], v[188:191], v[108:111]
	v_mfma_f32_16x16x32_bf16 v[100:103], v[140:143], v[188:191], v[100:103]
	v_mfma_f32_16x16x32_bf16 v[76:79], v[132:135], v[196:199], v[76:79]
	v_mfma_f32_16x16x32_bf16 v[72:75], v[140:143], v[196:199], v[72:75]
	s_setprio 0
	s_barrier
	s_add_i32 s44, s35, s24
	s_mov_b32 m0, s44
	ds_read_b128 v[202:205], v170
	ds_read_b128 v[206:209], v170 offset:1024
	ds_read_b128 v[210:213], v170 offset:2048
	ds_read_b128 v[214:217], v170 offset:3072
	global_load_lds_dwordx4 v146, s[16:17]
	s_add_i32 m0, s44, 0x2000
	s_nop 0
	global_load_lds_dwordx4 v150, s[16:17]
	s_waitcnt vmcnt(10)
	s_barrier
	s_waitcnt lgkmcnt(0)
	s_setprio 1
	s_waitcnt lgkmcnt(0)
	v_mfma_f32_16x16x32_bf16 v[104:107], v[202:205], v[162:165], v[104:107]
	v_mfma_f32_16x16x32_bf16 v[96:99], v[210:213], v[162:165], v[96:99]
	v_mfma_f32_16x16x32_bf16 v[92:95], v[202:205], v[176:179], v[92:95]
	v_mfma_f32_16x16x32_bf16 v[88:91], v[210:213], v[176:179], v[88:91]
	v_mfma_f32_16x16x32_bf16 v[84:87], v[202:205], v[184:187], v[84:87]
	v_mfma_f32_16x16x32_bf16 v[80:83], v[210:213], v[184:187], v[80:83]
	v_mfma_f32_16x16x32_bf16 v[68:71], v[202:205], v[192:195], v[68:71]
	v_mfma_f32_16x16x32_bf16 v[64:67], v[210:213], v[192:195], v[64:67]
	v_mfma_f32_16x16x32_bf16 v[104:107], v[206:209], v[172:175], v[104:107]
	v_mfma_f32_16x16x32_bf16 v[96:99], v[214:217], v[172:175], v[96:99]
	v_mfma_f32_16x16x32_bf16 v[92:95], v[206:209], v[180:183], v[92:95]
	v_mfma_f32_16x16x32_bf16 v[88:91], v[214:217], v[180:183], v[88:91]
	v_mfma_f32_16x16x32_bf16 v[84:87], v[206:209], v[188:191], v[84:87]
	v_mfma_f32_16x16x32_bf16 v[80:83], v[214:217], v[188:191], v[80:83]
	v_mfma_f32_16x16x32_bf16 v[68:71], v[206:209], v[196:199], v[68:71]
	v_mfma_f32_16x16x32_bf16 v[64:67], v[214:217], v[196:199], v[64:67]
	s_setprio 0
	s_mov_b32 m0, s13
	v_lshl_add_u64 v[222:223], s[18:19], 0, v[144:145]
	s_barrier
	ds_read_b128 v[162:165], v169 offset:16384
	ds_read_b128 v[172:175], v169 offset:17408
	ds_read_b128 v[176:179], v169 offset:18432
	ds_read_b128 v[180:183], v169 offset:19456
	ds_read_b128 v[184:187], v169 offset:20480
	ds_read_b128 v[188:191], v169 offset:21504
	ds_read_b128 v[192:195], v169 offset:22528
	ds_read_b128 v[196:199], v169 offset:23552
	global_load_lds_dwordx4 v144, s[18:19]
	v_lshl_add_u64 v[224:225], s[18:19], 0, v[148:149]
	s_mov_b32 m0, s25
	s_nop 0
	global_load_lds_dwordx4 v148, s[18:19]
	s_barrier
	s_waitcnt lgkmcnt(0)
	s_setprio 1
	s_waitcnt lgkmcnt(0)
	v_mfma_f32_16x16x32_bf16 v[60:63], v[128:131], v[162:165], v[60:63]
	v_mfma_f32_16x16x32_bf16 v[56:59], v[136:139], v[162:165], v[56:59]
	v_mfma_f32_16x16x32_bf16 v[48:51], v[128:131], v[176:179], v[48:51]
	v_mfma_f32_16x16x32_bf16 v[40:43], v[136:139], v[176:179], v[40:43]
	v_mfma_f32_16x16x32_bf16 v[32:35], v[128:131], v[184:187], v[32:35]
	v_mfma_f32_16x16x32_bf16 v[24:27], v[136:139], v[184:187], v[24:27]
	v_mfma_f32_16x16x32_bf16 v[16:19], v[128:131], v[192:195], v[16:19]
	v_mfma_f32_16x16x32_bf16 v[8:11], v[136:139], v[192:195], v[8:11]
	v_mfma_f32_16x16x32_bf16 v[60:63], v[132:135], v[172:175], v[60:63]
	v_mfma_f32_16x16x32_bf16 v[56:59], v[140:143], v[172:175], v[56:59]
	v_mfma_f32_16x16x32_bf16 v[48:51], v[132:135], v[180:183], v[48:51]
	v_mfma_f32_16x16x32_bf16 v[40:43], v[140:143], v[180:183], v[40:43]
	v_mfma_f32_16x16x32_bf16 v[32:35], v[132:135], v[188:191], v[32:35]
	v_mfma_f32_16x16x32_bf16 v[24:27], v[140:143], v[188:191], v[24:27]
	v_mfma_f32_16x16x32_bf16 v[16:19], v[132:135], v[196:199], v[16:19]
	v_mfma_f32_16x16x32_bf16 v[8:11], v[140:143], v[196:199], v[8:11]
	s_setprio 0
	s_barrier
; #define PG8_STAGE(bufoff, gbase, voff) do { _Pragma("unroll") for (int _i = 0; _i < 2; ++_i) \
;         __builtin_amdgcn_global_load_lds((const unsigned*)((const char*)(gbase) + (voff)[_i]), (LAS unsigned*)(lds + (bufoff) + ldsw + _i * 8192), 16, 0, 0); } while (0)
; #define PG8_LDA(dst, b, h) do { _Pragma("unroll") for (int m = 0; m < 4; ++m) _Pragma("unroll") for (int k = 0; k < 2; ++k) dst[m][k] = *(const LAS bf16x8*)(lds + PG8_SA(b, h) + aoff + m * 2048 + k * 1024); } while (0)
; #define PG8_LDB(dst, b, h) do { _Pragma("unroll") for (int n = 0; n < 2; ++n) _Pragma("unroll") for (int k = 0; k < 2; ++k) dst[n][k] = *(const LAS bf16x8*)(lds + PG8_SB(b, h) + boff + n * 2048 + k * 1024); } while (0)
; #define PG8_MMA(ai, bj, At, Bt) do { __builtin_amdgcn_s_setprio(1); _Pragma("unroll") for (int m = 0; m < 4; ++m) _Pragma("unroll") for (int n = 0; n < 2; ++n) _Pragma("unroll") for (int k = 0; k < 2; ++k) \
;         acc[ai][bj][m][n] = __builtin_amdgcn_mfma_f32_16x16x32_bf16(Bt[n][k], At[m][k], acc[ai][bj][m][n], 0, 0, 0); __builtin_amdgcn_s_setprio(0); } while (0)
; #define PG8_WAIT_V(n) asm volatile("s_waitcnt vmcnt(" #n ")" ::: "memory")
; #define PG8_WAIT_L(n) asm volatile("s_waitcnt lgkmcnt(" #n ")" ::: "memory")
; #define PG8_BAR __builtin_amdgcn_s_barrier()
; #define PG8_SCHED __builtin_amdgcn_sched_barrier(0)
; template <class Epi, class Sched>
; __device__ __forceinline__ void gemm_phase(LAS unsigned char* lds, const Gemm g, const Sched& S, const Epi& E) {
;     ...
;             PG8_STAGE(PG8_SB(0, 1), b2 + hstep, voffB);
;             PG8_WAIT_V(6); PG8_BAR; PG8_MMA(1, 1, At, B1); PG8_BAR;
;             PG8_LDB(B0, 1, 0); PG8_SCHED; PG8_LDA(At, 1, 0); PG8_STAGE(PG8_SA(0, 1), a2 + hstep, voffA);
;             PG8_WAIT_L(8); PG8_BAR; PG8_WAIT_L(0); PG8_MMA(0, 0, At, B0); PG8_BAR; PG8_SCHED;
;             PG8_LDB(B1, 1, 1); PG8_STAGE(PG8_SB(1, 0), b3, voffB);
;             PG8_BAR; PG8_WAIT_L(0); PG8_MMA(0, 1, At, B1); PG8_BAR;
;             PG8_LDA(At, 1, 1); PG8_STAGE(PG8_SA(1, 0), a3, voffA);
;             PG8_BAR; PG8_WAIT_L(0); PG8_MMA(1, 0, At, B0); PG8_BAR; PG8_SCHED;
	s_add_u32 s44, s16, 0x80000
	s_addc_u32 s45, s17, 0
	s_add_i32 s46, s36, s24
	s_mov_b32 m0, s46
	s_nop 0
	global_load_lds_dwordx4 v146, s[44:45]
	s_add_i32 m0, s46, 0x2000
	s_nop 0
	global_load_lds_dwordx4 v150, s[44:45]
	s_add_u32 s18, s18, 0x80000
	s_addc_u32 s19, s19, 0
	s_mov_b32 m0, s26
	s_nop 0
	global_load_lds_dwordx4 v144, s[18:19]
	s_mov_b32 m0, s27
	s_nop 0
	global_load_lds_dwordx4 v148, s[18:19]
	s_waitcnt vmcnt(12)
	s_barrier
	s_setprio 1
	v_mfma_f32_16x16x32_bf16 v[52:55], v[202:205], v[162:165], v[52:55]
	v_mfma_f32_16x16x32_bf16 v[44:47], v[210:213], v[162:165], v[44:47]
	v_mfma_f32_16x16x32_bf16 v[36:39], v[202:205], v[176:179], v[36:39]
	v_mfma_f32_16x16x32_bf16 v[28:31], v[210:213], v[176:179], v[28:31]
	v_mfma_f32_16x16x32_bf16 v[20:23], v[202:205], v[184:187], v[20:23]
	v_mfma_f32_16x16x32_bf16 v[12:15], v[210:213], v[184:187], v[12:15]
	v_mfma_f32_16x16x32_bf16 v[4:7], v[202:205], v[192:195], v[4:7]
	v_mfma_f32_16x16x32_bf16 v[0:3], v[210:213], v[192:195], v[0:3]
	v_mfma_f32_16x16x32_bf16 v[52:55], v[206:209], v[172:175], v[52:55]
	v_mfma_f32_16x16x32_bf16 v[44:47], v[214:217], v[172:175], v[44:47]
	v_mfma_f32_16x16x32_bf16 v[36:39], v[206:209], v[180:183], v[36:39]
	v_mfma_f32_16x16x32_bf16 v[28:31], v[214:217], v[180:183], v[28:31]
	v_mfma_f32_16x16x32_bf16 v[20:23], v[206:209], v[188:191], v[20:23]
	v_mfma_f32_16x16x32_bf16 v[12:15], v[214:217], v[188:191], v[12:15]
	v_mfma_f32_16x16x32_bf16 v[4:7], v[206:209], v[196:199], v[4:7]
	v_mfma_f32_16x16x32_bf16 v[0:3], v[214:217], v[196:199], v[0:3]
	s_setprio 0
	s_add_i32 s44, 0, 0x18000
	v_add_u32_e32 v140, s44, v167
	s_barrier
	ds_read_b128 v[128:131], v140
	ds_read_b128 v[132:135], v140 offset:1024
	ds_read_b128 v[136:139], v140 offset:2048
	ds_read_b128 v[140:143], v140 offset:3072
	ds_read_b128 v[162:165], v169 offset:32768
	ds_read_b128 v[172:175], v169 offset:33792
	ds_read_b128 v[176:179], v169 offset:34816
	ds_read_b128 v[180:183], v169 offset:35840
	ds_read_b128 v[184:187], v169 offset:36864
	ds_read_b128 v[188:191], v169 offset:37888
	ds_read_b128 v[192:195], v169 offset:38912
	ds_read_b128 v[196:199], v169 offset:39936
	s_waitcnt lgkmcnt(8)
	s_waitcnt vmcnt(10)
	s_barrier
	s_waitcnt lgkmcnt(0)
	s_setprio 1
	s_waitcnt lgkmcnt(0)
	v_mfma_f32_16x16x32_bf16 v[124:127], v[128:131], v[162:165], v[124:127]
	v_mfma_f32_16x16x32_bf16 v[120:123], v[136:139], v[162:165], v[120:123]
	v_mfma_f32_16x16x32_bf16 v[116:119], v[128:131], v[176:179], v[116:119]
	v_mfma_f32_16x16x32_bf16 v[112:115], v[136:139], v[176:179], v[112:115]
	v_mfma_f32_16x16x32_bf16 v[108:111], v[128:131], v[184:187], v[108:111]
	v_mfma_f32_16x16x32_bf16 v[100:103], v[136:139], v[184:187], v[100:103]
	v_mfma_f32_16x16x32_bf16 v[76:79], v[128:131], v[192:195], v[76:79]
	v_mfma_f32_16x16x32_bf16 v[72:75], v[136:139], v[192:195], v[72:75]
	v_mfma_f32_16x16x32_bf16 v[124:127], v[132:135], v[172:175], v[124:127]
	v_mfma_f32_16x16x32_bf16 v[120:123], v[140:143], v[172:175], v[120:123]
	v_mfma_f32_16x16x32_bf16 v[116:119], v[132:135], v[180:183], v[116:119]
	v_mfma_f32_16x16x32_bf16 v[112:115], v[140:143], v[180:183], v[112:115]
	v_mfma_f32_16x16x32_bf16 v[108:111], v[132:135], v[188:191], v[108:111]
	v_mfma_f32_16x16x32_bf16 v[100:103], v[140:143], v[188:191], v[100:103]
	v_mfma_f32_16x16x32_bf16 v[76:79], v[132:135], v[196:199], v[76:79]
	v_mfma_f32_16x16x32_bf16 v[72:75], v[140:143], v[196:199], v[72:75]
	s_setprio 0
	s_barrier
	s_add_i32 s18, 0, 0x1c000
	s_add_i32 s19, s44, s24
	v_add_u32_e32 v160, s18, v167
	s_add_u32 s0, s16, 0x80
	s_addc_u32 s1, s17, 0
	s_mov_b32 m0, s19
	ds_read_b128 v[202:205], v160
	ds_read_b128 v[206:209], v160 offset:1024
	ds_read_b128 v[210:213], v160 offset:2048
	ds_read_b128 v[214:217], v160 offset:3072
	global_load_lds_dwordx4 v146, s[0:1]
	s_add_i32 m0, s19, 0x2000
	s_nop 0
	global_load_lds_dwordx4 v150, s[0:1]
	s_waitcnt vmcnt(10)
	s_barrier
	s_waitcnt lgkmcnt(0)
	s_setprio 1
	s_waitcnt lgkmcnt(0)
	v_mfma_f32_16x16x32_bf16 v[104:107], v[202:205], v[162:165], v[104:107]
	v_mfma_f32_16x16x32_bf16 v[96:99], v[210:213], v[162:165], v[96:99]
	v_mfma_f32_16x16x32_bf16 v[92:95], v[202:205], v[176:179], v[92:95]
	v_mfma_f32_16x16x32_bf16 v[88:91], v[210:213], v[176:179], v[88:91]
	v_mfma_f32_16x16x32_bf16 v[84:87], v[202:205], v[184:187], v[84:87]
	v_mfma_f32_16x16x32_bf16 v[80:83], v[210:213], v[184:187], v[80:83]
	v_mfma_f32_16x16x32_bf16 v[68:71], v[202:205], v[192:195], v[68:71]
	v_mfma_f32_16x16x32_bf16 v[64:67], v[210:213], v[192:195], v[64:67]
	v_mfma_f32_16x16x32_bf16 v[104:107], v[206:209], v[172:175], v[104:107]
	v_mfma_f32_16x16x32_bf16 v[96:99], v[214:217], v[172:175], v[96:99]
	v_mfma_f32_16x16x32_bf16 v[92:95], v[206:209], v[180:183], v[92:95]
	v_mfma_f32_16x16x32_bf16 v[88:91], v[214:217], v[180:183], v[88:91]
	v_mfma_f32_16x16x32_bf16 v[84:87], v[206:209], v[188:191], v[84:87]
	v_mfma_f32_16x16x32_bf16 v[80:83], v[214:217], v[188:191], v[80:83]
	v_mfma_f32_16x16x32_bf16 v[68:71], v[206:209], v[196:199], v[68:71]
	v_mfma_f32_16x16x32_bf16 v[64:67], v[214:217], v[196:199], v[64:67]
	s_setprio 0
	s_mov_b32 m0, s31
	s_mov_b64 s[0:1], 0x80
	v_lshl_add_u64 v[218:219], v[222:223], 0, s[0:1]
	s_barrier
	ds_read_b128 v[162:165], v169 offset:49152
	ds_read_b128 v[172:175], v169 offset:50176
	ds_read_b128 v[176:179], v169 offset:51200
	ds_read_b128 v[180:183], v169 offset:52224
	ds_read_b128 v[184:187], v169 offset:53248
	ds_read_b128 v[188:191], v169 offset:54272
	ds_read_b128 v[192:195], v169 offset:55296
	ds_read_b128 v[196:199], v169 offset:56320
	global_load_lds_dwordx4 v[218:219], off
	v_lshl_add_u64 v[218:219], v[224:225], 0, s[0:1]
	s_mov_b32 m0, s33
	s_nop 0
	global_load_lds_dwordx4 v[218:219], off
	s_barrier
; #define PG8_STAGE(bufoff, gbase, voff) do { _Pragma("unroll") for (int _i = 0; _i < 2; ++_i) \
;         __builtin_amdgcn_global_load_lds((const unsigned*)((const char*)(gbase) + (voff)[_i]), (LAS unsigned*)(lds + (bufoff) + ldsw + _i * 8192), 16, 0, 0); } while (0)
; #define PG8_MMA(ai, bj, At, Bt) do { __builtin_amdgcn_s_setprio(1); _Pragma("unroll") for (int m = 0; m < 4; ++m) _Pragma("unroll") for (int n = 0; n < 2; ++n) _Pragma("unroll") for (int k = 0; k < 2; ++k) \
;         acc[ai][bj][m][n] = __builtin_amdgcn_mfma_f32_16x16x32_bf16(Bt[n][k], At[m][k], acc[ai][bj][m][n], 0, 0, 0); __builtin_amdgcn_s_setprio(0); } while (0)
; #define PG8_WAIT_V(n) asm volatile("s_waitcnt vmcnt(" #n ")" ::: "memory")
; #define PG8_WAIT_L(n) asm volatile("s_waitcnt lgkmcnt(" #n ")" ::: "memory")
; #define PG8_BAR __builtin_amdgcn_s_barrier()
; #define PG8_SCHED __builtin_amdgcn_sched_barrier(0)
; template <class Epi, class Sched>
; __device__ __forceinline__ void gemm_phase(LAS unsigned char* lds, const Gemm g, const Sched& S, const Epi& E) {
;     ...
;             PG8_BAR; PG8_WAIT_L(0); PG8_MMA(1, 0, At, B0); PG8_BAR; PG8_SCHED;
;             PG8_STAGE(PG8_SB(1, 1), b3 + hstep, voffB);
;             PG8_WAIT_V(6); PG8_BAR; PG8_MMA(1, 1, At, B1); PG8_BAR;
;     __device__ __forceinline__ void operator()(const AccT& acc, const Unit& u, int wr, int wc, int fr, int fq) const {
;         asm volatile("" : "+v"(fr), "+v"(fq));
;         const int row0 = u.pm * 256 + wr * 64 + fr; const int b = u.pn >> 1, ch0 = (u.pn & 1) * 256 + wc * 32 + 8 * fq;
;         const float sg = (fr & 1) ? -1.0f : 1.0f;
;         f32x4 yh[2][2];
; #pragma unroll
;         for (int bj = 0; bj < 2; ++bj)
; #pragma unroll
;             for (int n = 0; n < 2; ++n) yh[bj][n] = *(const f32x4*)(YCH + b * 512 + ch0 + bj * 128 + 4 * n) * sg;
	s_waitcnt lgkmcnt(0)
	s_setprio 1
	s_waitcnt lgkmcnt(0)
	v_mfma_f32_16x16x32_bf16 v[60:63], v[128:131], v[162:165], v[60:63]
	v_mfma_f32_16x16x32_bf16 v[56:59], v[136:139], v[162:165], v[56:59]
	v_mfma_f32_16x16x32_bf16 v[48:51], v[128:131], v[176:179], v[48:51]
	v_mfma_f32_16x16x32_bf16 v[40:43], v[136:139], v[176:179], v[40:43]
	v_mfma_f32_16x16x32_bf16 v[32:35], v[128:131], v[184:187], v[32:35]
	v_mfma_f32_16x16x32_bf16 v[24:27], v[136:139], v[184:187], v[24:27]
	v_mfma_f32_16x16x32_bf16 v[16:19], v[128:131], v[192:195], v[16:19]
	v_mfma_f32_16x16x32_bf16 v[8:11], v[136:139], v[192:195], v[8:11]
	v_mfma_f32_16x16x32_bf16 v[60:63], v[132:135], v[172:175], v[60:63]
	v_mfma_f32_16x16x32_bf16 v[56:59], v[140:143], v[172:175], v[56:59]
	v_mfma_f32_16x16x32_bf16 v[48:51], v[132:135], v[180:183], v[48:51]
	v_mfma_f32_16x16x32_bf16 v[40:43], v[140:143], v[180:183], v[40:43]
	v_mfma_f32_16x16x32_bf16 v[32:35], v[132:135], v[188:191], v[32:35]
	v_mfma_f32_16x16x32_bf16 v[24:27], v[140:143], v[188:191], v[24:27]
	v_mfma_f32_16x16x32_bf16 v[16:19], v[132:135], v[196:199], v[16:19]
	v_mfma_f32_16x16x32_bf16 v[8:11], v[140:143], v[196:199], v[8:11]
	s_setprio 0
	s_barrier
	s_add_u32 s16, s16, 0x80080
	s_addc_u32 s17, s17, 0
	s_add_i32 s18, s18, s24
	s_mov_b32 m0, s18
	s_nop 0
	global_load_lds_dwordx4 v146, s[16:17]
	s_add_i32 m0, s18, 0x2000
	s_nop 0
	global_load_lds_dwordx4 v150, s[16:17]
	s_waitcnt vmcnt(10)
	s_barrier
	s_setprio 1
	v_mfma_f32_16x16x32_bf16 v[52:55], v[202:205], v[162:165], v[52:55]
	v_mfma_f32_16x16x32_bf16 v[44:47], v[210:213], v[162:165], v[44:47]
	v_mfma_f32_16x16x32_bf16 v[36:39], v[202:205], v[176:179], v[36:39]
	v_mfma_f32_16x16x32_bf16 v[28:31], v[210:213], v[176:179], v[28:31]
	v_mfma_f32_16x16x32_bf16 v[20:23], v[202:205], v[184:187], v[20:23]
	v_mfma_f32_16x16x32_bf16 v[12:15], v[210:213], v[184:187], v[12:15]
	v_mfma_f32_16x16x32_bf16 v[4:7], v[202:205], v[192:195], v[4:7]
	v_mfma_f32_16x16x32_bf16 v[0:3], v[210:213], v[192:195], v[0:3]
	v_mfma_f32_16x16x32_bf16 v[52:55], v[206:209], v[172:175], v[52:55]
	v_mfma_f32_16x16x32_bf16 v[44:47], v[214:217], v[172:175], v[44:47]
	v_mfma_f32_16x16x32_bf16 v[36:39], v[206:209], v[180:183], v[36:39]
	v_mfma_f32_16x16x32_bf16 v[28:31], v[214:217], v[180:183], v[28:31]
	v_mfma_f32_16x16x32_bf16 v[20:23], v[206:209], v[188:191], v[20:23]
	v_mfma_f32_16x16x32_bf16 v[12:15], v[214:217], v[188:191], v[12:15]
	v_mfma_f32_16x16x32_bf16 v[4:7], v[206:209], v[196:199], v[4:7]
	v_mfma_f32_16x16x32_bf16 v[0:3], v[214:217], v[196:199], v[0:3]
	s_setprio 0
	s_add_i32 s43, s43, 2
	s_add_u32 s14, s14, 0x100
	s_addc_u32 s15, s15, 0
	s_add_u32 s41, s41, 0x100
	s_addc_u32 s42, s42, 0
	s_cmp_gt_u32 s43, 29
	s_cbranch_scc1 .Lconc_last_g9
	s_barrier
	s_branch .LBB0_826
.Lconc_last_g9:
	v_readfirstlane_b32 s5, v200
	s_nop 3
	s_cmp_gt_u32 s5, 0xff
	s_cbranch_scc1 .Lconc_epi1_g9
	s_barrier
	s_ashr_i32 s5, s38, 1
	s_lshl_b32 s7, s38, 8
	s_lshl_b32 s14, s5, 9
	s_and_b32 s7, s7, 0x100
	s_ashr_i32 s15, s14, 31
	v_mov_b32_e32 v171, v161
	v_mov_b32_e32 v128, v166
	s_or_b32 s7, s7, s30
	s_lshl_b64 s[14:15], s[14:15], 2
	s_add_u32 s14, s48, s14
	v_lshl_add_u32 v164, v128, 3, s7
	s_addc_u32 s15, s49, s15
	v_ashrrev_i32_e32 v165, 31, v164
	v_lshl_add_u64 v[128:129], v[164:165], 2, s[14:15]
	global_load_dwordx4 v[140:143], v[128:129], off
	global_load_dwordx4 v[136:139], v[128:129], off offset:16
	global_load_dwordx4 v[132:135], v[128:129], off offset:512
	s_nop 0
	global_load_dwordx4 v[128:131], v[128:129], off offset:528
	s_lshl_b32 s7, s12, 8
	s_lshl_b32 s5, s5, 11
	s_add_i32 s7, s7, s29
	v_and_b32_e32 v160, 1, v171
	s_add_i32 s7, s7, s5
	v_mov_b64_e32 v[162:163], s[96:97]
	v_cmp_eq_u32_e32 vcc, 0, v160
	v_add_u32_e32 v171, s7, v171
	v_lshlrev_b64 v[164:165], 1, v[164:165]
	v_cndmask_b32_e64 v160, -1.0, 1.0, vcc
	v_mad_i64_i32 v[172:173], s[14:15], v171, s37, v[162:163]
	v_add_u32_e32 v174, 16, v171
	v_lshl_add_u64 v[172:173], v[172:173], 0, v[164:165]
	v_mad_i64_i32 v[174:175], s[14:15], v174, s37, v[162:163]
	v_add_u32_e32 v176, 32, v171
	v_lshl_add_u64 v[174:175], v[174:175], 0, v[164:165]
	v_mad_i64_i32 v[176:177], s[14:15], v176, s37, v[162:163]
	v_lshl_add_u64 v[176:177], v[176:177], 0, v[164:165]
	v_add_u32_e32 v182, 48, v171
	s_and_b64 vcc, exec, s[2:3]
	s_mov_b32 s38, s4
	s_mov_b32 s12, s6
	s_mov_b64 s[16:17], s[10:11]
	s_waitcnt vmcnt(0)
; __device__ __forceinline__ unsigned cvt_pk_bf16(float lo, float hi) { unsigned r; asm volatile("v_cvt_pk_bf16_f32 %0, %1, %2" : "=v"(r) : "v"(lo), "v"(hi)); return r; }
;     __device__ __forceinline__ void operator()(const AccT& acc, const Unit& u, int wr, int wc, int fr, int fq) const {
;     ...
; #pragma unroll
;         for (int ai = 0; ai < 2; ++ai)
; #pragma unroll
;             for (int m = 0; m < 4; ++m) {
;                 const int k = row0 + ai * 128 + m * 16;
; #pragma unroll
;                 for (int bj = 0; bj < 2; ++bj) {
;                     const f32x4 v0 = acc[ai][bj][m][0] + yh[bj][0], v1 = acc[ai][bj][m][1] + yh[bj][1];
;                     u32x4 w; w.x = cvt_pk_bf16(v0[0], v0[1]); w.y = cvt_pk_bf16(v0[2], v0[3]); w.z = cvt_pk_bf16(v1[0], v1[1]); w.w = cvt_pk_bf16(v1[2], v1[3]);
;                     *(u32x4*)(CAT + (size_t)(b * 2048 + k) * CATW + 1024 + ch0 + bj * 128) = w;
;                 }
;             }
	v_pk_fma_f32 v[126:127], v[142:143], v[160:161], v[126:127] op_sel_hi:[1,0,1]
	v_pk_fma_f32 v[124:125], v[140:141], v[160:161], v[124:125] op_sel_hi:[1,0,1]
	v_pk_fma_f32 v[122:123], v[138:139], v[160:161], v[122:123] op_sel_hi:[1,0,1]
	v_pk_fma_f32 v[180:181], v[128:129], v[160:161], v[80:81] op_sel_hi:[1,0,1]
	v_cvt_pk_bf16_f32 v80, v124, v125
	v_cvt_pk_bf16_f32 v81, v126, v127
	v_pk_fma_f32 v[120:121], v[136:137], v[160:161], v[120:121] op_sel_hi:[1,0,1]
	v_pk_fma_f32 v[106:107], v[134:135], v[160:161], v[106:107] op_sel_hi:[1,0,1]
	v_pk_fma_f32 v[104:105], v[132:133], v[160:161], v[104:105] op_sel_hi:[1,0,1]
	v_pk_fma_f32 v[178:179], v[130:131], v[160:161], v[82:83] op_sel_hi:[1,0,1]
	v_cvt_pk_bf16_f32 v82, v120, v121
	v_cvt_pk_bf16_f32 v83, v122, v123
	global_store_dwordx4 v[172:173], v[80:83], off offset:2048
	v_pk_fma_f32 v[98:99], v[130:131], v[160:161], v[98:99] op_sel_hi:[1,0,1]
	v_pk_fma_f32 v[96:97], v[128:129], v[160:161], v[96:97] op_sel_hi:[1,0,1]
	v_cvt_pk_bf16_f32 v80, v104, v105
	v_cvt_pk_bf16_f32 v81, v106, v107
	v_pk_fma_f32 v[118:119], v[142:143], v[160:161], v[118:119] op_sel_hi:[1,0,1]
	v_pk_fma_f32 v[116:117], v[140:141], v[160:161], v[116:117] op_sel_hi:[1,0,1]
	v_cvt_pk_bf16_f32 v82, v96, v97
	v_cvt_pk_bf16_f32 v83, v98, v99
	global_store_dwordx4 v[172:173], v[80:83], off offset:2304
	v_pk_fma_f32 v[114:115], v[138:139], v[160:161], v[114:115] op_sel_hi:[1,0,1]
	v_pk_fma_f32 v[112:113], v[136:137], v[160:161], v[112:113] op_sel_hi:[1,0,1]
	v_cvt_pk_bf16_f32 v80, v116, v117
	v_cvt_pk_bf16_f32 v81, v118, v119
	v_pk_fma_f32 v[94:95], v[134:135], v[160:161], v[94:95] op_sel_hi:[1,0,1]
	v_pk_fma_f32 v[92:93], v[132:133], v[160:161], v[92:93] op_sel_hi:[1,0,1]
	v_cvt_pk_bf16_f32 v82, v112, v113
	v_cvt_pk_bf16_f32 v83, v114, v115
	global_store_dwordx4 v[174:175], v[80:83], off offset:2048
	v_pk_fma_f32 v[90:91], v[130:131], v[160:161], v[90:91] op_sel_hi:[1,0,1]
	v_pk_fma_f32 v[88:89], v[128:129], v[160:161], v[88:89] op_sel_hi:[1,0,1]
	v_cvt_pk_bf16_f32 v80, v92, v93
	v_cvt_pk_bf16_f32 v81, v94, v95
	v_pk_fma_f32 v[110:111], v[142:143], v[160:161], v[110:111] op_sel_hi:[1,0,1]
	v_pk_fma_f32 v[108:109], v[140:141], v[160:161], v[108:109] op_sel_hi:[1,0,1]
	v_cvt_pk_bf16_f32 v82, v88, v89
	v_cvt_pk_bf16_f32 v83, v90, v91
	global_store_dwordx4 v[174:175], v[80:83], off offset:2304
	v_pk_fma_f32 v[102:103], v[138:139], v[160:161], v[102:103] op_sel_hi:[1,0,1]
	v_pk_fma_f32 v[100:101], v[136:137], v[160:161], v[100:101] op_sel_hi:[1,0,1]
	v_cvt_pk_bf16_f32 v80, v108, v109
	v_cvt_pk_bf16_f32 v81, v110, v111
	v_pk_fma_f32 v[86:87], v[134:135], v[160:161], v[86:87] op_sel_hi:[1,0,1]
	v_pk_fma_f32 v[84:85], v[132:133], v[160:161], v[84:85] op_sel_hi:[1,0,1]
	v_cvt_pk_bf16_f32 v82, v100, v101
	v_cvt_pk_bf16_f32 v83, v102, v103
	global_store_dwordx4 v[176:177], v[80:83], off offset:2048
	v_pk_fma_f32 v[76:77], v[140:141], v[160:161], v[76:77] op_sel_hi:[1,0,1]
	v_pk_fma_f32 v[78:79], v[142:143], v[160:161], v[78:79] op_sel_hi:[1,0,1]
	v_cvt_pk_bf16_f32 v80, v84, v85
	v_cvt_pk_bf16_f32 v81, v86, v87
	v_cvt_pk_bf16_f32 v82, v180, v181
	v_cvt_pk_bf16_f32 v83, v178, v179
	global_store_dwordx4 v[176:177], v[80:83], off offset:2304
	v_pk_fma_f32 v[70:71], v[134:135], v[160:161], v[70:71] op_sel_hi:[1,0,1]
	v_pk_fma_f32 v[68:69], v[132:133], v[160:161], v[68:69] op_sel_hi:[1,0,1]
	v_pk_fma_f32 v[80:81], v[138:139], v[160:161], v[74:75] op_sel_hi:[1,0,1]
	v_pk_fma_f32 v[74:75], v[136:137], v[160:161], v[72:73] op_sel_hi:[1,0,1]
	v_cvt_pk_bf16_f32 v72, v76, v77
	v_mad_i64_i32 v[76:77], s[14:15], v182, s37, v[162:163]
	v_cvt_pk_bf16_f32 v73, v78, v79
	v_lshl_add_u64 v[76:77], v[76:77], 0, v[164:165]
	v_cvt_pk_bf16_f32 v74, v74, v75
	v_cvt_pk_bf16_f32 v75, v80, v81
	global_store_dwordx4 v[76:77], v[72:75], off offset:2048
	v_pk_fma_f32 v[60:61], v[140:141], v[160:161], v[60:61] op_sel_hi:[1,0,1]
	v_pk_fma_f32 v[62:63], v[142:143], v[160:161], v[62:63] op_sel_hi:[1,0,1]
	v_pk_fma_f32 v[72:73], v[130:131], v[160:161], v[66:67] op_sel_hi:[1,0,1]
	v_pk_fma_f32 v[66:67], v[128:129], v[160:161], v[64:65] op_sel_hi:[1,0,1]
	v_cvt_pk_bf16_f32 v64, v68, v69
	v_cvt_pk_bf16_f32 v65, v70, v71
	v_pk_fma_f32 v[54:55], v[134:135], v[160:161], v[54:55] op_sel_hi:[1,0,1]
	v_cvt_pk_bf16_f32 v66, v66, v67
	v_cvt_pk_bf16_f32 v67, v72, v73
	global_store_dwordx4 v[76:77], v[64:67], off offset:2304
	v_pk_fma_f32 v[52:53], v[132:133], v[160:161], v[52:53] op_sel_hi:[1,0,1]
	v_pk_fma_f32 v[38:39], v[134:135], v[160:161], v[38:39] op_sel_hi:[1,0,1]
	v_add_u32_e32 v66, 0x80, v171
	v_pk_fma_f32 v[64:65], v[138:139], v[160:161], v[58:59] op_sel_hi:[1,0,1]
	v_pk_fma_f32 v[58:59], v[136:137], v[160:161], v[56:57] op_sel_hi:[1,0,1]
	v_cvt_pk_bf16_f32 v56, v60, v61
	v_mad_i64_i32 v[60:61], s[14:15], v66, s37, v[162:163]
	v_cvt_pk_bf16_f32 v57, v62, v63
	v_lshl_add_u64 v[60:61], v[60:61], 0, v[164:165]
	v_cvt_pk_bf16_f32 v58, v58, v59
	v_cvt_pk_bf16_f32 v59, v64, v65
	global_store_dwordx4 v[60:61], v[56:59], off offset:2048
	v_pk_fma_f32 v[36:37], v[132:133], v[160:161], v[36:37] op_sel_hi:[1,0,1]
	v_pk_fma_f32 v[22:23], v[134:135], v[160:161], v[22:23] op_sel_hi:[1,0,1]
	v_pk_fma_f32 v[56:57], v[130:131], v[160:161], v[46:47] op_sel_hi:[1,0,1]
	v_pk_fma_f32 v[46:47], v[128:129], v[160:161], v[44:45] op_sel_hi:[1,0,1]
	v_cvt_pk_bf16_f32 v44, v52, v53
	v_cvt_pk_bf16_f32 v45, v54, v55
	v_add_u32_e32 v52, 0x90, v171
	v_cvt_pk_bf16_f32 v46, v46, v47
	v_cvt_pk_bf16_f32 v47, v56, v57
	global_store_dwordx4 v[60:61], v[44:47], off offset:2304
	v_pk_fma_f32 v[20:21], v[132:133], v[160:161], v[20:21] op_sel_hi:[1,0,1]
	v_pk_fma_f32 v[6:7], v[134:135], v[160:161], v[6:7] op_sel_hi:[1,0,1]
; __device__ __forceinline__ unsigned cvt_pk_bf16(float lo, float hi) { unsigned r; asm volatile("v_cvt_pk_bf16_f32 %0, %1, %2" : "=v"(r) : "v"(lo), "v"(hi)); return r; }
;     __device__ __forceinline__ void operator()(const AccT& acc, const Unit& u, int wr, int wc, int fr, int fq) const {
;         asm volatile("" : "+v"(fr), "+v"(fq));
;         const int row0 = u.pm * 256 + wr * 64 + fr; const int b = u.pn >> 1, ch0 = (u.pn & 1) * 256 + wc * 32 + 8 * fq;
;         const float sg = (fr & 1) ? -1.0f : 1.0f;
;         f32x4 yh[2][2];
; #pragma unroll
;         for (int bj = 0; bj < 2; ++bj)
; #pragma unroll
;             for (int n = 0; n < 2; ++n) yh[bj][n] = *(const f32x4*)(YCH + b * 512 + ch0 + bj * 128 + 4 * n) * sg;
; #pragma unroll
;         for (int ai = 0; ai < 2; ++ai)
; #pragma unroll
;             for (int m = 0; m < 4; ++m) {
;                 const int k = row0 + ai * 128 + m * 16;
; #pragma unroll
;                 for (int bj = 0; bj < 2; ++bj) {
;                     const f32x4 v0 = acc[ai][bj][m][0] + yh[bj][0], v1 = acc[ai][bj][m][1] + yh[bj][1];
;                     u32x4 w; w.x = cvt_pk_bf16(v0[0], v0[1]); w.y = cvt_pk_bf16(v0[2], v0[3]); w.z = cvt_pk_bf16(v1[0], v1[1]); w.w = cvt_pk_bf16(v1[2], v1[3]);
;                     *(u32x4*)(CAT + (size_t)(b * 2048 + k) * CATW + 1024 + ch0 + bj * 128) = w;
;                 }
;             }
	v_pk_fma_f32 v[44:45], v[142:143], v[160:161], v[50:51] op_sel_hi:[1,0,1]
	v_pk_fma_f32 v[46:47], v[140:141], v[160:161], v[48:49] op_sel_hi:[1,0,1]
	v_pk_fma_f32 v[48:49], v[138:139], v[160:161], v[42:43] op_sel_hi:[1,0,1]
	v_pk_fma_f32 v[42:43], v[136:137], v[160:161], v[40:41] op_sel_hi:[1,0,1]
	v_cvt_pk_bf16_f32 v40, v46, v47
	v_cvt_pk_bf16_f32 v41, v44, v45
	v_mad_i64_i32 v[44:45], s[14:15], v52, s37, v[162:163]
	v_lshl_add_u64 v[44:45], v[44:45], 0, v[164:165]
	v_cvt_pk_bf16_f32 v42, v42, v43
	v_cvt_pk_bf16_f32 v43, v48, v49
	global_store_dwordx4 v[44:45], v[40:43], off offset:2048
	v_pk_fma_f32 v[4:5], v[132:133], v[160:161], v[4:5] op_sel_hi:[1,0,1]
	s_nop 0
	v_pk_fma_f32 v[40:41], v[130:131], v[160:161], v[30:31] op_sel_hi:[1,0,1]
	v_pk_fma_f32 v[30:31], v[128:129], v[160:161], v[28:29] op_sel_hi:[1,0,1]
	v_cvt_pk_bf16_f32 v28, v36, v37
	v_cvt_pk_bf16_f32 v29, v38, v39
	v_add_u32_e32 v36, 0xa0, v171
	v_cvt_pk_bf16_f32 v30, v30, v31
	v_cvt_pk_bf16_f32 v31, v40, v41
	global_store_dwordx4 v[44:45], v[28:31], off offset:2304
	s_nop 1
	v_pk_fma_f32 v[28:29], v[142:143], v[160:161], v[34:35] op_sel_hi:[1,0,1]
	v_pk_fma_f32 v[30:31], v[140:141], v[160:161], v[32:33] op_sel_hi:[1,0,1]
	v_pk_fma_f32 v[32:33], v[138:139], v[160:161], v[26:27] op_sel_hi:[1,0,1]
	v_pk_fma_f32 v[26:27], v[136:137], v[160:161], v[24:25] op_sel_hi:[1,0,1]
	v_cvt_pk_bf16_f32 v24, v30, v31
	v_cvt_pk_bf16_f32 v25, v28, v29
	v_mad_i64_i32 v[28:29], s[14:15], v36, s37, v[162:163]
	v_lshl_add_u64 v[28:29], v[28:29], 0, v[164:165]
	v_cvt_pk_bf16_f32 v26, v26, v27
	v_cvt_pk_bf16_f32 v27, v32, v33
	global_store_dwordx4 v[28:29], v[24:27], off offset:2048
	s_nop 1
	v_pk_fma_f32 v[24:25], v[130:131], v[160:161], v[14:15] op_sel_hi:[1,0,1]
	v_pk_fma_f32 v[14:15], v[128:129], v[160:161], v[12:13] op_sel_hi:[1,0,1]
	v_cvt_pk_bf16_f32 v12, v20, v21
	v_cvt_pk_bf16_f32 v13, v22, v23
	v_add_u32_e32 v20, 0xb0, v171
	v_cvt_pk_bf16_f32 v14, v14, v15
	v_cvt_pk_bf16_f32 v15, v24, v25
	global_store_dwordx4 v[28:29], v[12:15], off offset:2304
	s_nop 1
	v_pk_fma_f32 v[12:13], v[142:143], v[160:161], v[18:19] op_sel_hi:[1,0,1]
	v_pk_fma_f32 v[14:15], v[140:141], v[160:161], v[16:17] op_sel_hi:[1,0,1]
	v_pk_fma_f32 v[16:17], v[138:139], v[160:161], v[10:11] op_sel_hi:[1,0,1]
	v_pk_fma_f32 v[10:11], v[136:137], v[160:161], v[8:9] op_sel_hi:[1,0,1]
	v_cvt_pk_bf16_f32 v8, v14, v15
	v_cvt_pk_bf16_f32 v9, v12, v13
	v_mad_i64_i32 v[12:13], s[14:15], v20, s37, v[162:163]
	v_lshl_add_u64 v[12:13], v[12:13], 0, v[164:165]
	v_cvt_pk_bf16_f32 v10, v10, v11
	v_cvt_pk_bf16_f32 v11, v16, v17
	global_store_dwordx4 v[12:13], v[8:11], off offset:2048
	s_mov_b64 s[14:15], s[8:9]
	s_nop 0
	v_pk_fma_f32 v[8:9], v[130:131], v[160:161], v[2:3] op_sel_hi:[1,0,1]
	v_pk_fma_f32 v[2:3], v[128:129], v[160:161], v[0:1] op_sel_hi:[1,0,1]
	v_cvt_pk_bf16_f32 v0, v4, v5
	v_cvt_pk_bf16_f32 v1, v6, v7
	s_nop 0
	v_cvt_pk_bf16_f32 v2, v2, v3
	v_cvt_pk_bf16_f32 v3, v8, v9
	global_store_dwordx4 v[12:13], v[0:3], off offset:2304
	s_cbranch_vccz .LBB0_819
	s_branch .Lconc_end_g9
.Lconc_epi1_g9:
	s_ashr_i32 s5, s38, 1
	s_lshl_b32 s7, s38, 8
	s_lshl_b32 s14, s5, 9
	s_and_b32 s7, s7, 0x100
	s_ashr_i32 s15, s14, 31
	v_mov_b32_e32 v171, v161
	v_mov_b32_e32 v128, v166
	s_or_b32 s7, s7, s30
	s_lshl_b64 s[14:15], s[14:15], 2
	s_add_u32 s14, s48, s14
	v_lshl_add_u32 v164, v128, 3, s7
	s_addc_u32 s15, s49, s15
	v_ashrrev_i32_e32 v165, 31, v164
	v_lshl_add_u64 v[128:129], v[164:165], 2, s[14:15]
	global_load_dwordx4 v[140:143], v[128:129], off
	global_load_dwordx4 v[136:139], v[128:129], off offset:16
	global_load_dwordx4 v[132:135], v[128:129], off offset:512
	s_nop 0
	global_load_dwordx4 v[128:131], v[128:129], off offset:528
	s_lshl_b32 s7, s12, 8
	s_lshl_b32 s5, s5, 11
	s_add_i32 s7, s7, s29
	v_and_b32_e32 v160, 1, v171
	s_add_i32 s7, s7, s5
	v_mov_b64_e32 v[162:163], s[96:97]
	v_cmp_eq_u32_e32 vcc, 0, v160
	v_add_u32_e32 v171, s7, v171
	v_lshlrev_b64 v[164:165], 1, v[164:165]
	v_cndmask_b32_e64 v160, -1.0, 1.0, vcc
	v_mad_i64_i32 v[172:173], s[14:15], v171, s37, v[162:163]
	v_add_u32_e32 v174, 16, v171
	v_lshl_add_u64 v[172:173], v[172:173], 0, v[164:165]
	v_mad_i64_i32 v[174:175], s[14:15], v174, s37, v[162:163]
	v_add_u32_e32 v176, 32, v171
	v_lshl_add_u64 v[174:175], v[174:175], 0, v[164:165]
	v_mad_i64_i32 v[176:177], s[14:15], v176, s37, v[162:163]
	v_lshl_add_u64 v[176:177], v[176:177], 0, v[164:165]
	v_add_u32_e32 v182, 48, v171
	s_and_b64 vcc, exec, s[2:3]
	s_mov_b32 s38, s4
	s_mov_b32 s12, s6
	s_mov_b64 s[16:17], s[10:11]
	s_waitcnt vmcnt(0)
; __device__ __forceinline__ unsigned cvt_pk_bf16(float lo, float hi) { unsigned r; asm volatile("v_cvt_pk_bf16_f32 %0, %1, %2" : "=v"(r) : "v"(lo), "v"(hi)); return r; }
;     __device__ __forceinline__ void operator()(const AccT& acc, const Unit& u, int wr, int wc, int fr, int fq) const {
;     ...
; #pragma unroll
;         for (int ai = 0; ai < 2; ++ai)
; #pragma unroll
;             for (int m = 0; m < 4; ++m) {
;                 const int k = row0 + ai * 128 + m * 16;
; #pragma unroll
;                 for (int bj = 0; bj < 2; ++bj) {
;                     const f32x4 v0 = acc[ai][bj][m][0] + yh[bj][0], v1 = acc[ai][bj][m][1] + yh[bj][1];
;                     u32x4 w; w.x = cvt_pk_bf16(v0[0], v0[1]); w.y = cvt_pk_bf16(v0[2], v0[3]); w.z = cvt_pk_bf16(v1[0], v1[1]); w.w = cvt_pk_bf16(v1[2], v1[3]);
;                     *(u32x4*)(CAT + (size_t)(b * 2048 + k) * CATW + 1024 + ch0 + bj * 128) = w;
;                 }
;             }
	v_pk_fma_f32 v[126:127], v[142:143], v[160:161], v[126:127] op_sel_hi:[1,0,1]
	v_pk_fma_f32 v[124:125], v[140:141], v[160:161], v[124:125] op_sel_hi:[1,0,1]
	v_pk_fma_f32 v[122:123], v[138:139], v[160:161], v[122:123] op_sel_hi:[1,0,1]
	v_pk_fma_f32 v[180:181], v[128:129], v[160:161], v[80:81] op_sel_hi:[1,0,1]
	v_cvt_pk_bf16_f32 v80, v124, v125
	v_cvt_pk_bf16_f32 v81, v126, v127
	v_pk_fma_f32 v[120:121], v[136:137], v[160:161], v[120:121] op_sel_hi:[1,0,1]
	v_pk_fma_f32 v[106:107], v[134:135], v[160:161], v[106:107] op_sel_hi:[1,0,1]
	v_pk_fma_f32 v[104:105], v[132:133], v[160:161], v[104:105] op_sel_hi:[1,0,1]
	v_pk_fma_f32 v[178:179], v[130:131], v[160:161], v[82:83] op_sel_hi:[1,0,1]
	v_cvt_pk_bf16_f32 v82, v120, v121
	v_cvt_pk_bf16_f32 v83, v122, v123
	global_store_dwordx4 v[172:173], v[80:83], off offset:2048
	v_pk_fma_f32 v[98:99], v[130:131], v[160:161], v[98:99] op_sel_hi:[1,0,1]
	v_pk_fma_f32 v[96:97], v[128:129], v[160:161], v[96:97] op_sel_hi:[1,0,1]
	v_cvt_pk_bf16_f32 v80, v104, v105
	v_cvt_pk_bf16_f32 v81, v106, v107
	v_pk_fma_f32 v[118:119], v[142:143], v[160:161], v[118:119] op_sel_hi:[1,0,1]
	v_pk_fma_f32 v[116:117], v[140:141], v[160:161], v[116:117] op_sel_hi:[1,0,1]
	v_cvt_pk_bf16_f32 v82, v96, v97
	v_cvt_pk_bf16_f32 v83, v98, v99
	global_store_dwordx4 v[172:173], v[80:83], off offset:2304
	v_pk_fma_f32 v[114:115], v[138:139], v[160:161], v[114:115] op_sel_hi:[1,0,1]
	v_pk_fma_f32 v[112:113], v[136:137], v[160:161], v[112:113] op_sel_hi:[1,0,1]
	v_cvt_pk_bf16_f32 v80, v116, v117
	v_cvt_pk_bf16_f32 v81, v118, v119
	v_pk_fma_f32 v[94:95], v[134:135], v[160:161], v[94:95] op_sel_hi:[1,0,1]
	v_pk_fma_f32 v[92:93], v[132:133], v[160:161], v[92:93] op_sel_hi:[1,0,1]
	v_cvt_pk_bf16_f32 v82, v112, v113
	v_cvt_pk_bf16_f32 v83, v114, v115
	global_store_dwordx4 v[174:175], v[80:83], off offset:2048
	v_pk_fma_f32 v[90:91], v[130:131], v[160:161], v[90:91] op_sel_hi:[1,0,1]
	v_pk_fma_f32 v[88:89], v[128:129], v[160:161], v[88:89] op_sel_hi:[1,0,1]
	v_cvt_pk_bf16_f32 v80, v92, v93
	v_cvt_pk_bf16_f32 v81, v94, v95
	v_pk_fma_f32 v[110:111], v[142:143], v[160:161], v[110:111] op_sel_hi:[1,0,1]
	v_pk_fma_f32 v[108:109], v[140:141], v[160:161], v[108:109] op_sel_hi:[1,0,1]
	v_cvt_pk_bf16_f32 v82, v88, v89
	v_cvt_pk_bf16_f32 v83, v90, v91
	global_store_dwordx4 v[174:175], v[80:83], off offset:2304
	v_pk_fma_f32 v[102:103], v[138:139], v[160:161], v[102:103] op_sel_hi:[1,0,1]
	v_pk_fma_f32 v[100:101], v[136:137], v[160:161], v[100:101] op_sel_hi:[1,0,1]
	v_cvt_pk_bf16_f32 v80, v108, v109
	v_cvt_pk_bf16_f32 v81, v110, v111
	v_pk_fma_f32 v[86:87], v[134:135], v[160:161], v[86:87] op_sel_hi:[1,0,1]
	v_pk_fma_f32 v[84:85], v[132:133], v[160:161], v[84:85] op_sel_hi:[1,0,1]
	v_cvt_pk_bf16_f32 v82, v100, v101
	v_cvt_pk_bf16_f32 v83, v102, v103
	global_store_dwordx4 v[176:177], v[80:83], off offset:2048
	v_pk_fma_f32 v[76:77], v[140:141], v[160:161], v[76:77] op_sel_hi:[1,0,1]
	v_pk_fma_f32 v[78:79], v[142:143], v[160:161], v[78:79] op_sel_hi:[1,0,1]
	v_cvt_pk_bf16_f32 v80, v84, v85
	v_cvt_pk_bf16_f32 v81, v86, v87
	v_cvt_pk_bf16_f32 v82, v180, v181
	v_cvt_pk_bf16_f32 v83, v178, v179
	global_store_dwordx4 v[176:177], v[80:83], off offset:2304
	v_pk_fma_f32 v[70:71], v[134:135], v[160:161], v[70:71] op_sel_hi:[1,0,1]
	v_pk_fma_f32 v[68:69], v[132:133], v[160:161], v[68:69] op_sel_hi:[1,0,1]
	v_pk_fma_f32 v[80:81], v[138:139], v[160:161], v[74:75] op_sel_hi:[1,0,1]
	v_pk_fma_f32 v[74:75], v[136:137], v[160:161], v[72:73] op_sel_hi:[1,0,1]
	v_cvt_pk_bf16_f32 v72, v76, v77
	v_mad_i64_i32 v[76:77], s[14:15], v182, s37, v[162:163]
	v_cvt_pk_bf16_f32 v73, v78, v79
	v_lshl_add_u64 v[76:77], v[76:77], 0, v[164:165]
	v_cvt_pk_bf16_f32 v74, v74, v75
	v_cvt_pk_bf16_f32 v75, v80, v81
	global_store_dwordx4 v[76:77], v[72:75], off offset:2048
	v_pk_fma_f32 v[60:61], v[140:141], v[160:161], v[60:61] op_sel_hi:[1,0,1]
	v_pk_fma_f32 v[62:63], v[142:143], v[160:161], v[62:63] op_sel_hi:[1,0,1]
	v_pk_fma_f32 v[72:73], v[130:131], v[160:161], v[66:67] op_sel_hi:[1,0,1]
	v_pk_fma_f32 v[66:67], v[128:129], v[160:161], v[64:65] op_sel_hi:[1,0,1]
	v_cvt_pk_bf16_f32 v64, v68, v69
	v_cvt_pk_bf16_f32 v65, v70, v71
	v_pk_fma_f32 v[54:55], v[134:135], v[160:161], v[54:55] op_sel_hi:[1,0,1]
	v_cvt_pk_bf16_f32 v66, v66, v67
	v_cvt_pk_bf16_f32 v67, v72, v73
	global_store_dwordx4 v[76:77], v[64:67], off offset:2304
; __device__ __forceinline__ unsigned cvt_pk_bf16(float lo, float hi) { unsigned r; asm volatile("v_cvt_pk_bf16_f32 %0, %1, %2" : "=v"(r) : "v"(lo), "v"(hi)); return r; }
; #define PG8_WAIT_V(n) asm volatile("s_waitcnt vmcnt(" #n ")" ::: "memory")
; #define PG8_BAR __builtin_amdgcn_s_barrier()
; template <class Epi, class Sched>
; __device__ __forceinline__ void gemm_phase(LAS unsigned char* lds, const Gemm g, const Sched& S, const Epi& E) {
;     ...
;         E(acc, cur, wr, wc, fr, fq);
;         if (!has_next) break;
; #pragma unroll
;         for (int a = 0; a < 2; ++a)
; #pragma unroll
;             for (int b = 0; b < 2; ++b)
; #pragma unroll
;                 for (int m = 0; m < 4; ++m)
; #pragma unroll
;                     for (int n = 0; n < 2; ++n) acc[a][b][m][n] = (f32x4){0.f, 0.f, 0.f, 0.f};
;         cur = nxt; cA = nA; cB = nB; ++ui;
;     }
;     PG8_WAIT_V(0);
;     if (wr == 0) PG8_BAR;
;     PG8_BAR;
;     __device__ __forceinline__ void operator()(const AccT& acc, const Unit& u, int wr, int wc, int fr, int fq) const {
;     ...
; #pragma unroll
;         for (int ai = 0; ai < 2; ++ai)
; #pragma unroll
;             for (int m = 0; m < 4; ++m) {
;                 const int k = row0 + ai * 128 + m * 16;
; #pragma unroll
;                 for (int bj = 0; bj < 2; ++bj) {
;                     const f32x4 v0 = acc[ai][bj][m][0] + yh[bj][0], v1 = acc[ai][bj][m][1] + yh[bj][1];
;                     u32x4 w; w.x = cvt_pk_bf16(v0[0], v0[1]); w.y = cvt_pk_bf16(v0[2], v0[3]); w.z = cvt_pk_bf16(v1[0], v1[1]); w.w = cvt_pk_bf16(v1[2], v1[3]);
;                     *(u32x4*)(CAT + (size_t)(b * 2048 + k) * CATW + 1024 + ch0 + bj * 128) = w;
;                 }
;             }
	v_pk_fma_f32 v[52:53], v[132:133], v[160:161], v[52:53] op_sel_hi:[1,0,1]
	v_pk_fma_f32 v[38:39], v[134:135], v[160:161], v[38:39] op_sel_hi:[1,0,1]
	v_add_u32_e32 v66, 0x80, v171
	v_pk_fma_f32 v[64:65], v[138:139], v[160:161], v[58:59] op_sel_hi:[1,0,1]
	v_pk_fma_f32 v[58:59], v[136:137], v[160:161], v[56:57] op_sel_hi:[1,0,1]
	v_cvt_pk_bf16_f32 v56, v60, v61
	v_mad_i64_i32 v[60:61], s[14:15], v66, s37, v[162:163]
	v_cvt_pk_bf16_f32 v57, v62, v63
	v_lshl_add_u64 v[60:61], v[60:61], 0, v[164:165]
	v_cvt_pk_bf16_f32 v58, v58, v59
	v_cvt_pk_bf16_f32 v59, v64, v65
	global_store_dwordx4 v[60:61], v[56:59], off offset:2048
	v_pk_fma_f32 v[36:37], v[132:133], v[160:161], v[36:37] op_sel_hi:[1,0,1]
	v_pk_fma_f32 v[22:23], v[134:135], v[160:161], v[22:23] op_sel_hi:[1,0,1]
	v_pk_fma_f32 v[56:57], v[130:131], v[160:161], v[46:47] op_sel_hi:[1,0,1]
	v_pk_fma_f32 v[46:47], v[128:129], v[160:161], v[44:45] op_sel_hi:[1,0,1]
	v_cvt_pk_bf16_f32 v44, v52, v53
	v_cvt_pk_bf16_f32 v45, v54, v55
	v_add_u32_e32 v52, 0x90, v171
	v_cvt_pk_bf16_f32 v46, v46, v47
	v_cvt_pk_bf16_f32 v47, v56, v57
	global_store_dwordx4 v[60:61], v[44:47], off offset:2304
	v_pk_fma_f32 v[20:21], v[132:133], v[160:161], v[20:21] op_sel_hi:[1,0,1]
	v_pk_fma_f32 v[6:7], v[134:135], v[160:161], v[6:7] op_sel_hi:[1,0,1]
	v_pk_fma_f32 v[44:45], v[142:143], v[160:161], v[50:51] op_sel_hi:[1,0,1]
	v_pk_fma_f32 v[46:47], v[140:141], v[160:161], v[48:49] op_sel_hi:[1,0,1]
	v_pk_fma_f32 v[48:49], v[138:139], v[160:161], v[42:43] op_sel_hi:[1,0,1]
	v_pk_fma_f32 v[42:43], v[136:137], v[160:161], v[40:41] op_sel_hi:[1,0,1]
	v_cvt_pk_bf16_f32 v40, v46, v47
	v_cvt_pk_bf16_f32 v41, v44, v45
	v_mad_i64_i32 v[44:45], s[14:15], v52, s37, v[162:163]
	v_lshl_add_u64 v[44:45], v[44:45], 0, v[164:165]
	v_cvt_pk_bf16_f32 v42, v42, v43
	v_cvt_pk_bf16_f32 v43, v48, v49
	global_store_dwordx4 v[44:45], v[40:43], off offset:2048
	v_pk_fma_f32 v[4:5], v[132:133], v[160:161], v[4:5] op_sel_hi:[1,0,1]
	s_nop 0
	v_pk_fma_f32 v[40:41], v[130:131], v[160:161], v[30:31] op_sel_hi:[1,0,1]
	v_pk_fma_f32 v[30:31], v[128:129], v[160:161], v[28:29] op_sel_hi:[1,0,1]
	v_cvt_pk_bf16_f32 v28, v36, v37
	v_cvt_pk_bf16_f32 v29, v38, v39
	v_add_u32_e32 v36, 0xa0, v171
	v_cvt_pk_bf16_f32 v30, v30, v31
	v_cvt_pk_bf16_f32 v31, v40, v41
	global_store_dwordx4 v[44:45], v[28:31], off offset:2304
	s_nop 1
	v_pk_fma_f32 v[28:29], v[142:143], v[160:161], v[34:35] op_sel_hi:[1,0,1]
	v_pk_fma_f32 v[30:31], v[140:141], v[160:161], v[32:33] op_sel_hi:[1,0,1]
	v_pk_fma_f32 v[32:33], v[138:139], v[160:161], v[26:27] op_sel_hi:[1,0,1]
	v_pk_fma_f32 v[26:27], v[136:137], v[160:161], v[24:25] op_sel_hi:[1,0,1]
	v_cvt_pk_bf16_f32 v24, v30, v31
	v_cvt_pk_bf16_f32 v25, v28, v29
	v_mad_i64_i32 v[28:29], s[14:15], v36, s37, v[162:163]
	v_lshl_add_u64 v[28:29], v[28:29], 0, v[164:165]
	v_cvt_pk_bf16_f32 v26, v26, v27
	v_cvt_pk_bf16_f32 v27, v32, v33
	global_store_dwordx4 v[28:29], v[24:27], off offset:2048
	s_nop 1
	v_pk_fma_f32 v[24:25], v[130:131], v[160:161], v[14:15] op_sel_hi:[1,0,1]
	v_pk_fma_f32 v[14:15], v[128:129], v[160:161], v[12:13] op_sel_hi:[1,0,1]
	v_cvt_pk_bf16_f32 v12, v20, v21
	v_cvt_pk_bf16_f32 v13, v22, v23
	v_add_u32_e32 v20, 0xb0, v171
	v_cvt_pk_bf16_f32 v14, v14, v15
	v_cvt_pk_bf16_f32 v15, v24, v25
	global_store_dwordx4 v[28:29], v[12:15], off offset:2304
	s_nop 1
	v_pk_fma_f32 v[12:13], v[142:143], v[160:161], v[18:19] op_sel_hi:[1,0,1]
	v_pk_fma_f32 v[14:15], v[140:141], v[160:161], v[16:17] op_sel_hi:[1,0,1]
	v_pk_fma_f32 v[16:17], v[138:139], v[160:161], v[10:11] op_sel_hi:[1,0,1]
	v_pk_fma_f32 v[10:11], v[136:137], v[160:161], v[8:9] op_sel_hi:[1,0,1]
	v_cvt_pk_bf16_f32 v8, v14, v15
	v_cvt_pk_bf16_f32 v9, v12, v13
	v_mad_i64_i32 v[12:13], s[14:15], v20, s37, v[162:163]
	v_lshl_add_u64 v[12:13], v[12:13], 0, v[164:165]
	v_cvt_pk_bf16_f32 v10, v10, v11
	v_cvt_pk_bf16_f32 v11, v16, v17
	global_store_dwordx4 v[12:13], v[8:11], off offset:2048
	s_mov_b64 s[14:15], s[8:9]
	s_nop 0
	v_pk_fma_f32 v[8:9], v[130:131], v[160:161], v[2:3] op_sel_hi:[1,0,1]
	v_pk_fma_f32 v[2:3], v[128:129], v[160:161], v[0:1] op_sel_hi:[1,0,1]
	v_cvt_pk_bf16_f32 v0, v4, v5
	v_cvt_pk_bf16_f32 v1, v6, v7
	s_nop 0
	v_cvt_pk_bf16_f32 v2, v2, v3
	v_cvt_pk_bf16_f32 v3, v8, v9
	global_store_dwordx4 v[12:13], v[0:3], off offset:2304
	s_barrier
	s_cbranch_vccz .LBB0_819
.Lconc_end_g9:
	s_waitcnt vmcnt(0)
	s_cmpk_gt_u32 s20, 0xff
	s_cbranch_scc1 .LBB0_830
	s_barrier

; #define PG8_STAGE(bufoff, gbase, voff) do { _Pragma("unroll") for (int _i = 0; _i < 2; ++_i) \
;         __builtin_amdgcn_global_load_lds((const unsigned*)((const char*)(gbase) + (voff)[_i]), (LAS unsigned*)(lds + (bufoff) + ldsw + _i * 8192), 16, 0, 0); } while (0)
; #define PG8_LDA(dst, b, h) do { _Pragma("unroll") for (int m = 0; m < 4; ++m) _Pragma("unroll") for (int k = 0; k < 2; ++k) dst[m][k] = *(const LAS bf16x8*)(lds + PG8_SA(b, h) + aoff + m * 2048 + k * 1024); } while (0)
; #define PG8_LDB(dst, b, h) do { _Pragma("unroll") for (int n = 0; n < 2; ++n) _Pragma("unroll") for (int k = 0; k < 2; ++k) dst[n][k] = *(const LAS bf16x8*)(lds + PG8_SB(b, h) + boff + n * 2048 + k * 1024); } while (0)
; #define PG8_MMA(ai, bj, At, Bt) do { __builtin_amdgcn_s_setprio(1); _Pragma("unroll") for (int m = 0; m < 4; ++m) _Pragma("unroll") for (int n = 0; n < 2; ++n) _Pragma("unroll") for (int k = 0; k < 2; ++k) \
;         acc[ai][bj][m][n] = __builtin_amdgcn_mfma_f32_16x16x32_bf16(Bt[n][k], At[m][k], acc[ai][bj][m][n], 0, 0, 0); __builtin_amdgcn_s_setprio(0); } while (0)
; #define PG8_WAIT_V(n) asm volatile("s_waitcnt vmcnt(" #n ")" ::: "memory")
; #define PG8_WAIT_L(n) asm volatile("s_waitcnt lgkmcnt(" #n ")" ::: "memory")
; #define PG8_BAR __builtin_amdgcn_s_barrier()
; #define PG8_SCHED __builtin_amdgcn_sched_barrier(0)
; template <class Epi, class Sched>
; __device__ __forceinline__ void gemm_phase(LAS unsigned char* lds, const Gemm g, const Sched& S, const Epi& E) {
;     ...
;             PG8_LDB(B0, 0, 0); PG8_SCHED; PG8_LDA(At, 0, 0); PG8_STAGE(PG8_SA(1, 1), a1 + hstep, voffA);
;             PG8_WAIT_L(8); PG8_BAR; PG8_WAIT_L(0); PG8_MMA(0, 0, At, B0); PG8_BAR; PG8_SCHED;
;             PG8_LDB(B1, 0, 1); PG8_STAGE(PG8_SB(0, 0), b2, voffB);
;             PG8_BAR; PG8_WAIT_L(0); PG8_MMA(0, 1, At, B1); PG8_BAR;
;             PG8_LDA(At, 0, 1); PG8_STAGE(PG8_SA(0, 0), a2, voffA);
;             PG8_BAR; PG8_WAIT_L(0); PG8_MMA(1, 0, At, B0); PG8_BAR; PG8_SCHED;
;             PG8_STAGE(PG8_SB(0, 1), b2 + hstep, voffB);
;             PG8_WAIT_V(6); PG8_BAR; PG8_MMA(1, 1, At, B1); PG8_BAR;
.LBB0_902:
	ds_read_b128 v[128:131], v237
	ds_read_b128 v[132:135], v237 offset:1024
	ds_read_b128 v[136:139], v237 offset:2048
	ds_read_b128 v[140:143], v237 offset:3072
	s_add_u32 s26, s24, 0x100
	s_addc_u32 s27, s25, 0
	s_cmp_eq_u32 s58, 20
	s_cselect_b32 s31, s5, s27
	s_cselect_b32 s30, s4, s26
	s_cselect_b32 s29, s7, s57
	s_cselect_b32 s28, s6, s56
	v_lshl_add_u64 v[176:177], s[24:25], 0, v[210:211]
	s_add_i32 m0, s38, 0xc000
	ds_read_b128 v[144:147], v238
	ds_read_b128 v[148:151], v238 offset:1024
	ds_read_b128 v[152:155], v238 offset:2048
	ds_read_b128 v[156:159], v238 offset:3072
	ds_read_b128 v[160:163], v238 offset:4096
	ds_read_b128 v[164:167], v238 offset:5120
	ds_read_b128 v[168:171], v238 offset:6144
	ds_read_b128 v[172:175], v238 offset:7168
	global_load_lds_dwordx4 v[176:177], off
	v_lshl_add_u64 v[176:177], s[24:25], 0, v[212:213]
	s_add_i32 m0, s38, 0xe000
	s_nop 0
	global_load_lds_dwordx4 v[176:177], off
	s_waitcnt lgkmcnt(8)
	s_waitcnt vmcnt(10)
	s_barrier
	s_waitcnt lgkmcnt(0)
	s_setprio 1
	s_waitcnt lgkmcnt(0)
	v_mfma_f32_16x16x32_bf16 v[124:127], v[128:131], v[144:147], v[124:127]
	v_mfma_f32_16x16x32_bf16 v[120:123], v[136:139], v[144:147], v[120:123]
	v_mfma_f32_16x16x32_bf16 v[108:111], v[128:131], v[152:155], v[108:111]
	v_mfma_f32_16x16x32_bf16 v[104:107], v[136:139], v[152:155], v[104:107]
	v_mfma_f32_16x16x32_bf16 v[92:95], v[128:131], v[160:163], v[92:95]
	v_mfma_f32_16x16x32_bf16 v[88:91], v[136:139], v[160:163], v[88:91]
	v_mfma_f32_16x16x32_bf16 v[76:79], v[128:131], v[168:171], v[76:79]
	v_mfma_f32_16x16x32_bf16 v[72:75], v[136:139], v[168:171], v[72:75]
	v_mfma_f32_16x16x32_bf16 v[124:127], v[132:135], v[148:151], v[124:127]
	v_mfma_f32_16x16x32_bf16 v[120:123], v[140:143], v[148:151], v[120:123]
	v_mfma_f32_16x16x32_bf16 v[108:111], v[132:135], v[156:159], v[108:111]
	v_mfma_f32_16x16x32_bf16 v[104:107], v[140:143], v[156:159], v[104:107]
	v_mfma_f32_16x16x32_bf16 v[92:95], v[132:135], v[164:167], v[92:95]
	v_mfma_f32_16x16x32_bf16 v[88:91], v[140:143], v[164:167], v[88:91]
	v_mfma_f32_16x16x32_bf16 v[76:79], v[132:135], v[172:175], v[76:79]
	v_mfma_f32_16x16x32_bf16 v[72:75], v[140:143], v[172:175], v[72:75]
	s_setprio 0
	s_barrier
	s_add_i32 s24, s50, s37
	s_mov_b32 m0, s24
	ds_read_b128 v[176:179], v239
	ds_read_b128 v[180:183], v239 offset:1024
	ds_read_b128 v[184:187], v239 offset:2048
	ds_read_b128 v[188:191], v239 offset:3072
	global_load_lds_dwordx4 v204, s[28:29]
	s_add_i32 m0, s24, 0x2000
	s_nop 0
	global_load_lds_dwordx4 v208, s[28:29]
	s_waitcnt vmcnt(10)
	s_barrier
	s_waitcnt lgkmcnt(0)
	s_setprio 1
	s_waitcnt lgkmcnt(0)
	v_mfma_f32_16x16x32_bf16 v[116:119], v[176:179], v[144:147], v[116:119]
	v_mfma_f32_16x16x32_bf16 v[112:115], v[184:187], v[144:147], v[112:115]
	v_mfma_f32_16x16x32_bf16 v[100:103], v[176:179], v[152:155], v[100:103]
	v_mfma_f32_16x16x32_bf16 v[96:99], v[184:187], v[152:155], v[96:99]
	v_mfma_f32_16x16x32_bf16 v[84:87], v[176:179], v[160:163], v[84:87]
	v_mfma_f32_16x16x32_bf16 v[80:83], v[184:187], v[160:163], v[80:83]
	v_mfma_f32_16x16x32_bf16 v[68:71], v[176:179], v[168:171], v[68:71]
	v_mfma_f32_16x16x32_bf16 v[64:67], v[184:187], v[168:171], v[64:67]
	v_mfma_f32_16x16x32_bf16 v[116:119], v[180:183], v[148:151], v[116:119]
	v_mfma_f32_16x16x32_bf16 v[112:115], v[188:191], v[148:151], v[112:115]
	v_mfma_f32_16x16x32_bf16 v[100:103], v[180:183], v[156:159], v[100:103]
	v_mfma_f32_16x16x32_bf16 v[96:99], v[188:191], v[156:159], v[96:99]
	v_mfma_f32_16x16x32_bf16 v[84:87], v[180:183], v[164:167], v[84:87]
	v_mfma_f32_16x16x32_bf16 v[80:83], v[188:191], v[164:167], v[80:83]
	v_mfma_f32_16x16x32_bf16 v[68:71], v[180:183], v[172:175], v[68:71]
	v_mfma_f32_16x16x32_bf16 v[64:67], v[188:191], v[172:175], v[64:67]
	s_setprio 0
	s_mov_b32 m0, s38
	v_lshl_add_u64 v[196:197], s[30:31], 0, v[202:203]
	s_barrier
	ds_read_b128 v[144:147], v238 offset:16384
	ds_read_b128 v[148:151], v238 offset:17408
	ds_read_b128 v[152:155], v238 offset:18432
	ds_read_b128 v[156:159], v238 offset:19456
	ds_read_b128 v[160:163], v238 offset:20480
	ds_read_b128 v[164:167], v238 offset:21504
	ds_read_b128 v[168:171], v238 offset:22528
	ds_read_b128 v[172:175], v238 offset:23552
	global_load_lds_dwordx4 v202, s[30:31]
	v_lshl_add_u64 v[198:199], s[30:31], 0, v[206:207]
	s_mov_b32 m0, s39
	s_nop 0
	global_load_lds_dwordx4 v206, s[30:31]
	s_barrier
	s_waitcnt lgkmcnt(0)
	s_setprio 1
	s_waitcnt lgkmcnt(0)
	v_mfma_f32_16x16x32_bf16 v[60:63], v[128:131], v[144:147], v[60:63]
	v_mfma_f32_16x16x32_bf16 v[56:59], v[136:139], v[144:147], v[56:59]
	v_mfma_f32_16x16x32_bf16 v[44:47], v[128:131], v[152:155], v[44:47]
	v_mfma_f32_16x16x32_bf16 v[40:43], v[136:139], v[152:155], v[40:43]
	v_mfma_f32_16x16x32_bf16 v[28:31], v[128:131], v[160:163], v[28:31]
	v_mfma_f32_16x16x32_bf16 v[24:27], v[136:139], v[160:163], v[24:27]
	v_mfma_f32_16x16x32_bf16 v[12:15], v[128:131], v[168:171], v[12:15]
	v_mfma_f32_16x16x32_bf16 v[8:11], v[136:139], v[168:171], v[8:11]
	v_mfma_f32_16x16x32_bf16 v[60:63], v[132:135], v[148:151], v[60:63]
	v_mfma_f32_16x16x32_bf16 v[56:59], v[140:143], v[148:151], v[56:59]
	v_mfma_f32_16x16x32_bf16 v[44:47], v[132:135], v[156:159], v[44:47]
	v_mfma_f32_16x16x32_bf16 v[40:43], v[140:143], v[156:159], v[40:43]
	v_mfma_f32_16x16x32_bf16 v[28:31], v[132:135], v[164:167], v[28:31]
	v_mfma_f32_16x16x32_bf16 v[24:27], v[140:143], v[164:167], v[24:27]
	v_mfma_f32_16x16x32_bf16 v[12:15], v[132:135], v[172:175], v[12:15]
	v_mfma_f32_16x16x32_bf16 v[8:11], v[140:143], v[172:175], v[8:11]
	s_setprio 0
	s_barrier
; #define PG8_STAGE(bufoff, gbase, voff) do { _Pragma("unroll") for (int _i = 0; _i < 2; ++_i) \
;         __builtin_amdgcn_global_load_lds((const unsigned*)((const char*)(gbase) + (voff)[_i]), (LAS unsigned*)(lds + (bufoff) + ldsw + _i * 8192), 16, 0, 0); } while (0)
; #define PG8_LDA(dst, b, h) do { _Pragma("unroll") for (int m = 0; m < 4; ++m) _Pragma("unroll") for (int k = 0; k < 2; ++k) dst[m][k] = *(const LAS bf16x8*)(lds + PG8_SA(b, h) + aoff + m * 2048 + k * 1024); } while (0)
; #define PG8_LDB(dst, b, h) do { _Pragma("unroll") for (int n = 0; n < 2; ++n) _Pragma("unroll") for (int k = 0; k < 2; ++k) dst[n][k] = *(const LAS bf16x8*)(lds + PG8_SB(b, h) + boff + n * 2048 + k * 1024); } while (0)
; #define PG8_MMA(ai, bj, At, Bt) do { __builtin_amdgcn_s_setprio(1); _Pragma("unroll") for (int m = 0; m < 4; ++m) _Pragma("unroll") for (int n = 0; n < 2; ++n) _Pragma("unroll") for (int k = 0; k < 2; ++k) \
;         acc[ai][bj][m][n] = __builtin_amdgcn_mfma_f32_16x16x32_bf16(Bt[n][k], At[m][k], acc[ai][bj][m][n], 0, 0, 0); __builtin_amdgcn_s_setprio(0); } while (0)
; #define PG8_WAIT_V(n) asm volatile("s_waitcnt vmcnt(" #n ")" ::: "memory")
; #define PG8_WAIT_L(n) asm volatile("s_waitcnt lgkmcnt(" #n ")" ::: "memory")
; #define PG8_BAR __builtin_amdgcn_s_barrier()
; #define PG8_SCHED __builtin_amdgcn_sched_barrier(0)
; template <class Epi, class Sched>
; __device__ __forceinline__ void gemm_phase(LAS unsigned char* lds, const Gemm g, const Sched& S, const Epi& E) {
;     ...
;             PG8_STAGE(PG8_SB(0, 1), b2 + hstep, voffB);
;             PG8_WAIT_V(6); PG8_BAR; PG8_MMA(1, 1, At, B1); PG8_BAR;
;             PG8_LDB(B0, 1, 0); PG8_SCHED; PG8_LDA(At, 1, 0); PG8_STAGE(PG8_SA(0, 1), a2 + hstep, voffA);
;             PG8_WAIT_L(8); PG8_BAR; PG8_WAIT_L(0); PG8_MMA(0, 0, At, B0); PG8_BAR; PG8_SCHED;
;             PG8_LDB(B1, 1, 1); PG8_STAGE(PG8_SB(1, 0), b3, voffB);
;             PG8_BAR; PG8_WAIT_L(0); PG8_MMA(0, 1, At, B1); PG8_BAR;
;             PG8_LDA(At, 1, 1); PG8_STAGE(PG8_SA(1, 0), a3, voffA);
;             PG8_BAR; PG8_WAIT_L(0); PG8_MMA(1, 0, At, B0); PG8_BAR; PG8_SCHED;
	s_add_u32 s24, s28, 0x60000
	s_addc_u32 s25, s29, 0
	s_add_i32 s59, s51, s37
	s_mov_b32 m0, s59
	s_nop 0
	global_load_lds_dwordx4 v204, s[24:25]
	s_add_i32 m0, s59, 0x2000
	s_nop 0
	global_load_lds_dwordx4 v208, s[24:25]
	s_add_u32 s24, s30, 0x60000
	s_addc_u32 s25, s31, 0
	s_mov_b32 m0, s40
	s_nop 0
	global_load_lds_dwordx4 v202, s[24:25]
	s_mov_b32 m0, s41
	s_nop 0
	global_load_lds_dwordx4 v206, s[24:25]
	s_waitcnt vmcnt(12)
	s_barrier
	s_setprio 1
	v_mfma_f32_16x16x32_bf16 v[52:55], v[176:179], v[144:147], v[52:55]
	v_mfma_f32_16x16x32_bf16 v[48:51], v[184:187], v[144:147], v[48:51]
	v_mfma_f32_16x16x32_bf16 v[36:39], v[176:179], v[152:155], v[36:39]
	v_mfma_f32_16x16x32_bf16 v[32:35], v[184:187], v[152:155], v[32:35]
	v_mfma_f32_16x16x32_bf16 v[20:23], v[176:179], v[160:163], v[20:23]
	v_mfma_f32_16x16x32_bf16 v[16:19], v[184:187], v[160:163], v[16:19]
	v_mfma_f32_16x16x32_bf16 v[4:7], v[176:179], v[168:171], v[4:7]
	v_mfma_f32_16x16x32_bf16 v[0:3], v[184:187], v[168:171], v[0:3]
	v_mfma_f32_16x16x32_bf16 v[52:55], v[180:183], v[148:151], v[52:55]
	v_mfma_f32_16x16x32_bf16 v[48:51], v[188:191], v[148:151], v[48:51]
	v_mfma_f32_16x16x32_bf16 v[36:39], v[180:183], v[156:159], v[36:39]
	v_mfma_f32_16x16x32_bf16 v[32:35], v[188:191], v[156:159], v[32:35]
	v_mfma_f32_16x16x32_bf16 v[20:23], v[180:183], v[164:167], v[20:23]
	v_mfma_f32_16x16x32_bf16 v[16:19], v[188:191], v[164:167], v[16:19]
	v_mfma_f32_16x16x32_bf16 v[4:7], v[180:183], v[172:175], v[4:7]
	v_mfma_f32_16x16x32_bf16 v[0:3], v[188:191], v[172:175], v[0:3]
	s_setprio 0
	s_add_i32 s59, 0, 0x18000
	v_add_u32_e32 v140, s59, v236
	s_barrier
	ds_read_b128 v[128:131], v140
	ds_read_b128 v[132:135], v140 offset:1024
	ds_read_b128 v[136:139], v140 offset:2048
	ds_read_b128 v[140:143], v140 offset:3072
	ds_read_b128 v[144:147], v238 offset:32768
	ds_read_b128 v[148:151], v238 offset:33792
	ds_read_b128 v[152:155], v238 offset:34816
	ds_read_b128 v[156:159], v238 offset:35840
	ds_read_b128 v[160:163], v238 offset:36864
	ds_read_b128 v[164:167], v238 offset:37888
	ds_read_b128 v[168:171], v238 offset:38912
	ds_read_b128 v[172:175], v238 offset:39936
	s_waitcnt lgkmcnt(8)
	s_waitcnt vmcnt(10)
	s_barrier
	s_waitcnt lgkmcnt(0)
	s_setprio 1
	s_waitcnt lgkmcnt(0)
	v_mfma_f32_16x16x32_bf16 v[124:127], v[128:131], v[144:147], v[124:127]
	v_mfma_f32_16x16x32_bf16 v[120:123], v[136:139], v[144:147], v[120:123]
	v_mfma_f32_16x16x32_bf16 v[108:111], v[128:131], v[152:155], v[108:111]
	v_mfma_f32_16x16x32_bf16 v[104:107], v[136:139], v[152:155], v[104:107]
	v_mfma_f32_16x16x32_bf16 v[92:95], v[128:131], v[160:163], v[92:95]
	v_mfma_f32_16x16x32_bf16 v[88:91], v[136:139], v[160:163], v[88:91]
	v_mfma_f32_16x16x32_bf16 v[76:79], v[128:131], v[168:171], v[76:79]
	v_mfma_f32_16x16x32_bf16 v[72:75], v[136:139], v[168:171], v[72:75]
	v_mfma_f32_16x16x32_bf16 v[124:127], v[132:135], v[148:151], v[124:127]
	v_mfma_f32_16x16x32_bf16 v[120:123], v[140:143], v[148:151], v[120:123]
	v_mfma_f32_16x16x32_bf16 v[108:111], v[132:135], v[156:159], v[108:111]
	v_mfma_f32_16x16x32_bf16 v[104:107], v[140:143], v[156:159], v[104:107]
	v_mfma_f32_16x16x32_bf16 v[92:95], v[132:135], v[164:167], v[92:95]
	v_mfma_f32_16x16x32_bf16 v[88:91], v[140:143], v[164:167], v[88:91]
	v_mfma_f32_16x16x32_bf16 v[76:79], v[132:135], v[172:175], v[76:79]
	v_mfma_f32_16x16x32_bf16 v[72:75], v[140:143], v[172:175], v[72:75]
	s_setprio 0
	s_barrier
	s_add_i32 s30, 0, 0x1c000
	s_add_i32 s24, s59, s37
	v_add_u32_e32 v188, s30, v236
	s_add_u32 s0, s28, 0x80
	s_addc_u32 s1, s29, 0
	s_mov_b32 m0, s24
	ds_read_b128 v[176:179], v188
	ds_read_b128 v[180:183], v188 offset:1024
	ds_read_b128 v[184:187], v188 offset:2048
	ds_read_b128 v[188:191], v188 offset:3072
	global_load_lds_dwordx4 v204, s[0:1]
	s_add_i32 m0, s24, 0x2000
	s_nop 0
	global_load_lds_dwordx4 v208, s[0:1]
	s_waitcnt vmcnt(10)
	s_barrier
	s_waitcnt lgkmcnt(0)
	s_setprio 1
	s_waitcnt lgkmcnt(0)
	v_mfma_f32_16x16x32_bf16 v[116:119], v[176:179], v[144:147], v[116:119]
	v_mfma_f32_16x16x32_bf16 v[112:115], v[184:187], v[144:147], v[112:115]
	v_mfma_f32_16x16x32_bf16 v[100:103], v[176:179], v[152:155], v[100:103]
	v_mfma_f32_16x16x32_bf16 v[96:99], v[184:187], v[152:155], v[96:99]
	v_mfma_f32_16x16x32_bf16 v[84:87], v[176:179], v[160:163], v[84:87]
	v_mfma_f32_16x16x32_bf16 v[80:83], v[184:187], v[160:163], v[80:83]
	v_mfma_f32_16x16x32_bf16 v[68:71], v[176:179], v[168:171], v[68:71]
	v_mfma_f32_16x16x32_bf16 v[64:67], v[184:187], v[168:171], v[64:67]
	v_mfma_f32_16x16x32_bf16 v[116:119], v[180:183], v[148:151], v[116:119]
	v_mfma_f32_16x16x32_bf16 v[112:115], v[188:191], v[148:151], v[112:115]
	v_mfma_f32_16x16x32_bf16 v[100:103], v[180:183], v[156:159], v[100:103]
	v_mfma_f32_16x16x32_bf16 v[96:99], v[188:191], v[156:159], v[96:99]
	v_mfma_f32_16x16x32_bf16 v[84:87], v[180:183], v[164:167], v[84:87]
	v_mfma_f32_16x16x32_bf16 v[80:83], v[188:191], v[164:167], v[80:83]
	v_mfma_f32_16x16x32_bf16 v[68:71], v[180:183], v[172:175], v[68:71]
	v_mfma_f32_16x16x32_bf16 v[64:67], v[188:191], v[172:175], v[64:67]
	s_setprio 0
	s_mov_b32 m0, s47
	s_mov_b64 s[0:1], 0x80
	v_lshl_add_u64 v[192:193], v[196:197], 0, s[0:1]
	s_barrier
	ds_read_b128 v[144:147], v238 offset:49152
	ds_read_b128 v[148:151], v238 offset:50176
	ds_read_b128 v[152:155], v238 offset:51200
	ds_read_b128 v[156:159], v238 offset:52224
	ds_read_b128 v[160:163], v238 offset:53248
	ds_read_b128 v[164:167], v238 offset:54272
	ds_read_b128 v[168:171], v238 offset:55296
	ds_read_b128 v[172:175], v238 offset:56320
	global_load_lds_dwordx4 v[192:193], off
	v_lshl_add_u64 v[192:193], v[198:199], 0, s[0:1]
	s_mov_b32 m0, s48
	s_nop 0
	global_load_lds_dwordx4 v[192:193], off
	s_barrier
; #define PG8_STAGE(bufoff, gbase, voff) do { _Pragma("unroll") for (int _i = 0; _i < 2; ++_i) \
;         __builtin_amdgcn_global_load_lds((const unsigned*)((const char*)(gbase) + (voff)[_i]), (LAS unsigned*)(lds + (bufoff) + ldsw + _i * 8192), 16, 0, 0); } while (0)
; #define PG8_MMA(ai, bj, At, Bt) do { __builtin_amdgcn_s_setprio(1); _Pragma("unroll") for (int m = 0; m < 4; ++m) _Pragma("unroll") for (int n = 0; n < 2; ++n) _Pragma("unroll") for (int k = 0; k < 2; ++k) \
;         acc[ai][bj][m][n] = __builtin_amdgcn_mfma_f32_16x16x32_bf16(Bt[n][k], At[m][k], acc[ai][bj][m][n], 0, 0, 0); __builtin_amdgcn_s_setprio(0); } while (0)
; #define PG8_WAIT_V(n) asm volatile("s_waitcnt vmcnt(" #n ")" ::: "memory")
; #define PG8_WAIT_L(n) asm volatile("s_waitcnt lgkmcnt(" #n ")" ::: "memory")
; #define PG8_BAR __builtin_amdgcn_s_barrier()
; #define PG8_SCHED __builtin_amdgcn_sched_barrier(0)
; template <class Epi, class Sched>
; __device__ __forceinline__ void gemm_phase(LAS unsigned char* lds, const Gemm g, const Sched& S, const Epi& E) {
;     ...
;             PG8_BAR; PG8_WAIT_L(0); PG8_MMA(1, 0, At, B0); PG8_BAR; PG8_SCHED;
;             PG8_STAGE(PG8_SB(1, 1), b3 + hstep, voffB);
;             PG8_WAIT_V(6); PG8_BAR; PG8_MMA(1, 1, At, B1); PG8_BAR;
;     __device__ __forceinline__ void operator()(const AccT& acc, const Unit& u, int wr, int wc, int fr, int fq) const {
;         asm volatile("" : "+v"(fr), "+v"(fq));
;         const int rowt = u.pm * 256; const int b = rowt >> 11;
;         const bf16_t* res = res_b + (size_t)rowt * DM; bf16_t* out = hb + (size_t)rowt * DM;
;         const int col0 = u.pn * 256 + wc * 32 + 8 * fq;
;         f32x4 gv[2][2];
; #pragma unroll
;         for (int bj = 0; bj < 2; ++bj)
; #pragma unroll
;             for (int n = 0; n < 2; ++n) gv[bj][n] = *(const f32x4*)(gate + (size_t)b * NMOD + col0 + bj * 128 + n * 4) * gs;
;         u32x4 r[2][4][2];
; #pragma unroll
;         for (int ai = 0; ai < 2; ++ai)
; #pragma unroll
;             for (int m = 0; m < 4; ++m)
; #pragma unroll
;                 for (int bj = 0; bj < 2; ++bj) r[ai][m][bj] = *(const u32x4*)(res + (size_t)(wr * 64 + fr + ai * 128 + m * 16) * DM + col0 + bj * 128);
	s_waitcnt lgkmcnt(0)
	s_setprio 1
	s_waitcnt lgkmcnt(0)
	v_mfma_f32_16x16x32_bf16 v[60:63], v[128:131], v[144:147], v[60:63]
	v_mfma_f32_16x16x32_bf16 v[56:59], v[136:139], v[144:147], v[56:59]
	v_mfma_f32_16x16x32_bf16 v[44:47], v[128:131], v[152:155], v[44:47]
	v_mfma_f32_16x16x32_bf16 v[40:43], v[136:139], v[152:155], v[40:43]
	v_mfma_f32_16x16x32_bf16 v[28:31], v[128:131], v[160:163], v[28:31]
	v_mfma_f32_16x16x32_bf16 v[24:27], v[136:139], v[160:163], v[24:27]
	v_mfma_f32_16x16x32_bf16 v[12:15], v[128:131], v[168:171], v[12:15]
	v_mfma_f32_16x16x32_bf16 v[8:11], v[136:139], v[168:171], v[8:11]
	v_mfma_f32_16x16x32_bf16 v[60:63], v[132:135], v[148:151], v[60:63]
	v_mfma_f32_16x16x32_bf16 v[56:59], v[140:143], v[148:151], v[56:59]
	v_mfma_f32_16x16x32_bf16 v[44:47], v[132:135], v[156:159], v[44:47]
	v_mfma_f32_16x16x32_bf16 v[40:43], v[140:143], v[156:159], v[40:43]
	v_mfma_f32_16x16x32_bf16 v[28:31], v[132:135], v[164:167], v[28:31]
	v_mfma_f32_16x16x32_bf16 v[24:27], v[140:143], v[164:167], v[24:27]
	v_mfma_f32_16x16x32_bf16 v[12:15], v[132:135], v[172:175], v[12:15]
	v_mfma_f32_16x16x32_bf16 v[8:11], v[140:143], v[172:175], v[8:11]
	s_setprio 0
	s_barrier
	s_add_u32 s24, s28, 0x60080
	s_addc_u32 s25, s29, 0
	s_add_i32 s28, s30, s37
	s_mov_b32 m0, s28
	s_nop 0
	global_load_lds_dwordx4 v204, s[24:25]
	s_add_i32 m0, s28, 0x2000
	s_nop 0
	global_load_lds_dwordx4 v208, s[24:25]
	s_waitcnt vmcnt(10)
	s_barrier
	s_setprio 1
	v_mfma_f32_16x16x32_bf16 v[52:55], v[176:179], v[144:147], v[52:55]
	v_mfma_f32_16x16x32_bf16 v[48:51], v[184:187], v[144:147], v[48:51]
	v_mfma_f32_16x16x32_bf16 v[36:39], v[176:179], v[152:155], v[36:39]
	v_mfma_f32_16x16x32_bf16 v[32:35], v[184:187], v[152:155], v[32:35]
	v_mfma_f32_16x16x32_bf16 v[20:23], v[176:179], v[160:163], v[20:23]
	v_mfma_f32_16x16x32_bf16 v[16:19], v[184:187], v[160:163], v[16:19]
	v_mfma_f32_16x16x32_bf16 v[4:7], v[176:179], v[168:171], v[4:7]
	v_mfma_f32_16x16x32_bf16 v[0:3], v[184:187], v[168:171], v[0:3]
	v_mfma_f32_16x16x32_bf16 v[52:55], v[180:183], v[148:151], v[52:55]
	v_mfma_f32_16x16x32_bf16 v[48:51], v[188:191], v[148:151], v[48:51]
	v_mfma_f32_16x16x32_bf16 v[36:39], v[180:183], v[156:159], v[36:39]
	v_mfma_f32_16x16x32_bf16 v[32:35], v[188:191], v[156:159], v[32:35]
	v_mfma_f32_16x16x32_bf16 v[20:23], v[180:183], v[164:167], v[20:23]
	v_mfma_f32_16x16x32_bf16 v[16:19], v[188:191], v[164:167], v[16:19]
	v_mfma_f32_16x16x32_bf16 v[4:7], v[180:183], v[172:175], v[4:7]
	v_mfma_f32_16x16x32_bf16 v[0:3], v[188:191], v[172:175], v[0:3]
	s_setprio 0
	s_add_i32 s58, s58, 2
	s_add_u32 s56, s56, 0x100
	s_addc_u32 s57, s57, 0
	s_cmp_gt_u32 s58, 21
	s_mov_b64 s[24:25], s[26:27]
	s_cbranch_scc1 .Lconc_last_g10
	s_barrier
	s_branch .LBB0_902
.Lconc_last_g10:
	v_readfirstlane_b32 s27, v200
	s_nop 3
	s_cmp_gt_u32 s27, 0xff
	s_cbranch_scc1 .Lconc_epi1_g10
	s_barrier
	s_lshl_b32 s27, s55, 8
	v_mov_b32_e32 v146, v235
	v_mov_b32_e32 v128, v234
	s_lshl_b32 s24, s54, 8
	s_ashr_i32 s26, s54, 3
	s_or_b32 s27, s27, s46
	s_ashr_i32 s25, s24, 31
	v_lshl_add_u32 v144, v128, 3, s27
	s_mul_hi_i32 s27, s26, 0x9000
	s_mul_i32 s26, s26, 0x9000
	s_add_u32 s26, s43, s26
	s_addc_u32 s27, s44, s27
	v_ashrrev_i32_e32 v145, 31, v144
	s_lshl_b64 s[24:25], s[24:25], 11
	v_lshl_add_u64 v[132:133], v[144:145], 2, s[26:27]
	s_add_u32 s26, s62, s24
	v_add_u32_e32 v146, s45, v146
	s_addc_u32 s27, s63, s25
	v_lshlrev_b64 v[222:223], 1, v[144:145]
	v_ashrrev_i32_e32 v147, 31, v146
	v_lshl_add_u64 v[144:145], s[26:27], 0, v[222:223]
	v_lshlrev_b64 v[248:249], 11, v[146:147]
	v_lshl_add_u64 v[146:147], v[144:145], 0, v[248:249]
	global_load_dwordx4 v[136:139], v[132:133], off offset:16
	global_load_dwordx4 v[140:143], v[132:133], off
	global_load_dwordx4 v[128:131], v[132:133], off offset:528
	s_nop 0
	global_load_dwordx4 v[132:135], v[132:133], off offset:512
	s_nop 0
	global_load_dwordx4 v[240:243], v[146:147], off
	global_load_dwordx4 v[244:247], v[146:147], off offset:256
	v_lshl_add_u64 v[232:233], v[248:249], 0, s[10:11]
	v_lshl_add_u64 v[146:147], v[144:145], 0, v[232:233]
	global_load_dwordx4 v[196:199], v[146:147], off
	global_load_dwordx4 v[192:195], v[146:147], off offset:256
	v_lshl_add_u64 v[230:231], v[248:249], 0, s[12:13]
	v_lshl_add_u64 v[146:147], v[144:145], 0, v[230:231]
	global_load_dwordx4 v[188:191], v[146:147], off
	global_load_dwordx4 v[184:187], v[146:147], off offset:256
	v_lshl_add_u64 v[228:229], v[248:249], 0, s[14:15]
	v_lshl_add_u64 v[146:147], v[144:145], 0, v[228:229]
	global_load_dwordx4 v[180:183], v[146:147], off
	global_load_dwordx4 v[176:179], v[146:147], off offset:256
	v_lshl_add_u64 v[226:227], v[248:249], 0, s[16:17]
	v_lshl_add_u64 v[146:147], v[144:145], 0, v[226:227]
	global_load_dwordx4 v[172:175], v[146:147], off
	global_load_dwordx4 v[168:171], v[146:147], off offset:256
	v_lshl_add_u64 v[224:225], v[248:249], 0, s[18:19]
	v_lshl_add_u64 v[146:147], v[144:145], 0, v[224:225]
	global_load_dwordx4 v[164:167], v[146:147], off
	global_load_dwordx4 v[160:163], v[146:147], off offset:256
	v_lshl_add_u64 v[220:221], v[248:249], 0, s[20:21]
	v_lshl_add_u64 v[146:147], v[144:145], 0, v[220:221]
	global_load_dwordx4 v[156:159], v[146:147], off
	global_load_dwordx4 v[152:155], v[146:147], off offset:256
	v_lshl_add_u64 v[218:219], v[248:249], 0, s[22:23]
	v_lshl_add_u64 v[144:145], v[144:145], 0, v[218:219]
	global_load_dwordx4 v[148:151], v[144:145], off
	s_nop 0
	global_load_dwordx4 v[144:147], v[144:145], off offset:256
	s_add_u32 s24, s80, s24
	s_addc_u32 s25, s81, s25
	v_lshl_add_u64 v[222:223], s[24:25], 0, v[222:223]
	v_lshl_add_u64 v[248:249], v[222:223], 0, v[248:249]
	s_and_b64 vcc, exec, s[2:3]
	s_mov_b32 s55, s52
	s_mov_b32 s54, s53
	s_mov_b64 s[26:27], s[6:7]
	s_mov_b64 s[24:25], s[4:5]
	s_waitcnt vmcnt(0)
; __device__ __forceinline__ unsigned cvt_pk_bf16(float lo, float hi) { unsigned r; asm volatile("v_cvt_pk_bf16_f32 %0, %1, %2" : "=v"(r) : "v"(lo), "v"(hi)); return r; }
; __device__ __forceinline__ float bf_lo(unsigned u) { return __uint_as_float(u << 16); }
; __device__ __forceinline__ float bf_hi(unsigned u) { return __uint_as_float(u & 0xffff0000u); }
;     __device__ __forceinline__ void operator()(const AccT& acc, const Unit& u, int wr, int wc, int fr, int fq) const {
;     ...
; #pragma unroll
;         for (int ai = 0; ai < 2; ++ai)
; #pragma unroll
;             for (int m = 0; m < 4; ++m)
; #pragma unroll
;                 for (int bj = 0; bj < 2; ++bj) {
;                     const u32x4 q = r[ai][m][bj];
;                     const f32x4 r0 = {bf_lo(q.x), bf_hi(q.x), bf_lo(q.y), bf_hi(q.y)}, r1 = {bf_lo(q.z), bf_hi(q.z), bf_lo(q.w), bf_hi(q.w)};
;                     const f32x4 h0 = r0 + gv[bj][0] * acc[ai][bj][m][0], h1 = r1 + gv[bj][1] * acc[ai][bj][m][1];
;                     u32x4 w; w.x = cvt_pk_bf16(h0[0], h0[1]); w.y = cvt_pk_bf16(h0[2], h0[3]); w.z = cvt_pk_bf16(h1[0], h1[1]); w.w = cvt_pk_bf16(h1[2], h1[3]);
;                     *(u32x4*)(out + (size_t)(wr * 64 + fr + ai * 128 + m * 16) * DM + col0 + bj * 128) = w;
;                 }
	v_lshlrev_b32_e32 v250, 16, v240
	v_and_b32_e32 v251, 0xffff0000, v240
	v_lshlrev_b32_e32 v240, 16, v241
	v_and_b32_e32 v241, 0xffff0000, v241
	v_lshlrev_b32_e32 v252, 16, v242
	v_and_b32_e32 v253, 0xffff0000, v242
	v_lshlrev_b32_e32 v242, 16, v243
	v_and_b32_e32 v243, 0xffff0000, v243
	v_pk_fma_f32 v[126:127], v[126:127], v[142:143], v[240:241]
	v_pk_fma_f32 v[124:125], v[124:125], v[140:141], v[250:251]
	v_pk_fma_f32 v[240:241], v[122:123], v[138:139], v[242:243]
	v_pk_fma_f32 v[122:123], v[120:121], v[136:137], v[252:253]
	v_cvt_pk_bf16_f32 v120, v124, v125
	v_cvt_pk_bf16_f32 v121, v126, v127
	v_lshlrev_b32_e32 v124, 16, v246
	v_cvt_pk_bf16_f32 v122, v122, v123
	v_cvt_pk_bf16_f32 v123, v240, v241
	global_store_dwordx4 v[248:249], v[120:123], off
	v_and_b32_e32 v125, 0xffff0000, v246
	v_lshlrev_b32_e32 v126, 16, v247
	v_lshlrev_b32_e32 v120, 16, v244
	v_and_b32_e32 v121, 0xffff0000, v244
	v_and_b32_e32 v127, 0xffff0000, v247
	v_lshlrev_b32_e32 v122, 16, v245
	v_and_b32_e32 v123, 0xffff0000, v245
	v_pk_fma_f32 v[116:117], v[116:117], v[132:133], v[120:121]
	v_pk_fma_f32 v[120:121], v[114:115], v[130:131], v[126:127]
	v_pk_fma_f32 v[114:115], v[112:113], v[128:129], v[124:125]
	v_pk_fma_f32 v[118:119], v[118:119], v[134:135], v[122:123]
	v_cvt_pk_bf16_f32 v112, v116, v117
	v_lshlrev_b32_e32 v116, 16, v197
	v_cvt_pk_bf16_f32 v113, v118, v119
	v_cvt_pk_bf16_f32 v114, v114, v115
	v_cvt_pk_bf16_f32 v115, v120, v121
	global_store_dwordx4 v[248:249], v[112:115], off offset:256
	v_and_b32_e32 v117, 0xffff0000, v197
	v_lshlrev_b32_e32 v118, 16, v198
	v_lshlrev_b32_e32 v114, 16, v196
	v_and_b32_e32 v115, 0xffff0000, v196
	v_and_b32_e32 v119, 0xffff0000, v198
	v_lshlrev_b32_e32 v120, 16, v199
	v_and_b32_e32 v121, 0xffff0000, v199
	v_lshl_add_u64 v[112:113], v[222:223], 0, v[232:233]
	v_pk_fma_f32 v[110:111], v[110:111], v[142:143], v[116:117]
	v_pk_fma_f32 v[108:109], v[108:109], v[140:141], v[114:115]
	v_pk_fma_f32 v[114:115], v[106:107], v[138:139], v[120:121]
	v_pk_fma_f32 v[106:107], v[104:105], v[136:137], v[118:119]
	v_cvt_pk_bf16_f32 v104, v108, v109
	v_cvt_pk_bf16_f32 v105, v110, v111
	v_lshlrev_b32_e32 v108, 16, v194
	v_cvt_pk_bf16_f32 v106, v106, v107
	v_cvt_pk_bf16_f32 v107, v114, v115
	global_store_dwordx4 v[112:113], v[104:107], off
	v_and_b32_e32 v109, 0xffff0000, v194
	v_lshlrev_b32_e32 v110, 16, v195
	v_lshlrev_b32_e32 v104, 16, v192
	v_and_b32_e32 v105, 0xffff0000, v192
	v_and_b32_e32 v111, 0xffff0000, v195
	v_lshlrev_b32_e32 v106, 16, v193
	v_and_b32_e32 v107, 0xffff0000, v193
	v_pk_fma_f32 v[100:101], v[100:101], v[132:133], v[104:105]
	v_pk_fma_f32 v[104:105], v[98:99], v[130:131], v[110:111]
	v_pk_fma_f32 v[98:99], v[96:97], v[128:129], v[108:109]
	v_pk_fma_f32 v[102:103], v[102:103], v[134:135], v[106:107]
	v_cvt_pk_bf16_f32 v96, v100, v101
	v_lshlrev_b32_e32 v100, 16, v189
	v_cvt_pk_bf16_f32 v97, v102, v103
	v_cvt_pk_bf16_f32 v98, v98, v99
	v_cvt_pk_bf16_f32 v99, v104, v105
	global_store_dwordx4 v[112:113], v[96:99], off offset:256
	v_and_b32_e32 v101, 0xffff0000, v189
	v_lshlrev_b32_e32 v102, 16, v190
	v_lshlrev_b32_e32 v98, 16, v188
	v_and_b32_e32 v99, 0xffff0000, v188
	v_and_b32_e32 v103, 0xffff0000, v190
	v_lshlrev_b32_e32 v104, 16, v191
	v_and_b32_e32 v105, 0xffff0000, v191
	v_lshl_add_u64 v[96:97], v[222:223], 0, v[230:231]
	v_pk_fma_f32 v[94:95], v[94:95], v[142:143], v[100:101]
	v_pk_fma_f32 v[92:93], v[92:93], v[140:141], v[98:99]
	v_pk_fma_f32 v[98:99], v[90:91], v[138:139], v[104:105]
	v_pk_fma_f32 v[90:91], v[88:89], v[136:137], v[102:103]
	v_cvt_pk_bf16_f32 v88, v92, v93
	v_cvt_pk_bf16_f32 v89, v94, v95
	v_lshlrev_b32_e32 v92, 16, v186
	v_cvt_pk_bf16_f32 v90, v90, v91
	v_cvt_pk_bf16_f32 v91, v98, v99
	global_store_dwordx4 v[96:97], v[88:91], off
	v_and_b32_e32 v93, 0xffff0000, v186
	v_lshlrev_b32_e32 v94, 16, v187
	v_lshlrev_b32_e32 v88, 16, v184
	v_and_b32_e32 v89, 0xffff0000, v184
	v_and_b32_e32 v95, 0xffff0000, v187
	v_lshlrev_b32_e32 v90, 16, v185
	v_and_b32_e32 v91, 0xffff0000, v185
	v_pk_fma_f32 v[84:85], v[84:85], v[132:133], v[88:89]
	v_pk_fma_f32 v[88:89], v[82:83], v[130:131], v[94:95]
	v_pk_fma_f32 v[82:83], v[80:81], v[128:129], v[92:93]
	v_pk_fma_f32 v[86:87], v[86:87], v[134:135], v[90:91]
	v_cvt_pk_bf16_f32 v80, v84, v85
	v_lshlrev_b32_e32 v84, 16, v181
	v_cvt_pk_bf16_f32 v81, v86, v87
	v_cvt_pk_bf16_f32 v82, v82, v83
	v_cvt_pk_bf16_f32 v83, v88, v89
	global_store_dwordx4 v[96:97], v[80:83], off offset:256
	v_and_b32_e32 v85, 0xffff0000, v181
	v_lshlrev_b32_e32 v86, 16, v182
	v_lshlrev_b32_e32 v82, 16, v180
	v_and_b32_e32 v83, 0xffff0000, v180
	v_and_b32_e32 v87, 0xffff0000, v182
	v_lshlrev_b32_e32 v88, 16, v183
	v_and_b32_e32 v89, 0xffff0000, v183
	v_lshl_add_u64 v[80:81], v[222:223], 0, v[228:229]
	v_pk_fma_f32 v[78:79], v[78:79], v[142:143], v[84:85]
	v_pk_fma_f32 v[76:77], v[76:77], v[140:141], v[82:83]
	v_pk_fma_f32 v[82:83], v[74:75], v[138:139], v[88:89]
	v_pk_fma_f32 v[74:75], v[72:73], v[136:137], v[86:87]
	v_cvt_pk_bf16_f32 v72, v76, v77
	v_cvt_pk_bf16_f32 v73, v78, v79
	v_lshlrev_b32_e32 v76, 16, v178
	v_cvt_pk_bf16_f32 v74, v74, v75
	v_cvt_pk_bf16_f32 v75, v82, v83
	global_store_dwordx4 v[80:81], v[72:75], off
	v_and_b32_e32 v77, 0xffff0000, v178
	v_lshlrev_b32_e32 v78, 16, v179
	v_lshlrev_b32_e32 v72, 16, v176
	v_and_b32_e32 v73, 0xffff0000, v176
	v_and_b32_e32 v79, 0xffff0000, v179
	v_lshlrev_b32_e32 v74, 16, v177
	v_and_b32_e32 v75, 0xffff0000, v177
	v_pk_fma_f32 v[68:69], v[68:69], v[132:133], v[72:73]
	v_pk_fma_f32 v[72:73], v[66:67], v[130:131], v[78:79]
	v_pk_fma_f32 v[66:67], v[64:65], v[128:129], v[76:77]
	v_pk_fma_f32 v[70:71], v[70:71], v[134:135], v[74:75]
; __device__ __forceinline__ unsigned cvt_pk_bf16(float lo, float hi) { unsigned r; asm volatile("v_cvt_pk_bf16_f32 %0, %1, %2" : "=v"(r) : "v"(lo), "v"(hi)); return r; }
; __device__ __forceinline__ float bf_lo(unsigned u) { return __uint_as_float(u << 16); }
; __device__ __forceinline__ float bf_hi(unsigned u) { return __uint_as_float(u & 0xffff0000u); }
; template <class Epi, class Sched>
; __device__ __forceinline__ void gemm_phase(LAS unsigned char* lds, const Gemm g, const Sched& S, const Epi& E) {
;     ...
;         E(acc, cur, wr, wc, fr, fq);
;         if (!has_next) break;
;     __device__ __forceinline__ void operator()(const AccT& acc, const Unit& u, int wr, int wc, int fr, int fq) const {
;     ...
; #pragma unroll
;         for (int ai = 0; ai < 2; ++ai)
; #pragma unroll
;             for (int m = 0; m < 4; ++m)
; #pragma unroll
;                 for (int bj = 0; bj < 2; ++bj) {
;                     const u32x4 q = r[ai][m][bj];
;                     const f32x4 r0 = {bf_lo(q.x), bf_hi(q.x), bf_lo(q.y), bf_hi(q.y)}, r1 = {bf_lo(q.z), bf_hi(q.z), bf_lo(q.w), bf_hi(q.w)};
;                     const f32x4 h0 = r0 + gv[bj][0] * acc[ai][bj][m][0], h1 = r1 + gv[bj][1] * acc[ai][bj][m][1];
;                     u32x4 w; w.x = cvt_pk_bf16(h0[0], h0[1]); w.y = cvt_pk_bf16(h0[2], h0[3]); w.z = cvt_pk_bf16(h1[0], h1[1]); w.w = cvt_pk_bf16(h1[2], h1[3]);
;                     *(u32x4*)(out + (size_t)(wr * 64 + fr + ai * 128 + m * 16) * DM + col0 + bj * 128) = w;
;                 }
	v_cvt_pk_bf16_f32 v64, v68, v69
	v_lshlrev_b32_e32 v68, 16, v173
	v_cvt_pk_bf16_f32 v65, v70, v71
	v_cvt_pk_bf16_f32 v66, v66, v67
	v_cvt_pk_bf16_f32 v67, v72, v73
	global_store_dwordx4 v[80:81], v[64:67], off offset:256
	v_and_b32_e32 v69, 0xffff0000, v173
	v_lshlrev_b32_e32 v70, 16, v174
	v_lshlrev_b32_e32 v66, 16, v172
	v_and_b32_e32 v67, 0xffff0000, v172
	v_and_b32_e32 v71, 0xffff0000, v174
	v_lshlrev_b32_e32 v72, 16, v175
	v_and_b32_e32 v73, 0xffff0000, v175
	v_lshl_add_u64 v[64:65], v[222:223], 0, v[226:227]
	v_pk_fma_f32 v[62:63], v[62:63], v[142:143], v[68:69]
	v_pk_fma_f32 v[60:61], v[60:61], v[140:141], v[66:67]
	v_pk_fma_f32 v[66:67], v[58:59], v[138:139], v[72:73]
	v_pk_fma_f32 v[58:59], v[56:57], v[136:137], v[70:71]
	v_cvt_pk_bf16_f32 v56, v60, v61
	v_cvt_pk_bf16_f32 v57, v62, v63
	v_lshlrev_b32_e32 v60, 16, v170
	v_cvt_pk_bf16_f32 v58, v58, v59
	v_cvt_pk_bf16_f32 v59, v66, v67
	global_store_dwordx4 v[64:65], v[56:59], off
	v_and_b32_e32 v61, 0xffff0000, v170
	v_lshlrev_b32_e32 v62, 16, v171
	v_lshlrev_b32_e32 v56, 16, v168
	v_and_b32_e32 v57, 0xffff0000, v168
	v_and_b32_e32 v63, 0xffff0000, v171
	v_lshlrev_b32_e32 v58, 16, v169
	v_and_b32_e32 v59, 0xffff0000, v169
	v_pk_fma_f32 v[52:53], v[52:53], v[132:133], v[56:57]
	v_pk_fma_f32 v[56:57], v[50:51], v[130:131], v[62:63]
	v_pk_fma_f32 v[50:51], v[48:49], v[128:129], v[60:61]
	v_pk_fma_f32 v[54:55], v[54:55], v[134:135], v[58:59]
	v_cvt_pk_bf16_f32 v48, v52, v53
	v_lshlrev_b32_e32 v52, 16, v165
	v_cvt_pk_bf16_f32 v49, v54, v55
	v_cvt_pk_bf16_f32 v50, v50, v51
	v_cvt_pk_bf16_f32 v51, v56, v57
	global_store_dwordx4 v[64:65], v[48:51], off offset:256
	v_and_b32_e32 v53, 0xffff0000, v165
	v_lshlrev_b32_e32 v54, 16, v166
	v_lshlrev_b32_e32 v50, 16, v164
	v_and_b32_e32 v51, 0xffff0000, v164
	v_and_b32_e32 v55, 0xffff0000, v166
	v_lshlrev_b32_e32 v56, 16, v167
	v_and_b32_e32 v57, 0xffff0000, v167
	v_lshl_add_u64 v[48:49], v[222:223], 0, v[224:225]
	v_pk_fma_f32 v[46:47], v[46:47], v[142:143], v[52:53]
	v_pk_fma_f32 v[44:45], v[44:45], v[140:141], v[50:51]
	v_pk_fma_f32 v[50:51], v[42:43], v[138:139], v[56:57]
	v_pk_fma_f32 v[42:43], v[40:41], v[136:137], v[54:55]
	v_cvt_pk_bf16_f32 v40, v44, v45
	v_cvt_pk_bf16_f32 v41, v46, v47
	v_lshlrev_b32_e32 v44, 16, v162
	v_cvt_pk_bf16_f32 v42, v42, v43
	v_cvt_pk_bf16_f32 v43, v50, v51
	global_store_dwordx4 v[48:49], v[40:43], off
	v_and_b32_e32 v45, 0xffff0000, v162
	v_lshlrev_b32_e32 v46, 16, v163
	v_lshlrev_b32_e32 v40, 16, v160
	v_and_b32_e32 v41, 0xffff0000, v160
	v_and_b32_e32 v47, 0xffff0000, v163
	v_lshlrev_b32_e32 v42, 16, v161
	v_and_b32_e32 v43, 0xffff0000, v161
	v_pk_fma_f32 v[36:37], v[36:37], v[132:133], v[40:41]
	v_pk_fma_f32 v[40:41], v[34:35], v[130:131], v[46:47]
	v_pk_fma_f32 v[34:35], v[32:33], v[128:129], v[44:45]
	v_pk_fma_f32 v[38:39], v[38:39], v[134:135], v[42:43]
	v_cvt_pk_bf16_f32 v32, v36, v37
	v_lshlrev_b32_e32 v36, 16, v157
	v_cvt_pk_bf16_f32 v33, v38, v39
	v_cvt_pk_bf16_f32 v34, v34, v35
	v_cvt_pk_bf16_f32 v35, v40, v41
	global_store_dwordx4 v[48:49], v[32:35], off offset:256
	v_and_b32_e32 v37, 0xffff0000, v157
	v_lshlrev_b32_e32 v38, 16, v158
	v_lshlrev_b32_e32 v34, 16, v156
	v_and_b32_e32 v35, 0xffff0000, v156
	v_and_b32_e32 v39, 0xffff0000, v158
	v_lshlrev_b32_e32 v40, 16, v159
	v_and_b32_e32 v41, 0xffff0000, v159
	v_lshl_add_u64 v[32:33], v[222:223], 0, v[220:221]
	v_pk_fma_f32 v[30:31], v[30:31], v[142:143], v[36:37]
	v_pk_fma_f32 v[28:29], v[28:29], v[140:141], v[34:35]
	v_pk_fma_f32 v[34:35], v[26:27], v[138:139], v[40:41]
	v_pk_fma_f32 v[26:27], v[24:25], v[136:137], v[38:39]
	v_cvt_pk_bf16_f32 v24, v28, v29
	v_cvt_pk_bf16_f32 v25, v30, v31
	v_lshlrev_b32_e32 v28, 16, v154
	v_cvt_pk_bf16_f32 v26, v26, v27
	v_cvt_pk_bf16_f32 v27, v34, v35
	global_store_dwordx4 v[32:33], v[24:27], off
	v_and_b32_e32 v29, 0xffff0000, v154
	v_lshlrev_b32_e32 v30, 16, v155
	v_lshlrev_b32_e32 v24, 16, v152
	v_and_b32_e32 v25, 0xffff0000, v152
	v_and_b32_e32 v31, 0xffff0000, v155
	v_lshlrev_b32_e32 v26, 16, v153
	v_and_b32_e32 v27, 0xffff0000, v153
	v_pk_fma_f32 v[20:21], v[20:21], v[132:133], v[24:25]
	v_pk_fma_f32 v[24:25], v[18:19], v[130:131], v[30:31]
	v_pk_fma_f32 v[18:19], v[16:17], v[128:129], v[28:29]
	v_pk_fma_f32 v[22:23], v[22:23], v[134:135], v[26:27]
	v_cvt_pk_bf16_f32 v16, v20, v21
	v_lshlrev_b32_e32 v20, 16, v149
	v_cvt_pk_bf16_f32 v17, v22, v23
	v_cvt_pk_bf16_f32 v18, v18, v19
	v_cvt_pk_bf16_f32 v19, v24, v25
	global_store_dwordx4 v[32:33], v[16:19], off offset:256
	v_and_b32_e32 v21, 0xffff0000, v149
	v_lshlrev_b32_e32 v22, 16, v150
	v_lshlrev_b32_e32 v18, 16, v148
	v_and_b32_e32 v19, 0xffff0000, v148
	v_and_b32_e32 v23, 0xffff0000, v150
	v_lshlrev_b32_e32 v24, 16, v151
	v_and_b32_e32 v25, 0xffff0000, v151
	v_lshl_add_u64 v[16:17], v[222:223], 0, v[218:219]
	v_pk_fma_f32 v[14:15], v[14:15], v[142:143], v[20:21]
	v_pk_fma_f32 v[12:13], v[12:13], v[140:141], v[18:19]
	v_pk_fma_f32 v[18:19], v[10:11], v[138:139], v[24:25]
	v_pk_fma_f32 v[10:11], v[8:9], v[136:137], v[22:23]
	v_cvt_pk_bf16_f32 v8, v12, v13
	v_cvt_pk_bf16_f32 v9, v14, v15
	v_lshlrev_b32_e32 v12, 16, v146
	v_cvt_pk_bf16_f32 v10, v10, v11
	v_cvt_pk_bf16_f32 v11, v18, v19
	global_store_dwordx4 v[16:17], v[8:11], off
	v_and_b32_e32 v13, 0xffff0000, v146
	v_lshlrev_b32_e32 v14, 16, v147
	v_lshlrev_b32_e32 v8, 16, v144
	v_and_b32_e32 v9, 0xffff0000, v144
	v_and_b32_e32 v15, 0xffff0000, v147
	v_lshlrev_b32_e32 v10, 16, v145
	v_and_b32_e32 v11, 0xffff0000, v145
	v_pk_fma_f32 v[4:5], v[4:5], v[132:133], v[8:9]
	v_pk_fma_f32 v[8:9], v[2:3], v[130:131], v[14:15]
	v_pk_fma_f32 v[2:3], v[0:1], v[128:129], v[12:13]
	v_pk_fma_f32 v[6:7], v[6:7], v[134:135], v[10:11]
	v_cvt_pk_bf16_f32 v0, v4, v5
	s_nop 0
	v_cvt_pk_bf16_f32 v1, v6, v7
	v_cvt_pk_bf16_f32 v2, v2, v3
	v_cvt_pk_bf16_f32 v3, v8, v9
	global_store_dwordx4 v[16:17], v[0:3], off offset:256
	s_cbranch_vccz .LBB0_891
	s_branch .Lconc_end_g10
; __device__ __forceinline__ unsigned cvt_pk_bf16(float lo, float hi) { unsigned r; asm volatile("v_cvt_pk_bf16_f32 %0, %1, %2" : "=v"(r) : "v"(lo), "v"(hi)); return r; }
; __device__ __forceinline__ float bf_lo(unsigned u) { return __uint_as_float(u << 16); }
; __device__ __forceinline__ float bf_hi(unsigned u) { return __uint_as_float(u & 0xffff0000u); }
;     __device__ __forceinline__ void operator()(const AccT& acc, const Unit& u, int wr, int wc, int fr, int fq) const {
;         asm volatile("" : "+v"(fr), "+v"(fq));
;         const int rowt = u.pm * 256; const int b = rowt >> 11;
;         const bf16_t* res = res_b + (size_t)rowt * DM; bf16_t* out = hb + (size_t)rowt * DM;
;         const int col0 = u.pn * 256 + wc * 32 + 8 * fq;
;         f32x4 gv[2][2];
; #pragma unroll
;         for (int bj = 0; bj < 2; ++bj)
; #pragma unroll
;             for (int n = 0; n < 2; ++n) gv[bj][n] = *(const f32x4*)(gate + (size_t)b * NMOD + col0 + bj * 128 + n * 4) * gs;
;         u32x4 r[2][4][2];
; #pragma unroll
;         for (int ai = 0; ai < 2; ++ai)
; #pragma unroll
;             for (int m = 0; m < 4; ++m)
; #pragma unroll
;                 for (int bj = 0; bj < 2; ++bj) r[ai][m][bj] = *(const u32x4*)(res + (size_t)(wr * 64 + fr + ai * 128 + m * 16) * DM + col0 + bj * 128);
; #pragma unroll
;         for (int ai = 0; ai < 2; ++ai)
; #pragma unroll
;             for (int m = 0; m < 4; ++m)
; #pragma unroll
;                 for (int bj = 0; bj < 2; ++bj) {
;                     const u32x4 q = r[ai][m][bj];
;                     const f32x4 r0 = {bf_lo(q.x), bf_hi(q.x), bf_lo(q.y), bf_hi(q.y)}, r1 = {bf_lo(q.z), bf_hi(q.z), bf_lo(q.w), bf_hi(q.w)};
;                     const f32x4 h0 = r0 + gv[bj][0] * acc[ai][bj][m][0], h1 = r1 + gv[bj][1] * acc[ai][bj][m][1];
;                     u32x4 w; w.x = cvt_pk_bf16(h0[0], h0[1]); w.y = cvt_pk_bf16(h0[2], h0[3]); w.z = cvt_pk_bf16(h1[0], h1[1]); w.w = cvt_pk_bf16(h1[2], h1[3]);
;                     *(u32x4*)(out + (size_t)(wr * 64 + fr + ai * 128 + m * 16) * DM + col0 + bj * 128) = w;
;                 }
.Lconc_epi1_g10:
	s_lshl_b32 s27, s55, 8
	v_mov_b32_e32 v146, v235
	v_mov_b32_e32 v128, v234
	s_lshl_b32 s24, s54, 8
	s_ashr_i32 s26, s54, 3
	s_or_b32 s27, s27, s46
	s_ashr_i32 s25, s24, 31
	v_lshl_add_u32 v144, v128, 3, s27
	s_mul_hi_i32 s27, s26, 0x9000
	s_mul_i32 s26, s26, 0x9000
	s_add_u32 s26, s43, s26
	s_addc_u32 s27, s44, s27
	v_ashrrev_i32_e32 v145, 31, v144
	s_lshl_b64 s[24:25], s[24:25], 11
	v_lshl_add_u64 v[132:133], v[144:145], 2, s[26:27]
	s_add_u32 s26, s62, s24
	v_add_u32_e32 v146, s45, v146
	s_addc_u32 s27, s63, s25
	v_lshlrev_b64 v[222:223], 1, v[144:145]
	v_ashrrev_i32_e32 v147, 31, v146
	v_lshl_add_u64 v[144:145], s[26:27], 0, v[222:223]
	v_lshlrev_b64 v[248:249], 11, v[146:147]
	v_lshl_add_u64 v[146:147], v[144:145], 0, v[248:249]
	global_load_dwordx4 v[136:139], v[132:133], off offset:16
	global_load_dwordx4 v[140:143], v[132:133], off
	global_load_dwordx4 v[128:131], v[132:133], off offset:528
	s_nop 0
	global_load_dwordx4 v[132:135], v[132:133], off offset:512
	s_nop 0
	global_load_dwordx4 v[240:243], v[146:147], off
	global_load_dwordx4 v[244:247], v[146:147], off offset:256
	v_lshl_add_u64 v[232:233], v[248:249], 0, s[10:11]
	v_lshl_add_u64 v[146:147], v[144:145], 0, v[232:233]
	global_load_dwordx4 v[196:199], v[146:147], off
	global_load_dwordx4 v[192:195], v[146:147], off offset:256
	v_lshl_add_u64 v[230:231], v[248:249], 0, s[12:13]
	v_lshl_add_u64 v[146:147], v[144:145], 0, v[230:231]
	global_load_dwordx4 v[188:191], v[146:147], off
	global_load_dwordx4 v[184:187], v[146:147], off offset:256
	v_lshl_add_u64 v[228:229], v[248:249], 0, s[14:15]
	v_lshl_add_u64 v[146:147], v[144:145], 0, v[228:229]
	global_load_dwordx4 v[180:183], v[146:147], off
	global_load_dwordx4 v[176:179], v[146:147], off offset:256
	v_lshl_add_u64 v[226:227], v[248:249], 0, s[16:17]
	v_lshl_add_u64 v[146:147], v[144:145], 0, v[226:227]
	global_load_dwordx4 v[172:175], v[146:147], off
	global_load_dwordx4 v[168:171], v[146:147], off offset:256
	v_lshl_add_u64 v[224:225], v[248:249], 0, s[18:19]
	v_lshl_add_u64 v[146:147], v[144:145], 0, v[224:225]
	global_load_dwordx4 v[164:167], v[146:147], off
	global_load_dwordx4 v[160:163], v[146:147], off offset:256
	v_lshl_add_u64 v[220:221], v[248:249], 0, s[20:21]
	v_lshl_add_u64 v[146:147], v[144:145], 0, v[220:221]
	global_load_dwordx4 v[156:159], v[146:147], off
	global_load_dwordx4 v[152:155], v[146:147], off offset:256
	v_lshl_add_u64 v[218:219], v[248:249], 0, s[22:23]
	v_lshl_add_u64 v[144:145], v[144:145], 0, v[218:219]
	global_load_dwordx4 v[148:151], v[144:145], off
	s_nop 0
	global_load_dwordx4 v[144:147], v[144:145], off offset:256
	s_add_u32 s24, s80, s24
	s_addc_u32 s25, s81, s25
	v_lshl_add_u64 v[222:223], s[24:25], 0, v[222:223]
	v_lshl_add_u64 v[248:249], v[222:223], 0, v[248:249]
	s_and_b64 vcc, exec, s[2:3]
	s_mov_b32 s55, s52
	s_mov_b32 s54, s53
	s_mov_b64 s[26:27], s[6:7]
	s_mov_b64 s[24:25], s[4:5]
	s_waitcnt vmcnt(0)
	v_lshlrev_b32_e32 v250, 16, v240
	v_and_b32_e32 v251, 0xffff0000, v240
	v_lshlrev_b32_e32 v240, 16, v241
	v_and_b32_e32 v241, 0xffff0000, v241
	v_lshlrev_b32_e32 v252, 16, v242
	v_and_b32_e32 v253, 0xffff0000, v242
	v_lshlrev_b32_e32 v242, 16, v243
	v_and_b32_e32 v243, 0xffff0000, v243
	v_pk_fma_f32 v[126:127], v[126:127], v[142:143], v[240:241]
	v_pk_fma_f32 v[124:125], v[124:125], v[140:141], v[250:251]
	v_pk_fma_f32 v[240:241], v[122:123], v[138:139], v[242:243]
	v_pk_fma_f32 v[122:123], v[120:121], v[136:137], v[252:253]
	v_cvt_pk_bf16_f32 v120, v124, v125
	v_cvt_pk_bf16_f32 v121, v126, v127
	v_lshlrev_b32_e32 v124, 16, v246
	v_cvt_pk_bf16_f32 v122, v122, v123
	v_cvt_pk_bf16_f32 v123, v240, v241
	global_store_dwordx4 v[248:249], v[120:123], off
	v_and_b32_e32 v125, 0xffff0000, v246
	v_lshlrev_b32_e32 v126, 16, v247
	v_lshlrev_b32_e32 v120, 16, v244
	v_and_b32_e32 v121, 0xffff0000, v244
	v_and_b32_e32 v127, 0xffff0000, v247
	v_lshlrev_b32_e32 v122, 16, v245
	v_and_b32_e32 v123, 0xffff0000, v245
	v_pk_fma_f32 v[116:117], v[116:117], v[132:133], v[120:121]
	v_pk_fma_f32 v[120:121], v[114:115], v[130:131], v[126:127]
	v_pk_fma_f32 v[114:115], v[112:113], v[128:129], v[124:125]
	v_pk_fma_f32 v[118:119], v[118:119], v[134:135], v[122:123]
	v_cvt_pk_bf16_f32 v112, v116, v117
	v_lshlrev_b32_e32 v116, 16, v197
	v_cvt_pk_bf16_f32 v113, v118, v119
	v_cvt_pk_bf16_f32 v114, v114, v115
	v_cvt_pk_bf16_f32 v115, v120, v121
	global_store_dwordx4 v[248:249], v[112:115], off offset:256
	v_and_b32_e32 v117, 0xffff0000, v197
	v_lshlrev_b32_e32 v118, 16, v198
	v_lshlrev_b32_e32 v114, 16, v196
	v_and_b32_e32 v115, 0xffff0000, v196
	v_and_b32_e32 v119, 0xffff0000, v198
	v_lshlrev_b32_e32 v120, 16, v199
	v_and_b32_e32 v121, 0xffff0000, v199
	v_lshl_add_u64 v[112:113], v[222:223], 0, v[232:233]
	v_pk_fma_f32 v[110:111], v[110:111], v[142:143], v[116:117]
	v_pk_fma_f32 v[108:109], v[108:109], v[140:141], v[114:115]
	v_pk_fma_f32 v[114:115], v[106:107], v[138:139], v[120:121]
	v_pk_fma_f32 v[106:107], v[104:105], v[136:137], v[118:119]
	v_cvt_pk_bf16_f32 v104, v108, v109
	v_cvt_pk_bf16_f32 v105, v110, v111
	v_lshlrev_b32_e32 v108, 16, v194
	v_cvt_pk_bf16_f32 v106, v106, v107
	v_cvt_pk_bf16_f32 v107, v114, v115
	global_store_dwordx4 v[112:113], v[104:107], off
	v_and_b32_e32 v109, 0xffff0000, v194
	v_lshlrev_b32_e32 v110, 16, v195
	v_lshlrev_b32_e32 v104, 16, v192
	v_and_b32_e32 v105, 0xffff0000, v192
	v_and_b32_e32 v111, 0xffff0000, v195
	v_lshlrev_b32_e32 v106, 16, v193
	v_and_b32_e32 v107, 0xffff0000, v193
	v_pk_fma_f32 v[100:101], v[100:101], v[132:133], v[104:105]
	v_pk_fma_f32 v[104:105], v[98:99], v[130:131], v[110:111]
	v_pk_fma_f32 v[98:99], v[96:97], v[128:129], v[108:109]
; __device__ __forceinline__ unsigned cvt_pk_bf16(float lo, float hi) { unsigned r; asm volatile("v_cvt_pk_bf16_f32 %0, %1, %2" : "=v"(r) : "v"(lo), "v"(hi)); return r; }
; __device__ __forceinline__ float bf_lo(unsigned u) { return __uint_as_float(u << 16); }
; __device__ __forceinline__ float bf_hi(unsigned u) { return __uint_as_float(u & 0xffff0000u); }
;     __device__ __forceinline__ void operator()(const AccT& acc, const Unit& u, int wr, int wc, int fr, int fq) const {
;     ...
; #pragma unroll
;         for (int ai = 0; ai < 2; ++ai)
; #pragma unroll
;             for (int m = 0; m < 4; ++m)
; #pragma unroll
;                 for (int bj = 0; bj < 2; ++bj) {
;                     const u32x4 q = r[ai][m][bj];
;                     const f32x4 r0 = {bf_lo(q.x), bf_hi(q.x), bf_lo(q.y), bf_hi(q.y)}, r1 = {bf_lo(q.z), bf_hi(q.z), bf_lo(q.w), bf_hi(q.w)};
;                     const f32x4 h0 = r0 + gv[bj][0] * acc[ai][bj][m][0], h1 = r1 + gv[bj][1] * acc[ai][bj][m][1];
;                     u32x4 w; w.x = cvt_pk_bf16(h0[0], h0[1]); w.y = cvt_pk_bf16(h0[2], h0[3]); w.z = cvt_pk_bf16(h1[0], h1[1]); w.w = cvt_pk_bf16(h1[2], h1[3]);
;                     *(u32x4*)(out + (size_t)(wr * 64 + fr + ai * 128 + m * 16) * DM + col0 + bj * 128) = w;
;                 }
	v_pk_fma_f32 v[102:103], v[102:103], v[134:135], v[106:107]
	v_cvt_pk_bf16_f32 v96, v100, v101
	v_lshlrev_b32_e32 v100, 16, v189
	v_cvt_pk_bf16_f32 v97, v102, v103
	v_cvt_pk_bf16_f32 v98, v98, v99
	v_cvt_pk_bf16_f32 v99, v104, v105
	global_store_dwordx4 v[112:113], v[96:99], off offset:256
	v_and_b32_e32 v101, 0xffff0000, v189
	v_lshlrev_b32_e32 v102, 16, v190
	v_lshlrev_b32_e32 v98, 16, v188
	v_and_b32_e32 v99, 0xffff0000, v188
	v_and_b32_e32 v103, 0xffff0000, v190
	v_lshlrev_b32_e32 v104, 16, v191
	v_and_b32_e32 v105, 0xffff0000, v191
	v_lshl_add_u64 v[96:97], v[222:223], 0, v[230:231]
	v_pk_fma_f32 v[94:95], v[94:95], v[142:143], v[100:101]
	v_pk_fma_f32 v[92:93], v[92:93], v[140:141], v[98:99]
	v_pk_fma_f32 v[98:99], v[90:91], v[138:139], v[104:105]
	v_pk_fma_f32 v[90:91], v[88:89], v[136:137], v[102:103]
	v_cvt_pk_bf16_f32 v88, v92, v93
	v_cvt_pk_bf16_f32 v89, v94, v95
	v_lshlrev_b32_e32 v92, 16, v186
	v_cvt_pk_bf16_f32 v90, v90, v91
	v_cvt_pk_bf16_f32 v91, v98, v99
	global_store_dwordx4 v[96:97], v[88:91], off
	v_and_b32_e32 v93, 0xffff0000, v186
	v_lshlrev_b32_e32 v94, 16, v187
	v_lshlrev_b32_e32 v88, 16, v184
	v_and_b32_e32 v89, 0xffff0000, v184
	v_and_b32_e32 v95, 0xffff0000, v187
	v_lshlrev_b32_e32 v90, 16, v185
	v_and_b32_e32 v91, 0xffff0000, v185
	v_pk_fma_f32 v[84:85], v[84:85], v[132:133], v[88:89]
	v_pk_fma_f32 v[88:89], v[82:83], v[130:131], v[94:95]
	v_pk_fma_f32 v[82:83], v[80:81], v[128:129], v[92:93]
	v_pk_fma_f32 v[86:87], v[86:87], v[134:135], v[90:91]
	v_cvt_pk_bf16_f32 v80, v84, v85
	v_lshlrev_b32_e32 v84, 16, v181
	v_cvt_pk_bf16_f32 v81, v86, v87
	v_cvt_pk_bf16_f32 v82, v82, v83
	v_cvt_pk_bf16_f32 v83, v88, v89
	global_store_dwordx4 v[96:97], v[80:83], off offset:256
	v_and_b32_e32 v85, 0xffff0000, v181
	v_lshlrev_b32_e32 v86, 16, v182
	v_lshlrev_b32_e32 v82, 16, v180
	v_and_b32_e32 v83, 0xffff0000, v180
	v_and_b32_e32 v87, 0xffff0000, v182
	v_lshlrev_b32_e32 v88, 16, v183
	v_and_b32_e32 v89, 0xffff0000, v183
	v_lshl_add_u64 v[80:81], v[222:223], 0, v[228:229]
	v_pk_fma_f32 v[78:79], v[78:79], v[142:143], v[84:85]
	v_pk_fma_f32 v[76:77], v[76:77], v[140:141], v[82:83]
	v_pk_fma_f32 v[82:83], v[74:75], v[138:139], v[88:89]
	v_pk_fma_f32 v[74:75], v[72:73], v[136:137], v[86:87]
	v_cvt_pk_bf16_f32 v72, v76, v77
	v_cvt_pk_bf16_f32 v73, v78, v79
	v_lshlrev_b32_e32 v76, 16, v178
	v_cvt_pk_bf16_f32 v74, v74, v75
	v_cvt_pk_bf16_f32 v75, v82, v83
	global_store_dwordx4 v[80:81], v[72:75], off
	v_and_b32_e32 v77, 0xffff0000, v178
	v_lshlrev_b32_e32 v78, 16, v179
	v_lshlrev_b32_e32 v72, 16, v176
	v_and_b32_e32 v73, 0xffff0000, v176
	v_and_b32_e32 v79, 0xffff0000, v179
	v_lshlrev_b32_e32 v74, 16, v177
	v_and_b32_e32 v75, 0xffff0000, v177
	v_pk_fma_f32 v[68:69], v[68:69], v[132:133], v[72:73]
	v_pk_fma_f32 v[72:73], v[66:67], v[130:131], v[78:79]
	v_pk_fma_f32 v[66:67], v[64:65], v[128:129], v[76:77]
	v_pk_fma_f32 v[70:71], v[70:71], v[134:135], v[74:75]
	v_cvt_pk_bf16_f32 v64, v68, v69
	v_lshlrev_b32_e32 v68, 16, v173
	v_cvt_pk_bf16_f32 v65, v70, v71
	v_cvt_pk_bf16_f32 v66, v66, v67
	v_cvt_pk_bf16_f32 v67, v72, v73
	global_store_dwordx4 v[80:81], v[64:67], off offset:256
	v_and_b32_e32 v69, 0xffff0000, v173
	v_lshlrev_b32_e32 v70, 16, v174
	v_lshlrev_b32_e32 v66, 16, v172
	v_and_b32_e32 v67, 0xffff0000, v172
	v_and_b32_e32 v71, 0xffff0000, v174
	v_lshlrev_b32_e32 v72, 16, v175
	v_and_b32_e32 v73, 0xffff0000, v175
	v_lshl_add_u64 v[64:65], v[222:223], 0, v[226:227]
	v_pk_fma_f32 v[62:63], v[62:63], v[142:143], v[68:69]
	v_pk_fma_f32 v[60:61], v[60:61], v[140:141], v[66:67]
	v_pk_fma_f32 v[66:67], v[58:59], v[138:139], v[72:73]
	v_pk_fma_f32 v[58:59], v[56:57], v[136:137], v[70:71]
	v_cvt_pk_bf16_f32 v56, v60, v61
	v_cvt_pk_bf16_f32 v57, v62, v63
	v_lshlrev_b32_e32 v60, 16, v170
	v_cvt_pk_bf16_f32 v58, v58, v59
	v_cvt_pk_bf16_f32 v59, v66, v67
	global_store_dwordx4 v[64:65], v[56:59], off
	v_and_b32_e32 v61, 0xffff0000, v170
	v_lshlrev_b32_e32 v62, 16, v171
	v_lshlrev_b32_e32 v56, 16, v168
	v_and_b32_e32 v57, 0xffff0000, v168
	v_and_b32_e32 v63, 0xffff0000, v171
	v_lshlrev_b32_e32 v58, 16, v169
	v_and_b32_e32 v59, 0xffff0000, v169
	v_pk_fma_f32 v[52:53], v[52:53], v[132:133], v[56:57]
	v_pk_fma_f32 v[56:57], v[50:51], v[130:131], v[62:63]
	v_pk_fma_f32 v[50:51], v[48:49], v[128:129], v[60:61]
	v_pk_fma_f32 v[54:55], v[54:55], v[134:135], v[58:59]
	v_cvt_pk_bf16_f32 v48, v52, v53
	v_lshlrev_b32_e32 v52, 16, v165
; __device__ __forceinline__ unsigned cvt_pk_bf16(float lo, float hi) { unsigned r; asm volatile("v_cvt_pk_bf16_f32 %0, %1, %2" : "=v"(r) : "v"(lo), "v"(hi)); return r; }
; __device__ __forceinline__ float bf_lo(unsigned u) { return __uint_as_float(u << 16); }
; __device__ __forceinline__ float bf_hi(unsigned u) { return __uint_as_float(u & 0xffff0000u); }
;     __device__ __forceinline__ void operator()(const AccT& acc, const Unit& u, int wr, int wc, int fr, int fq) const {
;     ...
; #pragma unroll
;         for (int ai = 0; ai < 2; ++ai)
; #pragma unroll
;             for (int m = 0; m < 4; ++m)
; #pragma unroll
;                 for (int bj = 0; bj < 2; ++bj) {
;                     const u32x4 q = r[ai][m][bj];
;                     const f32x4 r0 = {bf_lo(q.x), bf_hi(q.x), bf_lo(q.y), bf_hi(q.y)}, r1 = {bf_lo(q.z), bf_hi(q.z), bf_lo(q.w), bf_hi(q.w)};
;                     const f32x4 h0 = r0 + gv[bj][0] * acc[ai][bj][m][0], h1 = r1 + gv[bj][1] * acc[ai][bj][m][1];
;                     u32x4 w; w.x = cvt_pk_bf16(h0[0], h0[1]); w.y = cvt_pk_bf16(h0[2], h0[3]); w.z = cvt_pk_bf16(h1[0], h1[1]); w.w = cvt_pk_bf16(h1[2], h1[3]);
;                     *(u32x4*)(out + (size_t)(wr * 64 + fr + ai * 128 + m * 16) * DM + col0 + bj * 128) = w;
;                 }
	v_cvt_pk_bf16_f32 v49, v54, v55
	v_cvt_pk_bf16_f32 v50, v50, v51
	v_cvt_pk_bf16_f32 v51, v56, v57
	global_store_dwordx4 v[64:65], v[48:51], off offset:256
	v_and_b32_e32 v53, 0xffff0000, v165
	v_lshlrev_b32_e32 v54, 16, v166
	v_lshlrev_b32_e32 v50, 16, v164
	v_and_b32_e32 v51, 0xffff0000, v164
	v_and_b32_e32 v55, 0xffff0000, v166
	v_lshlrev_b32_e32 v56, 16, v167
	v_and_b32_e32 v57, 0xffff0000, v167
	v_lshl_add_u64 v[48:49], v[222:223], 0, v[224:225]
	v_pk_fma_f32 v[46:47], v[46:47], v[142:143], v[52:53]
	v_pk_fma_f32 v[44:45], v[44:45], v[140:141], v[50:51]
	v_pk_fma_f32 v[50:51], v[42:43], v[138:139], v[56:57]
	v_pk_fma_f32 v[42:43], v[40:41], v[136:137], v[54:55]
	v_cvt_pk_bf16_f32 v40, v44, v45
	v_cvt_pk_bf16_f32 v41, v46, v47
	v_lshlrev_b32_e32 v44, 16, v162
	v_cvt_pk_bf16_f32 v42, v42, v43
	v_cvt_pk_bf16_f32 v43, v50, v51
	global_store_dwordx4 v[48:49], v[40:43], off
	v_and_b32_e32 v45, 0xffff0000, v162
	v_lshlrev_b32_e32 v46, 16, v163
	v_lshlrev_b32_e32 v40, 16, v160
	v_and_b32_e32 v41, 0xffff0000, v160
	v_and_b32_e32 v47, 0xffff0000, v163
	v_lshlrev_b32_e32 v42, 16, v161
	v_and_b32_e32 v43, 0xffff0000, v161
	v_pk_fma_f32 v[36:37], v[36:37], v[132:133], v[40:41]
	v_pk_fma_f32 v[40:41], v[34:35], v[130:131], v[46:47]
	v_pk_fma_f32 v[34:35], v[32:33], v[128:129], v[44:45]
	v_pk_fma_f32 v[38:39], v[38:39], v[134:135], v[42:43]
	v_cvt_pk_bf16_f32 v32, v36, v37
	v_lshlrev_b32_e32 v36, 16, v157
	v_cvt_pk_bf16_f32 v33, v38, v39
	v_cvt_pk_bf16_f32 v34, v34, v35
	v_cvt_pk_bf16_f32 v35, v40, v41
	global_store_dwordx4 v[48:49], v[32:35], off offset:256
	v_and_b32_e32 v37, 0xffff0000, v157
	v_lshlrev_b32_e32 v38, 16, v158
	v_lshlrev_b32_e32 v34, 16, v156
	v_and_b32_e32 v35, 0xffff0000, v156
	v_and_b32_e32 v39, 0xffff0000, v158
	v_lshlrev_b32_e32 v40, 16, v159
	v_and_b32_e32 v41, 0xffff0000, v159
	v_lshl_add_u64 v[32:33], v[222:223], 0, v[220:221]
	v_pk_fma_f32 v[30:31], v[30:31], v[142:143], v[36:37]
	v_pk_fma_f32 v[28:29], v[28:29], v[140:141], v[34:35]
	v_pk_fma_f32 v[34:35], v[26:27], v[138:139], v[40:41]
	v_pk_fma_f32 v[26:27], v[24:25], v[136:137], v[38:39]
	v_cvt_pk_bf16_f32 v24, v28, v29
	v_cvt_pk_bf16_f32 v25, v30, v31
	v_lshlrev_b32_e32 v28, 16, v154
	v_cvt_pk_bf16_f32 v26, v26, v27
	v_cvt_pk_bf16_f32 v27, v34, v35
	global_store_dwordx4 v[32:33], v[24:27], off
	v_and_b32_e32 v29, 0xffff0000, v154
	v_lshlrev_b32_e32 v30, 16, v155
	v_lshlrev_b32_e32 v24, 16, v152
	v_and_b32_e32 v25, 0xffff0000, v152
	v_and_b32_e32 v31, 0xffff0000, v155
	v_lshlrev_b32_e32 v26, 16, v153
	v_and_b32_e32 v27, 0xffff0000, v153
	v_pk_fma_f32 v[20:21], v[20:21], v[132:133], v[24:25]
	v_pk_fma_f32 v[24:25], v[18:19], v[130:131], v[30:31]
	v_pk_fma_f32 v[18:19], v[16:17], v[128:129], v[28:29]
	v_pk_fma_f32 v[22:23], v[22:23], v[134:135], v[26:27]
	v_cvt_pk_bf16_f32 v16, v20, v21
	v_lshlrev_b32_e32 v20, 16, v149
	v_cvt_pk_bf16_f32 v17, v22, v23
	v_cvt_pk_bf16_f32 v18, v18, v19
	v_cvt_pk_bf16_f32 v19, v24, v25
	global_store_dwordx4 v[32:33], v[16:19], off offset:256
	v_and_b32_e32 v21, 0xffff0000, v149
	v_lshlrev_b32_e32 v22, 16, v150
	v_lshlrev_b32_e32 v18, 16, v148
	v_and_b32_e32 v19, 0xffff0000, v148
	v_and_b32_e32 v23, 0xffff0000, v150
	v_lshlrev_b32_e32 v24, 16, v151
	v_and_b32_e32 v25, 0xffff0000, v151
	v_lshl_add_u64 v[16:17], v[222:223], 0, v[218:219]
	v_pk_fma_f32 v[14:15], v[14:15], v[142:143], v[20:21]
	v_pk_fma_f32 v[12:13], v[12:13], v[140:141], v[18:19]
	v_pk_fma_f32 v[18:19], v[10:11], v[138:139], v[24:25]
	v_pk_fma_f32 v[10:11], v[8:9], v[136:137], v[22:23]
	v_cvt_pk_bf16_f32 v8, v12, v13
	v_cvt_pk_bf16_f32 v9, v14, v15
	v_lshlrev_b32_e32 v12, 16, v146
	v_cvt_pk_bf16_f32 v10, v10, v11
	v_cvt_pk_bf16_f32 v11, v18, v19
	global_store_dwordx4 v[16:17], v[8:11], off
	v_and_b32_e32 v13, 0xffff0000, v146
	v_lshlrev_b32_e32 v14, 16, v147
	v_lshlrev_b32_e32 v8, 16, v144
	v_and_b32_e32 v9, 0xffff0000, v144
	v_and_b32_e32 v15, 0xffff0000, v147
	v_lshlrev_b32_e32 v10, 16, v145
	v_and_b32_e32 v11, 0xffff0000, v145
	v_pk_fma_f32 v[4:5], v[4:5], v[132:133], v[8:9]
	v_pk_fma_f32 v[8:9], v[2:3], v[130:131], v[14:15]
	v_pk_fma_f32 v[2:3], v[0:1], v[128:129], v[12:13]
	v_pk_fma_f32 v[6:7], v[6:7], v[134:135], v[10:11]
	v_cvt_pk_bf16_f32 v0, v4, v5
	s_nop 0
	v_cvt_pk_bf16_f32 v1, v6, v7
	v_cvt_pk_bf16_f32 v2, v2, v3
	v_cvt_pk_bf16_f32 v3, v8, v9
	global_store_dwordx4 v[16:17], v[0:3], off offset:256
	s_barrier
	s_cbranch_vccz .LBB0_891

; #define PG8_STAGE(bufoff, gbase, voff) do { _Pragma("unroll") for (int _i = 0; _i < 2; ++_i) \
;         __builtin_amdgcn_global_load_lds((const unsigned*)((const char*)(gbase) + (voff)[_i]), (LAS unsigned*)(lds + (bufoff) + ldsw + _i * 8192), 16, 0, 0); } while (0)
; #define PG8_LDA(dst, b, h) do { _Pragma("unroll") for (int m = 0; m < 4; ++m) _Pragma("unroll") for (int k = 0; k < 2; ++k) dst[m][k] = *(const LAS bf16x8*)(lds + PG8_SA(b, h) + aoff + m * 2048 + k * 1024); } while (0)
; #define PG8_LDB(dst, b, h) do { _Pragma("unroll") for (int n = 0; n < 2; ++n) _Pragma("unroll") for (int k = 0; k < 2; ++k) dst[n][k] = *(const LAS bf16x8*)(lds + PG8_SB(b, h) + boff + n * 2048 + k * 1024); } while (0)
; #define PG8_MMA(ai, bj, At, Bt) do { __builtin_amdgcn_s_setprio(1); _Pragma("unroll") for (int m = 0; m < 4; ++m) _Pragma("unroll") for (int n = 0; n < 2; ++n) _Pragma("unroll") for (int k = 0; k < 2; ++k) \
;         acc[ai][bj][m][n] = __builtin_amdgcn_mfma_f32_16x16x32_bf16(Bt[n][k], At[m][k], acc[ai][bj][m][n], 0, 0, 0); __builtin_amdgcn_s_setprio(0); } while (0)
; #define PG8_WAIT_V(n) asm volatile("s_waitcnt vmcnt(" #n ")" ::: "memory")
; #define PG8_WAIT_L(n) asm volatile("s_waitcnt lgkmcnt(" #n ")" ::: "memory")
; #define PG8_BAR __builtin_amdgcn_s_barrier()
; #define PG8_SCHED __builtin_amdgcn_sched_barrier(0)
; template <class Epi, class Sched>
; __device__ __forceinline__ void gemm_phase(LAS unsigned char* lds, const Gemm g, const Sched& S, const Epi& E) {
;     ...
;             PG8_LDB(B0, 0, 0); PG8_SCHED; PG8_LDA(At, 0, 0); PG8_STAGE(PG8_SA(1, 1), a1 + hstep, voffA);
;             PG8_WAIT_L(8); PG8_BAR; PG8_WAIT_L(0); PG8_MMA(0, 0, At, B0); PG8_BAR; PG8_SCHED;
;             PG8_LDB(B1, 0, 1); PG8_STAGE(PG8_SB(0, 0), b2, voffB);
;             PG8_BAR; PG8_WAIT_L(0); PG8_MMA(0, 1, At, B1); PG8_BAR;
;             PG8_LDA(At, 0, 1); PG8_STAGE(PG8_SA(0, 0), a2, voffA);
;             PG8_BAR; PG8_WAIT_L(0); PG8_MMA(1, 0, At, B0); PG8_BAR; PG8_SCHED;
;             PG8_STAGE(PG8_SB(0, 1), b2 + hstep, voffB);
;             PG8_WAIT_V(6); PG8_BAR; PG8_MMA(1, 1, At, B1); PG8_BAR;
;             PG8_LDB(B0, 1, 0); PG8_SCHED; PG8_LDA(At, 1, 0); PG8_STAGE(PG8_SA(0, 1), a2 + hstep, voffA);
;             PG8_WAIT_L(8); PG8_BAR; PG8_WAIT_L(0); PG8_MMA(0, 0, At, B0); PG8_BAR; PG8_SCHED;
.LBB0_1097:
	ds_read_b128 v[128:131], v241
	ds_read_b128 v[132:135], v241 offset:1024
	ds_read_b128 v[136:139], v241 offset:2048
	ds_read_b128 v[140:143], v241 offset:3072
	s_add_u32 s24, s22, 0x100
	s_addc_u32 s25, s23, 0
	s_cmp_eq_u32 s56, 40
	s_cselect_b32 s29, s5, s25
	s_cselect_b32 s28, s4, s24
	s_cselect_b32 s27, s7, s55
	s_cselect_b32 s26, s6, s54
	v_lshl_add_u64 v[176:177], s[22:23], 0, v[196:197]
	s_add_i32 m0, s35, 0xc000
	ds_read_b128 v[144:147], v242
	ds_read_b128 v[148:151], v242 offset:1024
	ds_read_b128 v[152:155], v242 offset:2048
	ds_read_b128 v[156:159], v242 offset:3072
	ds_read_b128 v[160:163], v242 offset:4096
	ds_read_b128 v[164:167], v242 offset:5120
	ds_read_b128 v[168:171], v242 offset:6144
	ds_read_b128 v[172:175], v242 offset:7168
	global_load_lds_dwordx4 v[176:177], off
	v_lshl_add_u64 v[176:177], s[22:23], 0, v[198:199]
	s_add_i32 m0, s35, 0xe000
	s_nop 0
	global_load_lds_dwordx4 v[176:177], off
	s_waitcnt lgkmcnt(8)
	s_waitcnt vmcnt(10)
	s_barrier
	s_waitcnt lgkmcnt(0)
	s_setprio 1
	s_waitcnt lgkmcnt(0)
	v_mfma_f32_16x16x32_bf16 v[124:127], v[128:131], v[144:147], v[124:127]
	v_mfma_f32_16x16x32_bf16 v[120:123], v[136:139], v[144:147], v[120:123]
	v_mfma_f32_16x16x32_bf16 v[108:111], v[128:131], v[152:155], v[108:111]
	v_mfma_f32_16x16x32_bf16 v[104:107], v[136:139], v[152:155], v[104:107]
	v_mfma_f32_16x16x32_bf16 v[92:95], v[128:131], v[160:163], v[92:95]
	v_mfma_f32_16x16x32_bf16 v[88:91], v[136:139], v[160:163], v[88:91]
	v_mfma_f32_16x16x32_bf16 v[76:79], v[128:131], v[168:171], v[76:79]
	v_mfma_f32_16x16x32_bf16 v[72:75], v[136:139], v[168:171], v[72:75]
	v_mfma_f32_16x16x32_bf16 v[124:127], v[132:135], v[148:151], v[124:127]
	v_mfma_f32_16x16x32_bf16 v[120:123], v[140:143], v[148:151], v[120:123]
	v_mfma_f32_16x16x32_bf16 v[108:111], v[132:135], v[156:159], v[108:111]
	v_mfma_f32_16x16x32_bf16 v[104:107], v[140:143], v[156:159], v[104:107]
	v_mfma_f32_16x16x32_bf16 v[92:95], v[132:135], v[164:167], v[92:95]
	v_mfma_f32_16x16x32_bf16 v[88:91], v[140:143], v[164:167], v[88:91]
	v_mfma_f32_16x16x32_bf16 v[76:79], v[132:135], v[172:175], v[76:79]
	v_mfma_f32_16x16x32_bf16 v[72:75], v[140:143], v[172:175], v[72:75]
	s_setprio 0
	s_barrier
	s_add_i32 s22, s48, s34
	s_mov_b32 m0, s22
	ds_read_b128 v[176:179], v243
	ds_read_b128 v[180:183], v243 offset:1024
	ds_read_b128 v[184:187], v243 offset:2048
	ds_read_b128 v[206:209], v243 offset:3072
	global_load_lds_dwordx4 v190, s[26:27]
	s_add_i32 m0, s22, 0x2000
	s_nop 0
	global_load_lds_dwordx4 v194, s[26:27]
	s_waitcnt vmcnt(10)
	s_barrier
	s_waitcnt lgkmcnt(0)
	s_setprio 1
	s_waitcnt lgkmcnt(0)
	v_mfma_f32_16x16x32_bf16 v[116:119], v[176:179], v[144:147], v[116:119]
	v_mfma_f32_16x16x32_bf16 v[112:115], v[184:187], v[144:147], v[112:115]
	v_mfma_f32_16x16x32_bf16 v[100:103], v[176:179], v[152:155], v[100:103]
	v_mfma_f32_16x16x32_bf16 v[96:99], v[184:187], v[152:155], v[96:99]
	v_mfma_f32_16x16x32_bf16 v[84:87], v[176:179], v[160:163], v[84:87]
	v_mfma_f32_16x16x32_bf16 v[80:83], v[184:187], v[160:163], v[80:83]
	v_mfma_f32_16x16x32_bf16 v[68:71], v[176:179], v[168:171], v[68:71]
	v_mfma_f32_16x16x32_bf16 v[64:67], v[184:187], v[168:171], v[64:67]
	v_mfma_f32_16x16x32_bf16 v[116:119], v[180:183], v[148:151], v[116:119]
	v_mfma_f32_16x16x32_bf16 v[112:115], v[206:209], v[148:151], v[112:115]
	v_mfma_f32_16x16x32_bf16 v[100:103], v[180:183], v[156:159], v[100:103]
	v_mfma_f32_16x16x32_bf16 v[96:99], v[206:209], v[156:159], v[96:99]
	v_mfma_f32_16x16x32_bf16 v[84:87], v[180:183], v[164:167], v[84:87]
	v_mfma_f32_16x16x32_bf16 v[80:83], v[206:209], v[164:167], v[80:83]
	v_mfma_f32_16x16x32_bf16 v[68:71], v[180:183], v[172:175], v[68:71]
	v_mfma_f32_16x16x32_bf16 v[64:67], v[206:209], v[172:175], v[64:67]
	s_setprio 0
	s_mov_b32 m0, s35
	v_lshl_add_u64 v[214:215], s[28:29], 0, v[188:189]
	s_barrier
	ds_read_b128 v[144:147], v242 offset:16384
	ds_read_b128 v[148:151], v242 offset:17408
	ds_read_b128 v[152:155], v242 offset:18432
	ds_read_b128 v[156:159], v242 offset:19456
	ds_read_b128 v[160:163], v242 offset:20480
	ds_read_b128 v[164:167], v242 offset:21504
	ds_read_b128 v[168:171], v242 offset:22528
	ds_read_b128 v[172:175], v242 offset:23552
	global_load_lds_dwordx4 v188, s[28:29]
	v_lshl_add_u64 v[216:217], s[28:29], 0, v[192:193]
	s_mov_b32 m0, s36
	s_nop 0
	global_load_lds_dwordx4 v192, s[28:29]
	s_barrier
	s_waitcnt lgkmcnt(0)
	s_setprio 1
	s_waitcnt lgkmcnt(0)
	v_mfma_f32_16x16x32_bf16 v[60:63], v[128:131], v[144:147], v[60:63]
	v_mfma_f32_16x16x32_bf16 v[56:59], v[136:139], v[144:147], v[56:59]
	v_mfma_f32_16x16x32_bf16 v[44:47], v[128:131], v[152:155], v[44:47]
	v_mfma_f32_16x16x32_bf16 v[40:43], v[136:139], v[152:155], v[40:43]
	v_mfma_f32_16x16x32_bf16 v[28:31], v[128:131], v[160:163], v[28:31]
	v_mfma_f32_16x16x32_bf16 v[24:27], v[136:139], v[160:163], v[24:27]
	v_mfma_f32_16x16x32_bf16 v[12:15], v[128:131], v[168:171], v[12:15]
	v_mfma_f32_16x16x32_bf16 v[8:11], v[136:139], v[168:171], v[8:11]
	v_mfma_f32_16x16x32_bf16 v[60:63], v[132:135], v[148:151], v[60:63]
	v_mfma_f32_16x16x32_bf16 v[56:59], v[140:143], v[148:151], v[56:59]
	v_mfma_f32_16x16x32_bf16 v[44:47], v[132:135], v[156:159], v[44:47]
	v_mfma_f32_16x16x32_bf16 v[40:43], v[140:143], v[156:159], v[40:43]
	v_mfma_f32_16x16x32_bf16 v[28:31], v[132:135], v[164:167], v[28:31]
	v_mfma_f32_16x16x32_bf16 v[24:27], v[140:143], v[164:167], v[24:27]
	v_mfma_f32_16x16x32_bf16 v[12:15], v[132:135], v[172:175], v[12:15]
	v_mfma_f32_16x16x32_bf16 v[8:11], v[140:143], v[172:175], v[8:11]
	s_setprio 0
	s_barrier
; #define PG8_STAGE(bufoff, gbase, voff) do { _Pragma("unroll") for (int _i = 0; _i < 2; ++_i) \
;         __builtin_amdgcn_global_load_lds((const unsigned*)((const char*)(gbase) + (voff)[_i]), (LAS unsigned*)(lds + (bufoff) + ldsw + _i * 8192), 16, 0, 0); } while (0)
; #define PG8_LDA(dst, b, h) do { _Pragma("unroll") for (int m = 0; m < 4; ++m) _Pragma("unroll") for (int k = 0; k < 2; ++k) dst[m][k] = *(const LAS bf16x8*)(lds + PG8_SA(b, h) + aoff + m * 2048 + k * 1024); } while (0)
; #define PG8_LDB(dst, b, h) do { _Pragma("unroll") for (int n = 0; n < 2; ++n) _Pragma("unroll") for (int k = 0; k < 2; ++k) dst[n][k] = *(const LAS bf16x8*)(lds + PG8_SB(b, h) + boff + n * 2048 + k * 1024); } while (0)
; #define PG8_MMA(ai, bj, At, Bt) do { __builtin_amdgcn_s_setprio(1); _Pragma("unroll") for (int m = 0; m < 4; ++m) _Pragma("unroll") for (int n = 0; n < 2; ++n) _Pragma("unroll") for (int k = 0; k < 2; ++k) \
;         acc[ai][bj][m][n] = __builtin_amdgcn_mfma_f32_16x16x32_bf16(Bt[n][k], At[m][k], acc[ai][bj][m][n], 0, 0, 0); __builtin_amdgcn_s_setprio(0); } while (0)
; #define PG8_WAIT_V(n) asm volatile("s_waitcnt vmcnt(" #n ")" ::: "memory")
; #define PG8_WAIT_L(n) asm volatile("s_waitcnt lgkmcnt(" #n ")" ::: "memory")
; #define PG8_BAR __builtin_amdgcn_s_barrier()
; #define PG8_SCHED __builtin_amdgcn_sched_barrier(0)
; template <class Epi, class Sched>
; __device__ __forceinline__ void gemm_phase(LAS unsigned char* lds, const Gemm g, const Sched& S, const Epi& E) {
;     ...
;             PG8_WAIT_V(6); PG8_BAR; PG8_MMA(1, 1, At, B1); PG8_BAR;
;             PG8_LDB(B0, 1, 0); PG8_SCHED; PG8_LDA(At, 1, 0); PG8_STAGE(PG8_SA(0, 1), a2 + hstep, voffA);
;             PG8_WAIT_L(8); PG8_BAR; PG8_WAIT_L(0); PG8_MMA(0, 0, At, B0); PG8_BAR; PG8_SCHED;
;             PG8_LDB(B1, 1, 1); PG8_STAGE(PG8_SB(1, 0), b3, voffB);
;             PG8_BAR; PG8_WAIT_L(0); PG8_MMA(0, 1, At, B1); PG8_BAR;
;             PG8_LDA(At, 1, 1); PG8_STAGE(PG8_SA(1, 0), a3, voffA);
;             PG8_BAR; PG8_WAIT_L(0); PG8_MMA(1, 0, At, B0); PG8_BAR; PG8_SCHED;
	s_add_u32 s22, s26, 0xb0000
	s_addc_u32 s23, s27, 0
	s_add_i32 s57, s49, s34
	s_mov_b32 m0, s57
	s_nop 0
	global_load_lds_dwordx4 v190, s[22:23]
	s_add_i32 m0, s57, 0x2000
	s_nop 0
	global_load_lds_dwordx4 v194, s[22:23]
	s_add_u32 s22, s28, 0xb0000
	s_addc_u32 s23, s29, 0
	s_mov_b32 m0, s37
	s_nop 0
	global_load_lds_dwordx4 v188, s[22:23]
	s_mov_b32 m0, s38
	s_nop 0
	global_load_lds_dwordx4 v192, s[22:23]
	s_waitcnt vmcnt(12)
	s_barrier
	s_setprio 1
	v_mfma_f32_16x16x32_bf16 v[52:55], v[176:179], v[144:147], v[52:55]
	v_mfma_f32_16x16x32_bf16 v[48:51], v[184:187], v[144:147], v[48:51]
	v_mfma_f32_16x16x32_bf16 v[36:39], v[176:179], v[152:155], v[36:39]
	v_mfma_f32_16x16x32_bf16 v[32:35], v[184:187], v[152:155], v[32:35]
	v_mfma_f32_16x16x32_bf16 v[20:23], v[176:179], v[160:163], v[20:23]
	v_mfma_f32_16x16x32_bf16 v[16:19], v[184:187], v[160:163], v[16:19]
	v_mfma_f32_16x16x32_bf16 v[4:7], v[176:179], v[168:171], v[4:7]
	v_mfma_f32_16x16x32_bf16 v[0:3], v[184:187], v[168:171], v[0:3]
	v_mfma_f32_16x16x32_bf16 v[52:55], v[180:183], v[148:151], v[52:55]
	v_mfma_f32_16x16x32_bf16 v[48:51], v[206:209], v[148:151], v[48:51]
	v_mfma_f32_16x16x32_bf16 v[36:39], v[180:183], v[156:159], v[36:39]
	v_mfma_f32_16x16x32_bf16 v[32:35], v[206:209], v[156:159], v[32:35]
	v_mfma_f32_16x16x32_bf16 v[20:23], v[180:183], v[164:167], v[20:23]
	v_mfma_f32_16x16x32_bf16 v[16:19], v[206:209], v[164:167], v[16:19]
	v_mfma_f32_16x16x32_bf16 v[4:7], v[180:183], v[172:175], v[4:7]
	v_mfma_f32_16x16x32_bf16 v[0:3], v[206:209], v[172:175], v[0:3]
	s_setprio 0
	s_add_i32 s57, 0, 0x18000
	v_add_u32_e32 v140, s57, v240
	s_barrier
	ds_read_b128 v[128:131], v140
	ds_read_b128 v[132:135], v140 offset:1024
	ds_read_b128 v[136:139], v140 offset:2048
	ds_read_b128 v[140:143], v140 offset:3072
	ds_read_b128 v[144:147], v242 offset:32768
	ds_read_b128 v[148:151], v242 offset:33792
	ds_read_b128 v[152:155], v242 offset:34816
	ds_read_b128 v[156:159], v242 offset:35840
	ds_read_b128 v[160:163], v242 offset:36864
	ds_read_b128 v[164:167], v242 offset:37888
	ds_read_b128 v[168:171], v242 offset:38912
	ds_read_b128 v[172:175], v242 offset:39936
	s_waitcnt lgkmcnt(8)
	s_waitcnt vmcnt(10)
	s_barrier
	s_waitcnt lgkmcnt(0)
	s_setprio 1
	s_waitcnt lgkmcnt(0)
	v_mfma_f32_16x16x32_bf16 v[124:127], v[128:131], v[144:147], v[124:127]
	v_mfma_f32_16x16x32_bf16 v[120:123], v[136:139], v[144:147], v[120:123]
	v_mfma_f32_16x16x32_bf16 v[108:111], v[128:131], v[152:155], v[108:111]
	v_mfma_f32_16x16x32_bf16 v[104:107], v[136:139], v[152:155], v[104:107]
	v_mfma_f32_16x16x32_bf16 v[92:95], v[128:131], v[160:163], v[92:95]
	v_mfma_f32_16x16x32_bf16 v[88:91], v[136:139], v[160:163], v[88:91]
	v_mfma_f32_16x16x32_bf16 v[76:79], v[128:131], v[168:171], v[76:79]
	v_mfma_f32_16x16x32_bf16 v[72:75], v[136:139], v[168:171], v[72:75]
	v_mfma_f32_16x16x32_bf16 v[124:127], v[132:135], v[148:151], v[124:127]
	v_mfma_f32_16x16x32_bf16 v[120:123], v[140:143], v[148:151], v[120:123]
	v_mfma_f32_16x16x32_bf16 v[108:111], v[132:135], v[156:159], v[108:111]
	v_mfma_f32_16x16x32_bf16 v[104:107], v[140:143], v[156:159], v[104:107]
	v_mfma_f32_16x16x32_bf16 v[92:95], v[132:135], v[164:167], v[92:95]
	v_mfma_f32_16x16x32_bf16 v[88:91], v[140:143], v[164:167], v[88:91]
	v_mfma_f32_16x16x32_bf16 v[76:79], v[132:135], v[172:175], v[76:79]
	v_mfma_f32_16x16x32_bf16 v[72:75], v[140:143], v[172:175], v[72:75]
	s_setprio 0
	s_barrier
	s_add_i32 s28, 0, 0x1c000
	s_add_i32 s22, s57, s34
	v_add_u32_e32 v206, s28, v240
	s_add_u32 s0, s26, 0x80
	s_addc_u32 s1, s27, 0
	s_mov_b32 m0, s22
	ds_read_b128 v[176:179], v206
	ds_read_b128 v[180:183], v206 offset:1024
	ds_read_b128 v[184:187], v206 offset:2048
	ds_read_b128 v[206:209], v206 offset:3072
	global_load_lds_dwordx4 v190, s[0:1]
	s_add_i32 m0, s22, 0x2000
	s_nop 0
	global_load_lds_dwordx4 v194, s[0:1]
	s_waitcnt vmcnt(10)
	s_barrier
	s_waitcnt lgkmcnt(0)
	s_setprio 1
	s_waitcnt lgkmcnt(0)
	v_mfma_f32_16x16x32_bf16 v[116:119], v[176:179], v[144:147], v[116:119]
	v_mfma_f32_16x16x32_bf16 v[112:115], v[184:187], v[144:147], v[112:115]
	v_mfma_f32_16x16x32_bf16 v[100:103], v[176:179], v[152:155], v[100:103]
	v_mfma_f32_16x16x32_bf16 v[96:99], v[184:187], v[152:155], v[96:99]
	v_mfma_f32_16x16x32_bf16 v[84:87], v[176:179], v[160:163], v[84:87]
	v_mfma_f32_16x16x32_bf16 v[80:83], v[184:187], v[160:163], v[80:83]
	v_mfma_f32_16x16x32_bf16 v[68:71], v[176:179], v[168:171], v[68:71]
	v_mfma_f32_16x16x32_bf16 v[64:67], v[184:187], v[168:171], v[64:67]
	v_mfma_f32_16x16x32_bf16 v[116:119], v[180:183], v[148:151], v[116:119]
	v_mfma_f32_16x16x32_bf16 v[112:115], v[206:209], v[148:151], v[112:115]
	v_mfma_f32_16x16x32_bf16 v[100:103], v[180:183], v[156:159], v[100:103]
	v_mfma_f32_16x16x32_bf16 v[96:99], v[206:209], v[156:159], v[96:99]
	v_mfma_f32_16x16x32_bf16 v[84:87], v[180:183], v[164:167], v[84:87]
	v_mfma_f32_16x16x32_bf16 v[80:83], v[206:209], v[164:167], v[80:83]
	v_mfma_f32_16x16x32_bf16 v[68:71], v[180:183], v[172:175], v[68:71]
	v_mfma_f32_16x16x32_bf16 v[64:67], v[206:209], v[172:175], v[64:67]
	s_setprio 0
	s_mov_b32 m0, s44
	s_mov_b64 s[0:1], 0x80
	v_lshl_add_u64 v[210:211], v[214:215], 0, s[0:1]
	s_barrier
	ds_read_b128 v[144:147], v242 offset:49152
	ds_read_b128 v[148:151], v242 offset:50176
	ds_read_b128 v[152:155], v242 offset:51200
	ds_read_b128 v[156:159], v242 offset:52224
	ds_read_b128 v[160:163], v242 offset:53248
	ds_read_b128 v[164:167], v242 offset:54272
	ds_read_b128 v[168:171], v242 offset:55296
	ds_read_b128 v[172:175], v242 offset:56320
	global_load_lds_dwordx4 v[210:211], off
	v_lshl_add_u64 v[210:211], v[216:217], 0, s[0:1]
	s_mov_b32 m0, s45
	s_nop 0
	global_load_lds_dwordx4 v[210:211], off
	s_barrier
; #define PG8_STAGE(bufoff, gbase, voff) do { _Pragma("unroll") for (int _i = 0; _i < 2; ++_i) \
;         __builtin_amdgcn_global_load_lds((const unsigned*)((const char*)(gbase) + (voff)[_i]), (LAS unsigned*)(lds + (bufoff) + ldsw + _i * 8192), 16, 0, 0); } while (0)
; #define PG8_MMA(ai, bj, At, Bt) do { __builtin_amdgcn_s_setprio(1); _Pragma("unroll") for (int m = 0; m < 4; ++m) _Pragma("unroll") for (int n = 0; n < 2; ++n) _Pragma("unroll") for (int k = 0; k < 2; ++k) \
;         acc[ai][bj][m][n] = __builtin_amdgcn_mfma_f32_16x16x32_bf16(Bt[n][k], At[m][k], acc[ai][bj][m][n], 0, 0, 0); __builtin_amdgcn_s_setprio(0); } while (0)
; #define PG8_WAIT_V(n) asm volatile("s_waitcnt vmcnt(" #n ")" ::: "memory")
; #define PG8_WAIT_L(n) asm volatile("s_waitcnt lgkmcnt(" #n ")" ::: "memory")
; #define PG8_BAR __builtin_amdgcn_s_barrier()
; #define PG8_SCHED __builtin_amdgcn_sched_barrier(0)
; template <class Epi, class Sched>
; __device__ __forceinline__ void gemm_phase(LAS unsigned char* lds, const Gemm g, const Sched& S, const Epi& E) {
;     ...
;             PG8_BAR; PG8_WAIT_L(0); PG8_MMA(1, 0, At, B0); PG8_BAR; PG8_SCHED;
;             PG8_STAGE(PG8_SB(1, 1), b3 + hstep, voffB);
;             PG8_WAIT_V(6); PG8_BAR; PG8_MMA(1, 1, At, B1); PG8_BAR;
;         }
;         E(acc, cur, wr, wc, fr, fq);
;         if (!has_next) break;
;     __device__ __forceinline__ void operator()(const AccT& acc, const Unit& u, int wr, int wc, int fr, int fq) const {
;         asm volatile("" : "+v"(fr), "+v"(fq));
;         const int rowt = u.pm * 256; const int b = rowt >> 11;
;         const bf16_t* res = res_b + (size_t)rowt * DM; bf16_t* out = hb + (size_t)rowt * DM;
;         const int col0 = u.pn * 256 + wc * 32 + 8 * fq;
;         f32x4 gv[2][2];
; #pragma unroll
;         for (int bj = 0; bj < 2; ++bj)
; #pragma unroll
;             for (int n = 0; n < 2; ++n) gv[bj][n] = *(const f32x4*)(gate + (size_t)b * NMOD + col0 + bj * 128 + n * 4) * gs;
;         u32x4 r[2][4][2];
; #pragma unroll
;         for (int ai = 0; ai < 2; ++ai)
; #pragma unroll
;             for (int m = 0; m < 4; ++m)
; #pragma unroll
;                 for (int bj = 0; bj < 2; ++bj) r[ai][m][bj] = *(const u32x4*)(res + (size_t)(wr * 64 + fr + ai * 128 + m * 16) * DM + col0 + bj * 128);
	s_waitcnt lgkmcnt(0)
	s_setprio 1
	s_waitcnt lgkmcnt(0)
	v_mfma_f32_16x16x32_bf16 v[60:63], v[128:131], v[144:147], v[60:63]
	v_mfma_f32_16x16x32_bf16 v[56:59], v[136:139], v[144:147], v[56:59]
	v_mfma_f32_16x16x32_bf16 v[44:47], v[128:131], v[152:155], v[44:47]
	v_mfma_f32_16x16x32_bf16 v[40:43], v[136:139], v[152:155], v[40:43]
	v_mfma_f32_16x16x32_bf16 v[28:31], v[128:131], v[160:163], v[28:31]
	v_mfma_f32_16x16x32_bf16 v[24:27], v[136:139], v[160:163], v[24:27]
	v_mfma_f32_16x16x32_bf16 v[12:15], v[128:131], v[168:171], v[12:15]
	v_mfma_f32_16x16x32_bf16 v[8:11], v[136:139], v[168:171], v[8:11]
	v_mfma_f32_16x16x32_bf16 v[60:63], v[132:135], v[148:151], v[60:63]
	v_mfma_f32_16x16x32_bf16 v[56:59], v[140:143], v[148:151], v[56:59]
	v_mfma_f32_16x16x32_bf16 v[44:47], v[132:135], v[156:159], v[44:47]
	v_mfma_f32_16x16x32_bf16 v[40:43], v[140:143], v[156:159], v[40:43]
	v_mfma_f32_16x16x32_bf16 v[28:31], v[132:135], v[164:167], v[28:31]
	v_mfma_f32_16x16x32_bf16 v[24:27], v[140:143], v[164:167], v[24:27]
	v_mfma_f32_16x16x32_bf16 v[12:15], v[132:135], v[172:175], v[12:15]
	v_mfma_f32_16x16x32_bf16 v[8:11], v[140:143], v[172:175], v[8:11]
	s_setprio 0
	s_barrier
	s_add_u32 s22, s26, 0xb0080
	s_addc_u32 s23, s27, 0
	s_add_i32 s26, s28, s34
	s_mov_b32 m0, s26
	s_nop 0
	global_load_lds_dwordx4 v190, s[22:23]
	s_add_i32 m0, s26, 0x2000
	s_nop 0
	global_load_lds_dwordx4 v194, s[22:23]
	s_waitcnt vmcnt(10)
	s_barrier
	s_setprio 1
	v_mfma_f32_16x16x32_bf16 v[52:55], v[176:179], v[144:147], v[52:55]
	v_mfma_f32_16x16x32_bf16 v[48:51], v[184:187], v[144:147], v[48:51]
	v_mfma_f32_16x16x32_bf16 v[36:39], v[176:179], v[152:155], v[36:39]
	v_mfma_f32_16x16x32_bf16 v[32:35], v[184:187], v[152:155], v[32:35]
	v_mfma_f32_16x16x32_bf16 v[20:23], v[176:179], v[160:163], v[20:23]
	v_mfma_f32_16x16x32_bf16 v[16:19], v[184:187], v[160:163], v[16:19]
	v_mfma_f32_16x16x32_bf16 v[4:7], v[176:179], v[168:171], v[4:7]
	v_mfma_f32_16x16x32_bf16 v[0:3], v[184:187], v[168:171], v[0:3]
	v_mfma_f32_16x16x32_bf16 v[52:55], v[180:183], v[148:151], v[52:55]
	v_mfma_f32_16x16x32_bf16 v[48:51], v[206:209], v[148:151], v[48:51]
	v_mfma_f32_16x16x32_bf16 v[36:39], v[180:183], v[156:159], v[36:39]
	v_mfma_f32_16x16x32_bf16 v[32:35], v[206:209], v[156:159], v[32:35]
	v_mfma_f32_16x16x32_bf16 v[20:23], v[180:183], v[164:167], v[20:23]
	v_mfma_f32_16x16x32_bf16 v[16:19], v[206:209], v[164:167], v[16:19]
	v_mfma_f32_16x16x32_bf16 v[4:7], v[180:183], v[172:175], v[4:7]
	v_mfma_f32_16x16x32_bf16 v[0:3], v[206:209], v[172:175], v[0:3]
	s_setprio 0
	s_add_i32 s56, s56, 2
	s_add_u32 s54, s54, 0x100
	s_addc_u32 s55, s55, 0
	s_cmp_gt_u32 s56, 41
	s_mov_b64 s[22:23], s[24:25]
	s_cbranch_scc1 .Lconc_last_g12
	s_barrier
	s_branch .LBB0_1097
.Lconc_last_g12:
	v_readfirstlane_b32 s25, v200
	s_nop 3
	s_cmp_gt_u32 s25, 0xff
	s_cbranch_scc1 .Lconc_epi1_g12
	s_barrier
	s_lshl_b32 s25, s52, 8
	v_mov_b32_e32 v140, v239
	v_mov_b32_e32 v128, v238
	s_lshl_b32 s22, s53, 8
	s_ashr_i32 s24, s53, 3
	s_or_b32 s25, s25, s43
	s_ashr_i32 s23, s22, 31
	v_lshl_add_u32 v136, v128, 3, s25
	s_mul_hi_i32 s25, s24, 0x9000
	s_mul_i32 s24, s24, 0x9000
	s_add_u32 s24, s40, s24
	s_addc_u32 s25, s41, s25
	v_ashrrev_i32_e32 v137, 31, v136
	v_lshl_add_u64 v[138:139], v[136:137], 2, s[24:25]
	global_load_dwordx4 v[128:131], v[138:139], off offset:16
	global_load_dwordx4 v[132:135], v[138:139], off
	s_lshl_b64 s[22:23], s[22:23], 11
	s_add_u32 s24, s80, s22
	s_addc_u32 s25, s81, s23
	v_lshlrev_b64 v[226:227], 1, v[136:137]
	s_add_u32 s22, s96, s22
	s_addc_u32 s23, s97, s23
	s_and_b64 vcc, exec, s[2:3]
	s_mov_b32 s52, s50
	s_mov_b32 s53, s51
	s_waitcnt vmcnt(0)
	v_pk_mul_f32 v[216:217], v[130:131], 0.5 op_sel_hi:[1,0]
	v_pk_mul_f32 v[220:221], v[134:135], 0.5 op_sel_hi:[1,0]
	v_pk_mul_f32 v[218:219], v[132:133], 0.5 op_sel_hi:[1,0]
	v_pk_mul_f32 v[214:215], v[128:129], 0.5 op_sel_hi:[1,0]
	global_load_dwordx4 v[128:131], v[138:139], off offset:528
	global_load_dwordx4 v[132:135], v[138:139], off offset:512
	s_waitcnt vmcnt(0)
	v_pk_mul_f32 v[206:207], v[128:129], 0.5 op_sel_hi:[1,0]
	v_add_u32_e32 v128, s42, v140
	v_ashrrev_i32_e32 v129, 31, v128
	v_pk_mul_f32 v[208:209], v[130:131], 0.5 op_sel_hi:[1,0]
	v_lshl_add_u64 v[130:131], s[24:25], 0, v[226:227]
	v_lshlrev_b64 v[248:249], 11, v[128:129]
	v_lshl_add_u64 v[128:129], v[130:131], 0, v[248:249]
	global_load_dwordx4 v[244:247], v[128:129], off
	global_load_dwordx4 v[184:187], v[128:129], off offset:256
	v_lshl_add_u64 v[236:237], v[248:249], 0, s[8:9]
	v_lshl_add_u64 v[128:129], v[130:131], 0, v[236:237]
	global_load_dwordx4 v[180:183], v[128:129], off
	global_load_dwordx4 v[176:179], v[128:129], off offset:256
	v_lshl_add_u64 v[234:235], v[248:249], 0, s[10:11]
	v_lshl_add_u64 v[128:129], v[130:131], 0, v[234:235]
	global_load_dwordx4 v[172:175], v[128:129], off
	global_load_dwordx4 v[168:171], v[128:129], off offset:256
	v_lshl_add_u64 v[232:233], v[248:249], 0, s[12:13]
	v_lshl_add_u64 v[128:129], v[130:131], 0, v[232:233]
	global_load_dwordx4 v[164:167], v[128:129], off
	global_load_dwordx4 v[160:163], v[128:129], off offset:256
	v_lshl_add_u64 v[230:231], v[248:249], 0, s[14:15]
	v_lshl_add_u64 v[128:129], v[130:131], 0, v[230:231]
	global_load_dwordx4 v[156:159], v[128:129], off
	global_load_dwordx4 v[152:155], v[128:129], off offset:256
	v_lshl_add_u64 v[228:229], v[248:249], 0, s[16:17]
	v_lshl_add_u64 v[128:129], v[130:131], 0, v[228:229]
	global_load_dwordx4 v[148:151], v[128:129], off
	global_load_dwordx4 v[144:147], v[128:129], off offset:256
	v_lshl_add_u64 v[224:225], v[248:249], 0, s[18:19]
	v_lshl_add_u64 v[128:129], v[130:131], 0, v[224:225]
	global_load_dwordx4 v[140:143], v[128:129], off
	global_load_dwordx4 v[136:139], v[128:129], off offset:256
	v_lshl_add_u64 v[222:223], v[248:249], 0, s[20:21]
	v_lshl_add_u64 v[128:129], v[130:131], 0, v[222:223]
	v_pk_mul_f32 v[212:213], v[134:135], 0.5 op_sel_hi:[1,0]
	v_pk_mul_f32 v[210:211], v[132:133], 0.5 op_sel_hi:[1,0]
	global_load_dwordx4 v[132:135], v[128:129], off
	s_nop 0
	global_load_dwordx4 v[128:131], v[128:129], off offset:256
	v_lshl_add_u64 v[226:227], s[22:23], 0, v[226:227]
	v_lshl_add_u64 v[248:249], v[226:227], 0, v[248:249]
	s_mov_b64 s[24:25], s[6:7]
	s_mov_b64 s[22:23], s[4:5]
	s_waitcnt vmcnt(0)
; __device__ __forceinline__ unsigned cvt_pk_bf16(float lo, float hi) { unsigned r; asm volatile("v_cvt_pk_bf16_f32 %0, %1, %2" : "=v"(r) : "v"(lo), "v"(hi)); return r; }
; __device__ __forceinline__ float bf_lo(unsigned u) { return __uint_as_float(u << 16); }
; __device__ __forceinline__ float bf_hi(unsigned u) { return __uint_as_float(u & 0xffff0000u); }
;     __device__ __forceinline__ void operator()(const AccT& acc, const Unit& u, int wr, int wc, int fr, int fq) const {
;     ...
; #pragma unroll
;         for (int ai = 0; ai < 2; ++ai)
; #pragma unroll
;             for (int m = 0; m < 4; ++m)
; #pragma unroll
;                 for (int bj = 0; bj < 2; ++bj) {
;                     const u32x4 q = r[ai][m][bj];
;                     const f32x4 r0 = {bf_lo(q.x), bf_hi(q.x), bf_lo(q.y), bf_hi(q.y)}, r1 = {bf_lo(q.z), bf_hi(q.z), bf_lo(q.w), bf_hi(q.w)};
;                     const f32x4 h0 = r0 + gv[bj][0] * acc[ai][bj][m][0], h1 = r1 + gv[bj][1] * acc[ai][bj][m][1];
;                     u32x4 w; w.x = cvt_pk_bf16(h0[0], h0[1]); w.y = cvt_pk_bf16(h0[2], h0[3]); w.z = cvt_pk_bf16(h1[0], h1[1]); w.w = cvt_pk_bf16(h1[2], h1[3]);
;                     *(u32x4*)(out + (size_t)(wr * 64 + fr + ai * 128 + m * 16) * DM + col0 + bj * 128) = w;
;                 }
	v_lshlrev_b32_e32 v250, 16, v244
	v_and_b32_e32 v251, 0xffff0000, v244
	v_lshlrev_b32_e32 v244, 16, v245
	v_and_b32_e32 v245, 0xffff0000, v245
	v_lshlrev_b32_e32 v252, 16, v246
	v_and_b32_e32 v253, 0xffff0000, v246
	v_lshlrev_b32_e32 v246, 16, v247
	v_and_b32_e32 v247, 0xffff0000, v247
	v_pk_fma_f32 v[126:127], v[126:127], v[220:221], v[244:245]
	v_pk_fma_f32 v[124:125], v[124:125], v[218:219], v[250:251]
	v_pk_fma_f32 v[244:245], v[122:123], v[216:217], v[246:247]
	v_pk_fma_f32 v[122:123], v[120:121], v[214:215], v[252:253]
	v_cvt_pk_bf16_f32 v120, v124, v125
	v_cvt_pk_bf16_f32 v121, v126, v127
	v_lshlrev_b32_e32 v124, 16, v186
	v_cvt_pk_bf16_f32 v122, v122, v123
	v_cvt_pk_bf16_f32 v123, v244, v245
	global_store_dwordx4 v[248:249], v[120:123], off
	v_and_b32_e32 v125, 0xffff0000, v186
	v_lshlrev_b32_e32 v126, 16, v187
	v_lshlrev_b32_e32 v120, 16, v184
	v_and_b32_e32 v121, 0xffff0000, v184
	v_and_b32_e32 v127, 0xffff0000, v187
	v_lshlrev_b32_e32 v122, 16, v185
	v_and_b32_e32 v123, 0xffff0000, v185
	v_pk_fma_f32 v[116:117], v[116:117], v[210:211], v[120:121]
	v_pk_fma_f32 v[120:121], v[114:115], v[208:209], v[126:127]
	v_pk_fma_f32 v[114:115], v[112:113], v[206:207], v[124:125]
	v_pk_fma_f32 v[118:119], v[118:119], v[212:213], v[122:123]
	v_cvt_pk_bf16_f32 v112, v116, v117
	v_lshlrev_b32_e32 v116, 16, v181
	v_cvt_pk_bf16_f32 v113, v118, v119
	v_cvt_pk_bf16_f32 v114, v114, v115
	v_cvt_pk_bf16_f32 v115, v120, v121
	global_store_dwordx4 v[248:249], v[112:115], off offset:256
	v_and_b32_e32 v117, 0xffff0000, v181
	v_lshlrev_b32_e32 v118, 16, v182
	v_lshlrev_b32_e32 v114, 16, v180
	v_and_b32_e32 v115, 0xffff0000, v180
	v_and_b32_e32 v119, 0xffff0000, v182
	v_lshlrev_b32_e32 v120, 16, v183
	v_and_b32_e32 v121, 0xffff0000, v183
	v_lshl_add_u64 v[112:113], v[226:227], 0, v[236:237]
	v_pk_fma_f32 v[110:111], v[110:111], v[220:221], v[116:117]
	v_pk_fma_f32 v[108:109], v[108:109], v[218:219], v[114:115]
	v_pk_fma_f32 v[114:115], v[106:107], v[216:217], v[120:121]
	v_pk_fma_f32 v[106:107], v[104:105], v[214:215], v[118:119]
	v_cvt_pk_bf16_f32 v104, v108, v109
	v_cvt_pk_bf16_f32 v105, v110, v111
	v_lshlrev_b32_e32 v108, 16, v178
	v_cvt_pk_bf16_f32 v106, v106, v107
	v_cvt_pk_bf16_f32 v107, v114, v115
	global_store_dwordx4 v[112:113], v[104:107], off
	v_and_b32_e32 v109, 0xffff0000, v178
	v_lshlrev_b32_e32 v110, 16, v179
	v_lshlrev_b32_e32 v104, 16, v176
	v_and_b32_e32 v105, 0xffff0000, v176
	v_and_b32_e32 v111, 0xffff0000, v179
	v_lshlrev_b32_e32 v106, 16, v177
	v_and_b32_e32 v107, 0xffff0000, v177
	v_pk_fma_f32 v[100:101], v[100:101], v[210:211], v[104:105]
	v_pk_fma_f32 v[104:105], v[98:99], v[208:209], v[110:111]
	v_pk_fma_f32 v[98:99], v[96:97], v[206:207], v[108:109]
	v_pk_fma_f32 v[102:103], v[102:103], v[212:213], v[106:107]
	v_cvt_pk_bf16_f32 v96, v100, v101
	v_lshlrev_b32_e32 v100, 16, v173
	v_cvt_pk_bf16_f32 v97, v102, v103
	v_cvt_pk_bf16_f32 v98, v98, v99
	v_cvt_pk_bf16_f32 v99, v104, v105
	global_store_dwordx4 v[112:113], v[96:99], off offset:256
	v_and_b32_e32 v101, 0xffff0000, v173
	v_lshlrev_b32_e32 v102, 16, v174
	v_lshlrev_b32_e32 v98, 16, v172
	v_and_b32_e32 v99, 0xffff0000, v172
	v_and_b32_e32 v103, 0xffff0000, v174
	v_lshlrev_b32_e32 v104, 16, v175
	v_and_b32_e32 v105, 0xffff0000, v175
	v_lshl_add_u64 v[96:97], v[226:227], 0, v[234:235]
	v_pk_fma_f32 v[94:95], v[94:95], v[220:221], v[100:101]
	v_pk_fma_f32 v[92:93], v[92:93], v[218:219], v[98:99]
	v_pk_fma_f32 v[98:99], v[90:91], v[216:217], v[104:105]
	v_pk_fma_f32 v[90:91], v[88:89], v[214:215], v[102:103]
	v_cvt_pk_bf16_f32 v88, v92, v93
	v_cvt_pk_bf16_f32 v89, v94, v95
	v_lshlrev_b32_e32 v92, 16, v170
	v_cvt_pk_bf16_f32 v90, v90, v91
	v_cvt_pk_bf16_f32 v91, v98, v99
	global_store_dwordx4 v[96:97], v[88:91], off
	v_and_b32_e32 v93, 0xffff0000, v170
	v_lshlrev_b32_e32 v94, 16, v171
	v_lshlrev_b32_e32 v88, 16, v168
	v_and_b32_e32 v89, 0xffff0000, v168
	v_and_b32_e32 v95, 0xffff0000, v171
	v_lshlrev_b32_e32 v90, 16, v169
	v_and_b32_e32 v91, 0xffff0000, v169
	v_pk_fma_f32 v[84:85], v[84:85], v[210:211], v[88:89]
	v_pk_fma_f32 v[88:89], v[82:83], v[208:209], v[94:95]
	v_pk_fma_f32 v[82:83], v[80:81], v[206:207], v[92:93]
	v_pk_fma_f32 v[86:87], v[86:87], v[212:213], v[90:91]
	v_cvt_pk_bf16_f32 v80, v84, v85
	v_lshlrev_b32_e32 v84, 16, v165
	v_cvt_pk_bf16_f32 v81, v86, v87
	v_cvt_pk_bf16_f32 v82, v82, v83
	v_cvt_pk_bf16_f32 v83, v88, v89
	global_store_dwordx4 v[96:97], v[80:83], off offset:256
	v_and_b32_e32 v85, 0xffff0000, v165
	v_lshlrev_b32_e32 v86, 16, v166
	v_lshlrev_b32_e32 v82, 16, v164
	v_and_b32_e32 v83, 0xffff0000, v164
	v_and_b32_e32 v87, 0xffff0000, v166
	v_lshlrev_b32_e32 v88, 16, v167
	v_and_b32_e32 v89, 0xffff0000, v167
	v_lshl_add_u64 v[80:81], v[226:227], 0, v[232:233]
	v_pk_fma_f32 v[78:79], v[78:79], v[220:221], v[84:85]
	v_pk_fma_f32 v[76:77], v[76:77], v[218:219], v[82:83]
	v_pk_fma_f32 v[82:83], v[74:75], v[216:217], v[88:89]
	v_pk_fma_f32 v[74:75], v[72:73], v[214:215], v[86:87]
	v_cvt_pk_bf16_f32 v72, v76, v77
	v_cvt_pk_bf16_f32 v73, v78, v79
	v_lshlrev_b32_e32 v76, 16, v162
	v_cvt_pk_bf16_f32 v74, v74, v75
	v_cvt_pk_bf16_f32 v75, v82, v83
	global_store_dwordx4 v[80:81], v[72:75], off
	v_and_b32_e32 v77, 0xffff0000, v162
	v_lshlrev_b32_e32 v78, 16, v163
	v_lshlrev_b32_e32 v72, 16, v160
	v_and_b32_e32 v73, 0xffff0000, v160
	v_and_b32_e32 v79, 0xffff0000, v163
	v_lshlrev_b32_e32 v74, 16, v161
	v_and_b32_e32 v75, 0xffff0000, v161
	v_pk_fma_f32 v[68:69], v[68:69], v[210:211], v[72:73]
	v_pk_fma_f32 v[72:73], v[66:67], v[208:209], v[78:79]
	v_pk_fma_f32 v[66:67], v[64:65], v[206:207], v[76:77]
	v_pk_fma_f32 v[70:71], v[70:71], v[212:213], v[74:75]
; __device__ __forceinline__ unsigned cvt_pk_bf16(float lo, float hi) { unsigned r; asm volatile("v_cvt_pk_bf16_f32 %0, %1, %2" : "=v"(r) : "v"(lo), "v"(hi)); return r; }
; __device__ __forceinline__ float bf_lo(unsigned u) { return __uint_as_float(u << 16); }
; __device__ __forceinline__ float bf_hi(unsigned u) { return __uint_as_float(u & 0xffff0000u); }
;     __device__ __forceinline__ void operator()(const AccT& acc, const Unit& u, int wr, int wc, int fr, int fq) const {
;     ...
; #pragma unroll
;         for (int ai = 0; ai < 2; ++ai)
; #pragma unroll
;             for (int m = 0; m < 4; ++m)
; #pragma unroll
;                 for (int bj = 0; bj < 2; ++bj) {
;                     const u32x4 q = r[ai][m][bj];
;                     const f32x4 r0 = {bf_lo(q.x), bf_hi(q.x), bf_lo(q.y), bf_hi(q.y)}, r1 = {bf_lo(q.z), bf_hi(q.z), bf_lo(q.w), bf_hi(q.w)};
;                     const f32x4 h0 = r0 + gv[bj][0] * acc[ai][bj][m][0], h1 = r1 + gv[bj][1] * acc[ai][bj][m][1];
;                     u32x4 w; w.x = cvt_pk_bf16(h0[0], h0[1]); w.y = cvt_pk_bf16(h0[2], h0[3]); w.z = cvt_pk_bf16(h1[0], h1[1]); w.w = cvt_pk_bf16(h1[2], h1[3]);
;                     *(u32x4*)(out + (size_t)(wr * 64 + fr + ai * 128 + m * 16) * DM + col0 + bj * 128) = w;
;                 }
	v_cvt_pk_bf16_f32 v64, v68, v69
	v_lshlrev_b32_e32 v68, 16, v157
	v_cvt_pk_bf16_f32 v65, v70, v71
	v_cvt_pk_bf16_f32 v66, v66, v67
	v_cvt_pk_bf16_f32 v67, v72, v73
	global_store_dwordx4 v[80:81], v[64:67], off offset:256
	v_and_b32_e32 v69, 0xffff0000, v157
	v_lshlrev_b32_e32 v70, 16, v158
	v_lshlrev_b32_e32 v66, 16, v156
	v_and_b32_e32 v67, 0xffff0000, v156
	v_and_b32_e32 v71, 0xffff0000, v158
	v_lshlrev_b32_e32 v72, 16, v159
	v_and_b32_e32 v73, 0xffff0000, v159
	v_lshl_add_u64 v[64:65], v[226:227], 0, v[230:231]
	v_pk_fma_f32 v[62:63], v[62:63], v[220:221], v[68:69]
	v_pk_fma_f32 v[60:61], v[60:61], v[218:219], v[66:67]
	v_pk_fma_f32 v[66:67], v[58:59], v[216:217], v[72:73]
	v_pk_fma_f32 v[58:59], v[56:57], v[214:215], v[70:71]
	v_cvt_pk_bf16_f32 v56, v60, v61
	v_cvt_pk_bf16_f32 v57, v62, v63
	v_lshlrev_b32_e32 v60, 16, v154
	v_cvt_pk_bf16_f32 v58, v58, v59
	v_cvt_pk_bf16_f32 v59, v66, v67
	global_store_dwordx4 v[64:65], v[56:59], off
	v_and_b32_e32 v61, 0xffff0000, v154
	v_lshlrev_b32_e32 v62, 16, v155
	v_lshlrev_b32_e32 v56, 16, v152
	v_and_b32_e32 v57, 0xffff0000, v152
	v_and_b32_e32 v63, 0xffff0000, v155
	v_lshlrev_b32_e32 v58, 16, v153
	v_and_b32_e32 v59, 0xffff0000, v153
	v_pk_fma_f32 v[52:53], v[52:53], v[210:211], v[56:57]
	v_pk_fma_f32 v[56:57], v[50:51], v[208:209], v[62:63]
	v_pk_fma_f32 v[50:51], v[48:49], v[206:207], v[60:61]
	v_pk_fma_f32 v[54:55], v[54:55], v[212:213], v[58:59]
	v_cvt_pk_bf16_f32 v48, v52, v53
	v_lshlrev_b32_e32 v52, 16, v149
	v_cvt_pk_bf16_f32 v49, v54, v55
	v_cvt_pk_bf16_f32 v50, v50, v51
	v_cvt_pk_bf16_f32 v51, v56, v57
	global_store_dwordx4 v[64:65], v[48:51], off offset:256
	v_and_b32_e32 v53, 0xffff0000, v149
	v_lshlrev_b32_e32 v54, 16, v150
	v_lshlrev_b32_e32 v50, 16, v148
	v_and_b32_e32 v51, 0xffff0000, v148
	v_and_b32_e32 v55, 0xffff0000, v150
	v_lshlrev_b32_e32 v56, 16, v151
	v_and_b32_e32 v57, 0xffff0000, v151
	v_lshl_add_u64 v[48:49], v[226:227], 0, v[228:229]
	v_pk_fma_f32 v[46:47], v[46:47], v[220:221], v[52:53]
	v_pk_fma_f32 v[44:45], v[44:45], v[218:219], v[50:51]
	v_pk_fma_f32 v[50:51], v[42:43], v[216:217], v[56:57]
	v_pk_fma_f32 v[42:43], v[40:41], v[214:215], v[54:55]
	v_cvt_pk_bf16_f32 v40, v44, v45
	v_cvt_pk_bf16_f32 v41, v46, v47
	v_lshlrev_b32_e32 v44, 16, v146
	v_cvt_pk_bf16_f32 v42, v42, v43
	v_cvt_pk_bf16_f32 v43, v50, v51
	global_store_dwordx4 v[48:49], v[40:43], off
	v_and_b32_e32 v45, 0xffff0000, v146
	v_lshlrev_b32_e32 v46, 16, v147
	v_lshlrev_b32_e32 v40, 16, v144
	v_and_b32_e32 v41, 0xffff0000, v144
	v_and_b32_e32 v47, 0xffff0000, v147
	v_lshlrev_b32_e32 v42, 16, v145
	v_and_b32_e32 v43, 0xffff0000, v145
	v_pk_fma_f32 v[36:37], v[36:37], v[210:211], v[40:41]
	v_pk_fma_f32 v[40:41], v[34:35], v[208:209], v[46:47]
	v_pk_fma_f32 v[34:35], v[32:33], v[206:207], v[44:45]
	v_pk_fma_f32 v[38:39], v[38:39], v[212:213], v[42:43]
	v_cvt_pk_bf16_f32 v32, v36, v37
	v_lshlrev_b32_e32 v36, 16, v141
	v_cvt_pk_bf16_f32 v33, v38, v39
	v_cvt_pk_bf16_f32 v34, v34, v35
	v_cvt_pk_bf16_f32 v35, v40, v41
	global_store_dwordx4 v[48:49], v[32:35], off offset:256
	v_and_b32_e32 v37, 0xffff0000, v141
	v_lshlrev_b32_e32 v38, 16, v142
	v_lshlrev_b32_e32 v34, 16, v140
	v_and_b32_e32 v35, 0xffff0000, v140
	v_and_b32_e32 v39, 0xffff0000, v142
	v_lshlrev_b32_e32 v40, 16, v143
	v_and_b32_e32 v41, 0xffff0000, v143
	v_lshl_add_u64 v[32:33], v[226:227], 0, v[224:225]
	v_pk_fma_f32 v[30:31], v[30:31], v[220:221], v[36:37]
	v_pk_fma_f32 v[28:29], v[28:29], v[218:219], v[34:35]
	v_pk_fma_f32 v[34:35], v[26:27], v[216:217], v[40:41]
	v_pk_fma_f32 v[26:27], v[24:25], v[214:215], v[38:39]
	v_cvt_pk_bf16_f32 v24, v28, v29
	v_cvt_pk_bf16_f32 v25, v30, v31
	v_lshlrev_b32_e32 v28, 16, v138
	v_cvt_pk_bf16_f32 v26, v26, v27
	v_cvt_pk_bf16_f32 v27, v34, v35
	global_store_dwordx4 v[32:33], v[24:27], off
	v_and_b32_e32 v29, 0xffff0000, v138
	v_lshlrev_b32_e32 v30, 16, v139
	v_lshlrev_b32_e32 v24, 16, v136
	v_and_b32_e32 v25, 0xffff0000, v136
	v_and_b32_e32 v31, 0xffff0000, v139
	v_lshlrev_b32_e32 v26, 16, v137
	v_and_b32_e32 v27, 0xffff0000, v137
	v_pk_fma_f32 v[20:21], v[20:21], v[210:211], v[24:25]
	v_pk_fma_f32 v[24:25], v[18:19], v[208:209], v[30:31]
	v_pk_fma_f32 v[18:19], v[16:17], v[206:207], v[28:29]
	v_pk_fma_f32 v[22:23], v[22:23], v[212:213], v[26:27]
	v_cvt_pk_bf16_f32 v16, v20, v21
	v_lshlrev_b32_e32 v20, 16, v133
	v_cvt_pk_bf16_f32 v17, v22, v23
	v_cvt_pk_bf16_f32 v18, v18, v19
	v_cvt_pk_bf16_f32 v19, v24, v25
	global_store_dwordx4 v[32:33], v[16:19], off offset:256
	v_and_b32_e32 v21, 0xffff0000, v133
	v_lshlrev_b32_e32 v22, 16, v134
	v_lshlrev_b32_e32 v18, 16, v132
	v_and_b32_e32 v19, 0xffff0000, v132
	v_and_b32_e32 v23, 0xffff0000, v134
	v_lshlrev_b32_e32 v24, 16, v135
	v_and_b32_e32 v25, 0xffff0000, v135
	v_lshl_add_u64 v[16:17], v[226:227], 0, v[222:223]
	v_pk_fma_f32 v[14:15], v[14:15], v[220:221], v[20:21]
	v_pk_fma_f32 v[12:13], v[12:13], v[218:219], v[18:19]
	v_pk_fma_f32 v[18:19], v[10:11], v[216:217], v[24:25]
	v_pk_fma_f32 v[10:11], v[8:9], v[214:215], v[22:23]
	v_cvt_pk_bf16_f32 v8, v12, v13
	v_cvt_pk_bf16_f32 v9, v14, v15
	v_lshlrev_b32_e32 v12, 16, v130
	v_cvt_pk_bf16_f32 v10, v10, v11
	v_cvt_pk_bf16_f32 v11, v18, v19
	global_store_dwordx4 v[16:17], v[8:11], off
	v_and_b32_e32 v13, 0xffff0000, v130
	v_lshlrev_b32_e32 v14, 16, v131
	v_lshlrev_b32_e32 v8, 16, v128
	v_and_b32_e32 v9, 0xffff0000, v128
	v_and_b32_e32 v15, 0xffff0000, v131
	v_lshlrev_b32_e32 v10, 16, v129
	v_and_b32_e32 v11, 0xffff0000, v129
	v_pk_fma_f32 v[4:5], v[4:5], v[210:211], v[8:9]
	v_pk_fma_f32 v[8:9], v[2:3], v[208:209], v[14:15]
	v_pk_fma_f32 v[2:3], v[0:1], v[206:207], v[12:13]
	v_pk_fma_f32 v[6:7], v[6:7], v[212:213], v[10:11]
	v_cvt_pk_bf16_f32 v0, v4, v5
	s_nop 0
	v_cvt_pk_bf16_f32 v1, v6, v7
	v_cvt_pk_bf16_f32 v2, v2, v3
	v_cvt_pk_bf16_f32 v3, v8, v9
	global_store_dwordx4 v[16:17], v[0:3], off offset:256
	s_cbranch_vccz .LBB0_1086
	s_branch .Lconc_end_g12
; __device__ __forceinline__ unsigned cvt_pk_bf16(float lo, float hi) { unsigned r; asm volatile("v_cvt_pk_bf16_f32 %0, %1, %2" : "=v"(r) : "v"(lo), "v"(hi)); return r; }
; __device__ __forceinline__ float bf_lo(unsigned u) { return __uint_as_float(u << 16); }
; __device__ __forceinline__ float bf_hi(unsigned u) { return __uint_as_float(u & 0xffff0000u); }
;     __device__ __forceinline__ void operator()(const AccT& acc, const Unit& u, int wr, int wc, int fr, int fq) const {
;         asm volatile("" : "+v"(fr), "+v"(fq));
;         const int rowt = u.pm * 256; const int b = rowt >> 11;
;         const bf16_t* res = res_b + (size_t)rowt * DM; bf16_t* out = hb + (size_t)rowt * DM;
;         const int col0 = u.pn * 256 + wc * 32 + 8 * fq;
;         f32x4 gv[2][2];
; #pragma unroll
;         for (int bj = 0; bj < 2; ++bj)
; #pragma unroll
;             for (int n = 0; n < 2; ++n) gv[bj][n] = *(const f32x4*)(gate + (size_t)b * NMOD + col0 + bj * 128 + n * 4) * gs;
;         u32x4 r[2][4][2];
; #pragma unroll
;         for (int ai = 0; ai < 2; ++ai)
; #pragma unroll
;             for (int m = 0; m < 4; ++m)
; #pragma unroll
;                 for (int bj = 0; bj < 2; ++bj) r[ai][m][bj] = *(const u32x4*)(res + (size_t)(wr * 64 + fr + ai * 128 + m * 16) * DM + col0 + bj * 128);
; #pragma unroll
;         for (int ai = 0; ai < 2; ++ai)
; #pragma unroll
;             for (int m = 0; m < 4; ++m)
; #pragma unroll
;                 for (int bj = 0; bj < 2; ++bj) {
;                     const u32x4 q = r[ai][m][bj];
;                     const f32x4 r0 = {bf_lo(q.x), bf_hi(q.x), bf_lo(q.y), bf_hi(q.y)}, r1 = {bf_lo(q.z), bf_hi(q.z), bf_lo(q.w), bf_hi(q.w)};
;                     const f32x4 h0 = r0 + gv[bj][0] * acc[ai][bj][m][0], h1 = r1 + gv[bj][1] * acc[ai][bj][m][1];
;                     u32x4 w; w.x = cvt_pk_bf16(h0[0], h0[1]); w.y = cvt_pk_bf16(h0[2], h0[3]); w.z = cvt_pk_bf16(h1[0], h1[1]); w.w = cvt_pk_bf16(h1[2], h1[3]);
;                     *(u32x4*)(out + (size_t)(wr * 64 + fr + ai * 128 + m * 16) * DM + col0 + bj * 128) = w;
;                 }
.Lconc_epi1_g12:
	s_lshl_b32 s25, s52, 8
	v_mov_b32_e32 v140, v239
	v_mov_b32_e32 v128, v238
	s_lshl_b32 s22, s53, 8
	s_ashr_i32 s24, s53, 3
	s_or_b32 s25, s25, s43
	s_ashr_i32 s23, s22, 31
	v_lshl_add_u32 v136, v128, 3, s25
	s_mul_hi_i32 s25, s24, 0x9000
	s_mul_i32 s24, s24, 0x9000
	s_add_u32 s24, s40, s24
	s_addc_u32 s25, s41, s25
	v_ashrrev_i32_e32 v137, 31, v136
	v_lshl_add_u64 v[138:139], v[136:137], 2, s[24:25]
	global_load_dwordx4 v[128:131], v[138:139], off offset:16
	global_load_dwordx4 v[132:135], v[138:139], off
	s_lshl_b64 s[22:23], s[22:23], 11
	s_add_u32 s24, s80, s22
	s_addc_u32 s25, s81, s23
	v_lshlrev_b64 v[226:227], 1, v[136:137]
	s_add_u32 s22, s96, s22
	s_addc_u32 s23, s97, s23
	s_and_b64 vcc, exec, s[2:3]
	s_mov_b32 s52, s50
	s_mov_b32 s53, s51
	s_waitcnt vmcnt(0)
	v_pk_mul_f32 v[216:217], v[130:131], 0.5 op_sel_hi:[1,0]
	v_pk_mul_f32 v[220:221], v[134:135], 0.5 op_sel_hi:[1,0]
	v_pk_mul_f32 v[218:219], v[132:133], 0.5 op_sel_hi:[1,0]
	v_pk_mul_f32 v[214:215], v[128:129], 0.5 op_sel_hi:[1,0]
	global_load_dwordx4 v[128:131], v[138:139], off offset:528
	global_load_dwordx4 v[132:135], v[138:139], off offset:512
	s_waitcnt vmcnt(0)
	v_pk_mul_f32 v[206:207], v[128:129], 0.5 op_sel_hi:[1,0]
	v_add_u32_e32 v128, s42, v140
	v_ashrrev_i32_e32 v129, 31, v128
	v_pk_mul_f32 v[208:209], v[130:131], 0.5 op_sel_hi:[1,0]
	v_lshl_add_u64 v[130:131], s[24:25], 0, v[226:227]
	v_lshlrev_b64 v[248:249], 11, v[128:129]
	v_lshl_add_u64 v[128:129], v[130:131], 0, v[248:249]
	global_load_dwordx4 v[244:247], v[128:129], off
	global_load_dwordx4 v[184:187], v[128:129], off offset:256
	v_lshl_add_u64 v[236:237], v[248:249], 0, s[8:9]
	v_lshl_add_u64 v[128:129], v[130:131], 0, v[236:237]
	global_load_dwordx4 v[180:183], v[128:129], off
	global_load_dwordx4 v[176:179], v[128:129], off offset:256
	v_lshl_add_u64 v[234:235], v[248:249], 0, s[10:11]
	v_lshl_add_u64 v[128:129], v[130:131], 0, v[234:235]
	global_load_dwordx4 v[172:175], v[128:129], off
	global_load_dwordx4 v[168:171], v[128:129], off offset:256
	v_lshl_add_u64 v[232:233], v[248:249], 0, s[12:13]
	v_lshl_add_u64 v[128:129], v[130:131], 0, v[232:233]
	global_load_dwordx4 v[164:167], v[128:129], off
	global_load_dwordx4 v[160:163], v[128:129], off offset:256
	v_lshl_add_u64 v[230:231], v[248:249], 0, s[14:15]
	v_lshl_add_u64 v[128:129], v[130:131], 0, v[230:231]
	global_load_dwordx4 v[156:159], v[128:129], off
	global_load_dwordx4 v[152:155], v[128:129], off offset:256
	v_lshl_add_u64 v[228:229], v[248:249], 0, s[16:17]
	v_lshl_add_u64 v[128:129], v[130:131], 0, v[228:229]
	global_load_dwordx4 v[148:151], v[128:129], off
	global_load_dwordx4 v[144:147], v[128:129], off offset:256
	v_lshl_add_u64 v[224:225], v[248:249], 0, s[18:19]
	v_lshl_add_u64 v[128:129], v[130:131], 0, v[224:225]
	global_load_dwordx4 v[140:143], v[128:129], off
	global_load_dwordx4 v[136:139], v[128:129], off offset:256
	v_lshl_add_u64 v[222:223], v[248:249], 0, s[20:21]
	v_lshl_add_u64 v[128:129], v[130:131], 0, v[222:223]
	v_pk_mul_f32 v[212:213], v[134:135], 0.5 op_sel_hi:[1,0]
	v_pk_mul_f32 v[210:211], v[132:133], 0.5 op_sel_hi:[1,0]
	global_load_dwordx4 v[132:135], v[128:129], off
	s_nop 0
	global_load_dwordx4 v[128:131], v[128:129], off offset:256
	v_lshl_add_u64 v[226:227], s[22:23], 0, v[226:227]
	v_lshl_add_u64 v[248:249], v[226:227], 0, v[248:249]
	s_mov_b64 s[24:25], s[6:7]
	s_mov_b64 s[22:23], s[4:5]
	s_waitcnt vmcnt(0)
	v_lshlrev_b32_e32 v250, 16, v244
	v_and_b32_e32 v251, 0xffff0000, v244
	v_lshlrev_b32_e32 v244, 16, v245
	v_and_b32_e32 v245, 0xffff0000, v245
	v_lshlrev_b32_e32 v252, 16, v246
	v_and_b32_e32 v253, 0xffff0000, v246
	v_lshlrev_b32_e32 v246, 16, v247
	v_and_b32_e32 v247, 0xffff0000, v247
	v_pk_fma_f32 v[126:127], v[126:127], v[220:221], v[244:245]
	v_pk_fma_f32 v[124:125], v[124:125], v[218:219], v[250:251]
	v_pk_fma_f32 v[244:245], v[122:123], v[216:217], v[246:247]
	v_pk_fma_f32 v[122:123], v[120:121], v[214:215], v[252:253]
	v_cvt_pk_bf16_f32 v120, v124, v125
	v_cvt_pk_bf16_f32 v121, v126, v127
	v_lshlrev_b32_e32 v124, 16, v186
	v_cvt_pk_bf16_f32 v122, v122, v123
	v_cvt_pk_bf16_f32 v123, v244, v245
	global_store_dwordx4 v[248:249], v[120:123], off
	v_and_b32_e32 v125, 0xffff0000, v186
	v_lshlrev_b32_e32 v126, 16, v187
	v_lshlrev_b32_e32 v120, 16, v184
	v_and_b32_e32 v121, 0xffff0000, v184
	v_and_b32_e32 v127, 0xffff0000, v187
	v_lshlrev_b32_e32 v122, 16, v185
	v_and_b32_e32 v123, 0xffff0000, v185
	v_pk_fma_f32 v[116:117], v[116:117], v[210:211], v[120:121]
	v_pk_fma_f32 v[120:121], v[114:115], v[208:209], v[126:127]
	v_pk_fma_f32 v[114:115], v[112:113], v[206:207], v[124:125]
	v_pk_fma_f32 v[118:119], v[118:119], v[212:213], v[122:123]
	v_cvt_pk_bf16_f32 v112, v116, v117
	v_lshlrev_b32_e32 v116, 16, v181
	v_cvt_pk_bf16_f32 v113, v118, v119
	v_cvt_pk_bf16_f32 v114, v114, v115
	v_cvt_pk_bf16_f32 v115, v120, v121
	global_store_dwordx4 v[248:249], v[112:115], off offset:256
	v_and_b32_e32 v117, 0xffff0000, v181
	v_lshlrev_b32_e32 v118, 16, v182
	v_lshlrev_b32_e32 v114, 16, v180
	v_and_b32_e32 v115, 0xffff0000, v180
	v_and_b32_e32 v119, 0xffff0000, v182
	v_lshlrev_b32_e32 v120, 16, v183
	v_and_b32_e32 v121, 0xffff0000, v183
	v_lshl_add_u64 v[112:113], v[226:227], 0, v[236:237]
	v_pk_fma_f32 v[110:111], v[110:111], v[220:221], v[116:117]
	v_pk_fma_f32 v[108:109], v[108:109], v[218:219], v[114:115]
	v_pk_fma_f32 v[114:115], v[106:107], v[216:217], v[120:121]
	v_pk_fma_f32 v[106:107], v[104:105], v[214:215], v[118:119]
	v_cvt_pk_bf16_f32 v104, v108, v109
	v_cvt_pk_bf16_f32 v105, v110, v111
	v_lshlrev_b32_e32 v108, 16, v178
	v_cvt_pk_bf16_f32 v106, v106, v107
	v_cvt_pk_bf16_f32 v107, v114, v115
; __device__ __forceinline__ unsigned cvt_pk_bf16(float lo, float hi) { unsigned r; asm volatile("v_cvt_pk_bf16_f32 %0, %1, %2" : "=v"(r) : "v"(lo), "v"(hi)); return r; }
; __device__ __forceinline__ float bf_lo(unsigned u) { return __uint_as_float(u << 16); }
; __device__ __forceinline__ float bf_hi(unsigned u) { return __uint_as_float(u & 0xffff0000u); }
;     __device__ __forceinline__ void operator()(const AccT& acc, const Unit& u, int wr, int wc, int fr, int fq) const {
;     ...
; #pragma unroll
;         for (int ai = 0; ai < 2; ++ai)
; #pragma unroll
;             for (int m = 0; m < 4; ++m)
; #pragma unroll
;                 for (int bj = 0; bj < 2; ++bj) {
;                     const u32x4 q = r[ai][m][bj];
;                     const f32x4 r0 = {bf_lo(q.x), bf_hi(q.x), bf_lo(q.y), bf_hi(q.y)}, r1 = {bf_lo(q.z), bf_hi(q.z), bf_lo(q.w), bf_hi(q.w)};
;                     const f32x4 h0 = r0 + gv[bj][0] * acc[ai][bj][m][0], h1 = r1 + gv[bj][1] * acc[ai][bj][m][1];
;                     u32x4 w; w.x = cvt_pk_bf16(h0[0], h0[1]); w.y = cvt_pk_bf16(h0[2], h0[3]); w.z = cvt_pk_bf16(h1[0], h1[1]); w.w = cvt_pk_bf16(h1[2], h1[3]);
;                     *(u32x4*)(out + (size_t)(wr * 64 + fr + ai * 128 + m * 16) * DM + col0 + bj * 128) = w;
;                 }
	global_store_dwordx4 v[112:113], v[104:107], off
	v_and_b32_e32 v109, 0xffff0000, v178
	v_lshlrev_b32_e32 v110, 16, v179
	v_lshlrev_b32_e32 v104, 16, v176
	v_and_b32_e32 v105, 0xffff0000, v176
	v_and_b32_e32 v111, 0xffff0000, v179
	v_lshlrev_b32_e32 v106, 16, v177
	v_and_b32_e32 v107, 0xffff0000, v177
	v_pk_fma_f32 v[100:101], v[100:101], v[210:211], v[104:105]
	v_pk_fma_f32 v[104:105], v[98:99], v[208:209], v[110:111]
	v_pk_fma_f32 v[98:99], v[96:97], v[206:207], v[108:109]
	v_pk_fma_f32 v[102:103], v[102:103], v[212:213], v[106:107]
	v_cvt_pk_bf16_f32 v96, v100, v101
	v_lshlrev_b32_e32 v100, 16, v173
	v_cvt_pk_bf16_f32 v97, v102, v103
	v_cvt_pk_bf16_f32 v98, v98, v99
	v_cvt_pk_bf16_f32 v99, v104, v105
	global_store_dwordx4 v[112:113], v[96:99], off offset:256
	v_and_b32_e32 v101, 0xffff0000, v173
	v_lshlrev_b32_e32 v102, 16, v174
	v_lshlrev_b32_e32 v98, 16, v172
	v_and_b32_e32 v99, 0xffff0000, v172
	v_and_b32_e32 v103, 0xffff0000, v174
	v_lshlrev_b32_e32 v104, 16, v175
	v_and_b32_e32 v105, 0xffff0000, v175
	v_lshl_add_u64 v[96:97], v[226:227], 0, v[234:235]
	v_pk_fma_f32 v[94:95], v[94:95], v[220:221], v[100:101]
	v_pk_fma_f32 v[92:93], v[92:93], v[218:219], v[98:99]
	v_pk_fma_f32 v[98:99], v[90:91], v[216:217], v[104:105]
	v_pk_fma_f32 v[90:91], v[88:89], v[214:215], v[102:103]
	v_cvt_pk_bf16_f32 v88, v92, v93
	v_cvt_pk_bf16_f32 v89, v94, v95
	v_lshlrev_b32_e32 v92, 16, v170
	v_cvt_pk_bf16_f32 v90, v90, v91
	v_cvt_pk_bf16_f32 v91, v98, v99
	global_store_dwordx4 v[96:97], v[88:91], off
	v_and_b32_e32 v93, 0xffff0000, v170
	v_lshlrev_b32_e32 v94, 16, v171
	v_lshlrev_b32_e32 v88, 16, v168
	v_and_b32_e32 v89, 0xffff0000, v168
	v_and_b32_e32 v95, 0xffff0000, v171
	v_lshlrev_b32_e32 v90, 16, v169
	v_and_b32_e32 v91, 0xffff0000, v169
	v_pk_fma_f32 v[84:85], v[84:85], v[210:211], v[88:89]
	v_pk_fma_f32 v[88:89], v[82:83], v[208:209], v[94:95]
	v_pk_fma_f32 v[82:83], v[80:81], v[206:207], v[92:93]
	v_pk_fma_f32 v[86:87], v[86:87], v[212:213], v[90:91]
	v_cvt_pk_bf16_f32 v80, v84, v85
	v_lshlrev_b32_e32 v84, 16, v165
	v_cvt_pk_bf16_f32 v81, v86, v87
	v_cvt_pk_bf16_f32 v82, v82, v83
	v_cvt_pk_bf16_f32 v83, v88, v89
	global_store_dwordx4 v[96:97], v[80:83], off offset:256
	v_and_b32_e32 v85, 0xffff0000, v165
	v_lshlrev_b32_e32 v86, 16, v166
	v_lshlrev_b32_e32 v82, 16, v164
	v_and_b32_e32 v83, 0xffff0000, v164
	v_and_b32_e32 v87, 0xffff0000, v166
	v_lshlrev_b32_e32 v88, 16, v167
	v_and_b32_e32 v89, 0xffff0000, v167
	v_lshl_add_u64 v[80:81], v[226:227], 0, v[232:233]
	v_pk_fma_f32 v[78:79], v[78:79], v[220:221], v[84:85]
	v_pk_fma_f32 v[76:77], v[76:77], v[218:219], v[82:83]
	v_pk_fma_f32 v[82:83], v[74:75], v[216:217], v[88:89]
	v_pk_fma_f32 v[74:75], v[72:73], v[214:215], v[86:87]
	v_cvt_pk_bf16_f32 v72, v76, v77
	v_cvt_pk_bf16_f32 v73, v78, v79
	v_lshlrev_b32_e32 v76, 16, v162
	v_cvt_pk_bf16_f32 v74, v74, v75
	v_cvt_pk_bf16_f32 v75, v82, v83
	global_store_dwordx4 v[80:81], v[72:75], off
	v_and_b32_e32 v77, 0xffff0000, v162
	v_lshlrev_b32_e32 v78, 16, v163
	v_lshlrev_b32_e32 v72, 16, v160
	v_and_b32_e32 v73, 0xffff0000, v160
	v_and_b32_e32 v79, 0xffff0000, v163
	v_lshlrev_b32_e32 v74, 16, v161
	v_and_b32_e32 v75, 0xffff0000, v161
	v_pk_fma_f32 v[68:69], v[68:69], v[210:211], v[72:73]
	v_pk_fma_f32 v[72:73], v[66:67], v[208:209], v[78:79]
	v_pk_fma_f32 v[66:67], v[64:65], v[206:207], v[76:77]
	v_pk_fma_f32 v[70:71], v[70:71], v[212:213], v[74:75]
	v_cvt_pk_bf16_f32 v64, v68, v69
	v_lshlrev_b32_e32 v68, 16, v157
	v_cvt_pk_bf16_f32 v65, v70, v71
	v_cvt_pk_bf16_f32 v66, v66, v67
	v_cvt_pk_bf16_f32 v67, v72, v73
	global_store_dwordx4 v[80:81], v[64:67], off offset:256
	v_and_b32_e32 v69, 0xffff0000, v157
	v_lshlrev_b32_e32 v70, 16, v158
	v_lshlrev_b32_e32 v66, 16, v156
	v_and_b32_e32 v67, 0xffff0000, v156
	v_and_b32_e32 v71, 0xffff0000, v158
	v_lshlrev_b32_e32 v72, 16, v159
	v_and_b32_e32 v73, 0xffff0000, v159
	v_lshl_add_u64 v[64:65], v[226:227], 0, v[230:231]
	v_pk_fma_f32 v[62:63], v[62:63], v[220:221], v[68:69]
	v_pk_fma_f32 v[60:61], v[60:61], v[218:219], v[66:67]
	v_pk_fma_f32 v[66:67], v[58:59], v[216:217], v[72:73]
	v_pk_fma_f32 v[58:59], v[56:57], v[214:215], v[70:71]
	v_cvt_pk_bf16_f32 v56, v60, v61
	v_cvt_pk_bf16_f32 v57, v62, v63
	v_lshlrev_b32_e32 v60, 16, v154
	v_cvt_pk_bf16_f32 v58, v58, v59
	v_cvt_pk_bf16_f32 v59, v66, v67
	global_store_dwordx4 v[64:65], v[56:59], off
	v_and_b32_e32 v61, 0xffff0000, v154
	v_lshlrev_b32_e32 v62, 16, v155
	v_lshlrev_b32_e32 v56, 16, v152
	v_and_b32_e32 v57, 0xffff0000, v152
	v_and_b32_e32 v63, 0xffff0000, v155
	v_lshlrev_b32_e32 v58, 16, v153
	v_and_b32_e32 v59, 0xffff0000, v153
	v_pk_fma_f32 v[52:53], v[52:53], v[210:211], v[56:57]
; __device__ __forceinline__ unsigned cvt_pk_bf16(float lo, float hi) { unsigned r; asm volatile("v_cvt_pk_bf16_f32 %0, %1, %2" : "=v"(r) : "v"(lo), "v"(hi)); return r; }
; __device__ __forceinline__ float bf_lo(unsigned u) { return __uint_as_float(u << 16); }
; __device__ __forceinline__ float bf_hi(unsigned u) { return __uint_as_float(u & 0xffff0000u); }
;     __device__ __forceinline__ void operator()(const AccT& acc, const Unit& u, int wr, int wc, int fr, int fq) const {
;     ...
; #pragma unroll
;         for (int ai = 0; ai < 2; ++ai)
; #pragma unroll
;             for (int m = 0; m < 4; ++m)
; #pragma unroll
;                 for (int bj = 0; bj < 2; ++bj) {
;                     const u32x4 q = r[ai][m][bj];
;                     const f32x4 r0 = {bf_lo(q.x), bf_hi(q.x), bf_lo(q.y), bf_hi(q.y)}, r1 = {bf_lo(q.z), bf_hi(q.z), bf_lo(q.w), bf_hi(q.w)};
;                     const f32x4 h0 = r0 + gv[bj][0] * acc[ai][bj][m][0], h1 = r1 + gv[bj][1] * acc[ai][bj][m][1];
;                     u32x4 w; w.x = cvt_pk_bf16(h0[0], h0[1]); w.y = cvt_pk_bf16(h0[2], h0[3]); w.z = cvt_pk_bf16(h1[0], h1[1]); w.w = cvt_pk_bf16(h1[2], h1[3]);
;                     *(u32x4*)(out + (size_t)(wr * 64 + fr + ai * 128 + m * 16) * DM + col0 + bj * 128) = w;
;                 }
	v_pk_fma_f32 v[56:57], v[50:51], v[208:209], v[62:63]
	v_pk_fma_f32 v[50:51], v[48:49], v[206:207], v[60:61]
	v_pk_fma_f32 v[54:55], v[54:55], v[212:213], v[58:59]
	v_cvt_pk_bf16_f32 v48, v52, v53
	v_lshlrev_b32_e32 v52, 16, v149
	v_cvt_pk_bf16_f32 v49, v54, v55
	v_cvt_pk_bf16_f32 v50, v50, v51
	v_cvt_pk_bf16_f32 v51, v56, v57
	global_store_dwordx4 v[64:65], v[48:51], off offset:256
	v_and_b32_e32 v53, 0xffff0000, v149
	v_lshlrev_b32_e32 v54, 16, v150
	v_lshlrev_b32_e32 v50, 16, v148
	v_and_b32_e32 v51, 0xffff0000, v148
	v_and_b32_e32 v55, 0xffff0000, v150
	v_lshlrev_b32_e32 v56, 16, v151
	v_and_b32_e32 v57, 0xffff0000, v151
	v_lshl_add_u64 v[48:49], v[226:227], 0, v[228:229]
	v_pk_fma_f32 v[46:47], v[46:47], v[220:221], v[52:53]
	v_pk_fma_f32 v[44:45], v[44:45], v[218:219], v[50:51]
	v_pk_fma_f32 v[50:51], v[42:43], v[216:217], v[56:57]
	v_pk_fma_f32 v[42:43], v[40:41], v[214:215], v[54:55]
	v_cvt_pk_bf16_f32 v40, v44, v45
	v_cvt_pk_bf16_f32 v41, v46, v47
	v_lshlrev_b32_e32 v44, 16, v146
	v_cvt_pk_bf16_f32 v42, v42, v43
	v_cvt_pk_bf16_f32 v43, v50, v51
	global_store_dwordx4 v[48:49], v[40:43], off
	v_and_b32_e32 v45, 0xffff0000, v146
	v_lshlrev_b32_e32 v46, 16, v147
	v_lshlrev_b32_e32 v40, 16, v144
	v_and_b32_e32 v41, 0xffff0000, v144
	v_and_b32_e32 v47, 0xffff0000, v147
	v_lshlrev_b32_e32 v42, 16, v145
	v_and_b32_e32 v43, 0xffff0000, v145
	v_pk_fma_f32 v[36:37], v[36:37], v[210:211], v[40:41]
	v_pk_fma_f32 v[40:41], v[34:35], v[208:209], v[46:47]
	v_pk_fma_f32 v[34:35], v[32:33], v[206:207], v[44:45]
	v_pk_fma_f32 v[38:39], v[38:39], v[212:213], v[42:43]
	v_cvt_pk_bf16_f32 v32, v36, v37
	v_lshlrev_b32_e32 v36, 16, v141
	v_cvt_pk_bf16_f32 v33, v38, v39
	v_cvt_pk_bf16_f32 v34, v34, v35
	v_cvt_pk_bf16_f32 v35, v40, v41
	global_store_dwordx4 v[48:49], v[32:35], off offset:256
	v_and_b32_e32 v37, 0xffff0000, v141
	v_lshlrev_b32_e32 v38, 16, v142
	v_lshlrev_b32_e32 v34, 16, v140
	v_and_b32_e32 v35, 0xffff0000, v140
	v_and_b32_e32 v39, 0xffff0000, v142
	v_lshlrev_b32_e32 v40, 16, v143
	v_and_b32_e32 v41, 0xffff0000, v143
	v_lshl_add_u64 v[32:33], v[226:227], 0, v[224:225]
	v_pk_fma_f32 v[30:31], v[30:31], v[220:221], v[36:37]
	v_pk_fma_f32 v[28:29], v[28:29], v[218:219], v[34:35]
	v_pk_fma_f32 v[34:35], v[26:27], v[216:217], v[40:41]
	v_pk_fma_f32 v[26:27], v[24:25], v[214:215], v[38:39]
	v_cvt_pk_bf16_f32 v24, v28, v29
	v_cvt_pk_bf16_f32 v25, v30, v31
	v_lshlrev_b32_e32 v28, 16, v138
	v_cvt_pk_bf16_f32 v26, v26, v27
	v_cvt_pk_bf16_f32 v27, v34, v35
	global_store_dwordx4 v[32:33], v[24:27], off
	v_and_b32_e32 v29, 0xffff0000, v138
	v_lshlrev_b32_e32 v30, 16, v139
	v_lshlrev_b32_e32 v24, 16, v136
	v_and_b32_e32 v25, 0xffff0000, v136
	v_and_b32_e32 v31, 0xffff0000, v139
	v_lshlrev_b32_e32 v26, 16, v137
	v_and_b32_e32 v27, 0xffff0000, v137
	v_pk_fma_f32 v[20:21], v[20:21], v[210:211], v[24:25]
	v_pk_fma_f32 v[24:25], v[18:19], v[208:209], v[30:31]
	v_pk_fma_f32 v[18:19], v[16:17], v[206:207], v[28:29]
	v_pk_fma_f32 v[22:23], v[22:23], v[212:213], v[26:27]
	v_cvt_pk_bf16_f32 v16, v20, v21
	v_lshlrev_b32_e32 v20, 16, v133
	v_cvt_pk_bf16_f32 v17, v22, v23
	v_cvt_pk_bf16_f32 v18, v18, v19
	v_cvt_pk_bf16_f32 v19, v24, v25
	global_store_dwordx4 v[32:33], v[16:19], off offset:256
	v_and_b32_e32 v21, 0xffff0000, v133
	v_lshlrev_b32_e32 v22, 16, v134
	v_lshlrev_b32_e32 v18, 16, v132
	v_and_b32_e32 v19, 0xffff0000, v132
	v_and_b32_e32 v23, 0xffff0000, v134
	v_lshlrev_b32_e32 v24, 16, v135
	v_and_b32_e32 v25, 0xffff0000, v135
	v_lshl_add_u64 v[16:17], v[226:227], 0, v[222:223]
	v_pk_fma_f32 v[14:15], v[14:15], v[220:221], v[20:21]
	v_pk_fma_f32 v[12:13], v[12:13], v[218:219], v[18:19]
	v_pk_fma_f32 v[18:19], v[10:11], v[216:217], v[24:25]
	v_pk_fma_f32 v[10:11], v[8:9], v[214:215], v[22:23]
	v_cvt_pk_bf16_f32 v8, v12, v13
	v_cvt_pk_bf16_f32 v9, v14, v15
	v_lshlrev_b32_e32 v12, 16, v130
	v_cvt_pk_bf16_f32 v10, v10, v11
	v_cvt_pk_bf16_f32 v11, v18, v19
	global_store_dwordx4 v[16:17], v[8:11], off
	v_and_b32_e32 v13, 0xffff0000, v130
	v_lshlrev_b32_e32 v14, 16, v131
	v_lshlrev_b32_e32 v8, 16, v128
	v_and_b32_e32 v9, 0xffff0000, v128
	v_and_b32_e32 v15, 0xffff0000, v131
	v_lshlrev_b32_e32 v10, 16, v129
	v_and_b32_e32 v11, 0xffff0000, v129
	v_pk_fma_f32 v[4:5], v[4:5], v[210:211], v[8:9]
	v_pk_fma_f32 v[8:9], v[2:3], v[208:209], v[14:15]
	v_pk_fma_f32 v[2:3], v[0:1], v[206:207], v[12:13]
	v_pk_fma_f32 v[6:7], v[6:7], v[212:213], v[10:11]
	v_cvt_pk_bf16_f32 v0, v4, v5
	s_nop 0
	v_cvt_pk_bf16_f32 v1, v6, v7
	v_cvt_pk_bf16_f32 v2, v2, v3
	v_cvt_pk_bf16_f32 v3, v8, v9
	global_store_dwordx4 v[16:17], v[0:3], off offset:256
	s_barrier
	s_cbranch_vccz .LBB0_1086
